# GEMM loops: LDS-DMA loads use SGPR-base+VGPR-offset form (removes 12-16 v_lshl_add_u64 per iteration), on top of first-iteration peel and in-proj wait fix
# speedup vs baseline: 1.0052x; 1.0052x over previous
; #define PG8_STAGE(bufoff, gbase, voff) do { _Pragma("unroll") for (int _i = 0; _i < 2; ++_i) \
;         __builtin_amdgcn_global_load_lds((const unsigned*)((const char*)(gbase) + (voff)[_i]), (LAS unsigned*)(lds + (bufoff) + ldsw + _i * 8192), 16, 0, 0); } while (0)
; #define PG8_LDA(dst, b, h) do { _Pragma("unroll") for (int m = 0; m < 4; ++m) _Pragma("unroll") for (int k = 0; k < 2; ++k) dst[m][k] = *(const LAS bf16x8*)(lds + PG8_SA(b, h) + aoff + m * 2048 + k * 1024); } while (0)
; #define PG8_LDB(dst, b, h) do { _Pragma("unroll") for (int n = 0; n < 2; ++n) _Pragma("unroll") for (int k = 0; k < 2; ++k) dst[n][k] = *(const LAS bf16x8*)(lds + PG8_SB(b, h) + boff + n * 2048 + k * 1024); } while (0)
; #define PG8_MMA(ai, bj, At, Bt) do { __builtin_amdgcn_s_setprio(1); _Pragma("unroll") for (int m = 0; m < 4; ++m) _Pragma("unroll") for (int n = 0; n < 2; ++n) _Pragma("unroll") for (int k = 0; k < 2; ++k) \
;         acc[ai][bj][m][n] = __builtin_amdgcn_mfma_f32_16x16x32_bf16(Bt[n][k], At[m][k], acc[ai][bj][m][n], 0, 0, 0); __builtin_amdgcn_s_setprio(0); } while (0)
; #define PG8_WAIT_L(n) asm volatile("s_waitcnt lgkmcnt(" #n ")" ::: "memory")
; #define PG8_BAR __builtin_amdgcn_s_barrier()
; #define PG8_SCHED __builtin_amdgcn_sched_barrier(0)
; template <class Epi, class Sched>
; __device__ __forceinline__ void gemm_phase(LAS unsigned char* lds, const Gemm g, const Sched& S, const Epi& E) {
;     ...
;         for (int t = 0; t < nt; t += 2) {
;             const bool last = (t == nt - 2);
;             const char* a1 = cA + (size_t)(t + 1) * kstep;
;             const char* a2 = last ? nA : cA + (size_t)(t + 2) * kstep; const char* b2 = last ? nB : cB + (size_t)(t + 2) * kstep;
;             const char* a3 = a2 + kstep; const char* b3 = b2 + kstep;
;             PG8_LDB(B0, 0, 0); PG8_SCHED; PG8_LDA(At, 0, 0); PG8_STAGE(PG8_SA(1, 1), a1 + hstep, voffA);
;             PG8_WAIT_L(8); PG8_BAR; PG8_WAIT_L(0); PG8_MMA(0, 0, At, B0); PG8_BAR; PG8_SCHED;
;             PG8_LDB(B1, 0, 1); PG8_STAGE(PG8_SB(0, 0), b2, voffB);
;             PG8_BAR; PG8_WAIT_L(0); PG8_MMA(0, 1, At, B1); PG8_BAR;
;             PG8_LDA(At, 0, 1); PG8_STAGE(PG8_SA(0, 0), a2, voffA);
;             PG8_BAR; PG8_WAIT_L(0); PG8_MMA(1, 0, At, B0); PG8_BAR; PG8_SCHED;
.LBB0_234:
	s_ashr_i32 s7, s6, 31
	v_cmp_lt_i64_e32 vcc, s[8:9], v[140:141]
	s_lshl_b64 s[8:9], s[6:7], 19
	s_add_u32 s8, s96, s8
	s_addc_u32 s9, s97, s9
	s_and_b64 s[10:11], vcc, exec
	s_cselect_b32 s7, s9, s15
	s_cselect_b32 s44, s8, s14
	s_ashr_i32 s5, s4, 31
	s_lshl_b64 s[10:11], s[4:5], 19
	s_add_u32 s10, s72, s10
	s_addc_u32 s11, s73, s11
	s_and_b64 s[16:17], vcc, exec
	s_cselect_b32 s5, s11, s19
	s_cselect_b32 s45, s10, s18
	s_add_u32 s14, s14, 0x40080
	s_addc_u32 s15, s15, 0
	s_add_u32 s46, s18, 0x100
	s_addc_u32 s47, s19, 0
	s_mov_b32 s48, -2
	ds_read_b128 v[150:153], v147
	ds_read_b128 v[154:157], v147 offset:1024
	ds_read_b128 v[158:161], v147 offset:2048
	ds_read_b128 v[162:165], v147 offset:3072
	s_add_u32 s16, s14, 0xfffc0080
	s_addc_u32 s17, s15, -1
	s_cmp_eq_u32 s48, 12
	s_cselect_b32 s23, s7, s17
	s_cselect_b32 s22, s44, s16
	s_cselect_b32 s19, s5, s47
	s_cselect_b32 s18, s45, s46
	s_add_i32 m0, s13, 0xc000
	ds_read_b128 v[166:169], v148
	ds_read_b128 v[170:173], v148 offset:1024
	ds_read_b128 v[174:177], v148 offset:2048
	ds_read_b128 v[178:181], v148 offset:3072
	ds_read_b128 v[182:185], v148 offset:4096
	ds_read_b128 v[186:189], v148 offset:5120
	ds_read_b128 v[190:193], v148 offset:6144
	ds_read_b128 v[194:197], v148 offset:7168
	global_load_lds_dwordx4 v136, s[14:15]
	s_add_i32 m0, s13, 0xe000
	s_nop 0
	global_load_lds_dwordx4 v138, s[14:15]
	s_waitcnt lgkmcnt(8)
	s_barrier
	s_waitcnt lgkmcnt(0)
	s_setprio 1
	s_waitcnt lgkmcnt(0)
	v_mfma_f32_16x16x32_bf16 v[124:127], v[150:153], v[166:169], 0
	v_mfma_f32_16x16x32_bf16 v[116:119], v[158:161], v[166:169], 0
	v_mfma_f32_16x16x32_bf16 v[108:111], v[150:153], v[174:177], 0
	v_mfma_f32_16x16x32_bf16 v[100:103], v[158:161], v[174:177], 0
	v_mfma_f32_16x16x32_bf16 v[92:95], v[150:153], v[182:185], 0
	v_mfma_f32_16x16x32_bf16 v[84:87], v[158:161], v[182:185], 0
	v_mfma_f32_16x16x32_bf16 v[76:79], v[150:153], v[190:193], 0
	v_mfma_f32_16x16x32_bf16 v[68:71], v[158:161], v[190:193], 0
	v_mfma_f32_16x16x32_bf16 v[124:127], v[154:157], v[170:173], v[124:127]
	v_mfma_f32_16x16x32_bf16 v[116:119], v[162:165], v[170:173], v[116:119]
	v_mfma_f32_16x16x32_bf16 v[108:111], v[154:157], v[178:181], v[108:111]
	v_mfma_f32_16x16x32_bf16 v[100:103], v[162:165], v[178:181], v[100:103]
	v_mfma_f32_16x16x32_bf16 v[92:95], v[154:157], v[186:189], v[92:95]
	v_mfma_f32_16x16x32_bf16 v[84:87], v[162:165], v[186:189], v[84:87]
	v_mfma_f32_16x16x32_bf16 v[76:79], v[154:157], v[194:197], v[76:79]
	v_mfma_f32_16x16x32_bf16 v[68:71], v[162:165], v[194:197], v[68:71]
	s_setprio 0
	s_barrier
	s_add_i32 s16, s40, s25
	s_mov_b32 m0, s16
	ds_read_b128 v[202:205], v149
	ds_read_b128 v[206:209], v149 offset:1024
	ds_read_b128 v[210:213], v149 offset:2048
	ds_read_b128 v[214:217], v149 offset:3072
	global_load_lds_dwordx4 v132, s[18:19]
	s_add_i32 m0, s16, 0x2000
	s_nop 0
	global_load_lds_dwordx4 v128, s[18:19]
	s_barrier
	s_waitcnt lgkmcnt(0)
	s_setprio 1
	s_waitcnt lgkmcnt(0)
	v_mfma_f32_16x16x32_bf16 v[120:123], v[202:205], v[166:169], 0
	v_mfma_f32_16x16x32_bf16 v[112:115], v[210:213], v[166:169], 0
	v_mfma_f32_16x16x32_bf16 v[104:107], v[202:205], v[174:177], 0
	v_mfma_f32_16x16x32_bf16 v[96:99], v[210:213], v[174:177], 0
	v_mfma_f32_16x16x32_bf16 v[88:91], v[202:205], v[182:185], 0
	v_mfma_f32_16x16x32_bf16 v[80:83], v[210:213], v[182:185], 0
	v_mfma_f32_16x16x32_bf16 v[72:75], v[202:205], v[190:193], 0
	v_mfma_f32_16x16x32_bf16 v[64:67], v[210:213], v[190:193], 0
	v_mfma_f32_16x16x32_bf16 v[120:123], v[206:209], v[170:173], v[120:123]
	v_mfma_f32_16x16x32_bf16 v[112:115], v[214:217], v[170:173], v[112:115]
	v_mfma_f32_16x16x32_bf16 v[104:107], v[206:209], v[178:181], v[104:107]
	v_mfma_f32_16x16x32_bf16 v[96:99], v[214:217], v[178:181], v[96:99]
	v_mfma_f32_16x16x32_bf16 v[88:91], v[206:209], v[186:189], v[88:91]
	v_mfma_f32_16x16x32_bf16 v[80:83], v[214:217], v[186:189], v[80:83]
	v_mfma_f32_16x16x32_bf16 v[72:75], v[206:209], v[194:197], v[72:75]
	v_mfma_f32_16x16x32_bf16 v[64:67], v[214:217], v[194:197], v[64:67]
	s_setprio 0
	s_mov_b32 m0, s13
	s_barrier
	ds_read_b128 v[166:169], v148 offset:16384
	ds_read_b128 v[170:173], v148 offset:17408
	ds_read_b128 v[174:177], v148 offset:18432
	ds_read_b128 v[178:181], v148 offset:19456
	ds_read_b128 v[182:185], v148 offset:20480
	ds_read_b128 v[186:189], v148 offset:21504
	ds_read_b128 v[190:193], v148 offset:22528
	ds_read_b128 v[194:197], v148 offset:23552
	global_load_lds_dwordx4 v134, s[22:23]
	s_mov_b32 m0, s28
	s_nop 0
	global_load_lds_dwordx4 v130, s[22:23]
	s_barrier
	s_waitcnt lgkmcnt(0)
	s_setprio 1
	s_waitcnt lgkmcnt(0)
	v_mfma_f32_16x16x32_bf16 v[60:63], v[150:153], v[166:169], 0
	v_mfma_f32_16x16x32_bf16 v[56:59], v[158:161], v[166:169], 0
	v_mfma_f32_16x16x32_bf16 v[44:47], v[150:153], v[174:177], 0
	v_mfma_f32_16x16x32_bf16 v[40:43], v[158:161], v[174:177], 0
	v_mfma_f32_16x16x32_bf16 v[28:31], v[150:153], v[182:185], 0
	v_mfma_f32_16x16x32_bf16 v[24:27], v[158:161], v[182:185], 0
	v_mfma_f32_16x16x32_bf16 v[12:15], v[150:153], v[190:193], 0
	v_mfma_f32_16x16x32_bf16 v[8:11], v[158:161], v[190:193], 0
	v_mfma_f32_16x16x32_bf16 v[60:63], v[154:157], v[170:173], v[60:63]
	v_mfma_f32_16x16x32_bf16 v[56:59], v[162:165], v[170:173], v[56:59]
	v_mfma_f32_16x16x32_bf16 v[44:47], v[154:157], v[178:181], v[44:47]
	v_mfma_f32_16x16x32_bf16 v[40:43], v[162:165], v[178:181], v[40:43]
	v_mfma_f32_16x16x32_bf16 v[28:31], v[154:157], v[186:189], v[28:31]
	v_mfma_f32_16x16x32_bf16 v[24:27], v[162:165], v[186:189], v[24:27]
	v_mfma_f32_16x16x32_bf16 v[12:15], v[154:157], v[194:197], v[12:15]
	v_mfma_f32_16x16x32_bf16 v[8:11], v[162:165], v[194:197], v[8:11]
	s_setprio 0
	s_barrier
; #define PG8_STAGE(bufoff, gbase, voff) do { _Pragma("unroll") for (int _i = 0; _i < 2; ++_i) \
;         __builtin_amdgcn_global_load_lds((const unsigned*)((const char*)(gbase) + (voff)[_i]), (LAS unsigned*)(lds + (bufoff) + ldsw + _i * 8192), 16, 0, 0); } while (0)
; #define PG8_LDA(dst, b, h) do { _Pragma("unroll") for (int m = 0; m < 4; ++m) _Pragma("unroll") for (int k = 0; k < 2; ++k) dst[m][k] = *(const LAS bf16x8*)(lds + PG8_SA(b, h) + aoff + m * 2048 + k * 1024); } while (0)
; #define PG8_LDB(dst, b, h) do { _Pragma("unroll") for (int n = 0; n < 2; ++n) _Pragma("unroll") for (int k = 0; k < 2; ++k) dst[n][k] = *(const LAS bf16x8*)(lds + PG8_SB(b, h) + boff + n * 2048 + k * 1024); } while (0)
; #define PG8_MMA(ai, bj, At, Bt) do { __builtin_amdgcn_s_setprio(1); _Pragma("unroll") for (int m = 0; m < 4; ++m) _Pragma("unroll") for (int n = 0; n < 2; ++n) _Pragma("unroll") for (int k = 0; k < 2; ++k) \
;         acc[ai][bj][m][n] = __builtin_amdgcn_mfma_f32_16x16x32_bf16(Bt[n][k], At[m][k], acc[ai][bj][m][n], 0, 0, 0); __builtin_amdgcn_s_setprio(0); } while (0)
; #define PG8_WAIT_V(n) asm volatile("s_waitcnt vmcnt(" #n ")" ::: "memory")
; #define PG8_WAIT_L(n) asm volatile("s_waitcnt lgkmcnt(" #n ")" ::: "memory")
; #define PG8_BAR __builtin_amdgcn_s_barrier()
; #define PG8_SCHED __builtin_amdgcn_sched_barrier(0)
; template <class Epi, class Sched>
; __device__ __forceinline__ void gemm_phase(LAS unsigned char* lds, const Gemm g, const Sched& S, const Epi& E) {
;     ...
;             PG8_STAGE(PG8_SB(0, 1), b2 + hstep, voffB);
;             PG8_WAIT_V(6); PG8_BAR; PG8_MMA(1, 1, At, B1); PG8_BAR;
;             PG8_LDB(B0, 1, 0); PG8_SCHED; PG8_LDA(At, 1, 0); PG8_STAGE(PG8_SA(0, 1), a2 + hstep, voffA);
;             PG8_WAIT_L(8); PG8_BAR; PG8_WAIT_L(0); PG8_MMA(0, 0, At, B0); PG8_BAR; PG8_SCHED;
;             PG8_LDB(B1, 1, 1); PG8_STAGE(PG8_SB(1, 0), b3, voffB);
;             PG8_BAR; PG8_WAIT_L(0); PG8_MMA(0, 1, At, B1); PG8_BAR;
;             PG8_LDA(At, 1, 1); PG8_STAGE(PG8_SA(1, 0), a3, voffA);
;             PG8_BAR; PG8_WAIT_L(0); PG8_MMA(1, 0, At, B0); PG8_BAR; PG8_SCHED;
	s_add_u32 s16, s18, 0x40000
	s_addc_u32 s17, s19, 0
	s_add_i32 s20, s41, s25
	s_mov_b32 m0, s20
	s_nop 0
	global_load_lds_dwordx4 v132, s[16:17]
	s_add_i32 m0, s20, 0x2000
	s_nop 0
	global_load_lds_dwordx4 v128, s[16:17]
	s_waitcnt vmcnt(6)
	s_barrier
	s_setprio 1
	v_mfma_f32_16x16x32_bf16 v[52:55], v[202:205], v[166:169], 0
	v_mfma_f32_16x16x32_bf16 v[48:51], v[210:213], v[166:169], 0
	v_mfma_f32_16x16x32_bf16 v[36:39], v[202:205], v[174:177], 0
	v_mfma_f32_16x16x32_bf16 v[32:35], v[210:213], v[174:177], 0
	v_mfma_f32_16x16x32_bf16 v[20:23], v[202:205], v[182:185], 0
	v_mfma_f32_16x16x32_bf16 v[16:19], v[210:213], v[182:185], 0
	v_mfma_f32_16x16x32_bf16 v[4:7], v[202:205], v[190:193], 0
	v_mfma_f32_16x16x32_bf16 v[0:3], v[210:213], v[190:193], 0
	v_mfma_f32_16x16x32_bf16 v[52:55], v[206:209], v[170:173], v[52:55]
	v_mfma_f32_16x16x32_bf16 v[48:51], v[214:217], v[170:173], v[48:51]
	v_mfma_f32_16x16x32_bf16 v[36:39], v[206:209], v[178:181], v[36:39]
	v_mfma_f32_16x16x32_bf16 v[32:35], v[214:217], v[178:181], v[32:35]
	v_mfma_f32_16x16x32_bf16 v[20:23], v[206:209], v[186:189], v[20:23]
	v_mfma_f32_16x16x32_bf16 v[16:19], v[214:217], v[186:189], v[16:19]
	v_mfma_f32_16x16x32_bf16 v[4:7], v[206:209], v[194:197], v[4:7]
	v_mfma_f32_16x16x32_bf16 v[0:3], v[214:217], v[194:197], v[0:3]
	s_setprio 0
	s_add_i32 s20, 0, 0x18000
	v_add_u32_e32 v162, s20, v146
	s_barrier
	ds_read_b128 v[150:153], v162
	ds_read_b128 v[154:157], v162 offset:1024
	ds_read_b128 v[158:161], v162 offset:2048
	ds_read_b128 v[162:165], v162 offset:3072
	s_add_u32 s16, s22, 0x40000
	s_addc_u32 s17, s23, 0
	s_mov_b32 m0, s29
	ds_read_b128 v[166:169], v148 offset:32768
	ds_read_b128 v[170:173], v148 offset:33792
	ds_read_b128 v[174:177], v148 offset:34816
	ds_read_b128 v[178:181], v148 offset:35840
	ds_read_b128 v[182:185], v148 offset:36864
	ds_read_b128 v[186:189], v148 offset:37888
	ds_read_b128 v[190:193], v148 offset:38912
	ds_read_b128 v[194:197], v148 offset:39936
	global_load_lds_dwordx4 v134, s[16:17]
	s_mov_b32 m0, s33
	s_nop 0
	global_load_lds_dwordx4 v130, s[16:17]
	s_waitcnt lgkmcnt(8)
	s_barrier
	s_waitcnt lgkmcnt(0)
	s_setprio 1
	s_waitcnt lgkmcnt(0)
	v_mfma_f32_16x16x32_bf16 v[124:127], v[150:153], v[166:169], v[124:127]
	v_mfma_f32_16x16x32_bf16 v[116:119], v[158:161], v[166:169], v[116:119]
	v_mfma_f32_16x16x32_bf16 v[108:111], v[150:153], v[174:177], v[108:111]
	v_mfma_f32_16x16x32_bf16 v[100:103], v[158:161], v[174:177], v[100:103]
	v_mfma_f32_16x16x32_bf16 v[92:95], v[150:153], v[182:185], v[92:95]
	v_mfma_f32_16x16x32_bf16 v[84:87], v[158:161], v[182:185], v[84:87]
	v_mfma_f32_16x16x32_bf16 v[76:79], v[150:153], v[190:193], v[76:79]
	v_mfma_f32_16x16x32_bf16 v[68:71], v[158:161], v[190:193], v[68:71]
	v_mfma_f32_16x16x32_bf16 v[124:127], v[154:157], v[170:173], v[124:127]
	v_mfma_f32_16x16x32_bf16 v[116:119], v[162:165], v[170:173], v[116:119]
	v_mfma_f32_16x16x32_bf16 v[108:111], v[154:157], v[178:181], v[108:111]
	v_mfma_f32_16x16x32_bf16 v[100:103], v[162:165], v[178:181], v[100:103]
	v_mfma_f32_16x16x32_bf16 v[92:95], v[154:157], v[186:189], v[92:95]
	v_mfma_f32_16x16x32_bf16 v[84:87], v[162:165], v[186:189], v[84:87]
	v_mfma_f32_16x16x32_bf16 v[76:79], v[154:157], v[194:197], v[76:79]
	v_mfma_f32_16x16x32_bf16 v[68:71], v[162:165], v[194:197], v[68:71]
	s_setprio 0
	s_barrier
	s_add_i32 s21, 0, 0x1c000
	s_add_i32 s16, s20, s25
	v_add_u32_e32 v214, s21, v146
	s_add_u32 s0, s18, 0x80
	s_addc_u32 s1, s19, 0
	s_mov_b32 m0, s16
	ds_read_b128 v[202:205], v214
	ds_read_b128 v[206:209], v214 offset:1024
	ds_read_b128 v[210:213], v214 offset:2048
	ds_read_b128 v[214:217], v214 offset:3072
	global_load_lds_dwordx4 v132, s[0:1]
	s_add_i32 m0, s16, 0x2000
	s_nop 0
	global_load_lds_dwordx4 v128, s[0:1]
	s_barrier
	s_waitcnt lgkmcnt(0)
	s_setprio 1
	s_waitcnt lgkmcnt(0)
	v_mfma_f32_16x16x32_bf16 v[120:123], v[202:205], v[166:169], v[120:123]
	v_mfma_f32_16x16x32_bf16 v[112:115], v[210:213], v[166:169], v[112:115]
	v_mfma_f32_16x16x32_bf16 v[104:107], v[202:205], v[174:177], v[104:107]
	v_mfma_f32_16x16x32_bf16 v[96:99], v[210:213], v[174:177], v[96:99]
	v_mfma_f32_16x16x32_bf16 v[88:91], v[202:205], v[182:185], v[88:91]
	v_mfma_f32_16x16x32_bf16 v[80:83], v[210:213], v[182:185], v[80:83]
	v_mfma_f32_16x16x32_bf16 v[72:75], v[202:205], v[190:193], v[72:75]
	v_mfma_f32_16x16x32_bf16 v[64:67], v[210:213], v[190:193], v[64:67]
	v_mfma_f32_16x16x32_bf16 v[120:123], v[206:209], v[170:173], v[120:123]
	v_mfma_f32_16x16x32_bf16 v[112:115], v[214:217], v[170:173], v[112:115]
	v_mfma_f32_16x16x32_bf16 v[104:107], v[206:209], v[178:181], v[104:107]
	v_mfma_f32_16x16x32_bf16 v[96:99], v[214:217], v[178:181], v[96:99]
	v_mfma_f32_16x16x32_bf16 v[88:91], v[206:209], v[186:189], v[88:91]
	v_mfma_f32_16x16x32_bf16 v[80:83], v[214:217], v[186:189], v[80:83]
	v_mfma_f32_16x16x32_bf16 v[72:75], v[206:209], v[194:197], v[72:75]
	v_mfma_f32_16x16x32_bf16 v[64:67], v[214:217], v[194:197], v[64:67]
	s_setprio 0
	s_mov_b32 m0, s36
	s_add_u32 s0, s22, 0x80
	s_addc_u32 s1, s23, 0
	s_barrier
	ds_read_b128 v[166:169], v148 offset:49152
	ds_read_b128 v[170:173], v148 offset:50176
	ds_read_b128 v[174:177], v148 offset:51200
	ds_read_b128 v[178:181], v148 offset:52224
	ds_read_b128 v[182:185], v148 offset:53248
	ds_read_b128 v[186:189], v148 offset:54272
	ds_read_b128 v[190:193], v148 offset:55296
	ds_read_b128 v[194:197], v148 offset:56320
	global_load_lds_dwordx4 v134, s[0:1]
	s_mov_b32 m0, s37
	s_nop 0
	global_load_lds_dwordx4 v130, s[0:1]
	s_barrier
; #define PG8_STAGE(bufoff, gbase, voff) do { _Pragma("unroll") for (int _i = 0; _i < 2; ++_i) \
;         __builtin_amdgcn_global_load_lds((const unsigned*)((const char*)(gbase) + (voff)[_i]), (LAS unsigned*)(lds + (bufoff) + ldsw + _i * 8192), 16, 0, 0); } while (0)
; #define PG8_LDA(dst, b, h) do { _Pragma("unroll") for (int m = 0; m < 4; ++m) _Pragma("unroll") for (int k = 0; k < 2; ++k) dst[m][k] = *(const LAS bf16x8*)(lds + PG8_SA(b, h) + aoff + m * 2048 + k * 1024); } while (0)
; #define PG8_WAIT_V(n) asm volatile("s_waitcnt vmcnt(" #n ")" ::: "memory")
; #define PG8_WAIT_L(n) asm volatile("s_waitcnt lgkmcnt(" #n ")" ::: "memory")
; template <class Epi, class Sched>
; __device__ __forceinline__ void gemm_phase(LAS unsigned char* lds, const Gemm g, const Sched& S, const Epi& E) {
;     ...
;         for (int t = 0; t < nt; t += 2) {
;             const bool last = (t == nt - 2);
;             const char* a1 = cA + (size_t)(t + 1) * kstep;
;             const char* a2 = last ? nA : cA + (size_t)(t + 2) * kstep; const char* b2 = last ? nB : cB + (size_t)(t + 2) * kstep;
;             const char* a3 = a2 + kstep; const char* b3 = b2 + kstep;
;             PG8_LDB(B0, 0, 0); PG8_SCHED; PG8_LDA(At, 0, 0); PG8_STAGE(PG8_SA(1, 1), a1 + hstep, voffA);
;             PG8_WAIT_L(8); PG8_BAR; PG8_WAIT_L(0); PG8_MMA(0, 0, At, B0); PG8_BAR; PG8_SCHED;
;             PG8_LDB(B1, 0, 1); PG8_STAGE(PG8_SB(0, 0), b2, voffB);
;             PG8_BAR; PG8_WAIT_L(0); PG8_MMA(0, 1, At, B1); PG8_BAR;
;             PG8_LDA(At, 0, 1); PG8_STAGE(PG8_SA(0, 0), a2, voffA);
;             PG8_BAR; PG8_WAIT_L(0); PG8_MMA(1, 0, At, B0); PG8_BAR; PG8_SCHED;
;             PG8_STAGE(PG8_SB(0, 1), b2 + hstep, voffB);
;             PG8_WAIT_V(6); PG8_BAR; PG8_MMA(1, 1, At, B1); PG8_BAR;
;             PG8_LDB(B0, 1, 0); PG8_SCHED; PG8_LDA(At, 1, 0); PG8_STAGE(PG8_SA(0, 1), a2 + hstep, voffA);
;             PG8_WAIT_L(8); PG8_BAR; PG8_WAIT_L(0); PG8_MMA(0, 0, At, B0); PG8_BAR; PG8_SCHED;
;             PG8_LDB(B1, 1, 1); PG8_STAGE(PG8_SB(1, 0), b3, voffB);
;             PG8_BAR; PG8_WAIT_L(0); PG8_MMA(0, 1, At, B1); PG8_BAR;
;             PG8_LDA(At, 1, 1); PG8_STAGE(PG8_SA(1, 0), a3, voffA);
;             PG8_BAR; PG8_WAIT_L(0); PG8_MMA(1, 0, At, B0); PG8_BAR; PG8_SCHED;
;             PG8_STAGE(PG8_SB(1, 1), b3 + hstep, voffB);
;             PG8_WAIT_V(6); PG8_BAR; PG8_MMA(1, 1, At, B1); PG8_BAR;
	s_waitcnt lgkmcnt(0)
	s_setprio 1
	s_waitcnt lgkmcnt(0)
	v_mfma_f32_16x16x32_bf16 v[60:63], v[150:153], v[166:169], v[60:63]
	v_mfma_f32_16x16x32_bf16 v[56:59], v[158:161], v[166:169], v[56:59]
	v_mfma_f32_16x16x32_bf16 v[44:47], v[150:153], v[174:177], v[44:47]
	v_mfma_f32_16x16x32_bf16 v[40:43], v[158:161], v[174:177], v[40:43]
	v_mfma_f32_16x16x32_bf16 v[28:31], v[150:153], v[182:185], v[28:31]
	v_mfma_f32_16x16x32_bf16 v[24:27], v[158:161], v[182:185], v[24:27]
	v_mfma_f32_16x16x32_bf16 v[12:15], v[150:153], v[190:193], v[12:15]
	v_mfma_f32_16x16x32_bf16 v[8:11], v[158:161], v[190:193], v[8:11]
	v_mfma_f32_16x16x32_bf16 v[60:63], v[154:157], v[170:173], v[60:63]
	v_mfma_f32_16x16x32_bf16 v[56:59], v[162:165], v[170:173], v[56:59]
	v_mfma_f32_16x16x32_bf16 v[44:47], v[154:157], v[178:181], v[44:47]
	v_mfma_f32_16x16x32_bf16 v[40:43], v[162:165], v[178:181], v[40:43]
	v_mfma_f32_16x16x32_bf16 v[28:31], v[154:157], v[186:189], v[28:31]
	v_mfma_f32_16x16x32_bf16 v[24:27], v[162:165], v[186:189], v[24:27]
	v_mfma_f32_16x16x32_bf16 v[12:15], v[154:157], v[194:197], v[12:15]
	v_mfma_f32_16x16x32_bf16 v[8:11], v[162:165], v[194:197], v[8:11]
	s_setprio 0
	s_barrier
	s_add_u32 s16, s18, 0x40080
	s_addc_u32 s17, s19, 0
	s_add_i32 s18, s21, s25
	s_mov_b32 m0, s18
	s_nop 0
	global_load_lds_dwordx4 v132, s[16:17]
	s_add_i32 m0, s18, 0x2000
	s_nop 0
	global_load_lds_dwordx4 v128, s[16:17]
	s_waitcnt vmcnt(6)
	s_barrier
	s_setprio 1
	v_mfma_f32_16x16x32_bf16 v[52:55], v[202:205], v[166:169], v[52:55]
	v_mfma_f32_16x16x32_bf16 v[48:51], v[210:213], v[166:169], v[48:51]
	v_mfma_f32_16x16x32_bf16 v[36:39], v[202:205], v[174:177], v[36:39]
	v_mfma_f32_16x16x32_bf16 v[32:35], v[210:213], v[174:177], v[32:35]
	v_mfma_f32_16x16x32_bf16 v[20:23], v[202:205], v[182:185], v[20:23]
	v_mfma_f32_16x16x32_bf16 v[16:19], v[210:213], v[182:185], v[16:19]
	v_mfma_f32_16x16x32_bf16 v[4:7], v[202:205], v[190:193], v[4:7]
	v_mfma_f32_16x16x32_bf16 v[0:3], v[210:213], v[190:193], v[0:3]
	v_mfma_f32_16x16x32_bf16 v[52:55], v[206:209], v[170:173], v[52:55]
	v_mfma_f32_16x16x32_bf16 v[48:51], v[214:217], v[170:173], v[48:51]
	v_mfma_f32_16x16x32_bf16 v[36:39], v[206:209], v[178:181], v[36:39]
	v_mfma_f32_16x16x32_bf16 v[32:35], v[214:217], v[178:181], v[32:35]
	v_mfma_f32_16x16x32_bf16 v[20:23], v[206:209], v[186:189], v[20:23]
	v_mfma_f32_16x16x32_bf16 v[16:19], v[214:217], v[186:189], v[16:19]
	v_mfma_f32_16x16x32_bf16 v[4:7], v[206:209], v[194:197], v[4:7]
	v_mfma_f32_16x16x32_bf16 v[0:3], v[214:217], v[194:197], v[0:3]
	s_setprio 0
	s_add_i32 s48, s48, 2
	s_add_u32 s14, s14, 0x100
	s_addc_u32 s15, s15, 0
	s_add_u32 s46, s46, 0x100
	s_addc_u32 s47, s47, 0
	s_cmp_gt_u32 s48, 13
	s_barrier
.LBB0_235:
	ds_read_b128 v[150:153], v147
	ds_read_b128 v[154:157], v147 offset:1024
	ds_read_b128 v[158:161], v147 offset:2048
	ds_read_b128 v[162:165], v147 offset:3072
	s_add_u32 s16, s14, 0xfffc0080
	s_addc_u32 s17, s15, -1
	s_cmp_eq_u32 s48, 12
	s_cselect_b32 s23, s7, s17
	s_cselect_b32 s22, s44, s16
	s_cselect_b32 s19, s5, s47
	s_cselect_b32 s18, s45, s46
	s_add_i32 m0, s13, 0xc000
	ds_read_b128 v[166:169], v148
	ds_read_b128 v[170:173], v148 offset:1024
	ds_read_b128 v[174:177], v148 offset:2048
	ds_read_b128 v[178:181], v148 offset:3072
	ds_read_b128 v[182:185], v148 offset:4096
	ds_read_b128 v[186:189], v148 offset:5120
	ds_read_b128 v[190:193], v148 offset:6144
	ds_read_b128 v[194:197], v148 offset:7168
	global_load_lds_dwordx4 v136, s[14:15]
	s_add_i32 m0, s13, 0xe000
	s_nop 0
	global_load_lds_dwordx4 v138, s[14:15]
	s_waitcnt lgkmcnt(8)
	s_barrier
	s_waitcnt lgkmcnt(0)
	s_setprio 1
	s_waitcnt lgkmcnt(0)
	v_mfma_f32_16x16x32_bf16 v[124:127], v[150:153], v[166:169], v[124:127]
	v_mfma_f32_16x16x32_bf16 v[116:119], v[158:161], v[166:169], v[116:119]
	v_mfma_f32_16x16x32_bf16 v[108:111], v[150:153], v[174:177], v[108:111]
	v_mfma_f32_16x16x32_bf16 v[100:103], v[158:161], v[174:177], v[100:103]
	v_mfma_f32_16x16x32_bf16 v[92:95], v[150:153], v[182:185], v[92:95]
	v_mfma_f32_16x16x32_bf16 v[84:87], v[158:161], v[182:185], v[84:87]
	v_mfma_f32_16x16x32_bf16 v[76:79], v[150:153], v[190:193], v[76:79]
	v_mfma_f32_16x16x32_bf16 v[68:71], v[158:161], v[190:193], v[68:71]
	v_mfma_f32_16x16x32_bf16 v[124:127], v[154:157], v[170:173], v[124:127]
	v_mfma_f32_16x16x32_bf16 v[116:119], v[162:165], v[170:173], v[116:119]
	v_mfma_f32_16x16x32_bf16 v[108:111], v[154:157], v[178:181], v[108:111]
	v_mfma_f32_16x16x32_bf16 v[100:103], v[162:165], v[178:181], v[100:103]
	v_mfma_f32_16x16x32_bf16 v[92:95], v[154:157], v[186:189], v[92:95]
	v_mfma_f32_16x16x32_bf16 v[84:87], v[162:165], v[186:189], v[84:87]
	v_mfma_f32_16x16x32_bf16 v[76:79], v[154:157], v[194:197], v[76:79]
	v_mfma_f32_16x16x32_bf16 v[68:71], v[162:165], v[194:197], v[68:71]
	s_setprio 0
	s_barrier
	s_add_i32 s16, s40, s25
	s_mov_b32 m0, s16
	ds_read_b128 v[202:205], v149
	ds_read_b128 v[206:209], v149 offset:1024
	ds_read_b128 v[210:213], v149 offset:2048
	ds_read_b128 v[214:217], v149 offset:3072
	global_load_lds_dwordx4 v132, s[18:19]
	s_add_i32 m0, s16, 0x2000
	s_nop 0
	global_load_lds_dwordx4 v128, s[18:19]
	s_barrier
; #define PG8_STAGE(bufoff, gbase, voff) do { _Pragma("unroll") for (int _i = 0; _i < 2; ++_i) \
;         __builtin_amdgcn_global_load_lds((const unsigned*)((const char*)(gbase) + (voff)[_i]), (LAS unsigned*)(lds + (bufoff) + ldsw + _i * 8192), 16, 0, 0); } while (0)
; #define PG8_LDA(dst, b, h) do { _Pragma("unroll") for (int m = 0; m < 4; ++m) _Pragma("unroll") for (int k = 0; k < 2; ++k) dst[m][k] = *(const LAS bf16x8*)(lds + PG8_SA(b, h) + aoff + m * 2048 + k * 1024); } while (0)
; #define PG8_LDB(dst, b, h) do { _Pragma("unroll") for (int n = 0; n < 2; ++n) _Pragma("unroll") for (int k = 0; k < 2; ++k) dst[n][k] = *(const LAS bf16x8*)(lds + PG8_SB(b, h) + boff + n * 2048 + k * 1024); } while (0)
; #define PG8_MMA(ai, bj, At, Bt) do { __builtin_amdgcn_s_setprio(1); _Pragma("unroll") for (int m = 0; m < 4; ++m) _Pragma("unroll") for (int n = 0; n < 2; ++n) _Pragma("unroll") for (int k = 0; k < 2; ++k) \
;         acc[ai][bj][m][n] = __builtin_amdgcn_mfma_f32_16x16x32_bf16(Bt[n][k], At[m][k], acc[ai][bj][m][n], 0, 0, 0); __builtin_amdgcn_s_setprio(0); } while (0)
; #define PG8_WAIT_V(n) asm volatile("s_waitcnt vmcnt(" #n ")" ::: "memory")
; #define PG8_WAIT_L(n) asm volatile("s_waitcnt lgkmcnt(" #n ")" ::: "memory")
; #define PG8_BAR __builtin_amdgcn_s_barrier()
; #define PG8_SCHED __builtin_amdgcn_sched_barrier(0)
; template <class Epi, class Sched>
; __device__ __forceinline__ void gemm_phase(LAS unsigned char* lds, const Gemm g, const Sched& S, const Epi& E) {
;     ...
;             PG8_BAR; PG8_WAIT_L(0); PG8_MMA(0, 1, At, B1); PG8_BAR;
;             PG8_LDA(At, 0, 1); PG8_STAGE(PG8_SA(0, 0), a2, voffA);
;             PG8_BAR; PG8_WAIT_L(0); PG8_MMA(1, 0, At, B0); PG8_BAR; PG8_SCHED;
;             PG8_STAGE(PG8_SB(0, 1), b2 + hstep, voffB);
;             PG8_WAIT_V(6); PG8_BAR; PG8_MMA(1, 1, At, B1); PG8_BAR;
;             PG8_LDB(B0, 1, 0); PG8_SCHED; PG8_LDA(At, 1, 0); PG8_STAGE(PG8_SA(0, 1), a2 + hstep, voffA);
;             PG8_WAIT_L(8); PG8_BAR; PG8_WAIT_L(0); PG8_MMA(0, 0, At, B0); PG8_BAR; PG8_SCHED;
	s_waitcnt lgkmcnt(0)
	s_setprio 1
	s_waitcnt lgkmcnt(0)
	v_mfma_f32_16x16x32_bf16 v[120:123], v[202:205], v[166:169], v[120:123]
	v_mfma_f32_16x16x32_bf16 v[112:115], v[210:213], v[166:169], v[112:115]
	v_mfma_f32_16x16x32_bf16 v[104:107], v[202:205], v[174:177], v[104:107]
	v_mfma_f32_16x16x32_bf16 v[96:99], v[210:213], v[174:177], v[96:99]
	v_mfma_f32_16x16x32_bf16 v[88:91], v[202:205], v[182:185], v[88:91]
	v_mfma_f32_16x16x32_bf16 v[80:83], v[210:213], v[182:185], v[80:83]
	v_mfma_f32_16x16x32_bf16 v[72:75], v[202:205], v[190:193], v[72:75]
	v_mfma_f32_16x16x32_bf16 v[64:67], v[210:213], v[190:193], v[64:67]
	v_mfma_f32_16x16x32_bf16 v[120:123], v[206:209], v[170:173], v[120:123]
	v_mfma_f32_16x16x32_bf16 v[112:115], v[214:217], v[170:173], v[112:115]
	v_mfma_f32_16x16x32_bf16 v[104:107], v[206:209], v[178:181], v[104:107]
	v_mfma_f32_16x16x32_bf16 v[96:99], v[214:217], v[178:181], v[96:99]
	v_mfma_f32_16x16x32_bf16 v[88:91], v[206:209], v[186:189], v[88:91]
	v_mfma_f32_16x16x32_bf16 v[80:83], v[214:217], v[186:189], v[80:83]
	v_mfma_f32_16x16x32_bf16 v[72:75], v[206:209], v[194:197], v[72:75]
	v_mfma_f32_16x16x32_bf16 v[64:67], v[214:217], v[194:197], v[64:67]
	s_setprio 0
	s_mov_b32 m0, s13
	s_barrier
	ds_read_b128 v[166:169], v148 offset:16384
	ds_read_b128 v[170:173], v148 offset:17408
	ds_read_b128 v[174:177], v148 offset:18432
	ds_read_b128 v[178:181], v148 offset:19456
	ds_read_b128 v[182:185], v148 offset:20480
	ds_read_b128 v[186:189], v148 offset:21504
	ds_read_b128 v[190:193], v148 offset:22528
	ds_read_b128 v[194:197], v148 offset:23552
	global_load_lds_dwordx4 v134, s[22:23]
	s_mov_b32 m0, s28
	s_nop 0
	global_load_lds_dwordx4 v130, s[22:23]
	s_barrier
	s_waitcnt lgkmcnt(0)
	s_setprio 1
	s_waitcnt lgkmcnt(0)
	v_mfma_f32_16x16x32_bf16 v[60:63], v[150:153], v[166:169], v[60:63]
	v_mfma_f32_16x16x32_bf16 v[56:59], v[158:161], v[166:169], v[56:59]
	v_mfma_f32_16x16x32_bf16 v[44:47], v[150:153], v[174:177], v[44:47]
	v_mfma_f32_16x16x32_bf16 v[40:43], v[158:161], v[174:177], v[40:43]
	v_mfma_f32_16x16x32_bf16 v[28:31], v[150:153], v[182:185], v[28:31]
	v_mfma_f32_16x16x32_bf16 v[24:27], v[158:161], v[182:185], v[24:27]
	v_mfma_f32_16x16x32_bf16 v[12:15], v[150:153], v[190:193], v[12:15]
	v_mfma_f32_16x16x32_bf16 v[8:11], v[158:161], v[190:193], v[8:11]
	v_mfma_f32_16x16x32_bf16 v[60:63], v[154:157], v[170:173], v[60:63]
	v_mfma_f32_16x16x32_bf16 v[56:59], v[162:165], v[170:173], v[56:59]
	v_mfma_f32_16x16x32_bf16 v[44:47], v[154:157], v[178:181], v[44:47]
	v_mfma_f32_16x16x32_bf16 v[40:43], v[162:165], v[178:181], v[40:43]
	v_mfma_f32_16x16x32_bf16 v[28:31], v[154:157], v[186:189], v[28:31]
	v_mfma_f32_16x16x32_bf16 v[24:27], v[162:165], v[186:189], v[24:27]
	v_mfma_f32_16x16x32_bf16 v[12:15], v[154:157], v[194:197], v[12:15]
	v_mfma_f32_16x16x32_bf16 v[8:11], v[162:165], v[194:197], v[8:11]
	s_setprio 0
	s_barrier
	s_add_u32 s16, s18, 0x40000
	s_addc_u32 s17, s19, 0
	s_add_i32 s20, s41, s25
	s_mov_b32 m0, s20
	s_nop 0
	global_load_lds_dwordx4 v132, s[16:17]
	s_add_i32 m0, s20, 0x2000
	s_nop 0
	global_load_lds_dwordx4 v128, s[16:17]
	s_waitcnt vmcnt(6)
	s_barrier
	s_setprio 1
	v_mfma_f32_16x16x32_bf16 v[52:55], v[202:205], v[166:169], v[52:55]
	v_mfma_f32_16x16x32_bf16 v[48:51], v[210:213], v[166:169], v[48:51]
	v_mfma_f32_16x16x32_bf16 v[36:39], v[202:205], v[174:177], v[36:39]
	v_mfma_f32_16x16x32_bf16 v[32:35], v[210:213], v[174:177], v[32:35]
	v_mfma_f32_16x16x32_bf16 v[20:23], v[202:205], v[182:185], v[20:23]
	v_mfma_f32_16x16x32_bf16 v[16:19], v[210:213], v[182:185], v[16:19]
	v_mfma_f32_16x16x32_bf16 v[4:7], v[202:205], v[190:193], v[4:7]
	v_mfma_f32_16x16x32_bf16 v[0:3], v[210:213], v[190:193], v[0:3]
	v_mfma_f32_16x16x32_bf16 v[52:55], v[206:209], v[170:173], v[52:55]
	v_mfma_f32_16x16x32_bf16 v[48:51], v[214:217], v[170:173], v[48:51]
	v_mfma_f32_16x16x32_bf16 v[36:39], v[206:209], v[178:181], v[36:39]
	v_mfma_f32_16x16x32_bf16 v[32:35], v[214:217], v[178:181], v[32:35]
	v_mfma_f32_16x16x32_bf16 v[20:23], v[206:209], v[186:189], v[20:23]
	v_mfma_f32_16x16x32_bf16 v[16:19], v[214:217], v[186:189], v[16:19]
	v_mfma_f32_16x16x32_bf16 v[4:7], v[206:209], v[194:197], v[4:7]
	v_mfma_f32_16x16x32_bf16 v[0:3], v[214:217], v[194:197], v[0:3]
	s_setprio 0
	s_add_i32 s20, 0, 0x18000
	v_add_u32_e32 v162, s20, v146
	s_barrier
	ds_read_b128 v[150:153], v162
	ds_read_b128 v[154:157], v162 offset:1024
	ds_read_b128 v[158:161], v162 offset:2048
	ds_read_b128 v[162:165], v162 offset:3072
	s_add_u32 s16, s22, 0x40000
	s_addc_u32 s17, s23, 0
	s_mov_b32 m0, s29
	ds_read_b128 v[166:169], v148 offset:32768
	ds_read_b128 v[170:173], v148 offset:33792
	ds_read_b128 v[174:177], v148 offset:34816
	ds_read_b128 v[178:181], v148 offset:35840
	ds_read_b128 v[182:185], v148 offset:36864
	ds_read_b128 v[186:189], v148 offset:37888
	ds_read_b128 v[190:193], v148 offset:38912
	ds_read_b128 v[194:197], v148 offset:39936
	global_load_lds_dwordx4 v134, s[16:17]
	s_mov_b32 m0, s33
	s_nop 0
	global_load_lds_dwordx4 v130, s[16:17]
	s_waitcnt lgkmcnt(8)
	s_barrier
; #define PG8_STAGE(bufoff, gbase, voff) do { _Pragma("unroll") for (int _i = 0; _i < 2; ++_i) \
;         __builtin_amdgcn_global_load_lds((const unsigned*)((const char*)(gbase) + (voff)[_i]), (LAS unsigned*)(lds + (bufoff) + ldsw + _i * 8192), 16, 0, 0); } while (0)
; #define PG8_LDA(dst, b, h) do { _Pragma("unroll") for (int m = 0; m < 4; ++m) _Pragma("unroll") for (int k = 0; k < 2; ++k) dst[m][k] = *(const LAS bf16x8*)(lds + PG8_SA(b, h) + aoff + m * 2048 + k * 1024); } while (0)
; #define PG8_LDB(dst, b, h) do { _Pragma("unroll") for (int n = 0; n < 2; ++n) _Pragma("unroll") for (int k = 0; k < 2; ++k) dst[n][k] = *(const LAS bf16x8*)(lds + PG8_SB(b, h) + boff + n * 2048 + k * 1024); } while (0)
; #define PG8_MMA(ai, bj, At, Bt) do { __builtin_amdgcn_s_setprio(1); _Pragma("unroll") for (int m = 0; m < 4; ++m) _Pragma("unroll") for (int n = 0; n < 2; ++n) _Pragma("unroll") for (int k = 0; k < 2; ++k) \
;         acc[ai][bj][m][n] = __builtin_amdgcn_mfma_f32_16x16x32_bf16(Bt[n][k], At[m][k], acc[ai][bj][m][n], 0, 0, 0); __builtin_amdgcn_s_setprio(0); } while (0)
; #define PG8_WAIT_V(n) asm volatile("s_waitcnt vmcnt(" #n ")" ::: "memory")
; #define PG8_WAIT_L(n) asm volatile("s_waitcnt lgkmcnt(" #n ")" ::: "memory")
; #define PG8_BAR __builtin_amdgcn_s_barrier()
; #define PG8_SCHED __builtin_amdgcn_sched_barrier(0)
; template <class Epi, class Sched>
; __device__ __forceinline__ void gemm_phase(LAS unsigned char* lds, const Gemm g, const Sched& S, const Epi& E) {
;     ...
;             PG8_WAIT_L(8); PG8_BAR; PG8_WAIT_L(0); PG8_MMA(0, 0, At, B0); PG8_BAR; PG8_SCHED;
;             PG8_LDB(B1, 1, 1); PG8_STAGE(PG8_SB(1, 0), b3, voffB);
;             PG8_BAR; PG8_WAIT_L(0); PG8_MMA(0, 1, At, B1); PG8_BAR;
;             PG8_LDA(At, 1, 1); PG8_STAGE(PG8_SA(1, 0), a3, voffA);
;             PG8_BAR; PG8_WAIT_L(0); PG8_MMA(1, 0, At, B0); PG8_BAR; PG8_SCHED;
;             PG8_STAGE(PG8_SB(1, 1), b3 + hstep, voffB);
;             PG8_WAIT_V(6); PG8_BAR; PG8_MMA(1, 1, At, B1); PG8_BAR;
	s_waitcnt lgkmcnt(0)
	s_setprio 1
	s_waitcnt lgkmcnt(0)
	v_mfma_f32_16x16x32_bf16 v[124:127], v[150:153], v[166:169], v[124:127]
	v_mfma_f32_16x16x32_bf16 v[116:119], v[158:161], v[166:169], v[116:119]
	v_mfma_f32_16x16x32_bf16 v[108:111], v[150:153], v[174:177], v[108:111]
	v_mfma_f32_16x16x32_bf16 v[100:103], v[158:161], v[174:177], v[100:103]
	v_mfma_f32_16x16x32_bf16 v[92:95], v[150:153], v[182:185], v[92:95]
	v_mfma_f32_16x16x32_bf16 v[84:87], v[158:161], v[182:185], v[84:87]
	v_mfma_f32_16x16x32_bf16 v[76:79], v[150:153], v[190:193], v[76:79]
	v_mfma_f32_16x16x32_bf16 v[68:71], v[158:161], v[190:193], v[68:71]
	v_mfma_f32_16x16x32_bf16 v[124:127], v[154:157], v[170:173], v[124:127]
	v_mfma_f32_16x16x32_bf16 v[116:119], v[162:165], v[170:173], v[116:119]
	v_mfma_f32_16x16x32_bf16 v[108:111], v[154:157], v[178:181], v[108:111]
	v_mfma_f32_16x16x32_bf16 v[100:103], v[162:165], v[178:181], v[100:103]
	v_mfma_f32_16x16x32_bf16 v[92:95], v[154:157], v[186:189], v[92:95]
	v_mfma_f32_16x16x32_bf16 v[84:87], v[162:165], v[186:189], v[84:87]
	v_mfma_f32_16x16x32_bf16 v[76:79], v[154:157], v[194:197], v[76:79]
	v_mfma_f32_16x16x32_bf16 v[68:71], v[162:165], v[194:197], v[68:71]
	s_setprio 0
	s_barrier
	s_add_i32 s21, 0, 0x1c000
	s_add_i32 s16, s20, s25
	v_add_u32_e32 v214, s21, v146
	s_add_u32 s0, s18, 0x80
	s_addc_u32 s1, s19, 0
	s_mov_b32 m0, s16
	ds_read_b128 v[202:205], v214
	ds_read_b128 v[206:209], v214 offset:1024
	ds_read_b128 v[210:213], v214 offset:2048
	ds_read_b128 v[214:217], v214 offset:3072
	global_load_lds_dwordx4 v132, s[0:1]
	s_add_i32 m0, s16, 0x2000
	s_nop 0
	global_load_lds_dwordx4 v128, s[0:1]
	s_barrier
	s_waitcnt lgkmcnt(0)
	s_setprio 1
	s_waitcnt lgkmcnt(0)
	v_mfma_f32_16x16x32_bf16 v[120:123], v[202:205], v[166:169], v[120:123]
	v_mfma_f32_16x16x32_bf16 v[112:115], v[210:213], v[166:169], v[112:115]
	v_mfma_f32_16x16x32_bf16 v[104:107], v[202:205], v[174:177], v[104:107]
	v_mfma_f32_16x16x32_bf16 v[96:99], v[210:213], v[174:177], v[96:99]
	v_mfma_f32_16x16x32_bf16 v[88:91], v[202:205], v[182:185], v[88:91]
	v_mfma_f32_16x16x32_bf16 v[80:83], v[210:213], v[182:185], v[80:83]
	v_mfma_f32_16x16x32_bf16 v[72:75], v[202:205], v[190:193], v[72:75]
	v_mfma_f32_16x16x32_bf16 v[64:67], v[210:213], v[190:193], v[64:67]
	v_mfma_f32_16x16x32_bf16 v[120:123], v[206:209], v[170:173], v[120:123]
	v_mfma_f32_16x16x32_bf16 v[112:115], v[214:217], v[170:173], v[112:115]
	v_mfma_f32_16x16x32_bf16 v[104:107], v[206:209], v[178:181], v[104:107]
	v_mfma_f32_16x16x32_bf16 v[96:99], v[214:217], v[178:181], v[96:99]
	v_mfma_f32_16x16x32_bf16 v[88:91], v[206:209], v[186:189], v[88:91]
	v_mfma_f32_16x16x32_bf16 v[80:83], v[214:217], v[186:189], v[80:83]
	v_mfma_f32_16x16x32_bf16 v[72:75], v[206:209], v[194:197], v[72:75]
	v_mfma_f32_16x16x32_bf16 v[64:67], v[214:217], v[194:197], v[64:67]
	s_setprio 0
	s_mov_b32 m0, s36
	s_add_u32 s0, s22, 0x80
	s_addc_u32 s1, s23, 0
	s_barrier
	ds_read_b128 v[166:169], v148 offset:49152
	ds_read_b128 v[170:173], v148 offset:50176
	ds_read_b128 v[174:177], v148 offset:51200
	ds_read_b128 v[178:181], v148 offset:52224
	ds_read_b128 v[182:185], v148 offset:53248
	ds_read_b128 v[186:189], v148 offset:54272
	ds_read_b128 v[190:193], v148 offset:55296
	ds_read_b128 v[194:197], v148 offset:56320
	global_load_lds_dwordx4 v134, s[0:1]
	s_mov_b32 m0, s37
	s_nop 0
	global_load_lds_dwordx4 v130, s[0:1]
	s_barrier
	s_waitcnt lgkmcnt(0)
	s_setprio 1
	s_waitcnt lgkmcnt(0)
	v_mfma_f32_16x16x32_bf16 v[60:63], v[150:153], v[166:169], v[60:63]
	v_mfma_f32_16x16x32_bf16 v[56:59], v[158:161], v[166:169], v[56:59]
	v_mfma_f32_16x16x32_bf16 v[44:47], v[150:153], v[174:177], v[44:47]
	v_mfma_f32_16x16x32_bf16 v[40:43], v[158:161], v[174:177], v[40:43]
	v_mfma_f32_16x16x32_bf16 v[28:31], v[150:153], v[182:185], v[28:31]
	v_mfma_f32_16x16x32_bf16 v[24:27], v[158:161], v[182:185], v[24:27]
	v_mfma_f32_16x16x32_bf16 v[12:15], v[150:153], v[190:193], v[12:15]
	v_mfma_f32_16x16x32_bf16 v[8:11], v[158:161], v[190:193], v[8:11]
	v_mfma_f32_16x16x32_bf16 v[60:63], v[154:157], v[170:173], v[60:63]
	v_mfma_f32_16x16x32_bf16 v[56:59], v[162:165], v[170:173], v[56:59]
	v_mfma_f32_16x16x32_bf16 v[44:47], v[154:157], v[178:181], v[44:47]
	v_mfma_f32_16x16x32_bf16 v[40:43], v[162:165], v[178:181], v[40:43]
	v_mfma_f32_16x16x32_bf16 v[28:31], v[154:157], v[186:189], v[28:31]
	v_mfma_f32_16x16x32_bf16 v[24:27], v[162:165], v[186:189], v[24:27]
	v_mfma_f32_16x16x32_bf16 v[12:15], v[154:157], v[194:197], v[12:15]
	v_mfma_f32_16x16x32_bf16 v[8:11], v[162:165], v[194:197], v[8:11]
	s_setprio 0
	s_barrier
	s_add_u32 s16, s18, 0x40080
	s_addc_u32 s17, s19, 0
	s_add_i32 s18, s21, s25
	s_mov_b32 m0, s18
	s_nop 0
	global_load_lds_dwordx4 v132, s[16:17]
	s_add_i32 m0, s18, 0x2000
	s_nop 0
	global_load_lds_dwordx4 v128, s[16:17]
	s_waitcnt vmcnt(6)
	s_barrier
	s_setprio 1
	v_mfma_f32_16x16x32_bf16 v[52:55], v[202:205], v[166:169], v[52:55]
	v_mfma_f32_16x16x32_bf16 v[48:51], v[210:213], v[166:169], v[48:51]
	v_mfma_f32_16x16x32_bf16 v[36:39], v[202:205], v[174:177], v[36:39]
	v_mfma_f32_16x16x32_bf16 v[32:35], v[210:213], v[174:177], v[32:35]
	v_mfma_f32_16x16x32_bf16 v[20:23], v[202:205], v[182:185], v[20:23]
	v_mfma_f32_16x16x32_bf16 v[16:19], v[210:213], v[182:185], v[16:19]
	v_mfma_f32_16x16x32_bf16 v[4:7], v[202:205], v[190:193], v[4:7]
	v_mfma_f32_16x16x32_bf16 v[0:3], v[210:213], v[190:193], v[0:3]
	v_mfma_f32_16x16x32_bf16 v[52:55], v[206:209], v[170:173], v[52:55]
	v_mfma_f32_16x16x32_bf16 v[48:51], v[214:217], v[170:173], v[48:51]
	v_mfma_f32_16x16x32_bf16 v[36:39], v[206:209], v[178:181], v[36:39]
	v_mfma_f32_16x16x32_bf16 v[32:35], v[214:217], v[178:181], v[32:35]
	v_mfma_f32_16x16x32_bf16 v[20:23], v[206:209], v[186:189], v[20:23]
	v_mfma_f32_16x16x32_bf16 v[16:19], v[214:217], v[186:189], v[16:19]
	v_mfma_f32_16x16x32_bf16 v[4:7], v[206:209], v[194:197], v[4:7]
	v_mfma_f32_16x16x32_bf16 v[0:3], v[214:217], v[194:197], v[0:3]
	s_setprio 0
	s_add_i32 s48, s48, 2
	s_add_u32 s14, s14, 0x100
	s_addc_u32 s15, s15, 0
	s_add_u32 s46, s46, 0x100
	s_addc_u32 s47, s47, 0
	s_cmp_gt_u32 s48, 13
	s_barrier
; __device__ __forceinline__ unsigned cvt_pk_bf16(float lo, float hi) { unsigned r; asm volatile("v_cvt_pk_bf16_f32 %0, %1, %2" : "=v"(r) : "v"(lo), "v"(hi)); return r; }
; __device__ __forceinline__ float silu_f(float a) { return a * __builtin_amdgcn_rcpf(1.0f + __expf(-a)); }
; #define PG8_MMA(ai, bj, At, Bt) do { __builtin_amdgcn_s_setprio(1); _Pragma("unroll") for (int m = 0; m < 4; ++m) _Pragma("unroll") for (int n = 0; n < 2; ++n) _Pragma("unroll") for (int k = 0; k < 2; ++k) \
;         acc[ai][bj][m][n] = __builtin_amdgcn_mfma_f32_16x16x32_bf16(Bt[n][k], At[m][k], acc[ai][bj][m][n], 0, 0, 0); __builtin_amdgcn_s_setprio(0); } while (0)
; #define PG8_WAIT_V(n) asm volatile("s_waitcnt vmcnt(" #n ")" ::: "memory")
; #define PG8_BAR __builtin_amdgcn_s_barrier()
; template <class Epi, class Sched>
; __device__ __forceinline__ void gemm_phase(LAS unsigned char* lds, const Gemm g, const Sched& S, const Epi& E) {
;     ...
;             PG8_WAIT_V(6); PG8_BAR; PG8_MMA(1, 1, At, B1); PG8_BAR;
;         }
;         E(acc, cur, wr, wc, fr, fq);
;     __device__ __forceinline__ void operator()(const AccT& acc, const Unit& u, int wr, int wc, int fr, int fq) const {
;     ...
;         const int row0 = u.pm * 256 + wr * 64 + fr, hc0 = u.pn * 128 + wc * 32 + 8 * fq;
; #pragma unroll
;         for (int ai = 0; ai < 2; ++ai)
; #pragma unroll
;             for (int m = 0; m < 4; ++m) {
;                 const f32x4 a0 = acc[ai][0][m][0], a1 = acc[ai][0][m][1], b0 = acc[ai][1][m][0], b1 = acc[ai][1][m][1];
;                 u32x4 w;
;                 w.x = cvt_pk_bf16(silu_f(a0[0]) * b0[0], silu_f(a0[1]) * b0[1]); w.y = cvt_pk_bf16(silu_f(a0[2]) * b0[2], silu_f(a0[3]) * b0[3]);
;                 w.z = cvt_pk_bf16(silu_f(a1[0]) * b1[0], silu_f(a1[1]) * b1[1]); w.w = cvt_pk_bf16(silu_f(a1[2]) * b1[2], silu_f(a1[3]) * b1[3]);
;                 *(u32x4*)(H + (size_t)(row0 + ai * 128 + m * 16) * DFF + hc0) = w;
	s_cbranch_scc0 .LBB0_235
	v_mul_f32_e32 v152, 0xbfb8aa3b, v124
	v_mov_b32_e32 v151, v145
	v_mov_b32_e32 v150, v144
	s_lshl_b32 s5, s12, 8
	v_exp_f32_e32 v153, v152
	v_mul_f32_e32 v152, 0xbfb8aa3b, v125
	s_add_i32 s5, s5, s34
	v_exp_f32_e32 v154, v152
	v_add_u32_e32 v150, s5, v150
	s_lshl_b32 s5, s43, 7
	s_or_b32 s5, s5, s35
	v_lshl_add_u32 v152, v151, 3, s5
	v_add_f32_e32 v151, 1.0, v153
	v_rcp_f32_e32 v151, v151
	v_add_f32_e32 v153, 1.0, v154
	v_rcp_f32_e32 v154, v153
	v_ashrrev_i32_e32 v153, 31, v152
	v_mul_f32_e32 v124, v124, v151
	v_mul_f32_e32 v120, v124, v120
	v_mul_f32_e32 v124, v125, v154
	v_mul_f32_e32 v125, 0xbfb8aa3b, v126
	v_exp_f32_e32 v125, v125
	v_mul_f32_e32 v151, 0xbfb8aa3b, v127
	v_exp_f32_e32 v151, v151
	v_mul_f32_e32 v121, v124, v121
	v_add_f32_e32 v124, 1.0, v125
	v_rcp_f32_e32 v124, v124
	v_add_f32_e32 v125, 1.0, v151
	v_rcp_f32_e32 v125, v125
	v_cvt_pk_bf16_f32 v120, v120, v121
	v_mul_f32_e32 v121, v126, v124
	v_mul_f32_e32 v124, 0xbfb8aa3b, v116
	v_mul_f32_e32 v121, v121, v122
	v_mul_f32_e32 v122, v127, v125
	v_exp_f32_e32 v124, v124
	v_mul_f32_e32 v125, 0xbfb8aa3b, v117
	v_exp_f32_e32 v125, v125
	v_mul_f32_e32 v122, v122, v123
	v_add_f32_e32 v123, 1.0, v124
	v_rcp_f32_e32 v123, v123
	v_add_f32_e32 v124, 1.0, v125
	v_rcp_f32_e32 v124, v124
	v_cvt_pk_bf16_f32 v121, v121, v122
	v_mul_f32_e32 v116, v116, v123
	v_mul_f32_e32 v112, v116, v112
	v_mul_f32_e32 v116, v117, v124
	v_mul_f32_e32 v117, 0xbfb8aa3b, v118
	v_exp_f32_e32 v117, v117
	v_mul_f32_e32 v122, 0xbfb8aa3b, v119
	v_exp_f32_e32 v122, v122
	v_mul_f32_e32 v113, v116, v113
	v_add_f32_e32 v116, 1.0, v117
	v_rcp_f32_e32 v116, v116
	v_add_f32_e32 v117, 1.0, v122
	v_rcp_f32_e32 v117, v117
	v_cvt_pk_bf16_f32 v122, v112, v113
	v_mul_f32_e32 v112, v118, v116
	v_mul_f32_e32 v118, 0xbfb8aa3b, v108
	v_mul_f32_e32 v113, v119, v117
	v_exp_f32_e32 v118, v118
	v_mul_f32_e32 v119, 0xbfb8aa3b, v109
	v_exp_f32_e32 v119, v119
	v_mul_f32_e32 v112, v112, v114
	v_add_f32_e32 v118, 1.0, v118
	v_rcp_f32_e32 v118, v118
	v_add_f32_e32 v119, 1.0, v119
	v_rcp_f32_e32 v119, v119
	v_mul_f32_e32 v113, v113, v115
	v_cvt_pk_bf16_f32 v123, v112, v113
	v_mov_b64_e32 v[112:113], s[82:83]
	v_mad_i64_i32 v[116:117], s[14:15], v150, s42, v[112:113]
	v_lshlrev_b64 v[114:115], 1, v[152:153]
	v_mul_f32_e32 v108, v108, v118
	v_lshl_add_u64 v[116:117], v[116:117], 0, v[114:115]
	v_mul_f32_e32 v104, v108, v104
	v_mul_f32_e32 v108, v109, v119
	v_mul_f32_e32 v109, 0xbfb8aa3b, v110
	global_store_dwordx4 v[116:117], v[120:123], off
	v_exp_f32_e32 v109, v109
	v_mul_f32_e32 v116, 0xbfb8aa3b, v111
	v_exp_f32_e32 v116, v116
	v_mul_f32_e32 v105, v108, v105
	v_add_f32_e32 v108, 1.0, v109
	v_rcp_f32_e32 v108, v108
	v_add_f32_e32 v109, 1.0, v116
	v_rcp_f32_e32 v109, v109
	v_cvt_pk_bf16_f32 v104, v104, v105
	v_mul_f32_e32 v105, v110, v108
	v_mul_f32_e32 v108, 0xbfb8aa3b, v100
	v_mul_f32_e32 v105, v105, v106
	v_mul_f32_e32 v106, v111, v109
	v_exp_f32_e32 v108, v108
	v_mul_f32_e32 v109, 0xbfb8aa3b, v101
	v_exp_f32_e32 v109, v109
	v_mul_f32_e32 v106, v106, v107
	v_add_f32_e32 v107, 1.0, v108
	v_rcp_f32_e32 v107, v107
	v_add_f32_e32 v108, 1.0, v109
	v_rcp_f32_e32 v108, v108
	v_cvt_pk_bf16_f32 v105, v105, v106
	v_mul_f32_e32 v100, v100, v107
	v_mul_f32_e32 v96, v100, v96
	v_mul_f32_e32 v100, v101, v108
	v_mul_f32_e32 v101, 0xbfb8aa3b, v102
	v_exp_f32_e32 v101, v101
	v_mul_f32_e32 v106, 0xbfb8aa3b, v103
	v_exp_f32_e32 v106, v106
	v_mul_f32_e32 v97, v100, v97
	v_add_f32_e32 v100, 1.0, v101
	v_rcp_f32_e32 v100, v100
	v_add_f32_e32 v101, 1.0, v106
	v_rcp_f32_e32 v101, v101
	v_cvt_pk_bf16_f32 v106, v96, v97
	v_mul_f32_e32 v96, v102, v100
	v_mul_f32_e32 v96, v96, v98
	v_mul_f32_e32 v97, v103, v101
	v_mul_f32_e32 v98, 0xbfb8aa3b, v92
	v_mul_f32_e32 v97, v97, v99
	v_exp_f32_e32 v98, v98
	v_mul_f32_e32 v99, 0xbfb8aa3b, v93
	v_exp_f32_e32 v99, v99
	v_cvt_pk_bf16_f32 v107, v96, v97
	v_add_f32_e32 v98, 1.0, v98
	v_rcp_f32_e32 v98, v98
	v_add_f32_e32 v99, 1.0, v99
	v_rcp_f32_e32 v99, v99
	v_add_u32_e32 v96, 16, v150
	v_mad_i64_i32 v[96:97], s[14:15], v96, s42, v[112:113]
	v_mul_f32_e32 v92, v92, v98
	v_lshl_add_u64 v[96:97], v[96:97], 0, v[114:115]
	v_mul_f32_e32 v88, v92, v88
	v_mul_f32_e32 v92, v93, v99
	v_mul_f32_e32 v93, 0xbfb8aa3b, v94
	global_store_dwordx4 v[96:97], v[104:107], off
	v_exp_f32_e32 v93, v93
	v_mul_f32_e32 v96, 0xbfb8aa3b, v95
	v_exp_f32_e32 v96, v96
	v_mul_f32_e32 v89, v92, v89
	v_add_f32_e32 v92, 1.0, v93
	v_rcp_f32_e32 v92, v92
	v_add_f32_e32 v93, 1.0, v96
	v_rcp_f32_e32 v93, v93
	v_cvt_pk_bf16_f32 v88, v88, v89
	v_mul_f32_e32 v89, v94, v92
	v_mul_f32_e32 v92, 0xbfb8aa3b, v84
	v_mul_f32_e32 v89, v89, v90
	v_mul_f32_e32 v90, v95, v93
	v_exp_f32_e32 v92, v92
	v_mul_f32_e32 v93, 0xbfb8aa3b, v85
	v_exp_f32_e32 v93, v93
	v_mul_f32_e32 v90, v90, v91
	v_add_f32_e32 v91, 1.0, v92
	v_rcp_f32_e32 v91, v91
	v_add_f32_e32 v92, 1.0, v93
	v_rcp_f32_e32 v92, v92
	v_cvt_pk_bf16_f32 v89, v89, v90
	v_mul_f32_e32 v84, v84, v91
	v_mul_f32_e32 v80, v84, v80
	v_mul_f32_e32 v84, v85, v92
	v_mul_f32_e32 v85, 0xbfb8aa3b, v86
	v_exp_f32_e32 v85, v85
	v_mul_f32_e32 v90, 0xbfb8aa3b, v87
	v_exp_f32_e32 v90, v90
	v_mul_f32_e32 v81, v84, v81
	v_add_f32_e32 v84, 1.0, v85
	v_rcp_f32_e32 v84, v84
	v_add_f32_e32 v85, 1.0, v90
	v_rcp_f32_e32 v85, v85
	v_cvt_pk_bf16_f32 v90, v80, v81
	v_mul_f32_e32 v80, v86, v84
	v_mul_f32_e32 v80, v80, v82
	v_mul_f32_e32 v81, v87, v85
	v_mul_f32_e32 v82, 0xbfb8aa3b, v76
	v_mul_f32_e32 v81, v81, v83
	v_exp_f32_e32 v82, v82
	v_mul_f32_e32 v83, 0xbfb8aa3b, v77
	v_exp_f32_e32 v83, v83
	v_cvt_pk_bf16_f32 v91, v80, v81
	v_add_f32_e32 v82, 1.0, v82
	v_rcp_f32_e32 v82, v82
	v_add_f32_e32 v83, 1.0, v83
	v_rcp_f32_e32 v83, v83
; __device__ __forceinline__ unsigned cvt_pk_bf16(float lo, float hi) { unsigned r; asm volatile("v_cvt_pk_bf16_f32 %0, %1, %2" : "=v"(r) : "v"(lo), "v"(hi)); return r; }
; __device__ __forceinline__ float silu_f(float a) { return a * __builtin_amdgcn_rcpf(1.0f + __expf(-a)); }
;     __device__ __forceinline__ void operator()(const AccT& acc, const Unit& u, int wr, int wc, int fr, int fq) const {
;     ...
;         const int row0 = u.pm * 256 + wr * 64 + fr, hc0 = u.pn * 128 + wc * 32 + 8 * fq;
; #pragma unroll
;         for (int ai = 0; ai < 2; ++ai)
; #pragma unroll
;             for (int m = 0; m < 4; ++m) {
;                 const f32x4 a0 = acc[ai][0][m][0], a1 = acc[ai][0][m][1], b0 = acc[ai][1][m][0], b1 = acc[ai][1][m][1];
;                 u32x4 w;
;                 w.x = cvt_pk_bf16(silu_f(a0[0]) * b0[0], silu_f(a0[1]) * b0[1]); w.y = cvt_pk_bf16(silu_f(a0[2]) * b0[2], silu_f(a0[3]) * b0[3]);
;                 w.z = cvt_pk_bf16(silu_f(a1[0]) * b1[0], silu_f(a1[1]) * b1[1]); w.w = cvt_pk_bf16(silu_f(a1[2]) * b1[2], silu_f(a1[3]) * b1[3]);
;                 *(u32x4*)(H + (size_t)(row0 + ai * 128 + m * 16) * DFF + hc0) = w;
	v_add_u32_e32 v80, 32, v150
	v_mad_i64_i32 v[80:81], s[14:15], v80, s42, v[112:113]
	v_mul_f32_e32 v76, v76, v82
	v_lshl_add_u64 v[80:81], v[80:81], 0, v[114:115]
	v_mul_f32_e32 v72, v76, v72
	v_mul_f32_e32 v76, v77, v83
	v_mul_f32_e32 v77, 0xbfb8aa3b, v78
	global_store_dwordx4 v[80:81], v[88:91], off
	v_exp_f32_e32 v77, v77
	v_mul_f32_e32 v80, 0xbfb8aa3b, v79
	v_exp_f32_e32 v80, v80
	v_mul_f32_e32 v73, v76, v73
	v_add_f32_e32 v76, 1.0, v77
	v_rcp_f32_e32 v76, v76
	v_add_f32_e32 v77, 1.0, v80
	v_rcp_f32_e32 v77, v77
	v_cvt_pk_bf16_f32 v72, v72, v73
	v_mul_f32_e32 v73, v78, v76
	v_mul_f32_e32 v76, 0xbfb8aa3b, v68
	v_mul_f32_e32 v73, v73, v74
	v_mul_f32_e32 v74, v79, v77
	v_exp_f32_e32 v76, v76
	v_mul_f32_e32 v77, 0xbfb8aa3b, v69
	v_exp_f32_e32 v77, v77
	v_mul_f32_e32 v74, v74, v75
	v_add_f32_e32 v75, 1.0, v76
	v_rcp_f32_e32 v75, v75
	v_add_f32_e32 v76, 1.0, v77
	v_rcp_f32_e32 v76, v76
	v_cvt_pk_bf16_f32 v73, v73, v74
	v_mul_f32_e32 v68, v68, v75
	v_mul_f32_e32 v64, v68, v64
	v_mul_f32_e32 v68, v69, v76
	v_mul_f32_e32 v69, 0xbfb8aa3b, v70
	v_exp_f32_e32 v69, v69
	v_mul_f32_e32 v74, 0xbfb8aa3b, v71
	v_exp_f32_e32 v74, v74
	v_mul_f32_e32 v65, v68, v65
	v_add_f32_e32 v68, 1.0, v69
	v_rcp_f32_e32 v68, v68
	v_add_f32_e32 v69, 1.0, v74
	v_rcp_f32_e32 v69, v69
	v_cvt_pk_bf16_f32 v74, v64, v65
	v_mul_f32_e32 v64, v70, v68
	v_mul_f32_e32 v64, v64, v66
	v_mul_f32_e32 v65, v71, v69
	v_mul_f32_e32 v66, 0xbfb8aa3b, v60
	v_mul_f32_e32 v65, v65, v67
	v_exp_f32_e32 v66, v66
	v_mul_f32_e32 v67, 0xbfb8aa3b, v61
	v_cvt_pk_bf16_f32 v75, v64, v65
	v_add_u32_e32 v64, 48, v150
	v_exp_f32_e32 v67, v67
	v_mad_i64_i32 v[64:65], s[14:15], v64, s42, v[112:113]
	v_lshl_add_u64 v[64:65], v[64:65], 0, v[114:115]
	global_store_dwordx4 v[64:65], v[72:75], off
	v_add_f32_e32 v64, 1.0, v66
	v_rcp_f32_e32 v64, v64
	v_add_f32_e32 v65, 1.0, v67
	v_rcp_f32_e32 v65, v65
	v_add_u32_e32 v66, 0x80, v150
	v_mul_f32_e32 v60, v60, v64
	v_mul_f32_e32 v52, v60, v52
	v_mul_f32_e32 v60, v61, v65
	v_mul_f32_e32 v61, 0xbfb8aa3b, v62
	v_exp_f32_e32 v61, v61
	v_mul_f32_e32 v64, 0xbfb8aa3b, v63
	v_exp_f32_e32 v64, v64
	v_mul_f32_e32 v53, v60, v53
	v_add_f32_e32 v60, 1.0, v61
	v_rcp_f32_e32 v60, v60
	v_add_f32_e32 v61, 1.0, v64
	v_rcp_f32_e32 v61, v61
	v_cvt_pk_bf16_f32 v52, v52, v53
	v_mul_f32_e32 v53, v62, v60
	v_mul_f32_e32 v60, 0xbfb8aa3b, v56
	v_exp_f32_e32 v60, v60
	v_mul_f32_e32 v53, v53, v54
	v_mul_f32_e32 v54, v63, v61
	v_mul_f32_e32 v61, 0xbfb8aa3b, v57
	v_exp_f32_e32 v61, v61
	v_mul_f32_e32 v54, v54, v55
	v_add_f32_e32 v55, 1.0, v60
	v_rcp_f32_e32 v55, v55
	v_add_f32_e32 v60, 1.0, v61
	v_rcp_f32_e32 v60, v60
	v_cvt_pk_bf16_f32 v53, v53, v54
	v_mul_f32_e32 v54, v56, v55
	v_mul_f32_e32 v55, 0xbfb8aa3b, v58
	v_exp_f32_e32 v55, v55
	v_mul_f32_e32 v56, 0xbfb8aa3b, v59
	v_exp_f32_e32 v56, v56
	v_mul_f32_e32 v48, v54, v48
	v_mul_f32_e32 v54, v57, v60
	v_mul_f32_e32 v49, v54, v49
	v_add_f32_e32 v54, 1.0, v55
	v_rcp_f32_e32 v55, v54
	v_add_f32_e32 v54, 1.0, v56
	v_rcp_f32_e32 v56, v54
	v_cvt_pk_bf16_f32 v54, v48, v49
	v_mul_f32_e32 v48, v58, v55
	v_mul_f32_e32 v48, v48, v50
	v_mul_f32_e32 v49, v59, v56
	v_mul_f32_e32 v50, 0xbfb8aa3b, v44
	v_mul_f32_e32 v49, v49, v51
	v_exp_f32_e32 v50, v50
	v_mul_f32_e32 v51, 0xbfb8aa3b, v45
	v_exp_f32_e32 v51, v51
	v_cvt_pk_bf16_f32 v55, v48, v49
	v_add_f32_e32 v50, 1.0, v50
	v_rcp_f32_e32 v50, v50
	v_add_f32_e32 v51, 1.0, v51
	v_rcp_f32_e32 v51, v51
	v_mad_i64_i32 v[48:49], s[14:15], v66, s42, v[112:113]
	v_mul_f32_e32 v44, v44, v50
	v_mul_f32_e32 v36, v44, v36
	v_mul_f32_e32 v44, v45, v51
	v_mul_f32_e32 v45, 0xbfb8aa3b, v46
	v_exp_f32_e32 v45, v45
	v_lshl_add_u64 v[48:49], v[48:49], 0, v[114:115]
	global_store_dwordx4 v[48:49], v[52:55], off
	v_mul_f32_e32 v48, 0xbfb8aa3b, v47
	v_exp_f32_e32 v48, v48
	v_mul_f32_e32 v37, v44, v37
	v_add_f32_e32 v44, 1.0, v45
	v_rcp_f32_e32 v44, v44
	v_add_f32_e32 v45, 1.0, v48
	v_rcp_f32_e32 v45, v45
	v_cvt_pk_bf16_f32 v36, v36, v37
	v_mul_f32_e32 v37, v46, v44
	v_mul_f32_e32 v44, 0xbfb8aa3b, v40
	v_exp_f32_e32 v44, v44
	v_mul_f32_e32 v37, v37, v38
	v_mul_f32_e32 v38, v47, v45
	v_mul_f32_e32 v45, 0xbfb8aa3b, v41
	v_exp_f32_e32 v45, v45
	v_mul_f32_e32 v38, v38, v39
	v_add_f32_e32 v39, 1.0, v44
	v_rcp_f32_e32 v39, v39
	v_add_f32_e32 v44, 1.0, v45
	v_rcp_f32_e32 v44, v44
; __device__ __forceinline__ unsigned cvt_pk_bf16(float lo, float hi) { unsigned r; asm volatile("v_cvt_pk_bf16_f32 %0, %1, %2" : "=v"(r) : "v"(lo), "v"(hi)); return r; }
; __device__ __forceinline__ float silu_f(float a) { return a * __builtin_amdgcn_rcpf(1.0f + __expf(-a)); }
; template <class Epi, class Sched>
; __device__ __forceinline__ void gemm_phase(LAS unsigned char* lds, const Gemm g, const Sched& S, const Epi& E) {
;     ...
;         if (!has_next) break;
; #pragma unroll
;         for (int a = 0; a < 2; ++a)
; #pragma unroll
;             for (int b = 0; b < 2; ++b)
; #pragma unroll
;                 for (int m = 0; m < 4; ++m)
; #pragma unroll
;                     for (int n = 0; n < 2; ++n) acc[a][b][m][n] = (f32x4){0.f, 0.f, 0.f, 0.f};
;         cur = nxt; cA = nA; cB = nB; ++ui;
;     __device__ __forceinline__ void operator()(const AccT& acc, const Unit& u, int wr, int wc, int fr, int fq) const {
;     ...
;                 const f32x4 a0 = acc[ai][0][m][0], a1 = acc[ai][0][m][1], b0 = acc[ai][1][m][0], b1 = acc[ai][1][m][1];
;                 u32x4 w;
;                 w.x = cvt_pk_bf16(silu_f(a0[0]) * b0[0], silu_f(a0[1]) * b0[1]); w.y = cvt_pk_bf16(silu_f(a0[2]) * b0[2], silu_f(a0[3]) * b0[3]);
;                 w.z = cvt_pk_bf16(silu_f(a1[0]) * b1[0], silu_f(a1[1]) * b1[1]); w.w = cvt_pk_bf16(silu_f(a1[2]) * b1[2], silu_f(a1[3]) * b1[3]);
;                 *(u32x4*)(H + (size_t)(row0 + ai * 128 + m * 16) * DFF + hc0) = w;
	v_cvt_pk_bf16_f32 v37, v37, v38
	v_mul_f32_e32 v38, v40, v39
	v_mul_f32_e32 v39, 0xbfb8aa3b, v42
	v_exp_f32_e32 v39, v39
	v_mul_f32_e32 v40, 0xbfb8aa3b, v43
	v_exp_f32_e32 v40, v40
	v_mul_f32_e32 v32, v38, v32
	v_mul_f32_e32 v38, v41, v44
	v_mul_f32_e32 v33, v38, v33
	v_add_f32_e32 v38, 1.0, v39
	v_rcp_f32_e32 v39, v38
	v_add_f32_e32 v38, 1.0, v40
	v_rcp_f32_e32 v40, v38
	v_cvt_pk_bf16_f32 v38, v32, v33
	v_mul_f32_e32 v32, v42, v39
	v_mul_f32_e32 v32, v32, v34
	v_mul_f32_e32 v33, v43, v40
	v_mul_f32_e32 v34, 0xbfb8aa3b, v28
	v_mul_f32_e32 v33, v33, v35
	v_exp_f32_e32 v34, v34
	v_mul_f32_e32 v35, 0xbfb8aa3b, v29
	v_exp_f32_e32 v35, v35
	v_cvt_pk_bf16_f32 v39, v32, v33
	v_add_f32_e32 v34, 1.0, v34
	v_rcp_f32_e32 v34, v34
	v_add_f32_e32 v35, 1.0, v35
	v_rcp_f32_e32 v35, v35
	v_add_u32_e32 v32, 0x90, v150
	v_mul_f32_e32 v28, v28, v34
	v_mul_f32_e32 v20, v28, v20
	v_mul_f32_e32 v28, v29, v35
	v_mul_f32_e32 v29, 0xbfb8aa3b, v30
	v_exp_f32_e32 v29, v29
	v_mad_i64_i32 v[32:33], s[14:15], v32, s42, v[112:113]
	v_lshl_add_u64 v[32:33], v[32:33], 0, v[114:115]
	global_store_dwordx4 v[32:33], v[36:39], off
	v_mul_f32_e32 v32, 0xbfb8aa3b, v31
	v_exp_f32_e32 v32, v32
	v_mul_f32_e32 v21, v28, v21
	v_add_f32_e32 v28, 1.0, v29
	v_rcp_f32_e32 v28, v28
	v_add_f32_e32 v29, 1.0, v32
	v_rcp_f32_e32 v29, v29
	v_cvt_pk_bf16_f32 v20, v20, v21
	v_mul_f32_e32 v21, v30, v28
	v_mul_f32_e32 v28, 0xbfb8aa3b, v24
	v_exp_f32_e32 v28, v28
	v_mul_f32_e32 v21, v21, v22
	v_mul_f32_e32 v22, v31, v29
	v_mul_f32_e32 v29, 0xbfb8aa3b, v25
	v_exp_f32_e32 v29, v29
	v_mul_f32_e32 v22, v22, v23
	v_add_f32_e32 v23, 1.0, v28
	v_rcp_f32_e32 v23, v23
	v_add_f32_e32 v28, 1.0, v29
	v_rcp_f32_e32 v28, v28
	v_cvt_pk_bf16_f32 v21, v21, v22
	v_mul_f32_e32 v22, v24, v23
	v_mul_f32_e32 v23, 0xbfb8aa3b, v26
	v_exp_f32_e32 v23, v23
	v_mul_f32_e32 v24, 0xbfb8aa3b, v27
	v_exp_f32_e32 v24, v24
	v_mul_f32_e32 v16, v22, v16
	v_mul_f32_e32 v22, v25, v28
	v_mul_f32_e32 v17, v22, v17
	v_add_f32_e32 v22, 1.0, v23
	v_rcp_f32_e32 v23, v22
	v_add_f32_e32 v22, 1.0, v24
	v_rcp_f32_e32 v24, v22
	v_cvt_pk_bf16_f32 v22, v16, v17
	v_mul_f32_e32 v16, v26, v23
	v_mul_f32_e32 v16, v16, v18
	v_mul_f32_e32 v17, v27, v24
	v_mul_f32_e32 v18, 0xbfb8aa3b, v12
	v_mul_f32_e32 v17, v17, v19
	v_exp_f32_e32 v18, v18
	v_mul_f32_e32 v19, 0xbfb8aa3b, v13
	v_exp_f32_e32 v19, v19
	v_cvt_pk_bf16_f32 v23, v16, v17
	v_add_f32_e32 v18, 1.0, v18
	v_rcp_f32_e32 v18, v18
	v_add_f32_e32 v19, 1.0, v19
	v_rcp_f32_e32 v19, v19
	v_add_u32_e32 v16, 0xa0, v150
	v_mul_f32_e32 v12, v12, v18
	v_mul_f32_e32 v4, v12, v4
	v_mul_f32_e32 v12, v13, v19
	v_mul_f32_e32 v13, 0xbfb8aa3b, v14
	v_exp_f32_e32 v13, v13
	v_mad_i64_i32 v[16:17], s[14:15], v16, s42, v[112:113]
	v_lshl_add_u64 v[16:17], v[16:17], 0, v[114:115]
	global_store_dwordx4 v[16:17], v[20:23], off
	v_mul_f32_e32 v16, 0xbfb8aa3b, v15
	v_exp_f32_e32 v16, v16
	v_mul_f32_e32 v5, v12, v5
	v_add_f32_e32 v12, 1.0, v13
	v_rcp_f32_e32 v12, v12
	v_add_f32_e32 v13, 1.0, v16
	v_rcp_f32_e32 v13, v13
	v_cvt_pk_bf16_f32 v4, v4, v5
	v_mul_f32_e32 v5, v14, v12
	v_mul_f32_e32 v12, 0xbfb8aa3b, v8
	v_exp_f32_e32 v12, v12
	v_mul_f32_e32 v5, v5, v6
	v_mul_f32_e32 v6, v15, v13
	v_mul_f32_e32 v13, 0xbfb8aa3b, v9
	v_exp_f32_e32 v13, v13
	v_mul_f32_e32 v6, v6, v7
	v_add_f32_e32 v7, 1.0, v12
	v_rcp_f32_e32 v7, v7
	v_add_f32_e32 v12, 1.0, v13
	v_rcp_f32_e32 v12, v12
	v_cvt_pk_bf16_f32 v5, v5, v6
	v_mul_f32_e32 v6, v8, v7
	v_mul_f32_e32 v7, 0xbfb8aa3b, v10
	v_exp_f32_e32 v7, v7
	v_mul_f32_e32 v8, 0xbfb8aa3b, v11
	v_exp_f32_e32 v8, v8
	v_mul_f32_e32 v0, v6, v0
	v_mul_f32_e32 v6, v9, v12
	v_mul_f32_e32 v1, v6, v1
	v_add_f32_e32 v6, 1.0, v7
	v_rcp_f32_e32 v7, v6
	v_add_f32_e32 v6, 1.0, v8
	v_rcp_f32_e32 v8, v6
	v_cvt_pk_bf16_f32 v6, v0, v1
	v_mul_f32_e32 v0, v10, v7
	v_mul_f32_e32 v0, v0, v2
	v_mul_f32_e32 v1, v11, v8
	v_mul_f32_e32 v1, v1, v3
	v_cvt_pk_bf16_f32 v7, v0, v1
	v_add_u32_e32 v0, 0xb0, v150
	v_mad_i64_i32 v[0:1], s[14:15], v0, s42, v[112:113]
	v_lshl_add_u64 v[0:1], v[0:1], 0, v[114:115]
	s_and_b64 vcc, exec, s[2:3]
	s_mov_b32 s43, s4
	s_mov_b32 s12, s6
	s_mov_b64 s[18:19], s[10:11]
	s_mov_b64 s[14:15], s[8:9]
	global_store_dwordx4 v[0:1], v[4:7], off
	s_cbranch_vccz .LBB0_232
	s_waitcnt vmcnt(0)
	s_cmpk_gt_u32 s24, 0xff
	s_cbranch_scc1 .LBB0_239
	s_barrier

; #define PG8_STAGE(bufoff, gbase, voff) do { _Pragma("unroll") for (int _i = 0; _i < 2; ++_i) \
;         __builtin_amdgcn_global_load_lds((const unsigned*)((const char*)(gbase) + (voff)[_i]), (LAS unsigned*)(lds + (bufoff) + ldsw + _i * 8192), 16, 0, 0); } while (0)
; #define PG8_LDA(dst, b, h) do { _Pragma("unroll") for (int m = 0; m < 4; ++m) _Pragma("unroll") for (int k = 0; k < 2; ++k) dst[m][k] = *(const LAS bf16x8*)(lds + PG8_SA(b, h) + aoff + m * 2048 + k * 1024); } while (0)
; #define PG8_LDB(dst, b, h) do { _Pragma("unroll") for (int n = 0; n < 2; ++n) _Pragma("unroll") for (int k = 0; k < 2; ++k) dst[n][k] = *(const LAS bf16x8*)(lds + PG8_SB(b, h) + boff + n * 2048 + k * 1024); } while (0)
; #define PG8_MMA(ai, bj, At, Bt) do { __builtin_amdgcn_s_setprio(1); _Pragma("unroll") for (int m = 0; m < 4; ++m) _Pragma("unroll") for (int n = 0; n < 2; ++n) _Pragma("unroll") for (int k = 0; k < 2; ++k) \
;         acc[ai][bj][m][n] = __builtin_amdgcn_mfma_f32_16x16x32_bf16(Bt[n][k], At[m][k], acc[ai][bj][m][n], 0, 0, 0); __builtin_amdgcn_s_setprio(0); } while (0)
; #define PG8_WAIT_L(n) asm volatile("s_waitcnt lgkmcnt(" #n ")" ::: "memory")
; #define PG8_BAR __builtin_amdgcn_s_barrier()
; #define PG8_SCHED __builtin_amdgcn_sched_barrier(0)
; template <class Epi, class Sched>
; __device__ __forceinline__ void gemm_phase(LAS unsigned char* lds, const Gemm g, const Sched& S, const Epi& E) {
;     ...
;         for (int t = 0; t < nt; t += 2) {
;             const bool last = (t == nt - 2);
;             const char* a1 = cA + (size_t)(t + 1) * kstep;
;             const char* a2 = last ? nA : cA + (size_t)(t + 2) * kstep; const char* b2 = last ? nB : cB + (size_t)(t + 2) * kstep;
;             const char* a3 = a2 + kstep; const char* b3 = b2 + kstep;
;             PG8_LDB(B0, 0, 0); PG8_SCHED; PG8_LDA(At, 0, 0); PG8_STAGE(PG8_SA(1, 1), a1 + hstep, voffA);
;             PG8_WAIT_L(8); PG8_BAR; PG8_WAIT_L(0); PG8_MMA(0, 0, At, B0); PG8_BAR; PG8_SCHED;
;             PG8_LDB(B1, 0, 1); PG8_STAGE(PG8_SB(0, 0), b2, voffB);
;             PG8_BAR; PG8_WAIT_L(0); PG8_MMA(0, 1, At, B1); PG8_BAR;
;             PG8_LDA(At, 0, 1); PG8_STAGE(PG8_SA(0, 0), a2, voffA);
;             PG8_BAR; PG8_WAIT_L(0); PG8_MMA(1, 0, At, B0); PG8_BAR; PG8_SCHED;
.LBB0_304:
	s_add_u32 s0, s28, 0x100
	s_addc_u32 s67, s29, 0
	s_mov_b32 s68, -2
	ds_read_b128 v[144:147], v165
	ds_read_b128 v[148:151], v165 offset:1024
	ds_read_b128 v[152:155], v165 offset:2048
	ds_read_b128 v[156:159], v165 offset:3072
	s_add_u32 s28, s26, 0x100
	s_addc_u32 s29, s27, 0
	s_cmp_eq_u32 s68, 40
	s_cselect_b32 s37, s5, s29
	s_cselect_b32 s36, s4, s28
	s_cselect_b32 s35, s7, s67
	s_cselect_b32 s34, s6, s0
	v_lshl_add_u64 v[160:161], s[26:27], 0, v[136:137]
	s_add_i32 m0, s42, 0xc000
	ds_read_b128 v[168:171], v166
	ds_read_b128 v[172:175], v166 offset:1024
	ds_read_b128 v[176:179], v166 offset:2048
	ds_read_b128 v[180:183], v166 offset:3072
	ds_read_b128 v[184:187], v166 offset:4096
	ds_read_b128 v[188:191], v166 offset:5120
	ds_read_b128 v[192:195], v166 offset:6144
	ds_read_b128 v[196:199], v166 offset:7168
	global_load_lds_dwordx4 v[160:161], off
	v_lshl_add_u64 v[160:161], s[26:27], 0, v[138:139]
	s_add_i32 m0, s42, 0xe000
	s_nop 0
	global_load_lds_dwordx4 v[160:161], off
	s_waitcnt lgkmcnt(8)
	s_barrier
	s_waitcnt lgkmcnt(0)
	s_setprio 1
	s_waitcnt lgkmcnt(0)
	v_mfma_f32_16x16x32_bf16 v[124:127], v[144:147], v[168:171], 0
	v_mfma_f32_16x16x32_bf16 v[120:123], v[152:155], v[168:171], 0
	v_mfma_f32_16x16x32_bf16 v[116:119], v[144:147], v[176:179], 0
	v_mfma_f32_16x16x32_bf16 v[104:107], v[152:155], v[176:179], 0
	v_mfma_f32_16x16x32_bf16 v[96:99], v[144:147], v[184:187], 0
	v_mfma_f32_16x16x32_bf16 v[88:91], v[152:155], v[184:187], 0
	v_mfma_f32_16x16x32_bf16 v[80:83], v[144:147], v[192:195], 0
	v_mfma_f32_16x16x32_bf16 v[72:75], v[152:155], v[192:195], 0
	v_mfma_f32_16x16x32_bf16 v[124:127], v[148:151], v[172:175], v[124:127]
	v_mfma_f32_16x16x32_bf16 v[120:123], v[156:159], v[172:175], v[120:123]
	v_mfma_f32_16x16x32_bf16 v[116:119], v[148:151], v[180:183], v[116:119]
	v_mfma_f32_16x16x32_bf16 v[104:107], v[156:159], v[180:183], v[104:107]
	v_mfma_f32_16x16x32_bf16 v[96:99], v[148:151], v[188:191], v[96:99]
	v_mfma_f32_16x16x32_bf16 v[88:91], v[156:159], v[188:191], v[88:91]
	v_mfma_f32_16x16x32_bf16 v[80:83], v[148:151], v[196:199], v[80:83]
	v_mfma_f32_16x16x32_bf16 v[72:75], v[156:159], v[196:199], v[72:75]
	s_setprio 0
	s_barrier
	s_add_i32 s16, s58, s40
	s_mov_b32 m0, s16
	ds_read_b128 v[202:205], v167
	ds_read_b128 v[206:209], v167 offset:1024
	ds_read_b128 v[210:213], v167 offset:2048
	ds_read_b128 v[214:217], v167 offset:3072
	global_load_lds_dwordx4 v132, s[34:35]
	s_add_i32 m0, s16, 0x2000
	s_nop 0
	global_load_lds_dwordx4 v128, s[34:35]
	s_barrier
	s_waitcnt lgkmcnt(0)
	s_setprio 1
	s_waitcnt lgkmcnt(0)
	v_mfma_f32_16x16x32_bf16 v[112:115], v[202:205], v[168:171], 0
	v_mfma_f32_16x16x32_bf16 v[108:111], v[210:213], v[168:171], 0
	v_mfma_f32_16x16x32_bf16 v[100:103], v[202:205], v[176:179], 0
	v_mfma_f32_16x16x32_bf16 v[92:95], v[210:213], v[176:179], 0
	v_mfma_f32_16x16x32_bf16 v[84:87], v[202:205], v[184:187], 0
	v_mfma_f32_16x16x32_bf16 v[76:79], v[210:213], v[184:187], 0
	v_mfma_f32_16x16x32_bf16 v[68:71], v[202:205], v[192:195], 0
	v_mfma_f32_16x16x32_bf16 v[64:67], v[210:213], v[192:195], 0
	v_mfma_f32_16x16x32_bf16 v[112:115], v[206:209], v[172:175], v[112:115]
	v_mfma_f32_16x16x32_bf16 v[108:111], v[214:217], v[172:175], v[108:111]
	v_mfma_f32_16x16x32_bf16 v[100:103], v[206:209], v[180:183], v[100:103]
	v_mfma_f32_16x16x32_bf16 v[92:95], v[214:217], v[180:183], v[92:95]
	v_mfma_f32_16x16x32_bf16 v[84:87], v[206:209], v[188:191], v[84:87]
	v_mfma_f32_16x16x32_bf16 v[76:79], v[214:217], v[188:191], v[76:79]
	v_mfma_f32_16x16x32_bf16 v[68:71], v[206:209], v[196:199], v[68:71]
	v_mfma_f32_16x16x32_bf16 v[64:67], v[214:217], v[196:199], v[64:67]
	s_setprio 0
	s_mov_b32 m0, s42
	s_barrier
	ds_read_b128 v[168:171], v166 offset:16384
	ds_read_b128 v[172:175], v166 offset:17408
	ds_read_b128 v[176:179], v166 offset:18432
	ds_read_b128 v[180:183], v166 offset:19456
	ds_read_b128 v[184:187], v166 offset:20480
	ds_read_b128 v[188:191], v166 offset:21504
	ds_read_b128 v[192:195], v166 offset:22528
	ds_read_b128 v[196:199], v166 offset:23552
	global_load_lds_dwordx4 v134, s[36:37]
	s_mov_b32 m0, s43
	s_nop 0
	global_load_lds_dwordx4 v130, s[36:37]
	s_barrier
	s_waitcnt lgkmcnt(0)
	s_setprio 1
	s_waitcnt lgkmcnt(0)
	v_mfma_f32_16x16x32_bf16 v[60:63], v[144:147], v[168:171], 0
	v_mfma_f32_16x16x32_bf16 v[56:59], v[152:155], v[168:171], 0
	v_mfma_f32_16x16x32_bf16 v[48:51], v[144:147], v[176:179], 0
	v_mfma_f32_16x16x32_bf16 v[40:43], v[152:155], v[176:179], 0
	v_mfma_f32_16x16x32_bf16 v[32:35], v[144:147], v[184:187], 0
	v_mfma_f32_16x16x32_bf16 v[24:27], v[152:155], v[184:187], 0
	v_mfma_f32_16x16x32_bf16 v[16:19], v[144:147], v[192:195], 0
	v_mfma_f32_16x16x32_bf16 v[8:11], v[152:155], v[192:195], 0
	v_mfma_f32_16x16x32_bf16 v[60:63], v[148:151], v[172:175], v[60:63]
	v_mfma_f32_16x16x32_bf16 v[56:59], v[156:159], v[172:175], v[56:59]
	v_mfma_f32_16x16x32_bf16 v[48:51], v[148:151], v[180:183], v[48:51]
	v_mfma_f32_16x16x32_bf16 v[40:43], v[156:159], v[180:183], v[40:43]
	v_mfma_f32_16x16x32_bf16 v[32:35], v[148:151], v[188:191], v[32:35]
	v_mfma_f32_16x16x32_bf16 v[24:27], v[156:159], v[188:191], v[24:27]
	v_mfma_f32_16x16x32_bf16 v[16:19], v[148:151], v[196:199], v[16:19]
	v_mfma_f32_16x16x32_bf16 v[8:11], v[156:159], v[196:199], v[8:11]
	s_setprio 0
	s_barrier
	s_add_u32 s16, s34, 0xb0000
	s_addc_u32 s17, s35, 0
	s_add_i32 s20, s59, s40
	s_mov_b32 m0, s20
	s_nop 0
	global_load_lds_dwordx4 v132, s[16:17]
	s_add_i32 m0, s20, 0x2000
	s_nop 0
	global_load_lds_dwordx4 v128, s[16:17]
	s_waitcnt vmcnt(6)
	s_barrier
; #define PG8_STAGE(bufoff, gbase, voff) do { _Pragma("unroll") for (int _i = 0; _i < 2; ++_i) \
;         __builtin_amdgcn_global_load_lds((const unsigned*)((const char*)(gbase) + (voff)[_i]), (LAS unsigned*)(lds + (bufoff) + ldsw + _i * 8192), 16, 0, 0); } while (0)
; #define PG8_LDA(dst, b, h) do { _Pragma("unroll") for (int m = 0; m < 4; ++m) _Pragma("unroll") for (int k = 0; k < 2; ++k) dst[m][k] = *(const LAS bf16x8*)(lds + PG8_SA(b, h) + aoff + m * 2048 + k * 1024); } while (0)
; #define PG8_LDB(dst, b, h) do { _Pragma("unroll") for (int n = 0; n < 2; ++n) _Pragma("unroll") for (int k = 0; k < 2; ++k) dst[n][k] = *(const LAS bf16x8*)(lds + PG8_SB(b, h) + boff + n * 2048 + k * 1024); } while (0)
; #define PG8_MMA(ai, bj, At, Bt) do { __builtin_amdgcn_s_setprio(1); _Pragma("unroll") for (int m = 0; m < 4; ++m) _Pragma("unroll") for (int n = 0; n < 2; ++n) _Pragma("unroll") for (int k = 0; k < 2; ++k) \
;         acc[ai][bj][m][n] = __builtin_amdgcn_mfma_f32_16x16x32_bf16(Bt[n][k], At[m][k], acc[ai][bj][m][n], 0, 0, 0); __builtin_amdgcn_s_setprio(0); } while (0)
; #define PG8_WAIT_V(n) asm volatile("s_waitcnt vmcnt(" #n ")" ::: "memory")
; #define PG8_WAIT_L(n) asm volatile("s_waitcnt lgkmcnt(" #n ")" ::: "memory")
; #define PG8_BAR __builtin_amdgcn_s_barrier()
; #define PG8_SCHED __builtin_amdgcn_sched_barrier(0)
; template <class Epi, class Sched>
; __device__ __forceinline__ void gemm_phase(LAS unsigned char* lds, const Gemm g, const Sched& S, const Epi& E) {
;     ...
;             PG8_BAR; PG8_WAIT_L(0); PG8_MMA(1, 0, At, B0); PG8_BAR; PG8_SCHED;
;             PG8_STAGE(PG8_SB(0, 1), b2 + hstep, voffB);
;             PG8_WAIT_V(6); PG8_BAR; PG8_MMA(1, 1, At, B1); PG8_BAR;
;             PG8_LDB(B0, 1, 0); PG8_SCHED; PG8_LDA(At, 1, 0); PG8_STAGE(PG8_SA(0, 1), a2 + hstep, voffA);
;             PG8_WAIT_L(8); PG8_BAR; PG8_WAIT_L(0); PG8_MMA(0, 0, At, B0); PG8_BAR; PG8_SCHED;
;             PG8_LDB(B1, 1, 1); PG8_STAGE(PG8_SB(1, 0), b3, voffB);
;             PG8_BAR; PG8_WAIT_L(0); PG8_MMA(0, 1, At, B1); PG8_BAR;
;             PG8_LDA(At, 1, 1); PG8_STAGE(PG8_SA(1, 0), a3, voffA);
;             PG8_BAR; PG8_WAIT_L(0); PG8_MMA(1, 0, At, B0); PG8_BAR; PG8_SCHED;
	s_setprio 1
	v_mfma_f32_16x16x32_bf16 v[52:55], v[202:205], v[168:171], 0
	v_mfma_f32_16x16x32_bf16 v[44:47], v[210:213], v[168:171], 0
	v_mfma_f32_16x16x32_bf16 v[36:39], v[202:205], v[176:179], 0
	v_mfma_f32_16x16x32_bf16 v[28:31], v[210:213], v[176:179], 0
	v_mfma_f32_16x16x32_bf16 v[20:23], v[202:205], v[184:187], 0
	v_mfma_f32_16x16x32_bf16 v[12:15], v[210:213], v[184:187], 0
	v_mfma_f32_16x16x32_bf16 v[4:7], v[202:205], v[192:195], 0
	v_mfma_f32_16x16x32_bf16 v[0:3], v[210:213], v[192:195], 0
	v_mfma_f32_16x16x32_bf16 v[52:55], v[206:209], v[172:175], v[52:55]
	v_mfma_f32_16x16x32_bf16 v[44:47], v[214:217], v[172:175], v[44:47]
	v_mfma_f32_16x16x32_bf16 v[36:39], v[206:209], v[180:183], v[36:39]
	v_mfma_f32_16x16x32_bf16 v[28:31], v[214:217], v[180:183], v[28:31]
	v_mfma_f32_16x16x32_bf16 v[20:23], v[206:209], v[188:191], v[20:23]
	v_mfma_f32_16x16x32_bf16 v[12:15], v[214:217], v[188:191], v[12:15]
	v_mfma_f32_16x16x32_bf16 v[4:7], v[206:209], v[196:199], v[4:7]
	v_mfma_f32_16x16x32_bf16 v[0:3], v[214:217], v[196:199], v[0:3]
	s_setprio 0
	s_add_i32 s20, 0, 0x18000
	v_add_u32_e32 v156, s20, v164
	s_barrier
	ds_read_b128 v[144:147], v156
	ds_read_b128 v[148:151], v156 offset:1024
	ds_read_b128 v[152:155], v156 offset:2048
	ds_read_b128 v[156:159], v156 offset:3072
	s_add_u32 s16, s36, 0xb0000
	s_addc_u32 s17, s37, 0
	s_mov_b32 m0, s44
	ds_read_b128 v[168:171], v166 offset:32768
	ds_read_b128 v[172:175], v166 offset:33792
	ds_read_b128 v[176:179], v166 offset:34816
	ds_read_b128 v[180:183], v166 offset:35840
	ds_read_b128 v[184:187], v166 offset:36864
	ds_read_b128 v[188:191], v166 offset:37888
	ds_read_b128 v[192:195], v166 offset:38912
	ds_read_b128 v[196:199], v166 offset:39936
	global_load_lds_dwordx4 v134, s[16:17]
	s_mov_b32 m0, s45
	s_nop 0
	global_load_lds_dwordx4 v130, s[16:17]
	s_waitcnt lgkmcnt(8)
	s_barrier
	s_waitcnt lgkmcnt(0)
	s_setprio 1
	s_waitcnt lgkmcnt(0)
	v_mfma_f32_16x16x32_bf16 v[124:127], v[144:147], v[168:171], v[124:127]
	v_mfma_f32_16x16x32_bf16 v[120:123], v[152:155], v[168:171], v[120:123]
	v_mfma_f32_16x16x32_bf16 v[116:119], v[144:147], v[176:179], v[116:119]
	v_mfma_f32_16x16x32_bf16 v[104:107], v[152:155], v[176:179], v[104:107]
	v_mfma_f32_16x16x32_bf16 v[96:99], v[144:147], v[184:187], v[96:99]
	v_mfma_f32_16x16x32_bf16 v[88:91], v[152:155], v[184:187], v[88:91]
	v_mfma_f32_16x16x32_bf16 v[80:83], v[144:147], v[192:195], v[80:83]
	v_mfma_f32_16x16x32_bf16 v[72:75], v[152:155], v[192:195], v[72:75]
	v_mfma_f32_16x16x32_bf16 v[124:127], v[148:151], v[172:175], v[124:127]
	v_mfma_f32_16x16x32_bf16 v[120:123], v[156:159], v[172:175], v[120:123]
	v_mfma_f32_16x16x32_bf16 v[116:119], v[148:151], v[180:183], v[116:119]
	v_mfma_f32_16x16x32_bf16 v[104:107], v[156:159], v[180:183], v[104:107]
	v_mfma_f32_16x16x32_bf16 v[96:99], v[148:151], v[188:191], v[96:99]
	v_mfma_f32_16x16x32_bf16 v[88:91], v[156:159], v[188:191], v[88:91]
	v_mfma_f32_16x16x32_bf16 v[80:83], v[148:151], v[196:199], v[80:83]
	v_mfma_f32_16x16x32_bf16 v[72:75], v[156:159], v[196:199], v[72:75]
	s_setprio 0
	s_barrier
	s_add_i32 s21, 0, 0x1c000
	s_add_i32 s16, s20, s40
	v_add_u32_e32 v214, s21, v164
	s_add_u32 s8, s34, 0x80
	s_addc_u32 s9, s35, 0
	s_mov_b32 m0, s16
	ds_read_b128 v[202:205], v214
	ds_read_b128 v[206:209], v214 offset:1024
	ds_read_b128 v[210:213], v214 offset:2048
	ds_read_b128 v[214:217], v214 offset:3072
	global_load_lds_dwordx4 v132, s[8:9]
	s_add_i32 m0, s16, 0x2000
	s_nop 0
	global_load_lds_dwordx4 v128, s[8:9]
	s_barrier
	s_waitcnt lgkmcnt(0)
	s_setprio 1
	s_waitcnt lgkmcnt(0)
	v_mfma_f32_16x16x32_bf16 v[112:115], v[202:205], v[168:171], v[112:115]
	v_mfma_f32_16x16x32_bf16 v[108:111], v[210:213], v[168:171], v[108:111]
	v_mfma_f32_16x16x32_bf16 v[100:103], v[202:205], v[176:179], v[100:103]
	v_mfma_f32_16x16x32_bf16 v[92:95], v[210:213], v[176:179], v[92:95]
	v_mfma_f32_16x16x32_bf16 v[84:87], v[202:205], v[184:187], v[84:87]
	v_mfma_f32_16x16x32_bf16 v[76:79], v[210:213], v[184:187], v[76:79]
	v_mfma_f32_16x16x32_bf16 v[68:71], v[202:205], v[192:195], v[68:71]
	v_mfma_f32_16x16x32_bf16 v[64:67], v[210:213], v[192:195], v[64:67]
	v_mfma_f32_16x16x32_bf16 v[112:115], v[206:209], v[172:175], v[112:115]
	v_mfma_f32_16x16x32_bf16 v[108:111], v[214:217], v[172:175], v[108:111]
	v_mfma_f32_16x16x32_bf16 v[100:103], v[206:209], v[180:183], v[100:103]
	v_mfma_f32_16x16x32_bf16 v[92:95], v[214:217], v[180:183], v[92:95]
	v_mfma_f32_16x16x32_bf16 v[84:87], v[206:209], v[188:191], v[84:87]
	v_mfma_f32_16x16x32_bf16 v[76:79], v[214:217], v[188:191], v[76:79]
	v_mfma_f32_16x16x32_bf16 v[68:71], v[206:209], v[196:199], v[68:71]
	v_mfma_f32_16x16x32_bf16 v[64:67], v[214:217], v[196:199], v[64:67]
	s_setprio 0
	s_mov_b32 m0, s52
	s_add_u32 s8, s36, 0x80
	s_addc_u32 s9, s37, 0
	s_barrier
	ds_read_b128 v[168:171], v166 offset:49152
	ds_read_b128 v[172:175], v166 offset:50176
	ds_read_b128 v[176:179], v166 offset:51200
	ds_read_b128 v[180:183], v166 offset:52224
	ds_read_b128 v[184:187], v166 offset:53248
	ds_read_b128 v[188:191], v166 offset:54272
	ds_read_b128 v[192:195], v166 offset:55296
	ds_read_b128 v[196:199], v166 offset:56320
	global_load_lds_dwordx4 v134, s[8:9]
	s_mov_b32 m0, s53
	s_nop 0
	global_load_lds_dwordx4 v130, s[8:9]
	s_barrier
; #define PG8_STAGE(bufoff, gbase, voff) do { _Pragma("unroll") for (int _i = 0; _i < 2; ++_i) \
;         __builtin_amdgcn_global_load_lds((const unsigned*)((const char*)(gbase) + (voff)[_i]), (LAS unsigned*)(lds + (bufoff) + ldsw + _i * 8192), 16, 0, 0); } while (0)
; #define PG8_LDA(dst, b, h) do { _Pragma("unroll") for (int m = 0; m < 4; ++m) _Pragma("unroll") for (int k = 0; k < 2; ++k) dst[m][k] = *(const LAS bf16x8*)(lds + PG8_SA(b, h) + aoff + m * 2048 + k * 1024); } while (0)
; #define PG8_WAIT_V(n) asm volatile("s_waitcnt vmcnt(" #n ")" ::: "memory")
; #define PG8_WAIT_L(n) asm volatile("s_waitcnt lgkmcnt(" #n ")" ::: "memory")
; template <class Epi, class Sched>
; __device__ __forceinline__ void gemm_phase(LAS unsigned char* lds, const Gemm g, const Sched& S, const Epi& E) {
;     ...
;         for (int t = 0; t < nt; t += 2) {
;             const bool last = (t == nt - 2);
;             const char* a1 = cA + (size_t)(t + 1) * kstep;
;             const char* a2 = last ? nA : cA + (size_t)(t + 2) * kstep; const char* b2 = last ? nB : cB + (size_t)(t + 2) * kstep;
;             const char* a3 = a2 + kstep; const char* b3 = b2 + kstep;
;             PG8_LDB(B0, 0, 0); PG8_SCHED; PG8_LDA(At, 0, 0); PG8_STAGE(PG8_SA(1, 1), a1 + hstep, voffA);
;             PG8_WAIT_L(8); PG8_BAR; PG8_WAIT_L(0); PG8_MMA(0, 0, At, B0); PG8_BAR; PG8_SCHED;
;             PG8_LDB(B1, 0, 1); PG8_STAGE(PG8_SB(0, 0), b2, voffB);
;             PG8_BAR; PG8_WAIT_L(0); PG8_MMA(0, 1, At, B1); PG8_BAR;
;             PG8_LDA(At, 0, 1); PG8_STAGE(PG8_SA(0, 0), a2, voffA);
;             PG8_BAR; PG8_WAIT_L(0); PG8_MMA(1, 0, At, B0); PG8_BAR; PG8_SCHED;
;             PG8_STAGE(PG8_SB(0, 1), b2 + hstep, voffB);
;             PG8_WAIT_V(6); PG8_BAR; PG8_MMA(1, 1, At, B1); PG8_BAR;
;             PG8_LDB(B0, 1, 0); PG8_SCHED; PG8_LDA(At, 1, 0); PG8_STAGE(PG8_SA(0, 1), a2 + hstep, voffA);
;             PG8_WAIT_L(8); PG8_BAR; PG8_WAIT_L(0); PG8_MMA(0, 0, At, B0); PG8_BAR; PG8_SCHED;
;             PG8_LDB(B1, 1, 1); PG8_STAGE(PG8_SB(1, 0), b3, voffB);
;             PG8_BAR; PG8_WAIT_L(0); PG8_MMA(0, 1, At, B1); PG8_BAR;
;             PG8_LDA(At, 1, 1); PG8_STAGE(PG8_SA(1, 0), a3, voffA);
;             PG8_BAR; PG8_WAIT_L(0); PG8_MMA(1, 0, At, B0); PG8_BAR; PG8_SCHED;
;             PG8_STAGE(PG8_SB(1, 1), b3 + hstep, voffB);
;             PG8_WAIT_V(6); PG8_BAR; PG8_MMA(1, 1, At, B1); PG8_BAR;
	s_waitcnt lgkmcnt(0)
	s_setprio 1
	s_waitcnt lgkmcnt(0)
	v_mfma_f32_16x16x32_bf16 v[60:63], v[144:147], v[168:171], v[60:63]
	v_mfma_f32_16x16x32_bf16 v[56:59], v[152:155], v[168:171], v[56:59]
	v_mfma_f32_16x16x32_bf16 v[48:51], v[144:147], v[176:179], v[48:51]
	v_mfma_f32_16x16x32_bf16 v[40:43], v[152:155], v[176:179], v[40:43]
	v_mfma_f32_16x16x32_bf16 v[32:35], v[144:147], v[184:187], v[32:35]
	v_mfma_f32_16x16x32_bf16 v[24:27], v[152:155], v[184:187], v[24:27]
	v_mfma_f32_16x16x32_bf16 v[16:19], v[144:147], v[192:195], v[16:19]
	v_mfma_f32_16x16x32_bf16 v[8:11], v[152:155], v[192:195], v[8:11]
	v_mfma_f32_16x16x32_bf16 v[60:63], v[148:151], v[172:175], v[60:63]
	v_mfma_f32_16x16x32_bf16 v[56:59], v[156:159], v[172:175], v[56:59]
	v_mfma_f32_16x16x32_bf16 v[48:51], v[148:151], v[180:183], v[48:51]
	v_mfma_f32_16x16x32_bf16 v[40:43], v[156:159], v[180:183], v[40:43]
	v_mfma_f32_16x16x32_bf16 v[32:35], v[148:151], v[188:191], v[32:35]
	v_mfma_f32_16x16x32_bf16 v[24:27], v[156:159], v[188:191], v[24:27]
	v_mfma_f32_16x16x32_bf16 v[16:19], v[148:151], v[196:199], v[16:19]
	v_mfma_f32_16x16x32_bf16 v[8:11], v[156:159], v[196:199], v[8:11]
	s_setprio 0
	s_barrier
	s_add_u32 s16, s34, 0xb0080
	s_addc_u32 s17, s35, 0
	s_add_i32 s20, s21, s40
	s_mov_b32 m0, s20
	s_nop 0
	global_load_lds_dwordx4 v132, s[16:17]
	s_add_i32 m0, s20, 0x2000
	s_nop 0
	global_load_lds_dwordx4 v128, s[16:17]
	s_waitcnt vmcnt(6)
	s_barrier
	s_setprio 1
	v_mfma_f32_16x16x32_bf16 v[52:55], v[202:205], v[168:171], v[52:55]
	v_mfma_f32_16x16x32_bf16 v[44:47], v[210:213], v[168:171], v[44:47]
	v_mfma_f32_16x16x32_bf16 v[36:39], v[202:205], v[176:179], v[36:39]
	v_mfma_f32_16x16x32_bf16 v[28:31], v[210:213], v[176:179], v[28:31]
	v_mfma_f32_16x16x32_bf16 v[20:23], v[202:205], v[184:187], v[20:23]
	v_mfma_f32_16x16x32_bf16 v[12:15], v[210:213], v[184:187], v[12:15]
	v_mfma_f32_16x16x32_bf16 v[4:7], v[202:205], v[192:195], v[4:7]
	v_mfma_f32_16x16x32_bf16 v[0:3], v[210:213], v[192:195], v[0:3]
	v_mfma_f32_16x16x32_bf16 v[52:55], v[206:209], v[172:175], v[52:55]
	v_mfma_f32_16x16x32_bf16 v[44:47], v[214:217], v[172:175], v[44:47]
	v_mfma_f32_16x16x32_bf16 v[36:39], v[206:209], v[180:183], v[36:39]
	v_mfma_f32_16x16x32_bf16 v[28:31], v[214:217], v[180:183], v[28:31]
	v_mfma_f32_16x16x32_bf16 v[20:23], v[206:209], v[188:191], v[20:23]
	v_mfma_f32_16x16x32_bf16 v[12:15], v[214:217], v[188:191], v[12:15]
	v_mfma_f32_16x16x32_bf16 v[4:7], v[206:209], v[196:199], v[4:7]
	v_mfma_f32_16x16x32_bf16 v[0:3], v[214:217], v[196:199], v[0:3]
	s_setprio 0
	s_add_i32 s68, s68, 2
	s_add_u32 s0, s0, 0x100
	s_addc_u32 s67, s67, 0
	s_cmp_gt_u32 s68, 41
	s_mov_b64 s[26:27], s[28:29]
	s_barrier
.LBB0_305:
	ds_read_b128 v[144:147], v165
	ds_read_b128 v[148:151], v165 offset:1024
	ds_read_b128 v[152:155], v165 offset:2048
	ds_read_b128 v[156:159], v165 offset:3072
	s_add_u32 s28, s26, 0x100
	s_addc_u32 s29, s27, 0
	s_cmp_eq_u32 s68, 40
	s_cselect_b32 s37, s5, s29
	s_cselect_b32 s36, s4, s28
	s_cselect_b32 s35, s7, s67
	s_cselect_b32 s34, s6, s0
	v_lshl_add_u64 v[160:161], s[26:27], 0, v[136:137]
	s_add_i32 m0, s42, 0xc000
	ds_read_b128 v[168:171], v166
	ds_read_b128 v[172:175], v166 offset:1024
	ds_read_b128 v[176:179], v166 offset:2048
	ds_read_b128 v[180:183], v166 offset:3072
	ds_read_b128 v[184:187], v166 offset:4096
	ds_read_b128 v[188:191], v166 offset:5120
	ds_read_b128 v[192:195], v166 offset:6144
	ds_read_b128 v[196:199], v166 offset:7168
	global_load_lds_dwordx4 v[160:161], off
	v_lshl_add_u64 v[160:161], s[26:27], 0, v[138:139]
	s_add_i32 m0, s42, 0xe000
	s_nop 0
	global_load_lds_dwordx4 v[160:161], off
	s_waitcnt lgkmcnt(8)
	s_barrier
	s_waitcnt lgkmcnt(0)
	s_setprio 1
	s_waitcnt lgkmcnt(0)
	v_mfma_f32_16x16x32_bf16 v[124:127], v[144:147], v[168:171], v[124:127]
	v_mfma_f32_16x16x32_bf16 v[120:123], v[152:155], v[168:171], v[120:123]
	v_mfma_f32_16x16x32_bf16 v[116:119], v[144:147], v[176:179], v[116:119]
	v_mfma_f32_16x16x32_bf16 v[104:107], v[152:155], v[176:179], v[104:107]
	v_mfma_f32_16x16x32_bf16 v[96:99], v[144:147], v[184:187], v[96:99]
	v_mfma_f32_16x16x32_bf16 v[88:91], v[152:155], v[184:187], v[88:91]
	v_mfma_f32_16x16x32_bf16 v[80:83], v[144:147], v[192:195], v[80:83]
	v_mfma_f32_16x16x32_bf16 v[72:75], v[152:155], v[192:195], v[72:75]
	v_mfma_f32_16x16x32_bf16 v[124:127], v[148:151], v[172:175], v[124:127]
	v_mfma_f32_16x16x32_bf16 v[120:123], v[156:159], v[172:175], v[120:123]
	v_mfma_f32_16x16x32_bf16 v[116:119], v[148:151], v[180:183], v[116:119]
	v_mfma_f32_16x16x32_bf16 v[104:107], v[156:159], v[180:183], v[104:107]
	v_mfma_f32_16x16x32_bf16 v[96:99], v[148:151], v[188:191], v[96:99]
	v_mfma_f32_16x16x32_bf16 v[88:91], v[156:159], v[188:191], v[88:91]
	v_mfma_f32_16x16x32_bf16 v[80:83], v[148:151], v[196:199], v[80:83]
	v_mfma_f32_16x16x32_bf16 v[72:75], v[156:159], v[196:199], v[72:75]
	s_setprio 0
	s_barrier
	s_add_i32 s16, s58, s40
	s_mov_b32 m0, s16
	ds_read_b128 v[202:205], v167
	ds_read_b128 v[206:209], v167 offset:1024
	ds_read_b128 v[210:213], v167 offset:2048
	ds_read_b128 v[214:217], v167 offset:3072
	global_load_lds_dwordx4 v132, s[34:35]
	s_add_i32 m0, s16, 0x2000
	s_nop 0
	global_load_lds_dwordx4 v128, s[34:35]
	s_barrier
; #define PG8_STAGE(bufoff, gbase, voff) do { _Pragma("unroll") for (int _i = 0; _i < 2; ++_i) \
;         __builtin_amdgcn_global_load_lds((const unsigned*)((const char*)(gbase) + (voff)[_i]), (LAS unsigned*)(lds + (bufoff) + ldsw + _i * 8192), 16, 0, 0); } while (0)
; #define PG8_LDA(dst, b, h) do { _Pragma("unroll") for (int m = 0; m < 4; ++m) _Pragma("unroll") for (int k = 0; k < 2; ++k) dst[m][k] = *(const LAS bf16x8*)(lds + PG8_SA(b, h) + aoff + m * 2048 + k * 1024); } while (0)
; #define PG8_LDB(dst, b, h) do { _Pragma("unroll") for (int n = 0; n < 2; ++n) _Pragma("unroll") for (int k = 0; k < 2; ++k) dst[n][k] = *(const LAS bf16x8*)(lds + PG8_SB(b, h) + boff + n * 2048 + k * 1024); } while (0)
; #define PG8_MMA(ai, bj, At, Bt) do { __builtin_amdgcn_s_setprio(1); _Pragma("unroll") for (int m = 0; m < 4; ++m) _Pragma("unroll") for (int n = 0; n < 2; ++n) _Pragma("unroll") for (int k = 0; k < 2; ++k) \
;         acc[ai][bj][m][n] = __builtin_amdgcn_mfma_f32_16x16x32_bf16(Bt[n][k], At[m][k], acc[ai][bj][m][n], 0, 0, 0); __builtin_amdgcn_s_setprio(0); } while (0)
; #define PG8_WAIT_V(n) asm volatile("s_waitcnt vmcnt(" #n ")" ::: "memory")
; #define PG8_WAIT_L(n) asm volatile("s_waitcnt lgkmcnt(" #n ")" ::: "memory")
; #define PG8_BAR __builtin_amdgcn_s_barrier()
; #define PG8_SCHED __builtin_amdgcn_sched_barrier(0)
; template <class Epi, class Sched>
; __device__ __forceinline__ void gemm_phase(LAS unsigned char* lds, const Gemm g, const Sched& S, const Epi& E) {
;     ...
;             PG8_BAR; PG8_WAIT_L(0); PG8_MMA(0, 1, At, B1); PG8_BAR;
;             PG8_LDA(At, 0, 1); PG8_STAGE(PG8_SA(0, 0), a2, voffA);
;             PG8_BAR; PG8_WAIT_L(0); PG8_MMA(1, 0, At, B0); PG8_BAR; PG8_SCHED;
;             PG8_STAGE(PG8_SB(0, 1), b2 + hstep, voffB);
;             PG8_WAIT_V(6); PG8_BAR; PG8_MMA(1, 1, At, B1); PG8_BAR;
;             PG8_LDB(B0, 1, 0); PG8_SCHED; PG8_LDA(At, 1, 0); PG8_STAGE(PG8_SA(0, 1), a2 + hstep, voffA);
;             PG8_WAIT_L(8); PG8_BAR; PG8_WAIT_L(0); PG8_MMA(0, 0, At, B0); PG8_BAR; PG8_SCHED;
	s_waitcnt lgkmcnt(0)
	s_setprio 1
	s_waitcnt lgkmcnt(0)
	v_mfma_f32_16x16x32_bf16 v[112:115], v[202:205], v[168:171], v[112:115]
	v_mfma_f32_16x16x32_bf16 v[108:111], v[210:213], v[168:171], v[108:111]
	v_mfma_f32_16x16x32_bf16 v[100:103], v[202:205], v[176:179], v[100:103]
	v_mfma_f32_16x16x32_bf16 v[92:95], v[210:213], v[176:179], v[92:95]
	v_mfma_f32_16x16x32_bf16 v[84:87], v[202:205], v[184:187], v[84:87]
	v_mfma_f32_16x16x32_bf16 v[76:79], v[210:213], v[184:187], v[76:79]
	v_mfma_f32_16x16x32_bf16 v[68:71], v[202:205], v[192:195], v[68:71]
	v_mfma_f32_16x16x32_bf16 v[64:67], v[210:213], v[192:195], v[64:67]
	v_mfma_f32_16x16x32_bf16 v[112:115], v[206:209], v[172:175], v[112:115]
	v_mfma_f32_16x16x32_bf16 v[108:111], v[214:217], v[172:175], v[108:111]
	v_mfma_f32_16x16x32_bf16 v[100:103], v[206:209], v[180:183], v[100:103]
	v_mfma_f32_16x16x32_bf16 v[92:95], v[214:217], v[180:183], v[92:95]
	v_mfma_f32_16x16x32_bf16 v[84:87], v[206:209], v[188:191], v[84:87]
	v_mfma_f32_16x16x32_bf16 v[76:79], v[214:217], v[188:191], v[76:79]
	v_mfma_f32_16x16x32_bf16 v[68:71], v[206:209], v[196:199], v[68:71]
	v_mfma_f32_16x16x32_bf16 v[64:67], v[214:217], v[196:199], v[64:67]
	s_setprio 0
	s_mov_b32 m0, s42
	s_barrier
	ds_read_b128 v[168:171], v166 offset:16384
	ds_read_b128 v[172:175], v166 offset:17408
	ds_read_b128 v[176:179], v166 offset:18432
	ds_read_b128 v[180:183], v166 offset:19456
	ds_read_b128 v[184:187], v166 offset:20480
	ds_read_b128 v[188:191], v166 offset:21504
	ds_read_b128 v[192:195], v166 offset:22528
	ds_read_b128 v[196:199], v166 offset:23552
	global_load_lds_dwordx4 v134, s[36:37]
	s_mov_b32 m0, s43
	s_nop 0
	global_load_lds_dwordx4 v130, s[36:37]
	s_barrier
	s_waitcnt lgkmcnt(0)
	s_setprio 1
	s_waitcnt lgkmcnt(0)
	v_mfma_f32_16x16x32_bf16 v[60:63], v[144:147], v[168:171], v[60:63]
	v_mfma_f32_16x16x32_bf16 v[56:59], v[152:155], v[168:171], v[56:59]
	v_mfma_f32_16x16x32_bf16 v[48:51], v[144:147], v[176:179], v[48:51]
	v_mfma_f32_16x16x32_bf16 v[40:43], v[152:155], v[176:179], v[40:43]
	v_mfma_f32_16x16x32_bf16 v[32:35], v[144:147], v[184:187], v[32:35]
	v_mfma_f32_16x16x32_bf16 v[24:27], v[152:155], v[184:187], v[24:27]
	v_mfma_f32_16x16x32_bf16 v[16:19], v[144:147], v[192:195], v[16:19]
	v_mfma_f32_16x16x32_bf16 v[8:11], v[152:155], v[192:195], v[8:11]
	v_mfma_f32_16x16x32_bf16 v[60:63], v[148:151], v[172:175], v[60:63]
	v_mfma_f32_16x16x32_bf16 v[56:59], v[156:159], v[172:175], v[56:59]
	v_mfma_f32_16x16x32_bf16 v[48:51], v[148:151], v[180:183], v[48:51]
	v_mfma_f32_16x16x32_bf16 v[40:43], v[156:159], v[180:183], v[40:43]
	v_mfma_f32_16x16x32_bf16 v[32:35], v[148:151], v[188:191], v[32:35]
	v_mfma_f32_16x16x32_bf16 v[24:27], v[156:159], v[188:191], v[24:27]
	v_mfma_f32_16x16x32_bf16 v[16:19], v[148:151], v[196:199], v[16:19]
	v_mfma_f32_16x16x32_bf16 v[8:11], v[156:159], v[196:199], v[8:11]
	s_setprio 0
	s_barrier
	s_add_u32 s16, s34, 0xb0000
	s_addc_u32 s17, s35, 0
	s_add_i32 s20, s59, s40
	s_mov_b32 m0, s20
	s_nop 0
	global_load_lds_dwordx4 v132, s[16:17]
	s_add_i32 m0, s20, 0x2000
	s_nop 0
	global_load_lds_dwordx4 v128, s[16:17]
	s_waitcnt vmcnt(6)
	s_barrier
	s_setprio 1
	v_mfma_f32_16x16x32_bf16 v[52:55], v[202:205], v[168:171], v[52:55]
	v_mfma_f32_16x16x32_bf16 v[44:47], v[210:213], v[168:171], v[44:47]
	v_mfma_f32_16x16x32_bf16 v[36:39], v[202:205], v[176:179], v[36:39]
	v_mfma_f32_16x16x32_bf16 v[28:31], v[210:213], v[176:179], v[28:31]
	v_mfma_f32_16x16x32_bf16 v[20:23], v[202:205], v[184:187], v[20:23]
	v_mfma_f32_16x16x32_bf16 v[12:15], v[210:213], v[184:187], v[12:15]
	v_mfma_f32_16x16x32_bf16 v[4:7], v[202:205], v[192:195], v[4:7]
	v_mfma_f32_16x16x32_bf16 v[0:3], v[210:213], v[192:195], v[0:3]
	v_mfma_f32_16x16x32_bf16 v[52:55], v[206:209], v[172:175], v[52:55]
	v_mfma_f32_16x16x32_bf16 v[44:47], v[214:217], v[172:175], v[44:47]
	v_mfma_f32_16x16x32_bf16 v[36:39], v[206:209], v[180:183], v[36:39]
	v_mfma_f32_16x16x32_bf16 v[28:31], v[214:217], v[180:183], v[28:31]
	v_mfma_f32_16x16x32_bf16 v[20:23], v[206:209], v[188:191], v[20:23]
	v_mfma_f32_16x16x32_bf16 v[12:15], v[214:217], v[188:191], v[12:15]
	v_mfma_f32_16x16x32_bf16 v[4:7], v[206:209], v[196:199], v[4:7]
	v_mfma_f32_16x16x32_bf16 v[0:3], v[214:217], v[196:199], v[0:3]
	s_setprio 0
	s_add_i32 s20, 0, 0x18000
	v_add_u32_e32 v156, s20, v164
	s_barrier
	ds_read_b128 v[144:147], v156
	ds_read_b128 v[148:151], v156 offset:1024
	ds_read_b128 v[152:155], v156 offset:2048
	ds_read_b128 v[156:159], v156 offset:3072
	s_add_u32 s16, s36, 0xb0000
	s_addc_u32 s17, s37, 0
	s_mov_b32 m0, s44
	ds_read_b128 v[168:171], v166 offset:32768
	ds_read_b128 v[172:175], v166 offset:33792
	ds_read_b128 v[176:179], v166 offset:34816
	ds_read_b128 v[180:183], v166 offset:35840
	ds_read_b128 v[184:187], v166 offset:36864
	ds_read_b128 v[188:191], v166 offset:37888
	ds_read_b128 v[192:195], v166 offset:38912
	ds_read_b128 v[196:199], v166 offset:39936
	global_load_lds_dwordx4 v134, s[16:17]
	s_mov_b32 m0, s45
	s_nop 0
	global_load_lds_dwordx4 v130, s[16:17]
	s_waitcnt lgkmcnt(8)
	s_barrier
; #define PG8_STAGE(bufoff, gbase, voff) do { _Pragma("unroll") for (int _i = 0; _i < 2; ++_i) \
;         __builtin_amdgcn_global_load_lds((const unsigned*)((const char*)(gbase) + (voff)[_i]), (LAS unsigned*)(lds + (bufoff) + ldsw + _i * 8192), 16, 0, 0); } while (0)
; #define PG8_LDA(dst, b, h) do { _Pragma("unroll") for (int m = 0; m < 4; ++m) _Pragma("unroll") for (int k = 0; k < 2; ++k) dst[m][k] = *(const LAS bf16x8*)(lds + PG8_SA(b, h) + aoff + m * 2048 + k * 1024); } while (0)
; #define PG8_LDB(dst, b, h) do { _Pragma("unroll") for (int n = 0; n < 2; ++n) _Pragma("unroll") for (int k = 0; k < 2; ++k) dst[n][k] = *(const LAS bf16x8*)(lds + PG8_SB(b, h) + boff + n * 2048 + k * 1024); } while (0)
; #define PG8_MMA(ai, bj, At, Bt) do { __builtin_amdgcn_s_setprio(1); _Pragma("unroll") for (int m = 0; m < 4; ++m) _Pragma("unroll") for (int n = 0; n < 2; ++n) _Pragma("unroll") for (int k = 0; k < 2; ++k) \
;         acc[ai][bj][m][n] = __builtin_amdgcn_mfma_f32_16x16x32_bf16(Bt[n][k], At[m][k], acc[ai][bj][m][n], 0, 0, 0); __builtin_amdgcn_s_setprio(0); } while (0)
; #define PG8_WAIT_V(n) asm volatile("s_waitcnt vmcnt(" #n ")" ::: "memory")
; #define PG8_WAIT_L(n) asm volatile("s_waitcnt lgkmcnt(" #n ")" ::: "memory")
; template <class Epi, class Sched>
; __device__ __forceinline__ void gemm_phase(LAS unsigned char* lds, const Gemm g, const Sched& S, const Epi& E) {
;     ...
;             PG8_WAIT_L(8); PG8_BAR; PG8_WAIT_L(0); PG8_MMA(0, 0, At, B0); PG8_BAR; PG8_SCHED;
;             PG8_LDB(B1, 1, 1); PG8_STAGE(PG8_SB(1, 0), b3, voffB);
;             PG8_BAR; PG8_WAIT_L(0); PG8_MMA(0, 1, At, B1); PG8_BAR;
;             PG8_LDA(At, 1, 1); PG8_STAGE(PG8_SA(1, 0), a3, voffA);
;             PG8_BAR; PG8_WAIT_L(0); PG8_MMA(1, 0, At, B0); PG8_BAR; PG8_SCHED;
;             PG8_STAGE(PG8_SB(1, 1), b3 + hstep, voffB);
;             PG8_WAIT_V(6); PG8_BAR; PG8_MMA(1, 1, At, B1); PG8_BAR;
;         }
;         E(acc, cur, wr, wc, fr, fq);
;         if (!has_next) break;
;     __device__ __forceinline__ void operator()(const AccT& acc, const Unit& u, int wr, int wc, int fr, int fq) const {
;         asm volatile("" : "+v"(fr), "+v"(fq));
;         const int rowt = u.pm * 256; const bool isc = rowt >= MX; const int b = isc ? 32 : (rowt >> 11);
;         const float* res = isc ? res_c + (size_t)(rowt - MX) * DM : res_x + (size_t)rowt * DM; bf16_t* out = hb + (size_t)rowt * DM;
	s_waitcnt lgkmcnt(0)
	s_setprio 1
	s_waitcnt lgkmcnt(0)
	v_mfma_f32_16x16x32_bf16 v[124:127], v[144:147], v[168:171], v[124:127]
	v_mfma_f32_16x16x32_bf16 v[120:123], v[152:155], v[168:171], v[120:123]
	v_mfma_f32_16x16x32_bf16 v[116:119], v[144:147], v[176:179], v[116:119]
	v_mfma_f32_16x16x32_bf16 v[104:107], v[152:155], v[176:179], v[104:107]
	v_mfma_f32_16x16x32_bf16 v[96:99], v[144:147], v[184:187], v[96:99]
	v_mfma_f32_16x16x32_bf16 v[88:91], v[152:155], v[184:187], v[88:91]
	v_mfma_f32_16x16x32_bf16 v[80:83], v[144:147], v[192:195], v[80:83]
	v_mfma_f32_16x16x32_bf16 v[72:75], v[152:155], v[192:195], v[72:75]
	v_mfma_f32_16x16x32_bf16 v[124:127], v[148:151], v[172:175], v[124:127]
	v_mfma_f32_16x16x32_bf16 v[120:123], v[156:159], v[172:175], v[120:123]
	v_mfma_f32_16x16x32_bf16 v[116:119], v[148:151], v[180:183], v[116:119]
	v_mfma_f32_16x16x32_bf16 v[104:107], v[156:159], v[180:183], v[104:107]
	v_mfma_f32_16x16x32_bf16 v[96:99], v[148:151], v[188:191], v[96:99]
	v_mfma_f32_16x16x32_bf16 v[88:91], v[156:159], v[188:191], v[88:91]
	v_mfma_f32_16x16x32_bf16 v[80:83], v[148:151], v[196:199], v[80:83]
	v_mfma_f32_16x16x32_bf16 v[72:75], v[156:159], v[196:199], v[72:75]
	s_setprio 0
	s_barrier
	s_add_i32 s21, 0, 0x1c000
	s_add_i32 s16, s20, s40
	v_add_u32_e32 v214, s21, v164
	s_add_u32 s8, s34, 0x80
	s_addc_u32 s9, s35, 0
	s_mov_b32 m0, s16
	ds_read_b128 v[202:205], v214
	ds_read_b128 v[206:209], v214 offset:1024
	ds_read_b128 v[210:213], v214 offset:2048
	ds_read_b128 v[214:217], v214 offset:3072
	global_load_lds_dwordx4 v132, s[8:9]
	s_add_i32 m0, s16, 0x2000
	s_nop 0
	global_load_lds_dwordx4 v128, s[8:9]
	s_barrier
	s_waitcnt lgkmcnt(0)
	s_setprio 1
	s_waitcnt lgkmcnt(0)
	v_mfma_f32_16x16x32_bf16 v[112:115], v[202:205], v[168:171], v[112:115]
	v_mfma_f32_16x16x32_bf16 v[108:111], v[210:213], v[168:171], v[108:111]
	v_mfma_f32_16x16x32_bf16 v[100:103], v[202:205], v[176:179], v[100:103]
	v_mfma_f32_16x16x32_bf16 v[92:95], v[210:213], v[176:179], v[92:95]
	v_mfma_f32_16x16x32_bf16 v[84:87], v[202:205], v[184:187], v[84:87]
	v_mfma_f32_16x16x32_bf16 v[76:79], v[210:213], v[184:187], v[76:79]
	v_mfma_f32_16x16x32_bf16 v[68:71], v[202:205], v[192:195], v[68:71]
	v_mfma_f32_16x16x32_bf16 v[64:67], v[210:213], v[192:195], v[64:67]
	v_mfma_f32_16x16x32_bf16 v[112:115], v[206:209], v[172:175], v[112:115]
	v_mfma_f32_16x16x32_bf16 v[108:111], v[214:217], v[172:175], v[108:111]
	v_mfma_f32_16x16x32_bf16 v[100:103], v[206:209], v[180:183], v[100:103]
	v_mfma_f32_16x16x32_bf16 v[92:95], v[214:217], v[180:183], v[92:95]
	v_mfma_f32_16x16x32_bf16 v[84:87], v[206:209], v[188:191], v[84:87]
	v_mfma_f32_16x16x32_bf16 v[76:79], v[214:217], v[188:191], v[76:79]
	v_mfma_f32_16x16x32_bf16 v[68:71], v[206:209], v[196:199], v[68:71]
	v_mfma_f32_16x16x32_bf16 v[64:67], v[214:217], v[196:199], v[64:67]
	s_setprio 0
	s_mov_b32 m0, s52
	s_add_u32 s8, s36, 0x80
	s_addc_u32 s9, s37, 0
	s_barrier
	ds_read_b128 v[168:171], v166 offset:49152
	ds_read_b128 v[172:175], v166 offset:50176
	ds_read_b128 v[176:179], v166 offset:51200
	ds_read_b128 v[180:183], v166 offset:52224
	ds_read_b128 v[184:187], v166 offset:53248
	ds_read_b128 v[188:191], v166 offset:54272
	ds_read_b128 v[192:195], v166 offset:55296
	ds_read_b128 v[196:199], v166 offset:56320
	global_load_lds_dwordx4 v134, s[8:9]
	s_mov_b32 m0, s53
	s_nop 0
	global_load_lds_dwordx4 v130, s[8:9]
	s_barrier
	s_waitcnt lgkmcnt(0)
	s_setprio 1
	s_waitcnt lgkmcnt(0)
	v_mfma_f32_16x16x32_bf16 v[60:63], v[144:147], v[168:171], v[60:63]
	v_mfma_f32_16x16x32_bf16 v[56:59], v[152:155], v[168:171], v[56:59]
	v_mfma_f32_16x16x32_bf16 v[48:51], v[144:147], v[176:179], v[48:51]
	v_mfma_f32_16x16x32_bf16 v[40:43], v[152:155], v[176:179], v[40:43]
	v_mfma_f32_16x16x32_bf16 v[32:35], v[144:147], v[184:187], v[32:35]
	v_mfma_f32_16x16x32_bf16 v[24:27], v[152:155], v[184:187], v[24:27]
	v_mfma_f32_16x16x32_bf16 v[16:19], v[144:147], v[192:195], v[16:19]
	v_mfma_f32_16x16x32_bf16 v[8:11], v[152:155], v[192:195], v[8:11]
	v_mfma_f32_16x16x32_bf16 v[60:63], v[148:151], v[172:175], v[60:63]
	v_mfma_f32_16x16x32_bf16 v[56:59], v[156:159], v[172:175], v[56:59]
	v_mfma_f32_16x16x32_bf16 v[48:51], v[148:151], v[180:183], v[48:51]
	v_mfma_f32_16x16x32_bf16 v[40:43], v[156:159], v[180:183], v[40:43]
	v_mfma_f32_16x16x32_bf16 v[32:35], v[148:151], v[188:191], v[32:35]
	v_mfma_f32_16x16x32_bf16 v[24:27], v[156:159], v[188:191], v[24:27]
	v_mfma_f32_16x16x32_bf16 v[16:19], v[148:151], v[196:199], v[16:19]
	v_mfma_f32_16x16x32_bf16 v[8:11], v[156:159], v[196:199], v[8:11]
	s_setprio 0
	s_barrier
	s_add_u32 s16, s34, 0xb0080
	s_addc_u32 s17, s35, 0
	s_add_i32 s20, s21, s40
	s_mov_b32 m0, s20
	s_nop 0
	global_load_lds_dwordx4 v132, s[16:17]
	s_add_i32 m0, s20, 0x2000
	s_nop 0
	global_load_lds_dwordx4 v128, s[16:17]
	s_waitcnt vmcnt(6)
	s_barrier
	s_setprio 1
	v_mfma_f32_16x16x32_bf16 v[52:55], v[202:205], v[168:171], v[52:55]
	v_mfma_f32_16x16x32_bf16 v[44:47], v[210:213], v[168:171], v[44:47]
	v_mfma_f32_16x16x32_bf16 v[36:39], v[202:205], v[176:179], v[36:39]
	v_mfma_f32_16x16x32_bf16 v[28:31], v[210:213], v[176:179], v[28:31]
	v_mfma_f32_16x16x32_bf16 v[20:23], v[202:205], v[184:187], v[20:23]
	v_mfma_f32_16x16x32_bf16 v[12:15], v[210:213], v[184:187], v[12:15]
	v_mfma_f32_16x16x32_bf16 v[4:7], v[202:205], v[192:195], v[4:7]
	v_mfma_f32_16x16x32_bf16 v[0:3], v[210:213], v[192:195], v[0:3]
	v_mfma_f32_16x16x32_bf16 v[52:55], v[206:209], v[172:175], v[52:55]
	v_mfma_f32_16x16x32_bf16 v[44:47], v[214:217], v[172:175], v[44:47]
	v_mfma_f32_16x16x32_bf16 v[36:39], v[206:209], v[180:183], v[36:39]
	v_mfma_f32_16x16x32_bf16 v[28:31], v[214:217], v[180:183], v[28:31]
	v_mfma_f32_16x16x32_bf16 v[20:23], v[206:209], v[188:191], v[20:23]
	v_mfma_f32_16x16x32_bf16 v[12:15], v[214:217], v[188:191], v[12:15]
	v_mfma_f32_16x16x32_bf16 v[4:7], v[206:209], v[196:199], v[4:7]
	v_mfma_f32_16x16x32_bf16 v[0:3], v[214:217], v[196:199], v[0:3]
	s_setprio 0
	s_add_i32 s68, s68, 2
	s_add_u32 s0, s0, 0x100
	s_addc_u32 s67, s67, 0
	s_cmp_gt_u32 s68, 41
	s_mov_b64 s[26:27], s[28:29]
	s_barrier
	s_cbranch_scc0 .LBB0_305
	s_lshl_b32 s0, s66, 8
	v_mov_b32_e32 v145, v163
	v_mov_b32_e32 v144, v162
	s_cmpk_lt_i32 s66, 0x100
	s_cbranch_scc0 .LBB0_308
	s_ashr_i32 s29, s0, 31
	s_mov_b32 s28, s0
	s_lshl_b64 s[16:17], s[28:29], 12
	v_readlane_b32 s80, v254, 23
	v_readlane_b32 s81, v254, 24
	s_add_u32 s26, s80, s16
	v_readlane_b32 s82, v254, 25
	v_readlane_b32 s83, v254, 26
	v_readlane_b32 s84, v254, 27
	v_readlane_b32 s85, v254, 28
	v_readlane_b32 s86, v254, 29
	v_readlane_b32 s87, v254, 30
	v_readlane_b32 s88, v254, 31
	v_readlane_b32 s89, v254, 32
	v_readlane_b32 s90, v254, 33
	v_readlane_b32 s91, v254, 34
	v_readlane_b32 s92, v254, 35
	v_readlane_b32 s93, v254, 36
	v_readlane_b32 s94, v254, 37
	v_readlane_b32 s95, v254, 38
	s_addc_u32 s27, s81, s17
	s_cbranch_execnz .LBB0_297
	s_branch .LBB0_296

; #define PG8_STAGE(bufoff, gbase, voff) do { _Pragma("unroll") for (int _i = 0; _i < 2; ++_i) \
;         __builtin_amdgcn_global_load_lds((const unsigned*)((const char*)(gbase) + (voff)[_i]), (LAS unsigned*)(lds + (bufoff) + ldsw + _i * 8192), 16, 0, 0); } while (0)
; #define PG8_LDA(dst, b, h) do { _Pragma("unroll") for (int m = 0; m < 4; ++m) _Pragma("unroll") for (int k = 0; k < 2; ++k) dst[m][k] = *(const LAS bf16x8*)(lds + PG8_SA(b, h) + aoff + m * 2048 + k * 1024); } while (0)
; #define PG8_LDB(dst, b, h) do { _Pragma("unroll") for (int n = 0; n < 2; ++n) _Pragma("unroll") for (int k = 0; k < 2; ++k) dst[n][k] = *(const LAS bf16x8*)(lds + PG8_SB(b, h) + boff + n * 2048 + k * 1024); } while (0)
; #define PG8_MMA(ai, bj, At, Bt) do { __builtin_amdgcn_s_setprio(1); _Pragma("unroll") for (int m = 0; m < 4; ++m) _Pragma("unroll") for (int n = 0; n < 2; ++n) _Pragma("unroll") for (int k = 0; k < 2; ++k) \
;         acc[ai][bj][m][n] = __builtin_amdgcn_mfma_f32_16x16x32_bf16(Bt[n][k], At[m][k], acc[ai][bj][m][n], 0, 0, 0); __builtin_amdgcn_s_setprio(0); } while (0)
; #define PG8_WAIT_L(n) asm volatile("s_waitcnt lgkmcnt(" #n ")" ::: "memory")
; #define PG8_BAR __builtin_amdgcn_s_barrier()
; #define PG8_SCHED __builtin_amdgcn_sched_barrier(0)
; template <class Epi, class Sched>
; __device__ __forceinline__ void gemm_phase(LAS unsigned char* lds, const Gemm g, const Sched& S, const Epi& E) {
;     ...
;         for (int t = 0; t < nt; t += 2) {
;             const bool last = (t == nt - 2);
;             const char* a1 = cA + (size_t)(t + 1) * kstep;
;             const char* a2 = last ? nA : cA + (size_t)(t + 2) * kstep; const char* b2 = last ? nB : cB + (size_t)(t + 2) * kstep;
;             const char* a3 = a2 + kstep; const char* b3 = b2 + kstep;
;             PG8_LDB(B0, 0, 0); PG8_SCHED; PG8_LDA(At, 0, 0); PG8_STAGE(PG8_SA(1, 1), a1 + hstep, voffA);
;             PG8_WAIT_L(8); PG8_BAR; PG8_WAIT_L(0); PG8_MMA(0, 0, At, B0); PG8_BAR; PG8_SCHED;
;             PG8_LDB(B1, 0, 1); PG8_STAGE(PG8_SB(0, 0), b2, voffB);
;             PG8_BAR; PG8_WAIT_L(0); PG8_MMA(0, 1, At, B1); PG8_BAR;
;             PG8_LDA(At, 0, 1); PG8_STAGE(PG8_SA(0, 0), a2, voffA);
;             PG8_BAR; PG8_WAIT_L(0); PG8_MMA(1, 0, At, B0); PG8_BAR; PG8_SCHED;
.LBB0_577:
	s_ashr_i32 s21, s20, 31
	v_cmp_lt_i64_e32 vcc, s[22:23], v[156:157]
	s_lshl_b64 s[22:23], s[20:21], 19
	s_add_u32 s22, s96, s22
	s_addc_u32 s23, s97, s23
	s_and_b64 s[24:25], vcc, exec
	s_cselect_b32 s5, s23, s7
	s_cselect_b32 s21, s22, s6
	s_ashr_i32 s19, s18, 31
	s_lshl_b64 s[24:25], s[18:19], 19
	s_add_u32 s24, s31, s24
	s_addc_u32 s25, s33, s25
	s_and_b64 s[28:29], vcc, exec
	s_cselect_b32 s19, s25, s27
	s_cselect_b32 s53, s24, s26
	s_add_u32 s6, s6, 0x40080
	s_addc_u32 s7, s7, 0
	s_add_u32 s54, s26, 0x100
	s_addc_u32 s55, s27, 0
	s_mov_b32 s56, -2
	s_waitcnt lgkmcnt(0)
	ds_read_b128 v[128:131], v167
	ds_read_b128 v[132:135], v167 offset:1024
	ds_read_b128 v[136:139], v167 offset:2048
	ds_read_b128 v[160:163], v167 offset:3072
	s_add_u32 s26, s6, 0xfffc0080
	s_addc_u32 s27, s7, -1
	s_cmp_eq_u32 s56, 12
	s_cselect_b32 s29, s5, s27
	s_cselect_b32 s28, s21, s26
	s_cselect_b32 s27, s19, s55
	s_cselect_b32 s26, s53, s54
	s_add_i32 m0, s37, 0xc000
	ds_read_b128 v[170:173], v168
	ds_read_b128 v[174:177], v168 offset:1024
	ds_read_b128 v[178:181], v168 offset:2048
	ds_read_b128 v[182:185], v168 offset:3072
	ds_read_b128 v[186:189], v168 offset:4096
	ds_read_b128 v[190:193], v168 offset:5120
	ds_read_b128 v[194:197], v168 offset:6144
	ds_read_b128 v[202:205], v168 offset:7168
	global_load_lds_dwordx4 v152, s[6:7]
	s_add_i32 m0, s37, 0xe000
	s_nop 0
	global_load_lds_dwordx4 v154, s[6:7]
	s_waitcnt lgkmcnt(8)
	s_barrier
	s_waitcnt lgkmcnt(0)
	s_setprio 1
	s_waitcnt lgkmcnt(0)
	v_mfma_f32_16x16x32_bf16 v[124:127], v[128:131], v[170:173], 0
	v_mfma_f32_16x16x32_bf16 v[120:123], v[136:139], v[170:173], 0
	v_mfma_f32_16x16x32_bf16 v[108:111], v[128:131], v[178:181], 0
	v_mfma_f32_16x16x32_bf16 v[104:107], v[136:139], v[178:181], 0
	v_mfma_f32_16x16x32_bf16 v[92:95], v[128:131], v[186:189], 0
	v_mfma_f32_16x16x32_bf16 v[88:91], v[136:139], v[186:189], 0
	v_mfma_f32_16x16x32_bf16 v[76:79], v[128:131], v[194:197], 0
	v_mfma_f32_16x16x32_bf16 v[72:75], v[136:139], v[194:197], 0
	v_mfma_f32_16x16x32_bf16 v[124:127], v[132:135], v[174:177], v[124:127]
	v_mfma_f32_16x16x32_bf16 v[120:123], v[160:163], v[174:177], v[120:123]
	v_mfma_f32_16x16x32_bf16 v[108:111], v[132:135], v[182:185], v[108:111]
	v_mfma_f32_16x16x32_bf16 v[104:107], v[160:163], v[182:185], v[104:107]
	v_mfma_f32_16x16x32_bf16 v[92:95], v[132:135], v[190:193], v[92:95]
	v_mfma_f32_16x16x32_bf16 v[88:91], v[160:163], v[190:193], v[88:91]
	v_mfma_f32_16x16x32_bf16 v[76:79], v[132:135], v[202:205], v[76:79]
	v_mfma_f32_16x16x32_bf16 v[72:75], v[160:163], v[202:205], v[72:75]
	s_setprio 0
	s_barrier
	s_add_i32 s57, s48, s34
	s_mov_b32 m0, s57
	ds_read_b128 v[206:209], v169
	ds_read_b128 v[210:213], v169 offset:1024
	ds_read_b128 v[214:217], v169 offset:2048
	ds_read_b128 v[218:221], v169 offset:3072
	global_load_lds_dwordx4 v146, s[26:27]
	s_add_i32 m0, s57, 0x2000
	s_nop 0
	global_load_lds_dwordx4 v142, s[26:27]
	s_barrier
	s_waitcnt lgkmcnt(0)
	s_setprio 1
	s_waitcnt lgkmcnt(0)
	v_mfma_f32_16x16x32_bf16 v[116:119], v[206:209], v[170:173], 0
	v_mfma_f32_16x16x32_bf16 v[112:115], v[214:217], v[170:173], 0
	v_mfma_f32_16x16x32_bf16 v[100:103], v[206:209], v[178:181], 0
	v_mfma_f32_16x16x32_bf16 v[96:99], v[214:217], v[178:181], 0
	v_mfma_f32_16x16x32_bf16 v[84:87], v[206:209], v[186:189], 0
	v_mfma_f32_16x16x32_bf16 v[80:83], v[214:217], v[186:189], 0
	v_mfma_f32_16x16x32_bf16 v[68:71], v[206:209], v[194:197], 0
	v_mfma_f32_16x16x32_bf16 v[64:67], v[214:217], v[194:197], 0
	v_mfma_f32_16x16x32_bf16 v[116:119], v[210:213], v[174:177], v[116:119]
	v_mfma_f32_16x16x32_bf16 v[112:115], v[218:221], v[174:177], v[112:115]
	v_mfma_f32_16x16x32_bf16 v[100:103], v[210:213], v[182:185], v[100:103]
	v_mfma_f32_16x16x32_bf16 v[96:99], v[218:221], v[182:185], v[96:99]
	v_mfma_f32_16x16x32_bf16 v[84:87], v[210:213], v[190:193], v[84:87]
	v_mfma_f32_16x16x32_bf16 v[80:83], v[218:221], v[190:193], v[80:83]
	v_mfma_f32_16x16x32_bf16 v[68:71], v[210:213], v[202:205], v[68:71]
	v_mfma_f32_16x16x32_bf16 v[64:67], v[218:221], v[202:205], v[64:67]
	s_setprio 0
	s_mov_b32 m0, s37
	v_lshl_add_u64 v[222:223], s[28:29], 0, v[148:149]
	s_barrier
	ds_read_b128 v[170:173], v168 offset:16384
	ds_read_b128 v[174:177], v168 offset:17408
	ds_read_b128 v[178:181], v168 offset:18432
	ds_read_b128 v[182:185], v168 offset:19456
	ds_read_b128 v[186:189], v168 offset:20480
	ds_read_b128 v[190:193], v168 offset:21504
	ds_read_b128 v[194:197], v168 offset:22528
	ds_read_b128 v[202:205], v168 offset:23552
	global_load_lds_dwordx4 v148, s[28:29]
	v_lshl_add_u64 v[224:225], s[28:29], 0, v[144:145]
	s_mov_b32 m0, s38
	s_nop 0
	global_load_lds_dwordx4 v144, s[28:29]
	s_barrier
	s_waitcnt lgkmcnt(0)
	s_setprio 1
	s_waitcnt lgkmcnt(0)
	v_mfma_f32_16x16x32_bf16 v[60:63], v[128:131], v[170:173], 0
	v_mfma_f32_16x16x32_bf16 v[56:59], v[136:139], v[170:173], 0
	v_mfma_f32_16x16x32_bf16 v[44:47], v[128:131], v[178:181], 0
	v_mfma_f32_16x16x32_bf16 v[40:43], v[136:139], v[178:181], 0
	v_mfma_f32_16x16x32_bf16 v[28:31], v[128:131], v[186:189], 0
	v_mfma_f32_16x16x32_bf16 v[24:27], v[136:139], v[186:189], 0
	v_mfma_f32_16x16x32_bf16 v[12:15], v[128:131], v[194:197], 0
	v_mfma_f32_16x16x32_bf16 v[8:11], v[136:139], v[194:197], 0
	v_mfma_f32_16x16x32_bf16 v[60:63], v[132:135], v[174:177], v[60:63]
	v_mfma_f32_16x16x32_bf16 v[56:59], v[160:163], v[174:177], v[56:59]
	v_mfma_f32_16x16x32_bf16 v[44:47], v[132:135], v[182:185], v[44:47]
	v_mfma_f32_16x16x32_bf16 v[40:43], v[160:163], v[182:185], v[40:43]
	v_mfma_f32_16x16x32_bf16 v[28:31], v[132:135], v[190:193], v[28:31]
	v_mfma_f32_16x16x32_bf16 v[24:27], v[160:163], v[190:193], v[24:27]
	v_mfma_f32_16x16x32_bf16 v[12:15], v[132:135], v[202:205], v[12:15]
	v_mfma_f32_16x16x32_bf16 v[8:11], v[160:163], v[202:205], v[8:11]
	s_setprio 0
	s_barrier
; #define PG8_STAGE(bufoff, gbase, voff) do { _Pragma("unroll") for (int _i = 0; _i < 2; ++_i) \
;         __builtin_amdgcn_global_load_lds((const unsigned*)((const char*)(gbase) + (voff)[_i]), (LAS unsigned*)(lds + (bufoff) + ldsw + _i * 8192), 16, 0, 0); } while (0)
; #define PG8_LDA(dst, b, h) do { _Pragma("unroll") for (int m = 0; m < 4; ++m) _Pragma("unroll") for (int k = 0; k < 2; ++k) dst[m][k] = *(const LAS bf16x8*)(lds + PG8_SA(b, h) + aoff + m * 2048 + k * 1024); } while (0)
; #define PG8_LDB(dst, b, h) do { _Pragma("unroll") for (int n = 0; n < 2; ++n) _Pragma("unroll") for (int k = 0; k < 2; ++k) dst[n][k] = *(const LAS bf16x8*)(lds + PG8_SB(b, h) + boff + n * 2048 + k * 1024); } while (0)
; #define PG8_MMA(ai, bj, At, Bt) do { __builtin_amdgcn_s_setprio(1); _Pragma("unroll") for (int m = 0; m < 4; ++m) _Pragma("unroll") for (int n = 0; n < 2; ++n) _Pragma("unroll") for (int k = 0; k < 2; ++k) \
;         acc[ai][bj][m][n] = __builtin_amdgcn_mfma_f32_16x16x32_bf16(Bt[n][k], At[m][k], acc[ai][bj][m][n], 0, 0, 0); __builtin_amdgcn_s_setprio(0); } while (0)
; #define PG8_WAIT_V(n) asm volatile("s_waitcnt vmcnt(" #n ")" ::: "memory")
; #define PG8_WAIT_L(n) asm volatile("s_waitcnt lgkmcnt(" #n ")" ::: "memory")
; #define PG8_BAR __builtin_amdgcn_s_barrier()
; #define PG8_SCHED __builtin_amdgcn_sched_barrier(0)
; template <class Epi, class Sched>
; __device__ __forceinline__ void gemm_phase(LAS unsigned char* lds, const Gemm g, const Sched& S, const Epi& E) {
;     ...
;             PG8_BAR; PG8_WAIT_L(0); PG8_MMA(1, 0, At, B0); PG8_BAR; PG8_SCHED;
;             PG8_STAGE(PG8_SB(0, 1), b2 + hstep, voffB);
;             PG8_WAIT_V(6); PG8_BAR; PG8_MMA(1, 1, At, B1); PG8_BAR;
;             PG8_LDB(B0, 1, 0); PG8_SCHED; PG8_LDA(At, 1, 0); PG8_STAGE(PG8_SA(0, 1), a2 + hstep, voffA);
;             PG8_WAIT_L(8); PG8_BAR; PG8_WAIT_L(0); PG8_MMA(0, 0, At, B0); PG8_BAR; PG8_SCHED;
;             PG8_LDB(B1, 1, 1); PG8_STAGE(PG8_SB(1, 0), b3, voffB);
;             PG8_BAR; PG8_WAIT_L(0); PG8_MMA(0, 1, At, B1); PG8_BAR;
;             PG8_LDA(At, 1, 1); PG8_STAGE(PG8_SA(1, 0), a3, voffA);
;             PG8_BAR; PG8_WAIT_L(0); PG8_MMA(1, 0, At, B0); PG8_BAR; PG8_SCHED;
	s_add_u32 s58, s26, 0x40000
	s_addc_u32 s59, s27, 0
	s_add_i32 s57, s49, s34
	s_mov_b32 m0, s57
	s_nop 0
	global_load_lds_dwordx4 v146, s[58:59]
	s_add_i32 m0, s57, 0x2000
	s_nop 0
	global_load_lds_dwordx4 v142, s[58:59]
	s_waitcnt vmcnt(6)
	s_barrier
	s_setprio 1
	v_mfma_f32_16x16x32_bf16 v[52:55], v[206:209], v[170:173], 0
	v_mfma_f32_16x16x32_bf16 v[48:51], v[214:217], v[170:173], 0
	v_mfma_f32_16x16x32_bf16 v[36:39], v[206:209], v[178:181], 0
	v_mfma_f32_16x16x32_bf16 v[32:35], v[214:217], v[178:181], 0
	v_mfma_f32_16x16x32_bf16 v[20:23], v[206:209], v[186:189], 0
	v_mfma_f32_16x16x32_bf16 v[16:19], v[214:217], v[186:189], 0
	v_mfma_f32_16x16x32_bf16 v[4:7], v[206:209], v[194:197], 0
	v_mfma_f32_16x16x32_bf16 v[0:3], v[214:217], v[194:197], 0
	v_mfma_f32_16x16x32_bf16 v[52:55], v[210:213], v[174:177], v[52:55]
	v_mfma_f32_16x16x32_bf16 v[48:51], v[218:221], v[174:177], v[48:51]
	v_mfma_f32_16x16x32_bf16 v[36:39], v[210:213], v[182:185], v[36:39]
	v_mfma_f32_16x16x32_bf16 v[32:35], v[218:221], v[182:185], v[32:35]
	v_mfma_f32_16x16x32_bf16 v[20:23], v[210:213], v[190:193], v[20:23]
	v_mfma_f32_16x16x32_bf16 v[16:19], v[218:221], v[190:193], v[16:19]
	v_mfma_f32_16x16x32_bf16 v[4:7], v[210:213], v[202:205], v[4:7]
	v_mfma_f32_16x16x32_bf16 v[0:3], v[218:221], v[202:205], v[0:3]
	s_setprio 0
	s_add_i32 s57, 0, 0x18000
	v_add_u32_e32 v150, s57, v166
	s_barrier
	ds_read_b128 v[128:131], v150
	ds_read_b128 v[132:135], v150 offset:1024
	ds_read_b128 v[136:139], v150 offset:2048
	ds_read_b128 v[160:163], v150 offset:3072
	s_add_u32 s28, s28, 0x40000
	s_addc_u32 s29, s29, 0
	s_mov_b32 m0, s39
	ds_read_b128 v[170:173], v168 offset:32768
	ds_read_b128 v[174:177], v168 offset:33792
	ds_read_b128 v[178:181], v168 offset:34816
	ds_read_b128 v[182:185], v168 offset:35840
	ds_read_b128 v[186:189], v168 offset:36864
	ds_read_b128 v[190:193], v168 offset:37888
	ds_read_b128 v[194:197], v168 offset:38912
	ds_read_b128 v[202:205], v168 offset:39936
	global_load_lds_dwordx4 v148, s[28:29]
	s_mov_b32 m0, s40
	s_nop 0
	global_load_lds_dwordx4 v144, s[28:29]
	s_waitcnt lgkmcnt(8)
	s_barrier
	s_waitcnt lgkmcnt(0)
	s_setprio 1
	s_waitcnt lgkmcnt(0)
	v_mfma_f32_16x16x32_bf16 v[124:127], v[128:131], v[170:173], v[124:127]
	v_mfma_f32_16x16x32_bf16 v[120:123], v[136:139], v[170:173], v[120:123]
	v_mfma_f32_16x16x32_bf16 v[108:111], v[128:131], v[178:181], v[108:111]
	v_mfma_f32_16x16x32_bf16 v[104:107], v[136:139], v[178:181], v[104:107]
	v_mfma_f32_16x16x32_bf16 v[92:95], v[128:131], v[186:189], v[92:95]
	v_mfma_f32_16x16x32_bf16 v[88:91], v[136:139], v[186:189], v[88:91]
	v_mfma_f32_16x16x32_bf16 v[76:79], v[128:131], v[194:197], v[76:79]
	v_mfma_f32_16x16x32_bf16 v[72:75], v[136:139], v[194:197], v[72:75]
	v_mfma_f32_16x16x32_bf16 v[124:127], v[132:135], v[174:177], v[124:127]
	v_mfma_f32_16x16x32_bf16 v[120:123], v[160:163], v[174:177], v[120:123]
	v_mfma_f32_16x16x32_bf16 v[108:111], v[132:135], v[182:185], v[108:111]
	v_mfma_f32_16x16x32_bf16 v[104:107], v[160:163], v[182:185], v[104:107]
	v_mfma_f32_16x16x32_bf16 v[92:95], v[132:135], v[190:193], v[92:95]
	v_mfma_f32_16x16x32_bf16 v[88:91], v[160:163], v[190:193], v[88:91]
	v_mfma_f32_16x16x32_bf16 v[76:79], v[132:135], v[202:205], v[76:79]
	v_mfma_f32_16x16x32_bf16 v[72:75], v[160:163], v[202:205], v[72:75]
	s_setprio 0
	s_barrier
	s_add_i32 s28, 0, 0x1c000
	s_add_i32 s29, s57, s34
	v_add_u32_e32 v150, s28, v166
	s_add_u32 s0, s26, 0x80
	s_addc_u32 s1, s27, 0
	s_mov_b32 m0, s29
	ds_read_b128 v[206:209], v150
	ds_read_b128 v[210:213], v150 offset:1024
	ds_read_b128 v[214:217], v150 offset:2048
	ds_read_b128 v[218:221], v150 offset:3072
	global_load_lds_dwordx4 v146, s[0:1]
	s_add_i32 m0, s29, 0x2000
	s_nop 0
	global_load_lds_dwordx4 v142, s[0:1]
	s_barrier
	s_waitcnt lgkmcnt(0)
	s_setprio 1
	s_waitcnt lgkmcnt(0)
	v_mfma_f32_16x16x32_bf16 v[116:119], v[206:209], v[170:173], v[116:119]
	v_mfma_f32_16x16x32_bf16 v[112:115], v[214:217], v[170:173], v[112:115]
	v_mfma_f32_16x16x32_bf16 v[100:103], v[206:209], v[178:181], v[100:103]
	v_mfma_f32_16x16x32_bf16 v[96:99], v[214:217], v[178:181], v[96:99]
	v_mfma_f32_16x16x32_bf16 v[84:87], v[206:209], v[186:189], v[84:87]
	v_mfma_f32_16x16x32_bf16 v[80:83], v[214:217], v[186:189], v[80:83]
	v_mfma_f32_16x16x32_bf16 v[68:71], v[206:209], v[194:197], v[68:71]
	v_mfma_f32_16x16x32_bf16 v[64:67], v[214:217], v[194:197], v[64:67]
	v_mfma_f32_16x16x32_bf16 v[116:119], v[210:213], v[174:177], v[116:119]
	v_mfma_f32_16x16x32_bf16 v[112:115], v[218:221], v[174:177], v[112:115]
	v_mfma_f32_16x16x32_bf16 v[100:103], v[210:213], v[182:185], v[100:103]
	v_mfma_f32_16x16x32_bf16 v[96:99], v[218:221], v[182:185], v[96:99]
	v_mfma_f32_16x16x32_bf16 v[84:87], v[210:213], v[190:193], v[84:87]
	v_mfma_f32_16x16x32_bf16 v[80:83], v[218:221], v[190:193], v[80:83]
	v_mfma_f32_16x16x32_bf16 v[68:71], v[210:213], v[202:205], v[68:71]
	v_mfma_f32_16x16x32_bf16 v[64:67], v[218:221], v[202:205], v[64:67]
	s_setprio 0
	s_mov_b32 m0, s44
	s_mov_b64 s[0:1], 0x80
	v_lshl_add_u64 v[140:141], v[222:223], 0, s[0:1]
	s_barrier
	ds_read_b128 v[170:173], v168 offset:49152
	ds_read_b128 v[174:177], v168 offset:50176
	ds_read_b128 v[178:181], v168 offset:51200
	ds_read_b128 v[182:185], v168 offset:52224
	ds_read_b128 v[186:189], v168 offset:53248
	ds_read_b128 v[190:193], v168 offset:54272
	ds_read_b128 v[194:197], v168 offset:55296
	ds_read_b128 v[202:205], v168 offset:56320
	global_load_lds_dwordx4 v[140:141], off
	v_lshl_add_u64 v[140:141], v[224:225], 0, s[0:1]
	s_mov_b32 m0, s45
	s_nop 0
	global_load_lds_dwordx4 v[140:141], off
	s_barrier
; #define PG8_STAGE(bufoff, gbase, voff) do { _Pragma("unroll") for (int _i = 0; _i < 2; ++_i) \
;         __builtin_amdgcn_global_load_lds((const unsigned*)((const char*)(gbase) + (voff)[_i]), (LAS unsigned*)(lds + (bufoff) + ldsw + _i * 8192), 16, 0, 0); } while (0)
; #define PG8_LDA(dst, b, h) do { _Pragma("unroll") for (int m = 0; m < 4; ++m) _Pragma("unroll") for (int k = 0; k < 2; ++k) dst[m][k] = *(const LAS bf16x8*)(lds + PG8_SA(b, h) + aoff + m * 2048 + k * 1024); } while (0)
; #define PG8_WAIT_V(n) asm volatile("s_waitcnt vmcnt(" #n ")" ::: "memory")
; #define PG8_WAIT_L(n) asm volatile("s_waitcnt lgkmcnt(" #n ")" ::: "memory")
; template <class Epi, class Sched>
; __device__ __forceinline__ void gemm_phase(LAS unsigned char* lds, const Gemm g, const Sched& S, const Epi& E) {
;     ...
;         for (int t = 0; t < nt; t += 2) {
;             const bool last = (t == nt - 2);
;             const char* a1 = cA + (size_t)(t + 1) * kstep;
;             const char* a2 = last ? nA : cA + (size_t)(t + 2) * kstep; const char* b2 = last ? nB : cB + (size_t)(t + 2) * kstep;
;             const char* a3 = a2 + kstep; const char* b3 = b2 + kstep;
;             PG8_LDB(B0, 0, 0); PG8_SCHED; PG8_LDA(At, 0, 0); PG8_STAGE(PG8_SA(1, 1), a1 + hstep, voffA);
;             PG8_WAIT_L(8); PG8_BAR; PG8_WAIT_L(0); PG8_MMA(0, 0, At, B0); PG8_BAR; PG8_SCHED;
;             PG8_LDB(B1, 0, 1); PG8_STAGE(PG8_SB(0, 0), b2, voffB);
;             PG8_BAR; PG8_WAIT_L(0); PG8_MMA(0, 1, At, B1); PG8_BAR;
;             PG8_LDA(At, 0, 1); PG8_STAGE(PG8_SA(0, 0), a2, voffA);
;             PG8_BAR; PG8_WAIT_L(0); PG8_MMA(1, 0, At, B0); PG8_BAR; PG8_SCHED;
;             PG8_STAGE(PG8_SB(0, 1), b2 + hstep, voffB);
;             PG8_WAIT_V(6); PG8_BAR; PG8_MMA(1, 1, At, B1); PG8_BAR;
;             PG8_LDB(B0, 1, 0); PG8_SCHED; PG8_LDA(At, 1, 0); PG8_STAGE(PG8_SA(0, 1), a2 + hstep, voffA);
;             PG8_WAIT_L(8); PG8_BAR; PG8_WAIT_L(0); PG8_MMA(0, 0, At, B0); PG8_BAR; PG8_SCHED;
;             PG8_LDB(B1, 1, 1); PG8_STAGE(PG8_SB(1, 0), b3, voffB);
;             PG8_BAR; PG8_WAIT_L(0); PG8_MMA(0, 1, At, B1); PG8_BAR;
;             PG8_LDA(At, 1, 1); PG8_STAGE(PG8_SA(1, 0), a3, voffA);
;             PG8_BAR; PG8_WAIT_L(0); PG8_MMA(1, 0, At, B0); PG8_BAR; PG8_SCHED;
;             PG8_STAGE(PG8_SB(1, 1), b3 + hstep, voffB);
;             PG8_WAIT_V(6); PG8_BAR; PG8_MMA(1, 1, At, B1); PG8_BAR;
	s_waitcnt lgkmcnt(0)
	s_setprio 1
	s_waitcnt lgkmcnt(0)
	v_mfma_f32_16x16x32_bf16 v[60:63], v[128:131], v[170:173], v[60:63]
	v_mfma_f32_16x16x32_bf16 v[56:59], v[136:139], v[170:173], v[56:59]
	v_mfma_f32_16x16x32_bf16 v[44:47], v[128:131], v[178:181], v[44:47]
	v_mfma_f32_16x16x32_bf16 v[40:43], v[136:139], v[178:181], v[40:43]
	v_mfma_f32_16x16x32_bf16 v[28:31], v[128:131], v[186:189], v[28:31]
	v_mfma_f32_16x16x32_bf16 v[24:27], v[136:139], v[186:189], v[24:27]
	v_mfma_f32_16x16x32_bf16 v[12:15], v[128:131], v[194:197], v[12:15]
	v_mfma_f32_16x16x32_bf16 v[8:11], v[136:139], v[194:197], v[8:11]
	v_mfma_f32_16x16x32_bf16 v[60:63], v[132:135], v[174:177], v[60:63]
	v_mfma_f32_16x16x32_bf16 v[56:59], v[160:163], v[174:177], v[56:59]
	v_mfma_f32_16x16x32_bf16 v[44:47], v[132:135], v[182:185], v[44:47]
	v_mfma_f32_16x16x32_bf16 v[40:43], v[160:163], v[182:185], v[40:43]
	v_mfma_f32_16x16x32_bf16 v[28:31], v[132:135], v[190:193], v[28:31]
	v_mfma_f32_16x16x32_bf16 v[24:27], v[160:163], v[190:193], v[24:27]
	v_mfma_f32_16x16x32_bf16 v[12:15], v[132:135], v[202:205], v[12:15]
	v_mfma_f32_16x16x32_bf16 v[8:11], v[160:163], v[202:205], v[8:11]
	s_setprio 0
	s_barrier
	s_add_u32 s26, s26, 0x40080
	s_addc_u32 s27, s27, 0
	s_add_i32 s28, s28, s34
	s_mov_b32 m0, s28
	s_nop 0
	global_load_lds_dwordx4 v146, s[26:27]
	s_add_i32 m0, s28, 0x2000
	s_nop 0
	global_load_lds_dwordx4 v142, s[26:27]
	s_waitcnt vmcnt(6)
	s_barrier
	s_setprio 1
	v_mfma_f32_16x16x32_bf16 v[52:55], v[206:209], v[170:173], v[52:55]
	v_mfma_f32_16x16x32_bf16 v[48:51], v[214:217], v[170:173], v[48:51]
	v_mfma_f32_16x16x32_bf16 v[36:39], v[206:209], v[178:181], v[36:39]
	v_mfma_f32_16x16x32_bf16 v[32:35], v[214:217], v[178:181], v[32:35]
	v_mfma_f32_16x16x32_bf16 v[20:23], v[206:209], v[186:189], v[20:23]
	v_mfma_f32_16x16x32_bf16 v[16:19], v[214:217], v[186:189], v[16:19]
	v_mfma_f32_16x16x32_bf16 v[4:7], v[206:209], v[194:197], v[4:7]
	v_mfma_f32_16x16x32_bf16 v[0:3], v[214:217], v[194:197], v[0:3]
	v_mfma_f32_16x16x32_bf16 v[52:55], v[210:213], v[174:177], v[52:55]
	v_mfma_f32_16x16x32_bf16 v[48:51], v[218:221], v[174:177], v[48:51]
	v_mfma_f32_16x16x32_bf16 v[36:39], v[210:213], v[182:185], v[36:39]
	v_mfma_f32_16x16x32_bf16 v[32:35], v[218:221], v[182:185], v[32:35]
	v_mfma_f32_16x16x32_bf16 v[20:23], v[210:213], v[190:193], v[20:23]
	v_mfma_f32_16x16x32_bf16 v[16:19], v[218:221], v[190:193], v[16:19]
	v_mfma_f32_16x16x32_bf16 v[4:7], v[210:213], v[202:205], v[4:7]
	v_mfma_f32_16x16x32_bf16 v[0:3], v[218:221], v[202:205], v[0:3]
	s_setprio 0
	s_add_i32 s56, s56, 2
	s_add_u32 s6, s6, 0x100
	s_addc_u32 s7, s7, 0
	s_add_u32 s54, s54, 0x100
	s_addc_u32 s55, s55, 0
	s_cmp_gt_u32 s56, 13
	s_barrier
.LBB0_578:
	ds_read_b128 v[128:131], v167
	ds_read_b128 v[132:135], v167 offset:1024
	ds_read_b128 v[136:139], v167 offset:2048
	ds_read_b128 v[160:163], v167 offset:3072
	s_add_u32 s26, s6, 0xfffc0080
	s_addc_u32 s27, s7, -1
	s_cmp_eq_u32 s56, 12
	s_cselect_b32 s29, s5, s27
	s_cselect_b32 s28, s21, s26
	s_cselect_b32 s27, s19, s55
	s_cselect_b32 s26, s53, s54
	s_add_i32 m0, s37, 0xc000
	ds_read_b128 v[170:173], v168
	ds_read_b128 v[174:177], v168 offset:1024
	ds_read_b128 v[178:181], v168 offset:2048
	ds_read_b128 v[182:185], v168 offset:3072
	ds_read_b128 v[186:189], v168 offset:4096
	ds_read_b128 v[190:193], v168 offset:5120
	ds_read_b128 v[194:197], v168 offset:6144
	ds_read_b128 v[202:205], v168 offset:7168
	global_load_lds_dwordx4 v152, s[6:7]
	s_add_i32 m0, s37, 0xe000
	s_nop 0
	global_load_lds_dwordx4 v154, s[6:7]
	s_waitcnt lgkmcnt(8)
	s_barrier
	s_waitcnt lgkmcnt(0)
	s_setprio 1
	s_waitcnt lgkmcnt(0)
	v_mfma_f32_16x16x32_bf16 v[124:127], v[128:131], v[170:173], v[124:127]
	v_mfma_f32_16x16x32_bf16 v[120:123], v[136:139], v[170:173], v[120:123]
	v_mfma_f32_16x16x32_bf16 v[108:111], v[128:131], v[178:181], v[108:111]
	v_mfma_f32_16x16x32_bf16 v[104:107], v[136:139], v[178:181], v[104:107]
	v_mfma_f32_16x16x32_bf16 v[92:95], v[128:131], v[186:189], v[92:95]
	v_mfma_f32_16x16x32_bf16 v[88:91], v[136:139], v[186:189], v[88:91]
	v_mfma_f32_16x16x32_bf16 v[76:79], v[128:131], v[194:197], v[76:79]
	v_mfma_f32_16x16x32_bf16 v[72:75], v[136:139], v[194:197], v[72:75]
	v_mfma_f32_16x16x32_bf16 v[124:127], v[132:135], v[174:177], v[124:127]
	v_mfma_f32_16x16x32_bf16 v[120:123], v[160:163], v[174:177], v[120:123]
	v_mfma_f32_16x16x32_bf16 v[108:111], v[132:135], v[182:185], v[108:111]
	v_mfma_f32_16x16x32_bf16 v[104:107], v[160:163], v[182:185], v[104:107]
	v_mfma_f32_16x16x32_bf16 v[92:95], v[132:135], v[190:193], v[92:95]
	v_mfma_f32_16x16x32_bf16 v[88:91], v[160:163], v[190:193], v[88:91]
	v_mfma_f32_16x16x32_bf16 v[76:79], v[132:135], v[202:205], v[76:79]
	v_mfma_f32_16x16x32_bf16 v[72:75], v[160:163], v[202:205], v[72:75]
	s_setprio 0
	s_barrier
	s_add_i32 s57, s48, s34
	s_mov_b32 m0, s57
	ds_read_b128 v[206:209], v169
	ds_read_b128 v[210:213], v169 offset:1024
	ds_read_b128 v[214:217], v169 offset:2048
	ds_read_b128 v[218:221], v169 offset:3072
	global_load_lds_dwordx4 v146, s[26:27]
	s_add_i32 m0, s57, 0x2000
	s_nop 0
	global_load_lds_dwordx4 v142, s[26:27]
	s_barrier
; #define PG8_STAGE(bufoff, gbase, voff) do { _Pragma("unroll") for (int _i = 0; _i < 2; ++_i) \
;         __builtin_amdgcn_global_load_lds((const unsigned*)((const char*)(gbase) + (voff)[_i]), (LAS unsigned*)(lds + (bufoff) + ldsw + _i * 8192), 16, 0, 0); } while (0)
; #define PG8_LDA(dst, b, h) do { _Pragma("unroll") for (int m = 0; m < 4; ++m) _Pragma("unroll") for (int k = 0; k < 2; ++k) dst[m][k] = *(const LAS bf16x8*)(lds + PG8_SA(b, h) + aoff + m * 2048 + k * 1024); } while (0)
; #define PG8_LDB(dst, b, h) do { _Pragma("unroll") for (int n = 0; n < 2; ++n) _Pragma("unroll") for (int k = 0; k < 2; ++k) dst[n][k] = *(const LAS bf16x8*)(lds + PG8_SB(b, h) + boff + n * 2048 + k * 1024); } while (0)
; #define PG8_MMA(ai, bj, At, Bt) do { __builtin_amdgcn_s_setprio(1); _Pragma("unroll") for (int m = 0; m < 4; ++m) _Pragma("unroll") for (int n = 0; n < 2; ++n) _Pragma("unroll") for (int k = 0; k < 2; ++k) \
;         acc[ai][bj][m][n] = __builtin_amdgcn_mfma_f32_16x16x32_bf16(Bt[n][k], At[m][k], acc[ai][bj][m][n], 0, 0, 0); __builtin_amdgcn_s_setprio(0); } while (0)
; #define PG8_WAIT_V(n) asm volatile("s_waitcnt vmcnt(" #n ")" ::: "memory")
; #define PG8_WAIT_L(n) asm volatile("s_waitcnt lgkmcnt(" #n ")" ::: "memory")
; #define PG8_BAR __builtin_amdgcn_s_barrier()
; #define PG8_SCHED __builtin_amdgcn_sched_barrier(0)
; template <class Epi, class Sched>
; __device__ __forceinline__ void gemm_phase(LAS unsigned char* lds, const Gemm g, const Sched& S, const Epi& E) {
;     ...
;             PG8_BAR; PG8_WAIT_L(0); PG8_MMA(0, 1, At, B1); PG8_BAR;
;             PG8_LDA(At, 0, 1); PG8_STAGE(PG8_SA(0, 0), a2, voffA);
;             PG8_BAR; PG8_WAIT_L(0); PG8_MMA(1, 0, At, B0); PG8_BAR; PG8_SCHED;
;             PG8_STAGE(PG8_SB(0, 1), b2 + hstep, voffB);
;             PG8_WAIT_V(6); PG8_BAR; PG8_MMA(1, 1, At, B1); PG8_BAR;
;             PG8_LDB(B0, 1, 0); PG8_SCHED; PG8_LDA(At, 1, 0); PG8_STAGE(PG8_SA(0, 1), a2 + hstep, voffA);
;             PG8_WAIT_L(8); PG8_BAR; PG8_WAIT_L(0); PG8_MMA(0, 0, At, B0); PG8_BAR; PG8_SCHED;
	s_waitcnt lgkmcnt(0)
	s_setprio 1
	s_waitcnt lgkmcnt(0)
	v_mfma_f32_16x16x32_bf16 v[116:119], v[206:209], v[170:173], v[116:119]
	v_mfma_f32_16x16x32_bf16 v[112:115], v[214:217], v[170:173], v[112:115]
	v_mfma_f32_16x16x32_bf16 v[100:103], v[206:209], v[178:181], v[100:103]
	v_mfma_f32_16x16x32_bf16 v[96:99], v[214:217], v[178:181], v[96:99]
	v_mfma_f32_16x16x32_bf16 v[84:87], v[206:209], v[186:189], v[84:87]
	v_mfma_f32_16x16x32_bf16 v[80:83], v[214:217], v[186:189], v[80:83]
	v_mfma_f32_16x16x32_bf16 v[68:71], v[206:209], v[194:197], v[68:71]
	v_mfma_f32_16x16x32_bf16 v[64:67], v[214:217], v[194:197], v[64:67]
	v_mfma_f32_16x16x32_bf16 v[116:119], v[210:213], v[174:177], v[116:119]
	v_mfma_f32_16x16x32_bf16 v[112:115], v[218:221], v[174:177], v[112:115]
	v_mfma_f32_16x16x32_bf16 v[100:103], v[210:213], v[182:185], v[100:103]
	v_mfma_f32_16x16x32_bf16 v[96:99], v[218:221], v[182:185], v[96:99]
	v_mfma_f32_16x16x32_bf16 v[84:87], v[210:213], v[190:193], v[84:87]
	v_mfma_f32_16x16x32_bf16 v[80:83], v[218:221], v[190:193], v[80:83]
	v_mfma_f32_16x16x32_bf16 v[68:71], v[210:213], v[202:205], v[68:71]
	v_mfma_f32_16x16x32_bf16 v[64:67], v[218:221], v[202:205], v[64:67]
	s_setprio 0
	s_mov_b32 m0, s37
	v_lshl_add_u64 v[222:223], s[28:29], 0, v[148:149]
	s_barrier
	ds_read_b128 v[170:173], v168 offset:16384
	ds_read_b128 v[174:177], v168 offset:17408
	ds_read_b128 v[178:181], v168 offset:18432
	ds_read_b128 v[182:185], v168 offset:19456
	ds_read_b128 v[186:189], v168 offset:20480
	ds_read_b128 v[190:193], v168 offset:21504
	ds_read_b128 v[194:197], v168 offset:22528
	ds_read_b128 v[202:205], v168 offset:23552
	global_load_lds_dwordx4 v148, s[28:29]
	v_lshl_add_u64 v[224:225], s[28:29], 0, v[144:145]
	s_mov_b32 m0, s38
	s_nop 0
	global_load_lds_dwordx4 v144, s[28:29]
	s_barrier
	s_waitcnt lgkmcnt(0)
	s_setprio 1
	s_waitcnt lgkmcnt(0)
	v_mfma_f32_16x16x32_bf16 v[60:63], v[128:131], v[170:173], v[60:63]
	v_mfma_f32_16x16x32_bf16 v[56:59], v[136:139], v[170:173], v[56:59]
	v_mfma_f32_16x16x32_bf16 v[44:47], v[128:131], v[178:181], v[44:47]
	v_mfma_f32_16x16x32_bf16 v[40:43], v[136:139], v[178:181], v[40:43]
	v_mfma_f32_16x16x32_bf16 v[28:31], v[128:131], v[186:189], v[28:31]
	v_mfma_f32_16x16x32_bf16 v[24:27], v[136:139], v[186:189], v[24:27]
	v_mfma_f32_16x16x32_bf16 v[12:15], v[128:131], v[194:197], v[12:15]
	v_mfma_f32_16x16x32_bf16 v[8:11], v[136:139], v[194:197], v[8:11]
	v_mfma_f32_16x16x32_bf16 v[60:63], v[132:135], v[174:177], v[60:63]
	v_mfma_f32_16x16x32_bf16 v[56:59], v[160:163], v[174:177], v[56:59]
	v_mfma_f32_16x16x32_bf16 v[44:47], v[132:135], v[182:185], v[44:47]
	v_mfma_f32_16x16x32_bf16 v[40:43], v[160:163], v[182:185], v[40:43]
	v_mfma_f32_16x16x32_bf16 v[28:31], v[132:135], v[190:193], v[28:31]
	v_mfma_f32_16x16x32_bf16 v[24:27], v[160:163], v[190:193], v[24:27]
	v_mfma_f32_16x16x32_bf16 v[12:15], v[132:135], v[202:205], v[12:15]
	v_mfma_f32_16x16x32_bf16 v[8:11], v[160:163], v[202:205], v[8:11]
	s_setprio 0
	s_barrier
	s_add_u32 s58, s26, 0x40000
	s_addc_u32 s59, s27, 0
	s_add_i32 s57, s49, s34
	s_mov_b32 m0, s57
	s_nop 0
	global_load_lds_dwordx4 v146, s[58:59]
	s_add_i32 m0, s57, 0x2000
	s_nop 0
	global_load_lds_dwordx4 v142, s[58:59]
	s_waitcnt vmcnt(6)
	s_barrier
	s_setprio 1
	v_mfma_f32_16x16x32_bf16 v[52:55], v[206:209], v[170:173], v[52:55]
	v_mfma_f32_16x16x32_bf16 v[48:51], v[214:217], v[170:173], v[48:51]
	v_mfma_f32_16x16x32_bf16 v[36:39], v[206:209], v[178:181], v[36:39]
	v_mfma_f32_16x16x32_bf16 v[32:35], v[214:217], v[178:181], v[32:35]
	v_mfma_f32_16x16x32_bf16 v[20:23], v[206:209], v[186:189], v[20:23]
	v_mfma_f32_16x16x32_bf16 v[16:19], v[214:217], v[186:189], v[16:19]
	v_mfma_f32_16x16x32_bf16 v[4:7], v[206:209], v[194:197], v[4:7]
	v_mfma_f32_16x16x32_bf16 v[0:3], v[214:217], v[194:197], v[0:3]
	v_mfma_f32_16x16x32_bf16 v[52:55], v[210:213], v[174:177], v[52:55]
	v_mfma_f32_16x16x32_bf16 v[48:51], v[218:221], v[174:177], v[48:51]
	v_mfma_f32_16x16x32_bf16 v[36:39], v[210:213], v[182:185], v[36:39]
	v_mfma_f32_16x16x32_bf16 v[32:35], v[218:221], v[182:185], v[32:35]
	v_mfma_f32_16x16x32_bf16 v[20:23], v[210:213], v[190:193], v[20:23]
	v_mfma_f32_16x16x32_bf16 v[16:19], v[218:221], v[190:193], v[16:19]
	v_mfma_f32_16x16x32_bf16 v[4:7], v[210:213], v[202:205], v[4:7]
	v_mfma_f32_16x16x32_bf16 v[0:3], v[218:221], v[202:205], v[0:3]
	s_setprio 0
	s_add_i32 s57, 0, 0x18000
	v_add_u32_e32 v150, s57, v166
	s_barrier
	ds_read_b128 v[128:131], v150
	ds_read_b128 v[132:135], v150 offset:1024
	ds_read_b128 v[136:139], v150 offset:2048
	ds_read_b128 v[160:163], v150 offset:3072
	s_add_u32 s28, s28, 0x40000
	s_addc_u32 s29, s29, 0
	s_mov_b32 m0, s39
	ds_read_b128 v[170:173], v168 offset:32768
	ds_read_b128 v[174:177], v168 offset:33792
	ds_read_b128 v[178:181], v168 offset:34816
	ds_read_b128 v[182:185], v168 offset:35840
	ds_read_b128 v[186:189], v168 offset:36864
	ds_read_b128 v[190:193], v168 offset:37888
	ds_read_b128 v[194:197], v168 offset:38912
	ds_read_b128 v[202:205], v168 offset:39936
	global_load_lds_dwordx4 v148, s[28:29]
	s_mov_b32 m0, s40
	s_nop 0
	global_load_lds_dwordx4 v144, s[28:29]
	s_waitcnt lgkmcnt(8)
	s_barrier
; #define PG8_STAGE(bufoff, gbase, voff) do { _Pragma("unroll") for (int _i = 0; _i < 2; ++_i) \
;         __builtin_amdgcn_global_load_lds((const unsigned*)((const char*)(gbase) + (voff)[_i]), (LAS unsigned*)(lds + (bufoff) + ldsw + _i * 8192), 16, 0, 0); } while (0)
; #define PG8_LDA(dst, b, h) do { _Pragma("unroll") for (int m = 0; m < 4; ++m) _Pragma("unroll") for (int k = 0; k < 2; ++k) dst[m][k] = *(const LAS bf16x8*)(lds + PG8_SA(b, h) + aoff + m * 2048 + k * 1024); } while (0)
; #define PG8_LDB(dst, b, h) do { _Pragma("unroll") for (int n = 0; n < 2; ++n) _Pragma("unroll") for (int k = 0; k < 2; ++k) dst[n][k] = *(const LAS bf16x8*)(lds + PG8_SB(b, h) + boff + n * 2048 + k * 1024); } while (0)
; #define PG8_MMA(ai, bj, At, Bt) do { __builtin_amdgcn_s_setprio(1); _Pragma("unroll") for (int m = 0; m < 4; ++m) _Pragma("unroll") for (int n = 0; n < 2; ++n) _Pragma("unroll") for (int k = 0; k < 2; ++k) \
;         acc[ai][bj][m][n] = __builtin_amdgcn_mfma_f32_16x16x32_bf16(Bt[n][k], At[m][k], acc[ai][bj][m][n], 0, 0, 0); __builtin_amdgcn_s_setprio(0); } while (0)
; #define PG8_WAIT_L(n) asm volatile("s_waitcnt lgkmcnt(" #n ")" ::: "memory")
; #define PG8_BAR __builtin_amdgcn_s_barrier()
; #define PG8_SCHED __builtin_amdgcn_sched_barrier(0)
; template <class Epi, class Sched>
; __device__ __forceinline__ void gemm_phase(LAS unsigned char* lds, const Gemm g, const Sched& S, const Epi& E) {
;     ...
;             PG8_WAIT_L(8); PG8_BAR; PG8_WAIT_L(0); PG8_MMA(0, 0, At, B0); PG8_BAR; PG8_SCHED;
;             PG8_LDB(B1, 1, 1); PG8_STAGE(PG8_SB(1, 0), b3, voffB);
;             PG8_BAR; PG8_WAIT_L(0); PG8_MMA(0, 1, At, B1); PG8_BAR;
;             PG8_LDA(At, 1, 1); PG8_STAGE(PG8_SA(1, 0), a3, voffA);
;             PG8_BAR; PG8_WAIT_L(0); PG8_MMA(1, 0, At, B0); PG8_BAR; PG8_SCHED;
	s_waitcnt lgkmcnt(0)
	s_setprio 1
	s_waitcnt lgkmcnt(0)
	v_mfma_f32_16x16x32_bf16 v[124:127], v[128:131], v[170:173], v[124:127]
	v_mfma_f32_16x16x32_bf16 v[120:123], v[136:139], v[170:173], v[120:123]
	v_mfma_f32_16x16x32_bf16 v[108:111], v[128:131], v[178:181], v[108:111]
	v_mfma_f32_16x16x32_bf16 v[104:107], v[136:139], v[178:181], v[104:107]
	v_mfma_f32_16x16x32_bf16 v[92:95], v[128:131], v[186:189], v[92:95]
	v_mfma_f32_16x16x32_bf16 v[88:91], v[136:139], v[186:189], v[88:91]
	v_mfma_f32_16x16x32_bf16 v[76:79], v[128:131], v[194:197], v[76:79]
	v_mfma_f32_16x16x32_bf16 v[72:75], v[136:139], v[194:197], v[72:75]
	v_mfma_f32_16x16x32_bf16 v[124:127], v[132:135], v[174:177], v[124:127]
	v_mfma_f32_16x16x32_bf16 v[120:123], v[160:163], v[174:177], v[120:123]
	v_mfma_f32_16x16x32_bf16 v[108:111], v[132:135], v[182:185], v[108:111]
	v_mfma_f32_16x16x32_bf16 v[104:107], v[160:163], v[182:185], v[104:107]
	v_mfma_f32_16x16x32_bf16 v[92:95], v[132:135], v[190:193], v[92:95]
	v_mfma_f32_16x16x32_bf16 v[88:91], v[160:163], v[190:193], v[88:91]
	v_mfma_f32_16x16x32_bf16 v[76:79], v[132:135], v[202:205], v[76:79]
	v_mfma_f32_16x16x32_bf16 v[72:75], v[160:163], v[202:205], v[72:75]
	s_setprio 0
	s_barrier
	s_add_i32 s28, 0, 0x1c000
	s_add_i32 s29, s57, s34
	v_add_u32_e32 v150, s28, v166
	s_add_u32 s0, s26, 0x80
	s_addc_u32 s1, s27, 0
	s_mov_b32 m0, s29
	ds_read_b128 v[206:209], v150
	ds_read_b128 v[210:213], v150 offset:1024
	ds_read_b128 v[214:217], v150 offset:2048
	ds_read_b128 v[218:221], v150 offset:3072
	global_load_lds_dwordx4 v146, s[0:1]
	s_add_i32 m0, s29, 0x2000
	s_nop 0
	global_load_lds_dwordx4 v142, s[0:1]
	s_barrier
	s_waitcnt lgkmcnt(0)
	s_setprio 1
	s_waitcnt lgkmcnt(0)
	v_mfma_f32_16x16x32_bf16 v[116:119], v[206:209], v[170:173], v[116:119]
	v_mfma_f32_16x16x32_bf16 v[112:115], v[214:217], v[170:173], v[112:115]
	v_mfma_f32_16x16x32_bf16 v[100:103], v[206:209], v[178:181], v[100:103]
	v_mfma_f32_16x16x32_bf16 v[96:99], v[214:217], v[178:181], v[96:99]
	v_mfma_f32_16x16x32_bf16 v[84:87], v[206:209], v[186:189], v[84:87]
	v_mfma_f32_16x16x32_bf16 v[80:83], v[214:217], v[186:189], v[80:83]
	v_mfma_f32_16x16x32_bf16 v[68:71], v[206:209], v[194:197], v[68:71]
	v_mfma_f32_16x16x32_bf16 v[64:67], v[214:217], v[194:197], v[64:67]
	v_mfma_f32_16x16x32_bf16 v[116:119], v[210:213], v[174:177], v[116:119]
	v_mfma_f32_16x16x32_bf16 v[112:115], v[218:221], v[174:177], v[112:115]
	v_mfma_f32_16x16x32_bf16 v[100:103], v[210:213], v[182:185], v[100:103]
	v_mfma_f32_16x16x32_bf16 v[96:99], v[218:221], v[182:185], v[96:99]
	v_mfma_f32_16x16x32_bf16 v[84:87], v[210:213], v[190:193], v[84:87]
	v_mfma_f32_16x16x32_bf16 v[80:83], v[218:221], v[190:193], v[80:83]
	v_mfma_f32_16x16x32_bf16 v[68:71], v[210:213], v[202:205], v[68:71]
	v_mfma_f32_16x16x32_bf16 v[64:67], v[218:221], v[202:205], v[64:67]
	s_setprio 0
	s_mov_b32 m0, s44
	s_mov_b64 s[0:1], 0x80
	v_lshl_add_u64 v[140:141], v[222:223], 0, s[0:1]
	s_barrier
	ds_read_b128 v[170:173], v168 offset:49152
	ds_read_b128 v[174:177], v168 offset:50176
	ds_read_b128 v[178:181], v168 offset:51200
	ds_read_b128 v[182:185], v168 offset:52224
	ds_read_b128 v[186:189], v168 offset:53248
	ds_read_b128 v[190:193], v168 offset:54272
	ds_read_b128 v[194:197], v168 offset:55296
	ds_read_b128 v[202:205], v168 offset:56320
	global_load_lds_dwordx4 v[140:141], off
	v_lshl_add_u64 v[140:141], v[224:225], 0, s[0:1]
	s_mov_b32 m0, s45
	s_nop 0
	global_load_lds_dwordx4 v[140:141], off
	s_barrier
; #define PG8_STAGE(bufoff, gbase, voff) do { _Pragma("unroll") for (int _i = 0; _i < 2; ++_i) \
;         __builtin_amdgcn_global_load_lds((const unsigned*)((const char*)(gbase) + (voff)[_i]), (LAS unsigned*)(lds + (bufoff) + ldsw + _i * 8192), 16, 0, 0); } while (0)
; #define PG8_MMA(ai, bj, At, Bt) do { __builtin_amdgcn_s_setprio(1); _Pragma("unroll") for (int m = 0; m < 4; ++m) _Pragma("unroll") for (int n = 0; n < 2; ++n) _Pragma("unroll") for (int k = 0; k < 2; ++k) \
;         acc[ai][bj][m][n] = __builtin_amdgcn_mfma_f32_16x16x32_bf16(Bt[n][k], At[m][k], acc[ai][bj][m][n], 0, 0, 0); __builtin_amdgcn_s_setprio(0); } while (0)
; #define PG8_WAIT_V(n) asm volatile("s_waitcnt vmcnt(" #n ")" ::: "memory")
; #define PG8_WAIT_L(n) asm volatile("s_waitcnt lgkmcnt(" #n ")" ::: "memory")
; #define PG8_BAR __builtin_amdgcn_s_barrier()
; #define PG8_SCHED __builtin_amdgcn_sched_barrier(0)
; template <class Epi, class Sched>
; __device__ __forceinline__ void gemm_phase(LAS unsigned char* lds, const Gemm g, const Sched& S, const Epi& E) {
;     ...
;             PG8_BAR; PG8_WAIT_L(0); PG8_MMA(1, 0, At, B0); PG8_BAR; PG8_SCHED;
;             PG8_STAGE(PG8_SB(1, 1), b3 + hstep, voffB);
;             PG8_WAIT_V(6); PG8_BAR; PG8_MMA(1, 1, At, B1); PG8_BAR;
;     __device__ __forceinline__ void operator()(const AccT& acc, const Unit& u, int wr, int wc, int fr, int fq) const {
;     ...
;         const int row0 = u.pm * 256 + wr * 64 + fr, col0 = u.pn * 256 + wc * 32 + 8 * fq;
;         const bool rope = u.pn < 2;
;         const int i = 4 * (wc & 1) + fq;
; #pragma unroll
;         for (int ai = 0; ai < 2; ++ai)
; #pragma unroll
;             for (int m = 0; m < 4; ++m) {
;                 const int row = row0 + ai * 128 + m * 16;
;                 f32x4 cs = {1.f, 1.f, 1.f, 1.f}, sn = {0.f, 0.f, 0.f, 0.f};
;                 if (rope) { const int t = row & 2047; const int pos = (i < 4) ? (t >> 6) : (t & 63);
;                     cs = *(const f32x4*)(ropeA + pos * 16 + ((4 * i) & 15)); sn = *(const f32x4*)(ropeA + 1024 + pos * 16 + ((4 * i) & 15)); }
	s_waitcnt lgkmcnt(0)
	s_setprio 1
	s_waitcnt lgkmcnt(0)
	v_mfma_f32_16x16x32_bf16 v[60:63], v[128:131], v[170:173], v[60:63]
	v_mfma_f32_16x16x32_bf16 v[56:59], v[136:139], v[170:173], v[56:59]
	v_mfma_f32_16x16x32_bf16 v[44:47], v[128:131], v[178:181], v[44:47]
	v_mfma_f32_16x16x32_bf16 v[40:43], v[136:139], v[178:181], v[40:43]
	v_mfma_f32_16x16x32_bf16 v[28:31], v[128:131], v[186:189], v[28:31]
	v_mfma_f32_16x16x32_bf16 v[24:27], v[136:139], v[186:189], v[24:27]
	v_mfma_f32_16x16x32_bf16 v[12:15], v[128:131], v[194:197], v[12:15]
	v_mfma_f32_16x16x32_bf16 v[8:11], v[136:139], v[194:197], v[8:11]
	v_mfma_f32_16x16x32_bf16 v[60:63], v[132:135], v[174:177], v[60:63]
	v_mfma_f32_16x16x32_bf16 v[56:59], v[160:163], v[174:177], v[56:59]
	v_mfma_f32_16x16x32_bf16 v[44:47], v[132:135], v[182:185], v[44:47]
	v_mfma_f32_16x16x32_bf16 v[40:43], v[160:163], v[182:185], v[40:43]
	v_mfma_f32_16x16x32_bf16 v[28:31], v[132:135], v[190:193], v[28:31]
	v_mfma_f32_16x16x32_bf16 v[24:27], v[160:163], v[190:193], v[24:27]
	v_mfma_f32_16x16x32_bf16 v[12:15], v[132:135], v[202:205], v[12:15]
	v_mfma_f32_16x16x32_bf16 v[8:11], v[160:163], v[202:205], v[8:11]
	s_setprio 0
	s_barrier
	s_add_u32 s26, s26, 0x40080
	s_addc_u32 s27, s27, 0
	s_add_i32 s28, s28, s34
	s_mov_b32 m0, s28
	s_nop 0
	global_load_lds_dwordx4 v146, s[26:27]
	s_add_i32 m0, s28, 0x2000
	s_nop 0
	global_load_lds_dwordx4 v142, s[26:27]
	s_waitcnt vmcnt(6)
	s_barrier
	s_setprio 1
	v_mfma_f32_16x16x32_bf16 v[52:55], v[206:209], v[170:173], v[52:55]
	v_mfma_f32_16x16x32_bf16 v[48:51], v[214:217], v[170:173], v[48:51]
	v_mfma_f32_16x16x32_bf16 v[36:39], v[206:209], v[178:181], v[36:39]
	v_mfma_f32_16x16x32_bf16 v[32:35], v[214:217], v[178:181], v[32:35]
	v_mfma_f32_16x16x32_bf16 v[20:23], v[206:209], v[186:189], v[20:23]
	v_mfma_f32_16x16x32_bf16 v[16:19], v[214:217], v[186:189], v[16:19]
	v_mfma_f32_16x16x32_bf16 v[4:7], v[206:209], v[194:197], v[4:7]
	v_mfma_f32_16x16x32_bf16 v[0:3], v[214:217], v[194:197], v[0:3]
	v_mfma_f32_16x16x32_bf16 v[52:55], v[210:213], v[174:177], v[52:55]
	v_mfma_f32_16x16x32_bf16 v[48:51], v[218:221], v[174:177], v[48:51]
	v_mfma_f32_16x16x32_bf16 v[36:39], v[210:213], v[182:185], v[36:39]
	v_mfma_f32_16x16x32_bf16 v[32:35], v[218:221], v[182:185], v[32:35]
	v_mfma_f32_16x16x32_bf16 v[20:23], v[210:213], v[190:193], v[20:23]
	v_mfma_f32_16x16x32_bf16 v[16:19], v[218:221], v[190:193], v[16:19]
	v_mfma_f32_16x16x32_bf16 v[4:7], v[210:213], v[202:205], v[4:7]
	v_mfma_f32_16x16x32_bf16 v[0:3], v[218:221], v[202:205], v[0:3]
	s_setprio 0
	s_add_i32 s56, s56, 2
	s_add_u32 s6, s6, 0x100
	s_addc_u32 s7, s7, 0
	s_add_u32 s54, s54, 0x100
	s_addc_u32 s55, s55, 0
	s_cmp_gt_u32 s56, 13
	s_barrier
	s_cbranch_scc0 .LBB0_578
	v_mov_b32_e32 v129, v165
	v_mov_b32_e32 v173, v164
	s_lshl_b32 s4, s4, 8
	s_add_i32 s4, s4, s42
	v_add_u32_e32 v128, s46, v129
	v_add_u32_e32 v170, s4, v173
	v_cmp_gt_i32_e64 s[4:5], 4, v128
	v_lshlrev_b32_e32 v128, 2, v128
	s_cmp_lt_i32 s52, 2
	v_and_b32_e32 v130, 12, v128
	s_cselect_b64 s[26:27], -1, 0
	s_cmp_gt_i32 s52, 1
	v_and_b32_e32 v172, 63, v173
	v_mov_b32_e32 v128, 1.0
	v_mov_b32_e32 v132, 0
	v_lshlrev_b32_e32 v162, 2, v130
	v_mov_b32_e32 v134, 0
	v_mov_b32_e32 v135, 0
	v_mov_b32_e32 v136, 0
	v_mov_b32_e32 v137, 0
	v_mov_b32_e32 v138, 1.0
	v_mov_b32_e32 v139, 1.0
	v_mov_b32_e32 v140, 1.0
	v_mov_b32_e32 v141, 1.0
	s_cbranch_scc1 .LBB0_581
	v_bfe_u32 v130, v170, 6, 5
	v_cndmask_b32_e64 v130, v172, v130, s[4:5]
	v_lshlrev_b32_e32 v150, 6, v130
	v_lshl_add_u64 v[130:131], s[16:17], 0, v[150:151]
	v_mov_b32_e32 v163, v151
	v_lshl_add_u64 v[134:135], s[8:9], 0, v[150:151]
	v_lshl_add_u64 v[130:131], v[130:131], 0, v[162:163]
	v_lshl_add_u64 v[134:135], v[134:135], 0, v[162:163]
	global_load_dwordx4 v[138:141], v[130:131], off
	s_nop 0
	global_load_dwordx4 v[134:137], v[134:135], off
	s_waitcnt vmcnt(0)

; #define PG8_STAGE(bufoff, gbase, voff) do { _Pragma("unroll") for (int _i = 0; _i < 2; ++_i) \
;         __builtin_amdgcn_global_load_lds((const unsigned*)((const char*)(gbase) + (voff)[_i]), (LAS unsigned*)(lds + (bufoff) + ldsw + _i * 8192), 16, 0, 0); } while (0)
; #define PG8_LDA(dst, b, h) do { _Pragma("unroll") for (int m = 0; m < 4; ++m) _Pragma("unroll") for (int k = 0; k < 2; ++k) dst[m][k] = *(const LAS bf16x8*)(lds + PG8_SA(b, h) + aoff + m * 2048 + k * 1024); } while (0)
; #define PG8_LDB(dst, b, h) do { _Pragma("unroll") for (int n = 0; n < 2; ++n) _Pragma("unroll") for (int k = 0; k < 2; ++k) dst[n][k] = *(const LAS bf16x8*)(lds + PG8_SB(b, h) + boff + n * 2048 + k * 1024); } while (0)
; #define PG8_WAIT_V(n) asm volatile("s_waitcnt vmcnt(" #n ")" ::: "memory")
; #define PG8_BAR __builtin_amdgcn_s_barrier()
; template <class Epi, class Sched>
; __device__ __forceinline__ void gemm_phase(LAS unsigned char* lds, const Gemm g, const Sched& S, const Epi& E) {
;     ...
;         const bool has_next = S.next(ui + 1, nxt);
;         const char* nA = has_next ? (const char*)g.A + (size_t)nxt.pm * tstep : cA; const char* nB = has_next ? (const char*)g.Bt + (size_t)nxt.pn * tstep : cB;
;         for (int t = 0; t < nt; t += 2) {
;             const bool last = (t == nt - 2);
;             const char* a1 = cA + (size_t)(t + 1) * kstep;
;             const char* a2 = last ? nA : cA + (size_t)(t + 2) * kstep; const char* b2 = last ? nB : cB + (size_t)(t + 2) * kstep;
;             const char* a3 = a2 + kstep; const char* b3 = b2 + kstep;
;             PG8_LDB(B0, 0, 0); PG8_SCHED; PG8_LDA(At, 0, 0); PG8_STAGE(PG8_SA(1, 1), a1 + hstep, voffA);
;             PG8_WAIT_L(8); PG8_BAR; PG8_WAIT_L(0); PG8_MMA(0, 0, At, B0); PG8_BAR; PG8_SCHED;
;             PG8_LDB(B1, 0, 1); PG8_STAGE(PG8_SB(0, 0), b2, voffB);
;             PG8_BAR; PG8_WAIT_L(0); PG8_MMA(0, 1, At, B1); PG8_BAR;
;             PG8_LDA(At, 0, 1); PG8_STAGE(PG8_SA(0, 0), a2, voffA);
;             PG8_BAR; PG8_WAIT_L(0); PG8_MMA(1, 0, At, B0); PG8_BAR; PG8_SCHED;
;             PG8_STAGE(PG8_SB(0, 1), b2 + hstep, voffB);
;             PG8_WAIT_V(6); PG8_BAR; PG8_MMA(1, 1, At, B1); PG8_BAR;
;             PG8_LDB(B0, 1, 0); PG8_SCHED; PG8_LDA(At, 1, 0); PG8_STAGE(PG8_SA(0, 1), a2 + hstep, voffA);
;             PG8_WAIT_L(8); PG8_BAR; PG8_WAIT_L(0); PG8_MMA(0, 0, At, B0); PG8_BAR; PG8_SCHED;
.LBB0_612:
	s_ashr_i32 s35, s34, 31
	v_cmp_lt_i64_e32 vcc, s[6:7], v[142:143]
	s_lshl_b64 s[6:7], s[34:35], 19
	s_add_u32 s36, s40, s6
	s_addc_u32 s37, s41, s7
	s_and_b64 s[6:7], vcc, exec
	s_cselect_b32 s8, s37, s1
	s_cselect_b32 s9, s36, s0
	s_ashr_i32 s31, s30, 31
	s_lshl_b64 s[6:7], s[30:31], 19
	s_add_u32 s38, s96, s6
	s_addc_u32 s39, s97, s7
	s_and_b64 s[6:7], vcc, exec
	s_cselect_b32 s31, s39, s5
	s_cselect_b32 s35, s38, s4
	s_add_u32 s0, s0, 0x40080
	s_addc_u32 s1, s1, 0
	s_add_u32 s65, s4, 0x100
	s_addc_u32 s66, s5, 0
	s_mov_b32 s67, -2
	s_waitcnt lgkmcnt(0)
	ds_read_b128 v[146:149], v171
	ds_read_b128 v[150:153], v171 offset:1024
	ds_read_b128 v[154:157], v171 offset:2048
	ds_read_b128 v[158:161], v171 offset:3072
	s_add_u32 s4, s0, 0xfffc0080
	s_addc_u32 s5, s1, -1
	s_cmp_eq_u32 s67, 12
	s_cselect_b32 s7, s8, s5
	s_cselect_b32 s6, s9, s4
	s_cselect_b32 s5, s31, s66
	s_cselect_b32 s4, s35, s65
	s_add_i32 m0, s45, 0xc000
	ds_read_b128 v[162:165], v172
	ds_read_b128 v[178:181], v172 offset:1024
	ds_read_b128 v[182:185], v172 offset:2048
	ds_read_b128 v[186:189], v172 offset:3072
	ds_read_b128 v[190:193], v172 offset:4096
	ds_read_b128 v[194:197], v172 offset:5120
	ds_read_b128 v[202:205], v172 offset:6144
	ds_read_b128 v[206:209], v172 offset:7168
	global_load_lds_dwordx4 v138, s[0:1]
	s_add_i32 m0, s45, 0xe000
	s_nop 0
	global_load_lds_dwordx4 v140, s[0:1]
	s_waitcnt lgkmcnt(8)
	s_barrier
	s_waitcnt lgkmcnt(0)
	s_setprio 1
	s_waitcnt lgkmcnt(0)
	v_mfma_f32_16x16x32_bf16 v[124:127], v[146:149], v[162:165], 0
	v_mfma_f32_16x16x32_bf16 v[120:123], v[154:157], v[162:165], 0
	v_mfma_f32_16x16x32_bf16 v[108:111], v[146:149], v[182:185], 0
	v_mfma_f32_16x16x32_bf16 v[104:107], v[154:157], v[182:185], 0
	v_mfma_f32_16x16x32_bf16 v[92:95], v[146:149], v[190:193], 0
	v_mfma_f32_16x16x32_bf16 v[88:91], v[154:157], v[190:193], 0
	v_mfma_f32_16x16x32_bf16 v[76:79], v[146:149], v[202:205], 0
	v_mfma_f32_16x16x32_bf16 v[72:75], v[154:157], v[202:205], 0
	v_mfma_f32_16x16x32_bf16 v[124:127], v[150:153], v[178:181], v[124:127]
	v_mfma_f32_16x16x32_bf16 v[120:123], v[158:161], v[178:181], v[120:123]
	v_mfma_f32_16x16x32_bf16 v[108:111], v[150:153], v[186:189], v[108:111]
	v_mfma_f32_16x16x32_bf16 v[104:107], v[158:161], v[186:189], v[104:107]
	v_mfma_f32_16x16x32_bf16 v[92:95], v[150:153], v[194:197], v[92:95]
	v_mfma_f32_16x16x32_bf16 v[88:91], v[158:161], v[194:197], v[88:91]
	v_mfma_f32_16x16x32_bf16 v[76:79], v[150:153], v[206:209], v[76:79]
	v_mfma_f32_16x16x32_bf16 v[72:75], v[158:161], v[206:209], v[72:75]
	s_setprio 0
	s_barrier
	s_add_i32 s68, s57, s44
	s_mov_b32 m0, s68
	ds_read_b128 v[210:213], v173
	ds_read_b128 v[214:217], v173 offset:1024
	ds_read_b128 v[218:221], v173 offset:2048
	ds_read_b128 v[222:225], v173 offset:3072
	global_load_lds_dwordx4 v130, s[4:5]
	s_add_i32 m0, s68, 0x2000
	s_nop 0
	global_load_lds_dwordx4 v134, s[4:5]
	s_barrier
	s_waitcnt lgkmcnt(0)
	s_setprio 1
	s_waitcnt lgkmcnt(0)
	v_mfma_f32_16x16x32_bf16 v[116:119], v[210:213], v[162:165], 0
	v_mfma_f32_16x16x32_bf16 v[112:115], v[218:221], v[162:165], 0
	v_mfma_f32_16x16x32_bf16 v[100:103], v[210:213], v[182:185], 0
	v_mfma_f32_16x16x32_bf16 v[96:99], v[218:221], v[182:185], 0
	v_mfma_f32_16x16x32_bf16 v[84:87], v[210:213], v[190:193], 0
	v_mfma_f32_16x16x32_bf16 v[80:83], v[218:221], v[190:193], 0
	v_mfma_f32_16x16x32_bf16 v[68:71], v[210:213], v[202:205], 0
	v_mfma_f32_16x16x32_bf16 v[64:67], v[218:221], v[202:205], 0
	v_mfma_f32_16x16x32_bf16 v[116:119], v[214:217], v[178:181], v[116:119]
	v_mfma_f32_16x16x32_bf16 v[112:115], v[222:225], v[178:181], v[112:115]
	v_mfma_f32_16x16x32_bf16 v[100:103], v[214:217], v[186:189], v[100:103]
	v_mfma_f32_16x16x32_bf16 v[96:99], v[222:225], v[186:189], v[96:99]
	v_mfma_f32_16x16x32_bf16 v[84:87], v[214:217], v[194:197], v[84:87]
	v_mfma_f32_16x16x32_bf16 v[80:83], v[222:225], v[194:197], v[80:83]
	v_mfma_f32_16x16x32_bf16 v[68:71], v[214:217], v[206:209], v[68:71]
	v_mfma_f32_16x16x32_bf16 v[64:67], v[222:225], v[206:209], v[64:67]
	s_setprio 0
	s_mov_b32 m0, s45
	v_lshl_add_u64 v[226:227], s[6:7], 0, v[128:129]
	s_barrier
	ds_read_b128 v[162:165], v172 offset:16384
	ds_read_b128 v[178:181], v172 offset:17408
	ds_read_b128 v[182:185], v172 offset:18432
	ds_read_b128 v[186:189], v172 offset:19456
	ds_read_b128 v[190:193], v172 offset:20480
	ds_read_b128 v[194:197], v172 offset:21504
	ds_read_b128 v[202:205], v172 offset:22528
	ds_read_b128 v[206:209], v172 offset:23552
	global_load_lds_dwordx4 v128, s[6:7]
	v_lshl_add_u64 v[228:229], s[6:7], 0, v[132:133]
	s_mov_b32 m0, s46
	s_nop 0
	global_load_lds_dwordx4 v132, s[6:7]
	s_barrier
	s_waitcnt lgkmcnt(0)
	s_setprio 1
	s_waitcnt lgkmcnt(0)
	v_mfma_f32_16x16x32_bf16 v[60:63], v[146:149], v[162:165], 0
	v_mfma_f32_16x16x32_bf16 v[56:59], v[154:157], v[162:165], 0
	v_mfma_f32_16x16x32_bf16 v[44:47], v[146:149], v[182:185], 0
	v_mfma_f32_16x16x32_bf16 v[40:43], v[154:157], v[182:185], 0
	v_mfma_f32_16x16x32_bf16 v[28:31], v[146:149], v[190:193], 0
	v_mfma_f32_16x16x32_bf16 v[24:27], v[154:157], v[190:193], 0
	v_mfma_f32_16x16x32_bf16 v[12:15], v[146:149], v[202:205], 0
	v_mfma_f32_16x16x32_bf16 v[8:11], v[154:157], v[202:205], 0
	v_mfma_f32_16x16x32_bf16 v[60:63], v[150:153], v[178:181], v[60:63]
	v_mfma_f32_16x16x32_bf16 v[56:59], v[158:161], v[178:181], v[56:59]
	v_mfma_f32_16x16x32_bf16 v[44:47], v[150:153], v[186:189], v[44:47]
	v_mfma_f32_16x16x32_bf16 v[40:43], v[158:161], v[186:189], v[40:43]
	v_mfma_f32_16x16x32_bf16 v[28:31], v[150:153], v[194:197], v[28:31]
	v_mfma_f32_16x16x32_bf16 v[24:27], v[158:161], v[194:197], v[24:27]
	v_mfma_f32_16x16x32_bf16 v[12:15], v[150:153], v[206:209], v[12:15]
	v_mfma_f32_16x16x32_bf16 v[8:11], v[158:161], v[206:209], v[8:11]
	s_setprio 0
	s_barrier
; #define PG8_STAGE(bufoff, gbase, voff) do { _Pragma("unroll") for (int _i = 0; _i < 2; ++_i) \
;         __builtin_amdgcn_global_load_lds((const unsigned*)((const char*)(gbase) + (voff)[_i]), (LAS unsigned*)(lds + (bufoff) + ldsw + _i * 8192), 16, 0, 0); } while (0)
; #define PG8_LDA(dst, b, h) do { _Pragma("unroll") for (int m = 0; m < 4; ++m) _Pragma("unroll") for (int k = 0; k < 2; ++k) dst[m][k] = *(const LAS bf16x8*)(lds + PG8_SA(b, h) + aoff + m * 2048 + k * 1024); } while (0)
; #define PG8_LDB(dst, b, h) do { _Pragma("unroll") for (int n = 0; n < 2; ++n) _Pragma("unroll") for (int k = 0; k < 2; ++k) dst[n][k] = *(const LAS bf16x8*)(lds + PG8_SB(b, h) + boff + n * 2048 + k * 1024); } while (0)
; #define PG8_MMA(ai, bj, At, Bt) do { __builtin_amdgcn_s_setprio(1); _Pragma("unroll") for (int m = 0; m < 4; ++m) _Pragma("unroll") for (int n = 0; n < 2; ++n) _Pragma("unroll") for (int k = 0; k < 2; ++k) \
;         acc[ai][bj][m][n] = __builtin_amdgcn_mfma_f32_16x16x32_bf16(Bt[n][k], At[m][k], acc[ai][bj][m][n], 0, 0, 0); __builtin_amdgcn_s_setprio(0); } while (0)
; #define PG8_WAIT_V(n) asm volatile("s_waitcnt vmcnt(" #n ")" ::: "memory")
; #define PG8_WAIT_L(n) asm volatile("s_waitcnt lgkmcnt(" #n ")" ::: "memory")
; #define PG8_BAR __builtin_amdgcn_s_barrier()
; #define PG8_SCHED __builtin_amdgcn_sched_barrier(0)
; template <class Epi, class Sched>
; __device__ __forceinline__ void gemm_phase(LAS unsigned char* lds, const Gemm g, const Sched& S, const Epi& E) {
;     ...
;             PG8_STAGE(PG8_SB(0, 1), b2 + hstep, voffB);
;             PG8_WAIT_V(6); PG8_BAR; PG8_MMA(1, 1, At, B1); PG8_BAR;
;             PG8_LDB(B0, 1, 0); PG8_SCHED; PG8_LDA(At, 1, 0); PG8_STAGE(PG8_SA(0, 1), a2 + hstep, voffA);
;             PG8_WAIT_L(8); PG8_BAR; PG8_WAIT_L(0); PG8_MMA(0, 0, At, B0); PG8_BAR; PG8_SCHED;
;             PG8_LDB(B1, 1, 1); PG8_STAGE(PG8_SB(1, 0), b3, voffB);
;             PG8_BAR; PG8_WAIT_L(0); PG8_MMA(0, 1, At, B1); PG8_BAR;
;             PG8_LDA(At, 1, 1); PG8_STAGE(PG8_SA(1, 0), a3, voffA);
;             PG8_BAR; PG8_WAIT_L(0); PG8_MMA(1, 0, At, B0); PG8_BAR; PG8_SCHED;
	s_add_u32 s68, s4, 0x40000
	s_addc_u32 s69, s5, 0
	s_add_i32 s70, s58, s44
	s_mov_b32 m0, s70
	s_nop 0
	global_load_lds_dwordx4 v130, s[68:69]
	s_add_i32 m0, s70, 0x2000
	s_nop 0
	global_load_lds_dwordx4 v134, s[68:69]
	s_waitcnt vmcnt(6)
	s_barrier
	s_setprio 1
	v_mfma_f32_16x16x32_bf16 v[52:55], v[210:213], v[162:165], 0
	v_mfma_f32_16x16x32_bf16 v[48:51], v[218:221], v[162:165], 0
	v_mfma_f32_16x16x32_bf16 v[36:39], v[210:213], v[182:185], 0
	v_mfma_f32_16x16x32_bf16 v[32:35], v[218:221], v[182:185], 0
	v_mfma_f32_16x16x32_bf16 v[20:23], v[210:213], v[190:193], 0
	v_mfma_f32_16x16x32_bf16 v[16:19], v[218:221], v[190:193], 0
	v_mfma_f32_16x16x32_bf16 v[4:7], v[210:213], v[202:205], 0
	v_mfma_f32_16x16x32_bf16 v[0:3], v[218:221], v[202:205], 0
	v_mfma_f32_16x16x32_bf16 v[52:55], v[214:217], v[178:181], v[52:55]
	v_mfma_f32_16x16x32_bf16 v[48:51], v[222:225], v[178:181], v[48:51]
	v_mfma_f32_16x16x32_bf16 v[36:39], v[214:217], v[186:189], v[36:39]
	v_mfma_f32_16x16x32_bf16 v[32:35], v[222:225], v[186:189], v[32:35]
	v_mfma_f32_16x16x32_bf16 v[20:23], v[214:217], v[194:197], v[20:23]
	v_mfma_f32_16x16x32_bf16 v[16:19], v[222:225], v[194:197], v[16:19]
	v_mfma_f32_16x16x32_bf16 v[4:7], v[214:217], v[206:209], v[4:7]
	v_mfma_f32_16x16x32_bf16 v[0:3], v[222:225], v[206:209], v[0:3]
	s_setprio 0
	s_add_i32 s68, 0, 0x18000
	v_add_u32_e32 v136, s68, v170
	s_barrier
	ds_read_b128 v[146:149], v136
	ds_read_b128 v[150:153], v136 offset:1024
	ds_read_b128 v[154:157], v136 offset:2048
	ds_read_b128 v[158:161], v136 offset:3072
	s_add_u32 s6, s6, 0x40000
	s_addc_u32 s7, s7, 0
	s_mov_b32 m0, s47
	ds_read_b128 v[162:165], v172 offset:32768
	ds_read_b128 v[178:181], v172 offset:33792
	ds_read_b128 v[182:185], v172 offset:34816
	ds_read_b128 v[186:189], v172 offset:35840
	ds_read_b128 v[190:193], v172 offset:36864
	ds_read_b128 v[194:197], v172 offset:37888
	ds_read_b128 v[202:205], v172 offset:38912
	ds_read_b128 v[206:209], v172 offset:39936
	global_load_lds_dwordx4 v128, s[6:7]
	s_mov_b32 m0, s48
	s_nop 0
	global_load_lds_dwordx4 v132, s[6:7]
	s_waitcnt lgkmcnt(8)
	s_barrier
	s_waitcnt lgkmcnt(0)
	s_setprio 1
	s_waitcnt lgkmcnt(0)
	v_mfma_f32_16x16x32_bf16 v[124:127], v[146:149], v[162:165], v[124:127]
	v_mfma_f32_16x16x32_bf16 v[120:123], v[154:157], v[162:165], v[120:123]
	v_mfma_f32_16x16x32_bf16 v[108:111], v[146:149], v[182:185], v[108:111]
	v_mfma_f32_16x16x32_bf16 v[104:107], v[154:157], v[182:185], v[104:107]
	v_mfma_f32_16x16x32_bf16 v[92:95], v[146:149], v[190:193], v[92:95]
	v_mfma_f32_16x16x32_bf16 v[88:91], v[154:157], v[190:193], v[88:91]
	v_mfma_f32_16x16x32_bf16 v[76:79], v[146:149], v[202:205], v[76:79]
	v_mfma_f32_16x16x32_bf16 v[72:75], v[154:157], v[202:205], v[72:75]
	v_mfma_f32_16x16x32_bf16 v[124:127], v[150:153], v[178:181], v[124:127]
	v_mfma_f32_16x16x32_bf16 v[120:123], v[158:161], v[178:181], v[120:123]
	v_mfma_f32_16x16x32_bf16 v[108:111], v[150:153], v[186:189], v[108:111]
	v_mfma_f32_16x16x32_bf16 v[104:107], v[158:161], v[186:189], v[104:107]
	v_mfma_f32_16x16x32_bf16 v[92:95], v[150:153], v[194:197], v[92:95]
	v_mfma_f32_16x16x32_bf16 v[88:91], v[158:161], v[194:197], v[88:91]
	v_mfma_f32_16x16x32_bf16 v[76:79], v[150:153], v[206:209], v[76:79]
	v_mfma_f32_16x16x32_bf16 v[72:75], v[158:161], v[206:209], v[72:75]
	s_setprio 0
	s_barrier
	s_add_i32 s6, 0, 0x1c000
	s_add_i32 s7, s68, s44
	v_add_u32_e32 v136, s6, v170
	s_add_u32 s20, s4, 0x80
	s_addc_u32 s21, s5, 0
	s_mov_b32 m0, s7
	ds_read_b128 v[210:213], v136
	ds_read_b128 v[214:217], v136 offset:1024
	ds_read_b128 v[218:221], v136 offset:2048
	ds_read_b128 v[222:225], v136 offset:3072
	global_load_lds_dwordx4 v130, s[20:21]
	s_add_i32 m0, s7, 0x2000
	s_nop 0
	global_load_lds_dwordx4 v134, s[20:21]
	s_barrier
	s_waitcnt lgkmcnt(0)
	s_setprio 1
	s_waitcnt lgkmcnt(0)
	v_mfma_f32_16x16x32_bf16 v[116:119], v[210:213], v[162:165], v[116:119]
	v_mfma_f32_16x16x32_bf16 v[112:115], v[218:221], v[162:165], v[112:115]
	v_mfma_f32_16x16x32_bf16 v[100:103], v[210:213], v[182:185], v[100:103]
	v_mfma_f32_16x16x32_bf16 v[96:99], v[218:221], v[182:185], v[96:99]
	v_mfma_f32_16x16x32_bf16 v[84:87], v[210:213], v[190:193], v[84:87]
	v_mfma_f32_16x16x32_bf16 v[80:83], v[218:221], v[190:193], v[80:83]
	v_mfma_f32_16x16x32_bf16 v[68:71], v[210:213], v[202:205], v[68:71]
	v_mfma_f32_16x16x32_bf16 v[64:67], v[218:221], v[202:205], v[64:67]
	v_mfma_f32_16x16x32_bf16 v[116:119], v[214:217], v[178:181], v[116:119]
	v_mfma_f32_16x16x32_bf16 v[112:115], v[222:225], v[178:181], v[112:115]
	v_mfma_f32_16x16x32_bf16 v[100:103], v[214:217], v[186:189], v[100:103]
	v_mfma_f32_16x16x32_bf16 v[96:99], v[222:225], v[186:189], v[96:99]
	v_mfma_f32_16x16x32_bf16 v[84:87], v[214:217], v[194:197], v[84:87]
	v_mfma_f32_16x16x32_bf16 v[80:83], v[222:225], v[194:197], v[80:83]
	v_mfma_f32_16x16x32_bf16 v[68:71], v[214:217], v[206:209], v[68:71]
	v_mfma_f32_16x16x32_bf16 v[64:67], v[222:225], v[206:209], v[64:67]
	s_setprio 0
	s_mov_b32 m0, s54
	s_mov_b64 s[20:21], 0x80
	v_lshl_add_u64 v[166:167], v[226:227], 0, s[20:21]
	s_barrier
	ds_read_b128 v[162:165], v172 offset:49152
	ds_read_b128 v[178:181], v172 offset:50176
	ds_read_b128 v[182:185], v172 offset:51200
	ds_read_b128 v[186:189], v172 offset:52224
	ds_read_b128 v[190:193], v172 offset:53248
	ds_read_b128 v[194:197], v172 offset:54272
	ds_read_b128 v[202:205], v172 offset:55296
	ds_read_b128 v[206:209], v172 offset:56320
	global_load_lds_dwordx4 v[166:167], off
	v_lshl_add_u64 v[166:167], v[228:229], 0, s[20:21]
	s_mov_b32 m0, s55
	s_nop 0
	global_load_lds_dwordx4 v[166:167], off
	s_barrier
; #define PG8_STAGE(bufoff, gbase, voff) do { _Pragma("unroll") for (int _i = 0; _i < 2; ++_i) \
;         __builtin_amdgcn_global_load_lds((const unsigned*)((const char*)(gbase) + (voff)[_i]), (LAS unsigned*)(lds + (bufoff) + ldsw + _i * 8192), 16, 0, 0); } while (0)
; #define PG8_LDA(dst, b, h) do { _Pragma("unroll") for (int m = 0; m < 4; ++m) _Pragma("unroll") for (int k = 0; k < 2; ++k) dst[m][k] = *(const LAS bf16x8*)(lds + PG8_SA(b, h) + aoff + m * 2048 + k * 1024); } while (0)
; #define PG8_LDB(dst, b, h) do { _Pragma("unroll") for (int n = 0; n < 2; ++n) _Pragma("unroll") for (int k = 0; k < 2; ++k) dst[n][k] = *(const LAS bf16x8*)(lds + PG8_SB(b, h) + boff + n * 2048 + k * 1024); } while (0)
; #define PG8_MMA(ai, bj, At, Bt) do { __builtin_amdgcn_s_setprio(1); _Pragma("unroll") for (int m = 0; m < 4; ++m) _Pragma("unroll") for (int n = 0; n < 2; ++n) _Pragma("unroll") for (int k = 0; k < 2; ++k) \
;         acc[ai][bj][m][n] = __builtin_amdgcn_mfma_f32_16x16x32_bf16(Bt[n][k], At[m][k], acc[ai][bj][m][n], 0, 0, 0); __builtin_amdgcn_s_setprio(0); } while (0)
; #define PG8_WAIT_V(n) asm volatile("s_waitcnt vmcnt(" #n ")" ::: "memory")
; #define PG8_WAIT_L(n) asm volatile("s_waitcnt lgkmcnt(" #n ")" ::: "memory")
; template <class Epi, class Sched>
; __device__ __forceinline__ void gemm_phase(LAS unsigned char* lds, const Gemm g, const Sched& S, const Epi& E) {
;     ...
;         for (int t = 0; t < nt; t += 2) {
;             const bool last = (t == nt - 2);
;             const char* a1 = cA + (size_t)(t + 1) * kstep;
;             const char* a2 = last ? nA : cA + (size_t)(t + 2) * kstep; const char* b2 = last ? nB : cB + (size_t)(t + 2) * kstep;
;             const char* a3 = a2 + kstep; const char* b3 = b2 + kstep;
;             PG8_LDB(B0, 0, 0); PG8_SCHED; PG8_LDA(At, 0, 0); PG8_STAGE(PG8_SA(1, 1), a1 + hstep, voffA);
;             PG8_WAIT_L(8); PG8_BAR; PG8_WAIT_L(0); PG8_MMA(0, 0, At, B0); PG8_BAR; PG8_SCHED;
;             PG8_LDB(B1, 0, 1); PG8_STAGE(PG8_SB(0, 0), b2, voffB);
;             PG8_BAR; PG8_WAIT_L(0); PG8_MMA(0, 1, At, B1); PG8_BAR;
;             PG8_LDA(At, 0, 1); PG8_STAGE(PG8_SA(0, 0), a2, voffA);
;     ...
;             PG8_BAR; PG8_WAIT_L(0); PG8_MMA(1, 0, At, B0); PG8_BAR; PG8_SCHED;
;             PG8_STAGE(PG8_SB(1, 1), b3 + hstep, voffB);
;             PG8_WAIT_V(6); PG8_BAR; PG8_MMA(1, 1, At, B1); PG8_BAR;
	s_waitcnt lgkmcnt(0)
	s_setprio 1
	s_waitcnt lgkmcnt(0)
	v_mfma_f32_16x16x32_bf16 v[60:63], v[146:149], v[162:165], v[60:63]
	v_mfma_f32_16x16x32_bf16 v[56:59], v[154:157], v[162:165], v[56:59]
	v_mfma_f32_16x16x32_bf16 v[44:47], v[146:149], v[182:185], v[44:47]
	v_mfma_f32_16x16x32_bf16 v[40:43], v[154:157], v[182:185], v[40:43]
	v_mfma_f32_16x16x32_bf16 v[28:31], v[146:149], v[190:193], v[28:31]
	v_mfma_f32_16x16x32_bf16 v[24:27], v[154:157], v[190:193], v[24:27]
	v_mfma_f32_16x16x32_bf16 v[12:15], v[146:149], v[202:205], v[12:15]
	v_mfma_f32_16x16x32_bf16 v[8:11], v[154:157], v[202:205], v[8:11]
	v_mfma_f32_16x16x32_bf16 v[60:63], v[150:153], v[178:181], v[60:63]
	v_mfma_f32_16x16x32_bf16 v[56:59], v[158:161], v[178:181], v[56:59]
	v_mfma_f32_16x16x32_bf16 v[44:47], v[150:153], v[186:189], v[44:47]
	v_mfma_f32_16x16x32_bf16 v[40:43], v[158:161], v[186:189], v[40:43]
	v_mfma_f32_16x16x32_bf16 v[28:31], v[150:153], v[194:197], v[28:31]
	v_mfma_f32_16x16x32_bf16 v[24:27], v[158:161], v[194:197], v[24:27]
	v_mfma_f32_16x16x32_bf16 v[12:15], v[150:153], v[206:209], v[12:15]
	v_mfma_f32_16x16x32_bf16 v[8:11], v[158:161], v[206:209], v[8:11]
	s_setprio 0
	s_barrier
	s_add_u32 s4, s4, 0x40080
	s_addc_u32 s5, s5, 0
	s_add_i32 s6, s6, s44
	s_mov_b32 m0, s6
	s_nop 0
	global_load_lds_dwordx4 v130, s[4:5]
	s_add_i32 m0, s6, 0x2000
	s_nop 0
	global_load_lds_dwordx4 v134, s[4:5]
	s_waitcnt vmcnt(6)
	s_barrier
	s_setprio 1
	v_mfma_f32_16x16x32_bf16 v[52:55], v[210:213], v[162:165], v[52:55]
	v_mfma_f32_16x16x32_bf16 v[48:51], v[218:221], v[162:165], v[48:51]
	v_mfma_f32_16x16x32_bf16 v[36:39], v[210:213], v[182:185], v[36:39]
	v_mfma_f32_16x16x32_bf16 v[32:35], v[218:221], v[182:185], v[32:35]
	v_mfma_f32_16x16x32_bf16 v[20:23], v[210:213], v[190:193], v[20:23]
	v_mfma_f32_16x16x32_bf16 v[16:19], v[218:221], v[190:193], v[16:19]
	v_mfma_f32_16x16x32_bf16 v[4:7], v[210:213], v[202:205], v[4:7]
	v_mfma_f32_16x16x32_bf16 v[0:3], v[218:221], v[202:205], v[0:3]
	v_mfma_f32_16x16x32_bf16 v[52:55], v[214:217], v[178:181], v[52:55]
	v_mfma_f32_16x16x32_bf16 v[48:51], v[222:225], v[178:181], v[48:51]
	v_mfma_f32_16x16x32_bf16 v[36:39], v[214:217], v[186:189], v[36:39]
	v_mfma_f32_16x16x32_bf16 v[32:35], v[222:225], v[186:189], v[32:35]
	v_mfma_f32_16x16x32_bf16 v[20:23], v[214:217], v[194:197], v[20:23]
	v_mfma_f32_16x16x32_bf16 v[16:19], v[222:225], v[194:197], v[16:19]
	v_mfma_f32_16x16x32_bf16 v[4:7], v[214:217], v[206:209], v[4:7]
	v_mfma_f32_16x16x32_bf16 v[0:3], v[222:225], v[206:209], v[0:3]
	s_setprio 0
	s_add_i32 s67, s67, 2
	s_add_u32 s0, s0, 0x100
	s_addc_u32 s1, s1, 0
	s_add_u32 s65, s65, 0x100
	s_addc_u32 s66, s66, 0
	s_cmp_gt_u32 s67, 13
	s_barrier
.LBB0_613:
	ds_read_b128 v[146:149], v171
	ds_read_b128 v[150:153], v171 offset:1024
	ds_read_b128 v[154:157], v171 offset:2048
	ds_read_b128 v[158:161], v171 offset:3072
	s_add_u32 s4, s0, 0xfffc0080
	s_addc_u32 s5, s1, -1
	s_cmp_eq_u32 s67, 12
	s_cselect_b32 s7, s8, s5
	s_cselect_b32 s6, s9, s4
	s_cselect_b32 s5, s31, s66
	s_cselect_b32 s4, s35, s65
	s_add_i32 m0, s45, 0xc000
	ds_read_b128 v[162:165], v172
	ds_read_b128 v[178:181], v172 offset:1024
	ds_read_b128 v[182:185], v172 offset:2048
	ds_read_b128 v[186:189], v172 offset:3072
	ds_read_b128 v[190:193], v172 offset:4096
	ds_read_b128 v[194:197], v172 offset:5120
	ds_read_b128 v[202:205], v172 offset:6144
	ds_read_b128 v[206:209], v172 offset:7168
	global_load_lds_dwordx4 v138, s[0:1]
	s_add_i32 m0, s45, 0xe000
	s_nop 0
	global_load_lds_dwordx4 v140, s[0:1]
	s_waitcnt lgkmcnt(8)
	s_barrier
	s_waitcnt lgkmcnt(0)
	s_setprio 1
	s_waitcnt lgkmcnt(0)
	v_mfma_f32_16x16x32_bf16 v[124:127], v[146:149], v[162:165], v[124:127]
	v_mfma_f32_16x16x32_bf16 v[120:123], v[154:157], v[162:165], v[120:123]
	v_mfma_f32_16x16x32_bf16 v[108:111], v[146:149], v[182:185], v[108:111]
	v_mfma_f32_16x16x32_bf16 v[104:107], v[154:157], v[182:185], v[104:107]
	v_mfma_f32_16x16x32_bf16 v[92:95], v[146:149], v[190:193], v[92:95]
	v_mfma_f32_16x16x32_bf16 v[88:91], v[154:157], v[190:193], v[88:91]
	v_mfma_f32_16x16x32_bf16 v[76:79], v[146:149], v[202:205], v[76:79]
	v_mfma_f32_16x16x32_bf16 v[72:75], v[154:157], v[202:205], v[72:75]
	v_mfma_f32_16x16x32_bf16 v[124:127], v[150:153], v[178:181], v[124:127]
	v_mfma_f32_16x16x32_bf16 v[120:123], v[158:161], v[178:181], v[120:123]
	v_mfma_f32_16x16x32_bf16 v[108:111], v[150:153], v[186:189], v[108:111]
	v_mfma_f32_16x16x32_bf16 v[104:107], v[158:161], v[186:189], v[104:107]
	v_mfma_f32_16x16x32_bf16 v[92:95], v[150:153], v[194:197], v[92:95]
	v_mfma_f32_16x16x32_bf16 v[88:91], v[158:161], v[194:197], v[88:91]
	v_mfma_f32_16x16x32_bf16 v[76:79], v[150:153], v[206:209], v[76:79]
	v_mfma_f32_16x16x32_bf16 v[72:75], v[158:161], v[206:209], v[72:75]
	s_setprio 0
	s_barrier
	s_add_i32 s68, s57, s44
	s_mov_b32 m0, s68
	ds_read_b128 v[210:213], v173
	ds_read_b128 v[214:217], v173 offset:1024
	ds_read_b128 v[218:221], v173 offset:2048
	ds_read_b128 v[222:225], v173 offset:3072
	global_load_lds_dwordx4 v130, s[4:5]
	s_add_i32 m0, s68, 0x2000
	s_nop 0
	global_load_lds_dwordx4 v134, s[4:5]
	s_barrier
; #define PG8_STAGE(bufoff, gbase, voff) do { _Pragma("unroll") for (int _i = 0; _i < 2; ++_i) \
;         __builtin_amdgcn_global_load_lds((const unsigned*)((const char*)(gbase) + (voff)[_i]), (LAS unsigned*)(lds + (bufoff) + ldsw + _i * 8192), 16, 0, 0); } while (0)
; #define PG8_LDA(dst, b, h) do { _Pragma("unroll") for (int m = 0; m < 4; ++m) _Pragma("unroll") for (int k = 0; k < 2; ++k) dst[m][k] = *(const LAS bf16x8*)(lds + PG8_SA(b, h) + aoff + m * 2048 + k * 1024); } while (0)
; #define PG8_LDB(dst, b, h) do { _Pragma("unroll") for (int n = 0; n < 2; ++n) _Pragma("unroll") for (int k = 0; k < 2; ++k) dst[n][k] = *(const LAS bf16x8*)(lds + PG8_SB(b, h) + boff + n * 2048 + k * 1024); } while (0)
; #define PG8_MMA(ai, bj, At, Bt) do { __builtin_amdgcn_s_setprio(1); _Pragma("unroll") for (int m = 0; m < 4; ++m) _Pragma("unroll") for (int n = 0; n < 2; ++n) _Pragma("unroll") for (int k = 0; k < 2; ++k) \
;         acc[ai][bj][m][n] = __builtin_amdgcn_mfma_f32_16x16x32_bf16(Bt[n][k], At[m][k], acc[ai][bj][m][n], 0, 0, 0); __builtin_amdgcn_s_setprio(0); } while (0)
; #define PG8_WAIT_V(n) asm volatile("s_waitcnt vmcnt(" #n ")" ::: "memory")
; #define PG8_WAIT_L(n) asm volatile("s_waitcnt lgkmcnt(" #n ")" ::: "memory")
; #define PG8_BAR __builtin_amdgcn_s_barrier()
; #define PG8_SCHED __builtin_amdgcn_sched_barrier(0)
; template <class Epi, class Sched>
; __device__ __forceinline__ void gemm_phase(LAS unsigned char* lds, const Gemm g, const Sched& S, const Epi& E) {
;     ...
;             PG8_BAR; PG8_WAIT_L(0); PG8_MMA(0, 1, At, B1); PG8_BAR;
;             PG8_LDA(At, 0, 1); PG8_STAGE(PG8_SA(0, 0), a2, voffA);
;             PG8_BAR; PG8_WAIT_L(0); PG8_MMA(1, 0, At, B0); PG8_BAR; PG8_SCHED;
;             PG8_STAGE(PG8_SB(0, 1), b2 + hstep, voffB);
;             PG8_WAIT_V(6); PG8_BAR; PG8_MMA(1, 1, At, B1); PG8_BAR;
;             PG8_LDB(B0, 1, 0); PG8_SCHED; PG8_LDA(At, 1, 0); PG8_STAGE(PG8_SA(0, 1), a2 + hstep, voffA);
;             PG8_WAIT_L(8); PG8_BAR; PG8_WAIT_L(0); PG8_MMA(0, 0, At, B0); PG8_BAR; PG8_SCHED;
	s_waitcnt lgkmcnt(0)
	s_setprio 1
	s_waitcnt lgkmcnt(0)
	v_mfma_f32_16x16x32_bf16 v[116:119], v[210:213], v[162:165], v[116:119]
	v_mfma_f32_16x16x32_bf16 v[112:115], v[218:221], v[162:165], v[112:115]
	v_mfma_f32_16x16x32_bf16 v[100:103], v[210:213], v[182:185], v[100:103]
	v_mfma_f32_16x16x32_bf16 v[96:99], v[218:221], v[182:185], v[96:99]
	v_mfma_f32_16x16x32_bf16 v[84:87], v[210:213], v[190:193], v[84:87]
	v_mfma_f32_16x16x32_bf16 v[80:83], v[218:221], v[190:193], v[80:83]
	v_mfma_f32_16x16x32_bf16 v[68:71], v[210:213], v[202:205], v[68:71]
	v_mfma_f32_16x16x32_bf16 v[64:67], v[218:221], v[202:205], v[64:67]
	v_mfma_f32_16x16x32_bf16 v[116:119], v[214:217], v[178:181], v[116:119]
	v_mfma_f32_16x16x32_bf16 v[112:115], v[222:225], v[178:181], v[112:115]
	v_mfma_f32_16x16x32_bf16 v[100:103], v[214:217], v[186:189], v[100:103]
	v_mfma_f32_16x16x32_bf16 v[96:99], v[222:225], v[186:189], v[96:99]
	v_mfma_f32_16x16x32_bf16 v[84:87], v[214:217], v[194:197], v[84:87]
	v_mfma_f32_16x16x32_bf16 v[80:83], v[222:225], v[194:197], v[80:83]
	v_mfma_f32_16x16x32_bf16 v[68:71], v[214:217], v[206:209], v[68:71]
	v_mfma_f32_16x16x32_bf16 v[64:67], v[222:225], v[206:209], v[64:67]
	s_setprio 0
	s_mov_b32 m0, s45
	v_lshl_add_u64 v[226:227], s[6:7], 0, v[128:129]
	s_barrier
	ds_read_b128 v[162:165], v172 offset:16384
	ds_read_b128 v[178:181], v172 offset:17408
	ds_read_b128 v[182:185], v172 offset:18432
	ds_read_b128 v[186:189], v172 offset:19456
	ds_read_b128 v[190:193], v172 offset:20480
	ds_read_b128 v[194:197], v172 offset:21504
	ds_read_b128 v[202:205], v172 offset:22528
	ds_read_b128 v[206:209], v172 offset:23552
	global_load_lds_dwordx4 v128, s[6:7]
	v_lshl_add_u64 v[228:229], s[6:7], 0, v[132:133]
	s_mov_b32 m0, s46
	s_nop 0
	global_load_lds_dwordx4 v132, s[6:7]
	s_barrier
	s_waitcnt lgkmcnt(0)
	s_setprio 1
	s_waitcnt lgkmcnt(0)
	v_mfma_f32_16x16x32_bf16 v[60:63], v[146:149], v[162:165], v[60:63]
	v_mfma_f32_16x16x32_bf16 v[56:59], v[154:157], v[162:165], v[56:59]
	v_mfma_f32_16x16x32_bf16 v[44:47], v[146:149], v[182:185], v[44:47]
	v_mfma_f32_16x16x32_bf16 v[40:43], v[154:157], v[182:185], v[40:43]
	v_mfma_f32_16x16x32_bf16 v[28:31], v[146:149], v[190:193], v[28:31]
	v_mfma_f32_16x16x32_bf16 v[24:27], v[154:157], v[190:193], v[24:27]
	v_mfma_f32_16x16x32_bf16 v[12:15], v[146:149], v[202:205], v[12:15]
	v_mfma_f32_16x16x32_bf16 v[8:11], v[154:157], v[202:205], v[8:11]
	v_mfma_f32_16x16x32_bf16 v[60:63], v[150:153], v[178:181], v[60:63]
	v_mfma_f32_16x16x32_bf16 v[56:59], v[158:161], v[178:181], v[56:59]
	v_mfma_f32_16x16x32_bf16 v[44:47], v[150:153], v[186:189], v[44:47]
	v_mfma_f32_16x16x32_bf16 v[40:43], v[158:161], v[186:189], v[40:43]
	v_mfma_f32_16x16x32_bf16 v[28:31], v[150:153], v[194:197], v[28:31]
	v_mfma_f32_16x16x32_bf16 v[24:27], v[158:161], v[194:197], v[24:27]
	v_mfma_f32_16x16x32_bf16 v[12:15], v[150:153], v[206:209], v[12:15]
	v_mfma_f32_16x16x32_bf16 v[8:11], v[158:161], v[206:209], v[8:11]
	s_setprio 0
	s_barrier
	s_add_u32 s68, s4, 0x40000
	s_addc_u32 s69, s5, 0
	s_add_i32 s70, s58, s44
	s_mov_b32 m0, s70
	s_nop 0
	global_load_lds_dwordx4 v130, s[68:69]
	s_add_i32 m0, s70, 0x2000
	s_nop 0
	global_load_lds_dwordx4 v134, s[68:69]
	s_waitcnt vmcnt(6)
	s_barrier
	s_setprio 1
	v_mfma_f32_16x16x32_bf16 v[52:55], v[210:213], v[162:165], v[52:55]
	v_mfma_f32_16x16x32_bf16 v[48:51], v[218:221], v[162:165], v[48:51]
	v_mfma_f32_16x16x32_bf16 v[36:39], v[210:213], v[182:185], v[36:39]
	v_mfma_f32_16x16x32_bf16 v[32:35], v[218:221], v[182:185], v[32:35]
	v_mfma_f32_16x16x32_bf16 v[20:23], v[210:213], v[190:193], v[20:23]
	v_mfma_f32_16x16x32_bf16 v[16:19], v[218:221], v[190:193], v[16:19]
	v_mfma_f32_16x16x32_bf16 v[4:7], v[210:213], v[202:205], v[4:7]
	v_mfma_f32_16x16x32_bf16 v[0:3], v[218:221], v[202:205], v[0:3]
	v_mfma_f32_16x16x32_bf16 v[52:55], v[214:217], v[178:181], v[52:55]
	v_mfma_f32_16x16x32_bf16 v[48:51], v[222:225], v[178:181], v[48:51]
	v_mfma_f32_16x16x32_bf16 v[36:39], v[214:217], v[186:189], v[36:39]
	v_mfma_f32_16x16x32_bf16 v[32:35], v[222:225], v[186:189], v[32:35]
	v_mfma_f32_16x16x32_bf16 v[20:23], v[214:217], v[194:197], v[20:23]
	v_mfma_f32_16x16x32_bf16 v[16:19], v[222:225], v[194:197], v[16:19]
	v_mfma_f32_16x16x32_bf16 v[4:7], v[214:217], v[206:209], v[4:7]
	v_mfma_f32_16x16x32_bf16 v[0:3], v[222:225], v[206:209], v[0:3]
	s_setprio 0
	s_add_i32 s68, 0, 0x18000
	v_add_u32_e32 v136, s68, v170
	s_barrier
	ds_read_b128 v[146:149], v136
	ds_read_b128 v[150:153], v136 offset:1024
	ds_read_b128 v[154:157], v136 offset:2048
	ds_read_b128 v[158:161], v136 offset:3072
	s_add_u32 s6, s6, 0x40000
	s_addc_u32 s7, s7, 0
	s_mov_b32 m0, s47
	ds_read_b128 v[162:165], v172 offset:32768
	ds_read_b128 v[178:181], v172 offset:33792
	ds_read_b128 v[182:185], v172 offset:34816
	ds_read_b128 v[186:189], v172 offset:35840
	ds_read_b128 v[190:193], v172 offset:36864
	ds_read_b128 v[194:197], v172 offset:37888
	ds_read_b128 v[202:205], v172 offset:38912
	ds_read_b128 v[206:209], v172 offset:39936
	global_load_lds_dwordx4 v128, s[6:7]
	s_mov_b32 m0, s48
	s_nop 0
	global_load_lds_dwordx4 v132, s[6:7]
	s_waitcnt lgkmcnt(8)
	s_barrier
; #define PG8_STAGE(bufoff, gbase, voff) do { _Pragma("unroll") for (int _i = 0; _i < 2; ++_i) \
;         __builtin_amdgcn_global_load_lds((const unsigned*)((const char*)(gbase) + (voff)[_i]), (LAS unsigned*)(lds + (bufoff) + ldsw + _i * 8192), 16, 0, 0); } while (0)
; #define PG8_LDA(dst, b, h) do { _Pragma("unroll") for (int m = 0; m < 4; ++m) _Pragma("unroll") for (int k = 0; k < 2; ++k) dst[m][k] = *(const LAS bf16x8*)(lds + PG8_SA(b, h) + aoff + m * 2048 + k * 1024); } while (0)
; #define PG8_LDB(dst, b, h) do { _Pragma("unroll") for (int n = 0; n < 2; ++n) _Pragma("unroll") for (int k = 0; k < 2; ++k) dst[n][k] = *(const LAS bf16x8*)(lds + PG8_SB(b, h) + boff + n * 2048 + k * 1024); } while (0)
; #define PG8_MMA(ai, bj, At, Bt) do { __builtin_amdgcn_s_setprio(1); _Pragma("unroll") for (int m = 0; m < 4; ++m) _Pragma("unroll") for (int n = 0; n < 2; ++n) _Pragma("unroll") for (int k = 0; k < 2; ++k) \
;         acc[ai][bj][m][n] = __builtin_amdgcn_mfma_f32_16x16x32_bf16(Bt[n][k], At[m][k], acc[ai][bj][m][n], 0, 0, 0); __builtin_amdgcn_s_setprio(0); } while (0)
; #define PG8_WAIT_V(n) asm volatile("s_waitcnt vmcnt(" #n ")" ::: "memory")
; #define PG8_WAIT_L(n) asm volatile("s_waitcnt lgkmcnt(" #n ")" ::: "memory")
; #define PG8_BAR __builtin_amdgcn_s_barrier()
; #define PG8_SCHED __builtin_amdgcn_sched_barrier(0)
; template <class Epi, class Sched>
; __device__ __forceinline__ void gemm_phase(LAS unsigned char* lds, const Gemm g, const Sched& S, const Epi& E) {
;     ...
;             PG8_WAIT_L(8); PG8_BAR; PG8_WAIT_L(0); PG8_MMA(0, 0, At, B0); PG8_BAR; PG8_SCHED;
;             PG8_LDB(B1, 1, 1); PG8_STAGE(PG8_SB(1, 0), b3, voffB);
;             PG8_BAR; PG8_WAIT_L(0); PG8_MMA(0, 1, At, B1); PG8_BAR;
;             PG8_LDA(At, 1, 1); PG8_STAGE(PG8_SA(1, 0), a3, voffA);
;             PG8_BAR; PG8_WAIT_L(0); PG8_MMA(1, 0, At, B0); PG8_BAR; PG8_SCHED;
;             PG8_STAGE(PG8_SB(1, 1), b3 + hstep, voffB);
;             PG8_WAIT_V(6); PG8_BAR; PG8_MMA(1, 1, At, B1); PG8_BAR;
	s_waitcnt lgkmcnt(0)
	s_setprio 1
	s_waitcnt lgkmcnt(0)
	v_mfma_f32_16x16x32_bf16 v[124:127], v[146:149], v[162:165], v[124:127]
	v_mfma_f32_16x16x32_bf16 v[120:123], v[154:157], v[162:165], v[120:123]
	v_mfma_f32_16x16x32_bf16 v[108:111], v[146:149], v[182:185], v[108:111]
	v_mfma_f32_16x16x32_bf16 v[104:107], v[154:157], v[182:185], v[104:107]
	v_mfma_f32_16x16x32_bf16 v[92:95], v[146:149], v[190:193], v[92:95]
	v_mfma_f32_16x16x32_bf16 v[88:91], v[154:157], v[190:193], v[88:91]
	v_mfma_f32_16x16x32_bf16 v[76:79], v[146:149], v[202:205], v[76:79]
	v_mfma_f32_16x16x32_bf16 v[72:75], v[154:157], v[202:205], v[72:75]
	v_mfma_f32_16x16x32_bf16 v[124:127], v[150:153], v[178:181], v[124:127]
	v_mfma_f32_16x16x32_bf16 v[120:123], v[158:161], v[178:181], v[120:123]
	v_mfma_f32_16x16x32_bf16 v[108:111], v[150:153], v[186:189], v[108:111]
	v_mfma_f32_16x16x32_bf16 v[104:107], v[158:161], v[186:189], v[104:107]
	v_mfma_f32_16x16x32_bf16 v[92:95], v[150:153], v[194:197], v[92:95]
	v_mfma_f32_16x16x32_bf16 v[88:91], v[158:161], v[194:197], v[88:91]
	v_mfma_f32_16x16x32_bf16 v[76:79], v[150:153], v[206:209], v[76:79]
	v_mfma_f32_16x16x32_bf16 v[72:75], v[158:161], v[206:209], v[72:75]
	s_setprio 0
	s_barrier
	s_add_i32 s6, 0, 0x1c000
	s_add_i32 s7, s68, s44
	v_add_u32_e32 v136, s6, v170
	s_add_u32 s20, s4, 0x80
	s_addc_u32 s21, s5, 0
	s_mov_b32 m0, s7
	ds_read_b128 v[210:213], v136
	ds_read_b128 v[214:217], v136 offset:1024
	ds_read_b128 v[218:221], v136 offset:2048
	ds_read_b128 v[222:225], v136 offset:3072
	global_load_lds_dwordx4 v130, s[20:21]
	s_add_i32 m0, s7, 0x2000
	s_nop 0
	global_load_lds_dwordx4 v134, s[20:21]
	s_barrier
	s_waitcnt lgkmcnt(0)
	s_setprio 1
	s_waitcnt lgkmcnt(0)
	v_mfma_f32_16x16x32_bf16 v[116:119], v[210:213], v[162:165], v[116:119]
	v_mfma_f32_16x16x32_bf16 v[112:115], v[218:221], v[162:165], v[112:115]
	v_mfma_f32_16x16x32_bf16 v[100:103], v[210:213], v[182:185], v[100:103]
	v_mfma_f32_16x16x32_bf16 v[96:99], v[218:221], v[182:185], v[96:99]
	v_mfma_f32_16x16x32_bf16 v[84:87], v[210:213], v[190:193], v[84:87]
	v_mfma_f32_16x16x32_bf16 v[80:83], v[218:221], v[190:193], v[80:83]
	v_mfma_f32_16x16x32_bf16 v[68:71], v[210:213], v[202:205], v[68:71]
	v_mfma_f32_16x16x32_bf16 v[64:67], v[218:221], v[202:205], v[64:67]
	v_mfma_f32_16x16x32_bf16 v[116:119], v[214:217], v[178:181], v[116:119]
	v_mfma_f32_16x16x32_bf16 v[112:115], v[222:225], v[178:181], v[112:115]
	v_mfma_f32_16x16x32_bf16 v[100:103], v[214:217], v[186:189], v[100:103]
	v_mfma_f32_16x16x32_bf16 v[96:99], v[222:225], v[186:189], v[96:99]
	v_mfma_f32_16x16x32_bf16 v[84:87], v[214:217], v[194:197], v[84:87]
	v_mfma_f32_16x16x32_bf16 v[80:83], v[222:225], v[194:197], v[80:83]
	v_mfma_f32_16x16x32_bf16 v[68:71], v[214:217], v[206:209], v[68:71]
	v_mfma_f32_16x16x32_bf16 v[64:67], v[222:225], v[206:209], v[64:67]
	s_setprio 0
	s_mov_b32 m0, s54
	s_mov_b64 s[20:21], 0x80
	v_lshl_add_u64 v[166:167], v[226:227], 0, s[20:21]
	s_barrier
	ds_read_b128 v[162:165], v172 offset:49152
	ds_read_b128 v[178:181], v172 offset:50176
	ds_read_b128 v[182:185], v172 offset:51200
	ds_read_b128 v[186:189], v172 offset:52224
	ds_read_b128 v[190:193], v172 offset:53248
	ds_read_b128 v[194:197], v172 offset:54272
	ds_read_b128 v[202:205], v172 offset:55296
	ds_read_b128 v[206:209], v172 offset:56320
	global_load_lds_dwordx4 v[166:167], off
	v_lshl_add_u64 v[166:167], v[228:229], 0, s[20:21]
	s_mov_b32 m0, s55
	s_nop 0
	global_load_lds_dwordx4 v[166:167], off
	s_barrier
	s_waitcnt lgkmcnt(0)
	s_setprio 1
	s_waitcnt lgkmcnt(0)
	v_mfma_f32_16x16x32_bf16 v[60:63], v[146:149], v[162:165], v[60:63]
	v_mfma_f32_16x16x32_bf16 v[56:59], v[154:157], v[162:165], v[56:59]
	v_mfma_f32_16x16x32_bf16 v[44:47], v[146:149], v[182:185], v[44:47]
	v_mfma_f32_16x16x32_bf16 v[40:43], v[154:157], v[182:185], v[40:43]
	v_mfma_f32_16x16x32_bf16 v[28:31], v[146:149], v[190:193], v[28:31]
	v_mfma_f32_16x16x32_bf16 v[24:27], v[154:157], v[190:193], v[24:27]
	v_mfma_f32_16x16x32_bf16 v[12:15], v[146:149], v[202:205], v[12:15]
	v_mfma_f32_16x16x32_bf16 v[8:11], v[154:157], v[202:205], v[8:11]
	v_mfma_f32_16x16x32_bf16 v[60:63], v[150:153], v[178:181], v[60:63]
	v_mfma_f32_16x16x32_bf16 v[56:59], v[158:161], v[178:181], v[56:59]
	v_mfma_f32_16x16x32_bf16 v[44:47], v[150:153], v[186:189], v[44:47]
	v_mfma_f32_16x16x32_bf16 v[40:43], v[158:161], v[186:189], v[40:43]
	v_mfma_f32_16x16x32_bf16 v[28:31], v[150:153], v[194:197], v[28:31]
	v_mfma_f32_16x16x32_bf16 v[24:27], v[158:161], v[194:197], v[24:27]
	v_mfma_f32_16x16x32_bf16 v[12:15], v[150:153], v[206:209], v[12:15]
	v_mfma_f32_16x16x32_bf16 v[8:11], v[158:161], v[206:209], v[8:11]
	s_setprio 0
	s_barrier
	s_add_u32 s4, s4, 0x40080
	s_addc_u32 s5, s5, 0
	s_add_i32 s6, s6, s44
	s_mov_b32 m0, s6
	s_nop 0
	global_load_lds_dwordx4 v130, s[4:5]
	s_add_i32 m0, s6, 0x2000
	s_nop 0
	global_load_lds_dwordx4 v134, s[4:5]
	s_waitcnt vmcnt(6)
	s_barrier
	s_setprio 1
	v_mfma_f32_16x16x32_bf16 v[52:55], v[210:213], v[162:165], v[52:55]
	v_mfma_f32_16x16x32_bf16 v[48:51], v[218:221], v[162:165], v[48:51]
	v_mfma_f32_16x16x32_bf16 v[36:39], v[210:213], v[182:185], v[36:39]
	v_mfma_f32_16x16x32_bf16 v[32:35], v[218:221], v[182:185], v[32:35]
	v_mfma_f32_16x16x32_bf16 v[20:23], v[210:213], v[190:193], v[20:23]
	v_mfma_f32_16x16x32_bf16 v[16:19], v[218:221], v[190:193], v[16:19]
	v_mfma_f32_16x16x32_bf16 v[4:7], v[210:213], v[202:205], v[4:7]
	v_mfma_f32_16x16x32_bf16 v[0:3], v[218:221], v[202:205], v[0:3]
	v_mfma_f32_16x16x32_bf16 v[52:55], v[214:217], v[178:181], v[52:55]
	v_mfma_f32_16x16x32_bf16 v[48:51], v[222:225], v[178:181], v[48:51]
	v_mfma_f32_16x16x32_bf16 v[36:39], v[214:217], v[186:189], v[36:39]
	v_mfma_f32_16x16x32_bf16 v[32:35], v[222:225], v[186:189], v[32:35]
	v_mfma_f32_16x16x32_bf16 v[20:23], v[214:217], v[194:197], v[20:23]
	v_mfma_f32_16x16x32_bf16 v[16:19], v[222:225], v[194:197], v[16:19]
	v_mfma_f32_16x16x32_bf16 v[4:7], v[214:217], v[206:209], v[4:7]
	v_mfma_f32_16x16x32_bf16 v[0:3], v[222:225], v[206:209], v[0:3]
	s_setprio 0
	s_add_i32 s67, s67, 2
	s_add_u32 s0, s0, 0x100
	s_addc_u32 s1, s1, 0
	s_add_u32 s65, s65, 0x100
	s_addc_u32 s66, s66, 0
	s_cmp_gt_u32 s67, 13
	s_barrier
; #define PG8_BAR __builtin_amdgcn_s_barrier()
; template <class Epi, class Sched>
; __device__ __forceinline__ void gemm_phase(LAS unsigned char* lds, const Gemm g, const Sched& S, const Epi& E) {
;     ...
;         for (int t = 0; t < nt; t += 2) {
;             const bool last = (t == nt - 2);
;             const char* a1 = cA + (size_t)(t + 1) * kstep;
;             const char* a2 = last ? nA : cA + (size_t)(t + 2) * kstep; const char* b2 = last ? nB : cB + (size_t)(t + 2) * kstep;
;             const char* a3 = a2 + kstep; const char* b3 = b2 + kstep;
;             PG8_LDB(B0, 0, 0); PG8_SCHED; PG8_LDA(At, 0, 0); PG8_STAGE(PG8_SA(1, 1), a1 + hstep, voffA);
;             PG8_WAIT_L(8); PG8_BAR; PG8_WAIT_L(0); PG8_MMA(0, 0, At, B0); PG8_BAR; PG8_SCHED;
;             PG8_LDB(B1, 0, 1); PG8_STAGE(PG8_SB(0, 0), b2, voffB);
;             PG8_BAR; PG8_WAIT_L(0); PG8_MMA(0, 1, At, B1); PG8_BAR;
;             PG8_LDA(At, 0, 1); PG8_STAGE(PG8_SA(0, 0), a2, voffA);
;             PG8_BAR; PG8_WAIT_L(0); PG8_MMA(1, 0, At, B0); PG8_BAR; PG8_SCHED;
;             PG8_STAGE(PG8_SB(0, 1), b2 + hstep, voffB);
;             PG8_WAIT_V(6); PG8_BAR; PG8_MMA(1, 1, At, B1); PG8_BAR;
;             PG8_LDB(B0, 1, 0); PG8_SCHED; PG8_LDA(At, 1, 0); PG8_STAGE(PG8_SA(0, 1), a2 + hstep, voffA);
;             PG8_WAIT_L(8); PG8_BAR; PG8_WAIT_L(0); PG8_MMA(0, 0, At, B0); PG8_BAR; PG8_SCHED;
;             PG8_LDB(B1, 1, 1); PG8_STAGE(PG8_SB(1, 0), b3, voffB);
;             PG8_BAR; PG8_WAIT_L(0); PG8_MMA(0, 1, At, B1); PG8_BAR;
;             PG8_LDA(At, 1, 1); PG8_STAGE(PG8_SA(1, 0), a3, voffA);
;             PG8_BAR; PG8_WAIT_L(0); PG8_MMA(1, 0, At, B0); PG8_BAR; PG8_SCHED;
;             PG8_STAGE(PG8_SB(1, 1), b3 + hstep, voffB);
;             PG8_WAIT_V(6); PG8_BAR; PG8_MMA(1, 1, At, B1); PG8_BAR;
;         }
;         E(acc, cur, wr, wc, fr, fq);
;     __device__ __forceinline__ void operator()(const AccT& acc, const Unit& u, int wr, int wc, int fr, int fq) const {
;     ...
;         const int rbase = wr * 64 + fr;
;         const int tb = u.pn * 256 + wc * 32 + 8 * fq;
;         const int o0 = wc * 32 + 8 * fq;
;         const int j = fr & 3; const float sgn = ((fr >> 2) & 1) ? 1.0f : -1.0f;
; #pragma unroll
;         for (int ai = 0; ai < 2; ++ai) {
;             const int hh = 2 * ai + wr;
;             const float l2f = lgd[hh] * 1.4426950408889634f, l2b = lgd[4 + hh] * 1.4426950408889634f;
	s_cbranch_scc0 .LBB0_613
	v_mov_b32_e32 v136, v169
	v_mov_b32_e32 v150, v168
	s_lshl_b32 s0, s33, 8
	global_load_dword v154, v137, s[22:23]
	global_load_dword v155, v137, s[22:23] offset:16
	s_or_b32 s0, s0, s53
	v_lshlrev_b32_e32 v151, 3, v136
	v_ashrrev_i32_e32 v136, 1, v150
	v_add_u32_e32 v162, s0, v151
	v_bfi_b32 v136, -4, v136, v150
	v_lshrrev_b32_e32 v146, 2, v162
	v_add_u32_e32 v192, 0x400, v136
	v_and_b32_e32 v187, 0x1f0, v146
	v_add_u32_e32 v146, v192, v187
	v_add_u32_e32 v148, v187, v136
	v_ashrrev_i32_e32 v147, 31, v146
	v_ashrrev_i32_e32 v149, 31, v148
	v_lshl_add_u64 v[146:147], v[146:147], 2, s[16:17]
	v_lshl_add_u64 v[148:149], v[148:149], 2, s[16:17]
	global_load_dword v153, v[146:147], off
	global_load_dword v166, v[148:149], off
	v_and_b32_e32 v157, 64, v174
	v_xor_b32_e32 v156, 4, v174
	v_add_u32_e32 v157, 64, v157
	v_cmp_lt_i32_e32 vcc, v156, v157
	v_mov_b32_e32 v152, v124
	v_add_u32_e32 v151, s53, v151
	v_cndmask_b32_e32 v156, v174, v156, vcc
	v_lshlrev_b32_e32 v177, 2, v156
	ds_bpermute_b32 v124, v177, v124
	v_sub_u32_e32 v156, 0x7f, v151
	v_add_u32_e32 v164, s52, v150
	v_and_b32_e32 v150, 4, v150
	v_cvt_f32_i32_e32 v179, v156
	v_cvt_f32_i32_e32 v178, v151
	v_cmp_eq_u32_e32 vcc, 0, v150
	ds_bpermute_b32 v157, v177, v125
	ds_bpermute_b32 v158, v177, v127
	s_waitcnt lgkmcnt(0)
	v_cndmask_b32_e64 v167, v124, -v124, vcc
	ds_bpermute_b32 v151, v177, v126
	v_ashrrev_i32_e32 v165, 31, v164
	v_and_b32_e32 v186, 56, v162
	s_waitcnt lgkmcnt(0)
	v_cndmask_b32_e64 v151, v151, -v151, vcc
	s_waitcnt vmcnt(0)
	v_mul_f32_e32 v124, 0x3fb8aa3b, v154
	v_mul_f32_e32 v150, 0x3fb8aa3b, v155
	v_cmp_lt_f32_e64 s[4:5], s60, v124
	v_mul_f32_e32 v156, v124, v179
	v_cmp_gt_f32_e64 s[6:7], s59, v150
	v_cndmask_b32_e64 v159, 0, v176, s[4:5]
	v_mul_f32_e32 v160, v150, v178
	v_cndmask_b32_e64 v161, 0, v176, s[6:7]
	v_cmp_gt_f32_e64 s[8:9], s59, v156
	v_fmac_f32_e32 v159, 0xbfb8aa3b, v154
	s_and_b64 s[0:1], s[4:5], exec
	v_cmp_gt_f32_e64 s[4:5], s59, v160
	v_fmac_f32_e32 v161, 0x3fb8aa3b, v155
	v_cndmask_b32_e64 v154, 0, v176, s[8:9]
	v_exp_f32_e32 v155, v159
	v_cndmask_b32_e64 v159, 0, v176, s[4:5]
	v_fmac_f32_e32 v154, v124, v179
	v_fmac_f32_e32 v159, v150, v178
	v_exp_f32_e32 v150, v154
	v_cndmask_b32_e64 v156, 0, v175, s[8:9]
	s_cselect_b32 s8, 0xffffffc0, 0
	v_exp_f32_e32 v161, v161
	v_exp_f32_e32 v159, v159
	v_ldexp_f32 v163, v155, s8
	v_pk_mul_f32 v[154:155], v[152:153], v[166:167]
	v_cndmask_b32_e64 v167, v157, -v157, vcc
	v_mov_b32_e32 v152, v125
	s_and_b64 s[0:1], s[6:7], exec
	v_add_f32_e32 v190, v154, v155
	v_pk_mul_f32 v[154:155], v[152:153], v[166:167]
	v_cndmask_b32_e64 v167, v158, -v158, vcc
	v_mov_b32_e32 v152, v127
	v_cndmask_b32_e64 v160, 0, v175, s[4:5]
	s_cselect_b32 s0, 0xffffffc0, 0
	v_ldexp_f32 v180, v150, v156
	v_add_f32_e32 v191, v154, v155
	v_pk_mul_f32 v[154:155], v[152:153], v[166:167]
	v_ldexp_f32 v124, v161, s0
	v_mul_f32_e32 v161, v126, v166
	v_ldexp_f32 v150, v159, v160
	v_mul_f32_e32 v181, v163, v180
	v_add_f32_e32 v193, v154, v155
	global_load_dword v188, v[148:149], off
	global_load_dword v157, v[146:147], off
	ds_bpermute_b32 v127, v177, v121
	v_mov_b32_e32 v156, v121
	ds_bpermute_b32 v121, v177, v123
	ds_bpermute_b32 v125, v177, v120
	ds_bpermute_b32 v152, v177, v122
	s_waitcnt lgkmcnt(3)
	v_cndmask_b32_e64 v189, v127, -v127, vcc
	s_waitcnt lgkmcnt(1)
	v_cndmask_b32_e64 v158, v125, -v125, vcc
	s_waitcnt lgkmcnt(0)
	v_cndmask_b32_e64 v127, v152, -v152, vcc
	s_waitcnt vmcnt(1)
	v_mul_f32_e32 v159, v120, v188
	s_waitcnt vmcnt(0)
	v_pk_mul_f32 v[154:155], v[156:157], v[188:189]
	v_cndmask_b32_e64 v189, v121, -v121, vcc
	v_mov_b32_e32 v156, v123
	v_add_f32_e32 v121, v154, v155
	v_pk_mul_f32 v[154:155], v[156:157], v[188:189]
	s_nop 0
	v_add_f32_e32 v123, v154, v155
	v_mov_b32_e32 v125, v153
	v_pk_mul_f32 v[152:153], v[124:125], v[150:151]
	v_mov_b32_e32 v125, v161
	v_pk_mul_f32 v[154:155], v[124:125], v[152:153]
	v_mov_b32_e32 v125, v157
	v_mov_b32_e32 v155, v158
	v_pk_mul_f32 v[156:157], v[124:125], v[154:155]
	v_mov_b32_e32 v158, v124
	v_pk_mul_f32 v[158:159], v[158:159], v[156:157]
	v_mul_f32_e32 v167, v163, v181
	v_mov_b32_e32 v159, v127
	v_mul_f32_e32 v183, v163, v167
	v_pk_mul_f32 v[160:161], v[124:125], v[158:159]
	v_mul_f32_e32 v182, v163, v183
	v_mul_f32_e32 v151, v124, v160
	v_mul_f32_e32 v185, v163, v182
	v_mul_f32_e32 v155, v124, v151
	v_mul_f32_e32 v124, v180, v190
	v_mul_f32_e32 v125, v181, v191
	v_fma_f32 v153, v126, v166, v153
	v_mul_f32_e32 v184, v163, v185
	v_cvt_pk_bf16_f32 v124, v124, v125
	v_mul_f32_e32 v125, v167, v153
	v_mul_f32_e32 v126, v183, v193
	v_fma_f32 v120, v120, v188, v157
	v_mul_f32_e32 v159, v163, v184
	v_cvt_pk_bf16_f32 v125, v125, v126
	v_mul_f32_e32 v126, v182, v120
	v_mul_f32_e32 v127, v185, v121
	v_fma_f32 v122, v122, v188, v161
	v_cvt_pk_bf16_f32 v126, v126, v127
	v_mul_f32_e32 v127, v184, v122
	v_mul_f32_e32 v157, v159, v123
	v_cvt_pk_bf16_f32 v127, v127, v157
	v_mul_f32_e32 v157, v150, v190
	v_mul_f32_e32 v120, v158, v120
	v_mul_f32_e32 v121, v160, v121
	v_mul_f32_e32 v161, v152, v191
	v_cvt_pk_bf16_f32 v188, v157, v161
	v_mul_f32_e32 v153, v154, v153
	v_mul_f32_e32 v157, v156, v193
	v_cvt_pk_bf16_f32 v189, v153, v157
	v_cvt_pk_bf16_f32 v190, v120, v121
	v_mul_f32_e32 v120, v151, v122
	v_mul_f32_e32 v121, v155, v123
	v_cvt_pk_bf16_f32 v191, v120, v121
	v_lshlrev_b64 v[120:121], 17, v[164:165]
	v_lshl_add_u64 v[120:121], s[80:81], 0, v[120:121]
	v_ashrrev_i32_e32 v163, 31, v162
	v_lshl_add_u64 v[120:121], v[162:163], 1, v[120:121]
	s_mov_b64 s[0:1], 0x2000000
	global_store_dwordx4 v[120:121], v[124:127], off
	s_nop 1
	v_lshl_add_u64 v[126:127], v[120:121], 0, s[0:1]
	s_brev_b32 s0, 64
	v_add_co_u32_e64 v122, s[4:5], s0, v120
	s_nop 1
	v_addc_co_u32_e64 v123, s[4:5], 0, v121, s[4:5]
	global_store_dwordx4 v[122:123], v[188:191], off
	v_add_u32_e32 v122, 0x80, v162
	v_lshrrev_b32_e32 v122, 2, v122
	v_and_b32_e32 v153, 0x1f0, v122
	v_add_u32_e32 v122, v153, v192
	v_add_u32_e32 v124, v153, v136
	v_ashrrev_i32_e32 v123, 31, v122
	v_ashrrev_i32_e32 v125, 31, v124
	v_lshl_add_u64 v[122:123], v[122:123], 2, s[16:17]
	v_lshl_add_u64 v[124:125], v[124:125], 2, s[16:17]
	global_load_dword v163, v[122:123], off
	global_load_dword v164, v[124:125], off
	ds_bpermute_b32 v157, v177, v116
	v_mov_b32_e32 v162, v116
	ds_bpermute_b32 v116, v177, v117
	ds_bpermute_b32 v161, v177, v118
	ds_bpermute_b32 v166, v177, v119
	s_waitcnt lgkmcnt(3)
;     __device__ __forceinline__ void operator()(const AccT& acc, const Unit& u, int wr, int wc, int fr, int fq) const {
;     ...
;             for (int m = 0; m < 4; ++m) {
;                 const int r = rbase + ai * 128 + m * 16;
;                 const int d = 4 * (2 * m + (fr >> 3)) + j;
; #pragma unroll
;                 for (int bj = 0; bj < 2; ++bj) {
;                     const int t0 = tb + bj * 128;
;                     float v[8];
; #pragma unroll
;                     for (int jj = 0; jj < 4; ++jj) { v[jj] = acc[ai][bj][m][0][jj]; v[4 + jj] = acc[ai][bj][m][1][jj]; }
;                     if constexpr (ROPE) {
;                         const int t = t0 & 2047;
; #pragma unroll
;                         for (int hf = 0; hf < 2; ++hf) {
;                             f32x4 cs, sn;
;                             if (m < 2) { const float c1 = ropeA[(t >> 6) * 16 + d], s1 = ropeA[1024 + (t >> 6) * 16 + d]; cs = (f32x4){c1, c1, c1, c1}; sn = (f32x4){s1, s1, s1, s1}; }
;                             else { const float* cb = ropeA + 2048 + (d - 16) * 64 + (t & 63) + 4 * hf; cs = *(const f32x4*)(cb); sn = *(const f32x4*)(cb + 1024); }
; #pragma unroll
;                             for (int jj = 0; jj < 4; ++jj) { const float pr = __shfl_xor(v[4 * hf + jj], 4); v[4 * hf + jj] = v[4 * hf + jj] * cs[jj] + sgn * pr * sn[jj]; }
;                             __builtin_amdgcn_sched_barrier(0);
;                         }
;                     }
;                     float zf[8], zb[8]; zf[0] = zf0; zb[0] = zb0;
; #pragma unroll
;                     for (int jj = 1; jj < 8; ++jj) { zf[jj] = zf[jj - 1] * zfs; zb[jj] = zb[jj - 1] * zbs; }
;                     u32x4 wf, wb;
;                     wf.x = cvt_pk_bf16(v[0] * zf[0], v[1] * zf[1]); wf.y = cvt_pk_bf16(v[2] * zf[2], v[3] * zf[3]); wf.z = cvt_pk_bf16(v[4] * zf[4], v[5] * zf[5]); wf.w = cvt_pk_bf16(v[6] * zf[6], v[7] * zf[7]);
;                     wb.x = cvt_pk_bf16(v[0] * zb[0], v[1] * zb[1]); wb.y = cvt_pk_bf16(v[2] * zb[2], v[3] * zb[3]); wb.z = cvt_pk_bf16(v[4] * zb[4], v[5] * zb[5]); wb.w = cvt_pk_bf16(v[6] * zb[6], v[7] * zb[7]);
;                     *(u32x4*)(KTZ + (size_t)r * NT + t0) = wf;
;                     *(u32x4*)(KTZ + (size_t)(256 + r) * NT + t0) = wb;
;                     __builtin_amdgcn_sched_barrier(0);
	v_cndmask_b32_e64 v165, v157, -v157, vcc
	s_waitcnt vmcnt(0)
	v_pk_mul_f32 v[188:189], v[162:163], v[164:165]
	s_waitcnt lgkmcnt(2)
	v_cndmask_b32_e64 v165, v116, -v116, vcc
	v_mov_b32_e32 v162, v117
	v_pk_mul_f32 v[116:117], v[162:163], v[164:165]
	s_waitcnt lgkmcnt(1)
	v_cndmask_b32_e64 v165, v161, -v161, vcc
	v_mov_b32_e32 v162, v118
	v_add_f32_e32 v161, v116, v117
	v_pk_mul_f32 v[116:117], v[162:163], v[164:165]
	s_waitcnt lgkmcnt(0)
	v_cndmask_b32_e64 v165, v166, -v166, vcc
	v_mov_b32_e32 v162, v119
	v_add_f32_e32 v166, v116, v117
	v_pk_mul_f32 v[116:117], v[162:163], v[164:165]
	v_add_f32_e32 v157, v188, v189
	v_add_f32_e32 v164, v116, v117
	global_load_dword v117, v[122:123], off
	global_load_dword v118, v[124:125], off
	ds_bpermute_b32 v119, v177, v112
	v_mov_b32_e32 v116, v112
	ds_bpermute_b32 v112, v177, v113
	ds_bpermute_b32 v165, v177, v114
	ds_bpermute_b32 v188, v177, v115
	s_waitcnt lgkmcnt(3)
	v_cndmask_b32_e64 v119, v119, -v119, vcc
	s_waitcnt vmcnt(0)
	v_pk_mul_f32 v[162:163], v[116:117], v[118:119]
	s_waitcnt lgkmcnt(2)
	v_cndmask_b32_e64 v119, v112, -v112, vcc
	v_mov_b32_e32 v116, v113
	v_pk_mul_f32 v[112:113], v[116:117], v[118:119]
	s_waitcnt lgkmcnt(1)
	v_cndmask_b32_e64 v119, v165, -v165, vcc
	v_mov_b32_e32 v116, v114
	v_add_f32_e32 v162, v162, v163
	v_add_f32_e32 v163, v112, v113
	v_pk_mul_f32 v[112:113], v[116:117], v[118:119]
	s_waitcnt lgkmcnt(0)
	v_cndmask_b32_e64 v119, v188, -v188, vcc
	v_mov_b32_e32 v116, v115
	v_add_f32_e32 v165, v112, v113
	v_pk_mul_f32 v[112:113], v[116:117], v[118:119]
	s_nop 0
	v_add_f32_e32 v119, v112, v113
	v_mul_f32_e32 v112, v180, v157
	v_mul_f32_e32 v113, v181, v161
	v_cvt_pk_bf16_f32 v112, v112, v113
	v_mul_f32_e32 v113, v167, v166
	v_mul_f32_e32 v114, v183, v164
	v_cvt_pk_bf16_f32 v113, v113, v114
	v_mul_f32_e32 v114, v182, v162
	v_mul_f32_e32 v115, v185, v163
	v_cvt_pk_bf16_f32 v114, v114, v115
	v_mul_f32_e32 v115, v184, v165
	v_mul_f32_e32 v116, v159, v119
	v_cvt_pk_bf16_f32 v115, v115, v116
	v_mul_f32_e32 v116, v150, v157
	v_mul_f32_e32 v117, v152, v161
	v_cvt_pk_bf16_f32 v116, v116, v117
	v_mul_f32_e32 v117, v154, v166
	v_mul_f32_e32 v118, v156, v164
	v_cvt_pk_bf16_f32 v117, v117, v118
	v_mul_f32_e32 v118, v158, v162
	v_mul_f32_e32 v157, v160, v163
	v_mul_f32_e32 v119, v155, v119
	v_cvt_pk_bf16_f32 v118, v118, v157
	v_mul_f32_e32 v157, v151, v165
	v_cvt_pk_bf16_f32 v119, v157, v119
	global_store_dwordx4 v[120:121], v[112:115], off offset:256
	global_store_dwordx4 v[126:127], v[116:119], off offset:256
	v_add_u32_e32 v161, 0x408, v136
	v_add_u32_e32 v157, 8, v136
	v_add_u32_e32 v112, v161, v187
	v_add_u32_e32 v114, v187, v157
	v_ashrrev_i32_e32 v113, 31, v112
	v_ashrrev_i32_e32 v115, 31, v114
	v_lshl_add_u64 v[112:113], v[112:113], 2, s[16:17]
	v_lshl_add_u64 v[114:115], v[114:115], 2, s[16:17]
	global_load_dword v117, v[112:113], off
	global_load_dword v118, v[114:115], off
	ds_bpermute_b32 v119, v177, v108
	v_mov_b32_e32 v116, v108
	ds_bpermute_b32 v108, v177, v109
	ds_bpermute_b32 v162, v177, v110
	ds_bpermute_b32 v163, v177, v111
	s_waitcnt lgkmcnt(3)
	v_cndmask_b32_e64 v119, v119, -v119, vcc
	s_waitcnt vmcnt(0)
	v_pk_mul_f32 v[126:127], v[116:117], v[118:119]
	s_waitcnt lgkmcnt(2)
	v_cndmask_b32_e64 v119, v108, -v108, vcc
	v_mov_b32_e32 v116, v109
	v_pk_mul_f32 v[108:109], v[116:117], v[118:119]
	s_waitcnt lgkmcnt(1)
	v_cndmask_b32_e64 v119, v162, -v162, vcc
	v_mov_b32_e32 v116, v110
	v_add_f32_e32 v126, v126, v127
	v_add_f32_e32 v127, v108, v109
	v_pk_mul_f32 v[108:109], v[116:117], v[118:119]
	s_waitcnt lgkmcnt(0)
	v_cndmask_b32_e64 v119, v163, -v163, vcc
	v_mov_b32_e32 v116, v111
	v_add_f32_e32 v162, v108, v109
	v_pk_mul_f32 v[108:109], v[116:117], v[118:119]
	s_nop 0
	v_add_f32_e32 v118, v108, v109
	global_load_dword v109, v[112:113], off
	global_load_dword v110, v[114:115], off
	ds_bpermute_b32 v111, v177, v104
	v_mov_b32_e32 v108, v104
	ds_bpermute_b32 v104, v177, v105
	ds_bpermute_b32 v119, v177, v106
	ds_bpermute_b32 v163, v177, v107
	s_waitcnt lgkmcnt(3)
	v_cndmask_b32_e64 v111, v111, -v111, vcc
	s_waitcnt vmcnt(0)
	v_pk_mul_f32 v[116:117], v[108:109], v[110:111]
	s_waitcnt lgkmcnt(2)
	v_cndmask_b32_e64 v111, v104, -v104, vcc
	v_mov_b32_e32 v108, v105
	v_pk_mul_f32 v[104:105], v[108:109], v[110:111]
	s_waitcnt lgkmcnt(1)
	v_cndmask_b32_e64 v111, v119, -v119, vcc
	v_mov_b32_e32 v108, v106
	v_add_f32_e32 v119, v104, v105
	v_pk_mul_f32 v[104:105], v[108:109], v[110:111]
	s_waitcnt lgkmcnt(0)
	v_cndmask_b32_e64 v111, v163, -v163, vcc
	v_mov_b32_e32 v108, v107
	v_add_f32_e32 v163, v104, v105
	v_pk_mul_f32 v[104:105], v[108:109], v[110:111]
	v_add_f32_e32 v164, v116, v117
	v_add_f32_e32 v108, v104, v105
	v_mul_f32_e32 v104, v180, v126
	v_mul_f32_e32 v105, v181, v127
	v_cvt_pk_bf16_f32 v104, v104, v105
	v_mul_f32_e32 v105, v167, v162
	v_mul_f32_e32 v106, v183, v118
	v_cvt_pk_bf16_f32 v105, v105, v106
	v_mul_f32_e32 v106, v182, v164
	v_mul_f32_e32 v107, v185, v119
	v_cvt_pk_bf16_f32 v106, v106, v107
	v_mul_f32_e32 v107, v184, v163
	v_mul_f32_e32 v109, v159, v108
	v_cvt_pk_bf16_f32 v107, v107, v109
	v_mul_f32_e32 v109, v150, v126
	v_mul_f32_e32 v110, v152, v127
	v_cvt_pk_bf16_f32 v116, v109, v110
	v_mul_f32_e32 v109, v154, v162
	v_mul_f32_e32 v110, v156, v118
	v_cvt_pk_bf16_f32 v117, v109, v110
	v_mul_f32_e32 v109, v158, v164
	v_mul_f32_e32 v110, v160, v119
	v_cvt_pk_bf16_f32 v118, v109, v110
	v_mul_f32_e32 v109, v151, v163
	v_mul_f32_e32 v108, v155, v108
	s_mov_b64 s[0:1], 0x200000
	v_cvt_pk_bf16_f32 v119, v109, v108
	v_lshl_add_u64 v[108:109], v[120:121], 0, s[0:1]
	s_mov_b32 s0, 0x200000
	v_add_co_u32_e64 v110, s[4:5], s0, v120
	s_mov_b64 s[0:1], 0x2200000
	s_nop 0
	v_addc_co_u32_e64 v111, s[4:5], 0, v121, s[4:5]
	global_store_dwordx4 v[110:111], v[104:107], off
	v_lshl_add_u64 v[110:111], v[120:121], 0, s[0:1]
	s_mov_b32 s0, 0x2200000
	v_add_co_u32_e64 v104, s[4:5], s0, v120
	s_nop 1
	v_addc_co_u32_e64 v105, s[4:5], 0, v121, s[4:5]
	global_store_dwordx4 v[104:105], v[116:119], off
	v_add_u32_e32 v104, v153, v161
	v_add_u32_e32 v106, v153, v157
	v_ashrrev_i32_e32 v105, 31, v104
	v_ashrrev_i32_e32 v107, 31, v106
	v_lshl_add_u64 v[104:105], v[104:105], 2, s[16:17]
	v_lshl_add_u64 v[106:107], v[106:107], 2, s[16:17]
	global_load_dword v117, v[104:105], off
	global_load_dword v118, v[106:107], off
	ds_bpermute_b32 v119, v177, v100
	v_mov_b32_e32 v116, v100
	ds_bpermute_b32 v100, v177, v101
	ds_bpermute_b32 v153, v177, v102
	ds_bpermute_b32 v157, v177, v103
	s_waitcnt lgkmcnt(3)
;     __device__ __forceinline__ void operator()(const AccT& acc, const Unit& u, int wr, int wc, int fr, int fq) const {
;     ...
;             for (int m = 0; m < 4; ++m) {
;                 const int r = rbase + ai * 128 + m * 16;
;                 const int d = 4 * (2 * m + (fr >> 3)) + j;
; #pragma unroll
;                 for (int bj = 0; bj < 2; ++bj) {
;                     const int t0 = tb + bj * 128;
;                     float v[8];
; #pragma unroll
;                     for (int jj = 0; jj < 4; ++jj) { v[jj] = acc[ai][bj][m][0][jj]; v[4 + jj] = acc[ai][bj][m][1][jj]; }
;                     if constexpr (ROPE) {
;                         const int t = t0 & 2047;
; #pragma unroll
;                         for (int hf = 0; hf < 2; ++hf) {
;                             f32x4 cs, sn;
;                             if (m < 2) { const float c1 = ropeA[(t >> 6) * 16 + d], s1 = ropeA[1024 + (t >> 6) * 16 + d]; cs = (f32x4){c1, c1, c1, c1}; sn = (f32x4){s1, s1, s1, s1}; }
;                             else { const float* cb = ropeA + 2048 + (d - 16) * 64 + (t & 63) + 4 * hf; cs = *(const f32x4*)(cb); sn = *(const f32x4*)(cb + 1024); }
; #pragma unroll
;                             for (int jj = 0; jj < 4; ++jj) { const float pr = __shfl_xor(v[4 * hf + jj], 4); v[4 * hf + jj] = v[4 * hf + jj] * cs[jj] + sgn * pr * sn[jj]; }
;                             __builtin_amdgcn_sched_barrier(0);
;                         }
;                     }
;                     float zf[8], zb[8]; zf[0] = zf0; zb[0] = zb0;
; #pragma unroll
;                     for (int jj = 1; jj < 8; ++jj) { zf[jj] = zf[jj - 1] * zfs; zb[jj] = zb[jj - 1] * zbs; }
;                     u32x4 wf, wb;
;                     wf.x = cvt_pk_bf16(v[0] * zf[0], v[1] * zf[1]); wf.y = cvt_pk_bf16(v[2] * zf[2], v[3] * zf[3]); wf.z = cvt_pk_bf16(v[4] * zf[4], v[5] * zf[5]); wf.w = cvt_pk_bf16(v[6] * zf[6], v[7] * zf[7]);
;                     wb.x = cvt_pk_bf16(v[0] * zb[0], v[1] * zb[1]); wb.y = cvt_pk_bf16(v[2] * zb[2], v[3] * zb[3]); wb.z = cvt_pk_bf16(v[4] * zb[4], v[5] * zb[5]); wb.w = cvt_pk_bf16(v[6] * zb[6], v[7] * zb[7]);
;                     *(u32x4*)(KTZ + (size_t)r * NT + t0) = wf;
;                     *(u32x4*)(KTZ + (size_t)(256 + r) * NT + t0) = wb;
;                     __builtin_amdgcn_sched_barrier(0);
	v_cndmask_b32_e64 v119, v119, -v119, vcc
	s_waitcnt vmcnt(0)
	v_pk_mul_f32 v[126:127], v[116:117], v[118:119]
	s_waitcnt lgkmcnt(2)
	v_cndmask_b32_e64 v119, v100, -v100, vcc
	v_mov_b32_e32 v116, v101
	v_pk_mul_f32 v[100:101], v[116:117], v[118:119]
	s_waitcnt lgkmcnt(1)
	v_cndmask_b32_e64 v119, v153, -v153, vcc
	v_mov_b32_e32 v116, v102
	v_add_f32_e32 v126, v126, v127
	v_add_f32_e32 v127, v100, v101
	v_pk_mul_f32 v[100:101], v[116:117], v[118:119]
	s_waitcnt lgkmcnt(0)
	v_cndmask_b32_e64 v119, v157, -v157, vcc
	v_mov_b32_e32 v116, v103
	v_add_f32_e32 v153, v100, v101
	v_pk_mul_f32 v[100:101], v[116:117], v[118:119]
	s_nop 0
	v_add_f32_e32 v118, v100, v101
	global_load_dword v101, v[104:105], off
	global_load_dword v102, v[106:107], off
	ds_bpermute_b32 v103, v177, v96
	v_mov_b32_e32 v100, v96
	ds_bpermute_b32 v96, v177, v97
	ds_bpermute_b32 v119, v177, v98
	ds_bpermute_b32 v157, v177, v99
	s_waitcnt lgkmcnt(3)
	v_cndmask_b32_e64 v103, v103, -v103, vcc
	s_waitcnt vmcnt(0)
	v_pk_mul_f32 v[116:117], v[100:101], v[102:103]
	s_waitcnt lgkmcnt(2)
	v_cndmask_b32_e64 v103, v96, -v96, vcc
	v_mov_b32_e32 v100, v97
	v_pk_mul_f32 v[96:97], v[100:101], v[102:103]
	s_waitcnt lgkmcnt(1)
	v_cndmask_b32_e64 v103, v119, -v119, vcc
	v_mov_b32_e32 v100, v98
	v_add_f32_e32 v116, v116, v117
	v_add_f32_e32 v117, v96, v97
	v_pk_mul_f32 v[96:97], v[100:101], v[102:103]
	s_waitcnt lgkmcnt(0)
	v_cndmask_b32_e64 v103, v157, -v157, vcc
	v_mov_b32_e32 v100, v99
	v_add_f32_e32 v119, v96, v97
	v_pk_mul_f32 v[96:97], v[100:101], v[102:103]
	s_nop 0
	v_add_f32_e32 v103, v96, v97
	v_mul_f32_e32 v96, v180, v126
	v_mul_f32_e32 v97, v181, v127
	v_cvt_pk_bf16_f32 v96, v96, v97
	v_mul_f32_e32 v97, v167, v153
	v_mul_f32_e32 v98, v183, v118
	v_cvt_pk_bf16_f32 v97, v97, v98
	v_mul_f32_e32 v98, v182, v116
	v_mul_f32_e32 v99, v185, v117
	v_cvt_pk_bf16_f32 v98, v98, v99
	v_mul_f32_e32 v99, v184, v119
	v_mul_f32_e32 v100, v159, v103
	v_cvt_pk_bf16_f32 v99, v99, v100
	v_mul_f32_e32 v100, v150, v126
	v_mul_f32_e32 v101, v152, v127
	v_cvt_pk_bf16_f32 v100, v100, v101
	v_mul_f32_e32 v101, v154, v153
	v_mul_f32_e32 v102, v156, v118
	v_cvt_pk_bf16_f32 v101, v101, v102
	v_mul_f32_e32 v102, v158, v116
	v_mul_f32_e32 v116, v160, v117
	v_mul_f32_e32 v103, v155, v103
	v_cvt_pk_bf16_f32 v102, v102, v116
	v_mul_f32_e32 v116, v151, v119
	v_cvt_pk_bf16_f32 v103, v116, v103
	global_store_dwordx4 v[108:109], v[96:99], off offset:256
	global_store_dwordx4 v[110:111], v[100:103], off offset:256
	s_nop 1
	v_lshlrev_b32_e32 v100, 6, v136
	v_ashrrev_i32_e32 v101, 31, v100
	v_lshlrev_b64 v[102:103], 2, v[100:101]
	v_lshl_add_u64 v[96:97], s[24:25], 0, v[102:103]
	v_lshlrev_b32_e32 v136, 2, v186
	v_lshl_add_u64 v[96:97], v[96:97], 0, v[136:137]
	v_add_co_u32_e64 v98, s[4:5], s61, v96
	ds_bpermute_b32 v101, v177, v92
	s_nop 0
	v_addc_co_u32_e64 v99, s[4:5], 0, v97, s[4:5]
	global_load_dwordx4 v[108:111], v[98:99], off
	global_load_dwordx4 v[116:119], v[96:97], off
	ds_bpermute_b32 v127, v177, v93
	ds_bpermute_b32 v153, v177, v94
	ds_bpermute_b32 v157, v177, v95
	v_mov_b32_e32 v126, v92
	v_mov_b32_e32 v92, v94
	s_waitcnt lgkmcnt(3)
	v_cndmask_b32_e64 v163, v101, -v101, vcc
	s_waitcnt lgkmcnt(2)
	v_cndmask_b32_e64 v165, v127, -v127, vcc
	s_waitcnt lgkmcnt(1)
	v_cndmask_b32_e64 v187, v153, -v153, vcc
	s_waitcnt lgkmcnt(0)
	v_cndmask_b32_e64 v189, v157, -v157, vcc
	s_waitcnt vmcnt(1)
	v_mov_b32_e32 v127, v108
	s_waitcnt vmcnt(0)
	v_mov_b32_e32 v162, v116
	v_mov_b32_e32 v108, v93
	v_mov_b32_e32 v164, v117
	v_mov_b32_e32 v93, v110
	v_mov_b32_e32 v186, v118
	v_mov_b32_e32 v110, v95
	v_mov_b32_e32 v188, v119
	v_pk_mul_f32 v[94:95], v[126:127], v[162:163]
	v_pk_mul_f32 v[108:109], v[108:109], v[164:165]
	v_pk_mul_f32 v[92:93], v[92:93], v[186:187]
	v_pk_mul_f32 v[110:111], v[110:111], v[188:189]
	v_add_f32_e32 v101, v94, v95
	v_add_f32_e32 v153, v108, v109
	v_add_f32_e32 v157, v92, v93
	v_add_f32_e32 v161, v110, v111
	v_lshl_add_u64 v[92:93], s[16:17], 0, v[102:103]
	v_lshl_add_u64 v[94:95], v[92:93], 0, v[136:137]
	v_add_co_u32_e64 v92, s[4:5], s62, v94
	ds_bpermute_b32 v103, v177, v88
	s_nop 0
	v_addc_co_u32_e64 v93, s[4:5], 0, v95, s[4:5]
	v_add_co_u32_e64 v94, s[4:5], s49, v94
	ds_bpermute_b32 v126, v177, v89
	s_nop 0
	v_addc_co_u32_e64 v95, s[4:5], 0, v95, s[4:5]
	global_load_dwordx4 v[108:111], v[92:93], off offset:16
	global_load_dwordx4 v[116:119], v[94:95], off offset:16
	ds_bpermute_b32 v162, v177, v90
	ds_bpermute_b32 v164, v177, v91
	v_mov_b32_e32 v102, v88
	v_mov_b32_e32 v88, v90
	s_waitcnt lgkmcnt(3)
	v_cndmask_b32_e64 v127, v103, -v103, vcc
	s_waitcnt lgkmcnt(2)
	v_cndmask_b32_e64 v163, v126, -v126, vcc
	s_waitcnt lgkmcnt(1)
	v_cndmask_b32_e64 v165, v162, -v162, vcc
	s_waitcnt lgkmcnt(0)
	v_cndmask_b32_e64 v187, v164, -v164, vcc
	s_waitcnt vmcnt(1)
	v_mov_b32_e32 v103, v108
	s_waitcnt vmcnt(0)
;     __device__ __forceinline__ void operator()(const AccT& acc, const Unit& u, int wr, int wc, int fr, int fq) const {
;     ...
;             for (int m = 0; m < 4; ++m) {
;                 const int r = rbase + ai * 128 + m * 16;
;                 const int d = 4 * (2 * m + (fr >> 3)) + j;
; #pragma unroll
;                 for (int bj = 0; bj < 2; ++bj) {
;                     const int t0 = tb + bj * 128;
;                     float v[8];
; #pragma unroll
;                     for (int jj = 0; jj < 4; ++jj) { v[jj] = acc[ai][bj][m][0][jj]; v[4 + jj] = acc[ai][bj][m][1][jj]; }
;                     if constexpr (ROPE) {
;                         const int t = t0 & 2047;
; #pragma unroll
;                         for (int hf = 0; hf < 2; ++hf) {
;                             f32x4 cs, sn;
;                             if (m < 2) { const float c1 = ropeA[(t >> 6) * 16 + d], s1 = ropeA[1024 + (t >> 6) * 16 + d]; cs = (f32x4){c1, c1, c1, c1}; sn = (f32x4){s1, s1, s1, s1}; }
;                             else { const float* cb = ropeA + 2048 + (d - 16) * 64 + (t & 63) + 4 * hf; cs = *(const f32x4*)(cb); sn = *(const f32x4*)(cb + 1024); }
; #pragma unroll
;                             for (int jj = 0; jj < 4; ++jj) { const float pr = __shfl_xor(v[4 * hf + jj], 4); v[4 * hf + jj] = v[4 * hf + jj] * cs[jj] + sgn * pr * sn[jj]; }
;                             __builtin_amdgcn_sched_barrier(0);
;                         }
;                     }
;                     float zf[8], zb[8]; zf[0] = zf0; zb[0] = zb0;
; #pragma unroll
;                     for (int jj = 1; jj < 8; ++jj) { zf[jj] = zf[jj - 1] * zfs; zb[jj] = zb[jj - 1] * zbs; }
;                     u32x4 wf, wb;
;                     wf.x = cvt_pk_bf16(v[0] * zf[0], v[1] * zf[1]); wf.y = cvt_pk_bf16(v[2] * zf[2], v[3] * zf[3]); wf.z = cvt_pk_bf16(v[4] * zf[4], v[5] * zf[5]); wf.w = cvt_pk_bf16(v[6] * zf[6], v[7] * zf[7]);
;                     wb.x = cvt_pk_bf16(v[0] * zb[0], v[1] * zb[1]); wb.y = cvt_pk_bf16(v[2] * zb[2], v[3] * zb[3]); wb.z = cvt_pk_bf16(v[4] * zb[4], v[5] * zb[5]); wb.w = cvt_pk_bf16(v[6] * zb[6], v[7] * zb[7]);
;                     *(u32x4*)(KTZ + (size_t)r * NT + t0) = wf;
;                     *(u32x4*)(KTZ + (size_t)(256 + r) * NT + t0) = wb;
;                     __builtin_amdgcn_sched_barrier(0);
	v_mov_b32_e32 v126, v116
	v_mov_b32_e32 v108, v89
	v_mov_b32_e32 v162, v117
	v_mov_b32_e32 v89, v110
	v_mov_b32_e32 v164, v118
	v_mov_b32_e32 v110, v91
	v_mov_b32_e32 v186, v119
	v_pk_mul_f32 v[90:91], v[102:103], v[126:127]
	v_pk_mul_f32 v[102:103], v[108:109], v[162:163]
	v_pk_mul_f32 v[88:89], v[88:89], v[164:165]
	v_pk_mul_f32 v[108:109], v[110:111], v[186:187]
	v_add_f32_e32 v90, v90, v91
	v_add_f32_e32 v91, v102, v103
	v_add_f32_e32 v88, v88, v89
	v_add_f32_e32 v89, v108, v109
	v_mul_f32_e32 v102, v180, v101
	v_mul_f32_e32 v103, v181, v153
	v_cvt_pk_bf16_f32 v108, v102, v103
	v_mul_f32_e32 v102, v167, v157
	v_mul_f32_e32 v103, v183, v161
	v_cvt_pk_bf16_f32 v109, v102, v103
	v_mul_f32_e32 v102, v182, v90
	v_mul_f32_e32 v103, v185, v91
	v_cvt_pk_bf16_f32 v110, v102, v103
	v_mul_f32_e32 v102, v184, v88
	v_mul_f32_e32 v103, v159, v89
	v_cvt_pk_bf16_f32 v111, v102, v103
	v_mul_f32_e32 v101, v150, v101
	v_mul_f32_e32 v102, v152, v153
	v_mul_f32_e32 v88, v151, v88
	v_mul_f32_e32 v89, v155, v89
	s_mov_b64 s[0:1], 0x400000
	v_cvt_pk_bf16_f32 v116, v101, v102
	v_mul_f32_e32 v101, v154, v157
	v_mul_f32_e32 v102, v156, v161
	v_cvt_pk_bf16_f32 v117, v101, v102
	v_mul_f32_e32 v90, v158, v90
	v_mul_f32_e32 v91, v160, v91
	v_cvt_pk_bf16_f32 v118, v90, v91
	v_cvt_pk_bf16_f32 v119, v88, v89
	v_lshl_add_u64 v[88:89], v[120:121], 0, s[0:1]
	s_mov_b32 s0, 0x400000
	v_add_co_u32_e64 v90, s[4:5], s0, v120
	s_mov_b64 s[0:1], 0x2400000
	s_nop 0
	v_addc_co_u32_e64 v91, s[4:5], 0, v121, s[4:5]
	global_store_dwordx4 v[90:91], v[108:111], off
	v_lshl_add_u64 v[90:91], v[120:121], 0, s[0:1]
	s_mov_b32 s0, 0x2400000
	v_add_co_u32_e64 v102, s[4:5], s0, v120
	s_nop 1
	v_addc_co_u32_e64 v103, s[4:5], 0, v121, s[4:5]
	global_store_dwordx4 v[102:103], v[116:119], off
	global_load_dwordx4 v[108:111], v[98:99], off
	s_nop 0
	global_load_dwordx4 v[116:119], v[96:97], off
	ds_bpermute_b32 v101, v177, v84
	ds_bpermute_b32 v103, v177, v85
	ds_bpermute_b32 v126, v177, v86
	ds_bpermute_b32 v153, v177, v87
	v_mov_b32_e32 v102, v84
	v_mov_b32_e32 v84, v86
	s_waitcnt lgkmcnt(3)
	v_cndmask_b32_e64 v127, v101, -v101, vcc
	s_waitcnt lgkmcnt(2)
	v_cndmask_b32_e64 v163, v103, -v103, vcc
	s_waitcnt lgkmcnt(1)
	v_cndmask_b32_e64 v165, v126, -v126, vcc
	s_waitcnt lgkmcnt(0)
	v_cndmask_b32_e64 v187, v153, -v153, vcc
	s_waitcnt vmcnt(1)
	v_mov_b32_e32 v103, v108
	s_waitcnt vmcnt(0)
	v_mov_b32_e32 v126, v116
	v_mov_b32_e32 v108, v85
	v_mov_b32_e32 v162, v117
	v_mov_b32_e32 v85, v110
	v_mov_b32_e32 v164, v118
	v_mov_b32_e32 v110, v87
	v_mov_b32_e32 v186, v119
	v_pk_mul_f32 v[86:87], v[102:103], v[126:127]
	v_pk_mul_f32 v[102:103], v[108:109], v[162:163]
	v_pk_mul_f32 v[84:85], v[84:85], v[164:165]
	v_pk_mul_f32 v[108:109], v[110:111], v[186:187]
	v_add_f32_e32 v101, v86, v87
	v_add_f32_e32 v153, v102, v103
	v_add_f32_e32 v157, v84, v85
	v_add_f32_e32 v161, v108, v109
	global_load_dwordx4 v[84:87], v[92:93], off offset:16
	global_load_dwordx4 v[108:111], v[94:95], off offset:16
	ds_bpermute_b32 v103, v177, v80
	ds_bpermute_b32 v116, v177, v81
	ds_bpermute_b32 v118, v177, v82
	ds_bpermute_b32 v126, v177, v83
	v_mov_b32_e32 v102, v80
	v_mov_b32_e32 v80, v82
	s_waitcnt lgkmcnt(3)
	v_cndmask_b32_e64 v117, v103, -v103, vcc
	s_waitcnt lgkmcnt(2)
	v_cndmask_b32_e64 v119, v116, -v116, vcc
	s_waitcnt lgkmcnt(1)
	v_cndmask_b32_e64 v127, v118, -v118, vcc
	s_waitcnt lgkmcnt(0)
	v_cndmask_b32_e64 v163, v126, -v126, vcc
	s_waitcnt vmcnt(1)
	v_mov_b32_e32 v103, v84
	s_waitcnt vmcnt(0)
	v_mov_b32_e32 v116, v108
	v_mov_b32_e32 v84, v81
	v_mov_b32_e32 v118, v109
	v_mov_b32_e32 v81, v86
	v_mov_b32_e32 v126, v110
	v_mov_b32_e32 v86, v83
	v_mov_b32_e32 v162, v111
	v_pk_mul_f32 v[82:83], v[102:103], v[116:117]
	v_pk_mul_f32 v[84:85], v[84:85], v[118:119]
	v_pk_mul_f32 v[80:81], v[80:81], v[126:127]
	v_pk_mul_f32 v[86:87], v[86:87], v[162:163]
	v_add_f32_e32 v102, v82, v83
	v_add_f32_e32 v103, v84, v85
	v_add_f32_e32 v108, v80, v81
	v_add_f32_e32 v87, v86, v87
	v_mul_f32_e32 v80, v180, v101
	v_mul_f32_e32 v81, v181, v153
	v_cvt_pk_bf16_f32 v80, v80, v81
	v_mul_f32_e32 v81, v167, v157
	v_mul_f32_e32 v82, v183, v161
	v_cvt_pk_bf16_f32 v81, v81, v82
	v_mul_f32_e32 v82, v182, v102
	v_mul_f32_e32 v83, v185, v103
	v_cvt_pk_bf16_f32 v82, v82, v83
	v_mul_f32_e32 v83, v184, v108
	v_mul_f32_e32 v84, v159, v87
	v_cvt_pk_bf16_f32 v83, v83, v84
	v_mul_f32_e32 v84, v150, v101
	v_mul_f32_e32 v85, v152, v153
	v_cvt_pk_bf16_f32 v84, v84, v85
	v_mul_f32_e32 v85, v154, v157
	v_mul_f32_e32 v86, v156, v161
	v_cvt_pk_bf16_f32 v85, v85, v86
	v_mul_f32_e32 v86, v158, v102
	v_mul_f32_e32 v101, v160, v103
	v_mul_f32_e32 v87, v155, v87
	v_cvt_pk_bf16_f32 v86, v86, v101
	v_mul_f32_e32 v101, v151, v108
	v_cvt_pk_bf16_f32 v87, v101, v87
	global_store_dwordx4 v[88:89], v[80:83], off offset:256
	global_store_dwordx4 v[90:91], v[84:87], off offset:256
	s_nop 0
	v_add_u32_e32 v80, 0x200, v100
	v_ashrrev_i32_e32 v81, 31, v80
	v_lshl_add_u64 v[82:83], s[24:25], 0, v[136:137]
	v_lshlrev_b64 v[100:101], 2, v[80:81]
	v_lshl_add_u64 v[80:81], v[82:83], 0, v[100:101]
	v_add_co_u32_e64 v82, s[4:5], s61, v80
	ds_bpermute_b32 v103, v177, v76
	s_nop 0
	v_addc_co_u32_e64 v83, s[4:5], 0, v81, s[4:5]
	global_load_dwordx4 v[84:87], v[82:83], off
	global_load_dwordx4 v[88:91], v[80:81], off
	ds_bpermute_b32 v108, v177, v77
	ds_bpermute_b32 v110, v177, v78
	ds_bpermute_b32 v116, v177, v79
	v_mov_b32_e32 v102, v76
	v_mov_b32_e32 v76, v78
	s_waitcnt lgkmcnt(3)
	v_cndmask_b32_e64 v109, v103, -v103, vcc
	s_waitcnt lgkmcnt(2)
	v_cndmask_b32_e64 v111, v108, -v108, vcc
	s_waitcnt lgkmcnt(1)
	v_cndmask_b32_e64 v117, v110, -v110, vcc
	s_waitcnt lgkmcnt(0)
;     __device__ __forceinline__ void operator()(const AccT& acc, const Unit& u, int wr, int wc, int fr, int fq) const {
;     ...
;             for (int m = 0; m < 4; ++m) {
;                 const int r = rbase + ai * 128 + m * 16;
;                 const int d = 4 * (2 * m + (fr >> 3)) + j;
; #pragma unroll
;                 for (int bj = 0; bj < 2; ++bj) {
;                     const int t0 = tb + bj * 128;
;                     float v[8];
; #pragma unroll
;                     for (int jj = 0; jj < 4; ++jj) { v[jj] = acc[ai][bj][m][0][jj]; v[4 + jj] = acc[ai][bj][m][1][jj]; }
;                     if constexpr (ROPE) {
;                         const int t = t0 & 2047;
; #pragma unroll
;                         for (int hf = 0; hf < 2; ++hf) {
;                             f32x4 cs, sn;
;                             if (m < 2) { const float c1 = ropeA[(t >> 6) * 16 + d], s1 = ropeA[1024 + (t >> 6) * 16 + d]; cs = (f32x4){c1, c1, c1, c1}; sn = (f32x4){s1, s1, s1, s1}; }
;                             else { const float* cb = ropeA + 2048 + (d - 16) * 64 + (t & 63) + 4 * hf; cs = *(const f32x4*)(cb); sn = *(const f32x4*)(cb + 1024); }
; #pragma unroll
;                             for (int jj = 0; jj < 4; ++jj) { const float pr = __shfl_xor(v[4 * hf + jj], 4); v[4 * hf + jj] = v[4 * hf + jj] * cs[jj] + sgn * pr * sn[jj]; }
;                             __builtin_amdgcn_sched_barrier(0);
;                         }
;                     }
;                     float zf[8], zb[8]; zf[0] = zf0; zb[0] = zb0;
; #pragma unroll
;                     for (int jj = 1; jj < 8; ++jj) { zf[jj] = zf[jj - 1] * zfs; zb[jj] = zb[jj - 1] * zbs; }
;                     u32x4 wf, wb;
;                     wf.x = cvt_pk_bf16(v[0] * zf[0], v[1] * zf[1]); wf.y = cvt_pk_bf16(v[2] * zf[2], v[3] * zf[3]); wf.z = cvt_pk_bf16(v[4] * zf[4], v[5] * zf[5]); wf.w = cvt_pk_bf16(v[6] * zf[6], v[7] * zf[7]);
;                     wb.x = cvt_pk_bf16(v[0] * zb[0], v[1] * zb[1]); wb.y = cvt_pk_bf16(v[2] * zb[2], v[3] * zb[3]); wb.z = cvt_pk_bf16(v[4] * zb[4], v[5] * zb[5]); wb.w = cvt_pk_bf16(v[6] * zb[6], v[7] * zb[7]);
;                     *(u32x4*)(KTZ + (size_t)r * NT + t0) = wf;
;                     *(u32x4*)(KTZ + (size_t)(256 + r) * NT + t0) = wb;
;                     __builtin_amdgcn_sched_barrier(0);
	v_cndmask_b32_e64 v119, v116, -v116, vcc
	s_waitcnt vmcnt(1)
	v_mov_b32_e32 v103, v84
	s_waitcnt vmcnt(0)
	v_mov_b32_e32 v108, v88
	v_mov_b32_e32 v84, v77
	v_mov_b32_e32 v110, v89
	v_mov_b32_e32 v77, v86
	v_mov_b32_e32 v116, v90
	v_mov_b32_e32 v86, v79
	v_mov_b32_e32 v118, v91
	v_pk_mul_f32 v[78:79], v[102:103], v[108:109]
	v_pk_mul_f32 v[84:85], v[84:85], v[110:111]
	v_pk_mul_f32 v[76:77], v[76:77], v[116:117]
	v_pk_mul_f32 v[86:87], v[86:87], v[118:119]
	v_add_f32_e32 v118, v78, v79
	v_add_f32_e32 v119, v84, v85
	v_add_f32_e32 v126, v76, v77
	v_add_f32_e32 v127, v86, v87
	v_lshl_add_u64 v[76:77], s[16:17], 0, v[100:101]
	v_lshl_add_u64 v[78:79], v[76:77], 0, v[136:137]
	v_add_co_u32_e64 v76, s[4:5], s62, v78
	ds_bpermute_b32 v101, v177, v72
	s_nop 0
	v_addc_co_u32_e64 v77, s[4:5], 0, v79, s[4:5]
	v_add_co_u32_e64 v78, s[4:5], s49, v78
	ds_bpermute_b32 v102, v177, v73
	s_nop 0
	v_addc_co_u32_e64 v79, s[4:5], 0, v79, s[4:5]
	global_load_dwordx4 v[84:87], v[76:77], off offset:16
	global_load_dwordx4 v[88:91], v[78:79], off offset:16
	ds_bpermute_b32 v108, v177, v74
	ds_bpermute_b32 v110, v177, v75
	v_mov_b32_e32 v100, v72
	v_mov_b32_e32 v72, v74
	s_waitcnt lgkmcnt(3)
	v_cndmask_b32_e64 v103, v101, -v101, vcc
	s_waitcnt lgkmcnt(2)
	v_cndmask_b32_e64 v109, v102, -v102, vcc
	s_waitcnt lgkmcnt(1)
	v_cndmask_b32_e64 v111, v108, -v108, vcc
	s_waitcnt lgkmcnt(0)
	v_cndmask_b32_e64 v117, v110, -v110, vcc
	s_waitcnt vmcnt(1)
	v_mov_b32_e32 v101, v84
	s_waitcnt vmcnt(0)
	v_mov_b32_e32 v102, v88
	v_mov_b32_e32 v84, v73
	v_mov_b32_e32 v108, v89
	v_mov_b32_e32 v73, v86
	v_mov_b32_e32 v110, v90
	v_mov_b32_e32 v86, v75
	v_mov_b32_e32 v116, v91
	v_pk_mul_f32 v[74:75], v[100:101], v[102:103]
	v_pk_mul_f32 v[84:85], v[84:85], v[108:109]
	v_pk_mul_f32 v[72:73], v[72:73], v[110:111]
	v_pk_mul_f32 v[86:87], v[86:87], v[116:117]
	v_add_f32_e32 v74, v74, v75
	v_add_f32_e32 v75, v84, v85
	v_add_f32_e32 v72, v72, v73
	v_add_f32_e32 v73, v86, v87
	v_mul_f32_e32 v84, v180, v118
	v_mul_f32_e32 v85, v181, v119
	v_cvt_pk_bf16_f32 v84, v84, v85
	v_mul_f32_e32 v85, v167, v126
	v_mul_f32_e32 v86, v183, v127
	v_cvt_pk_bf16_f32 v85, v85, v86
	v_mul_f32_e32 v86, v182, v74
	v_mul_f32_e32 v87, v185, v75
	v_cvt_pk_bf16_f32 v86, v86, v87
	v_mul_f32_e32 v87, v184, v72
	v_mul_f32_e32 v88, v159, v73
	v_cvt_pk_bf16_f32 v87, v87, v88
	v_mul_f32_e32 v88, v150, v118
	v_mul_f32_e32 v89, v152, v119
	v_cvt_pk_bf16_f32 v88, v88, v89
	v_mul_f32_e32 v89, v154, v126
	v_mul_f32_e32 v90, v156, v127
	v_mul_f32_e32 v72, v151, v72
	v_mul_f32_e32 v73, v155, v73
	s_mov_b64 s[0:1], 0x600000
	v_cvt_pk_bf16_f32 v89, v89, v90
	v_mul_f32_e32 v74, v158, v74
	v_mul_f32_e32 v75, v160, v75
	v_cvt_pk_bf16_f32 v90, v74, v75
	v_cvt_pk_bf16_f32 v91, v72, v73
	v_lshl_add_u64 v[72:73], v[120:121], 0, s[0:1]
	s_mov_b32 s0, 0x600000
	v_add_co_u32_e64 v74, s[4:5], s0, v120
	s_mov_b64 s[0:1], 0x2600000
	s_nop 0
	v_addc_co_u32_e64 v75, s[4:5], 0, v121, s[4:5]
	global_store_dwordx4 v[74:75], v[84:87], off
	v_lshl_add_u64 v[74:75], v[120:121], 0, s[0:1]
	s_mov_b32 s0, 0x2600000
	v_add_co_u32_e64 v84, s[4:5], s0, v120
	s_nop 1
	v_addc_co_u32_e64 v85, s[4:5], 0, v121, s[4:5]
	global_store_dwordx4 v[84:85], v[88:91], off
	global_load_dwordx4 v[84:87], v[82:83], off
	s_nop 0
	global_load_dwordx4 v[88:91], v[80:81], off
	ds_bpermute_b32 v101, v177, v68
	ds_bpermute_b32 v102, v177, v69
	ds_bpermute_b32 v108, v177, v70
	ds_bpermute_b32 v110, v177, v71
	v_mov_b32_e32 v100, v68
	v_mov_b32_e32 v68, v70
	s_waitcnt lgkmcnt(3)
	v_cndmask_b32_e64 v103, v101, -v101, vcc
	s_waitcnt lgkmcnt(2)
	v_cndmask_b32_e64 v109, v102, -v102, vcc
	s_waitcnt lgkmcnt(1)
	v_cndmask_b32_e64 v111, v108, -v108, vcc
	s_waitcnt lgkmcnt(0)
	v_cndmask_b32_e64 v117, v110, -v110, vcc
	s_waitcnt vmcnt(1)
	v_mov_b32_e32 v101, v84
	s_waitcnt vmcnt(0)
	v_mov_b32_e32 v102, v88
	v_mov_b32_e32 v84, v69
	v_mov_b32_e32 v108, v89
	v_mov_b32_e32 v69, v86
	v_mov_b32_e32 v110, v90
	v_mov_b32_e32 v86, v71
	v_mov_b32_e32 v116, v91
	v_pk_mul_f32 v[70:71], v[100:101], v[102:103]
	v_pk_mul_f32 v[84:85], v[84:85], v[108:109]
	v_pk_mul_f32 v[68:69], v[68:69], v[110:111]
	v_pk_mul_f32 v[86:87], v[86:87], v[116:117]
	v_add_f32_e32 v110, v70, v71
	v_add_f32_e32 v111, v84, v85
	v_add_f32_e32 v116, v68, v69
	v_add_f32_e32 v117, v86, v87
	global_load_dwordx4 v[68:71], v[76:77], off offset:16
	global_load_dwordx4 v[84:87], v[78:79], off offset:16
	ds_bpermute_b32 v89, v177, v64
	ds_bpermute_b32 v90, v177, v65
	ds_bpermute_b32 v100, v177, v66
	ds_bpermute_b32 v102, v177, v67
	v_mov_b32_e32 v88, v64
	v_mov_b32_e32 v64, v66
	s_waitcnt lgkmcnt(3)
	v_cndmask_b32_e64 v91, v89, -v89, vcc
	s_waitcnt lgkmcnt(2)
	v_cndmask_b32_e64 v101, v90, -v90, vcc
	s_waitcnt lgkmcnt(1)
	v_cndmask_b32_e64 v103, v100, -v100, vcc
	s_waitcnt lgkmcnt(0)
	v_cndmask_b32_e64 v109, v102, -v102, vcc
	s_waitcnt vmcnt(1)
	v_mov_b32_e32 v89, v68
	s_waitcnt vmcnt(0)
;     __device__ __forceinline__ void operator()(const AccT& acc, const Unit& u, int wr, int wc, int fr, int fq) const {
;     ...
;         for (int ai = 0; ai < 2; ++ai) {
;             const int hh = 2 * ai + wr;
;             const float l2f = lgd[hh] * 1.4426950408889634f, l2b = lgd[4 + hh] * 1.4426950408889634f;
;             const float zf0 = exp2f((float)(127 - o0) * l2f), zfs = exp2f(-l2f), zb0 = exp2f((float)o0 * l2b), zbs = exp2f(l2b);
; #pragma unroll
;             for (int m = 0; m < 4; ++m) {
;                 const int r = rbase + ai * 128 + m * 16;
;                 const int d = 4 * (2 * m + (fr >> 3)) + j;
; #pragma unroll
;                 for (int bj = 0; bj < 2; ++bj) {
;                     const int t0 = tb + bj * 128;
;                     float v[8];
; #pragma unroll
;                     for (int jj = 0; jj < 4; ++jj) { v[jj] = acc[ai][bj][m][0][jj]; v[4 + jj] = acc[ai][bj][m][1][jj]; }
;                     if constexpr (ROPE) {
;                         const int t = t0 & 2047;
; #pragma unroll
;                         for (int hf = 0; hf < 2; ++hf) {
;                             f32x4 cs, sn;
;                             if (m < 2) { const float c1 = ropeA[(t >> 6) * 16 + d], s1 = ropeA[1024 + (t >> 6) * 16 + d]; cs = (f32x4){c1, c1, c1, c1}; sn = (f32x4){s1, s1, s1, s1}; }
;                             else { const float* cb = ropeA + 2048 + (d - 16) * 64 + (t & 63) + 4 * hf; cs = *(const f32x4*)(cb); sn = *(const f32x4*)(cb + 1024); }
; #pragma unroll
;                             for (int jj = 0; jj < 4; ++jj) { const float pr = __shfl_xor(v[4 * hf + jj], 4); v[4 * hf + jj] = v[4 * hf + jj] * cs[jj] + sgn * pr * sn[jj]; }
;                             __builtin_amdgcn_sched_barrier(0);
;                         }
;                     }
;                     float zf[8], zb[8]; zf[0] = zf0; zb[0] = zb0;
; #pragma unroll
;                     for (int jj = 1; jj < 8; ++jj) { zf[jj] = zf[jj - 1] * zfs; zb[jj] = zb[jj - 1] * zbs; }
;                     u32x4 wf, wb;
;                     wf.x = cvt_pk_bf16(v[0] * zf[0], v[1] * zf[1]); wf.y = cvt_pk_bf16(v[2] * zf[2], v[3] * zf[3]); wf.z = cvt_pk_bf16(v[4] * zf[4], v[5] * zf[5]); wf.w = cvt_pk_bf16(v[6] * zf[6], v[7] * zf[7]);
	v_mov_b32_e32 v90, v84
	v_mov_b32_e32 v68, v65
	v_mov_b32_e32 v100, v85
	v_mov_b32_e32 v65, v70
	v_mov_b32_e32 v102, v86
	v_mov_b32_e32 v70, v67
	v_mov_b32_e32 v108, v87
	v_pk_mul_f32 v[66:67], v[88:89], v[90:91]
	v_pk_mul_f32 v[68:69], v[68:69], v[100:101]
	v_pk_mul_f32 v[64:65], v[64:65], v[102:103]
	v_pk_mul_f32 v[70:71], v[70:71], v[108:109]
	v_add_f32_e32 v84, v66, v67
	v_add_f32_e32 v85, v68, v69
	v_add_f32_e32 v86, v64, v65
	v_add_f32_e32 v71, v70, v71
	v_mul_f32_e32 v64, v180, v110
	v_mul_f32_e32 v65, v181, v111
	v_cvt_pk_bf16_f32 v64, v64, v65
	v_mul_f32_e32 v65, v167, v116
	v_mul_f32_e32 v66, v183, v117
	v_cvt_pk_bf16_f32 v65, v65, v66
	v_mul_f32_e32 v66, v182, v84
	v_mul_f32_e32 v67, v185, v85
	v_cvt_pk_bf16_f32 v66, v66, v67
	v_mul_f32_e32 v67, v184, v86
	v_mul_f32_e32 v68, v159, v71
	v_cvt_pk_bf16_f32 v67, v67, v68
	v_mul_f32_e32 v68, v150, v110
	v_mul_f32_e32 v69, v152, v111
	v_cvt_pk_bf16_f32 v68, v68, v69
	v_mul_f32_e32 v69, v154, v116
	v_mul_f32_e32 v70, v156, v117
	v_cvt_pk_bf16_f32 v69, v69, v70
	v_mul_f32_e32 v70, v158, v84
	v_mul_f32_e32 v84, v160, v85
	v_mul_f32_e32 v71, v155, v71
	v_cvt_pk_bf16_f32 v70, v70, v84
	v_mul_f32_e32 v84, v151, v86
	v_cvt_pk_bf16_f32 v71, v84, v71
	global_store_dwordx4 v[72:73], v[64:67], off offset:256
	global_store_dwordx4 v[74:75], v[68:71], off offset:256
	global_load_dword v64, v137, s[22:23] offset:8
	s_nop 0
	global_load_dword v70, v137, s[22:23] offset:24
	global_load_dword v67, v[146:147], off
	global_load_dword v74, v[148:149], off
	ds_bpermute_b32 v65, v177, v60
	ds_bpermute_b32 v68, v177, v62
	v_mov_b32_e32 v66, v60
	ds_bpermute_b32 v60, v177, v61
	ds_bpermute_b32 v71, v177, v63
	s_waitcnt lgkmcnt(3)
	v_cndmask_b32_e64 v75, v65, -v65, vcc
	s_waitcnt lgkmcnt(2)
	v_cndmask_b32_e64 v65, v68, -v68, vcc
	s_waitcnt vmcnt(3)
	v_mul_f32_e32 v72, 0x3fb8aa3b, v64
	s_waitcnt vmcnt(2)
	v_mul_f32_e32 v73, 0x3fb8aa3b, v70
	v_mul_f32_e32 v84, v72, v179
	s_waitcnt vmcnt(0)
	v_pk_mul_f32 v[68:69], v[66:67], v[74:75]
	s_waitcnt lgkmcnt(1)
	v_cndmask_b32_e64 v75, v60, -v60, vcc
	v_mov_b32_e32 v66, v61
	v_cmp_lt_f32_e64 s[4:5], s60, v72
	v_mul_f32_e32 v87, v73, v178
	v_pk_mul_f32 v[60:61], v[66:67], v[74:75]
	s_waitcnt lgkmcnt(0)
	v_cndmask_b32_e64 v75, v71, -v71, vcc
	v_mov_b32_e32 v66, v63
	v_cmp_gt_f32_e64 s[8:9], s59, v84
	v_cndmask_b32_e64 v86, 0, v176, s[4:5]
	v_cmp_gt_f32_e64 s[6:7], s59, v73
	s_and_b64 s[0:1], s[4:5], exec
	v_cmp_gt_f32_e64 s[4:5], s59, v87
	v_add_f32_e32 v110, v60, v61
	v_pk_mul_f32 v[60:61], v[66:67], v[74:75]
	v_cndmask_b32_e64 v66, 0, v176, s[8:9]
	v_cndmask_b32_e64 v88, 0, v176, s[6:7]
	v_add_f32_e32 v89, v68, v69
	v_fmac_f32_e32 v86, 0xbfb8aa3b, v64
	v_cndmask_b32_e64 v69, 0, v176, s[4:5]
	v_fmac_f32_e32 v66, v72, v179
	v_fmac_f32_e32 v88, 0x3fb8aa3b, v70
	v_exp_f32_e32 v68, v86
	v_fmac_f32_e32 v69, v73, v178
	v_exp_f32_e32 v66, v66
	v_exp_f32_e32 v70, v88
	v_exp_f32_e32 v69, v69
	v_cndmask_b32_e64 v63, 0, v175, s[8:9]
	s_cselect_b32 s8, 0xffffffc0, 0
	s_and_b64 s[0:1], s[6:7], exec
	v_cndmask_b32_e64 v64, 0, v175, s[4:5]
	s_cselect_b32 s0, 0xffffffc0, 0
	v_ldexp_f32 v100, v68, s8
	v_ldexp_f32 v63, v66, v63
	v_mul_f32_e32 v85, v62, v74
	v_ldexp_f32 v90, v70, s0
	v_ldexp_f32 v64, v69, v64
	v_mul_f32_e32 v75, v100, v63
	v_add_f32_e32 v111, v60, v61
	global_load_dword v108, v[148:149], off
	global_load_dword v69, v[146:147], off
	ds_bpermute_b32 v61, v177, v57
	ds_bpermute_b32 v60, v177, v56
	v_mov_b32_e32 v68, v57
	ds_bpermute_b32 v57, v177, v59
	ds_bpermute_b32 v66, v177, v58
	s_waitcnt lgkmcnt(3)
	v_cndmask_b32_e64 v109, v61, -v61, vcc
	s_waitcnt lgkmcnt(2)
	v_cndmask_b32_e64 v70, v60, -v60, vcc
	s_waitcnt lgkmcnt(0)
	v_cndmask_b32_e64 v72, v66, -v66, vcc
	s_waitcnt vmcnt(1)
	v_mul_f32_e32 v71, v56, v108
	s_waitcnt vmcnt(0)
	v_pk_mul_f32 v[60:61], v[68:69], v[108:109]
	v_cndmask_b32_e64 v109, v57, -v57, vcc
	v_mov_b32_e32 v68, v59
	v_add_f32_e32 v57, v60, v61
	v_pk_mul_f32 v[60:61], v[68:69], v[108:109]
	s_nop 0
	v_add_f32_e32 v59, v60, v61
	v_mov_b32_e32 v91, v67
	v_pk_mul_f32 v[60:61], v[90:91], v[64:65]
	v_mov_b32_e32 v91, v85
	v_pk_mul_f32 v[66:67], v[90:91], v[60:61]
	v_mov_b32_e32 v91, v69
	v_mov_b32_e32 v67, v70
	v_mul_f32_e32 v84, v100, v75
	v_pk_mul_f32 v[68:69], v[90:91], v[66:67]
	v_mov_b32_e32 v70, v90
	v_mul_f32_e32 v86, v100, v84
	v_pk_mul_f32 v[70:71], v[70:71], v[68:69]
	v_mul_f32_e32 v85, v100, v86
	v_mov_b32_e32 v71, v72
	v_mul_f32_e32 v88, v100, v85
	v_pk_mul_f32 v[72:73], v[90:91], v[70:71]
	v_fma_f32 v61, v62, v74, v61
	v_mul_f32_e32 v87, v100, v88
	v_mul_f32_e32 v65, v90, v72
	v_mul_f32_e32 v62, v84, v61
	v_fma_f32 v56, v56, v108, v69
	v_mul_f32_e32 v71, v100, v87
	v_mul_f32_e32 v67, v90, v65
	v_mul_f32_e32 v90, v63, v89
	v_mul_f32_e32 v91, v75, v110
	v_cvt_pk_bf16_f32 v100, v90, v91
	v_mul_f32_e32 v74, v86, v111
	v_cvt_pk_bf16_f32 v101, v62, v74
	v_mul_f32_e32 v62, v85, v56
	v_fma_f32 v58, v58, v108, v73
	v_mul_f32_e32 v69, v88, v57
	v_cvt_pk_bf16_f32 v102, v62, v69
	v_mul_f32_e32 v62, v87, v58
	v_mul_f32_e32 v69, v71, v59
	v_cvt_pk_bf16_f32 v103, v62, v69
	v_mul_f32_e32 v62, v64, v89
	v_mul_f32_e32 v56, v70, v56
	v_mul_f32_e32 v57, v72, v57
	v_mul_f32_e32 v69, v60, v110
	v_cvt_pk_bf16_f32 v108, v62, v69
	v_mul_f32_e32 v61, v66, v61
	v_mul_f32_e32 v62, v68, v111
	v_cvt_pk_bf16_f32 v109, v61, v62
	v_cvt_pk_bf16_f32 v110, v56, v57
	v_mul_f32_e32 v56, v65, v58
	v_mul_f32_e32 v57, v67, v59
	s_mov_b64 s[0:1], 0x1000000
	v_cvt_pk_bf16_f32 v111, v56, v57
	v_lshl_add_u64 v[56:57], v[120:121], 0, s[0:1]
	s_mov_b32 s0, 0x1000000
	v_add_co_u32_e64 v58, s[4:5], s0, v120
	s_mov_b64 s[0:1], 0x3000000
	s_nop 0
	v_addc_co_u32_e64 v59, s[4:5], 0, v121, s[4:5]
	global_store_dwordx4 v[58:59], v[100:103], off
	v_lshl_add_u64 v[58:59], v[120:121], 0, s[0:1]
	s_mov_b32 s0, 0x3000000
	v_add_co_u32_e64 v90, s[4:5], s0, v120
	s_nop 1
	v_addc_co_u32_e64 v91, s[4:5], 0, v121, s[4:5]
	global_store_dwordx4 v[90:91], v[108:111], off
	global_load_dword v91, v[122:123], off
	s_nop 0
	global_load_dword v100, v[124:125], off
	ds_bpermute_b32 v61, v177, v52
	v_mov_b32_e32 v90, v52
	ds_bpermute_b32 v52, v177, v53
	ds_bpermute_b32 v62, v177, v54
	ds_bpermute_b32 v69, v177, v55
	s_waitcnt lgkmcnt(3)
;     __device__ __forceinline__ void operator()(const AccT& acc, const Unit& u, int wr, int wc, int fr, int fq) const {
;     ...
;             for (int m = 0; m < 4; ++m) {
;                 const int r = rbase + ai * 128 + m * 16;
;                 const int d = 4 * (2 * m + (fr >> 3)) + j;
; #pragma unroll
;                 for (int bj = 0; bj < 2; ++bj) {
;                     const int t0 = tb + bj * 128;
;                     float v[8];
; #pragma unroll
;                     for (int jj = 0; jj < 4; ++jj) { v[jj] = acc[ai][bj][m][0][jj]; v[4 + jj] = acc[ai][bj][m][1][jj]; }
;                     if constexpr (ROPE) {
;                         const int t = t0 & 2047;
; #pragma unroll
;                         for (int hf = 0; hf < 2; ++hf) {
;                             f32x4 cs, sn;
;                             if (m < 2) { const float c1 = ropeA[(t >> 6) * 16 + d], s1 = ropeA[1024 + (t >> 6) * 16 + d]; cs = (f32x4){c1, c1, c1, c1}; sn = (f32x4){s1, s1, s1, s1}; }
;                             else { const float* cb = ropeA + 2048 + (d - 16) * 64 + (t & 63) + 4 * hf; cs = *(const f32x4*)(cb); sn = *(const f32x4*)(cb + 1024); }
; #pragma unroll
;                             for (int jj = 0; jj < 4; ++jj) { const float pr = __shfl_xor(v[4 * hf + jj], 4); v[4 * hf + jj] = v[4 * hf + jj] * cs[jj] + sgn * pr * sn[jj]; }
;                             __builtin_amdgcn_sched_barrier(0);
;                         }
;                     }
;                     float zf[8], zb[8]; zf[0] = zf0; zb[0] = zb0;
; #pragma unroll
;                     for (int jj = 1; jj < 8; ++jj) { zf[jj] = zf[jj - 1] * zfs; zb[jj] = zb[jj - 1] * zbs; }
;                     u32x4 wf, wb;
;                     wf.x = cvt_pk_bf16(v[0] * zf[0], v[1] * zf[1]); wf.y = cvt_pk_bf16(v[2] * zf[2], v[3] * zf[3]); wf.z = cvt_pk_bf16(v[4] * zf[4], v[5] * zf[5]); wf.w = cvt_pk_bf16(v[6] * zf[6], v[7] * zf[7]);
;                     wb.x = cvt_pk_bf16(v[0] * zb[0], v[1] * zb[1]); wb.y = cvt_pk_bf16(v[2] * zb[2], v[3] * zb[3]); wb.z = cvt_pk_bf16(v[4] * zb[4], v[5] * zb[5]); wb.w = cvt_pk_bf16(v[6] * zb[6], v[7] * zb[7]);
;                     *(u32x4*)(KTZ + (size_t)r * NT + t0) = wf;
;                     *(u32x4*)(KTZ + (size_t)(256 + r) * NT + t0) = wb;
;                     __builtin_amdgcn_sched_barrier(0);
	v_cndmask_b32_e64 v101, v61, -v61, vcc
	s_waitcnt vmcnt(0)
	v_pk_mul_f32 v[102:103], v[90:91], v[100:101]
	s_waitcnt lgkmcnt(2)
	v_cndmask_b32_e64 v101, v52, -v52, vcc
	v_mov_b32_e32 v90, v53
	v_pk_mul_f32 v[52:53], v[90:91], v[100:101]
	s_waitcnt lgkmcnt(1)
	v_cndmask_b32_e64 v101, v62, -v62, vcc
	v_mov_b32_e32 v90, v54
	v_add_f32_e32 v62, v52, v53
	v_pk_mul_f32 v[52:53], v[90:91], v[100:101]
	s_waitcnt lgkmcnt(0)
	v_cndmask_b32_e64 v101, v69, -v69, vcc
	v_mov_b32_e32 v90, v55
	v_add_f32_e32 v69, v52, v53
	v_pk_mul_f32 v[52:53], v[90:91], v[100:101]
	v_add_f32_e32 v61, v102, v103
	v_add_f32_e32 v73, v52, v53
	global_load_dword v53, v[122:123], off
	global_load_dword v54, v[124:125], off
	ds_bpermute_b32 v55, v177, v48
	v_mov_b32_e32 v52, v48
	ds_bpermute_b32 v48, v177, v49
	ds_bpermute_b32 v74, v177, v50
	ds_bpermute_b32 v89, v177, v51
	s_waitcnt lgkmcnt(3)
	v_cndmask_b32_e64 v55, v55, -v55, vcc
	s_waitcnt vmcnt(0)
	v_pk_mul_f32 v[90:91], v[52:53], v[54:55]
	s_waitcnt lgkmcnt(2)
	v_cndmask_b32_e64 v55, v48, -v48, vcc
	v_mov_b32_e32 v52, v49
	v_pk_mul_f32 v[48:49], v[52:53], v[54:55]
	s_waitcnt lgkmcnt(1)
	v_cndmask_b32_e64 v55, v74, -v74, vcc
	v_mov_b32_e32 v52, v50
	v_add_f32_e32 v74, v48, v49
	v_pk_mul_f32 v[48:49], v[52:53], v[54:55]
	s_waitcnt lgkmcnt(0)
	v_cndmask_b32_e64 v55, v89, -v89, vcc
	v_mov_b32_e32 v52, v51
	v_add_f32_e32 v89, v48, v49
	v_pk_mul_f32 v[48:49], v[52:53], v[54:55]
	v_add_f32_e32 v90, v90, v91
	v_add_f32_e32 v55, v48, v49
	v_mul_f32_e32 v48, v63, v61
	v_mul_f32_e32 v49, v75, v62
	v_cvt_pk_bf16_f32 v48, v48, v49
	v_mul_f32_e32 v49, v84, v69
	v_mul_f32_e32 v50, v86, v73
	v_cvt_pk_bf16_f32 v49, v49, v50
	v_mul_f32_e32 v50, v85, v90
	v_mul_f32_e32 v51, v88, v74
	v_cvt_pk_bf16_f32 v50, v50, v51
	v_mul_f32_e32 v51, v87, v89
	v_mul_f32_e32 v52, v71, v55
	v_cvt_pk_bf16_f32 v51, v51, v52
	v_mul_f32_e32 v52, v64, v61
	v_mul_f32_e32 v53, v60, v62
	v_cvt_pk_bf16_f32 v52, v52, v53
	v_mul_f32_e32 v53, v66, v69
	v_mul_f32_e32 v54, v68, v73
	v_cvt_pk_bf16_f32 v53, v53, v54
	v_mul_f32_e32 v54, v70, v90
	v_mul_f32_e32 v61, v72, v74
	v_mul_f32_e32 v55, v67, v55
	v_cvt_pk_bf16_f32 v54, v54, v61
	v_mul_f32_e32 v61, v65, v89
	v_cvt_pk_bf16_f32 v55, v61, v55
	global_store_dwordx4 v[56:57], v[48:51], off offset:256
	global_store_dwordx4 v[58:59], v[52:55], off offset:256
	global_load_dword v49, v[112:113], off
	s_nop 0
	global_load_dword v50, v[114:115], off
	ds_bpermute_b32 v51, v177, v44
	v_mov_b32_e32 v48, v44
	ds_bpermute_b32 v44, v177, v45
	ds_bpermute_b32 v54, v177, v46
	ds_bpermute_b32 v55, v177, v47
	s_waitcnt lgkmcnt(3)
	v_cndmask_b32_e64 v51, v51, -v51, vcc
	s_waitcnt vmcnt(0)
	v_pk_mul_f32 v[52:53], v[48:49], v[50:51]
	s_waitcnt lgkmcnt(2)
	v_cndmask_b32_e64 v51, v44, -v44, vcc
	v_mov_b32_e32 v48, v45
	v_pk_mul_f32 v[44:45], v[48:49], v[50:51]
	s_waitcnt lgkmcnt(1)
	v_cndmask_b32_e64 v51, v54, -v54, vcc
	v_mov_b32_e32 v48, v46
	v_add_f32_e32 v52, v52, v53
	v_add_f32_e32 v53, v44, v45
	v_pk_mul_f32 v[44:45], v[48:49], v[50:51]
	s_waitcnt lgkmcnt(0)
	v_cndmask_b32_e64 v51, v55, -v55, vcc
	v_mov_b32_e32 v48, v47
	v_add_f32_e32 v54, v44, v45
	v_pk_mul_f32 v[44:45], v[48:49], v[50:51]
	s_nop 0
	v_add_f32_e32 v50, v44, v45
	global_load_dword v45, v[112:113], off
	global_load_dword v46, v[114:115], off
	ds_bpermute_b32 v47, v177, v40
	v_mov_b32_e32 v44, v40
	ds_bpermute_b32 v40, v177, v41
	ds_bpermute_b32 v51, v177, v42
	ds_bpermute_b32 v55, v177, v43
	s_waitcnt lgkmcnt(3)
	v_cndmask_b32_e64 v47, v47, -v47, vcc
	s_waitcnt vmcnt(0)
	v_pk_mul_f32 v[48:49], v[44:45], v[46:47]
	s_waitcnt lgkmcnt(2)
	v_cndmask_b32_e64 v47, v40, -v40, vcc
	v_mov_b32_e32 v44, v41
	v_pk_mul_f32 v[40:41], v[44:45], v[46:47]
	s_waitcnt lgkmcnt(1)
	v_cndmask_b32_e64 v47, v51, -v51, vcc
	v_mov_b32_e32 v44, v42
	v_add_f32_e32 v48, v48, v49
	v_add_f32_e32 v49, v40, v41
	v_pk_mul_f32 v[40:41], v[44:45], v[46:47]
	s_waitcnt lgkmcnt(0)
	v_cndmask_b32_e64 v47, v55, -v55, vcc
	v_mov_b32_e32 v44, v43
	v_add_f32_e32 v51, v40, v41
	v_pk_mul_f32 v[40:41], v[44:45], v[46:47]
	s_nop 0
	v_add_f32_e32 v40, v40, v41
	v_mul_f32_e32 v41, v63, v52
	v_mul_f32_e32 v42, v75, v53
	v_cvt_pk_bf16_f32 v42, v41, v42
	v_mul_f32_e32 v41, v84, v54
	v_mul_f32_e32 v43, v86, v50
	v_cvt_pk_bf16_f32 v43, v41, v43
	v_mul_f32_e32 v41, v85, v48
	v_mul_f32_e32 v44, v88, v49
	v_cvt_pk_bf16_f32 v44, v41, v44
	v_mul_f32_e32 v41, v87, v51
	v_mul_f32_e32 v45, v71, v40
	v_cvt_pk_bf16_f32 v45, v41, v45
	v_mul_f32_e32 v41, v64, v52
	v_mul_f32_e32 v46, v60, v53
	v_cvt_pk_bf16_f32 v46, v41, v46
	v_mul_f32_e32 v41, v66, v54
	v_mul_f32_e32 v47, v68, v50
	v_cvt_pk_bf16_f32 v47, v41, v47
	v_mul_f32_e32 v41, v70, v48
	v_mul_f32_e32 v48, v72, v49
	v_cvt_pk_bf16_f32 v48, v41, v48
	v_mul_f32_e32 v41, v65, v51
	v_mul_f32_e32 v40, v67, v40
	s_mov_b64 s[0:1], 0x1200000
	v_cvt_pk_bf16_f32 v49, v41, v40
	v_lshl_add_u64 v[40:41], v[120:121], 0, s[0:1]
	s_mov_b32 s0, 0x1200000
	v_add_co_u32_e64 v50, s[4:5], s0, v120
	s_mov_b64 s[0:1], 0x3200000
	s_nop 0
	v_addc_co_u32_e64 v51, s[4:5], 0, v121, s[4:5]
	global_store_dwordx4 v[50:51], v[42:45], off
	s_nop 1
	v_lshl_add_u64 v[42:43], v[120:121], 0, s[0:1]
	s_mov_b32 s0, 0x3200000
	v_add_co_u32_e64 v44, s[4:5], s0, v120
	s_nop 1
	v_addc_co_u32_e64 v45, s[4:5], 0, v121, s[4:5]
	global_store_dwordx4 v[44:45], v[46:49], off
	global_load_dword v45, v[104:105], off
	s_nop 0
	global_load_dword v46, v[106:107], off
	ds_bpermute_b32 v47, v177, v36
	v_mov_b32_e32 v44, v36
	ds_bpermute_b32 v36, v177, v37
	ds_bpermute_b32 v50, v177, v38
	ds_bpermute_b32 v51, v177, v39
	s_waitcnt lgkmcnt(3)
	v_cndmask_b32_e64 v47, v47, -v47, vcc
	s_waitcnt vmcnt(0)
	v_pk_mul_f32 v[48:49], v[44:45], v[46:47]
	s_waitcnt lgkmcnt(2)
;     __device__ __forceinline__ void operator()(const AccT& acc, const Unit& u, int wr, int wc, int fr, int fq) const {
;     ...
;             for (int m = 0; m < 4; ++m) {
;                 const int r = rbase + ai * 128 + m * 16;
;                 const int d = 4 * (2 * m + (fr >> 3)) + j;
; #pragma unroll
;                 for (int bj = 0; bj < 2; ++bj) {
;                     const int t0 = tb + bj * 128;
;                     float v[8];
; #pragma unroll
;                     for (int jj = 0; jj < 4; ++jj) { v[jj] = acc[ai][bj][m][0][jj]; v[4 + jj] = acc[ai][bj][m][1][jj]; }
;                     if constexpr (ROPE) {
;                         const int t = t0 & 2047;
; #pragma unroll
;                         for (int hf = 0; hf < 2; ++hf) {
;                             f32x4 cs, sn;
;                             if (m < 2) { const float c1 = ropeA[(t >> 6) * 16 + d], s1 = ropeA[1024 + (t >> 6) * 16 + d]; cs = (f32x4){c1, c1, c1, c1}; sn = (f32x4){s1, s1, s1, s1}; }
;                             else { const float* cb = ropeA + 2048 + (d - 16) * 64 + (t & 63) + 4 * hf; cs = *(const f32x4*)(cb); sn = *(const f32x4*)(cb + 1024); }
; #pragma unroll
;                             for (int jj = 0; jj < 4; ++jj) { const float pr = __shfl_xor(v[4 * hf + jj], 4); v[4 * hf + jj] = v[4 * hf + jj] * cs[jj] + sgn * pr * sn[jj]; }
;                             __builtin_amdgcn_sched_barrier(0);
;                         }
;                     }
;                     float zf[8], zb[8]; zf[0] = zf0; zb[0] = zb0;
; #pragma unroll
;                     for (int jj = 1; jj < 8; ++jj) { zf[jj] = zf[jj - 1] * zfs; zb[jj] = zb[jj - 1] * zbs; }
;                     u32x4 wf, wb;
;                     wf.x = cvt_pk_bf16(v[0] * zf[0], v[1] * zf[1]); wf.y = cvt_pk_bf16(v[2] * zf[2], v[3] * zf[3]); wf.z = cvt_pk_bf16(v[4] * zf[4], v[5] * zf[5]); wf.w = cvt_pk_bf16(v[6] * zf[6], v[7] * zf[7]);
;                     wb.x = cvt_pk_bf16(v[0] * zb[0], v[1] * zb[1]); wb.y = cvt_pk_bf16(v[2] * zb[2], v[3] * zb[3]); wb.z = cvt_pk_bf16(v[4] * zb[4], v[5] * zb[5]); wb.w = cvt_pk_bf16(v[6] * zb[6], v[7] * zb[7]);
;                     *(u32x4*)(KTZ + (size_t)r * NT + t0) = wf;
;                     *(u32x4*)(KTZ + (size_t)(256 + r) * NT + t0) = wb;
;                     __builtin_amdgcn_sched_barrier(0);
	v_cndmask_b32_e64 v47, v36, -v36, vcc
	v_mov_b32_e32 v44, v37
	v_pk_mul_f32 v[36:37], v[44:45], v[46:47]
	s_waitcnt lgkmcnt(1)
	v_cndmask_b32_e64 v47, v50, -v50, vcc
	v_mov_b32_e32 v44, v38
	v_add_f32_e32 v48, v48, v49
	v_add_f32_e32 v49, v36, v37
	v_pk_mul_f32 v[36:37], v[44:45], v[46:47]
	s_waitcnt lgkmcnt(0)
	v_cndmask_b32_e64 v47, v51, -v51, vcc
	v_mov_b32_e32 v44, v39
	v_add_f32_e32 v50, v36, v37
	v_pk_mul_f32 v[36:37], v[44:45], v[46:47]
	s_nop 0
	v_add_f32_e32 v46, v36, v37
	global_load_dword v37, v[104:105], off
	global_load_dword v38, v[106:107], off
	ds_bpermute_b32 v39, v177, v32
	v_mov_b32_e32 v36, v32
	ds_bpermute_b32 v32, v177, v33
	ds_bpermute_b32 v47, v177, v34
	ds_bpermute_b32 v51, v177, v35
	s_waitcnt lgkmcnt(3)
	v_cndmask_b32_e64 v39, v39, -v39, vcc
	s_waitcnt vmcnt(0)
	v_pk_mul_f32 v[44:45], v[36:37], v[38:39]
	s_waitcnt lgkmcnt(2)
	v_cndmask_b32_e64 v39, v32, -v32, vcc
	v_mov_b32_e32 v36, v33
	v_pk_mul_f32 v[32:33], v[36:37], v[38:39]
	s_waitcnt lgkmcnt(1)
	v_cndmask_b32_e64 v39, v47, -v47, vcc
	v_mov_b32_e32 v36, v34
	v_add_f32_e32 v44, v44, v45
	v_add_f32_e32 v45, v32, v33
	v_pk_mul_f32 v[32:33], v[36:37], v[38:39]
	s_waitcnt lgkmcnt(0)
	v_cndmask_b32_e64 v39, v51, -v51, vcc
	v_mov_b32_e32 v36, v35
	v_add_f32_e32 v47, v32, v33
	v_pk_mul_f32 v[32:33], v[36:37], v[38:39]
	s_nop 0
	v_add_f32_e32 v39, v32, v33
	v_mul_f32_e32 v32, v63, v48
	v_mul_f32_e32 v33, v75, v49
	v_cvt_pk_bf16_f32 v32, v32, v33
	v_mul_f32_e32 v33, v84, v50
	v_mul_f32_e32 v34, v86, v46
	v_cvt_pk_bf16_f32 v33, v33, v34
	v_mul_f32_e32 v34, v85, v44
	v_mul_f32_e32 v35, v88, v45
	v_cvt_pk_bf16_f32 v34, v34, v35
	v_mul_f32_e32 v35, v87, v47
	v_mul_f32_e32 v36, v71, v39
	v_cvt_pk_bf16_f32 v35, v35, v36
	v_mul_f32_e32 v36, v64, v48
	v_mul_f32_e32 v37, v60, v49
	v_cvt_pk_bf16_f32 v36, v36, v37
	v_mul_f32_e32 v37, v66, v50
	v_mul_f32_e32 v38, v68, v46
	v_cvt_pk_bf16_f32 v37, v37, v38
	v_mul_f32_e32 v38, v70, v44
	v_mul_f32_e32 v44, v72, v45
	v_mul_f32_e32 v39, v67, v39
	v_cvt_pk_bf16_f32 v38, v38, v44
	v_mul_f32_e32 v44, v65, v47
	v_cvt_pk_bf16_f32 v39, v44, v39
	global_store_dwordx4 v[40:41], v[32:35], off offset:256
	global_store_dwordx4 v[42:43], v[36:39], off offset:256
	global_load_dwordx4 v[32:35], v[98:99], off
	s_nop 0
	global_load_dwordx4 v[36:39], v[96:97], off
	ds_bpermute_b32 v41, v177, v28
	ds_bpermute_b32 v42, v177, v29
	ds_bpermute_b32 v44, v177, v30
	ds_bpermute_b32 v46, v177, v31
	v_mov_b32_e32 v40, v28
	v_mov_b32_e32 v28, v30
	s_waitcnt lgkmcnt(3)
	v_cndmask_b32_e64 v43, v41, -v41, vcc
	s_waitcnt lgkmcnt(2)
	v_cndmask_b32_e64 v45, v42, -v42, vcc
	s_waitcnt lgkmcnt(1)
	v_cndmask_b32_e64 v47, v44, -v44, vcc
	s_waitcnt lgkmcnt(0)
	v_cndmask_b32_e64 v49, v46, -v46, vcc
	s_waitcnt vmcnt(1)
	v_mov_b32_e32 v41, v32
	s_waitcnt vmcnt(0)
	v_mov_b32_e32 v42, v36
	v_mov_b32_e32 v32, v29
	v_mov_b32_e32 v44, v37
	v_mov_b32_e32 v29, v34
	v_mov_b32_e32 v46, v38
	v_mov_b32_e32 v34, v31
	v_mov_b32_e32 v48, v39
	v_pk_mul_f32 v[30:31], v[40:41], v[42:43]
	v_pk_mul_f32 v[32:33], v[32:33], v[44:45]
	v_pk_mul_f32 v[28:29], v[28:29], v[46:47]
	v_pk_mul_f32 v[34:35], v[34:35], v[48:49]
	v_add_f32_e32 v46, v30, v31
	v_add_f32_e32 v47, v32, v33
	v_add_f32_e32 v48, v28, v29
	v_add_f32_e32 v49, v34, v35
	global_load_dwordx4 v[28:31], v[92:93], off offset:16
	global_load_dwordx4 v[32:35], v[94:95], off offset:16
	ds_bpermute_b32 v37, v177, v24
	ds_bpermute_b32 v38, v177, v25
	ds_bpermute_b32 v40, v177, v26
	ds_bpermute_b32 v42, v177, v27
	v_mov_b32_e32 v36, v24
	v_mov_b32_e32 v24, v26
	s_waitcnt lgkmcnt(3)
	v_cndmask_b32_e64 v39, v37, -v37, vcc
	s_waitcnt lgkmcnt(2)
	v_cndmask_b32_e64 v41, v38, -v38, vcc
	s_waitcnt lgkmcnt(1)
	v_cndmask_b32_e64 v43, v40, -v40, vcc
	s_waitcnt lgkmcnt(0)
	v_cndmask_b32_e64 v45, v42, -v42, vcc
	s_waitcnt vmcnt(1)
	v_mov_b32_e32 v37, v28
	s_waitcnt vmcnt(0)
	v_mov_b32_e32 v38, v32
	v_mov_b32_e32 v28, v25
	v_mov_b32_e32 v40, v33
	v_mov_b32_e32 v25, v30
	v_mov_b32_e32 v42, v34
	v_mov_b32_e32 v30, v27
	v_mov_b32_e32 v44, v35
	v_pk_mul_f32 v[26:27], v[36:37], v[38:39]
	v_pk_mul_f32 v[28:29], v[28:29], v[40:41]
	v_pk_mul_f32 v[24:25], v[24:25], v[42:43]
	v_pk_mul_f32 v[30:31], v[30:31], v[44:45]
	v_add_f32_e32 v32, v26, v27
	v_add_f32_e32 v33, v28, v29
	v_add_f32_e32 v24, v24, v25
	v_add_f32_e32 v25, v30, v31
	v_mul_f32_e32 v26, v63, v46
	v_mul_f32_e32 v27, v75, v47
	v_cvt_pk_bf16_f32 v26, v26, v27
	v_mul_f32_e32 v27, v84, v48
	v_mul_f32_e32 v28, v86, v49
	v_cvt_pk_bf16_f32 v27, v27, v28
	v_mul_f32_e32 v28, v85, v32
	v_mul_f32_e32 v29, v88, v33
	v_cvt_pk_bf16_f32 v28, v28, v29
	v_mul_f32_e32 v29, v87, v24
	v_mul_f32_e32 v30, v71, v25
	v_cvt_pk_bf16_f32 v29, v29, v30
	v_mul_f32_e32 v30, v64, v46
	v_mul_f32_e32 v31, v60, v47
	v_cvt_pk_bf16_f32 v30, v30, v31
	v_mul_f32_e32 v31, v66, v48
	v_mul_f32_e32 v32, v70, v32
	v_mul_f32_e32 v33, v72, v33
	v_mul_f32_e32 v24, v65, v24
	v_mul_f32_e32 v25, v67, v25
	s_mov_b64 s[0:1], 0x1400000
	v_mul_f32_e32 v34, v68, v49
	v_cvt_pk_bf16_f32 v31, v31, v34
	v_cvt_pk_bf16_f32 v32, v32, v33
	v_cvt_pk_bf16_f32 v33, v24, v25
	v_lshl_add_u64 v[24:25], v[120:121], 0, s[0:1]
	s_mov_b32 s0, 0x1400000
	v_add_co_u32_e64 v34, s[4:5], s0, v120
	s_mov_b64 s[0:1], 0x3400000
	s_nop 0
	v_addc_co_u32_e64 v35, s[4:5], 0, v121, s[4:5]
	global_store_dwordx4 v[34:35], v[26:29], off
	s_nop 1
	v_lshl_add_u64 v[26:27], v[120:121], 0, s[0:1]
	s_mov_b32 s0, 0x3400000
	v_add_co_u32_e64 v28, s[4:5], s0, v120
	s_nop 1
	v_addc_co_u32_e64 v29, s[4:5], 0, v121, s[4:5]
	global_store_dwordx4 v[28:29], v[30:33], off
	global_load_dwordx4 v[28:31], v[98:99], off
	s_nop 0
	global_load_dwordx4 v[32:35], v[96:97], off
	ds_bpermute_b32 v37, v177, v20
	ds_bpermute_b32 v38, v177, v21
	ds_bpermute_b32 v40, v177, v22
	ds_bpermute_b32 v42, v177, v23
	v_mov_b32_e32 v36, v20
	v_mov_b32_e32 v20, v22
	s_waitcnt lgkmcnt(3)
;     __device__ __forceinline__ void operator()(const AccT& acc, const Unit& u, int wr, int wc, int fr, int fq) const {
;     ...
;             for (int m = 0; m < 4; ++m) {
;                 const int r = rbase + ai * 128 + m * 16;
;                 const int d = 4 * (2 * m + (fr >> 3)) + j;
; #pragma unroll
;                 for (int bj = 0; bj < 2; ++bj) {
;                     const int t0 = tb + bj * 128;
;                     float v[8];
; #pragma unroll
;                     for (int jj = 0; jj < 4; ++jj) { v[jj] = acc[ai][bj][m][0][jj]; v[4 + jj] = acc[ai][bj][m][1][jj]; }
;                     if constexpr (ROPE) {
;                         const int t = t0 & 2047;
; #pragma unroll
;                         for (int hf = 0; hf < 2; ++hf) {
;                             f32x4 cs, sn;
;                             if (m < 2) { const float c1 = ropeA[(t >> 6) * 16 + d], s1 = ropeA[1024 + (t >> 6) * 16 + d]; cs = (f32x4){c1, c1, c1, c1}; sn = (f32x4){s1, s1, s1, s1}; }
;                             else { const float* cb = ropeA + 2048 + (d - 16) * 64 + (t & 63) + 4 * hf; cs = *(const f32x4*)(cb); sn = *(const f32x4*)(cb + 1024); }
; #pragma unroll
;                             for (int jj = 0; jj < 4; ++jj) { const float pr = __shfl_xor(v[4 * hf + jj], 4); v[4 * hf + jj] = v[4 * hf + jj] * cs[jj] + sgn * pr * sn[jj]; }
;                             __builtin_amdgcn_sched_barrier(0);
;                         }
;                     }
;                     float zf[8], zb[8]; zf[0] = zf0; zb[0] = zb0;
; #pragma unroll
;                     for (int jj = 1; jj < 8; ++jj) { zf[jj] = zf[jj - 1] * zfs; zb[jj] = zb[jj - 1] * zbs; }
;                     u32x4 wf, wb;
;                     wf.x = cvt_pk_bf16(v[0] * zf[0], v[1] * zf[1]); wf.y = cvt_pk_bf16(v[2] * zf[2], v[3] * zf[3]); wf.z = cvt_pk_bf16(v[4] * zf[4], v[5] * zf[5]); wf.w = cvt_pk_bf16(v[6] * zf[6], v[7] * zf[7]);
;                     wb.x = cvt_pk_bf16(v[0] * zb[0], v[1] * zb[1]); wb.y = cvt_pk_bf16(v[2] * zb[2], v[3] * zb[3]); wb.z = cvt_pk_bf16(v[4] * zb[4], v[5] * zb[5]); wb.w = cvt_pk_bf16(v[6] * zb[6], v[7] * zb[7]);
;                     *(u32x4*)(KTZ + (size_t)r * NT + t0) = wf;
;                     *(u32x4*)(KTZ + (size_t)(256 + r) * NT + t0) = wb;
;                     __builtin_amdgcn_sched_barrier(0);
	v_cndmask_b32_e64 v39, v37, -v37, vcc
	s_waitcnt lgkmcnt(2)
	v_cndmask_b32_e64 v41, v38, -v38, vcc
	s_waitcnt lgkmcnt(1)
	v_cndmask_b32_e64 v43, v40, -v40, vcc
	s_waitcnt lgkmcnt(0)
	v_cndmask_b32_e64 v45, v42, -v42, vcc
	s_waitcnt vmcnt(1)
	v_mov_b32_e32 v37, v28
	s_waitcnt vmcnt(0)
	v_mov_b32_e32 v38, v32
	v_mov_b32_e32 v28, v21
	v_mov_b32_e32 v40, v33
	v_mov_b32_e32 v21, v30
	v_mov_b32_e32 v42, v34
	v_mov_b32_e32 v30, v23
	v_mov_b32_e32 v44, v35
	v_pk_mul_f32 v[22:23], v[36:37], v[38:39]
	v_pk_mul_f32 v[28:29], v[28:29], v[40:41]
	v_pk_mul_f32 v[20:21], v[20:21], v[42:43]
	v_pk_mul_f32 v[30:31], v[30:31], v[44:45]
	v_add_f32_e32 v42, v22, v23
	v_add_f32_e32 v43, v28, v29
	v_add_f32_e32 v44, v20, v21
	v_add_f32_e32 v45, v30, v31
	global_load_dwordx4 v[20:23], v[92:93], off offset:16
	global_load_dwordx4 v[28:31], v[94:95], off offset:16
	ds_bpermute_b32 v33, v177, v16
	ds_bpermute_b32 v34, v177, v17
	ds_bpermute_b32 v36, v177, v18
	ds_bpermute_b32 v38, v177, v19
	v_mov_b32_e32 v32, v16
	v_mov_b32_e32 v16, v18
	s_waitcnt lgkmcnt(3)
	v_cndmask_b32_e64 v35, v33, -v33, vcc
	s_waitcnt lgkmcnt(2)
	v_cndmask_b32_e64 v37, v34, -v34, vcc
	s_waitcnt lgkmcnt(1)
	v_cndmask_b32_e64 v39, v36, -v36, vcc
	s_waitcnt lgkmcnt(0)
	v_cndmask_b32_e64 v41, v38, -v38, vcc
	s_waitcnt vmcnt(1)
	v_mov_b32_e32 v33, v20
	s_waitcnt vmcnt(0)
	v_mov_b32_e32 v34, v28
	v_mov_b32_e32 v20, v17
	v_mov_b32_e32 v36, v29
	v_mov_b32_e32 v17, v22
	v_mov_b32_e32 v38, v30
	v_mov_b32_e32 v22, v19
	v_mov_b32_e32 v40, v31
	v_pk_mul_f32 v[18:19], v[32:33], v[34:35]
	v_pk_mul_f32 v[20:21], v[20:21], v[36:37]
	v_pk_mul_f32 v[16:17], v[16:17], v[38:39]
	v_pk_mul_f32 v[22:23], v[22:23], v[40:41]
	v_add_f32_e32 v28, v18, v19
	v_add_f32_e32 v29, v20, v21
	v_add_f32_e32 v30, v16, v17
	v_add_f32_e32 v23, v22, v23
	v_mul_f32_e32 v16, v63, v42
	v_mul_f32_e32 v17, v75, v43
	v_cvt_pk_bf16_f32 v16, v16, v17
	v_mul_f32_e32 v17, v84, v44
	v_mul_f32_e32 v18, v86, v45
	v_cvt_pk_bf16_f32 v17, v17, v18
	v_mul_f32_e32 v18, v85, v28
	v_mul_f32_e32 v19, v88, v29
	v_cvt_pk_bf16_f32 v18, v18, v19
	v_mul_f32_e32 v19, v87, v30
	v_mul_f32_e32 v20, v71, v23
	v_cvt_pk_bf16_f32 v19, v19, v20
	v_mul_f32_e32 v20, v64, v42
	v_mul_f32_e32 v21, v60, v43
	v_cvt_pk_bf16_f32 v20, v20, v21
	v_mul_f32_e32 v21, v66, v44
	v_mul_f32_e32 v22, v68, v45
	v_cvt_pk_bf16_f32 v21, v21, v22
	v_mul_f32_e32 v22, v70, v28
	v_mul_f32_e32 v28, v72, v29
	v_mul_f32_e32 v23, v67, v23
	v_cvt_pk_bf16_f32 v22, v22, v28
	v_mul_f32_e32 v28, v65, v30
	v_cvt_pk_bf16_f32 v23, v28, v23
	global_store_dwordx4 v[24:25], v[16:19], off offset:256
	global_store_dwordx4 v[26:27], v[20:23], off offset:256
	global_load_dwordx4 v[16:19], v[82:83], off
	s_nop 0
	global_load_dwordx4 v[20:23], v[80:81], off
	ds_bpermute_b32 v25, v177, v12
	ds_bpermute_b32 v26, v177, v13
	ds_bpermute_b32 v28, v177, v14
	ds_bpermute_b32 v30, v177, v15
	v_mov_b32_e32 v24, v12
	v_mov_b32_e32 v12, v14
	s_waitcnt lgkmcnt(3)
	v_cndmask_b32_e64 v27, v25, -v25, vcc
	s_waitcnt lgkmcnt(2)
	v_cndmask_b32_e64 v29, v26, -v26, vcc
	s_waitcnt lgkmcnt(1)
	v_cndmask_b32_e64 v31, v28, -v28, vcc
	s_waitcnt lgkmcnt(0)
	v_cndmask_b32_e64 v33, v30, -v30, vcc
	s_waitcnt vmcnt(1)
	v_mov_b32_e32 v25, v16
	s_waitcnt vmcnt(0)
	v_mov_b32_e32 v26, v20
	v_mov_b32_e32 v16, v13
	v_mov_b32_e32 v28, v21
	v_mov_b32_e32 v13, v18
	v_mov_b32_e32 v30, v22
	v_mov_b32_e32 v18, v15
	v_mov_b32_e32 v32, v23
	v_pk_mul_f32 v[14:15], v[24:25], v[26:27]
	v_pk_mul_f32 v[16:17], v[16:17], v[28:29]
	v_pk_mul_f32 v[12:13], v[12:13], v[30:31]
	v_pk_mul_f32 v[18:19], v[18:19], v[32:33]
	v_add_f32_e32 v30, v14, v15
	v_add_f32_e32 v31, v16, v17
	v_add_f32_e32 v32, v12, v13
	v_add_f32_e32 v33, v18, v19
	global_load_dwordx4 v[12:15], v[76:77], off offset:16
	global_load_dwordx4 v[16:19], v[78:79], off offset:16
	ds_bpermute_b32 v21, v177, v8
	ds_bpermute_b32 v22, v177, v9
	ds_bpermute_b32 v24, v177, v10
	ds_bpermute_b32 v26, v177, v11
	v_mov_b32_e32 v20, v8
	v_mov_b32_e32 v8, v10
	s_waitcnt lgkmcnt(3)
	v_cndmask_b32_e64 v23, v21, -v21, vcc
	s_waitcnt lgkmcnt(2)
	v_cndmask_b32_e64 v25, v22, -v22, vcc
	s_waitcnt lgkmcnt(1)
	v_cndmask_b32_e64 v27, v24, -v24, vcc
	s_waitcnt lgkmcnt(0)
	v_cndmask_b32_e64 v29, v26, -v26, vcc
	s_waitcnt vmcnt(1)
	v_mov_b32_e32 v21, v12
	s_waitcnt vmcnt(0)
; __device__ __forceinline__ unsigned cvt_pk_bf16(float lo, float hi) { unsigned r; asm volatile("v_cvt_pk_bf16_f32 %0, %1, %2" : "=v"(r) : "v"(lo), "v"(hi)); return r; }
; #define PG8_WAIT_V(n) asm volatile("s_waitcnt vmcnt(" #n ")" ::: "memory")
; #define PG8_BAR __builtin_amdgcn_s_barrier()
; template <class Epi, class Sched>
; __device__ __forceinline__ void gemm_phase(LAS unsigned char* lds, const Gemm g, const Sched& S, const Epi& E) {
;     ...
;         if (!has_next) break;
; #pragma unroll
;         for (int a = 0; a < 2; ++a)
; #pragma unroll
;             for (int b = 0; b < 2; ++b)
; #pragma unroll
;                 for (int m = 0; m < 4; ++m)
; #pragma unroll
;                     for (int n = 0; n < 2; ++n) acc[a][b][m][n] = (f32x4){0.f, 0.f, 0.f, 0.f};
;         cur = nxt; cA = nA; cB = nB; ++ui;
;     }
;     PG8_WAIT_V(0);
;     if (wr == 0) PG8_BAR;
;     PG8_BAR;
;     __device__ __forceinline__ void operator()(const AccT& acc, const Unit& u, int wr, int wc, int fr, int fq) const {
;     ...
;                     float zf[8], zb[8]; zf[0] = zf0; zb[0] = zb0;
; #pragma unroll
;                     for (int jj = 1; jj < 8; ++jj) { zf[jj] = zf[jj - 1] * zfs; zb[jj] = zb[jj - 1] * zbs; }
;                     u32x4 wf, wb;
;                     wf.x = cvt_pk_bf16(v[0] * zf[0], v[1] * zf[1]); wf.y = cvt_pk_bf16(v[2] * zf[2], v[3] * zf[3]); wf.z = cvt_pk_bf16(v[4] * zf[4], v[5] * zf[5]); wf.w = cvt_pk_bf16(v[6] * zf[6], v[7] * zf[7]);
;                     wb.x = cvt_pk_bf16(v[0] * zb[0], v[1] * zb[1]); wb.y = cvt_pk_bf16(v[2] * zb[2], v[3] * zb[3]); wb.z = cvt_pk_bf16(v[4] * zb[4], v[5] * zb[5]); wb.w = cvt_pk_bf16(v[6] * zb[6], v[7] * zb[7]);
;                     *(u32x4*)(KTZ + (size_t)r * NT + t0) = wf;
;                     *(u32x4*)(KTZ + (size_t)(256 + r) * NT + t0) = wb;
;                     __builtin_amdgcn_sched_barrier(0);
;                 }
;             }
;         }
;     }
	v_mov_b32_e32 v22, v16
	v_mov_b32_e32 v12, v9
	v_mov_b32_e32 v24, v17
	v_mov_b32_e32 v9, v14
	v_mov_b32_e32 v26, v18
	v_mov_b32_e32 v14, v11
	v_mov_b32_e32 v28, v19
	v_pk_mul_f32 v[10:11], v[20:21], v[22:23]
	v_pk_mul_f32 v[12:13], v[12:13], v[24:25]
	v_pk_mul_f32 v[8:9], v[8:9], v[26:27]
	v_pk_mul_f32 v[14:15], v[14:15], v[28:29]
	v_add_f32_e32 v16, v10, v11
	v_add_f32_e32 v17, v12, v13
	v_add_f32_e32 v8, v8, v9
	v_add_f32_e32 v9, v14, v15
	v_mul_f32_e32 v10, v63, v30
	v_mul_f32_e32 v11, v75, v31
	v_cvt_pk_bf16_f32 v10, v10, v11
	v_mul_f32_e32 v11, v84, v32
	v_mul_f32_e32 v12, v86, v33
	v_cvt_pk_bf16_f32 v11, v11, v12
	v_mul_f32_e32 v12, v85, v16
	v_mul_f32_e32 v13, v88, v17
	v_cvt_pk_bf16_f32 v12, v12, v13
	v_mul_f32_e32 v13, v87, v8
	v_mul_f32_e32 v14, v71, v9
	v_cvt_pk_bf16_f32 v13, v13, v14
	v_mul_f32_e32 v14, v64, v30
	v_mul_f32_e32 v15, v60, v31
	v_cvt_pk_bf16_f32 v14, v14, v15
	v_mul_f32_e32 v15, v66, v32
	v_mul_f32_e32 v18, v68, v33
	v_cvt_pk_bf16_f32 v15, v15, v18
	v_add_co_u32_e64 v18, s[4:5], s63, v120
	v_mul_f32_e32 v16, v70, v16
	v_mul_f32_e32 v17, v72, v17
	v_addc_co_u32_e64 v19, s[4:5], 0, v121, s[4:5]
	v_cvt_pk_bf16_f32 v16, v16, v17
	v_mul_f32_e32 v8, v65, v8
	v_mul_f32_e32 v9, v67, v9
	v_cvt_pk_bf16_f32 v17, v8, v9
	global_store_dwordx4 v[18:19], v[10:13], off
	v_lshl_add_u64 v[8:9], v[120:121], 0, s[26:27]
	s_nop 0
	v_add_co_u32_e64 v12, s[4:5], s64, v120
	v_lshl_add_u64 v[10:11], v[120:121], 0, s[28:29]
	s_nop 0
	v_addc_co_u32_e64 v13, s[4:5], 0, v121, s[4:5]
	global_store_dwordx4 v[12:13], v[14:17], off
	global_load_dwordx4 v[12:15], v[82:83], off
	s_nop 0
	global_load_dwordx4 v[16:19], v[80:81], off
	ds_bpermute_b32 v34, v177, v4
	ds_bpermute_b32 v32, v177, v5
	ds_bpermute_b32 v33, v177, v6
	ds_bpermute_b32 v28, v177, v7
	global_load_dwordx4 v[20:23], v[76:77], off offset:16
	global_load_dwordx4 v[24:27], v[78:79], off offset:16
	s_waitcnt lgkmcnt(0)
	v_cndmask_b32_e64 v29, v28, -v28, vcc
	v_mov_b32_e32 v30, v7
	s_waitcnt vmcnt(3)
	v_mov_b32_e32 v31, v15
	s_waitcnt vmcnt(2)
	v_mov_b32_e32 v28, v19
	v_cndmask_b32_e64 v19, v33, -v33, vcc
	v_mov_b32_e32 v7, v14
	v_cndmask_b32_e64 v15, v32, -v32, vcc
	v_mov_b32_e32 v32, v5
	v_mov_b32_e32 v33, v13
	v_mov_b32_e32 v14, v17
	v_cndmask_b32_e64 v17, v34, -v34, vcc
	v_mov_b32_e32 v5, v12
	ds_bpermute_b32 v13, v177, v0
	v_mov_b32_e32 v12, v0
	ds_bpermute_b32 v34, v177, v1
	ds_bpermute_b32 v35, v177, v2
	v_mov_b32_e32 v0, v2
	ds_bpermute_b32 v2, v177, v3
	v_pk_mul_f32 v[28:29], v[30:31], v[28:29]
	v_pk_mul_f32 v[6:7], v[6:7], v[18:19]
	v_pk_mul_f32 v[14:15], v[32:33], v[14:15]
	v_pk_mul_f32 v[4:5], v[4:5], v[16:17]
	v_add_f32_e32 v18, v28, v29
	v_add_f32_e32 v19, v6, v7
	v_add_f32_e32 v28, v14, v15
	v_add_f32_e32 v29, v4, v5
	s_waitcnt lgkmcnt(3)
	v_cndmask_b32_e64 v5, v13, -v13, vcc
	s_waitcnt lgkmcnt(2)
	v_cndmask_b32_e64 v7, v34, -v34, vcc
	s_waitcnt lgkmcnt(1)
	v_cndmask_b32_e64 v15, v35, -v35, vcc
	s_waitcnt lgkmcnt(0)
	v_cndmask_b32_e64 v17, v2, -v2, vcc
	s_waitcnt vmcnt(1)
	v_mov_b32_e32 v13, v20
	s_waitcnt vmcnt(0)
	v_mov_b32_e32 v4, v24
	v_mov_b32_e32 v20, v1
	v_mov_b32_e32 v6, v25
	v_mov_b32_e32 v1, v22
	v_mov_b32_e32 v14, v26
	v_mov_b32_e32 v22, v3
	v_mov_b32_e32 v16, v27
	v_pk_mul_f32 v[2:3], v[12:13], v[4:5]
	v_pk_mul_f32 v[4:5], v[20:21], v[6:7]
	v_pk_mul_f32 v[0:1], v[0:1], v[14:15]
	v_pk_mul_f32 v[6:7], v[22:23], v[16:17]
	v_add_f32_e32 v12, v2, v3
	v_add_f32_e32 v13, v4, v5
	v_add_f32_e32 v14, v0, v1
	v_add_f32_e32 v7, v6, v7
	v_mul_f32_e32 v0, v63, v29
	v_mul_f32_e32 v1, v75, v28
	v_cvt_pk_bf16_f32 v0, v0, v1
	v_mul_f32_e32 v1, v84, v19
	v_mul_f32_e32 v2, v86, v18
	v_cvt_pk_bf16_f32 v1, v1, v2
	v_mul_f32_e32 v2, v85, v12
	v_mul_f32_e32 v3, v88, v13
	v_cvt_pk_bf16_f32 v2, v2, v3
	v_mul_f32_e32 v3, v87, v14
	v_mul_f32_e32 v4, v71, v7
	v_cvt_pk_bf16_f32 v3, v3, v4
	v_mul_f32_e32 v4, v64, v29
	v_mul_f32_e32 v5, v60, v28
	v_cvt_pk_bf16_f32 v4, v4, v5
	v_mul_f32_e32 v5, v66, v19
	v_mul_f32_e32 v6, v68, v18
	v_cvt_pk_bf16_f32 v5, v5, v6
	v_mul_f32_e32 v6, v70, v12
	v_mul_f32_e32 v12, v72, v13
	v_mul_f32_e32 v7, v67, v7
	v_cvt_pk_bf16_f32 v6, v6, v12
	v_mul_f32_e32 v12, v65, v14
	v_cvt_pk_bf16_f32 v7, v12, v7
	global_store_dwordx4 v[8:9], v[0:3], off offset:256
	global_store_dwordx4 v[10:11], v[4:7], off offset:256
	s_and_b64 vcc, exec, s[2:3]
	s_mov_b32 s33, s30
	s_mov_b64 s[4:5], s[38:39]
	s_mov_b64 s[0:1], s[36:37]
	s_cbranch_vccz .LBB0_606
	s_waitcnt vmcnt(0)
	s_cmpk_gt_u32 s42, 0xff
	s_cbranch_scc1 .LBB0_617
	s_barrier

; #define PG8_STAGE(bufoff, gbase, voff) do { _Pragma("unroll") for (int _i = 0; _i < 2; ++_i) \
;         __builtin_amdgcn_global_load_lds((const unsigned*)((const char*)(gbase) + (voff)[_i]), (LAS unsigned*)(lds + (bufoff) + ldsw + _i * 8192), 16, 0, 0); } while (0)
; #define PG8_LDA(dst, b, h) do { _Pragma("unroll") for (int m = 0; m < 4; ++m) _Pragma("unroll") for (int k = 0; k < 2; ++k) dst[m][k] = *(const LAS bf16x8*)(lds + PG8_SA(b, h) + aoff + m * 2048 + k * 1024); } while (0)
; #define PG8_LDB(dst, b, h) do { _Pragma("unroll") for (int n = 0; n < 2; ++n) _Pragma("unroll") for (int k = 0; k < 2; ++k) dst[n][k] = *(const LAS bf16x8*)(lds + PG8_SB(b, h) + boff + n * 2048 + k * 1024); } while (0)
; #define PG8_WAIT_V(n) asm volatile("s_waitcnt vmcnt(" #n ")" ::: "memory")
; #define PG8_BAR __builtin_amdgcn_s_barrier()
; template <class Epi, class Sched>
; __device__ __forceinline__ void gemm_phase(LAS unsigned char* lds, const Gemm g, const Sched& S, const Epi& E) {
;     ...
;         const bool has_next = S.next(ui + 1, nxt);
;         const char* nA = has_next ? (const char*)g.A + (size_t)nxt.pm * tstep : cA; const char* nB = has_next ? (const char*)g.Bt + (size_t)nxt.pn * tstep : cB;
;         for (int t = 0; t < nt; t += 2) {
;             const bool last = (t == nt - 2);
;             const char* a1 = cA + (size_t)(t + 1) * kstep;
;             const char* a2 = last ? nA : cA + (size_t)(t + 2) * kstep; const char* b2 = last ? nB : cB + (size_t)(t + 2) * kstep;
;             const char* a3 = a2 + kstep; const char* b3 = b2 + kstep;
;             PG8_LDB(B0, 0, 0); PG8_SCHED; PG8_LDA(At, 0, 0); PG8_STAGE(PG8_SA(1, 1), a1 + hstep, voffA);
;             PG8_WAIT_L(8); PG8_BAR; PG8_WAIT_L(0); PG8_MMA(0, 0, At, B0); PG8_BAR; PG8_SCHED;
;             PG8_LDB(B1, 0, 1); PG8_STAGE(PG8_SB(0, 0), b2, voffB);
;             PG8_BAR; PG8_WAIT_L(0); PG8_MMA(0, 1, At, B1); PG8_BAR;
;             PG8_LDA(At, 0, 1); PG8_STAGE(PG8_SA(0, 0), a2, voffA);
;             PG8_BAR; PG8_WAIT_L(0); PG8_MMA(1, 0, At, B0); PG8_BAR; PG8_SCHED;
;             PG8_STAGE(PG8_SB(0, 1), b2 + hstep, voffB);
;             PG8_WAIT_V(6); PG8_BAR; PG8_MMA(1, 1, At, B1); PG8_BAR;
;             PG8_LDB(B0, 1, 0); PG8_SCHED; PG8_LDA(At, 1, 0); PG8_STAGE(PG8_SA(0, 1), a2 + hstep, voffA);
;             PG8_WAIT_L(8); PG8_BAR; PG8_WAIT_L(0); PG8_MMA(0, 0, At, B0); PG8_BAR; PG8_SCHED;
.LBB0_632:
	s_ashr_i32 s23, s22, 31
	v_cmp_lt_i64_e32 vcc, s[24:25], v[140:141]
	s_lshl_b64 s[24:25], s[22:23], 19
	s_add_u32 s24, s38, s24
	s_addc_u32 s25, s39, s25
	s_and_b64 s[26:27], vcc, exec
	s_cselect_b32 s23, s25, s31
	s_cselect_b32 s61, s24, s30
	s_ashr_i32 s21, s20, 31
	s_lshl_b64 s[26:27], s[20:21], 19
	s_add_u32 s26, s96, s26
	s_addc_u32 s27, s97, s27
	s_and_b64 s[36:37], vcc, exec
	s_cselect_b32 s21, s27, s35
	s_cselect_b32 s62, s26, s34
	s_add_u32 s30, s30, 0x40080
	s_addc_u32 s31, s31, 0
	s_add_u32 s63, s34, 0x100
	s_addc_u32 s64, s35, 0
	s_mov_b32 s65, -2
	s_waitcnt lgkmcnt(0)
	ds_read_b128 v[150:153], v147
	ds_read_b128 v[154:157], v147 offset:1024
	ds_read_b128 v[158:161], v147 offset:2048
	ds_read_b128 v[162:165], v147 offset:3072
	s_add_u32 s34, s30, 0xfffc0080
	s_addc_u32 s35, s31, -1
	s_cmp_eq_u32 s65, 12
	s_cselect_b32 s37, s23, s35
	s_cselect_b32 s36, s61, s34
	s_cselect_b32 s35, s21, s64
	s_cselect_b32 s34, s62, s63
	s_add_i32 m0, s29, 0xc000
	ds_read_b128 v[166:169], v148
	ds_read_b128 v[170:173], v148 offset:1024
	ds_read_b128 v[174:177], v148 offset:2048
	ds_read_b128 v[178:181], v148 offset:3072
	ds_read_b128 v[182:185], v148 offset:4096
	ds_read_b128 v[186:189], v148 offset:5120
	ds_read_b128 v[190:193], v148 offset:6144
	ds_read_b128 v[194:197], v148 offset:7168
	global_load_lds_dwordx4 v136, s[30:31]
	s_add_i32 m0, s29, 0xe000
	s_nop 0
	global_load_lds_dwordx4 v138, s[30:31]
	s_waitcnt lgkmcnt(8)
	s_barrier
	s_waitcnt lgkmcnt(0)
	s_setprio 1
	s_waitcnt lgkmcnt(0)
	v_mfma_f32_16x16x32_bf16 v[124:127], v[150:153], v[166:169], 0
	v_mfma_f32_16x16x32_bf16 v[120:123], v[158:161], v[166:169], 0
	v_mfma_f32_16x16x32_bf16 v[116:119], v[150:153], v[174:177], 0
	v_mfma_f32_16x16x32_bf16 v[108:111], v[158:161], v[174:177], 0
	v_mfma_f32_16x16x32_bf16 v[100:103], v[150:153], v[182:185], 0
	v_mfma_f32_16x16x32_bf16 v[92:95], v[158:161], v[182:185], 0
	v_mfma_f32_16x16x32_bf16 v[84:87], v[150:153], v[190:193], 0
	v_mfma_f32_16x16x32_bf16 v[76:79], v[158:161], v[190:193], 0
	v_mfma_f32_16x16x32_bf16 v[124:127], v[154:157], v[170:173], v[124:127]
	v_mfma_f32_16x16x32_bf16 v[120:123], v[162:165], v[170:173], v[120:123]
	v_mfma_f32_16x16x32_bf16 v[116:119], v[154:157], v[178:181], v[116:119]
	v_mfma_f32_16x16x32_bf16 v[108:111], v[162:165], v[178:181], v[108:111]
	v_mfma_f32_16x16x32_bf16 v[100:103], v[154:157], v[186:189], v[100:103]
	v_mfma_f32_16x16x32_bf16 v[92:95], v[162:165], v[186:189], v[92:95]
	v_mfma_f32_16x16x32_bf16 v[84:87], v[154:157], v[194:197], v[84:87]
	v_mfma_f32_16x16x32_bf16 v[76:79], v[162:165], v[194:197], v[76:79]
	s_setprio 0
	s_barrier
	s_add_i32 s66, s54, s43
	s_mov_b32 m0, s66
	ds_read_b128 v[202:205], v149
	ds_read_b128 v[206:209], v149 offset:1024
	ds_read_b128 v[210:213], v149 offset:2048
	ds_read_b128 v[214:217], v149 offset:3072
	global_load_lds_dwordx4 v130, s[34:35]
	s_add_i32 m0, s66, 0x2000
	s_nop 0
	global_load_lds_dwordx4 v134, s[34:35]
	s_barrier
	s_waitcnt lgkmcnt(0)
	s_setprio 1
	s_waitcnt lgkmcnt(0)
	v_mfma_f32_16x16x32_bf16 v[112:115], v[202:205], v[166:169], 0
	v_mfma_f32_16x16x32_bf16 v[104:107], v[210:213], v[166:169], 0
	v_mfma_f32_16x16x32_bf16 v[96:99], v[202:205], v[174:177], 0
	v_mfma_f32_16x16x32_bf16 v[88:91], v[210:213], v[174:177], 0
	v_mfma_f32_16x16x32_bf16 v[80:83], v[202:205], v[182:185], 0
	v_mfma_f32_16x16x32_bf16 v[72:75], v[210:213], v[182:185], 0
	v_mfma_f32_16x16x32_bf16 v[68:71], v[202:205], v[190:193], 0
	v_mfma_f32_16x16x32_bf16 v[64:67], v[210:213], v[190:193], 0
	v_mfma_f32_16x16x32_bf16 v[112:115], v[206:209], v[170:173], v[112:115]
	v_mfma_f32_16x16x32_bf16 v[104:107], v[214:217], v[170:173], v[104:107]
	v_mfma_f32_16x16x32_bf16 v[96:99], v[206:209], v[178:181], v[96:99]
	v_mfma_f32_16x16x32_bf16 v[88:91], v[214:217], v[178:181], v[88:91]
	v_mfma_f32_16x16x32_bf16 v[80:83], v[206:209], v[186:189], v[80:83]
	v_mfma_f32_16x16x32_bf16 v[72:75], v[214:217], v[186:189], v[72:75]
	v_mfma_f32_16x16x32_bf16 v[68:71], v[206:209], v[194:197], v[68:71]
	v_mfma_f32_16x16x32_bf16 v[64:67], v[214:217], v[194:197], v[64:67]
	s_setprio 0
	s_mov_b32 m0, s29
	v_lshl_add_u64 v[220:221], s[36:37], 0, v[128:129]
	s_barrier
	ds_read_b128 v[166:169], v148 offset:16384
	ds_read_b128 v[170:173], v148 offset:17408
	ds_read_b128 v[174:177], v148 offset:18432
	ds_read_b128 v[178:181], v148 offset:19456
	ds_read_b128 v[182:185], v148 offset:20480
	ds_read_b128 v[186:189], v148 offset:21504
	ds_read_b128 v[190:193], v148 offset:22528
	ds_read_b128 v[194:197], v148 offset:23552
	global_load_lds_dwordx4 v128, s[36:37]
	v_lshl_add_u64 v[222:223], s[36:37], 0, v[132:133]
	s_mov_b32 m0, s44
	s_nop 0
	global_load_lds_dwordx4 v132, s[36:37]
	s_barrier
	s_waitcnt lgkmcnt(0)
	s_setprio 1
	s_waitcnt lgkmcnt(0)
	v_mfma_f32_16x16x32_bf16 v[60:63], v[150:153], v[166:169], 0
	v_mfma_f32_16x16x32_bf16 v[56:59], v[158:161], v[166:169], 0
	v_mfma_f32_16x16x32_bf16 v[52:55], v[150:153], v[174:177], 0
	v_mfma_f32_16x16x32_bf16 v[44:47], v[158:161], v[174:177], 0
	v_mfma_f32_16x16x32_bf16 v[36:39], v[150:153], v[182:185], 0
	v_mfma_f32_16x16x32_bf16 v[28:31], v[158:161], v[182:185], 0
	v_mfma_f32_16x16x32_bf16 v[20:23], v[150:153], v[190:193], 0
	v_mfma_f32_16x16x32_bf16 v[12:15], v[158:161], v[190:193], 0
	v_mfma_f32_16x16x32_bf16 v[60:63], v[154:157], v[170:173], v[60:63]
	v_mfma_f32_16x16x32_bf16 v[56:59], v[162:165], v[170:173], v[56:59]
	v_mfma_f32_16x16x32_bf16 v[52:55], v[154:157], v[178:181], v[52:55]
	v_mfma_f32_16x16x32_bf16 v[44:47], v[162:165], v[178:181], v[44:47]
	v_mfma_f32_16x16x32_bf16 v[36:39], v[154:157], v[186:189], v[36:39]
	v_mfma_f32_16x16x32_bf16 v[28:31], v[162:165], v[186:189], v[28:31]
	v_mfma_f32_16x16x32_bf16 v[20:23], v[154:157], v[194:197], v[20:23]
	v_mfma_f32_16x16x32_bf16 v[12:15], v[162:165], v[194:197], v[12:15]
	s_setprio 0
	s_barrier
; #define PG8_STAGE(bufoff, gbase, voff) do { _Pragma("unroll") for (int _i = 0; _i < 2; ++_i) \
;         __builtin_amdgcn_global_load_lds((const unsigned*)((const char*)(gbase) + (voff)[_i]), (LAS unsigned*)(lds + (bufoff) + ldsw + _i * 8192), 16, 0, 0); } while (0)
; #define PG8_LDA(dst, b, h) do { _Pragma("unroll") for (int m = 0; m < 4; ++m) _Pragma("unroll") for (int k = 0; k < 2; ++k) dst[m][k] = *(const LAS bf16x8*)(lds + PG8_SA(b, h) + aoff + m * 2048 + k * 1024); } while (0)
; #define PG8_LDB(dst, b, h) do { _Pragma("unroll") for (int n = 0; n < 2; ++n) _Pragma("unroll") for (int k = 0; k < 2; ++k) dst[n][k] = *(const LAS bf16x8*)(lds + PG8_SB(b, h) + boff + n * 2048 + k * 1024); } while (0)
; #define PG8_MMA(ai, bj, At, Bt) do { __builtin_amdgcn_s_setprio(1); _Pragma("unroll") for (int m = 0; m < 4; ++m) _Pragma("unroll") for (int n = 0; n < 2; ++n) _Pragma("unroll") for (int k = 0; k < 2; ++k) \
;         acc[ai][bj][m][n] = __builtin_amdgcn_mfma_f32_16x16x32_bf16(Bt[n][k], At[m][k], acc[ai][bj][m][n], 0, 0, 0); __builtin_amdgcn_s_setprio(0); } while (0)
; #define PG8_WAIT_V(n) asm volatile("s_waitcnt vmcnt(" #n ")" ::: "memory")
; #define PG8_WAIT_L(n) asm volatile("s_waitcnt lgkmcnt(" #n ")" ::: "memory")
; #define PG8_BAR __builtin_amdgcn_s_barrier()
; #define PG8_SCHED __builtin_amdgcn_sched_barrier(0)
; template <class Epi, class Sched>
; __device__ __forceinline__ void gemm_phase(LAS unsigned char* lds, const Gemm g, const Sched& S, const Epi& E) {
;     ...
;             PG8_STAGE(PG8_SB(0, 1), b2 + hstep, voffB);
;             PG8_WAIT_V(6); PG8_BAR; PG8_MMA(1, 1, At, B1); PG8_BAR;
;             PG8_LDB(B0, 1, 0); PG8_SCHED; PG8_LDA(At, 1, 0); PG8_STAGE(PG8_SA(0, 1), a2 + hstep, voffA);
;             PG8_WAIT_L(8); PG8_BAR; PG8_WAIT_L(0); PG8_MMA(0, 0, At, B0); PG8_BAR; PG8_SCHED;
;             PG8_LDB(B1, 1, 1); PG8_STAGE(PG8_SB(1, 0), b3, voffB);
;             PG8_BAR; PG8_WAIT_L(0); PG8_MMA(0, 1, At, B1); PG8_BAR;
;             PG8_LDA(At, 1, 1); PG8_STAGE(PG8_SA(1, 0), a3, voffA);
;             PG8_BAR; PG8_WAIT_L(0); PG8_MMA(1, 0, At, B0); PG8_BAR; PG8_SCHED;
	s_add_u32 s66, s34, 0x40000
	s_addc_u32 s67, s35, 0
	s_add_i32 s68, s55, s43
	s_mov_b32 m0, s68
	s_nop 0
	global_load_lds_dwordx4 v130, s[66:67]
	s_add_i32 m0, s68, 0x2000
	s_nop 0
	global_load_lds_dwordx4 v134, s[66:67]
	s_waitcnt vmcnt(6)
	s_barrier
	s_setprio 1
	v_mfma_f32_16x16x32_bf16 v[48:51], v[202:205], v[166:169], 0
	v_mfma_f32_16x16x32_bf16 v[40:43], v[210:213], v[166:169], 0
	v_mfma_f32_16x16x32_bf16 v[32:35], v[202:205], v[174:177], 0
	v_mfma_f32_16x16x32_bf16 v[24:27], v[210:213], v[174:177], 0
	v_mfma_f32_16x16x32_bf16 v[16:19], v[202:205], v[182:185], 0
	v_mfma_f32_16x16x32_bf16 v[8:11], v[210:213], v[182:185], 0
	v_mfma_f32_16x16x32_bf16 v[4:7], v[202:205], v[190:193], 0
	v_mfma_f32_16x16x32_bf16 v[0:3], v[210:213], v[190:193], 0
	v_mfma_f32_16x16x32_bf16 v[48:51], v[206:209], v[170:173], v[48:51]
	v_mfma_f32_16x16x32_bf16 v[40:43], v[214:217], v[170:173], v[40:43]
	v_mfma_f32_16x16x32_bf16 v[32:35], v[206:209], v[178:181], v[32:35]
	v_mfma_f32_16x16x32_bf16 v[24:27], v[214:217], v[178:181], v[24:27]
	v_mfma_f32_16x16x32_bf16 v[16:19], v[206:209], v[186:189], v[16:19]
	v_mfma_f32_16x16x32_bf16 v[8:11], v[214:217], v[186:189], v[8:11]
	v_mfma_f32_16x16x32_bf16 v[4:7], v[206:209], v[194:197], v[4:7]
	v_mfma_f32_16x16x32_bf16 v[0:3], v[214:217], v[194:197], v[0:3]
	s_setprio 0
	s_add_i32 s66, 0, 0x18000
	v_add_u32_e32 v162, s66, v146
	s_barrier
	ds_read_b128 v[150:153], v162
	ds_read_b128 v[154:157], v162 offset:1024
	ds_read_b128 v[158:161], v162 offset:2048
	ds_read_b128 v[162:165], v162 offset:3072
	s_add_u32 s36, s36, 0x40000
	s_addc_u32 s37, s37, 0
	s_mov_b32 m0, s45
	ds_read_b128 v[166:169], v148 offset:32768
	ds_read_b128 v[170:173], v148 offset:33792
	ds_read_b128 v[174:177], v148 offset:34816
	ds_read_b128 v[178:181], v148 offset:35840
	ds_read_b128 v[182:185], v148 offset:36864
	ds_read_b128 v[186:189], v148 offset:37888
	ds_read_b128 v[190:193], v148 offset:38912
	ds_read_b128 v[194:197], v148 offset:39936
	global_load_lds_dwordx4 v128, s[36:37]
	s_mov_b32 m0, s46
	s_nop 0
	global_load_lds_dwordx4 v132, s[36:37]
	s_waitcnt lgkmcnt(8)
	s_barrier
	s_waitcnt lgkmcnt(0)
	s_setprio 1
	s_waitcnt lgkmcnt(0)
	v_mfma_f32_16x16x32_bf16 v[124:127], v[150:153], v[166:169], v[124:127]
	v_mfma_f32_16x16x32_bf16 v[120:123], v[158:161], v[166:169], v[120:123]
	v_mfma_f32_16x16x32_bf16 v[116:119], v[150:153], v[174:177], v[116:119]
	v_mfma_f32_16x16x32_bf16 v[108:111], v[158:161], v[174:177], v[108:111]
	v_mfma_f32_16x16x32_bf16 v[100:103], v[150:153], v[182:185], v[100:103]
	v_mfma_f32_16x16x32_bf16 v[92:95], v[158:161], v[182:185], v[92:95]
	v_mfma_f32_16x16x32_bf16 v[84:87], v[150:153], v[190:193], v[84:87]
	v_mfma_f32_16x16x32_bf16 v[76:79], v[158:161], v[190:193], v[76:79]
	v_mfma_f32_16x16x32_bf16 v[124:127], v[154:157], v[170:173], v[124:127]
	v_mfma_f32_16x16x32_bf16 v[120:123], v[162:165], v[170:173], v[120:123]
	v_mfma_f32_16x16x32_bf16 v[116:119], v[154:157], v[178:181], v[116:119]
	v_mfma_f32_16x16x32_bf16 v[108:111], v[162:165], v[178:181], v[108:111]
	v_mfma_f32_16x16x32_bf16 v[100:103], v[154:157], v[186:189], v[100:103]
	v_mfma_f32_16x16x32_bf16 v[92:95], v[162:165], v[186:189], v[92:95]
	v_mfma_f32_16x16x32_bf16 v[84:87], v[154:157], v[194:197], v[84:87]
	v_mfma_f32_16x16x32_bf16 v[76:79], v[162:165], v[194:197], v[76:79]
	s_setprio 0
	s_barrier
	s_add_i32 s36, 0, 0x1c000
	s_add_i32 s37, s66, s43
	v_add_u32_e32 v214, s36, v146
	s_add_u32 s4, s34, 0x80
	s_addc_u32 s5, s35, 0
	s_mov_b32 m0, s37
	ds_read_b128 v[202:205], v214
	ds_read_b128 v[206:209], v214 offset:1024
	ds_read_b128 v[210:213], v214 offset:2048
	ds_read_b128 v[214:217], v214 offset:3072
	global_load_lds_dwordx4 v130, s[4:5]
	s_add_i32 m0, s37, 0x2000
	s_nop 0
	global_load_lds_dwordx4 v134, s[4:5]
	s_barrier
	s_waitcnt lgkmcnt(0)
	s_setprio 1
	s_waitcnt lgkmcnt(0)
	v_mfma_f32_16x16x32_bf16 v[112:115], v[202:205], v[166:169], v[112:115]
	v_mfma_f32_16x16x32_bf16 v[104:107], v[210:213], v[166:169], v[104:107]
	v_mfma_f32_16x16x32_bf16 v[96:99], v[202:205], v[174:177], v[96:99]
	v_mfma_f32_16x16x32_bf16 v[88:91], v[210:213], v[174:177], v[88:91]
	v_mfma_f32_16x16x32_bf16 v[80:83], v[202:205], v[182:185], v[80:83]
	v_mfma_f32_16x16x32_bf16 v[72:75], v[210:213], v[182:185], v[72:75]
	v_mfma_f32_16x16x32_bf16 v[68:71], v[202:205], v[190:193], v[68:71]
	v_mfma_f32_16x16x32_bf16 v[64:67], v[210:213], v[190:193], v[64:67]
	v_mfma_f32_16x16x32_bf16 v[112:115], v[206:209], v[170:173], v[112:115]
	v_mfma_f32_16x16x32_bf16 v[104:107], v[214:217], v[170:173], v[104:107]
	v_mfma_f32_16x16x32_bf16 v[96:99], v[206:209], v[178:181], v[96:99]
	v_mfma_f32_16x16x32_bf16 v[88:91], v[214:217], v[178:181], v[88:91]
	v_mfma_f32_16x16x32_bf16 v[80:83], v[206:209], v[186:189], v[80:83]
	v_mfma_f32_16x16x32_bf16 v[72:75], v[214:217], v[186:189], v[72:75]
	v_mfma_f32_16x16x32_bf16 v[68:71], v[206:209], v[194:197], v[68:71]
	v_mfma_f32_16x16x32_bf16 v[64:67], v[214:217], v[194:197], v[64:67]
	s_setprio 0
	s_mov_b32 m0, s51
	s_mov_b64 s[4:5], 0x80
	v_lshl_add_u64 v[198:199], v[220:221], 0, s[4:5]
	s_barrier
	ds_read_b128 v[166:169], v148 offset:49152
	ds_read_b128 v[170:173], v148 offset:50176
	ds_read_b128 v[174:177], v148 offset:51200
	ds_read_b128 v[178:181], v148 offset:52224
	ds_read_b128 v[182:185], v148 offset:53248
	ds_read_b128 v[186:189], v148 offset:54272
	ds_read_b128 v[190:193], v148 offset:55296
	ds_read_b128 v[194:197], v148 offset:56320
	global_load_lds_dwordx4 v[198:199], off
	v_lshl_add_u64 v[198:199], v[222:223], 0, s[4:5]
	s_mov_b32 m0, s52
	s_nop 0
	global_load_lds_dwordx4 v[198:199], off
	s_barrier
; #define PG8_STAGE(bufoff, gbase, voff) do { _Pragma("unroll") for (int _i = 0; _i < 2; ++_i) \
;         __builtin_amdgcn_global_load_lds((const unsigned*)((const char*)(gbase) + (voff)[_i]), (LAS unsigned*)(lds + (bufoff) + ldsw + _i * 8192), 16, 0, 0); } while (0)
; #define PG8_LDA(dst, b, h) do { _Pragma("unroll") for (int m = 0; m < 4; ++m) _Pragma("unroll") for (int k = 0; k < 2; ++k) dst[m][k] = *(const LAS bf16x8*)(lds + PG8_SA(b, h) + aoff + m * 2048 + k * 1024); } while (0)
; #define PG8_LDB(dst, b, h) do { _Pragma("unroll") for (int n = 0; n < 2; ++n) _Pragma("unroll") for (int k = 0; k < 2; ++k) dst[n][k] = *(const LAS bf16x8*)(lds + PG8_SB(b, h) + boff + n * 2048 + k * 1024); } while (0)
; #define PG8_MMA(ai, bj, At, Bt) do { __builtin_amdgcn_s_setprio(1); _Pragma("unroll") for (int m = 0; m < 4; ++m) _Pragma("unroll") for (int n = 0; n < 2; ++n) _Pragma("unroll") for (int k = 0; k < 2; ++k) \
;         acc[ai][bj][m][n] = __builtin_amdgcn_mfma_f32_16x16x32_bf16(Bt[n][k], At[m][k], acc[ai][bj][m][n], 0, 0, 0); __builtin_amdgcn_s_setprio(0); } while (0)
; #define PG8_WAIT_V(n) asm volatile("s_waitcnt vmcnt(" #n ")" ::: "memory")
; #define PG8_WAIT_L(n) asm volatile("s_waitcnt lgkmcnt(" #n ")" ::: "memory")
; template <class Epi, class Sched>
; __device__ __forceinline__ void gemm_phase(LAS unsigned char* lds, const Gemm g, const Sched& S, const Epi& E) {
;     ...
;         for (int t = 0; t < nt; t += 2) {
;             const bool last = (t == nt - 2);
;             const char* a1 = cA + (size_t)(t + 1) * kstep;
;             const char* a2 = last ? nA : cA + (size_t)(t + 2) * kstep; const char* b2 = last ? nB : cB + (size_t)(t + 2) * kstep;
;             const char* a3 = a2 + kstep; const char* b3 = b2 + kstep;
;             PG8_LDB(B0, 0, 0); PG8_SCHED; PG8_LDA(At, 0, 0); PG8_STAGE(PG8_SA(1, 1), a1 + hstep, voffA);
;             PG8_WAIT_L(8); PG8_BAR; PG8_WAIT_L(0); PG8_MMA(0, 0, At, B0); PG8_BAR; PG8_SCHED;
;             PG8_LDB(B1, 0, 1); PG8_STAGE(PG8_SB(0, 0), b2, voffB);
;             PG8_BAR; PG8_WAIT_L(0); PG8_MMA(0, 1, At, B1); PG8_BAR;
;             PG8_LDA(At, 0, 1); PG8_STAGE(PG8_SA(0, 0), a2, voffA);
;     ...
;             PG8_BAR; PG8_WAIT_L(0); PG8_MMA(1, 0, At, B0); PG8_BAR; PG8_SCHED;
;             PG8_STAGE(PG8_SB(1, 1), b3 + hstep, voffB);
;             PG8_WAIT_V(6); PG8_BAR; PG8_MMA(1, 1, At, B1); PG8_BAR;
	s_waitcnt lgkmcnt(0)
	s_setprio 1
	s_waitcnt lgkmcnt(0)
	v_mfma_f32_16x16x32_bf16 v[60:63], v[150:153], v[166:169], v[60:63]
	v_mfma_f32_16x16x32_bf16 v[56:59], v[158:161], v[166:169], v[56:59]
	v_mfma_f32_16x16x32_bf16 v[52:55], v[150:153], v[174:177], v[52:55]
	v_mfma_f32_16x16x32_bf16 v[44:47], v[158:161], v[174:177], v[44:47]
	v_mfma_f32_16x16x32_bf16 v[36:39], v[150:153], v[182:185], v[36:39]
	v_mfma_f32_16x16x32_bf16 v[28:31], v[158:161], v[182:185], v[28:31]
	v_mfma_f32_16x16x32_bf16 v[20:23], v[150:153], v[190:193], v[20:23]
	v_mfma_f32_16x16x32_bf16 v[12:15], v[158:161], v[190:193], v[12:15]
	v_mfma_f32_16x16x32_bf16 v[60:63], v[154:157], v[170:173], v[60:63]
	v_mfma_f32_16x16x32_bf16 v[56:59], v[162:165], v[170:173], v[56:59]
	v_mfma_f32_16x16x32_bf16 v[52:55], v[154:157], v[178:181], v[52:55]
	v_mfma_f32_16x16x32_bf16 v[44:47], v[162:165], v[178:181], v[44:47]
	v_mfma_f32_16x16x32_bf16 v[36:39], v[154:157], v[186:189], v[36:39]
	v_mfma_f32_16x16x32_bf16 v[28:31], v[162:165], v[186:189], v[28:31]
	v_mfma_f32_16x16x32_bf16 v[20:23], v[154:157], v[194:197], v[20:23]
	v_mfma_f32_16x16x32_bf16 v[12:15], v[162:165], v[194:197], v[12:15]
	s_setprio 0
	s_barrier
	s_add_u32 s34, s34, 0x40080
	s_addc_u32 s35, s35, 0
	s_add_i32 s36, s36, s43
	s_mov_b32 m0, s36
	s_nop 0
	global_load_lds_dwordx4 v130, s[34:35]
	s_add_i32 m0, s36, 0x2000
	s_nop 0
	global_load_lds_dwordx4 v134, s[34:35]
	s_waitcnt vmcnt(6)
	s_barrier
	s_setprio 1
	v_mfma_f32_16x16x32_bf16 v[48:51], v[202:205], v[166:169], v[48:51]
	v_mfma_f32_16x16x32_bf16 v[40:43], v[210:213], v[166:169], v[40:43]
	v_mfma_f32_16x16x32_bf16 v[32:35], v[202:205], v[174:177], v[32:35]
	v_mfma_f32_16x16x32_bf16 v[24:27], v[210:213], v[174:177], v[24:27]
	v_mfma_f32_16x16x32_bf16 v[16:19], v[202:205], v[182:185], v[16:19]
	v_mfma_f32_16x16x32_bf16 v[8:11], v[210:213], v[182:185], v[8:11]
	v_mfma_f32_16x16x32_bf16 v[4:7], v[202:205], v[190:193], v[4:7]
	v_mfma_f32_16x16x32_bf16 v[0:3], v[210:213], v[190:193], v[0:3]
	v_mfma_f32_16x16x32_bf16 v[48:51], v[206:209], v[170:173], v[48:51]
	v_mfma_f32_16x16x32_bf16 v[40:43], v[214:217], v[170:173], v[40:43]
	v_mfma_f32_16x16x32_bf16 v[32:35], v[206:209], v[178:181], v[32:35]
	v_mfma_f32_16x16x32_bf16 v[24:27], v[214:217], v[178:181], v[24:27]
	v_mfma_f32_16x16x32_bf16 v[16:19], v[206:209], v[186:189], v[16:19]
	v_mfma_f32_16x16x32_bf16 v[8:11], v[214:217], v[186:189], v[8:11]
	v_mfma_f32_16x16x32_bf16 v[4:7], v[206:209], v[194:197], v[4:7]
	v_mfma_f32_16x16x32_bf16 v[0:3], v[214:217], v[194:197], v[0:3]
	s_setprio 0
	s_add_i32 s65, s65, 2
	s_add_u32 s30, s30, 0x100
	s_addc_u32 s31, s31, 0
	s_add_u32 s63, s63, 0x100
	s_addc_u32 s64, s64, 0
	s_cmp_gt_u32 s65, 13
	s_barrier
.LBB0_633:
	ds_read_b128 v[150:153], v147
	ds_read_b128 v[154:157], v147 offset:1024
	ds_read_b128 v[158:161], v147 offset:2048
	ds_read_b128 v[162:165], v147 offset:3072
	s_add_u32 s34, s30, 0xfffc0080
	s_addc_u32 s35, s31, -1
	s_cmp_eq_u32 s65, 12
	s_cselect_b32 s37, s23, s35
	s_cselect_b32 s36, s61, s34
	s_cselect_b32 s35, s21, s64
	s_cselect_b32 s34, s62, s63
	s_add_i32 m0, s29, 0xc000
	ds_read_b128 v[166:169], v148
	ds_read_b128 v[170:173], v148 offset:1024
	ds_read_b128 v[174:177], v148 offset:2048
	ds_read_b128 v[178:181], v148 offset:3072
	ds_read_b128 v[182:185], v148 offset:4096
	ds_read_b128 v[186:189], v148 offset:5120
	ds_read_b128 v[190:193], v148 offset:6144
	ds_read_b128 v[194:197], v148 offset:7168
	global_load_lds_dwordx4 v136, s[30:31]
	s_add_i32 m0, s29, 0xe000
	s_nop 0
	global_load_lds_dwordx4 v138, s[30:31]
	s_waitcnt lgkmcnt(8)
	s_barrier
	s_waitcnt lgkmcnt(0)
	s_setprio 1
	s_waitcnt lgkmcnt(0)
	v_mfma_f32_16x16x32_bf16 v[124:127], v[150:153], v[166:169], v[124:127]
	v_mfma_f32_16x16x32_bf16 v[120:123], v[158:161], v[166:169], v[120:123]
	v_mfma_f32_16x16x32_bf16 v[116:119], v[150:153], v[174:177], v[116:119]
	v_mfma_f32_16x16x32_bf16 v[108:111], v[158:161], v[174:177], v[108:111]
	v_mfma_f32_16x16x32_bf16 v[100:103], v[150:153], v[182:185], v[100:103]
	v_mfma_f32_16x16x32_bf16 v[92:95], v[158:161], v[182:185], v[92:95]
	v_mfma_f32_16x16x32_bf16 v[84:87], v[150:153], v[190:193], v[84:87]
	v_mfma_f32_16x16x32_bf16 v[76:79], v[158:161], v[190:193], v[76:79]
	v_mfma_f32_16x16x32_bf16 v[124:127], v[154:157], v[170:173], v[124:127]
	v_mfma_f32_16x16x32_bf16 v[120:123], v[162:165], v[170:173], v[120:123]
	v_mfma_f32_16x16x32_bf16 v[116:119], v[154:157], v[178:181], v[116:119]
	v_mfma_f32_16x16x32_bf16 v[108:111], v[162:165], v[178:181], v[108:111]
	v_mfma_f32_16x16x32_bf16 v[100:103], v[154:157], v[186:189], v[100:103]
	v_mfma_f32_16x16x32_bf16 v[92:95], v[162:165], v[186:189], v[92:95]
	v_mfma_f32_16x16x32_bf16 v[84:87], v[154:157], v[194:197], v[84:87]
	v_mfma_f32_16x16x32_bf16 v[76:79], v[162:165], v[194:197], v[76:79]
	s_setprio 0
	s_barrier
	s_add_i32 s66, s54, s43
	s_mov_b32 m0, s66
	ds_read_b128 v[202:205], v149
	ds_read_b128 v[206:209], v149 offset:1024
	ds_read_b128 v[210:213], v149 offset:2048
	ds_read_b128 v[214:217], v149 offset:3072
	global_load_lds_dwordx4 v130, s[34:35]
	s_add_i32 m0, s66, 0x2000
	s_nop 0
	global_load_lds_dwordx4 v134, s[34:35]
	s_barrier
; #define PG8_STAGE(bufoff, gbase, voff) do { _Pragma("unroll") for (int _i = 0; _i < 2; ++_i) \
;         __builtin_amdgcn_global_load_lds((const unsigned*)((const char*)(gbase) + (voff)[_i]), (LAS unsigned*)(lds + (bufoff) + ldsw + _i * 8192), 16, 0, 0); } while (0)
; #define PG8_LDA(dst, b, h) do { _Pragma("unroll") for (int m = 0; m < 4; ++m) _Pragma("unroll") for (int k = 0; k < 2; ++k) dst[m][k] = *(const LAS bf16x8*)(lds + PG8_SA(b, h) + aoff + m * 2048 + k * 1024); } while (0)
; #define PG8_LDB(dst, b, h) do { _Pragma("unroll") for (int n = 0; n < 2; ++n) _Pragma("unroll") for (int k = 0; k < 2; ++k) dst[n][k] = *(const LAS bf16x8*)(lds + PG8_SB(b, h) + boff + n * 2048 + k * 1024); } while (0)
; #define PG8_MMA(ai, bj, At, Bt) do { __builtin_amdgcn_s_setprio(1); _Pragma("unroll") for (int m = 0; m < 4; ++m) _Pragma("unroll") for (int n = 0; n < 2; ++n) _Pragma("unroll") for (int k = 0; k < 2; ++k) \
;         acc[ai][bj][m][n] = __builtin_amdgcn_mfma_f32_16x16x32_bf16(Bt[n][k], At[m][k], acc[ai][bj][m][n], 0, 0, 0); __builtin_amdgcn_s_setprio(0); } while (0)
; #define PG8_WAIT_V(n) asm volatile("s_waitcnt vmcnt(" #n ")" ::: "memory")
; #define PG8_WAIT_L(n) asm volatile("s_waitcnt lgkmcnt(" #n ")" ::: "memory")
; #define PG8_BAR __builtin_amdgcn_s_barrier()
; #define PG8_SCHED __builtin_amdgcn_sched_barrier(0)
; template <class Epi, class Sched>
; __device__ __forceinline__ void gemm_phase(LAS unsigned char* lds, const Gemm g, const Sched& S, const Epi& E) {
;     ...
;             PG8_BAR; PG8_WAIT_L(0); PG8_MMA(0, 1, At, B1); PG8_BAR;
;             PG8_LDA(At, 0, 1); PG8_STAGE(PG8_SA(0, 0), a2, voffA);
;             PG8_BAR; PG8_WAIT_L(0); PG8_MMA(1, 0, At, B0); PG8_BAR; PG8_SCHED;
;             PG8_STAGE(PG8_SB(0, 1), b2 + hstep, voffB);
;             PG8_WAIT_V(6); PG8_BAR; PG8_MMA(1, 1, At, B1); PG8_BAR;
;             PG8_LDB(B0, 1, 0); PG8_SCHED; PG8_LDA(At, 1, 0); PG8_STAGE(PG8_SA(0, 1), a2 + hstep, voffA);
;             PG8_WAIT_L(8); PG8_BAR; PG8_WAIT_L(0); PG8_MMA(0, 0, At, B0); PG8_BAR; PG8_SCHED;
	s_waitcnt lgkmcnt(0)
	s_setprio 1
	s_waitcnt lgkmcnt(0)
	v_mfma_f32_16x16x32_bf16 v[112:115], v[202:205], v[166:169], v[112:115]
	v_mfma_f32_16x16x32_bf16 v[104:107], v[210:213], v[166:169], v[104:107]
	v_mfma_f32_16x16x32_bf16 v[96:99], v[202:205], v[174:177], v[96:99]
	v_mfma_f32_16x16x32_bf16 v[88:91], v[210:213], v[174:177], v[88:91]
	v_mfma_f32_16x16x32_bf16 v[80:83], v[202:205], v[182:185], v[80:83]
	v_mfma_f32_16x16x32_bf16 v[72:75], v[210:213], v[182:185], v[72:75]
	v_mfma_f32_16x16x32_bf16 v[68:71], v[202:205], v[190:193], v[68:71]
	v_mfma_f32_16x16x32_bf16 v[64:67], v[210:213], v[190:193], v[64:67]
	v_mfma_f32_16x16x32_bf16 v[112:115], v[206:209], v[170:173], v[112:115]
	v_mfma_f32_16x16x32_bf16 v[104:107], v[214:217], v[170:173], v[104:107]
	v_mfma_f32_16x16x32_bf16 v[96:99], v[206:209], v[178:181], v[96:99]
	v_mfma_f32_16x16x32_bf16 v[88:91], v[214:217], v[178:181], v[88:91]
	v_mfma_f32_16x16x32_bf16 v[80:83], v[206:209], v[186:189], v[80:83]
	v_mfma_f32_16x16x32_bf16 v[72:75], v[214:217], v[186:189], v[72:75]
	v_mfma_f32_16x16x32_bf16 v[68:71], v[206:209], v[194:197], v[68:71]
	v_mfma_f32_16x16x32_bf16 v[64:67], v[214:217], v[194:197], v[64:67]
	s_setprio 0
	s_mov_b32 m0, s29
	v_lshl_add_u64 v[220:221], s[36:37], 0, v[128:129]
	s_barrier
	ds_read_b128 v[166:169], v148 offset:16384
	ds_read_b128 v[170:173], v148 offset:17408
	ds_read_b128 v[174:177], v148 offset:18432
	ds_read_b128 v[178:181], v148 offset:19456
	ds_read_b128 v[182:185], v148 offset:20480
	ds_read_b128 v[186:189], v148 offset:21504
	ds_read_b128 v[190:193], v148 offset:22528
	ds_read_b128 v[194:197], v148 offset:23552
	global_load_lds_dwordx4 v128, s[36:37]
	v_lshl_add_u64 v[222:223], s[36:37], 0, v[132:133]
	s_mov_b32 m0, s44
	s_nop 0
	global_load_lds_dwordx4 v132, s[36:37]
	s_barrier
	s_waitcnt lgkmcnt(0)
	s_setprio 1
	s_waitcnt lgkmcnt(0)
	v_mfma_f32_16x16x32_bf16 v[60:63], v[150:153], v[166:169], v[60:63]
	v_mfma_f32_16x16x32_bf16 v[56:59], v[158:161], v[166:169], v[56:59]
	v_mfma_f32_16x16x32_bf16 v[52:55], v[150:153], v[174:177], v[52:55]
	v_mfma_f32_16x16x32_bf16 v[44:47], v[158:161], v[174:177], v[44:47]
	v_mfma_f32_16x16x32_bf16 v[36:39], v[150:153], v[182:185], v[36:39]
	v_mfma_f32_16x16x32_bf16 v[28:31], v[158:161], v[182:185], v[28:31]
	v_mfma_f32_16x16x32_bf16 v[20:23], v[150:153], v[190:193], v[20:23]
	v_mfma_f32_16x16x32_bf16 v[12:15], v[158:161], v[190:193], v[12:15]
	v_mfma_f32_16x16x32_bf16 v[60:63], v[154:157], v[170:173], v[60:63]
	v_mfma_f32_16x16x32_bf16 v[56:59], v[162:165], v[170:173], v[56:59]
	v_mfma_f32_16x16x32_bf16 v[52:55], v[154:157], v[178:181], v[52:55]
	v_mfma_f32_16x16x32_bf16 v[44:47], v[162:165], v[178:181], v[44:47]
	v_mfma_f32_16x16x32_bf16 v[36:39], v[154:157], v[186:189], v[36:39]
	v_mfma_f32_16x16x32_bf16 v[28:31], v[162:165], v[186:189], v[28:31]
	v_mfma_f32_16x16x32_bf16 v[20:23], v[154:157], v[194:197], v[20:23]
	v_mfma_f32_16x16x32_bf16 v[12:15], v[162:165], v[194:197], v[12:15]
	s_setprio 0
	s_barrier
	s_add_u32 s66, s34, 0x40000
	s_addc_u32 s67, s35, 0
	s_add_i32 s68, s55, s43
	s_mov_b32 m0, s68
	s_nop 0
	global_load_lds_dwordx4 v130, s[66:67]
	s_add_i32 m0, s68, 0x2000
	s_nop 0
	global_load_lds_dwordx4 v134, s[66:67]
	s_waitcnt vmcnt(6)
	s_barrier
	s_setprio 1
	v_mfma_f32_16x16x32_bf16 v[48:51], v[202:205], v[166:169], v[48:51]
	v_mfma_f32_16x16x32_bf16 v[40:43], v[210:213], v[166:169], v[40:43]
	v_mfma_f32_16x16x32_bf16 v[32:35], v[202:205], v[174:177], v[32:35]
	v_mfma_f32_16x16x32_bf16 v[24:27], v[210:213], v[174:177], v[24:27]
	v_mfma_f32_16x16x32_bf16 v[16:19], v[202:205], v[182:185], v[16:19]
	v_mfma_f32_16x16x32_bf16 v[8:11], v[210:213], v[182:185], v[8:11]
	v_mfma_f32_16x16x32_bf16 v[4:7], v[202:205], v[190:193], v[4:7]
	v_mfma_f32_16x16x32_bf16 v[0:3], v[210:213], v[190:193], v[0:3]
	v_mfma_f32_16x16x32_bf16 v[48:51], v[206:209], v[170:173], v[48:51]
	v_mfma_f32_16x16x32_bf16 v[40:43], v[214:217], v[170:173], v[40:43]
	v_mfma_f32_16x16x32_bf16 v[32:35], v[206:209], v[178:181], v[32:35]
	v_mfma_f32_16x16x32_bf16 v[24:27], v[214:217], v[178:181], v[24:27]
	v_mfma_f32_16x16x32_bf16 v[16:19], v[206:209], v[186:189], v[16:19]
	v_mfma_f32_16x16x32_bf16 v[8:11], v[214:217], v[186:189], v[8:11]
	v_mfma_f32_16x16x32_bf16 v[4:7], v[206:209], v[194:197], v[4:7]
	v_mfma_f32_16x16x32_bf16 v[0:3], v[214:217], v[194:197], v[0:3]
	s_setprio 0
	s_add_i32 s66, 0, 0x18000
	v_add_u32_e32 v162, s66, v146
	s_barrier
	ds_read_b128 v[150:153], v162
	ds_read_b128 v[154:157], v162 offset:1024
	ds_read_b128 v[158:161], v162 offset:2048
	ds_read_b128 v[162:165], v162 offset:3072
	s_add_u32 s36, s36, 0x40000
	s_addc_u32 s37, s37, 0
	s_mov_b32 m0, s45
	ds_read_b128 v[166:169], v148 offset:32768
	ds_read_b128 v[170:173], v148 offset:33792
	ds_read_b128 v[174:177], v148 offset:34816
	ds_read_b128 v[178:181], v148 offset:35840
	ds_read_b128 v[182:185], v148 offset:36864
	ds_read_b128 v[186:189], v148 offset:37888
	ds_read_b128 v[190:193], v148 offset:38912
	ds_read_b128 v[194:197], v148 offset:39936
	global_load_lds_dwordx4 v128, s[36:37]
	s_mov_b32 m0, s46
	s_nop 0
	global_load_lds_dwordx4 v132, s[36:37]
	s_waitcnt lgkmcnt(8)
	s_barrier
; #define PG8_STAGE(bufoff, gbase, voff) do { _Pragma("unroll") for (int _i = 0; _i < 2; ++_i) \
;         __builtin_amdgcn_global_load_lds((const unsigned*)((const char*)(gbase) + (voff)[_i]), (LAS unsigned*)(lds + (bufoff) + ldsw + _i * 8192), 16, 0, 0); } while (0)
; #define PG8_LDA(dst, b, h) do { _Pragma("unroll") for (int m = 0; m < 4; ++m) _Pragma("unroll") for (int k = 0; k < 2; ++k) dst[m][k] = *(const LAS bf16x8*)(lds + PG8_SA(b, h) + aoff + m * 2048 + k * 1024); } while (0)
; #define PG8_LDB(dst, b, h) do { _Pragma("unroll") for (int n = 0; n < 2; ++n) _Pragma("unroll") for (int k = 0; k < 2; ++k) dst[n][k] = *(const LAS bf16x8*)(lds + PG8_SB(b, h) + boff + n * 2048 + k * 1024); } while (0)
; #define PG8_MMA(ai, bj, At, Bt) do { __builtin_amdgcn_s_setprio(1); _Pragma("unroll") for (int m = 0; m < 4; ++m) _Pragma("unroll") for (int n = 0; n < 2; ++n) _Pragma("unroll") for (int k = 0; k < 2; ++k) \
;         acc[ai][bj][m][n] = __builtin_amdgcn_mfma_f32_16x16x32_bf16(Bt[n][k], At[m][k], acc[ai][bj][m][n], 0, 0, 0); __builtin_amdgcn_s_setprio(0); } while (0)
; #define PG8_WAIT_V(n) asm volatile("s_waitcnt vmcnt(" #n ")" ::: "memory")
; #define PG8_WAIT_L(n) asm volatile("s_waitcnt lgkmcnt(" #n ")" ::: "memory")
; #define PG8_BAR __builtin_amdgcn_s_barrier()
; #define PG8_SCHED __builtin_amdgcn_sched_barrier(0)
; template <class Epi, class Sched>
; __device__ __forceinline__ void gemm_phase(LAS unsigned char* lds, const Gemm g, const Sched& S, const Epi& E) {
;     ...
;             PG8_WAIT_L(8); PG8_BAR; PG8_WAIT_L(0); PG8_MMA(0, 0, At, B0); PG8_BAR; PG8_SCHED;
;             PG8_LDB(B1, 1, 1); PG8_STAGE(PG8_SB(1, 0), b3, voffB);
;             PG8_BAR; PG8_WAIT_L(0); PG8_MMA(0, 1, At, B1); PG8_BAR;
;             PG8_LDA(At, 1, 1); PG8_STAGE(PG8_SA(1, 0), a3, voffA);
;             PG8_BAR; PG8_WAIT_L(0); PG8_MMA(1, 0, At, B0); PG8_BAR; PG8_SCHED;
;             PG8_STAGE(PG8_SB(1, 1), b3 + hstep, voffB);
;             PG8_WAIT_V(6); PG8_BAR; PG8_MMA(1, 1, At, B1); PG8_BAR;
	s_waitcnt lgkmcnt(0)
	s_setprio 1
	s_waitcnt lgkmcnt(0)
	v_mfma_f32_16x16x32_bf16 v[124:127], v[150:153], v[166:169], v[124:127]
	v_mfma_f32_16x16x32_bf16 v[120:123], v[158:161], v[166:169], v[120:123]
	v_mfma_f32_16x16x32_bf16 v[116:119], v[150:153], v[174:177], v[116:119]
	v_mfma_f32_16x16x32_bf16 v[108:111], v[158:161], v[174:177], v[108:111]
	v_mfma_f32_16x16x32_bf16 v[100:103], v[150:153], v[182:185], v[100:103]
	v_mfma_f32_16x16x32_bf16 v[92:95], v[158:161], v[182:185], v[92:95]
	v_mfma_f32_16x16x32_bf16 v[84:87], v[150:153], v[190:193], v[84:87]
	v_mfma_f32_16x16x32_bf16 v[76:79], v[158:161], v[190:193], v[76:79]
	v_mfma_f32_16x16x32_bf16 v[124:127], v[154:157], v[170:173], v[124:127]
	v_mfma_f32_16x16x32_bf16 v[120:123], v[162:165], v[170:173], v[120:123]
	v_mfma_f32_16x16x32_bf16 v[116:119], v[154:157], v[178:181], v[116:119]
	v_mfma_f32_16x16x32_bf16 v[108:111], v[162:165], v[178:181], v[108:111]
	v_mfma_f32_16x16x32_bf16 v[100:103], v[154:157], v[186:189], v[100:103]
	v_mfma_f32_16x16x32_bf16 v[92:95], v[162:165], v[186:189], v[92:95]
	v_mfma_f32_16x16x32_bf16 v[84:87], v[154:157], v[194:197], v[84:87]
	v_mfma_f32_16x16x32_bf16 v[76:79], v[162:165], v[194:197], v[76:79]
	s_setprio 0
	s_barrier
	s_add_i32 s36, 0, 0x1c000
	s_add_i32 s37, s66, s43
	v_add_u32_e32 v214, s36, v146
	s_add_u32 s4, s34, 0x80
	s_addc_u32 s5, s35, 0
	s_mov_b32 m0, s37
	ds_read_b128 v[202:205], v214
	ds_read_b128 v[206:209], v214 offset:1024
	ds_read_b128 v[210:213], v214 offset:2048
	ds_read_b128 v[214:217], v214 offset:3072
	global_load_lds_dwordx4 v130, s[4:5]
	s_add_i32 m0, s37, 0x2000
	s_nop 0
	global_load_lds_dwordx4 v134, s[4:5]
	s_barrier
	s_waitcnt lgkmcnt(0)
	s_setprio 1
	s_waitcnt lgkmcnt(0)
	v_mfma_f32_16x16x32_bf16 v[112:115], v[202:205], v[166:169], v[112:115]
	v_mfma_f32_16x16x32_bf16 v[104:107], v[210:213], v[166:169], v[104:107]
	v_mfma_f32_16x16x32_bf16 v[96:99], v[202:205], v[174:177], v[96:99]
	v_mfma_f32_16x16x32_bf16 v[88:91], v[210:213], v[174:177], v[88:91]
	v_mfma_f32_16x16x32_bf16 v[80:83], v[202:205], v[182:185], v[80:83]
	v_mfma_f32_16x16x32_bf16 v[72:75], v[210:213], v[182:185], v[72:75]
	v_mfma_f32_16x16x32_bf16 v[68:71], v[202:205], v[190:193], v[68:71]
	v_mfma_f32_16x16x32_bf16 v[64:67], v[210:213], v[190:193], v[64:67]
	v_mfma_f32_16x16x32_bf16 v[112:115], v[206:209], v[170:173], v[112:115]
	v_mfma_f32_16x16x32_bf16 v[104:107], v[214:217], v[170:173], v[104:107]
	v_mfma_f32_16x16x32_bf16 v[96:99], v[206:209], v[178:181], v[96:99]
	v_mfma_f32_16x16x32_bf16 v[88:91], v[214:217], v[178:181], v[88:91]
	v_mfma_f32_16x16x32_bf16 v[80:83], v[206:209], v[186:189], v[80:83]
	v_mfma_f32_16x16x32_bf16 v[72:75], v[214:217], v[186:189], v[72:75]
	v_mfma_f32_16x16x32_bf16 v[68:71], v[206:209], v[194:197], v[68:71]
	v_mfma_f32_16x16x32_bf16 v[64:67], v[214:217], v[194:197], v[64:67]
	s_setprio 0
	s_mov_b32 m0, s51
	s_mov_b64 s[4:5], 0x80
	v_lshl_add_u64 v[198:199], v[220:221], 0, s[4:5]
	s_barrier
	ds_read_b128 v[166:169], v148 offset:49152
	ds_read_b128 v[170:173], v148 offset:50176
	ds_read_b128 v[174:177], v148 offset:51200
	ds_read_b128 v[178:181], v148 offset:52224
	ds_read_b128 v[182:185], v148 offset:53248
	ds_read_b128 v[186:189], v148 offset:54272
	ds_read_b128 v[190:193], v148 offset:55296
	ds_read_b128 v[194:197], v148 offset:56320
	global_load_lds_dwordx4 v[198:199], off
	v_lshl_add_u64 v[198:199], v[222:223], 0, s[4:5]
	s_mov_b32 m0, s52
	s_nop 0
	global_load_lds_dwordx4 v[198:199], off
	s_barrier
	s_waitcnt lgkmcnt(0)
	s_setprio 1
	s_waitcnt lgkmcnt(0)
	v_mfma_f32_16x16x32_bf16 v[60:63], v[150:153], v[166:169], v[60:63]
	v_mfma_f32_16x16x32_bf16 v[56:59], v[158:161], v[166:169], v[56:59]
	v_mfma_f32_16x16x32_bf16 v[52:55], v[150:153], v[174:177], v[52:55]
	v_mfma_f32_16x16x32_bf16 v[44:47], v[158:161], v[174:177], v[44:47]
	v_mfma_f32_16x16x32_bf16 v[36:39], v[150:153], v[182:185], v[36:39]
	v_mfma_f32_16x16x32_bf16 v[28:31], v[158:161], v[182:185], v[28:31]
	v_mfma_f32_16x16x32_bf16 v[20:23], v[150:153], v[190:193], v[20:23]
	v_mfma_f32_16x16x32_bf16 v[12:15], v[158:161], v[190:193], v[12:15]
	v_mfma_f32_16x16x32_bf16 v[60:63], v[154:157], v[170:173], v[60:63]
	v_mfma_f32_16x16x32_bf16 v[56:59], v[162:165], v[170:173], v[56:59]
	v_mfma_f32_16x16x32_bf16 v[52:55], v[154:157], v[178:181], v[52:55]
	v_mfma_f32_16x16x32_bf16 v[44:47], v[162:165], v[178:181], v[44:47]
	v_mfma_f32_16x16x32_bf16 v[36:39], v[154:157], v[186:189], v[36:39]
	v_mfma_f32_16x16x32_bf16 v[28:31], v[162:165], v[186:189], v[28:31]
	v_mfma_f32_16x16x32_bf16 v[20:23], v[154:157], v[194:197], v[20:23]
	v_mfma_f32_16x16x32_bf16 v[12:15], v[162:165], v[194:197], v[12:15]
	s_setprio 0
	s_barrier
	s_add_u32 s34, s34, 0x40080
	s_addc_u32 s35, s35, 0
	s_add_i32 s36, s36, s43
	s_mov_b32 m0, s36
	s_nop 0
	global_load_lds_dwordx4 v130, s[34:35]
	s_add_i32 m0, s36, 0x2000
	s_nop 0
	global_load_lds_dwordx4 v134, s[34:35]
	s_waitcnt vmcnt(6)
	s_barrier
; __device__ __forceinline__ unsigned cvt_pk_bf16(float lo, float hi) { unsigned r; asm volatile("v_cvt_pk_bf16_f32 %0, %1, %2" : "=v"(r) : "v"(lo), "v"(hi)); return r; }
; #define PG8_MMA(ai, bj, At, Bt) do { __builtin_amdgcn_s_setprio(1); _Pragma("unroll") for (int m = 0; m < 4; ++m) _Pragma("unroll") for (int n = 0; n < 2; ++n) _Pragma("unroll") for (int k = 0; k < 2; ++k) \
;         acc[ai][bj][m][n] = __builtin_amdgcn_mfma_f32_16x16x32_bf16(Bt[n][k], At[m][k], acc[ai][bj][m][n], 0, 0, 0); __builtin_amdgcn_s_setprio(0); } while (0)
; #define PG8_WAIT_V(n) asm volatile("s_waitcnt vmcnt(" #n ")" ::: "memory")
; #define PG8_BAR __builtin_amdgcn_s_barrier()
; template <class Epi, class Sched>
; __device__ __forceinline__ void gemm_phase(LAS unsigned char* lds, const Gemm g, const Sched& S, const Epi& E) {
;     ...
;             PG8_WAIT_V(6); PG8_BAR; PG8_MMA(1, 1, At, B1); PG8_BAR;
;         }
;         E(acc, cur, wr, wc, fr, fq);
;         if (!has_next) break;
; #pragma unroll
;         for (int a = 0; a < 2; ++a)
; #pragma unroll
;             for (int b = 0; b < 2; ++b)
; #pragma unroll
;                 for (int m = 0; m < 4; ++m)
; #pragma unroll
;                     for (int n = 0; n < 2; ++n) acc[a][b][m][n] = (f32x4){0.f, 0.f, 0.f, 0.f};
;         cur = nxt; cA = nA; cB = nB; ++ui;
;     }
;     PG8_WAIT_V(0);
;     if (wr == 0) PG8_BAR;
;     __device__ __forceinline__ void operator()(const AccT& acc, const Unit& u, int wr, int wc, int fr, int fq) const {
;     ...
; #pragma unroll
;         for (int ai = 0; ai < 2; ++ai)
; #pragma unroll
;             for (int m = 0; m < 4; ++m) {
;                 const int r = rbase + ai * 128 + m * 16;
; #pragma unroll
;                 for (int bj = 0; bj < 2; ++bj) {
;                     const int t0 = tb + bj * 128;
;                     const f32x4 v0 = acc[ai][bj][m][0], v1 = acc[ai][bj][m][1];
;                     u32x4 w; w.x = cvt_pk_bf16(v0[0], v0[1]); w.y = cvt_pk_bf16(v0[2], v0[3]); w.z = cvt_pk_bf16(v1[0], v1[1]); w.w = cvt_pk_bf16(v1[2], v1[3]);
;                     *(u32x4*)(VT + (size_t)r * NT + t0) = w;
;                 }
	s_setprio 1
	v_mfma_f32_16x16x32_bf16 v[48:51], v[202:205], v[166:169], v[48:51]
	v_mfma_f32_16x16x32_bf16 v[40:43], v[210:213], v[166:169], v[40:43]
	v_mfma_f32_16x16x32_bf16 v[32:35], v[202:205], v[174:177], v[32:35]
	v_mfma_f32_16x16x32_bf16 v[24:27], v[210:213], v[174:177], v[24:27]
	v_mfma_f32_16x16x32_bf16 v[16:19], v[202:205], v[182:185], v[16:19]
	v_mfma_f32_16x16x32_bf16 v[8:11], v[210:213], v[182:185], v[8:11]
	v_mfma_f32_16x16x32_bf16 v[4:7], v[202:205], v[190:193], v[4:7]
	v_mfma_f32_16x16x32_bf16 v[0:3], v[210:213], v[190:193], v[0:3]
	v_mfma_f32_16x16x32_bf16 v[48:51], v[206:209], v[170:173], v[48:51]
	v_mfma_f32_16x16x32_bf16 v[40:43], v[214:217], v[170:173], v[40:43]
	v_mfma_f32_16x16x32_bf16 v[32:35], v[206:209], v[178:181], v[32:35]
	v_mfma_f32_16x16x32_bf16 v[24:27], v[214:217], v[178:181], v[24:27]
	v_mfma_f32_16x16x32_bf16 v[16:19], v[206:209], v[186:189], v[16:19]
	v_mfma_f32_16x16x32_bf16 v[8:11], v[214:217], v[186:189], v[8:11]
	v_mfma_f32_16x16x32_bf16 v[4:7], v[206:209], v[194:197], v[4:7]
	v_mfma_f32_16x16x32_bf16 v[0:3], v[214:217], v[194:197], v[0:3]
	s_setprio 0
	s_add_i32 s65, s65, 2
	s_add_u32 s30, s30, 0x100
	s_addc_u32 s31, s31, 0
	s_add_u32 s63, s63, 0x100
	s_addc_u32 s64, s64, 0
	s_cmp_gt_u32 s65, 13
	s_barrier
	s_cbranch_scc0 .LBB0_633
	v_mov_b32_e32 v150, v144
	v_mov_b32_e32 v151, v145
	s_lshl_b32 s21, s28, 8
	s_add_i32 s21, s21, s48
	v_add_u32_e32 v150, s21, v150
	s_lshl_b32 s21, s60, 8
	s_or_b32 s21, s21, s49
	v_lshl_add_u32 v152, v151, 3, s21
	v_ashrrev_i32_e32 v151, 31, v150
	v_cvt_pk_bf16_f32 v124, v124, v125
	v_cvt_pk_bf16_f32 v125, v126, v127
	v_cvt_pk_bf16_f32 v126, v120, v121
	v_lshlrev_b64 v[120:121], 17, v[150:151]
	v_lshl_add_u64 v[120:121], s[0:1], 0, v[120:121]
	v_ashrrev_i32_e32 v153, 31, v152
	v_lshl_add_u64 v[120:121], v[152:153], 1, v[120:121]
	s_mov_b32 s21, 0x200000
	v_cvt_pk_bf16_f32 v127, v122, v123
	global_store_dwordx4 v[120:121], v[124:127], off
	v_cvt_pk_bf16_f32 v112, v112, v113
	v_cvt_pk_bf16_f32 v113, v114, v115
	v_cvt_pk_bf16_f32 v114, v104, v105
	v_cvt_pk_bf16_f32 v115, v106, v107
	global_store_dwordx4 v[120:121], v[112:115], off offset:256
	v_cvt_pk_bf16_f32 v104, v116, v117
	v_cvt_pk_bf16_f32 v105, v118, v119
	v_cvt_pk_bf16_f32 v106, v108, v109
	v_cvt_pk_bf16_f32 v107, v110, v111
	s_mov_b64 s[30:31], 0x200000
	v_add_co_u32_e32 v110, vcc, s21, v120
	v_lshl_add_u64 v[108:109], v[120:121], 0, s[30:31]
	s_nop 0
	v_addc_co_u32_e32 v111, vcc, 0, v121, vcc
	s_mov_b32 s21, 0x400000
	global_store_dwordx4 v[110:111], v[104:107], off
	v_cvt_pk_bf16_f32 v96, v96, v97
	v_cvt_pk_bf16_f32 v97, v98, v99
	v_cvt_pk_bf16_f32 v98, v88, v89
	v_cvt_pk_bf16_f32 v99, v90, v91
	global_store_dwordx4 v[108:109], v[96:99], off offset:256
	v_cvt_pk_bf16_f32 v88, v100, v101
	v_cvt_pk_bf16_f32 v89, v102, v103
	v_cvt_pk_bf16_f32 v90, v92, v93
	v_cvt_pk_bf16_f32 v91, v94, v95
	s_mov_b64 s[30:31], 0x400000
	v_add_co_u32_e32 v94, vcc, s21, v120
	v_lshl_add_u64 v[92:93], v[120:121], 0, s[30:31]
	s_nop 0
	v_addc_co_u32_e32 v95, vcc, 0, v121, vcc
	s_mov_b32 s21, 0x600000
	global_store_dwordx4 v[94:95], v[88:91], off
	v_cvt_pk_bf16_f32 v80, v80, v81
	v_cvt_pk_bf16_f32 v81, v82, v83
	v_cvt_pk_bf16_f32 v82, v72, v73
	v_cvt_pk_bf16_f32 v83, v74, v75
	global_store_dwordx4 v[92:93], v[80:83], off offset:256
	v_cvt_pk_bf16_f32 v72, v84, v85
	v_cvt_pk_bf16_f32 v73, v86, v87
	v_cvt_pk_bf16_f32 v74, v76, v77
	v_cvt_pk_bf16_f32 v75, v78, v79
	s_mov_b64 s[30:31], 0x600000
	v_add_co_u32_e32 v78, vcc, s21, v120
	v_lshl_add_u64 v[76:77], v[120:121], 0, s[30:31]
	s_nop 0
	v_addc_co_u32_e32 v79, vcc, 0, v121, vcc
	global_store_dwordx4 v[78:79], v[72:75], off
	v_cvt_pk_bf16_f32 v68, v68, v69
	v_cvt_pk_bf16_f32 v69, v70, v71
	v_cvt_pk_bf16_f32 v70, v64, v65
	v_cvt_pk_bf16_f32 v71, v66, v67
	global_store_dwordx4 v[76:77], v[68:71], off offset:256
	v_cvt_pk_bf16_f32 v60, v60, v61
	v_cvt_pk_bf16_f32 v61, v62, v63
	v_cvt_pk_bf16_f32 v62, v56, v57
	v_cvt_pk_bf16_f32 v63, v58, v59
	s_mov_b64 s[30:31], 0x1000000
	v_add_co_u32_e32 v58, vcc, s56, v120
	v_lshl_add_u64 v[56:57], v[120:121], 0, s[30:31]
	s_nop 0
	v_addc_co_u32_e32 v59, vcc, 0, v121, vcc
	global_store_dwordx4 v[58:59], v[60:63], off
	v_cvt_pk_bf16_f32 v48, v48, v49
	v_cvt_pk_bf16_f32 v49, v50, v51
	v_cvt_pk_bf16_f32 v50, v40, v41
	v_cvt_pk_bf16_f32 v51, v42, v43
	global_store_dwordx4 v[56:57], v[48:51], off offset:256
	v_cvt_pk_bf16_f32 v40, v52, v53
	v_cvt_pk_bf16_f32 v41, v54, v55
	v_cvt_pk_bf16_f32 v42, v44, v45
	v_cvt_pk_bf16_f32 v43, v46, v47
	v_add_co_u32_e32 v46, vcc, s57, v120
	v_lshl_add_u64 v[44:45], v[120:121], 0, s[6:7]
	s_nop 0
	v_addc_co_u32_e32 v47, vcc, 0, v121, vcc
	global_store_dwordx4 v[46:47], v[40:43], off
	v_cvt_pk_bf16_f32 v32, v32, v33
	v_cvt_pk_bf16_f32 v33, v34, v35
	v_cvt_pk_bf16_f32 v34, v24, v25
	v_cvt_pk_bf16_f32 v35, v26, v27
	global_store_dwordx4 v[44:45], v[32:35], off offset:256
	v_cvt_pk_bf16_f32 v24, v36, v37
	v_cvt_pk_bf16_f32 v25, v38, v39
	v_cvt_pk_bf16_f32 v26, v28, v29
	v_cvt_pk_bf16_f32 v27, v30, v31
	v_add_co_u32_e32 v30, vcc, s58, v120
	v_lshl_add_u64 v[28:29], v[120:121], 0, s[8:9]
	s_nop 0
	v_addc_co_u32_e32 v31, vcc, 0, v121, vcc
	global_store_dwordx4 v[30:31], v[24:27], off
	v_cvt_pk_bf16_f32 v16, v16, v17
	v_cvt_pk_bf16_f32 v17, v18, v19
	v_cvt_pk_bf16_f32 v18, v8, v9
	v_cvt_pk_bf16_f32 v19, v10, v11
	global_store_dwordx4 v[28:29], v[16:19], off offset:256
	v_cvt_pk_bf16_f32 v8, v20, v21
	v_cvt_pk_bf16_f32 v9, v22, v23
	v_cvt_pk_bf16_f32 v10, v12, v13
	v_cvt_pk_bf16_f32 v11, v14, v15
	v_add_co_u32_e32 v14, vcc, s59, v120
	v_lshl_add_u64 v[12:13], v[120:121], 0, s[16:17]
	s_nop 0
	v_addc_co_u32_e32 v15, vcc, 0, v121, vcc
	s_and_b64 vcc, exec, s[2:3]
	s_mov_b32 s60, s20
	s_mov_b32 s28, s22
	s_mov_b64 s[34:35], s[26:27]
	s_mov_b64 s[30:31], s[24:25]
	global_store_dwordx4 v[14:15], v[8:11], off
	v_cvt_pk_bf16_f32 v4, v4, v5
	v_cvt_pk_bf16_f32 v5, v6, v7
	v_cvt_pk_bf16_f32 v6, v0, v1
	v_cvt_pk_bf16_f32 v7, v2, v3
	global_store_dwordx4 v[12:13], v[4:7], off offset:256
	s_cbranch_vccz .LBB0_626
	s_waitcnt vmcnt(0)
	s_cmpk_gt_u32 s33, 0xff
	s_cbranch_scc1 .LBB0_637
	s_barrier

; #define PG8_STAGE(bufoff, gbase, voff) do { _Pragma("unroll") for (int _i = 0; _i < 2; ++_i) \
;         __builtin_amdgcn_global_load_lds((const unsigned*)((const char*)(gbase) + (voff)[_i]), (LAS unsigned*)(lds + (bufoff) + ldsw + _i * 8192), 16, 0, 0); } while (0)
; #define PG8_LDA(dst, b, h) do { _Pragma("unroll") for (int m = 0; m < 4; ++m) _Pragma("unroll") for (int k = 0; k < 2; ++k) dst[m][k] = *(const LAS bf16x8*)(lds + PG8_SA(b, h) + aoff + m * 2048 + k * 1024); } while (0)
; #define PG8_LDB(dst, b, h) do { _Pragma("unroll") for (int n = 0; n < 2; ++n) _Pragma("unroll") for (int k = 0; k < 2; ++k) dst[n][k] = *(const LAS bf16x8*)(lds + PG8_SB(b, h) + boff + n * 2048 + k * 1024); } while (0)
; #define PG8_MMA(ai, bj, At, Bt) do { __builtin_amdgcn_s_setprio(1); _Pragma("unroll") for (int m = 0; m < 4; ++m) _Pragma("unroll") for (int n = 0; n < 2; ++n) _Pragma("unroll") for (int k = 0; k < 2; ++k) \
;         acc[ai][bj][m][n] = __builtin_amdgcn_mfma_f32_16x16x32_bf16(Bt[n][k], At[m][k], acc[ai][bj][m][n], 0, 0, 0); __builtin_amdgcn_s_setprio(0); } while (0)
; #define PG8_WAIT_L(n) asm volatile("s_waitcnt lgkmcnt(" #n ")" ::: "memory")
; template <class Epi, class Sched>
; __device__ __forceinline__ void gemm_phase(LAS unsigned char* lds, const Gemm g, const Sched& S, const Epi& E) {
;     ...
;         const bool has_next = S.next(ui + 1, nxt);
;         const char* nA = has_next ? (const char*)g.A + (size_t)nxt.pm * tstep : cA; const char* nB = has_next ? (const char*)g.Bt + (size_t)nxt.pn * tstep : cB;
;         for (int t = 0; t < nt; t += 2) {
;             const bool last = (t == nt - 2);
;             const char* a1 = cA + (size_t)(t + 1) * kstep;
;             const char* a2 = last ? nA : cA + (size_t)(t + 2) * kstep; const char* b2 = last ? nB : cB + (size_t)(t + 2) * kstep;
;             const char* a3 = a2 + kstep; const char* b3 = b2 + kstep;
;             PG8_LDB(B0, 0, 0); PG8_SCHED; PG8_LDA(At, 0, 0); PG8_STAGE(PG8_SA(1, 1), a1 + hstep, voffA);
;             PG8_WAIT_L(8); PG8_BAR; PG8_WAIT_L(0); PG8_MMA(0, 0, At, B0); PG8_BAR; PG8_SCHED;
;             PG8_LDB(B1, 0, 1); PG8_STAGE(PG8_SB(0, 0), b2, voffB);
;             PG8_BAR; PG8_WAIT_L(0); PG8_MMA(0, 1, At, B1); PG8_BAR;
;             PG8_LDA(At, 0, 1); PG8_STAGE(PG8_SA(0, 0), a2, voffA);
;             PG8_BAR; PG8_WAIT_L(0); PG8_MMA(1, 0, At, B0); PG8_BAR; PG8_SCHED;
.LBB0_652:
	s_ashr_i32 s9, s8, 31
	v_cmp_lt_i64_e32 vcc, s[16:17], v[142:143]
	s_lshl_b64 s[16:17], s[8:9], 19
	s_add_u32 s16, s14, s16
	s_addc_u32 s17, s15, s17
	s_and_b64 s[18:19], vcc, exec
	s_cselect_b32 s9, s17, s23
	s_cselect_b32 s48, s16, s22
	s_ashr_i32 s7, s6, 31
	s_lshl_b64 s[18:19], s[6:7], 19
	s_add_u32 s18, s12, s18
	s_addc_u32 s19, s13, s19
	s_and_b64 s[26:27], vcc, exec
	s_cselect_b32 s7, s19, s25
	s_cselect_b32 s49, s18, s24
	s_add_u32 s22, s22, 0x40080
	s_addc_u32 s23, s23, 0
	s_add_u32 s51, s24, 0x100
	s_addc_u32 s52, s25, 0
	s_mov_b32 s53, -2
	s_waitcnt lgkmcnt(0)
	ds_read_b128 v[152:155], v149
	ds_read_b128 v[156:159], v149 offset:1024
	ds_read_b128 v[160:163], v149 offset:2048
	ds_read_b128 v[164:167], v149 offset:3072
	s_add_u32 s24, s22, 0xfffc0080
	s_addc_u32 s25, s23, -1
	s_cmp_eq_u32 s53, 12
	s_cselect_b32 s27, s9, s25
	s_cselect_b32 s26, s48, s24
	s_cselect_b32 s25, s7, s52
	s_cselect_b32 s24, s49, s51
	s_add_i32 m0, s21, 0xc000
	ds_read_b128 v[168:171], v150
	ds_read_b128 v[172:175], v150 offset:1024
	ds_read_b128 v[176:179], v150 offset:2048
	ds_read_b128 v[180:183], v150 offset:3072
	ds_read_b128 v[184:187], v150 offset:4096
	ds_read_b128 v[188:191], v150 offset:5120
	ds_read_b128 v[192:195], v150 offset:6144
	ds_read_b128 v[196:199], v150 offset:7168
	global_load_lds_dwordx4 v138, s[22:23]
	s_add_i32 m0, s21, 0xe000
	s_nop 0
	global_load_lds_dwordx4 v140, s[22:23]
	s_waitcnt lgkmcnt(8)
	s_barrier
	s_waitcnt lgkmcnt(0)
	s_setprio 1
	s_waitcnt lgkmcnt(0)
	v_mfma_f32_16x16x32_bf16 v[124:127], v[152:155], v[168:171], 0
	v_mfma_f32_16x16x32_bf16 v[120:123], v[160:163], v[168:171], 0
	v_mfma_f32_16x16x32_bf16 v[112:115], v[152:155], v[176:179], 0
	v_mfma_f32_16x16x32_bf16 v[104:107], v[160:163], v[176:179], 0
	v_mfma_f32_16x16x32_bf16 v[96:99], v[152:155], v[184:187], 0
	v_mfma_f32_16x16x32_bf16 v[88:91], v[160:163], v[184:187], 0
	v_mfma_f32_16x16x32_bf16 v[80:83], v[152:155], v[192:195], 0
	v_mfma_f32_16x16x32_bf16 v[72:75], v[160:163], v[192:195], 0
	v_mfma_f32_16x16x32_bf16 v[124:127], v[156:159], v[172:175], v[124:127]
	v_mfma_f32_16x16x32_bf16 v[120:123], v[164:167], v[172:175], v[120:123]
	v_mfma_f32_16x16x32_bf16 v[112:115], v[156:159], v[180:183], v[112:115]
	v_mfma_f32_16x16x32_bf16 v[104:107], v[164:167], v[180:183], v[104:107]
	v_mfma_f32_16x16x32_bf16 v[96:99], v[156:159], v[188:191], v[96:99]
	v_mfma_f32_16x16x32_bf16 v[88:91], v[164:167], v[188:191], v[88:91]
	v_mfma_f32_16x16x32_bf16 v[80:83], v[156:159], v[196:199], v[80:83]
	v_mfma_f32_16x16x32_bf16 v[72:75], v[164:167], v[196:199], v[72:75]
	s_setprio 0
	s_barrier
	s_add_i32 s54, s45, s30
	s_mov_b32 m0, s54
	ds_read_b128 v[202:205], v151
	ds_read_b128 v[206:209], v151 offset:1024
	ds_read_b128 v[210:213], v151 offset:2048
	ds_read_b128 v[214:217], v151 offset:3072
	global_load_lds_dwordx4 v130, s[24:25]
	s_add_i32 m0, s54, 0x2000
	s_nop 0
	global_load_lds_dwordx4 v134, s[24:25]
	s_barrier
	s_waitcnt lgkmcnt(0)
	s_setprio 1
	s_waitcnt lgkmcnt(0)
	v_mfma_f32_16x16x32_bf16 v[116:119], v[202:205], v[168:171], 0
	v_mfma_f32_16x16x32_bf16 v[108:111], v[210:213], v[168:171], 0
	v_mfma_f32_16x16x32_bf16 v[100:103], v[202:205], v[176:179], 0
	v_mfma_f32_16x16x32_bf16 v[92:95], v[210:213], v[176:179], 0
	v_mfma_f32_16x16x32_bf16 v[84:87], v[202:205], v[184:187], 0
	v_mfma_f32_16x16x32_bf16 v[76:79], v[210:213], v[184:187], 0
	v_mfma_f32_16x16x32_bf16 v[68:71], v[202:205], v[192:195], 0
	v_mfma_f32_16x16x32_bf16 v[64:67], v[210:213], v[192:195], 0
	v_mfma_f32_16x16x32_bf16 v[116:119], v[206:209], v[172:175], v[116:119]
	v_mfma_f32_16x16x32_bf16 v[108:111], v[214:217], v[172:175], v[108:111]
	v_mfma_f32_16x16x32_bf16 v[100:103], v[206:209], v[180:183], v[100:103]
	v_mfma_f32_16x16x32_bf16 v[92:95], v[214:217], v[180:183], v[92:95]
	v_mfma_f32_16x16x32_bf16 v[84:87], v[206:209], v[188:191], v[84:87]
	v_mfma_f32_16x16x32_bf16 v[76:79], v[214:217], v[188:191], v[76:79]
	v_mfma_f32_16x16x32_bf16 v[68:71], v[206:209], v[196:199], v[68:71]
	v_mfma_f32_16x16x32_bf16 v[64:67], v[214:217], v[196:199], v[64:67]
	s_setprio 0
	s_mov_b32 m0, s21
	v_lshl_add_u64 v[222:223], s[26:27], 0, v[128:129]
	s_barrier
	ds_read_b128 v[168:171], v150 offset:16384
	ds_read_b128 v[172:175], v150 offset:17408
	ds_read_b128 v[176:179], v150 offset:18432
	ds_read_b128 v[180:183], v150 offset:19456
	ds_read_b128 v[184:187], v150 offset:20480
	ds_read_b128 v[188:191], v150 offset:21504
	ds_read_b128 v[192:195], v150 offset:22528
	ds_read_b128 v[196:199], v150 offset:23552
	global_load_lds_dwordx4 v128, s[26:27]
	v_lshl_add_u64 v[224:225], s[26:27], 0, v[132:133]
	s_mov_b32 m0, s31
	s_nop 0
	global_load_lds_dwordx4 v132, s[26:27]
	s_barrier
	s_waitcnt lgkmcnt(0)
	s_setprio 1
	s_waitcnt lgkmcnt(0)
	v_mfma_f32_16x16x32_bf16 v[60:63], v[152:155], v[168:171], 0
	v_mfma_f32_16x16x32_bf16 v[56:59], v[160:163], v[168:171], 0
	v_mfma_f32_16x16x32_bf16 v[48:51], v[152:155], v[176:179], 0
	v_mfma_f32_16x16x32_bf16 v[40:43], v[160:163], v[176:179], 0
	v_mfma_f32_16x16x32_bf16 v[32:35], v[152:155], v[184:187], 0
	v_mfma_f32_16x16x32_bf16 v[24:27], v[160:163], v[184:187], 0
	v_mfma_f32_16x16x32_bf16 v[16:19], v[152:155], v[192:195], 0
	v_mfma_f32_16x16x32_bf16 v[8:11], v[160:163], v[192:195], 0
	v_mfma_f32_16x16x32_bf16 v[60:63], v[156:159], v[172:175], v[60:63]
	v_mfma_f32_16x16x32_bf16 v[56:59], v[164:167], v[172:175], v[56:59]
	v_mfma_f32_16x16x32_bf16 v[48:51], v[156:159], v[180:183], v[48:51]
	v_mfma_f32_16x16x32_bf16 v[40:43], v[164:167], v[180:183], v[40:43]
	v_mfma_f32_16x16x32_bf16 v[32:35], v[156:159], v[188:191], v[32:35]
	v_mfma_f32_16x16x32_bf16 v[24:27], v[164:167], v[188:191], v[24:27]
	v_mfma_f32_16x16x32_bf16 v[16:19], v[156:159], v[196:199], v[16:19]
	v_mfma_f32_16x16x32_bf16 v[8:11], v[164:167], v[196:199], v[8:11]
	s_setprio 0
	s_barrier
; #define PG8_STAGE(bufoff, gbase, voff) do { _Pragma("unroll") for (int _i = 0; _i < 2; ++_i) \
;         __builtin_amdgcn_global_load_lds((const unsigned*)((const char*)(gbase) + (voff)[_i]), (LAS unsigned*)(lds + (bufoff) + ldsw + _i * 8192), 16, 0, 0); } while (0)
; #define PG8_LDA(dst, b, h) do { _Pragma("unroll") for (int m = 0; m < 4; ++m) _Pragma("unroll") for (int k = 0; k < 2; ++k) dst[m][k] = *(const LAS bf16x8*)(lds + PG8_SA(b, h) + aoff + m * 2048 + k * 1024); } while (0)
; #define PG8_LDB(dst, b, h) do { _Pragma("unroll") for (int n = 0; n < 2; ++n) _Pragma("unroll") for (int k = 0; k < 2; ++k) dst[n][k] = *(const LAS bf16x8*)(lds + PG8_SB(b, h) + boff + n * 2048 + k * 1024); } while (0)
; #define PG8_MMA(ai, bj, At, Bt) do { __builtin_amdgcn_s_setprio(1); _Pragma("unroll") for (int m = 0; m < 4; ++m) _Pragma("unroll") for (int n = 0; n < 2; ++n) _Pragma("unroll") for (int k = 0; k < 2; ++k) \
;         acc[ai][bj][m][n] = __builtin_amdgcn_mfma_f32_16x16x32_bf16(Bt[n][k], At[m][k], acc[ai][bj][m][n], 0, 0, 0); __builtin_amdgcn_s_setprio(0); } while (0)
; #define PG8_WAIT_V(n) asm volatile("s_waitcnt vmcnt(" #n ")" ::: "memory")
; #define PG8_WAIT_L(n) asm volatile("s_waitcnt lgkmcnt(" #n ")" ::: "memory")
; #define PG8_BAR __builtin_amdgcn_s_barrier()
; #define PG8_SCHED __builtin_amdgcn_sched_barrier(0)
; template <class Epi, class Sched>
; __device__ __forceinline__ void gemm_phase(LAS unsigned char* lds, const Gemm g, const Sched& S, const Epi& E) {
;     ...
;             PG8_STAGE(PG8_SB(0, 1), b2 + hstep, voffB);
;             PG8_WAIT_V(6); PG8_BAR; PG8_MMA(1, 1, At, B1); PG8_BAR;
;             PG8_LDB(B0, 1, 0); PG8_SCHED; PG8_LDA(At, 1, 0); PG8_STAGE(PG8_SA(0, 1), a2 + hstep, voffA);
;             PG8_WAIT_L(8); PG8_BAR; PG8_WAIT_L(0); PG8_MMA(0, 0, At, B0); PG8_BAR; PG8_SCHED;
;             PG8_LDB(B1, 1, 1); PG8_STAGE(PG8_SB(1, 0), b3, voffB);
;             PG8_BAR; PG8_WAIT_L(0); PG8_MMA(0, 1, At, B1); PG8_BAR;
;             PG8_LDA(At, 1, 1); PG8_STAGE(PG8_SA(1, 0), a3, voffA);
	s_add_u32 s54, s24, 0x40000
	s_addc_u32 s55, s25, 0
	s_add_i32 s56, s46, s30
	s_mov_b32 m0, s56
	s_nop 0
	global_load_lds_dwordx4 v130, s[54:55]
	s_add_i32 m0, s56, 0x2000
	s_nop 0
	global_load_lds_dwordx4 v134, s[54:55]
	s_waitcnt vmcnt(6)
	s_barrier
	s_setprio 1
	v_mfma_f32_16x16x32_bf16 v[52:55], v[202:205], v[168:171], 0
	v_mfma_f32_16x16x32_bf16 v[44:47], v[210:213], v[168:171], 0
	v_mfma_f32_16x16x32_bf16 v[36:39], v[202:205], v[176:179], 0
	v_mfma_f32_16x16x32_bf16 v[28:31], v[210:213], v[176:179], 0
	v_mfma_f32_16x16x32_bf16 v[20:23], v[202:205], v[184:187], 0
	v_mfma_f32_16x16x32_bf16 v[12:15], v[210:213], v[184:187], 0
	v_mfma_f32_16x16x32_bf16 v[4:7], v[202:205], v[192:195], 0
	v_mfma_f32_16x16x32_bf16 v[0:3], v[210:213], v[192:195], 0
	v_mfma_f32_16x16x32_bf16 v[52:55], v[206:209], v[172:175], v[52:55]
	v_mfma_f32_16x16x32_bf16 v[44:47], v[214:217], v[172:175], v[44:47]
	v_mfma_f32_16x16x32_bf16 v[36:39], v[206:209], v[180:183], v[36:39]
	v_mfma_f32_16x16x32_bf16 v[28:31], v[214:217], v[180:183], v[28:31]
	v_mfma_f32_16x16x32_bf16 v[20:23], v[206:209], v[188:191], v[20:23]
	v_mfma_f32_16x16x32_bf16 v[12:15], v[214:217], v[188:191], v[12:15]
	v_mfma_f32_16x16x32_bf16 v[4:7], v[206:209], v[196:199], v[4:7]
	v_mfma_f32_16x16x32_bf16 v[0:3], v[214:217], v[196:199], v[0:3]
	s_setprio 0
	s_add_i32 s54, 0, 0x18000
	v_add_u32_e32 v136, s54, v148
	s_barrier
	ds_read_b128 v[152:155], v136
	ds_read_b128 v[156:159], v136 offset:1024
	ds_read_b128 v[160:163], v136 offset:2048
	ds_read_b128 v[164:167], v136 offset:3072
	s_add_u32 s26, s26, 0x40000
	s_addc_u32 s27, s27, 0
	s_mov_b32 m0, s33
	ds_read_b128 v[168:171], v150 offset:32768
	ds_read_b128 v[172:175], v150 offset:33792
	ds_read_b128 v[176:179], v150 offset:34816
	ds_read_b128 v[180:183], v150 offset:35840
	ds_read_b128 v[184:187], v150 offset:36864
	ds_read_b128 v[188:191], v150 offset:37888
	ds_read_b128 v[192:195], v150 offset:38912
	ds_read_b128 v[196:199], v150 offset:39936
	global_load_lds_dwordx4 v128, s[26:27]
	s_mov_b32 m0, s34
	s_nop 0
	global_load_lds_dwordx4 v132, s[26:27]
	s_waitcnt lgkmcnt(8)
	s_barrier
	s_waitcnt lgkmcnt(0)
	s_setprio 1
	s_waitcnt lgkmcnt(0)
	v_mfma_f32_16x16x32_bf16 v[124:127], v[152:155], v[168:171], v[124:127]
	v_mfma_f32_16x16x32_bf16 v[120:123], v[160:163], v[168:171], v[120:123]
	v_mfma_f32_16x16x32_bf16 v[112:115], v[152:155], v[176:179], v[112:115]
	v_mfma_f32_16x16x32_bf16 v[104:107], v[160:163], v[176:179], v[104:107]
	v_mfma_f32_16x16x32_bf16 v[96:99], v[152:155], v[184:187], v[96:99]
	v_mfma_f32_16x16x32_bf16 v[88:91], v[160:163], v[184:187], v[88:91]
	v_mfma_f32_16x16x32_bf16 v[80:83], v[152:155], v[192:195], v[80:83]
	v_mfma_f32_16x16x32_bf16 v[72:75], v[160:163], v[192:195], v[72:75]
	v_mfma_f32_16x16x32_bf16 v[124:127], v[156:159], v[172:175], v[124:127]
	v_mfma_f32_16x16x32_bf16 v[120:123], v[164:167], v[172:175], v[120:123]
	v_mfma_f32_16x16x32_bf16 v[112:115], v[156:159], v[180:183], v[112:115]
	v_mfma_f32_16x16x32_bf16 v[104:107], v[164:167], v[180:183], v[104:107]
	v_mfma_f32_16x16x32_bf16 v[96:99], v[156:159], v[188:191], v[96:99]
	v_mfma_f32_16x16x32_bf16 v[88:91], v[164:167], v[188:191], v[88:91]
	v_mfma_f32_16x16x32_bf16 v[80:83], v[156:159], v[196:199], v[80:83]
	v_mfma_f32_16x16x32_bf16 v[72:75], v[164:167], v[196:199], v[72:75]
	s_setprio 0
	s_barrier
	s_add_i32 s26, 0, 0x1c000
	s_add_i32 s27, s54, s30
	v_add_u32_e32 v136, s26, v148
	s_add_u32 s0, s24, 0x80
	s_addc_u32 s1, s25, 0
	s_mov_b32 m0, s27
	ds_read_b128 v[202:205], v136
	ds_read_b128 v[206:209], v136 offset:1024
	ds_read_b128 v[210:213], v136 offset:2048
	ds_read_b128 v[214:217], v136 offset:3072
	global_load_lds_dwordx4 v130, s[0:1]
	s_add_i32 m0, s27, 0x2000
	s_nop 0
	global_load_lds_dwordx4 v134, s[0:1]
	s_barrier
	s_waitcnt lgkmcnt(0)
	s_setprio 1
	s_waitcnt lgkmcnt(0)
	v_mfma_f32_16x16x32_bf16 v[116:119], v[202:205], v[168:171], v[116:119]
	v_mfma_f32_16x16x32_bf16 v[108:111], v[210:213], v[168:171], v[108:111]
	v_mfma_f32_16x16x32_bf16 v[100:103], v[202:205], v[176:179], v[100:103]
	v_mfma_f32_16x16x32_bf16 v[92:95], v[210:213], v[176:179], v[92:95]
	v_mfma_f32_16x16x32_bf16 v[84:87], v[202:205], v[184:187], v[84:87]
	v_mfma_f32_16x16x32_bf16 v[76:79], v[210:213], v[184:187], v[76:79]
	v_mfma_f32_16x16x32_bf16 v[68:71], v[202:205], v[192:195], v[68:71]
	v_mfma_f32_16x16x32_bf16 v[64:67], v[210:213], v[192:195], v[64:67]
	v_mfma_f32_16x16x32_bf16 v[116:119], v[206:209], v[172:175], v[116:119]
	v_mfma_f32_16x16x32_bf16 v[108:111], v[214:217], v[172:175], v[108:111]
	v_mfma_f32_16x16x32_bf16 v[100:103], v[206:209], v[180:183], v[100:103]
	v_mfma_f32_16x16x32_bf16 v[92:95], v[214:217], v[180:183], v[92:95]
	v_mfma_f32_16x16x32_bf16 v[84:87], v[206:209], v[188:191], v[84:87]
	v_mfma_f32_16x16x32_bf16 v[76:79], v[214:217], v[188:191], v[76:79]
	v_mfma_f32_16x16x32_bf16 v[68:71], v[206:209], v[196:199], v[68:71]
	v_mfma_f32_16x16x32_bf16 v[64:67], v[214:217], v[196:199], v[64:67]
	s_setprio 0
	s_mov_b32 m0, s42
	s_mov_b64 s[0:1], 0x80
	v_lshl_add_u64 v[218:219], v[222:223], 0, s[0:1]
	s_barrier
	ds_read_b128 v[168:171], v150 offset:49152
	ds_read_b128 v[172:175], v150 offset:50176
	ds_read_b128 v[176:179], v150 offset:51200
	ds_read_b128 v[180:183], v150 offset:52224
	ds_read_b128 v[184:187], v150 offset:53248
	ds_read_b128 v[188:191], v150 offset:54272
	ds_read_b128 v[192:195], v150 offset:55296
	ds_read_b128 v[196:199], v150 offset:56320
	global_load_lds_dwordx4 v[218:219], off
	v_lshl_add_u64 v[218:219], v[224:225], 0, s[0:1]
	s_mov_b32 m0, s43
	s_nop 0
	global_load_lds_dwordx4 v[218:219], off
	s_barrier
; #define PG8_STAGE(bufoff, gbase, voff) do { _Pragma("unroll") for (int _i = 0; _i < 2; ++_i) \
;         __builtin_amdgcn_global_load_lds((const unsigned*)((const char*)(gbase) + (voff)[_i]), (LAS unsigned*)(lds + (bufoff) + ldsw + _i * 8192), 16, 0, 0); } while (0)
; #define PG8_LDA(dst, b, h) do { _Pragma("unroll") for (int m = 0; m < 4; ++m) _Pragma("unroll") for (int k = 0; k < 2; ++k) dst[m][k] = *(const LAS bf16x8*)(lds + PG8_SA(b, h) + aoff + m * 2048 + k * 1024); } while (0)
; #define PG8_WAIT_V(n) asm volatile("s_waitcnt vmcnt(" #n ")" ::: "memory")
; #define PG8_WAIT_L(n) asm volatile("s_waitcnt lgkmcnt(" #n ")" ::: "memory")
; template <class Epi, class Sched>
; __device__ __forceinline__ void gemm_phase(LAS unsigned char* lds, const Gemm g, const Sched& S, const Epi& E) {
;     ...
;         for (int t = 0; t < nt; t += 2) {
;             const bool last = (t == nt - 2);
;             const char* a1 = cA + (size_t)(t + 1) * kstep;
;             const char* a2 = last ? nA : cA + (size_t)(t + 2) * kstep; const char* b2 = last ? nB : cB + (size_t)(t + 2) * kstep;
;             const char* a3 = a2 + kstep; const char* b3 = b2 + kstep;
;             PG8_LDB(B0, 0, 0); PG8_SCHED; PG8_LDA(At, 0, 0); PG8_STAGE(PG8_SA(1, 1), a1 + hstep, voffA);
;             PG8_WAIT_L(8); PG8_BAR; PG8_WAIT_L(0); PG8_MMA(0, 0, At, B0); PG8_BAR; PG8_SCHED;
;             PG8_LDB(B1, 0, 1); PG8_STAGE(PG8_SB(0, 0), b2, voffB);
;             PG8_BAR; PG8_WAIT_L(0); PG8_MMA(0, 1, At, B1); PG8_BAR;
;             PG8_LDA(At, 0, 1); PG8_STAGE(PG8_SA(0, 0), a2, voffA);
;             PG8_BAR; PG8_WAIT_L(0); PG8_MMA(1, 0, At, B0); PG8_BAR; PG8_SCHED;
;             PG8_STAGE(PG8_SB(0, 1), b2 + hstep, voffB);
;             PG8_WAIT_V(6); PG8_BAR; PG8_MMA(1, 1, At, B1); PG8_BAR;
;             PG8_LDB(B0, 1, 0); PG8_SCHED; PG8_LDA(At, 1, 0); PG8_STAGE(PG8_SA(0, 1), a2 + hstep, voffA);
;             PG8_WAIT_L(8); PG8_BAR; PG8_WAIT_L(0); PG8_MMA(0, 0, At, B0); PG8_BAR; PG8_SCHED;
;             PG8_LDB(B1, 1, 1); PG8_STAGE(PG8_SB(1, 0), b3, voffB);
;             PG8_BAR; PG8_WAIT_L(0); PG8_MMA(0, 1, At, B1); PG8_BAR;
;             PG8_LDA(At, 1, 1); PG8_STAGE(PG8_SA(1, 0), a3, voffA);
;             PG8_BAR; PG8_WAIT_L(0); PG8_MMA(1, 0, At, B0); PG8_BAR; PG8_SCHED;
;             PG8_STAGE(PG8_SB(1, 1), b3 + hstep, voffB);
;             PG8_WAIT_V(6); PG8_BAR; PG8_MMA(1, 1, At, B1); PG8_BAR;
	s_waitcnt lgkmcnt(0)
	s_setprio 1
	s_waitcnt lgkmcnt(0)
	v_mfma_f32_16x16x32_bf16 v[60:63], v[152:155], v[168:171], v[60:63]
	v_mfma_f32_16x16x32_bf16 v[56:59], v[160:163], v[168:171], v[56:59]
	v_mfma_f32_16x16x32_bf16 v[48:51], v[152:155], v[176:179], v[48:51]
	v_mfma_f32_16x16x32_bf16 v[40:43], v[160:163], v[176:179], v[40:43]
	v_mfma_f32_16x16x32_bf16 v[32:35], v[152:155], v[184:187], v[32:35]
	v_mfma_f32_16x16x32_bf16 v[24:27], v[160:163], v[184:187], v[24:27]
	v_mfma_f32_16x16x32_bf16 v[16:19], v[152:155], v[192:195], v[16:19]
	v_mfma_f32_16x16x32_bf16 v[8:11], v[160:163], v[192:195], v[8:11]
	v_mfma_f32_16x16x32_bf16 v[60:63], v[156:159], v[172:175], v[60:63]
	v_mfma_f32_16x16x32_bf16 v[56:59], v[164:167], v[172:175], v[56:59]
	v_mfma_f32_16x16x32_bf16 v[48:51], v[156:159], v[180:183], v[48:51]
	v_mfma_f32_16x16x32_bf16 v[40:43], v[164:167], v[180:183], v[40:43]
	v_mfma_f32_16x16x32_bf16 v[32:35], v[156:159], v[188:191], v[32:35]
	v_mfma_f32_16x16x32_bf16 v[24:27], v[164:167], v[188:191], v[24:27]
	v_mfma_f32_16x16x32_bf16 v[16:19], v[156:159], v[196:199], v[16:19]
	v_mfma_f32_16x16x32_bf16 v[8:11], v[164:167], v[196:199], v[8:11]
	s_setprio 0
	s_barrier
	s_add_u32 s24, s24, 0x40080
	s_addc_u32 s25, s25, 0
	s_add_i32 s26, s26, s30
	s_mov_b32 m0, s26
	s_nop 0
	global_load_lds_dwordx4 v130, s[24:25]
	s_add_i32 m0, s26, 0x2000
	s_nop 0
	global_load_lds_dwordx4 v134, s[24:25]
	s_waitcnt vmcnt(6)
	s_barrier
	s_setprio 1
	v_mfma_f32_16x16x32_bf16 v[52:55], v[202:205], v[168:171], v[52:55]
	v_mfma_f32_16x16x32_bf16 v[44:47], v[210:213], v[168:171], v[44:47]
	v_mfma_f32_16x16x32_bf16 v[36:39], v[202:205], v[176:179], v[36:39]
	v_mfma_f32_16x16x32_bf16 v[28:31], v[210:213], v[176:179], v[28:31]
	v_mfma_f32_16x16x32_bf16 v[20:23], v[202:205], v[184:187], v[20:23]
	v_mfma_f32_16x16x32_bf16 v[12:15], v[210:213], v[184:187], v[12:15]
	v_mfma_f32_16x16x32_bf16 v[4:7], v[202:205], v[192:195], v[4:7]
	v_mfma_f32_16x16x32_bf16 v[0:3], v[210:213], v[192:195], v[0:3]
	v_mfma_f32_16x16x32_bf16 v[52:55], v[206:209], v[172:175], v[52:55]
	v_mfma_f32_16x16x32_bf16 v[44:47], v[214:217], v[172:175], v[44:47]
	v_mfma_f32_16x16x32_bf16 v[36:39], v[206:209], v[180:183], v[36:39]
	v_mfma_f32_16x16x32_bf16 v[28:31], v[214:217], v[180:183], v[28:31]
	v_mfma_f32_16x16x32_bf16 v[20:23], v[206:209], v[188:191], v[20:23]
	v_mfma_f32_16x16x32_bf16 v[12:15], v[214:217], v[188:191], v[12:15]
	v_mfma_f32_16x16x32_bf16 v[4:7], v[206:209], v[196:199], v[4:7]
	v_mfma_f32_16x16x32_bf16 v[0:3], v[214:217], v[196:199], v[0:3]
	s_setprio 0
	s_add_i32 s53, s53, 2
	s_add_u32 s22, s22, 0x100
	s_addc_u32 s23, s23, 0
	s_add_u32 s51, s51, 0x100
	s_addc_u32 s52, s52, 0
	s_cmp_gt_u32 s53, 13
	s_barrier
.LBB0_653:
	ds_read_b128 v[152:155], v149
	ds_read_b128 v[156:159], v149 offset:1024
	ds_read_b128 v[160:163], v149 offset:2048
	ds_read_b128 v[164:167], v149 offset:3072
	s_add_u32 s24, s22, 0xfffc0080
	s_addc_u32 s25, s23, -1
	s_cmp_eq_u32 s53, 12
	s_cselect_b32 s27, s9, s25
	s_cselect_b32 s26, s48, s24
	s_cselect_b32 s25, s7, s52
	s_cselect_b32 s24, s49, s51
	s_add_i32 m0, s21, 0xc000
	ds_read_b128 v[168:171], v150
	ds_read_b128 v[172:175], v150 offset:1024
	ds_read_b128 v[176:179], v150 offset:2048
	ds_read_b128 v[180:183], v150 offset:3072
	ds_read_b128 v[184:187], v150 offset:4096
	ds_read_b128 v[188:191], v150 offset:5120
	ds_read_b128 v[192:195], v150 offset:6144
	ds_read_b128 v[196:199], v150 offset:7168
	global_load_lds_dwordx4 v138, s[22:23]
	s_add_i32 m0, s21, 0xe000
	s_nop 0
	global_load_lds_dwordx4 v140, s[22:23]
	s_waitcnt lgkmcnt(8)
	s_barrier
	s_waitcnt lgkmcnt(0)
	s_setprio 1
	s_waitcnt lgkmcnt(0)
	v_mfma_f32_16x16x32_bf16 v[124:127], v[152:155], v[168:171], v[124:127]
	v_mfma_f32_16x16x32_bf16 v[120:123], v[160:163], v[168:171], v[120:123]
	v_mfma_f32_16x16x32_bf16 v[112:115], v[152:155], v[176:179], v[112:115]
	v_mfma_f32_16x16x32_bf16 v[104:107], v[160:163], v[176:179], v[104:107]
	v_mfma_f32_16x16x32_bf16 v[96:99], v[152:155], v[184:187], v[96:99]
	v_mfma_f32_16x16x32_bf16 v[88:91], v[160:163], v[184:187], v[88:91]
	v_mfma_f32_16x16x32_bf16 v[80:83], v[152:155], v[192:195], v[80:83]
	v_mfma_f32_16x16x32_bf16 v[72:75], v[160:163], v[192:195], v[72:75]
	v_mfma_f32_16x16x32_bf16 v[124:127], v[156:159], v[172:175], v[124:127]
	v_mfma_f32_16x16x32_bf16 v[120:123], v[164:167], v[172:175], v[120:123]
	v_mfma_f32_16x16x32_bf16 v[112:115], v[156:159], v[180:183], v[112:115]
	v_mfma_f32_16x16x32_bf16 v[104:107], v[164:167], v[180:183], v[104:107]
	v_mfma_f32_16x16x32_bf16 v[96:99], v[156:159], v[188:191], v[96:99]
	v_mfma_f32_16x16x32_bf16 v[88:91], v[164:167], v[188:191], v[88:91]
	v_mfma_f32_16x16x32_bf16 v[80:83], v[156:159], v[196:199], v[80:83]
	v_mfma_f32_16x16x32_bf16 v[72:75], v[164:167], v[196:199], v[72:75]
	s_setprio 0
	s_barrier
	s_add_i32 s54, s45, s30
	s_mov_b32 m0, s54
	ds_read_b128 v[202:205], v151
	ds_read_b128 v[206:209], v151 offset:1024
	ds_read_b128 v[210:213], v151 offset:2048
	ds_read_b128 v[214:217], v151 offset:3072
	global_load_lds_dwordx4 v130, s[24:25]
	s_add_i32 m0, s54, 0x2000
	s_nop 0
	global_load_lds_dwordx4 v134, s[24:25]
	s_barrier
; #define PG8_STAGE(bufoff, gbase, voff) do { _Pragma("unroll") for (int _i = 0; _i < 2; ++_i) \
;         __builtin_amdgcn_global_load_lds((const unsigned*)((const char*)(gbase) + (voff)[_i]), (LAS unsigned*)(lds + (bufoff) + ldsw + _i * 8192), 16, 0, 0); } while (0)
; #define PG8_LDA(dst, b, h) do { _Pragma("unroll") for (int m = 0; m < 4; ++m) _Pragma("unroll") for (int k = 0; k < 2; ++k) dst[m][k] = *(const LAS bf16x8*)(lds + PG8_SA(b, h) + aoff + m * 2048 + k * 1024); } while (0)
; #define PG8_LDB(dst, b, h) do { _Pragma("unroll") for (int n = 0; n < 2; ++n) _Pragma("unroll") for (int k = 0; k < 2; ++k) dst[n][k] = *(const LAS bf16x8*)(lds + PG8_SB(b, h) + boff + n * 2048 + k * 1024); } while (0)
; #define PG8_MMA(ai, bj, At, Bt) do { __builtin_amdgcn_s_setprio(1); _Pragma("unroll") for (int m = 0; m < 4; ++m) _Pragma("unroll") for (int n = 0; n < 2; ++n) _Pragma("unroll") for (int k = 0; k < 2; ++k) \
;         acc[ai][bj][m][n] = __builtin_amdgcn_mfma_f32_16x16x32_bf16(Bt[n][k], At[m][k], acc[ai][bj][m][n], 0, 0, 0); __builtin_amdgcn_s_setprio(0); } while (0)
; #define PG8_WAIT_V(n) asm volatile("s_waitcnt vmcnt(" #n ")" ::: "memory")
; #define PG8_WAIT_L(n) asm volatile("s_waitcnt lgkmcnt(" #n ")" ::: "memory")
; #define PG8_BAR __builtin_amdgcn_s_barrier()
; #define PG8_SCHED __builtin_amdgcn_sched_barrier(0)
; template <class Epi, class Sched>
; __device__ __forceinline__ void gemm_phase(LAS unsigned char* lds, const Gemm g, const Sched& S, const Epi& E) {
;     ...
;             PG8_BAR; PG8_WAIT_L(0); PG8_MMA(0, 1, At, B1); PG8_BAR;
;             PG8_LDA(At, 0, 1); PG8_STAGE(PG8_SA(0, 0), a2, voffA);
;             PG8_BAR; PG8_WAIT_L(0); PG8_MMA(1, 0, At, B0); PG8_BAR; PG8_SCHED;
;             PG8_STAGE(PG8_SB(0, 1), b2 + hstep, voffB);
;             PG8_WAIT_V(6); PG8_BAR; PG8_MMA(1, 1, At, B1); PG8_BAR;
;             PG8_LDB(B0, 1, 0); PG8_SCHED; PG8_LDA(At, 1, 0); PG8_STAGE(PG8_SA(0, 1), a2 + hstep, voffA);
	s_waitcnt lgkmcnt(0)
	s_setprio 1
	s_waitcnt lgkmcnt(0)
	v_mfma_f32_16x16x32_bf16 v[116:119], v[202:205], v[168:171], v[116:119]
	v_mfma_f32_16x16x32_bf16 v[108:111], v[210:213], v[168:171], v[108:111]
	v_mfma_f32_16x16x32_bf16 v[100:103], v[202:205], v[176:179], v[100:103]
	v_mfma_f32_16x16x32_bf16 v[92:95], v[210:213], v[176:179], v[92:95]
	v_mfma_f32_16x16x32_bf16 v[84:87], v[202:205], v[184:187], v[84:87]
	v_mfma_f32_16x16x32_bf16 v[76:79], v[210:213], v[184:187], v[76:79]
	v_mfma_f32_16x16x32_bf16 v[68:71], v[202:205], v[192:195], v[68:71]
	v_mfma_f32_16x16x32_bf16 v[64:67], v[210:213], v[192:195], v[64:67]
	v_mfma_f32_16x16x32_bf16 v[116:119], v[206:209], v[172:175], v[116:119]
	v_mfma_f32_16x16x32_bf16 v[108:111], v[214:217], v[172:175], v[108:111]
	v_mfma_f32_16x16x32_bf16 v[100:103], v[206:209], v[180:183], v[100:103]
	v_mfma_f32_16x16x32_bf16 v[92:95], v[214:217], v[180:183], v[92:95]
	v_mfma_f32_16x16x32_bf16 v[84:87], v[206:209], v[188:191], v[84:87]
	v_mfma_f32_16x16x32_bf16 v[76:79], v[214:217], v[188:191], v[76:79]
	v_mfma_f32_16x16x32_bf16 v[68:71], v[206:209], v[196:199], v[68:71]
	v_mfma_f32_16x16x32_bf16 v[64:67], v[214:217], v[196:199], v[64:67]
	s_setprio 0
	s_mov_b32 m0, s21
	v_lshl_add_u64 v[222:223], s[26:27], 0, v[128:129]
	s_barrier
	ds_read_b128 v[168:171], v150 offset:16384
	ds_read_b128 v[172:175], v150 offset:17408
	ds_read_b128 v[176:179], v150 offset:18432
	ds_read_b128 v[180:183], v150 offset:19456
	ds_read_b128 v[184:187], v150 offset:20480
	ds_read_b128 v[188:191], v150 offset:21504
	ds_read_b128 v[192:195], v150 offset:22528
	ds_read_b128 v[196:199], v150 offset:23552
	global_load_lds_dwordx4 v128, s[26:27]
	v_lshl_add_u64 v[224:225], s[26:27], 0, v[132:133]
	s_mov_b32 m0, s31
	s_nop 0
	global_load_lds_dwordx4 v132, s[26:27]
	s_barrier
	s_waitcnt lgkmcnt(0)
	s_setprio 1
	s_waitcnt lgkmcnt(0)
	v_mfma_f32_16x16x32_bf16 v[60:63], v[152:155], v[168:171], v[60:63]
	v_mfma_f32_16x16x32_bf16 v[56:59], v[160:163], v[168:171], v[56:59]
	v_mfma_f32_16x16x32_bf16 v[48:51], v[152:155], v[176:179], v[48:51]
	v_mfma_f32_16x16x32_bf16 v[40:43], v[160:163], v[176:179], v[40:43]
	v_mfma_f32_16x16x32_bf16 v[32:35], v[152:155], v[184:187], v[32:35]
	v_mfma_f32_16x16x32_bf16 v[24:27], v[160:163], v[184:187], v[24:27]
	v_mfma_f32_16x16x32_bf16 v[16:19], v[152:155], v[192:195], v[16:19]
	v_mfma_f32_16x16x32_bf16 v[8:11], v[160:163], v[192:195], v[8:11]
	v_mfma_f32_16x16x32_bf16 v[60:63], v[156:159], v[172:175], v[60:63]
	v_mfma_f32_16x16x32_bf16 v[56:59], v[164:167], v[172:175], v[56:59]
	v_mfma_f32_16x16x32_bf16 v[48:51], v[156:159], v[180:183], v[48:51]
	v_mfma_f32_16x16x32_bf16 v[40:43], v[164:167], v[180:183], v[40:43]
	v_mfma_f32_16x16x32_bf16 v[32:35], v[156:159], v[188:191], v[32:35]
	v_mfma_f32_16x16x32_bf16 v[24:27], v[164:167], v[188:191], v[24:27]
	v_mfma_f32_16x16x32_bf16 v[16:19], v[156:159], v[196:199], v[16:19]
	v_mfma_f32_16x16x32_bf16 v[8:11], v[164:167], v[196:199], v[8:11]
	s_setprio 0
	s_barrier
	s_add_u32 s54, s24, 0x40000
	s_addc_u32 s55, s25, 0
	s_add_i32 s56, s46, s30
	s_mov_b32 m0, s56
	s_nop 0
	global_load_lds_dwordx4 v130, s[54:55]
	s_add_i32 m0, s56, 0x2000
	s_nop 0
	global_load_lds_dwordx4 v134, s[54:55]
	s_waitcnt vmcnt(6)
	s_barrier
	s_setprio 1
	v_mfma_f32_16x16x32_bf16 v[52:55], v[202:205], v[168:171], v[52:55]
	v_mfma_f32_16x16x32_bf16 v[44:47], v[210:213], v[168:171], v[44:47]
	v_mfma_f32_16x16x32_bf16 v[36:39], v[202:205], v[176:179], v[36:39]
	v_mfma_f32_16x16x32_bf16 v[28:31], v[210:213], v[176:179], v[28:31]
	v_mfma_f32_16x16x32_bf16 v[20:23], v[202:205], v[184:187], v[20:23]
	v_mfma_f32_16x16x32_bf16 v[12:15], v[210:213], v[184:187], v[12:15]
	v_mfma_f32_16x16x32_bf16 v[4:7], v[202:205], v[192:195], v[4:7]
	v_mfma_f32_16x16x32_bf16 v[0:3], v[210:213], v[192:195], v[0:3]
	v_mfma_f32_16x16x32_bf16 v[52:55], v[206:209], v[172:175], v[52:55]
	v_mfma_f32_16x16x32_bf16 v[44:47], v[214:217], v[172:175], v[44:47]
	v_mfma_f32_16x16x32_bf16 v[36:39], v[206:209], v[180:183], v[36:39]
	v_mfma_f32_16x16x32_bf16 v[28:31], v[214:217], v[180:183], v[28:31]
	v_mfma_f32_16x16x32_bf16 v[20:23], v[206:209], v[188:191], v[20:23]
	v_mfma_f32_16x16x32_bf16 v[12:15], v[214:217], v[188:191], v[12:15]
	v_mfma_f32_16x16x32_bf16 v[4:7], v[206:209], v[196:199], v[4:7]
	v_mfma_f32_16x16x32_bf16 v[0:3], v[214:217], v[196:199], v[0:3]
	s_setprio 0
	s_add_i32 s54, 0, 0x18000
	v_add_u32_e32 v136, s54, v148
	s_barrier
	ds_read_b128 v[152:155], v136
	ds_read_b128 v[156:159], v136 offset:1024
	ds_read_b128 v[160:163], v136 offset:2048
	ds_read_b128 v[164:167], v136 offset:3072
	s_add_u32 s26, s26, 0x40000
	s_addc_u32 s27, s27, 0
	s_mov_b32 m0, s33
	ds_read_b128 v[168:171], v150 offset:32768
	ds_read_b128 v[172:175], v150 offset:33792
	ds_read_b128 v[176:179], v150 offset:34816
	ds_read_b128 v[180:183], v150 offset:35840
	ds_read_b128 v[184:187], v150 offset:36864
	ds_read_b128 v[188:191], v150 offset:37888
	ds_read_b128 v[192:195], v150 offset:38912
	ds_read_b128 v[196:199], v150 offset:39936
	global_load_lds_dwordx4 v128, s[26:27]
	s_mov_b32 m0, s34
	s_nop 0
	global_load_lds_dwordx4 v132, s[26:27]
	s_waitcnt lgkmcnt(8)
	s_barrier
; #define PG8_STAGE(bufoff, gbase, voff) do { _Pragma("unroll") for (int _i = 0; _i < 2; ++_i) \
;         __builtin_amdgcn_global_load_lds((const unsigned*)((const char*)(gbase) + (voff)[_i]), (LAS unsigned*)(lds + (bufoff) + ldsw + _i * 8192), 16, 0, 0); } while (0)
; #define PG8_LDA(dst, b, h) do { _Pragma("unroll") for (int m = 0; m < 4; ++m) _Pragma("unroll") for (int k = 0; k < 2; ++k) dst[m][k] = *(const LAS bf16x8*)(lds + PG8_SA(b, h) + aoff + m * 2048 + k * 1024); } while (0)
; #define PG8_LDB(dst, b, h) do { _Pragma("unroll") for (int n = 0; n < 2; ++n) _Pragma("unroll") for (int k = 0; k < 2; ++k) dst[n][k] = *(const LAS bf16x8*)(lds + PG8_SB(b, h) + boff + n * 2048 + k * 1024); } while (0)
; #define PG8_MMA(ai, bj, At, Bt) do { __builtin_amdgcn_s_setprio(1); _Pragma("unroll") for (int m = 0; m < 4; ++m) _Pragma("unroll") for (int n = 0; n < 2; ++n) _Pragma("unroll") for (int k = 0; k < 2; ++k) \
;         acc[ai][bj][m][n] = __builtin_amdgcn_mfma_f32_16x16x32_bf16(Bt[n][k], At[m][k], acc[ai][bj][m][n], 0, 0, 0); __builtin_amdgcn_s_setprio(0); } while (0)
; #define PG8_WAIT_V(n) asm volatile("s_waitcnt vmcnt(" #n ")" ::: "memory")
; #define PG8_WAIT_L(n) asm volatile("s_waitcnt lgkmcnt(" #n ")" ::: "memory")
; #define PG8_BAR __builtin_amdgcn_s_barrier()
; #define PG8_SCHED __builtin_amdgcn_sched_barrier(0)
; template <class Epi, class Sched>
; __device__ __forceinline__ void gemm_phase(LAS unsigned char* lds, const Gemm g, const Sched& S, const Epi& E) {
;     ...
;             PG8_WAIT_L(8); PG8_BAR; PG8_WAIT_L(0); PG8_MMA(0, 0, At, B0); PG8_BAR; PG8_SCHED;
;             PG8_LDB(B1, 1, 1); PG8_STAGE(PG8_SB(1, 0), b3, voffB);
;             PG8_BAR; PG8_WAIT_L(0); PG8_MMA(0, 1, At, B1); PG8_BAR;
;             PG8_LDA(At, 1, 1); PG8_STAGE(PG8_SA(1, 0), a3, voffA);
;             PG8_BAR; PG8_WAIT_L(0); PG8_MMA(1, 0, At, B0); PG8_BAR; PG8_SCHED;
;             PG8_STAGE(PG8_SB(1, 1), b3 + hstep, voffB);
;             PG8_WAIT_V(6); PG8_BAR; PG8_MMA(1, 1, At, B1); PG8_BAR;
;         }
	s_waitcnt lgkmcnt(0)
	s_setprio 1
	s_waitcnt lgkmcnt(0)
	v_mfma_f32_16x16x32_bf16 v[124:127], v[152:155], v[168:171], v[124:127]
	v_mfma_f32_16x16x32_bf16 v[120:123], v[160:163], v[168:171], v[120:123]
	v_mfma_f32_16x16x32_bf16 v[112:115], v[152:155], v[176:179], v[112:115]
	v_mfma_f32_16x16x32_bf16 v[104:107], v[160:163], v[176:179], v[104:107]
	v_mfma_f32_16x16x32_bf16 v[96:99], v[152:155], v[184:187], v[96:99]
	v_mfma_f32_16x16x32_bf16 v[88:91], v[160:163], v[184:187], v[88:91]
	v_mfma_f32_16x16x32_bf16 v[80:83], v[152:155], v[192:195], v[80:83]
	v_mfma_f32_16x16x32_bf16 v[72:75], v[160:163], v[192:195], v[72:75]
	v_mfma_f32_16x16x32_bf16 v[124:127], v[156:159], v[172:175], v[124:127]
	v_mfma_f32_16x16x32_bf16 v[120:123], v[164:167], v[172:175], v[120:123]
	v_mfma_f32_16x16x32_bf16 v[112:115], v[156:159], v[180:183], v[112:115]
	v_mfma_f32_16x16x32_bf16 v[104:107], v[164:167], v[180:183], v[104:107]
	v_mfma_f32_16x16x32_bf16 v[96:99], v[156:159], v[188:191], v[96:99]
	v_mfma_f32_16x16x32_bf16 v[88:91], v[164:167], v[188:191], v[88:91]
	v_mfma_f32_16x16x32_bf16 v[80:83], v[156:159], v[196:199], v[80:83]
	v_mfma_f32_16x16x32_bf16 v[72:75], v[164:167], v[196:199], v[72:75]
	s_setprio 0
	s_barrier
	s_add_i32 s26, 0, 0x1c000
	s_add_i32 s27, s54, s30
	v_add_u32_e32 v136, s26, v148
	s_add_u32 s0, s24, 0x80
	s_addc_u32 s1, s25, 0
	s_mov_b32 m0, s27
	ds_read_b128 v[202:205], v136
	ds_read_b128 v[206:209], v136 offset:1024
	ds_read_b128 v[210:213], v136 offset:2048
	ds_read_b128 v[214:217], v136 offset:3072
	global_load_lds_dwordx4 v130, s[0:1]
	s_add_i32 m0, s27, 0x2000
	s_nop 0
	global_load_lds_dwordx4 v134, s[0:1]
	s_barrier
	s_waitcnt lgkmcnt(0)
	s_setprio 1
	s_waitcnt lgkmcnt(0)
	v_mfma_f32_16x16x32_bf16 v[116:119], v[202:205], v[168:171], v[116:119]
	v_mfma_f32_16x16x32_bf16 v[108:111], v[210:213], v[168:171], v[108:111]
	v_mfma_f32_16x16x32_bf16 v[100:103], v[202:205], v[176:179], v[100:103]
	v_mfma_f32_16x16x32_bf16 v[92:95], v[210:213], v[176:179], v[92:95]
	v_mfma_f32_16x16x32_bf16 v[84:87], v[202:205], v[184:187], v[84:87]
	v_mfma_f32_16x16x32_bf16 v[76:79], v[210:213], v[184:187], v[76:79]
	v_mfma_f32_16x16x32_bf16 v[68:71], v[202:205], v[192:195], v[68:71]
	v_mfma_f32_16x16x32_bf16 v[64:67], v[210:213], v[192:195], v[64:67]
	v_mfma_f32_16x16x32_bf16 v[116:119], v[206:209], v[172:175], v[116:119]
	v_mfma_f32_16x16x32_bf16 v[108:111], v[214:217], v[172:175], v[108:111]
	v_mfma_f32_16x16x32_bf16 v[100:103], v[206:209], v[180:183], v[100:103]
	v_mfma_f32_16x16x32_bf16 v[92:95], v[214:217], v[180:183], v[92:95]
	v_mfma_f32_16x16x32_bf16 v[84:87], v[206:209], v[188:191], v[84:87]
	v_mfma_f32_16x16x32_bf16 v[76:79], v[214:217], v[188:191], v[76:79]
	v_mfma_f32_16x16x32_bf16 v[68:71], v[206:209], v[196:199], v[68:71]
	v_mfma_f32_16x16x32_bf16 v[64:67], v[214:217], v[196:199], v[64:67]
	s_setprio 0
	s_mov_b32 m0, s42
	s_mov_b64 s[0:1], 0x80
	v_lshl_add_u64 v[218:219], v[222:223], 0, s[0:1]
	s_barrier
	ds_read_b128 v[168:171], v150 offset:49152
	ds_read_b128 v[172:175], v150 offset:50176
	ds_read_b128 v[176:179], v150 offset:51200
	ds_read_b128 v[180:183], v150 offset:52224
	ds_read_b128 v[184:187], v150 offset:53248
	ds_read_b128 v[188:191], v150 offset:54272
	ds_read_b128 v[192:195], v150 offset:55296
	ds_read_b128 v[196:199], v150 offset:56320
	global_load_lds_dwordx4 v[218:219], off
	v_lshl_add_u64 v[218:219], v[224:225], 0, s[0:1]
	s_mov_b32 m0, s43
	s_nop 0
	global_load_lds_dwordx4 v[218:219], off
	s_barrier
	s_waitcnt lgkmcnt(0)
	s_setprio 1
	s_waitcnt lgkmcnt(0)
	v_mfma_f32_16x16x32_bf16 v[60:63], v[152:155], v[168:171], v[60:63]
	v_mfma_f32_16x16x32_bf16 v[56:59], v[160:163], v[168:171], v[56:59]
	v_mfma_f32_16x16x32_bf16 v[48:51], v[152:155], v[176:179], v[48:51]
	v_mfma_f32_16x16x32_bf16 v[40:43], v[160:163], v[176:179], v[40:43]
	v_mfma_f32_16x16x32_bf16 v[32:35], v[152:155], v[184:187], v[32:35]
	v_mfma_f32_16x16x32_bf16 v[24:27], v[160:163], v[184:187], v[24:27]
	v_mfma_f32_16x16x32_bf16 v[16:19], v[152:155], v[192:195], v[16:19]
	v_mfma_f32_16x16x32_bf16 v[8:11], v[160:163], v[192:195], v[8:11]
	v_mfma_f32_16x16x32_bf16 v[60:63], v[156:159], v[172:175], v[60:63]
	v_mfma_f32_16x16x32_bf16 v[56:59], v[164:167], v[172:175], v[56:59]
	v_mfma_f32_16x16x32_bf16 v[48:51], v[156:159], v[180:183], v[48:51]
	v_mfma_f32_16x16x32_bf16 v[40:43], v[164:167], v[180:183], v[40:43]
	v_mfma_f32_16x16x32_bf16 v[32:35], v[156:159], v[188:191], v[32:35]
	v_mfma_f32_16x16x32_bf16 v[24:27], v[164:167], v[188:191], v[24:27]
	v_mfma_f32_16x16x32_bf16 v[16:19], v[156:159], v[196:199], v[16:19]
	v_mfma_f32_16x16x32_bf16 v[8:11], v[164:167], v[196:199], v[8:11]
	s_setprio 0
	s_barrier
	s_add_u32 s24, s24, 0x40080
	s_addc_u32 s25, s25, 0
	s_add_i32 s26, s26, s30
	s_mov_b32 m0, s26
	s_nop 0
	global_load_lds_dwordx4 v130, s[24:25]
	s_add_i32 m0, s26, 0x2000
	s_nop 0
	global_load_lds_dwordx4 v134, s[24:25]
	s_waitcnt vmcnt(6)
	s_barrier
	s_setprio 1
	v_mfma_f32_16x16x32_bf16 v[52:55], v[202:205], v[168:171], v[52:55]
	v_mfma_f32_16x16x32_bf16 v[44:47], v[210:213], v[168:171], v[44:47]
	v_mfma_f32_16x16x32_bf16 v[36:39], v[202:205], v[176:179], v[36:39]
	v_mfma_f32_16x16x32_bf16 v[28:31], v[210:213], v[176:179], v[28:31]
	v_mfma_f32_16x16x32_bf16 v[20:23], v[202:205], v[184:187], v[20:23]
	v_mfma_f32_16x16x32_bf16 v[12:15], v[210:213], v[184:187], v[12:15]
	v_mfma_f32_16x16x32_bf16 v[4:7], v[202:205], v[192:195], v[4:7]
	v_mfma_f32_16x16x32_bf16 v[0:3], v[210:213], v[192:195], v[0:3]
	v_mfma_f32_16x16x32_bf16 v[52:55], v[206:209], v[172:175], v[52:55]
	v_mfma_f32_16x16x32_bf16 v[44:47], v[214:217], v[172:175], v[44:47]
	v_mfma_f32_16x16x32_bf16 v[36:39], v[206:209], v[180:183], v[36:39]
	v_mfma_f32_16x16x32_bf16 v[28:31], v[214:217], v[180:183], v[28:31]
	v_mfma_f32_16x16x32_bf16 v[20:23], v[206:209], v[188:191], v[20:23]
	v_mfma_f32_16x16x32_bf16 v[12:15], v[214:217], v[188:191], v[12:15]
	v_mfma_f32_16x16x32_bf16 v[4:7], v[206:209], v[196:199], v[4:7]
	v_mfma_f32_16x16x32_bf16 v[0:3], v[214:217], v[196:199], v[0:3]
	s_setprio 0
	s_add_i32 s53, s53, 2
	s_add_u32 s22, s22, 0x100
	s_addc_u32 s23, s23, 0
	s_add_u32 s51, s51, 0x100
	s_addc_u32 s52, s52, 0
	s_cmp_gt_u32 s53, 13
	s_barrier
; __device__ __forceinline__ unsigned cvt_pk_bf16(float lo, float hi) { unsigned r; asm volatile("v_cvt_pk_bf16_f32 %0, %1, %2" : "=v"(r) : "v"(lo), "v"(hi)); return r; }
;     __device__ __forceinline__ void operator()(const AccT& acc, const Unit& u, int wr, int wc, int fr, int fq) const {
;     ...
;         const int rbase = u.pm * 256 + wr * 64 + fr;
;         const int tb = u.pn * 256 + wc * 32 + 8 * fq;
; #pragma unroll
;         for (int ai = 0; ai < 2; ++ai)
; #pragma unroll
;             for (int m = 0; m < 4; ++m) {
;                 const int gm = rbase + ai * 128 + m * 16;
; #pragma unroll
;                 for (int bj = 0; bj < 2; ++bj) {
;                     const int t0 = tb + bj * 128;
;                     const f32x4 v0 = acc[ai][bj][m][0], v1 = acc[ai][bj][m][1];
;                     u32x4 w; w.x = cvt_pk_bf16(v0[0], v0[1]); w.y = cvt_pk_bf16(v0[2], v0[3]); w.z = cvt_pk_bf16(v1[0], v1[1]); w.w = cvt_pk_bf16(v1[2], v1[3]);
;                     *(u32x4*)(YT + ((size_t)((t0 >> 10) * 512 + gm)) * 2048 + part * 1024 + (t0 & 1023)) = w;
	s_cbranch_scc0 .LBB0_653
	v_mov_b32_e32 v136, v147
	v_mov_b32_e32 v152, v146
	s_lshl_b32 s7, s20, 8
	s_add_i32 s7, s7, s36
	v_add_u32_e32 v152, s7, v152
	s_lshl_b32 s7, s47, 8
	s_or_b32 s7, s7, s37
	v_lshl_add_u32 v153, v136, 3, s7
	v_cvt_pk_bf16_f32 v124, v124, v125
	v_cvt_pk_bf16_f32 v125, v126, v127
	v_cvt_pk_bf16_f32 v126, v120, v121
	v_ashrrev_i32_e32 v120, 1, v153
	v_cvt_pk_bf16_f32 v127, v122, v123
	v_and_b32_e32 v122, 0xfffffe00, v120
	v_add_u32_e32 v120, v122, v152
	v_ashrrev_i32_e32 v121, 31, v120
	v_lshlrev_b64 v[120:121], 12, v[120:121]
	v_and_b32_e32 v123, 0x3f8, v153
	v_lshl_add_u64 v[120:121], s[68:69], 0, v[120:121]
	v_lshlrev_b32_e32 v136, 1, v123
	v_lshl_add_u64 v[120:121], v[120:121], 0, v[136:137]
	global_store_dwordx4 v[120:121], v[124:127], off
	v_add_u32_e32 v120, 0x80, v153
	v_cvt_pk_bf16_f32 v116, v116, v117
	v_cvt_pk_bf16_f32 v117, v118, v119
	v_cvt_pk_bf16_f32 v118, v108, v109
	v_ashrrev_i32_e32 v108, 1, v120
	v_and_b32_e32 v121, 0xfffffe00, v108
	v_add_u32_e32 v108, v121, v152
	v_ashrrev_i32_e32 v109, 31, v108
	v_lshlrev_b64 v[108:109], 12, v[108:109]
	v_cvt_pk_bf16_f32 v119, v110, v111
	v_lshl_add_u64 v[110:111], s[68:69], 0, v[108:109]
	v_and_b32_e32 v108, 0x3f8, v120
	v_lshlrev_b32_e32 v108, 1, v108
	v_mov_b32_e32 v109, v137
	v_lshl_add_u64 v[110:111], v[110:111], 0, v[108:109]
	global_store_dwordx4 v[110:111], v[116:119], off
	v_cvt_pk_bf16_f32 v110, v112, v113
	v_cvt_pk_bf16_f32 v111, v114, v115
	v_cvt_pk_bf16_f32 v112, v104, v105
	v_cvt_pk_bf16_f32 v113, v106, v107
	s_and_b64 vcc, exec, s[4:5]
	s_nop 0
	v_add_u32_e32 v116, 16, v152
	v_add_u32_e32 v104, v122, v116
	v_ashrrev_i32_e32 v105, 31, v104
	v_lshlrev_b64 v[104:105], 12, v[104:105]
	v_lshl_add_u64 v[104:105], s[68:69], 0, v[104:105]
	v_lshl_add_u64 v[104:105], v[104:105], 0, v[136:137]
	global_store_dwordx4 v[104:105], v[110:113], off
	v_cvt_pk_bf16_f32 v100, v100, v101
	v_cvt_pk_bf16_f32 v101, v102, v103
	v_cvt_pk_bf16_f32 v102, v92, v93
	v_add_u32_e32 v92, v121, v116
	v_ashrrev_i32_e32 v93, 31, v92
	v_lshlrev_b64 v[92:93], 12, v[92:93]
	v_lshl_add_u64 v[92:93], s[68:69], 0, v[92:93]
	v_lshl_add_u64 v[92:93], v[92:93], 0, v[108:109]
	v_cvt_pk_bf16_f32 v103, v94, v95
	global_store_dwordx4 v[92:93], v[100:103], off
	v_cvt_pk_bf16_f32 v92, v96, v97
	v_cvt_pk_bf16_f32 v93, v98, v99
	v_cvt_pk_bf16_f32 v94, v88, v89
	v_cvt_pk_bf16_f32 v95, v90, v91
	s_mov_b32 s47, s6
	s_nop 0
	v_add_u32_e32 v100, 32, v152
	v_add_u32_e32 v88, v122, v100
	v_ashrrev_i32_e32 v89, 31, v88
	v_lshlrev_b64 v[88:89], 12, v[88:89]
	v_lshl_add_u64 v[88:89], s[68:69], 0, v[88:89]
	v_lshl_add_u64 v[88:89], v[88:89], 0, v[136:137]
	global_store_dwordx4 v[88:89], v[92:95], off
	v_cvt_pk_bf16_f32 v84, v84, v85
	v_cvt_pk_bf16_f32 v85, v86, v87
	v_cvt_pk_bf16_f32 v86, v76, v77
	v_add_u32_e32 v76, v121, v100
	v_ashrrev_i32_e32 v77, 31, v76
	v_lshlrev_b64 v[76:77], 12, v[76:77]
	v_lshl_add_u64 v[76:77], s[68:69], 0, v[76:77]
	v_lshl_add_u64 v[76:77], v[76:77], 0, v[108:109]
	v_cvt_pk_bf16_f32 v87, v78, v79
	global_store_dwordx4 v[76:77], v[84:87], off
	v_cvt_pk_bf16_f32 v76, v80, v81
	v_cvt_pk_bf16_f32 v77, v82, v83
	v_cvt_pk_bf16_f32 v78, v72, v73
	v_cvt_pk_bf16_f32 v79, v74, v75
	s_mov_b32 s20, s8
	s_nop 0
	v_add_u32_e32 v84, 48, v152
	v_add_u32_e32 v72, v122, v84
	v_ashrrev_i32_e32 v73, 31, v72
	v_lshlrev_b64 v[72:73], 12, v[72:73]
	v_lshl_add_u64 v[72:73], s[68:69], 0, v[72:73]
	v_lshl_add_u64 v[72:73], v[72:73], 0, v[136:137]
	global_store_dwordx4 v[72:73], v[76:79], off
	v_cvt_pk_bf16_f32 v68, v68, v69
	v_cvt_pk_bf16_f32 v69, v70, v71
; __device__ __forceinline__ unsigned cvt_pk_bf16(float lo, float hi) { unsigned r; asm volatile("v_cvt_pk_bf16_f32 %0, %1, %2" : "=v"(r) : "v"(lo), "v"(hi)); return r; }
; #define PG8_WAIT_V(n) asm volatile("s_waitcnt vmcnt(" #n ")" ::: "memory")
; #define PG8_BAR __builtin_amdgcn_s_barrier()
; template <class Epi, class Sched>
; __device__ __forceinline__ void gemm_phase(LAS unsigned char* lds, const Gemm g, const Sched& S, const Epi& E) {
;     ...
;         if (!has_next) break;
; #pragma unroll
;         for (int a = 0; a < 2; ++a)
; #pragma unroll
;             for (int b = 0; b < 2; ++b)
; #pragma unroll
;                 for (int m = 0; m < 4; ++m)
; #pragma unroll
;                     for (int n = 0; n < 2; ++n) acc[a][b][m][n] = (f32x4){0.f, 0.f, 0.f, 0.f};
;         cur = nxt; cA = nA; cB = nB; ++ui;
;     }
;     PG8_WAIT_V(0);
;     if (wr == 0) PG8_BAR;
;     __device__ __forceinline__ void operator()(const AccT& acc, const Unit& u, int wr, int wc, int fr, int fq) const {
;     ...
;         for (int ai = 0; ai < 2; ++ai)
; #pragma unroll
;             for (int m = 0; m < 4; ++m) {
;                 const int gm = rbase + ai * 128 + m * 16;
; #pragma unroll
;                 for (int bj = 0; bj < 2; ++bj) {
;                     const int t0 = tb + bj * 128;
;                     const f32x4 v0 = acc[ai][bj][m][0], v1 = acc[ai][bj][m][1];
;                     u32x4 w; w.x = cvt_pk_bf16(v0[0], v0[1]); w.y = cvt_pk_bf16(v0[2], v0[3]); w.z = cvt_pk_bf16(v1[0], v1[1]); w.w = cvt_pk_bf16(v1[2], v1[3]);
;                     *(u32x4*)(YT + ((size_t)((t0 >> 10) * 512 + gm)) * 2048 + part * 1024 + (t0 & 1023)) = w;
	v_cvt_pk_bf16_f32 v70, v64, v65
	v_add_u32_e32 v64, v121, v84
	v_ashrrev_i32_e32 v65, 31, v64
	v_lshlrev_b64 v[64:65], 12, v[64:65]
	v_lshl_add_u64 v[64:65], s[68:69], 0, v[64:65]
	v_lshl_add_u64 v[64:65], v[64:65], 0, v[108:109]
	v_cvt_pk_bf16_f32 v71, v66, v67
	global_store_dwordx4 v[64:65], v[68:71], off
	v_add_u32_e32 v64, 0x80, v152
	v_cvt_pk_bf16_f32 v60, v60, v61
	v_cvt_pk_bf16_f32 v61, v62, v63
	v_cvt_pk_bf16_f32 v62, v56, v57
	v_add_u32_e32 v56, v122, v64
	v_ashrrev_i32_e32 v57, 31, v56
	v_lshlrev_b64 v[56:57], 12, v[56:57]
	v_lshl_add_u64 v[56:57], s[68:69], 0, v[56:57]
	v_lshl_add_u64 v[56:57], v[56:57], 0, v[136:137]
	v_cvt_pk_bf16_f32 v63, v58, v59
	global_store_dwordx4 v[56:57], v[60:63], off
	v_cvt_pk_bf16_f32 v52, v52, v53
	v_cvt_pk_bf16_f32 v53, v54, v55
	v_cvt_pk_bf16_f32 v54, v44, v45
	v_add_u32_e32 v44, v121, v64
	v_ashrrev_i32_e32 v45, 31, v44
	v_lshlrev_b64 v[44:45], 12, v[44:45]
	v_lshl_add_u64 v[44:45], s[68:69], 0, v[44:45]
	v_lshl_add_u64 v[44:45], v[44:45], 0, v[108:109]
	v_cvt_pk_bf16_f32 v55, v46, v47
	global_store_dwordx4 v[44:45], v[52:55], off
	v_cvt_pk_bf16_f32 v44, v48, v49
	v_cvt_pk_bf16_f32 v45, v50, v51
	v_cvt_pk_bf16_f32 v46, v40, v41
	v_cvt_pk_bf16_f32 v47, v42, v43
	s_mov_b64 s[24:25], s[18:19]
	s_nop 0
	v_add_u32_e32 v52, 0x90, v152
	v_add_u32_e32 v40, v122, v52
	v_ashrrev_i32_e32 v41, 31, v40
	v_lshlrev_b64 v[40:41], 12, v[40:41]
	v_lshl_add_u64 v[40:41], s[68:69], 0, v[40:41]
	v_lshl_add_u64 v[40:41], v[40:41], 0, v[136:137]
	global_store_dwordx4 v[40:41], v[44:47], off
	v_cvt_pk_bf16_f32 v36, v36, v37
	v_cvt_pk_bf16_f32 v37, v38, v39
	v_cvt_pk_bf16_f32 v38, v28, v29
	v_add_u32_e32 v28, v121, v52
	v_ashrrev_i32_e32 v29, 31, v28
	v_lshlrev_b64 v[28:29], 12, v[28:29]
	v_lshl_add_u64 v[28:29], s[68:69], 0, v[28:29]
	v_lshl_add_u64 v[28:29], v[28:29], 0, v[108:109]
	v_cvt_pk_bf16_f32 v39, v30, v31
	global_store_dwordx4 v[28:29], v[36:39], off
	v_cvt_pk_bf16_f32 v28, v32, v33
	v_cvt_pk_bf16_f32 v29, v34, v35
	v_cvt_pk_bf16_f32 v30, v24, v25
	v_cvt_pk_bf16_f32 v31, v26, v27
	s_mov_b64 s[22:23], s[16:17]
	s_nop 0
	v_add_u32_e32 v36, 0xa0, v152
	v_add_u32_e32 v24, v122, v36
	v_ashrrev_i32_e32 v25, 31, v24
	v_lshlrev_b64 v[24:25], 12, v[24:25]
	v_lshl_add_u64 v[24:25], s[68:69], 0, v[24:25]
	v_lshl_add_u64 v[24:25], v[24:25], 0, v[136:137]
	global_store_dwordx4 v[24:25], v[28:31], off
	v_cvt_pk_bf16_f32 v20, v20, v21
	v_cvt_pk_bf16_f32 v21, v22, v23
	v_cvt_pk_bf16_f32 v22, v12, v13
	v_add_u32_e32 v12, v121, v36
	v_ashrrev_i32_e32 v13, 31, v12
	v_lshlrev_b64 v[12:13], 12, v[12:13]
	v_lshl_add_u64 v[12:13], s[68:69], 0, v[12:13]
	v_lshl_add_u64 v[12:13], v[12:13], 0, v[108:109]
	v_cvt_pk_bf16_f32 v23, v14, v15
	global_store_dwordx4 v[12:13], v[20:23], off
	v_cvt_pk_bf16_f32 v12, v16, v17
	v_cvt_pk_bf16_f32 v13, v18, v19
	v_cvt_pk_bf16_f32 v14, v8, v9
	v_cvt_pk_bf16_f32 v15, v10, v11
	s_nop 1
	v_add_u32_e32 v20, 0xb0, v152
	v_add_u32_e32 v8, v122, v20
	v_ashrrev_i32_e32 v9, 31, v8
	v_lshlrev_b64 v[8:9], 12, v[8:9]
	v_lshl_add_u64 v[8:9], s[68:69], 0, v[8:9]
	v_lshl_add_u64 v[8:9], v[8:9], 0, v[136:137]
	global_store_dwordx4 v[8:9], v[12:15], off
	v_cvt_pk_bf16_f32 v4, v4, v5
	v_cvt_pk_bf16_f32 v5, v6, v7
	v_cvt_pk_bf16_f32 v6, v0, v1
	v_add_u32_e32 v0, v121, v20
	v_ashrrev_i32_e32 v1, 31, v0
	v_lshlrev_b64 v[0:1], 12, v[0:1]
	v_lshl_add_u64 v[0:1], s[68:69], 0, v[0:1]
	v_lshl_add_u64 v[0:1], v[0:1], 0, v[108:109]
	v_cvt_pk_bf16_f32 v7, v2, v3
	global_store_dwordx4 v[0:1], v[4:7], off
	s_cbranch_vccz .LBB0_646
	s_waitcnt vmcnt(0)
	s_cmpk_gt_u32 s28, 0xff
	s_cbranch_scc1 .LBB0_657
	s_barrier

; #define PG8_STAGE(bufoff, gbase, voff) do { _Pragma("unroll") for (int _i = 0; _i < 2; ++_i) \
;         __builtin_amdgcn_global_load_lds((const unsigned*)((const char*)(gbase) + (voff)[_i]), (LAS unsigned*)(lds + (bufoff) + ldsw + _i * 8192), 16, 0, 0); } while (0)
; #define PG8_LDA(dst, b, h) do { _Pragma("unroll") for (int m = 0; m < 4; ++m) _Pragma("unroll") for (int k = 0; k < 2; ++k) dst[m][k] = *(const LAS bf16x8*)(lds + PG8_SA(b, h) + aoff + m * 2048 + k * 1024); } while (0)
; #define PG8_LDB(dst, b, h) do { _Pragma("unroll") for (int n = 0; n < 2; ++n) _Pragma("unroll") for (int k = 0; k < 2; ++k) dst[n][k] = *(const LAS bf16x8*)(lds + PG8_SB(b, h) + boff + n * 2048 + k * 1024); } while (0)
; #define PG8_MMA(ai, bj, At, Bt) do { __builtin_amdgcn_s_setprio(1); _Pragma("unroll") for (int m = 0; m < 4; ++m) _Pragma("unroll") for (int n = 0; n < 2; ++n) _Pragma("unroll") for (int k = 0; k < 2; ++k) \
;         acc[ai][bj][m][n] = __builtin_amdgcn_mfma_f32_16x16x32_bf16(Bt[n][k], At[m][k], acc[ai][bj][m][n], 0, 0, 0); __builtin_amdgcn_s_setprio(0); } while (0)
; #define PG8_WAIT_L(n) asm volatile("s_waitcnt lgkmcnt(" #n ")" ::: "memory")
; template <class Epi, class Sched>
; __device__ __forceinline__ void gemm_phase(LAS unsigned char* lds, const Gemm g, const Sched& S, const Epi& E) {
;     ...
;         const bool has_next = S.next(ui + 1, nxt);
;         const char* nA = has_next ? (const char*)g.A + (size_t)nxt.pm * tstep : cA; const char* nB = has_next ? (const char*)g.Bt + (size_t)nxt.pn * tstep : cB;
;         for (int t = 0; t < nt; t += 2) {
;             const bool last = (t == nt - 2);
;             const char* a1 = cA + (size_t)(t + 1) * kstep;
;             const char* a2 = last ? nA : cA + (size_t)(t + 2) * kstep; const char* b2 = last ? nB : cB + (size_t)(t + 2) * kstep;
;             const char* a3 = a2 + kstep; const char* b3 = b2 + kstep;
;             PG8_LDB(B0, 0, 0); PG8_SCHED; PG8_LDA(At, 0, 0); PG8_STAGE(PG8_SA(1, 1), a1 + hstep, voffA);
;             PG8_WAIT_L(8); PG8_BAR; PG8_WAIT_L(0); PG8_MMA(0, 0, At, B0); PG8_BAR; PG8_SCHED;
;             PG8_LDB(B1, 0, 1); PG8_STAGE(PG8_SB(0, 0), b2, voffB);
;             PG8_BAR; PG8_WAIT_L(0); PG8_MMA(0, 1, At, B1); PG8_BAR;
;             PG8_LDA(At, 0, 1); PG8_STAGE(PG8_SA(0, 0), a2, voffA);
;             PG8_BAR; PG8_WAIT_L(0); PG8_MMA(1, 0, At, B0); PG8_BAR; PG8_SCHED;
.LBB0_672:
	s_ashr_i32 s9, s8, 31
	v_cmp_lt_i64_e32 vcc, s[12:13], v[142:143]
	s_lshl_b64 s[12:13], s[8:9], 19
	s_add_u32 s12, s26, s12
	s_addc_u32 s13, s27, s13
	s_and_b64 s[14:15], vcc, exec
	s_cselect_b32 s9, s13, s19
	s_cselect_b32 s46, s12, s18
	s_ashr_i32 s7, s6, 31
	s_lshl_b64 s[14:15], s[6:7], 19
	s_add_u32 s14, s10, s14
	s_addc_u32 s15, s11, s15
	s_and_b64 s[22:23], vcc, exec
	s_cselect_b32 s7, s15, s21
	s_cselect_b32 s47, s14, s20
	s_add_u32 s18, s18, 0x40080
	s_addc_u32 s19, s19, 0
	s_add_u32 s48, s20, 0x100
	s_addc_u32 s49, s21, 0
	s_mov_b32 s51, -2
	s_waitcnt lgkmcnt(0)
	ds_read_b128 v[152:155], v149
	ds_read_b128 v[156:159], v149 offset:1024
	ds_read_b128 v[160:163], v149 offset:2048
	ds_read_b128 v[164:167], v149 offset:3072
	s_add_u32 s20, s18, 0xfffc0080
	s_addc_u32 s21, s19, -1
	s_cmp_eq_u32 s51, 12
	s_cselect_b32 s23, s9, s21
	s_cselect_b32 s22, s46, s20
	s_cselect_b32 s21, s7, s49
	s_cselect_b32 s20, s47, s48
	s_add_i32 m0, s17, 0xc000
	ds_read_b128 v[168:171], v150
	ds_read_b128 v[172:175], v150 offset:1024
	ds_read_b128 v[176:179], v150 offset:2048
	ds_read_b128 v[180:183], v150 offset:3072
	ds_read_b128 v[184:187], v150 offset:4096
	ds_read_b128 v[188:191], v150 offset:5120
	ds_read_b128 v[192:195], v150 offset:6144
	ds_read_b128 v[196:199], v150 offset:7168
	global_load_lds_dwordx4 v138, s[18:19]
	s_add_i32 m0, s17, 0xe000
	s_nop 0
	global_load_lds_dwordx4 v140, s[18:19]
	s_waitcnt lgkmcnt(8)
	s_barrier
	s_waitcnt lgkmcnt(0)
	s_setprio 1
	s_waitcnt lgkmcnt(0)
	v_mfma_f32_16x16x32_bf16 v[124:127], v[152:155], v[168:171], 0
	v_mfma_f32_16x16x32_bf16 v[120:123], v[160:163], v[168:171], 0
	v_mfma_f32_16x16x32_bf16 v[112:115], v[152:155], v[176:179], 0
	v_mfma_f32_16x16x32_bf16 v[104:107], v[160:163], v[176:179], 0
	v_mfma_f32_16x16x32_bf16 v[96:99], v[152:155], v[184:187], 0
	v_mfma_f32_16x16x32_bf16 v[88:91], v[160:163], v[184:187], 0
	v_mfma_f32_16x16x32_bf16 v[80:83], v[152:155], v[192:195], 0
	v_mfma_f32_16x16x32_bf16 v[72:75], v[160:163], v[192:195], 0
	v_mfma_f32_16x16x32_bf16 v[124:127], v[156:159], v[172:175], v[124:127]
	v_mfma_f32_16x16x32_bf16 v[120:123], v[164:167], v[172:175], v[120:123]
	v_mfma_f32_16x16x32_bf16 v[112:115], v[156:159], v[180:183], v[112:115]
	v_mfma_f32_16x16x32_bf16 v[104:107], v[164:167], v[180:183], v[104:107]
	v_mfma_f32_16x16x32_bf16 v[96:99], v[156:159], v[188:191], v[96:99]
	v_mfma_f32_16x16x32_bf16 v[88:91], v[164:167], v[188:191], v[88:91]
	v_mfma_f32_16x16x32_bf16 v[80:83], v[156:159], v[196:199], v[80:83]
	v_mfma_f32_16x16x32_bf16 v[72:75], v[164:167], v[196:199], v[72:75]
	s_setprio 0
	s_barrier
	s_add_i32 s52, s43, s28
	s_mov_b32 m0, s52
	ds_read_b128 v[202:205], v151
	ds_read_b128 v[206:209], v151 offset:1024
	ds_read_b128 v[210:213], v151 offset:2048
	ds_read_b128 v[214:217], v151 offset:3072
	global_load_lds_dwordx4 v130, s[20:21]
	s_add_i32 m0, s52, 0x2000
	s_nop 0
	global_load_lds_dwordx4 v134, s[20:21]
	s_barrier
	s_waitcnt lgkmcnt(0)
	s_setprio 1
	s_waitcnt lgkmcnt(0)
	v_mfma_f32_16x16x32_bf16 v[116:119], v[202:205], v[168:171], 0
	v_mfma_f32_16x16x32_bf16 v[108:111], v[210:213], v[168:171], 0
	v_mfma_f32_16x16x32_bf16 v[100:103], v[202:205], v[176:179], 0
	v_mfma_f32_16x16x32_bf16 v[92:95], v[210:213], v[176:179], 0
	v_mfma_f32_16x16x32_bf16 v[84:87], v[202:205], v[184:187], 0
	v_mfma_f32_16x16x32_bf16 v[76:79], v[210:213], v[184:187], 0
	v_mfma_f32_16x16x32_bf16 v[68:71], v[202:205], v[192:195], 0
	v_mfma_f32_16x16x32_bf16 v[64:67], v[210:213], v[192:195], 0
	v_mfma_f32_16x16x32_bf16 v[116:119], v[206:209], v[172:175], v[116:119]
	v_mfma_f32_16x16x32_bf16 v[108:111], v[214:217], v[172:175], v[108:111]
	v_mfma_f32_16x16x32_bf16 v[100:103], v[206:209], v[180:183], v[100:103]
	v_mfma_f32_16x16x32_bf16 v[92:95], v[214:217], v[180:183], v[92:95]
	v_mfma_f32_16x16x32_bf16 v[84:87], v[206:209], v[188:191], v[84:87]
	v_mfma_f32_16x16x32_bf16 v[76:79], v[214:217], v[188:191], v[76:79]
	v_mfma_f32_16x16x32_bf16 v[68:71], v[206:209], v[196:199], v[68:71]
	v_mfma_f32_16x16x32_bf16 v[64:67], v[214:217], v[196:199], v[64:67]
	s_setprio 0
	s_mov_b32 m0, s17
	v_lshl_add_u64 v[222:223], s[22:23], 0, v[128:129]
	s_barrier
	ds_read_b128 v[168:171], v150 offset:16384
	ds_read_b128 v[172:175], v150 offset:17408
	ds_read_b128 v[176:179], v150 offset:18432
	ds_read_b128 v[180:183], v150 offset:19456
	ds_read_b128 v[184:187], v150 offset:20480
	ds_read_b128 v[188:191], v150 offset:21504
	ds_read_b128 v[192:195], v150 offset:22528
	ds_read_b128 v[196:199], v150 offset:23552
	global_load_lds_dwordx4 v128, s[22:23]
	v_lshl_add_u64 v[224:225], s[22:23], 0, v[132:133]
	s_mov_b32 m0, s29
	s_nop 0
	global_load_lds_dwordx4 v132, s[22:23]
	s_barrier
	s_waitcnt lgkmcnt(0)
	s_setprio 1
	s_waitcnt lgkmcnt(0)
	v_mfma_f32_16x16x32_bf16 v[60:63], v[152:155], v[168:171], 0
	v_mfma_f32_16x16x32_bf16 v[56:59], v[160:163], v[168:171], 0
	v_mfma_f32_16x16x32_bf16 v[48:51], v[152:155], v[176:179], 0
	v_mfma_f32_16x16x32_bf16 v[40:43], v[160:163], v[176:179], 0
	v_mfma_f32_16x16x32_bf16 v[32:35], v[152:155], v[184:187], 0
	v_mfma_f32_16x16x32_bf16 v[24:27], v[160:163], v[184:187], 0
	v_mfma_f32_16x16x32_bf16 v[16:19], v[152:155], v[192:195], 0
	v_mfma_f32_16x16x32_bf16 v[8:11], v[160:163], v[192:195], 0
	v_mfma_f32_16x16x32_bf16 v[60:63], v[156:159], v[172:175], v[60:63]
	v_mfma_f32_16x16x32_bf16 v[56:59], v[164:167], v[172:175], v[56:59]
	v_mfma_f32_16x16x32_bf16 v[48:51], v[156:159], v[180:183], v[48:51]
	v_mfma_f32_16x16x32_bf16 v[40:43], v[164:167], v[180:183], v[40:43]
	v_mfma_f32_16x16x32_bf16 v[32:35], v[156:159], v[188:191], v[32:35]
	v_mfma_f32_16x16x32_bf16 v[24:27], v[164:167], v[188:191], v[24:27]
	v_mfma_f32_16x16x32_bf16 v[16:19], v[156:159], v[196:199], v[16:19]
	v_mfma_f32_16x16x32_bf16 v[8:11], v[164:167], v[196:199], v[8:11]
	s_setprio 0
	s_barrier
; #define PG8_STAGE(bufoff, gbase, voff) do { _Pragma("unroll") for (int _i = 0; _i < 2; ++_i) \
;         __builtin_amdgcn_global_load_lds((const unsigned*)((const char*)(gbase) + (voff)[_i]), (LAS unsigned*)(lds + (bufoff) + ldsw + _i * 8192), 16, 0, 0); } while (0)
; #define PG8_LDA(dst, b, h) do { _Pragma("unroll") for (int m = 0; m < 4; ++m) _Pragma("unroll") for (int k = 0; k < 2; ++k) dst[m][k] = *(const LAS bf16x8*)(lds + PG8_SA(b, h) + aoff + m * 2048 + k * 1024); } while (0)
; #define PG8_LDB(dst, b, h) do { _Pragma("unroll") for (int n = 0; n < 2; ++n) _Pragma("unroll") for (int k = 0; k < 2; ++k) dst[n][k] = *(const LAS bf16x8*)(lds + PG8_SB(b, h) + boff + n * 2048 + k * 1024); } while (0)
; #define PG8_MMA(ai, bj, At, Bt) do { __builtin_amdgcn_s_setprio(1); _Pragma("unroll") for (int m = 0; m < 4; ++m) _Pragma("unroll") for (int n = 0; n < 2; ++n) _Pragma("unroll") for (int k = 0; k < 2; ++k) \
;         acc[ai][bj][m][n] = __builtin_amdgcn_mfma_f32_16x16x32_bf16(Bt[n][k], At[m][k], acc[ai][bj][m][n], 0, 0, 0); __builtin_amdgcn_s_setprio(0); } while (0)
; #define PG8_WAIT_V(n) asm volatile("s_waitcnt vmcnt(" #n ")" ::: "memory")
; #define PG8_WAIT_L(n) asm volatile("s_waitcnt lgkmcnt(" #n ")" ::: "memory")
; #define PG8_BAR __builtin_amdgcn_s_barrier()
; #define PG8_SCHED __builtin_amdgcn_sched_barrier(0)
; template <class Epi, class Sched>
; __device__ __forceinline__ void gemm_phase(LAS unsigned char* lds, const Gemm g, const Sched& S, const Epi& E) {
;     ...
;             PG8_STAGE(PG8_SB(0, 1), b2 + hstep, voffB);
;             PG8_WAIT_V(6); PG8_BAR; PG8_MMA(1, 1, At, B1); PG8_BAR;
;             PG8_LDB(B0, 1, 0); PG8_SCHED; PG8_LDA(At, 1, 0); PG8_STAGE(PG8_SA(0, 1), a2 + hstep, voffA);
;             PG8_WAIT_L(8); PG8_BAR; PG8_WAIT_L(0); PG8_MMA(0, 0, At, B0); PG8_BAR; PG8_SCHED;
;             PG8_LDB(B1, 1, 1); PG8_STAGE(PG8_SB(1, 0), b3, voffB);
;             PG8_BAR; PG8_WAIT_L(0); PG8_MMA(0, 1, At, B1); PG8_BAR;
;             PG8_LDA(At, 1, 1); PG8_STAGE(PG8_SA(1, 0), a3, voffA);
	s_add_u32 s52, s20, 0x40000
	s_addc_u32 s53, s21, 0
	s_add_i32 s54, s44, s28
	s_mov_b32 m0, s54
	s_nop 0
	global_load_lds_dwordx4 v130, s[52:53]
	s_add_i32 m0, s54, 0x2000
	s_nop 0
	global_load_lds_dwordx4 v134, s[52:53]
	s_waitcnt vmcnt(6)
	s_barrier
	s_setprio 1
	v_mfma_f32_16x16x32_bf16 v[52:55], v[202:205], v[168:171], 0
	v_mfma_f32_16x16x32_bf16 v[44:47], v[210:213], v[168:171], 0
	v_mfma_f32_16x16x32_bf16 v[36:39], v[202:205], v[176:179], 0
	v_mfma_f32_16x16x32_bf16 v[28:31], v[210:213], v[176:179], 0
	v_mfma_f32_16x16x32_bf16 v[20:23], v[202:205], v[184:187], 0
	v_mfma_f32_16x16x32_bf16 v[12:15], v[210:213], v[184:187], 0
	v_mfma_f32_16x16x32_bf16 v[4:7], v[202:205], v[192:195], 0
	v_mfma_f32_16x16x32_bf16 v[0:3], v[210:213], v[192:195], 0
	v_mfma_f32_16x16x32_bf16 v[52:55], v[206:209], v[172:175], v[52:55]
	v_mfma_f32_16x16x32_bf16 v[44:47], v[214:217], v[172:175], v[44:47]
	v_mfma_f32_16x16x32_bf16 v[36:39], v[206:209], v[180:183], v[36:39]
	v_mfma_f32_16x16x32_bf16 v[28:31], v[214:217], v[180:183], v[28:31]
	v_mfma_f32_16x16x32_bf16 v[20:23], v[206:209], v[188:191], v[20:23]
	v_mfma_f32_16x16x32_bf16 v[12:15], v[214:217], v[188:191], v[12:15]
	v_mfma_f32_16x16x32_bf16 v[4:7], v[206:209], v[196:199], v[4:7]
	v_mfma_f32_16x16x32_bf16 v[0:3], v[214:217], v[196:199], v[0:3]
	s_setprio 0
	s_add_i32 s52, 0, 0x18000
	v_add_u32_e32 v136, s52, v148
	s_barrier
	ds_read_b128 v[152:155], v136
	ds_read_b128 v[156:159], v136 offset:1024
	ds_read_b128 v[160:163], v136 offset:2048
	ds_read_b128 v[164:167], v136 offset:3072
	s_add_u32 s22, s22, 0x40000
	s_addc_u32 s23, s23, 0
	s_mov_b32 m0, s30
	ds_read_b128 v[168:171], v150 offset:32768
	ds_read_b128 v[172:175], v150 offset:33792
	ds_read_b128 v[176:179], v150 offset:34816
	ds_read_b128 v[180:183], v150 offset:35840
	ds_read_b128 v[184:187], v150 offset:36864
	ds_read_b128 v[188:191], v150 offset:37888
	ds_read_b128 v[192:195], v150 offset:38912
	ds_read_b128 v[196:199], v150 offset:39936
	global_load_lds_dwordx4 v128, s[22:23]
	s_mov_b32 m0, s31
	s_nop 0
	global_load_lds_dwordx4 v132, s[22:23]
	s_waitcnt lgkmcnt(8)
	s_barrier
	s_waitcnt lgkmcnt(0)
	s_setprio 1
	s_waitcnt lgkmcnt(0)
	v_mfma_f32_16x16x32_bf16 v[124:127], v[152:155], v[168:171], v[124:127]
	v_mfma_f32_16x16x32_bf16 v[120:123], v[160:163], v[168:171], v[120:123]
	v_mfma_f32_16x16x32_bf16 v[112:115], v[152:155], v[176:179], v[112:115]
	v_mfma_f32_16x16x32_bf16 v[104:107], v[160:163], v[176:179], v[104:107]
	v_mfma_f32_16x16x32_bf16 v[96:99], v[152:155], v[184:187], v[96:99]
	v_mfma_f32_16x16x32_bf16 v[88:91], v[160:163], v[184:187], v[88:91]
	v_mfma_f32_16x16x32_bf16 v[80:83], v[152:155], v[192:195], v[80:83]
	v_mfma_f32_16x16x32_bf16 v[72:75], v[160:163], v[192:195], v[72:75]
	v_mfma_f32_16x16x32_bf16 v[124:127], v[156:159], v[172:175], v[124:127]
	v_mfma_f32_16x16x32_bf16 v[120:123], v[164:167], v[172:175], v[120:123]
	v_mfma_f32_16x16x32_bf16 v[112:115], v[156:159], v[180:183], v[112:115]
	v_mfma_f32_16x16x32_bf16 v[104:107], v[164:167], v[180:183], v[104:107]
	v_mfma_f32_16x16x32_bf16 v[96:99], v[156:159], v[188:191], v[96:99]
	v_mfma_f32_16x16x32_bf16 v[88:91], v[164:167], v[188:191], v[88:91]
	v_mfma_f32_16x16x32_bf16 v[80:83], v[156:159], v[196:199], v[80:83]
	v_mfma_f32_16x16x32_bf16 v[72:75], v[164:167], v[196:199], v[72:75]
	s_setprio 0
	s_barrier
	s_add_i32 s22, 0, 0x1c000
	s_add_i32 s23, s52, s28
	v_add_u32_e32 v136, s22, v148
	s_add_u32 s0, s20, 0x80
	s_addc_u32 s1, s21, 0
	s_mov_b32 m0, s23
	ds_read_b128 v[202:205], v136
	ds_read_b128 v[206:209], v136 offset:1024
	ds_read_b128 v[210:213], v136 offset:2048
	ds_read_b128 v[214:217], v136 offset:3072
	global_load_lds_dwordx4 v130, s[0:1]
	s_add_i32 m0, s23, 0x2000
	s_nop 0
	global_load_lds_dwordx4 v134, s[0:1]
	s_barrier
	s_waitcnt lgkmcnt(0)
	s_setprio 1
	s_waitcnt lgkmcnt(0)
	v_mfma_f32_16x16x32_bf16 v[116:119], v[202:205], v[168:171], v[116:119]
	v_mfma_f32_16x16x32_bf16 v[108:111], v[210:213], v[168:171], v[108:111]
	v_mfma_f32_16x16x32_bf16 v[100:103], v[202:205], v[176:179], v[100:103]
	v_mfma_f32_16x16x32_bf16 v[92:95], v[210:213], v[176:179], v[92:95]
	v_mfma_f32_16x16x32_bf16 v[84:87], v[202:205], v[184:187], v[84:87]
	v_mfma_f32_16x16x32_bf16 v[76:79], v[210:213], v[184:187], v[76:79]
	v_mfma_f32_16x16x32_bf16 v[68:71], v[202:205], v[192:195], v[68:71]
	v_mfma_f32_16x16x32_bf16 v[64:67], v[210:213], v[192:195], v[64:67]
	v_mfma_f32_16x16x32_bf16 v[116:119], v[206:209], v[172:175], v[116:119]
	v_mfma_f32_16x16x32_bf16 v[108:111], v[214:217], v[172:175], v[108:111]
	v_mfma_f32_16x16x32_bf16 v[100:103], v[206:209], v[180:183], v[100:103]
	v_mfma_f32_16x16x32_bf16 v[92:95], v[214:217], v[180:183], v[92:95]
	v_mfma_f32_16x16x32_bf16 v[84:87], v[206:209], v[188:191], v[84:87]
	v_mfma_f32_16x16x32_bf16 v[76:79], v[214:217], v[188:191], v[76:79]
	v_mfma_f32_16x16x32_bf16 v[68:71], v[206:209], v[196:199], v[68:71]
	v_mfma_f32_16x16x32_bf16 v[64:67], v[214:217], v[196:199], v[64:67]
	s_setprio 0
	s_mov_b32 m0, s36
	s_mov_b64 s[0:1], 0x80
	v_lshl_add_u64 v[218:219], v[222:223], 0, s[0:1]
	s_barrier
	ds_read_b128 v[168:171], v150 offset:49152
	ds_read_b128 v[172:175], v150 offset:50176
	ds_read_b128 v[176:179], v150 offset:51200
	ds_read_b128 v[180:183], v150 offset:52224
	ds_read_b128 v[184:187], v150 offset:53248
	ds_read_b128 v[188:191], v150 offset:54272
	ds_read_b128 v[192:195], v150 offset:55296
	ds_read_b128 v[196:199], v150 offset:56320
	global_load_lds_dwordx4 v[218:219], off
	v_lshl_add_u64 v[218:219], v[224:225], 0, s[0:1]
	s_mov_b32 m0, s37
	s_nop 0
	global_load_lds_dwordx4 v[218:219], off
	s_barrier
; #define PG8_STAGE(bufoff, gbase, voff) do { _Pragma("unroll") for (int _i = 0; _i < 2; ++_i) \
;         __builtin_amdgcn_global_load_lds((const unsigned*)((const char*)(gbase) + (voff)[_i]), (LAS unsigned*)(lds + (bufoff) + ldsw + _i * 8192), 16, 0, 0); } while (0)
; #define PG8_LDA(dst, b, h) do { _Pragma("unroll") for (int m = 0; m < 4; ++m) _Pragma("unroll") for (int k = 0; k < 2; ++k) dst[m][k] = *(const LAS bf16x8*)(lds + PG8_SA(b, h) + aoff + m * 2048 + k * 1024); } while (0)
; #define PG8_WAIT_V(n) asm volatile("s_waitcnt vmcnt(" #n ")" ::: "memory")
; #define PG8_WAIT_L(n) asm volatile("s_waitcnt lgkmcnt(" #n ")" ::: "memory")
; template <class Epi, class Sched>
; __device__ __forceinline__ void gemm_phase(LAS unsigned char* lds, const Gemm g, const Sched& S, const Epi& E) {
;     ...
;         for (int t = 0; t < nt; t += 2) {
;             const bool last = (t == nt - 2);
;             const char* a1 = cA + (size_t)(t + 1) * kstep;
;             const char* a2 = last ? nA : cA + (size_t)(t + 2) * kstep; const char* b2 = last ? nB : cB + (size_t)(t + 2) * kstep;
;             const char* a3 = a2 + kstep; const char* b3 = b2 + kstep;
;             PG8_LDB(B0, 0, 0); PG8_SCHED; PG8_LDA(At, 0, 0); PG8_STAGE(PG8_SA(1, 1), a1 + hstep, voffA);
;             PG8_WAIT_L(8); PG8_BAR; PG8_WAIT_L(0); PG8_MMA(0, 0, At, B0); PG8_BAR; PG8_SCHED;
;             PG8_LDB(B1, 0, 1); PG8_STAGE(PG8_SB(0, 0), b2, voffB);
;             PG8_BAR; PG8_WAIT_L(0); PG8_MMA(0, 1, At, B1); PG8_BAR;
;             PG8_LDA(At, 0, 1); PG8_STAGE(PG8_SA(0, 0), a2, voffA);
;             PG8_BAR; PG8_WAIT_L(0); PG8_MMA(1, 0, At, B0); PG8_BAR; PG8_SCHED;
;             PG8_STAGE(PG8_SB(0, 1), b2 + hstep, voffB);
;             PG8_WAIT_V(6); PG8_BAR; PG8_MMA(1, 1, At, B1); PG8_BAR;
;             PG8_LDB(B0, 1, 0); PG8_SCHED; PG8_LDA(At, 1, 0); PG8_STAGE(PG8_SA(0, 1), a2 + hstep, voffA);
;             PG8_WAIT_L(8); PG8_BAR; PG8_WAIT_L(0); PG8_MMA(0, 0, At, B0); PG8_BAR; PG8_SCHED;
;             PG8_LDB(B1, 1, 1); PG8_STAGE(PG8_SB(1, 0), b3, voffB);
;             PG8_BAR; PG8_WAIT_L(0); PG8_MMA(0, 1, At, B1); PG8_BAR;
;             PG8_LDA(At, 1, 1); PG8_STAGE(PG8_SA(1, 0), a3, voffA);
;             PG8_BAR; PG8_WAIT_L(0); PG8_MMA(1, 0, At, B0); PG8_BAR; PG8_SCHED;
;             PG8_STAGE(PG8_SB(1, 1), b3 + hstep, voffB);
;             PG8_WAIT_V(6); PG8_BAR; PG8_MMA(1, 1, At, B1); PG8_BAR;
	s_waitcnt lgkmcnt(0)
	s_setprio 1
	s_waitcnt lgkmcnt(0)
	v_mfma_f32_16x16x32_bf16 v[60:63], v[152:155], v[168:171], v[60:63]
	v_mfma_f32_16x16x32_bf16 v[56:59], v[160:163], v[168:171], v[56:59]
	v_mfma_f32_16x16x32_bf16 v[48:51], v[152:155], v[176:179], v[48:51]
	v_mfma_f32_16x16x32_bf16 v[40:43], v[160:163], v[176:179], v[40:43]
	v_mfma_f32_16x16x32_bf16 v[32:35], v[152:155], v[184:187], v[32:35]
	v_mfma_f32_16x16x32_bf16 v[24:27], v[160:163], v[184:187], v[24:27]
	v_mfma_f32_16x16x32_bf16 v[16:19], v[152:155], v[192:195], v[16:19]
	v_mfma_f32_16x16x32_bf16 v[8:11], v[160:163], v[192:195], v[8:11]
	v_mfma_f32_16x16x32_bf16 v[60:63], v[156:159], v[172:175], v[60:63]
	v_mfma_f32_16x16x32_bf16 v[56:59], v[164:167], v[172:175], v[56:59]
	v_mfma_f32_16x16x32_bf16 v[48:51], v[156:159], v[180:183], v[48:51]
	v_mfma_f32_16x16x32_bf16 v[40:43], v[164:167], v[180:183], v[40:43]
	v_mfma_f32_16x16x32_bf16 v[32:35], v[156:159], v[188:191], v[32:35]
	v_mfma_f32_16x16x32_bf16 v[24:27], v[164:167], v[188:191], v[24:27]
	v_mfma_f32_16x16x32_bf16 v[16:19], v[156:159], v[196:199], v[16:19]
	v_mfma_f32_16x16x32_bf16 v[8:11], v[164:167], v[196:199], v[8:11]
	s_setprio 0
	s_barrier
	s_add_u32 s20, s20, 0x40080
	s_addc_u32 s21, s21, 0
	s_add_i32 s22, s22, s28
	s_mov_b32 m0, s22
	s_nop 0
	global_load_lds_dwordx4 v130, s[20:21]
	s_add_i32 m0, s22, 0x2000
	s_nop 0
	global_load_lds_dwordx4 v134, s[20:21]
	s_waitcnt vmcnt(6)
	s_barrier
	s_setprio 1
	v_mfma_f32_16x16x32_bf16 v[52:55], v[202:205], v[168:171], v[52:55]
	v_mfma_f32_16x16x32_bf16 v[44:47], v[210:213], v[168:171], v[44:47]
	v_mfma_f32_16x16x32_bf16 v[36:39], v[202:205], v[176:179], v[36:39]
	v_mfma_f32_16x16x32_bf16 v[28:31], v[210:213], v[176:179], v[28:31]
	v_mfma_f32_16x16x32_bf16 v[20:23], v[202:205], v[184:187], v[20:23]
	v_mfma_f32_16x16x32_bf16 v[12:15], v[210:213], v[184:187], v[12:15]
	v_mfma_f32_16x16x32_bf16 v[4:7], v[202:205], v[192:195], v[4:7]
	v_mfma_f32_16x16x32_bf16 v[0:3], v[210:213], v[192:195], v[0:3]
	v_mfma_f32_16x16x32_bf16 v[52:55], v[206:209], v[172:175], v[52:55]
	v_mfma_f32_16x16x32_bf16 v[44:47], v[214:217], v[172:175], v[44:47]
	v_mfma_f32_16x16x32_bf16 v[36:39], v[206:209], v[180:183], v[36:39]
	v_mfma_f32_16x16x32_bf16 v[28:31], v[214:217], v[180:183], v[28:31]
	v_mfma_f32_16x16x32_bf16 v[20:23], v[206:209], v[188:191], v[20:23]
	v_mfma_f32_16x16x32_bf16 v[12:15], v[214:217], v[188:191], v[12:15]
	v_mfma_f32_16x16x32_bf16 v[4:7], v[206:209], v[196:199], v[4:7]
	v_mfma_f32_16x16x32_bf16 v[0:3], v[214:217], v[196:199], v[0:3]
	s_setprio 0
	s_add_i32 s51, s51, 2
	s_add_u32 s18, s18, 0x100
	s_addc_u32 s19, s19, 0
	s_add_u32 s48, s48, 0x100
	s_addc_u32 s49, s49, 0
	s_cmp_gt_u32 s51, 13
	s_barrier
.LBB0_673:
	ds_read_b128 v[152:155], v149
	ds_read_b128 v[156:159], v149 offset:1024
	ds_read_b128 v[160:163], v149 offset:2048
	ds_read_b128 v[164:167], v149 offset:3072
	s_add_u32 s20, s18, 0xfffc0080
	s_addc_u32 s21, s19, -1
	s_cmp_eq_u32 s51, 12
	s_cselect_b32 s23, s9, s21
	s_cselect_b32 s22, s46, s20
	s_cselect_b32 s21, s7, s49
	s_cselect_b32 s20, s47, s48
	s_add_i32 m0, s17, 0xc000
	ds_read_b128 v[168:171], v150
	ds_read_b128 v[172:175], v150 offset:1024
	ds_read_b128 v[176:179], v150 offset:2048
	ds_read_b128 v[180:183], v150 offset:3072
	ds_read_b128 v[184:187], v150 offset:4096
	ds_read_b128 v[188:191], v150 offset:5120
	ds_read_b128 v[192:195], v150 offset:6144
	ds_read_b128 v[196:199], v150 offset:7168
	global_load_lds_dwordx4 v138, s[18:19]
	s_add_i32 m0, s17, 0xe000
	s_nop 0
	global_load_lds_dwordx4 v140, s[18:19]
	s_waitcnt lgkmcnt(8)
	s_barrier
	s_waitcnt lgkmcnt(0)
	s_setprio 1
	s_waitcnt lgkmcnt(0)
	v_mfma_f32_16x16x32_bf16 v[124:127], v[152:155], v[168:171], v[124:127]
	v_mfma_f32_16x16x32_bf16 v[120:123], v[160:163], v[168:171], v[120:123]
	v_mfma_f32_16x16x32_bf16 v[112:115], v[152:155], v[176:179], v[112:115]
	v_mfma_f32_16x16x32_bf16 v[104:107], v[160:163], v[176:179], v[104:107]
	v_mfma_f32_16x16x32_bf16 v[96:99], v[152:155], v[184:187], v[96:99]
	v_mfma_f32_16x16x32_bf16 v[88:91], v[160:163], v[184:187], v[88:91]
	v_mfma_f32_16x16x32_bf16 v[80:83], v[152:155], v[192:195], v[80:83]
	v_mfma_f32_16x16x32_bf16 v[72:75], v[160:163], v[192:195], v[72:75]
	v_mfma_f32_16x16x32_bf16 v[124:127], v[156:159], v[172:175], v[124:127]
	v_mfma_f32_16x16x32_bf16 v[120:123], v[164:167], v[172:175], v[120:123]
	v_mfma_f32_16x16x32_bf16 v[112:115], v[156:159], v[180:183], v[112:115]
	v_mfma_f32_16x16x32_bf16 v[104:107], v[164:167], v[180:183], v[104:107]
	v_mfma_f32_16x16x32_bf16 v[96:99], v[156:159], v[188:191], v[96:99]
	v_mfma_f32_16x16x32_bf16 v[88:91], v[164:167], v[188:191], v[88:91]
	v_mfma_f32_16x16x32_bf16 v[80:83], v[156:159], v[196:199], v[80:83]
	v_mfma_f32_16x16x32_bf16 v[72:75], v[164:167], v[196:199], v[72:75]
	s_setprio 0
	s_barrier
	s_add_i32 s52, s43, s28
	s_mov_b32 m0, s52
	ds_read_b128 v[202:205], v151
	ds_read_b128 v[206:209], v151 offset:1024
	ds_read_b128 v[210:213], v151 offset:2048
	ds_read_b128 v[214:217], v151 offset:3072
	global_load_lds_dwordx4 v130, s[20:21]
	s_add_i32 m0, s52, 0x2000
	s_nop 0
	global_load_lds_dwordx4 v134, s[20:21]
	s_barrier
; #define PG8_STAGE(bufoff, gbase, voff) do { _Pragma("unroll") for (int _i = 0; _i < 2; ++_i) \
;         __builtin_amdgcn_global_load_lds((const unsigned*)((const char*)(gbase) + (voff)[_i]), (LAS unsigned*)(lds + (bufoff) + ldsw + _i * 8192), 16, 0, 0); } while (0)
; #define PG8_LDA(dst, b, h) do { _Pragma("unroll") for (int m = 0; m < 4; ++m) _Pragma("unroll") for (int k = 0; k < 2; ++k) dst[m][k] = *(const LAS bf16x8*)(lds + PG8_SA(b, h) + aoff + m * 2048 + k * 1024); } while (0)
; #define PG8_LDB(dst, b, h) do { _Pragma("unroll") for (int n = 0; n < 2; ++n) _Pragma("unroll") for (int k = 0; k < 2; ++k) dst[n][k] = *(const LAS bf16x8*)(lds + PG8_SB(b, h) + boff + n * 2048 + k * 1024); } while (0)
; #define PG8_MMA(ai, bj, At, Bt) do { __builtin_amdgcn_s_setprio(1); _Pragma("unroll") for (int m = 0; m < 4; ++m) _Pragma("unroll") for (int n = 0; n < 2; ++n) _Pragma("unroll") for (int k = 0; k < 2; ++k) \
;         acc[ai][bj][m][n] = __builtin_amdgcn_mfma_f32_16x16x32_bf16(Bt[n][k], At[m][k], acc[ai][bj][m][n], 0, 0, 0); __builtin_amdgcn_s_setprio(0); } while (0)
; #define PG8_WAIT_V(n) asm volatile("s_waitcnt vmcnt(" #n ")" ::: "memory")
; #define PG8_WAIT_L(n) asm volatile("s_waitcnt lgkmcnt(" #n ")" ::: "memory")
; #define PG8_BAR __builtin_amdgcn_s_barrier()
; #define PG8_SCHED __builtin_amdgcn_sched_barrier(0)
; template <class Epi, class Sched>
; __device__ __forceinline__ void gemm_phase(LAS unsigned char* lds, const Gemm g, const Sched& S, const Epi& E) {
;     ...
;             PG8_BAR; PG8_WAIT_L(0); PG8_MMA(0, 1, At, B1); PG8_BAR;
;             PG8_LDA(At, 0, 1); PG8_STAGE(PG8_SA(0, 0), a2, voffA);
;             PG8_BAR; PG8_WAIT_L(0); PG8_MMA(1, 0, At, B0); PG8_BAR; PG8_SCHED;
;             PG8_STAGE(PG8_SB(0, 1), b2 + hstep, voffB);
;             PG8_WAIT_V(6); PG8_BAR; PG8_MMA(1, 1, At, B1); PG8_BAR;
;             PG8_LDB(B0, 1, 0); PG8_SCHED; PG8_LDA(At, 1, 0); PG8_STAGE(PG8_SA(0, 1), a2 + hstep, voffA);
	s_waitcnt lgkmcnt(0)
	s_setprio 1
	s_waitcnt lgkmcnt(0)
	v_mfma_f32_16x16x32_bf16 v[116:119], v[202:205], v[168:171], v[116:119]
	v_mfma_f32_16x16x32_bf16 v[108:111], v[210:213], v[168:171], v[108:111]
	v_mfma_f32_16x16x32_bf16 v[100:103], v[202:205], v[176:179], v[100:103]
	v_mfma_f32_16x16x32_bf16 v[92:95], v[210:213], v[176:179], v[92:95]
	v_mfma_f32_16x16x32_bf16 v[84:87], v[202:205], v[184:187], v[84:87]
	v_mfma_f32_16x16x32_bf16 v[76:79], v[210:213], v[184:187], v[76:79]
	v_mfma_f32_16x16x32_bf16 v[68:71], v[202:205], v[192:195], v[68:71]
	v_mfma_f32_16x16x32_bf16 v[64:67], v[210:213], v[192:195], v[64:67]
	v_mfma_f32_16x16x32_bf16 v[116:119], v[206:209], v[172:175], v[116:119]
	v_mfma_f32_16x16x32_bf16 v[108:111], v[214:217], v[172:175], v[108:111]
	v_mfma_f32_16x16x32_bf16 v[100:103], v[206:209], v[180:183], v[100:103]
	v_mfma_f32_16x16x32_bf16 v[92:95], v[214:217], v[180:183], v[92:95]
	v_mfma_f32_16x16x32_bf16 v[84:87], v[206:209], v[188:191], v[84:87]
	v_mfma_f32_16x16x32_bf16 v[76:79], v[214:217], v[188:191], v[76:79]
	v_mfma_f32_16x16x32_bf16 v[68:71], v[206:209], v[196:199], v[68:71]
	v_mfma_f32_16x16x32_bf16 v[64:67], v[214:217], v[196:199], v[64:67]
	s_setprio 0
	s_mov_b32 m0, s17
	v_lshl_add_u64 v[222:223], s[22:23], 0, v[128:129]
	s_barrier
	ds_read_b128 v[168:171], v150 offset:16384
	ds_read_b128 v[172:175], v150 offset:17408
	ds_read_b128 v[176:179], v150 offset:18432
	ds_read_b128 v[180:183], v150 offset:19456
	ds_read_b128 v[184:187], v150 offset:20480
	ds_read_b128 v[188:191], v150 offset:21504
	ds_read_b128 v[192:195], v150 offset:22528
	ds_read_b128 v[196:199], v150 offset:23552
	global_load_lds_dwordx4 v128, s[22:23]
	v_lshl_add_u64 v[224:225], s[22:23], 0, v[132:133]
	s_mov_b32 m0, s29
	s_nop 0
	global_load_lds_dwordx4 v132, s[22:23]
	s_barrier
	s_waitcnt lgkmcnt(0)
	s_setprio 1
	s_waitcnt lgkmcnt(0)
	v_mfma_f32_16x16x32_bf16 v[60:63], v[152:155], v[168:171], v[60:63]
	v_mfma_f32_16x16x32_bf16 v[56:59], v[160:163], v[168:171], v[56:59]
	v_mfma_f32_16x16x32_bf16 v[48:51], v[152:155], v[176:179], v[48:51]
	v_mfma_f32_16x16x32_bf16 v[40:43], v[160:163], v[176:179], v[40:43]
	v_mfma_f32_16x16x32_bf16 v[32:35], v[152:155], v[184:187], v[32:35]
	v_mfma_f32_16x16x32_bf16 v[24:27], v[160:163], v[184:187], v[24:27]
	v_mfma_f32_16x16x32_bf16 v[16:19], v[152:155], v[192:195], v[16:19]
	v_mfma_f32_16x16x32_bf16 v[8:11], v[160:163], v[192:195], v[8:11]
	v_mfma_f32_16x16x32_bf16 v[60:63], v[156:159], v[172:175], v[60:63]
	v_mfma_f32_16x16x32_bf16 v[56:59], v[164:167], v[172:175], v[56:59]
	v_mfma_f32_16x16x32_bf16 v[48:51], v[156:159], v[180:183], v[48:51]
	v_mfma_f32_16x16x32_bf16 v[40:43], v[164:167], v[180:183], v[40:43]
	v_mfma_f32_16x16x32_bf16 v[32:35], v[156:159], v[188:191], v[32:35]
	v_mfma_f32_16x16x32_bf16 v[24:27], v[164:167], v[188:191], v[24:27]
	v_mfma_f32_16x16x32_bf16 v[16:19], v[156:159], v[196:199], v[16:19]
	v_mfma_f32_16x16x32_bf16 v[8:11], v[164:167], v[196:199], v[8:11]
	s_setprio 0
	s_barrier
	s_add_u32 s52, s20, 0x40000
	s_addc_u32 s53, s21, 0
	s_add_i32 s54, s44, s28
	s_mov_b32 m0, s54
	s_nop 0
	global_load_lds_dwordx4 v130, s[52:53]
	s_add_i32 m0, s54, 0x2000
	s_nop 0
	global_load_lds_dwordx4 v134, s[52:53]
	s_waitcnt vmcnt(6)
	s_barrier
	s_setprio 1
	v_mfma_f32_16x16x32_bf16 v[52:55], v[202:205], v[168:171], v[52:55]
	v_mfma_f32_16x16x32_bf16 v[44:47], v[210:213], v[168:171], v[44:47]
	v_mfma_f32_16x16x32_bf16 v[36:39], v[202:205], v[176:179], v[36:39]
	v_mfma_f32_16x16x32_bf16 v[28:31], v[210:213], v[176:179], v[28:31]
	v_mfma_f32_16x16x32_bf16 v[20:23], v[202:205], v[184:187], v[20:23]
	v_mfma_f32_16x16x32_bf16 v[12:15], v[210:213], v[184:187], v[12:15]
	v_mfma_f32_16x16x32_bf16 v[4:7], v[202:205], v[192:195], v[4:7]
	v_mfma_f32_16x16x32_bf16 v[0:3], v[210:213], v[192:195], v[0:3]
	v_mfma_f32_16x16x32_bf16 v[52:55], v[206:209], v[172:175], v[52:55]
	v_mfma_f32_16x16x32_bf16 v[44:47], v[214:217], v[172:175], v[44:47]
	v_mfma_f32_16x16x32_bf16 v[36:39], v[206:209], v[180:183], v[36:39]
	v_mfma_f32_16x16x32_bf16 v[28:31], v[214:217], v[180:183], v[28:31]
	v_mfma_f32_16x16x32_bf16 v[20:23], v[206:209], v[188:191], v[20:23]
	v_mfma_f32_16x16x32_bf16 v[12:15], v[214:217], v[188:191], v[12:15]
	v_mfma_f32_16x16x32_bf16 v[4:7], v[206:209], v[196:199], v[4:7]
	v_mfma_f32_16x16x32_bf16 v[0:3], v[214:217], v[196:199], v[0:3]
	s_setprio 0
	s_add_i32 s52, 0, 0x18000
	v_add_u32_e32 v136, s52, v148
	s_barrier
	ds_read_b128 v[152:155], v136
	ds_read_b128 v[156:159], v136 offset:1024
	ds_read_b128 v[160:163], v136 offset:2048
	ds_read_b128 v[164:167], v136 offset:3072
	s_add_u32 s22, s22, 0x40000
	s_addc_u32 s23, s23, 0
	s_mov_b32 m0, s30
	ds_read_b128 v[168:171], v150 offset:32768
	ds_read_b128 v[172:175], v150 offset:33792
	ds_read_b128 v[176:179], v150 offset:34816
	ds_read_b128 v[180:183], v150 offset:35840
	ds_read_b128 v[184:187], v150 offset:36864
	ds_read_b128 v[188:191], v150 offset:37888
	ds_read_b128 v[192:195], v150 offset:38912
	ds_read_b128 v[196:199], v150 offset:39936
	global_load_lds_dwordx4 v128, s[22:23]
	s_mov_b32 m0, s31
	s_nop 0
	global_load_lds_dwordx4 v132, s[22:23]
	s_waitcnt lgkmcnt(8)
	s_barrier
; #define PG8_STAGE(bufoff, gbase, voff) do { _Pragma("unroll") for (int _i = 0; _i < 2; ++_i) \
;         __builtin_amdgcn_global_load_lds((const unsigned*)((const char*)(gbase) + (voff)[_i]), (LAS unsigned*)(lds + (bufoff) + ldsw + _i * 8192), 16, 0, 0); } while (0)
; #define PG8_LDA(dst, b, h) do { _Pragma("unroll") for (int m = 0; m < 4; ++m) _Pragma("unroll") for (int k = 0; k < 2; ++k) dst[m][k] = *(const LAS bf16x8*)(lds + PG8_SA(b, h) + aoff + m * 2048 + k * 1024); } while (0)
; #define PG8_LDB(dst, b, h) do { _Pragma("unroll") for (int n = 0; n < 2; ++n) _Pragma("unroll") for (int k = 0; k < 2; ++k) dst[n][k] = *(const LAS bf16x8*)(lds + PG8_SB(b, h) + boff + n * 2048 + k * 1024); } while (0)
; #define PG8_MMA(ai, bj, At, Bt) do { __builtin_amdgcn_s_setprio(1); _Pragma("unroll") for (int m = 0; m < 4; ++m) _Pragma("unroll") for (int n = 0; n < 2; ++n) _Pragma("unroll") for (int k = 0; k < 2; ++k) \
;         acc[ai][bj][m][n] = __builtin_amdgcn_mfma_f32_16x16x32_bf16(Bt[n][k], At[m][k], acc[ai][bj][m][n], 0, 0, 0); __builtin_amdgcn_s_setprio(0); } while (0)
; #define PG8_WAIT_V(n) asm volatile("s_waitcnt vmcnt(" #n ")" ::: "memory")
; #define PG8_WAIT_L(n) asm volatile("s_waitcnt lgkmcnt(" #n ")" ::: "memory")
; #define PG8_BAR __builtin_amdgcn_s_barrier()
; #define PG8_SCHED __builtin_amdgcn_sched_barrier(0)
; template <class Epi, class Sched>
; __device__ __forceinline__ void gemm_phase(LAS unsigned char* lds, const Gemm g, const Sched& S, const Epi& E) {
;     ...
;             PG8_WAIT_L(8); PG8_BAR; PG8_WAIT_L(0); PG8_MMA(0, 0, At, B0); PG8_BAR; PG8_SCHED;
;             PG8_LDB(B1, 1, 1); PG8_STAGE(PG8_SB(1, 0), b3, voffB);
;             PG8_BAR; PG8_WAIT_L(0); PG8_MMA(0, 1, At, B1); PG8_BAR;
;             PG8_LDA(At, 1, 1); PG8_STAGE(PG8_SA(1, 0), a3, voffA);
;             PG8_BAR; PG8_WAIT_L(0); PG8_MMA(1, 0, At, B0); PG8_BAR; PG8_SCHED;
;             PG8_STAGE(PG8_SB(1, 1), b3 + hstep, voffB);
;             PG8_WAIT_V(6); PG8_BAR; PG8_MMA(1, 1, At, B1); PG8_BAR;
;         }
	s_waitcnt lgkmcnt(0)
	s_setprio 1
	s_waitcnt lgkmcnt(0)
	v_mfma_f32_16x16x32_bf16 v[124:127], v[152:155], v[168:171], v[124:127]
	v_mfma_f32_16x16x32_bf16 v[120:123], v[160:163], v[168:171], v[120:123]
	v_mfma_f32_16x16x32_bf16 v[112:115], v[152:155], v[176:179], v[112:115]
	v_mfma_f32_16x16x32_bf16 v[104:107], v[160:163], v[176:179], v[104:107]
	v_mfma_f32_16x16x32_bf16 v[96:99], v[152:155], v[184:187], v[96:99]
	v_mfma_f32_16x16x32_bf16 v[88:91], v[160:163], v[184:187], v[88:91]
	v_mfma_f32_16x16x32_bf16 v[80:83], v[152:155], v[192:195], v[80:83]
	v_mfma_f32_16x16x32_bf16 v[72:75], v[160:163], v[192:195], v[72:75]
	v_mfma_f32_16x16x32_bf16 v[124:127], v[156:159], v[172:175], v[124:127]
	v_mfma_f32_16x16x32_bf16 v[120:123], v[164:167], v[172:175], v[120:123]
	v_mfma_f32_16x16x32_bf16 v[112:115], v[156:159], v[180:183], v[112:115]
	v_mfma_f32_16x16x32_bf16 v[104:107], v[164:167], v[180:183], v[104:107]
	v_mfma_f32_16x16x32_bf16 v[96:99], v[156:159], v[188:191], v[96:99]
	v_mfma_f32_16x16x32_bf16 v[88:91], v[164:167], v[188:191], v[88:91]
	v_mfma_f32_16x16x32_bf16 v[80:83], v[156:159], v[196:199], v[80:83]
	v_mfma_f32_16x16x32_bf16 v[72:75], v[164:167], v[196:199], v[72:75]
	s_setprio 0
	s_barrier
	s_add_i32 s22, 0, 0x1c000
	s_add_i32 s23, s52, s28
	v_add_u32_e32 v136, s22, v148
	s_add_u32 s0, s20, 0x80
	s_addc_u32 s1, s21, 0
	s_mov_b32 m0, s23
	ds_read_b128 v[202:205], v136
	ds_read_b128 v[206:209], v136 offset:1024
	ds_read_b128 v[210:213], v136 offset:2048
	ds_read_b128 v[214:217], v136 offset:3072
	global_load_lds_dwordx4 v130, s[0:1]
	s_add_i32 m0, s23, 0x2000
	s_nop 0
	global_load_lds_dwordx4 v134, s[0:1]
	s_barrier
	s_waitcnt lgkmcnt(0)
	s_setprio 1
	s_waitcnt lgkmcnt(0)
	v_mfma_f32_16x16x32_bf16 v[116:119], v[202:205], v[168:171], v[116:119]
	v_mfma_f32_16x16x32_bf16 v[108:111], v[210:213], v[168:171], v[108:111]
	v_mfma_f32_16x16x32_bf16 v[100:103], v[202:205], v[176:179], v[100:103]
	v_mfma_f32_16x16x32_bf16 v[92:95], v[210:213], v[176:179], v[92:95]
	v_mfma_f32_16x16x32_bf16 v[84:87], v[202:205], v[184:187], v[84:87]
	v_mfma_f32_16x16x32_bf16 v[76:79], v[210:213], v[184:187], v[76:79]
	v_mfma_f32_16x16x32_bf16 v[68:71], v[202:205], v[192:195], v[68:71]
	v_mfma_f32_16x16x32_bf16 v[64:67], v[210:213], v[192:195], v[64:67]
	v_mfma_f32_16x16x32_bf16 v[116:119], v[206:209], v[172:175], v[116:119]
	v_mfma_f32_16x16x32_bf16 v[108:111], v[214:217], v[172:175], v[108:111]
	v_mfma_f32_16x16x32_bf16 v[100:103], v[206:209], v[180:183], v[100:103]
	v_mfma_f32_16x16x32_bf16 v[92:95], v[214:217], v[180:183], v[92:95]
	v_mfma_f32_16x16x32_bf16 v[84:87], v[206:209], v[188:191], v[84:87]
	v_mfma_f32_16x16x32_bf16 v[76:79], v[214:217], v[188:191], v[76:79]
	v_mfma_f32_16x16x32_bf16 v[68:71], v[206:209], v[196:199], v[68:71]
	v_mfma_f32_16x16x32_bf16 v[64:67], v[214:217], v[196:199], v[64:67]
	s_setprio 0
	s_mov_b32 m0, s36
	s_mov_b64 s[0:1], 0x80
	v_lshl_add_u64 v[218:219], v[222:223], 0, s[0:1]
	s_barrier
	ds_read_b128 v[168:171], v150 offset:49152
	ds_read_b128 v[172:175], v150 offset:50176
	ds_read_b128 v[176:179], v150 offset:51200
	ds_read_b128 v[180:183], v150 offset:52224
	ds_read_b128 v[184:187], v150 offset:53248
	ds_read_b128 v[188:191], v150 offset:54272
	ds_read_b128 v[192:195], v150 offset:55296
	ds_read_b128 v[196:199], v150 offset:56320
	global_load_lds_dwordx4 v[218:219], off
	v_lshl_add_u64 v[218:219], v[224:225], 0, s[0:1]
	s_mov_b32 m0, s37
	s_nop 0
	global_load_lds_dwordx4 v[218:219], off
	s_barrier
	s_waitcnt lgkmcnt(0)
	s_setprio 1
	s_waitcnt lgkmcnt(0)
	v_mfma_f32_16x16x32_bf16 v[60:63], v[152:155], v[168:171], v[60:63]
	v_mfma_f32_16x16x32_bf16 v[56:59], v[160:163], v[168:171], v[56:59]
	v_mfma_f32_16x16x32_bf16 v[48:51], v[152:155], v[176:179], v[48:51]
	v_mfma_f32_16x16x32_bf16 v[40:43], v[160:163], v[176:179], v[40:43]
	v_mfma_f32_16x16x32_bf16 v[32:35], v[152:155], v[184:187], v[32:35]
	v_mfma_f32_16x16x32_bf16 v[24:27], v[160:163], v[184:187], v[24:27]
	v_mfma_f32_16x16x32_bf16 v[16:19], v[152:155], v[192:195], v[16:19]
	v_mfma_f32_16x16x32_bf16 v[8:11], v[160:163], v[192:195], v[8:11]
	v_mfma_f32_16x16x32_bf16 v[60:63], v[156:159], v[172:175], v[60:63]
	v_mfma_f32_16x16x32_bf16 v[56:59], v[164:167], v[172:175], v[56:59]
	v_mfma_f32_16x16x32_bf16 v[48:51], v[156:159], v[180:183], v[48:51]
	v_mfma_f32_16x16x32_bf16 v[40:43], v[164:167], v[180:183], v[40:43]
	v_mfma_f32_16x16x32_bf16 v[32:35], v[156:159], v[188:191], v[32:35]
	v_mfma_f32_16x16x32_bf16 v[24:27], v[164:167], v[188:191], v[24:27]
	v_mfma_f32_16x16x32_bf16 v[16:19], v[156:159], v[196:199], v[16:19]
	v_mfma_f32_16x16x32_bf16 v[8:11], v[164:167], v[196:199], v[8:11]
	s_setprio 0
	s_barrier
	s_add_u32 s20, s20, 0x40080
	s_addc_u32 s21, s21, 0
	s_add_i32 s22, s22, s28
	s_mov_b32 m0, s22
	s_nop 0
	global_load_lds_dwordx4 v130, s[20:21]
	s_add_i32 m0, s22, 0x2000
	s_nop 0
	global_load_lds_dwordx4 v134, s[20:21]
	s_waitcnt vmcnt(6)
	s_barrier
	s_setprio 1
	v_mfma_f32_16x16x32_bf16 v[52:55], v[202:205], v[168:171], v[52:55]
	v_mfma_f32_16x16x32_bf16 v[44:47], v[210:213], v[168:171], v[44:47]
	v_mfma_f32_16x16x32_bf16 v[36:39], v[202:205], v[176:179], v[36:39]
	v_mfma_f32_16x16x32_bf16 v[28:31], v[210:213], v[176:179], v[28:31]
	v_mfma_f32_16x16x32_bf16 v[20:23], v[202:205], v[184:187], v[20:23]
	v_mfma_f32_16x16x32_bf16 v[12:15], v[210:213], v[184:187], v[12:15]
	v_mfma_f32_16x16x32_bf16 v[4:7], v[202:205], v[192:195], v[4:7]
	v_mfma_f32_16x16x32_bf16 v[0:3], v[210:213], v[192:195], v[0:3]
	v_mfma_f32_16x16x32_bf16 v[52:55], v[206:209], v[172:175], v[52:55]
	v_mfma_f32_16x16x32_bf16 v[44:47], v[214:217], v[172:175], v[44:47]
	v_mfma_f32_16x16x32_bf16 v[36:39], v[206:209], v[180:183], v[36:39]
	v_mfma_f32_16x16x32_bf16 v[28:31], v[214:217], v[180:183], v[28:31]
	v_mfma_f32_16x16x32_bf16 v[20:23], v[206:209], v[188:191], v[20:23]
	v_mfma_f32_16x16x32_bf16 v[12:15], v[214:217], v[188:191], v[12:15]
	v_mfma_f32_16x16x32_bf16 v[4:7], v[206:209], v[196:199], v[4:7]
	v_mfma_f32_16x16x32_bf16 v[0:3], v[214:217], v[196:199], v[0:3]
	s_setprio 0
	s_add_i32 s51, s51, 2
	s_add_u32 s18, s18, 0x100
	s_addc_u32 s19, s19, 0
	s_add_u32 s48, s48, 0x100
	s_addc_u32 s49, s49, 0
	s_cmp_gt_u32 s51, 13
	s_barrier
; __device__ __forceinline__ unsigned cvt_pk_bf16(float lo, float hi) { unsigned r; asm volatile("v_cvt_pk_bf16_f32 %0, %1, %2" : "=v"(r) : "v"(lo), "v"(hi)); return r; }
;     __device__ __forceinline__ void operator()(const AccT& acc, const Unit& u, int wr, int wc, int fr, int fq) const {
;     ...
;         const int rbase = u.pm * 256 + wr * 64 + fr;
;         const int tb = u.pn * 256 + wc * 32 + 8 * fq;
; #pragma unroll
;         for (int ai = 0; ai < 2; ++ai)
; #pragma unroll
;             for (int m = 0; m < 4; ++m) {
;                 const int gm = rbase + ai * 128 + m * 16;
; #pragma unroll
;                 for (int bj = 0; bj < 2; ++bj) {
;                     const int t0 = tb + bj * 128;
;                     const f32x4 v0 = acc[ai][bj][m][0], v1 = acc[ai][bj][m][1];
;                     u32x4 w; w.x = cvt_pk_bf16(v0[0], v0[1]); w.y = cvt_pk_bf16(v0[2], v0[3]); w.z = cvt_pk_bf16(v1[0], v1[1]); w.w = cvt_pk_bf16(v1[2], v1[3]);
;                     *(u32x4*)(YT + ((size_t)((t0 >> 10) * 512 + gm)) * 2048 + part * 1024 + (t0 & 1023)) = w;
;                 }
;             }
	s_cbranch_scc0 .LBB0_673
	v_mov_b32_e32 v136, v147
	v_mov_b32_e32 v152, v146
	s_lshl_b32 s7, s16, 8
	s_add_i32 s7, s7, s34
	v_add_u32_e32 v152, s7, v152
	s_lshl_b32 s7, s45, 8
	s_or_b32 s7, s7, s35
	v_lshl_add_u32 v153, v136, 3, s7
	v_cvt_pk_bf16_f32 v124, v124, v125
	v_cvt_pk_bf16_f32 v125, v126, v127
	v_cvt_pk_bf16_f32 v126, v120, v121
	v_ashrrev_i32_e32 v120, 1, v153
	v_cvt_pk_bf16_f32 v127, v122, v123
	v_and_b32_e32 v122, 0xfffffe00, v120
	v_add_u32_e32 v120, v122, v152
	v_ashrrev_i32_e32 v121, 31, v120
	v_lshlrev_b64 v[120:121], 12, v[120:121]
	v_and_b32_e32 v123, 0x3f8, v153
	v_lshl_add_u64 v[120:121], s[4:5], 0, v[120:121]
	v_lshlrev_b32_e32 v136, 1, v123
	v_lshl_add_u64 v[120:121], v[120:121], 0, v[136:137]
	global_store_dwordx4 v[120:121], v[124:127], off
	v_add_u32_e32 v120, 0x80, v153
	v_cvt_pk_bf16_f32 v116, v116, v117
	v_cvt_pk_bf16_f32 v117, v118, v119
	v_cvt_pk_bf16_f32 v118, v108, v109
	v_ashrrev_i32_e32 v108, 1, v120
	v_and_b32_e32 v121, 0xfffffe00, v108
	v_add_u32_e32 v108, v121, v152
	v_ashrrev_i32_e32 v109, 31, v108
	v_lshlrev_b64 v[108:109], 12, v[108:109]
	v_cvt_pk_bf16_f32 v119, v110, v111
	v_lshl_add_u64 v[110:111], s[4:5], 0, v[108:109]
	v_and_b32_e32 v108, 0x3f8, v120
	v_lshlrev_b32_e32 v108, 1, v108
	v_mov_b32_e32 v109, v137
	v_lshl_add_u64 v[110:111], v[110:111], 0, v[108:109]
	global_store_dwordx4 v[110:111], v[116:119], off
	v_cvt_pk_bf16_f32 v110, v112, v113
	v_cvt_pk_bf16_f32 v111, v114, v115
	v_cvt_pk_bf16_f32 v112, v104, v105
	v_cvt_pk_bf16_f32 v113, v106, v107
	s_and_b64 vcc, exec, s[2:3]
	s_nop 0
	v_add_u32_e32 v116, 16, v152
	v_add_u32_e32 v104, v122, v116
	v_ashrrev_i32_e32 v105, 31, v104
	v_lshlrev_b64 v[104:105], 12, v[104:105]
	v_lshl_add_u64 v[104:105], s[4:5], 0, v[104:105]
	v_lshl_add_u64 v[104:105], v[104:105], 0, v[136:137]
	global_store_dwordx4 v[104:105], v[110:113], off
	v_cvt_pk_bf16_f32 v100, v100, v101
	v_cvt_pk_bf16_f32 v101, v102, v103
	v_cvt_pk_bf16_f32 v102, v92, v93
	v_add_u32_e32 v92, v121, v116
	v_ashrrev_i32_e32 v93, 31, v92
	v_lshlrev_b64 v[92:93], 12, v[92:93]
	v_lshl_add_u64 v[92:93], s[4:5], 0, v[92:93]
	v_lshl_add_u64 v[92:93], v[92:93], 0, v[108:109]
	v_cvt_pk_bf16_f32 v103, v94, v95
	global_store_dwordx4 v[92:93], v[100:103], off
	v_cvt_pk_bf16_f32 v92, v96, v97
	v_cvt_pk_bf16_f32 v93, v98, v99
	v_cvt_pk_bf16_f32 v94, v88, v89
	v_cvt_pk_bf16_f32 v95, v90, v91
	s_mov_b32 s45, s6
	s_nop 0
	v_add_u32_e32 v100, 32, v152
	v_add_u32_e32 v88, v122, v100
	v_ashrrev_i32_e32 v89, 31, v88
	v_lshlrev_b64 v[88:89], 12, v[88:89]
	v_lshl_add_u64 v[88:89], s[4:5], 0, v[88:89]
	v_lshl_add_u64 v[88:89], v[88:89], 0, v[136:137]
	global_store_dwordx4 v[88:89], v[92:95], off
	v_cvt_pk_bf16_f32 v84, v84, v85
	v_cvt_pk_bf16_f32 v85, v86, v87
	v_cvt_pk_bf16_f32 v86, v76, v77
	v_add_u32_e32 v76, v121, v100
	v_ashrrev_i32_e32 v77, 31, v76
	v_lshlrev_b64 v[76:77], 12, v[76:77]
	v_lshl_add_u64 v[76:77], s[4:5], 0, v[76:77]
	v_lshl_add_u64 v[76:77], v[76:77], 0, v[108:109]
	v_cvt_pk_bf16_f32 v87, v78, v79
	global_store_dwordx4 v[76:77], v[84:87], off
	v_cvt_pk_bf16_f32 v76, v80, v81
	v_cvt_pk_bf16_f32 v77, v82, v83
	v_cvt_pk_bf16_f32 v78, v72, v73
	v_cvt_pk_bf16_f32 v79, v74, v75
	s_mov_b32 s16, s8
	s_nop 0
	v_add_u32_e32 v84, 48, v152
	v_add_u32_e32 v72, v122, v84
	v_ashrrev_i32_e32 v73, 31, v72
	v_lshlrev_b64 v[72:73], 12, v[72:73]
	v_lshl_add_u64 v[72:73], s[4:5], 0, v[72:73]
	v_lshl_add_u64 v[72:73], v[72:73], 0, v[136:137]
	global_store_dwordx4 v[72:73], v[76:79], off
	v_cvt_pk_bf16_f32 v68, v68, v69
	v_cvt_pk_bf16_f32 v69, v70, v71
	v_cvt_pk_bf16_f32 v70, v64, v65
	v_add_u32_e32 v64, v121, v84
	v_ashrrev_i32_e32 v65, 31, v64
	v_lshlrev_b64 v[64:65], 12, v[64:65]
	v_lshl_add_u64 v[64:65], s[4:5], 0, v[64:65]
	v_lshl_add_u64 v[64:65], v[64:65], 0, v[108:109]
	v_cvt_pk_bf16_f32 v71, v66, v67
	global_store_dwordx4 v[64:65], v[68:71], off
	v_add_u32_e32 v64, 0x80, v152
	v_cvt_pk_bf16_f32 v60, v60, v61
	v_cvt_pk_bf16_f32 v61, v62, v63
	v_cvt_pk_bf16_f32 v62, v56, v57
	v_add_u32_e32 v56, v122, v64
	v_ashrrev_i32_e32 v57, 31, v56
	v_lshlrev_b64 v[56:57], 12, v[56:57]
	v_lshl_add_u64 v[56:57], s[4:5], 0, v[56:57]
	v_lshl_add_u64 v[56:57], v[56:57], 0, v[136:137]
	v_cvt_pk_bf16_f32 v63, v58, v59
	global_store_dwordx4 v[56:57], v[60:63], off
	v_cvt_pk_bf16_f32 v52, v52, v53
	v_cvt_pk_bf16_f32 v53, v54, v55
	v_cvt_pk_bf16_f32 v54, v44, v45
	v_add_u32_e32 v44, v121, v64
	v_ashrrev_i32_e32 v45, 31, v44
	v_lshlrev_b64 v[44:45], 12, v[44:45]
	v_lshl_add_u64 v[44:45], s[4:5], 0, v[44:45]
	v_lshl_add_u64 v[44:45], v[44:45], 0, v[108:109]
	v_cvt_pk_bf16_f32 v55, v46, v47
	global_store_dwordx4 v[44:45], v[52:55], off
	v_cvt_pk_bf16_f32 v44, v48, v49
	v_cvt_pk_bf16_f32 v45, v50, v51
	v_cvt_pk_bf16_f32 v46, v40, v41
	v_cvt_pk_bf16_f32 v47, v42, v43
	s_mov_b64 s[20:21], s[14:15]
	s_nop 0
	v_add_u32_e32 v52, 0x90, v152
	v_add_u32_e32 v40, v122, v52
	v_ashrrev_i32_e32 v41, 31, v40
	v_lshlrev_b64 v[40:41], 12, v[40:41]
	v_lshl_add_u64 v[40:41], s[4:5], 0, v[40:41]
	v_lshl_add_u64 v[40:41], v[40:41], 0, v[136:137]
	global_store_dwordx4 v[40:41], v[44:47], off
	v_cvt_pk_bf16_f32 v36, v36, v37
	v_cvt_pk_bf16_f32 v37, v38, v39
	v_cvt_pk_bf16_f32 v38, v28, v29
	v_add_u32_e32 v28, v121, v52
	v_ashrrev_i32_e32 v29, 31, v28
	v_lshlrev_b64 v[28:29], 12, v[28:29]
	v_lshl_add_u64 v[28:29], s[4:5], 0, v[28:29]
	v_lshl_add_u64 v[28:29], v[28:29], 0, v[108:109]
	v_cvt_pk_bf16_f32 v39, v30, v31
	global_store_dwordx4 v[28:29], v[36:39], off
	v_cvt_pk_bf16_f32 v28, v32, v33
	v_cvt_pk_bf16_f32 v29, v34, v35
	v_cvt_pk_bf16_f32 v30, v24, v25
	v_cvt_pk_bf16_f32 v31, v26, v27
	s_mov_b64 s[18:19], s[12:13]
	s_nop 0
	v_add_u32_e32 v36, 0xa0, v152
	v_add_u32_e32 v24, v122, v36
	v_ashrrev_i32_e32 v25, 31, v24
	v_lshlrev_b64 v[24:25], 12, v[24:25]
	v_lshl_add_u64 v[24:25], s[4:5], 0, v[24:25]
	v_lshl_add_u64 v[24:25], v[24:25], 0, v[136:137]
	global_store_dwordx4 v[24:25], v[28:31], off
	v_cvt_pk_bf16_f32 v20, v20, v21
	v_cvt_pk_bf16_f32 v21, v22, v23
	v_cvt_pk_bf16_f32 v22, v12, v13
	v_add_u32_e32 v12, v121, v36
	v_ashrrev_i32_e32 v13, 31, v12
	v_lshlrev_b64 v[12:13], 12, v[12:13]
	v_lshl_add_u64 v[12:13], s[4:5], 0, v[12:13]
	v_lshl_add_u64 v[12:13], v[12:13], 0, v[108:109]
	v_cvt_pk_bf16_f32 v23, v14, v15
	global_store_dwordx4 v[12:13], v[20:23], off
	v_cvt_pk_bf16_f32 v12, v16, v17
	v_cvt_pk_bf16_f32 v13, v18, v19
	v_cvt_pk_bf16_f32 v14, v8, v9
	v_cvt_pk_bf16_f32 v15, v10, v11
	s_nop 1
	v_add_u32_e32 v20, 0xb0, v152
	v_add_u32_e32 v8, v122, v20
	v_ashrrev_i32_e32 v9, 31, v8
	v_lshlrev_b64 v[8:9], 12, v[8:9]
	v_lshl_add_u64 v[8:9], s[4:5], 0, v[8:9]
	v_lshl_add_u64 v[8:9], v[8:9], 0, v[136:137]
	global_store_dwordx4 v[8:9], v[12:15], off
	v_cvt_pk_bf16_f32 v4, v4, v5
	v_cvt_pk_bf16_f32 v5, v6, v7
	v_cvt_pk_bf16_f32 v6, v0, v1
	v_add_u32_e32 v0, v121, v20
	v_ashrrev_i32_e32 v1, 31, v0
	v_lshlrev_b64 v[0:1], 12, v[0:1]
	v_lshl_add_u64 v[0:1], s[4:5], 0, v[0:1]
	v_lshl_add_u64 v[0:1], v[0:1], 0, v[108:109]
	v_cvt_pk_bf16_f32 v7, v2, v3
	global_store_dwordx4 v[0:1], v[4:7], off
	s_cbranch_vccz .LBB0_666
; #define PG8_WAIT_V(n) asm volatile("s_waitcnt vmcnt(" #n ")" ::: "memory")
; #define PG8_BAR __builtin_amdgcn_s_barrier()
; template <class Epi, class Sched>
; __device__ __forceinline__ void gemm_phase(LAS unsigned char* lds, const Gemm g, const Sched& S, const Epi& E) {
;     ...
;     PG8_WAIT_V(0);
;     if (wr == 0) PG8_BAR;
;     PG8_BAR;
	s_waitcnt vmcnt(0)
	s_cmpk_gt_u32 s24, 0xff
	s_cbranch_scc1 .LBB0_677
	s_barrier

; #define PG8_STAGE(bufoff, gbase, voff) do { _Pragma("unroll") for (int _i = 0; _i < 2; ++_i) \
;         __builtin_amdgcn_global_load_lds((const unsigned*)((const char*)(gbase) + (voff)[_i]), (LAS unsigned*)(lds + (bufoff) + ldsw + _i * 8192), 16, 0, 0); } while (0)
; #define PG8_LDA(dst, b, h) do { _Pragma("unroll") for (int m = 0; m < 4; ++m) _Pragma("unroll") for (int k = 0; k < 2; ++k) dst[m][k] = *(const LAS bf16x8*)(lds + PG8_SA(b, h) + aoff + m * 2048 + k * 1024); } while (0)
; #define PG8_LDB(dst, b, h) do { _Pragma("unroll") for (int n = 0; n < 2; ++n) _Pragma("unroll") for (int k = 0; k < 2; ++k) dst[n][k] = *(const LAS bf16x8*)(lds + PG8_SB(b, h) + boff + n * 2048 + k * 1024); } while (0)
; #define PG8_MMA(ai, bj, At, Bt) do { __builtin_amdgcn_s_setprio(1); _Pragma("unroll") for (int m = 0; m < 4; ++m) _Pragma("unroll") for (int n = 0; n < 2; ++n) _Pragma("unroll") for (int k = 0; k < 2; ++k) \
;         acc[ai][bj][m][n] = __builtin_amdgcn_mfma_f32_16x16x32_bf16(Bt[n][k], At[m][k], acc[ai][bj][m][n], 0, 0, 0); __builtin_amdgcn_s_setprio(0); } while (0)
; #define PG8_WAIT_L(n) asm volatile("s_waitcnt lgkmcnt(" #n ")" ::: "memory")
; template <class Epi, class Sched>
; __device__ __forceinline__ void gemm_phase(LAS unsigned char* lds, const Gemm g, const Sched& S, const Epi& E) {
;     ...
;         const bool has_next = S.next(ui + 1, nxt);
;         const char* nA = has_next ? (const char*)g.A + (size_t)nxt.pm * tstep : cA; const char* nB = has_next ? (const char*)g.Bt + (size_t)nxt.pn * tstep : cB;
;         for (int t = 0; t < nt; t += 2) {
;             const bool last = (t == nt - 2);
;             const char* a1 = cA + (size_t)(t + 1) * kstep;
;             const char* a2 = last ? nA : cA + (size_t)(t + 2) * kstep; const char* b2 = last ? nB : cB + (size_t)(t + 2) * kstep;
;             const char* a3 = a2 + kstep; const char* b3 = b2 + kstep;
;             PG8_LDB(B0, 0, 0); PG8_SCHED; PG8_LDA(At, 0, 0); PG8_STAGE(PG8_SA(1, 1), a1 + hstep, voffA);
;             PG8_WAIT_L(8); PG8_BAR; PG8_WAIT_L(0); PG8_MMA(0, 0, At, B0); PG8_BAR; PG8_SCHED;
;             PG8_LDB(B1, 0, 1); PG8_STAGE(PG8_SB(0, 0), b2, voffB);
;             PG8_BAR; PG8_WAIT_L(0); PG8_MMA(0, 1, At, B1); PG8_BAR;
;             PG8_LDA(At, 0, 1); PG8_STAGE(PG8_SA(0, 0), a2, voffA);
;             PG8_BAR; PG8_WAIT_L(0); PG8_MMA(1, 0, At, B0); PG8_BAR; PG8_SCHED;
.LBB0_692:
	s_ashr_i32 s19, s18, 31
	v_cmp_lt_i64_e64 s[24:25], s[20:21], 32
	s_lshl_b64 s[20:21], s[18:19], 19
	s_add_u32 s20, s40, s20
	s_addc_u32 s21, s41, s21
	s_and_b64 s[22:23], s[24:25], exec
	s_cselect_b32 s19, s21, s3
	s_cselect_b32 s57, s20, s2
	s_ashr_i32 s17, s16, 31
	s_lshl_b64 s[22:23], s[16:17], 19
	s_add_u32 s22, s28, s22
	s_addc_u32 s23, s29, s23
	s_and_b64 s[24:25], s[24:25], exec
	s_cselect_b32 s17, s23, s5
	s_cselect_b32 s58, s22, s4
	s_add_u32 s2, s2, 0x40080
	s_addc_u32 s3, s3, 0
	s_add_u32 s59, s4, 0x100
	s_addc_u32 s60, s5, 0
	s_mov_b32 s61, -2
	s_waitcnt lgkmcnt(0)
	ds_read_b128 v[140:143], v149
	ds_read_b128 v[154:157], v149 offset:1024
	ds_read_b128 v[158:161], v149 offset:2048
	ds_read_b128 v[162:165], v149 offset:3072
	s_add_u32 s4, s2, 0xfffc0080
	s_addc_u32 s5, s3, -1
	s_cmp_eq_u32 s61, 12
	s_cselect_b32 s25, s19, s5
	s_cselect_b32 s24, s57, s4
	s_cselect_b32 s5, s17, s60
	s_cselect_b32 s4, s58, s59
	s_add_i32 m0, s33, 0xc000
	ds_read_b128 v[166:169], v150
	ds_read_b128 v[170:173], v150 offset:1024
	ds_read_b128 v[174:177], v150 offset:2048
	ds_read_b128 v[178:181], v150 offset:3072
	ds_read_b128 v[182:185], v150 offset:4096
	ds_read_b128 v[186:189], v150 offset:5120
	ds_read_b128 v[190:193], v150 offset:6144
	ds_read_b128 v[194:197], v150 offset:7168
	global_load_lds_dwordx4 v136, s[2:3]
	s_add_i32 m0, s33, 0xe000
	s_nop 0
	global_load_lds_dwordx4 v138, s[2:3]
	s_waitcnt lgkmcnt(8)
	s_barrier
	s_waitcnt lgkmcnt(0)
	s_setprio 1
	s_waitcnt lgkmcnt(0)
	v_mfma_f32_16x16x32_bf16 v[124:127], v[140:143], v[166:169], 0
	v_mfma_f32_16x16x32_bf16 v[120:123], v[158:161], v[166:169], 0
	v_mfma_f32_16x16x32_bf16 v[108:111], v[140:143], v[174:177], 0
	v_mfma_f32_16x16x32_bf16 v[104:107], v[158:161], v[174:177], 0
	v_mfma_f32_16x16x32_bf16 v[92:95], v[140:143], v[182:185], 0
	v_mfma_f32_16x16x32_bf16 v[88:91], v[158:161], v[182:185], 0
	v_mfma_f32_16x16x32_bf16 v[76:79], v[140:143], v[190:193], 0
	v_mfma_f32_16x16x32_bf16 v[72:75], v[158:161], v[190:193], 0
	v_mfma_f32_16x16x32_bf16 v[124:127], v[154:157], v[170:173], v[124:127]
	v_mfma_f32_16x16x32_bf16 v[120:123], v[162:165], v[170:173], v[120:123]
	v_mfma_f32_16x16x32_bf16 v[108:111], v[154:157], v[178:181], v[108:111]
	v_mfma_f32_16x16x32_bf16 v[104:107], v[162:165], v[178:181], v[104:107]
	v_mfma_f32_16x16x32_bf16 v[92:95], v[154:157], v[186:189], v[92:95]
	v_mfma_f32_16x16x32_bf16 v[88:91], v[162:165], v[186:189], v[88:91]
	v_mfma_f32_16x16x32_bf16 v[76:79], v[154:157], v[194:197], v[76:79]
	v_mfma_f32_16x16x32_bf16 v[72:75], v[162:165], v[194:197], v[72:75]
	s_setprio 0
	s_barrier
	s_add_i32 s62, s47, s31
	s_mov_b32 m0, s62
	ds_read_b128 v[202:205], v151
	ds_read_b128 v[206:209], v151 offset:1024
	ds_read_b128 v[210:213], v151 offset:2048
	ds_read_b128 v[214:217], v151 offset:3072
	global_load_lds_dwordx4 v130, s[4:5]
	s_add_i32 m0, s62, 0x2000
	s_nop 0
	global_load_lds_dwordx4 v134, s[4:5]
	s_barrier
	s_waitcnt lgkmcnt(0)
	s_setprio 1
	s_waitcnt lgkmcnt(0)
	v_mfma_f32_16x16x32_bf16 v[116:119], v[202:205], v[166:169], 0
	v_mfma_f32_16x16x32_bf16 v[112:115], v[210:213], v[166:169], 0
	v_mfma_f32_16x16x32_bf16 v[100:103], v[202:205], v[174:177], 0
	v_mfma_f32_16x16x32_bf16 v[96:99], v[210:213], v[174:177], 0
	v_mfma_f32_16x16x32_bf16 v[84:87], v[202:205], v[182:185], 0
	v_mfma_f32_16x16x32_bf16 v[80:83], v[210:213], v[182:185], 0
	v_mfma_f32_16x16x32_bf16 v[68:71], v[202:205], v[190:193], 0
	v_mfma_f32_16x16x32_bf16 v[64:67], v[210:213], v[190:193], 0
	v_mfma_f32_16x16x32_bf16 v[116:119], v[206:209], v[170:173], v[116:119]
	v_mfma_f32_16x16x32_bf16 v[112:115], v[214:217], v[170:173], v[112:115]
	v_mfma_f32_16x16x32_bf16 v[100:103], v[206:209], v[178:181], v[100:103]
	v_mfma_f32_16x16x32_bf16 v[96:99], v[214:217], v[178:181], v[96:99]
	v_mfma_f32_16x16x32_bf16 v[84:87], v[206:209], v[186:189], v[84:87]
	v_mfma_f32_16x16x32_bf16 v[80:83], v[214:217], v[186:189], v[80:83]
	v_mfma_f32_16x16x32_bf16 v[68:71], v[206:209], v[194:197], v[68:71]
	v_mfma_f32_16x16x32_bf16 v[64:67], v[214:217], v[194:197], v[64:67]
	s_setprio 0
	s_mov_b32 m0, s33
	v_lshl_add_u64 v[218:219], s[24:25], 0, v[128:129]
	s_barrier
	ds_read_b128 v[166:169], v150 offset:16384
	ds_read_b128 v[170:173], v150 offset:17408
	ds_read_b128 v[174:177], v150 offset:18432
	ds_read_b128 v[178:181], v150 offset:19456
	ds_read_b128 v[182:185], v150 offset:20480
	ds_read_b128 v[186:189], v150 offset:21504
	ds_read_b128 v[190:193], v150 offset:22528
	ds_read_b128 v[194:197], v150 offset:23552
	global_load_lds_dwordx4 v128, s[24:25]
	v_lshl_add_u64 v[220:221], s[24:25], 0, v[132:133]
	s_mov_b32 m0, s34
	s_nop 0
	global_load_lds_dwordx4 v132, s[24:25]
	s_barrier
	s_waitcnt lgkmcnt(0)
	s_setprio 1
	s_waitcnt lgkmcnt(0)
	v_mfma_f32_16x16x32_bf16 v[60:63], v[140:143], v[166:169], 0
	v_mfma_f32_16x16x32_bf16 v[56:59], v[158:161], v[166:169], 0
	v_mfma_f32_16x16x32_bf16 v[44:47], v[140:143], v[174:177], 0
	v_mfma_f32_16x16x32_bf16 v[40:43], v[158:161], v[174:177], 0
	v_mfma_f32_16x16x32_bf16 v[28:31], v[140:143], v[182:185], 0
	v_mfma_f32_16x16x32_bf16 v[24:27], v[158:161], v[182:185], 0
	v_mfma_f32_16x16x32_bf16 v[12:15], v[140:143], v[190:193], 0
	v_mfma_f32_16x16x32_bf16 v[8:11], v[158:161], v[190:193], 0
	v_mfma_f32_16x16x32_bf16 v[60:63], v[154:157], v[170:173], v[60:63]
	v_mfma_f32_16x16x32_bf16 v[56:59], v[162:165], v[170:173], v[56:59]
	v_mfma_f32_16x16x32_bf16 v[44:47], v[154:157], v[178:181], v[44:47]
	v_mfma_f32_16x16x32_bf16 v[40:43], v[162:165], v[178:181], v[40:43]
	v_mfma_f32_16x16x32_bf16 v[28:31], v[154:157], v[186:189], v[28:31]
	v_mfma_f32_16x16x32_bf16 v[24:27], v[162:165], v[186:189], v[24:27]
	v_mfma_f32_16x16x32_bf16 v[12:15], v[154:157], v[194:197], v[12:15]
	v_mfma_f32_16x16x32_bf16 v[8:11], v[162:165], v[194:197], v[8:11]
	s_setprio 0
	s_barrier
; #define PG8_STAGE(bufoff, gbase, voff) do { _Pragma("unroll") for (int _i = 0; _i < 2; ++_i) \
;         __builtin_amdgcn_global_load_lds((const unsigned*)((const char*)(gbase) + (voff)[_i]), (LAS unsigned*)(lds + (bufoff) + ldsw + _i * 8192), 16, 0, 0); } while (0)
; #define PG8_LDA(dst, b, h) do { _Pragma("unroll") for (int m = 0; m < 4; ++m) _Pragma("unroll") for (int k = 0; k < 2; ++k) dst[m][k] = *(const LAS bf16x8*)(lds + PG8_SA(b, h) + aoff + m * 2048 + k * 1024); } while (0)
; #define PG8_LDB(dst, b, h) do { _Pragma("unroll") for (int n = 0; n < 2; ++n) _Pragma("unroll") for (int k = 0; k < 2; ++k) dst[n][k] = *(const LAS bf16x8*)(lds + PG8_SB(b, h) + boff + n * 2048 + k * 1024); } while (0)
; #define PG8_MMA(ai, bj, At, Bt) do { __builtin_amdgcn_s_setprio(1); _Pragma("unroll") for (int m = 0; m < 4; ++m) _Pragma("unroll") for (int n = 0; n < 2; ++n) _Pragma("unroll") for (int k = 0; k < 2; ++k) \
;         acc[ai][bj][m][n] = __builtin_amdgcn_mfma_f32_16x16x32_bf16(Bt[n][k], At[m][k], acc[ai][bj][m][n], 0, 0, 0); __builtin_amdgcn_s_setprio(0); } while (0)
; #define PG8_WAIT_V(n) asm volatile("s_waitcnt vmcnt(" #n ")" ::: "memory")
; #define PG8_WAIT_L(n) asm volatile("s_waitcnt lgkmcnt(" #n ")" ::: "memory")
; #define PG8_BAR __builtin_amdgcn_s_barrier()
; #define PG8_SCHED __builtin_amdgcn_sched_barrier(0)
; template <class Epi, class Sched>
; __device__ __forceinline__ void gemm_phase(LAS unsigned char* lds, const Gemm g, const Sched& S, const Epi& E) {
;     ...
;             PG8_STAGE(PG8_SB(0, 1), b2 + hstep, voffB);
;             PG8_WAIT_V(6); PG8_BAR; PG8_MMA(1, 1, At, B1); PG8_BAR;
;             PG8_LDB(B0, 1, 0); PG8_SCHED; PG8_LDA(At, 1, 0); PG8_STAGE(PG8_SA(0, 1), a2 + hstep, voffA);
;             PG8_WAIT_L(8); PG8_BAR; PG8_WAIT_L(0); PG8_MMA(0, 0, At, B0); PG8_BAR; PG8_SCHED;
;             PG8_LDB(B1, 1, 1); PG8_STAGE(PG8_SB(1, 0), b3, voffB);
;             PG8_BAR; PG8_WAIT_L(0); PG8_MMA(0, 1, At, B1); PG8_BAR;
;             PG8_LDA(At, 1, 1); PG8_STAGE(PG8_SA(1, 0), a3, voffA);
	s_add_u32 s62, s4, 0x40000
	s_addc_u32 s63, s5, 0
	s_add_i32 s64, s48, s31
	s_mov_b32 m0, s64
	s_nop 0
	global_load_lds_dwordx4 v130, s[62:63]
	s_add_i32 m0, s64, 0x2000
	s_nop 0
	global_load_lds_dwordx4 v134, s[62:63]
	s_waitcnt vmcnt(6)
	s_barrier
	s_setprio 1
	v_mfma_f32_16x16x32_bf16 v[52:55], v[202:205], v[166:169], 0
	v_mfma_f32_16x16x32_bf16 v[48:51], v[210:213], v[166:169], 0
	v_mfma_f32_16x16x32_bf16 v[36:39], v[202:205], v[174:177], 0
	v_mfma_f32_16x16x32_bf16 v[32:35], v[210:213], v[174:177], 0
	v_mfma_f32_16x16x32_bf16 v[20:23], v[202:205], v[182:185], 0
	v_mfma_f32_16x16x32_bf16 v[16:19], v[210:213], v[182:185], 0
	v_mfma_f32_16x16x32_bf16 v[4:7], v[202:205], v[190:193], 0
	v_mfma_f32_16x16x32_bf16 v[0:3], v[210:213], v[190:193], 0
	v_mfma_f32_16x16x32_bf16 v[52:55], v[206:209], v[170:173], v[52:55]
	v_mfma_f32_16x16x32_bf16 v[48:51], v[214:217], v[170:173], v[48:51]
	v_mfma_f32_16x16x32_bf16 v[36:39], v[206:209], v[178:181], v[36:39]
	v_mfma_f32_16x16x32_bf16 v[32:35], v[214:217], v[178:181], v[32:35]
	v_mfma_f32_16x16x32_bf16 v[20:23], v[206:209], v[186:189], v[20:23]
	v_mfma_f32_16x16x32_bf16 v[16:19], v[214:217], v[186:189], v[16:19]
	v_mfma_f32_16x16x32_bf16 v[4:7], v[206:209], v[194:197], v[4:7]
	v_mfma_f32_16x16x32_bf16 v[0:3], v[214:217], v[194:197], v[0:3]
	s_setprio 0
	s_add_i32 s62, 0, 0x18000
	v_add_u32_e32 v162, s62, v148
	s_barrier
	ds_read_b128 v[140:143], v162
	ds_read_b128 v[154:157], v162 offset:1024
	ds_read_b128 v[158:161], v162 offset:2048
	ds_read_b128 v[162:165], v162 offset:3072
	s_add_u32 s24, s24, 0x40000
	s_addc_u32 s25, s25, 0
	s_mov_b32 m0, s35
	ds_read_b128 v[166:169], v150 offset:32768
	ds_read_b128 v[170:173], v150 offset:33792
	ds_read_b128 v[174:177], v150 offset:34816
	ds_read_b128 v[178:181], v150 offset:35840
	ds_read_b128 v[182:185], v150 offset:36864
	ds_read_b128 v[186:189], v150 offset:37888
	ds_read_b128 v[190:193], v150 offset:38912
	ds_read_b128 v[194:197], v150 offset:39936
	global_load_lds_dwordx4 v128, s[24:25]
	s_mov_b32 m0, s36
	s_nop 0
	global_load_lds_dwordx4 v132, s[24:25]
	s_waitcnt lgkmcnt(8)
	s_barrier
	s_waitcnt lgkmcnt(0)
	s_setprio 1
	s_waitcnt lgkmcnt(0)
	v_mfma_f32_16x16x32_bf16 v[124:127], v[140:143], v[166:169], v[124:127]
	v_mfma_f32_16x16x32_bf16 v[120:123], v[158:161], v[166:169], v[120:123]
	v_mfma_f32_16x16x32_bf16 v[108:111], v[140:143], v[174:177], v[108:111]
	v_mfma_f32_16x16x32_bf16 v[104:107], v[158:161], v[174:177], v[104:107]
	v_mfma_f32_16x16x32_bf16 v[92:95], v[140:143], v[182:185], v[92:95]
	v_mfma_f32_16x16x32_bf16 v[88:91], v[158:161], v[182:185], v[88:91]
	v_mfma_f32_16x16x32_bf16 v[76:79], v[140:143], v[190:193], v[76:79]
	v_mfma_f32_16x16x32_bf16 v[72:75], v[158:161], v[190:193], v[72:75]
	v_mfma_f32_16x16x32_bf16 v[124:127], v[154:157], v[170:173], v[124:127]
	v_mfma_f32_16x16x32_bf16 v[120:123], v[162:165], v[170:173], v[120:123]
	v_mfma_f32_16x16x32_bf16 v[108:111], v[154:157], v[178:181], v[108:111]
	v_mfma_f32_16x16x32_bf16 v[104:107], v[162:165], v[178:181], v[104:107]
	v_mfma_f32_16x16x32_bf16 v[92:95], v[154:157], v[186:189], v[92:95]
	v_mfma_f32_16x16x32_bf16 v[88:91], v[162:165], v[186:189], v[88:91]
	v_mfma_f32_16x16x32_bf16 v[76:79], v[154:157], v[194:197], v[76:79]
	v_mfma_f32_16x16x32_bf16 v[72:75], v[162:165], v[194:197], v[72:75]
	s_setprio 0
	s_barrier
	s_add_i32 s24, 0, 0x1c000
	s_add_i32 s25, s62, s31
	v_add_u32_e32 v214, s24, v148
	s_add_u32 s0, s4, 0x80
	s_addc_u32 s1, s5, 0
	s_mov_b32 m0, s25
	ds_read_b128 v[202:205], v214
	ds_read_b128 v[206:209], v214 offset:1024
	ds_read_b128 v[210:213], v214 offset:2048
	ds_read_b128 v[214:217], v214 offset:3072
	global_load_lds_dwordx4 v130, s[0:1]
	s_add_i32 m0, s25, 0x2000
	s_nop 0
	global_load_lds_dwordx4 v134, s[0:1]
	s_barrier
	s_waitcnt lgkmcnt(0)
	s_setprio 1
	s_waitcnt lgkmcnt(0)
	v_mfma_f32_16x16x32_bf16 v[116:119], v[202:205], v[166:169], v[116:119]
	v_mfma_f32_16x16x32_bf16 v[112:115], v[210:213], v[166:169], v[112:115]
	v_mfma_f32_16x16x32_bf16 v[100:103], v[202:205], v[174:177], v[100:103]
	v_mfma_f32_16x16x32_bf16 v[96:99], v[210:213], v[174:177], v[96:99]
	v_mfma_f32_16x16x32_bf16 v[84:87], v[202:205], v[182:185], v[84:87]
	v_mfma_f32_16x16x32_bf16 v[80:83], v[210:213], v[182:185], v[80:83]
	v_mfma_f32_16x16x32_bf16 v[68:71], v[202:205], v[190:193], v[68:71]
	v_mfma_f32_16x16x32_bf16 v[64:67], v[210:213], v[190:193], v[64:67]
	v_mfma_f32_16x16x32_bf16 v[116:119], v[206:209], v[170:173], v[116:119]
	v_mfma_f32_16x16x32_bf16 v[112:115], v[214:217], v[170:173], v[112:115]
	v_mfma_f32_16x16x32_bf16 v[100:103], v[206:209], v[178:181], v[100:103]
	v_mfma_f32_16x16x32_bf16 v[96:99], v[214:217], v[178:181], v[96:99]
	v_mfma_f32_16x16x32_bf16 v[84:87], v[206:209], v[186:189], v[84:87]
	v_mfma_f32_16x16x32_bf16 v[80:83], v[214:217], v[186:189], v[80:83]
	v_mfma_f32_16x16x32_bf16 v[68:71], v[206:209], v[194:197], v[68:71]
	v_mfma_f32_16x16x32_bf16 v[64:67], v[214:217], v[194:197], v[64:67]
	s_setprio 0
	s_mov_b32 m0, s44
	s_mov_b64 s[0:1], 0x80
	v_lshl_add_u64 v[144:145], v[218:219], 0, s[0:1]
	s_barrier
	ds_read_b128 v[166:169], v150 offset:49152
	ds_read_b128 v[170:173], v150 offset:50176
	ds_read_b128 v[174:177], v150 offset:51200
	ds_read_b128 v[178:181], v150 offset:52224
	ds_read_b128 v[182:185], v150 offset:53248
	ds_read_b128 v[186:189], v150 offset:54272
	ds_read_b128 v[190:193], v150 offset:55296
	ds_read_b128 v[194:197], v150 offset:56320
	global_load_lds_dwordx4 v[144:145], off
	v_lshl_add_u64 v[144:145], v[220:221], 0, s[0:1]
	s_mov_b32 m0, s45
	s_nop 0
	global_load_lds_dwordx4 v[144:145], off
	s_barrier
; #define PG8_STAGE(bufoff, gbase, voff) do { _Pragma("unroll") for (int _i = 0; _i < 2; ++_i) \
;         __builtin_amdgcn_global_load_lds((const unsigned*)((const char*)(gbase) + (voff)[_i]), (LAS unsigned*)(lds + (bufoff) + ldsw + _i * 8192), 16, 0, 0); } while (0)
; #define PG8_LDA(dst, b, h) do { _Pragma("unroll") for (int m = 0; m < 4; ++m) _Pragma("unroll") for (int k = 0; k < 2; ++k) dst[m][k] = *(const LAS bf16x8*)(lds + PG8_SA(b, h) + aoff + m * 2048 + k * 1024); } while (0)
; #define PG8_WAIT_V(n) asm volatile("s_waitcnt vmcnt(" #n ")" ::: "memory")
; #define PG8_WAIT_L(n) asm volatile("s_waitcnt lgkmcnt(" #n ")" ::: "memory")
; template <class Epi, class Sched>
; __device__ __forceinline__ void gemm_phase(LAS unsigned char* lds, const Gemm g, const Sched& S, const Epi& E) {
;     ...
;         for (int t = 0; t < nt; t += 2) {
;             const bool last = (t == nt - 2);
;             const char* a1 = cA + (size_t)(t + 1) * kstep;
;             const char* a2 = last ? nA : cA + (size_t)(t + 2) * kstep; const char* b2 = last ? nB : cB + (size_t)(t + 2) * kstep;
;             const char* a3 = a2 + kstep; const char* b3 = b2 + kstep;
;             PG8_LDB(B0, 0, 0); PG8_SCHED; PG8_LDA(At, 0, 0); PG8_STAGE(PG8_SA(1, 1), a1 + hstep, voffA);
;             PG8_WAIT_L(8); PG8_BAR; PG8_WAIT_L(0); PG8_MMA(0, 0, At, B0); PG8_BAR; PG8_SCHED;
;             PG8_LDB(B1, 0, 1); PG8_STAGE(PG8_SB(0, 0), b2, voffB);
;             PG8_BAR; PG8_WAIT_L(0); PG8_MMA(0, 1, At, B1); PG8_BAR;
;             PG8_LDA(At, 0, 1); PG8_STAGE(PG8_SA(0, 0), a2, voffA);
;             PG8_BAR; PG8_WAIT_L(0); PG8_MMA(1, 0, At, B0); PG8_BAR; PG8_SCHED;
;             PG8_STAGE(PG8_SB(0, 1), b2 + hstep, voffB);
;             PG8_WAIT_V(6); PG8_BAR; PG8_MMA(1, 1, At, B1); PG8_BAR;
;             PG8_LDB(B0, 1, 0); PG8_SCHED; PG8_LDA(At, 1, 0); PG8_STAGE(PG8_SA(0, 1), a2 + hstep, voffA);
;             PG8_WAIT_L(8); PG8_BAR; PG8_WAIT_L(0); PG8_MMA(0, 0, At, B0); PG8_BAR; PG8_SCHED;
;             PG8_LDB(B1, 1, 1); PG8_STAGE(PG8_SB(1, 0), b3, voffB);
;             PG8_BAR; PG8_WAIT_L(0); PG8_MMA(0, 1, At, B1); PG8_BAR;
;             PG8_LDA(At, 1, 1); PG8_STAGE(PG8_SA(1, 0), a3, voffA);
;             PG8_BAR; PG8_WAIT_L(0); PG8_MMA(1, 0, At, B0); PG8_BAR; PG8_SCHED;
;             PG8_STAGE(PG8_SB(1, 1), b3 + hstep, voffB);
;             PG8_WAIT_V(6); PG8_BAR; PG8_MMA(1, 1, At, B1); PG8_BAR;
	s_waitcnt lgkmcnt(0)
	s_setprio 1
	s_waitcnt lgkmcnt(0)
	v_mfma_f32_16x16x32_bf16 v[60:63], v[140:143], v[166:169], v[60:63]
	v_mfma_f32_16x16x32_bf16 v[56:59], v[158:161], v[166:169], v[56:59]
	v_mfma_f32_16x16x32_bf16 v[44:47], v[140:143], v[174:177], v[44:47]
	v_mfma_f32_16x16x32_bf16 v[40:43], v[158:161], v[174:177], v[40:43]
	v_mfma_f32_16x16x32_bf16 v[28:31], v[140:143], v[182:185], v[28:31]
	v_mfma_f32_16x16x32_bf16 v[24:27], v[158:161], v[182:185], v[24:27]
	v_mfma_f32_16x16x32_bf16 v[12:15], v[140:143], v[190:193], v[12:15]
	v_mfma_f32_16x16x32_bf16 v[8:11], v[158:161], v[190:193], v[8:11]
	v_mfma_f32_16x16x32_bf16 v[60:63], v[154:157], v[170:173], v[60:63]
	v_mfma_f32_16x16x32_bf16 v[56:59], v[162:165], v[170:173], v[56:59]
	v_mfma_f32_16x16x32_bf16 v[44:47], v[154:157], v[178:181], v[44:47]
	v_mfma_f32_16x16x32_bf16 v[40:43], v[162:165], v[178:181], v[40:43]
	v_mfma_f32_16x16x32_bf16 v[28:31], v[154:157], v[186:189], v[28:31]
	v_mfma_f32_16x16x32_bf16 v[24:27], v[162:165], v[186:189], v[24:27]
	v_mfma_f32_16x16x32_bf16 v[12:15], v[154:157], v[194:197], v[12:15]
	v_mfma_f32_16x16x32_bf16 v[8:11], v[162:165], v[194:197], v[8:11]
	s_setprio 0
	s_barrier
	s_add_u32 s4, s4, 0x40080
	s_addc_u32 s5, s5, 0
	s_add_i32 s24, s24, s31
	s_mov_b32 m0, s24
	s_nop 0
	global_load_lds_dwordx4 v130, s[4:5]
	s_add_i32 m0, s24, 0x2000
	s_nop 0
	global_load_lds_dwordx4 v134, s[4:5]
	s_waitcnt vmcnt(6)
	s_barrier
	s_setprio 1
	v_mfma_f32_16x16x32_bf16 v[52:55], v[202:205], v[166:169], v[52:55]
	v_mfma_f32_16x16x32_bf16 v[48:51], v[210:213], v[166:169], v[48:51]
	v_mfma_f32_16x16x32_bf16 v[36:39], v[202:205], v[174:177], v[36:39]
	v_mfma_f32_16x16x32_bf16 v[32:35], v[210:213], v[174:177], v[32:35]
	v_mfma_f32_16x16x32_bf16 v[20:23], v[202:205], v[182:185], v[20:23]
	v_mfma_f32_16x16x32_bf16 v[16:19], v[210:213], v[182:185], v[16:19]
	v_mfma_f32_16x16x32_bf16 v[4:7], v[202:205], v[190:193], v[4:7]
	v_mfma_f32_16x16x32_bf16 v[0:3], v[210:213], v[190:193], v[0:3]
	v_mfma_f32_16x16x32_bf16 v[52:55], v[206:209], v[170:173], v[52:55]
	v_mfma_f32_16x16x32_bf16 v[48:51], v[214:217], v[170:173], v[48:51]
	v_mfma_f32_16x16x32_bf16 v[36:39], v[206:209], v[178:181], v[36:39]
	v_mfma_f32_16x16x32_bf16 v[32:35], v[214:217], v[178:181], v[32:35]
	v_mfma_f32_16x16x32_bf16 v[20:23], v[206:209], v[186:189], v[20:23]
	v_mfma_f32_16x16x32_bf16 v[16:19], v[214:217], v[186:189], v[16:19]
	v_mfma_f32_16x16x32_bf16 v[4:7], v[206:209], v[194:197], v[4:7]
	v_mfma_f32_16x16x32_bf16 v[0:3], v[214:217], v[194:197], v[0:3]
	s_setprio 0
	s_add_i32 s61, s61, 2
	s_add_u32 s2, s2, 0x100
	s_addc_u32 s3, s3, 0
	s_add_u32 s59, s59, 0x100
	s_addc_u32 s60, s60, 0
	s_cmp_gt_u32 s61, 13
	s_barrier
.LBB0_693:
	ds_read_b128 v[140:143], v149
	ds_read_b128 v[154:157], v149 offset:1024
	ds_read_b128 v[158:161], v149 offset:2048
	ds_read_b128 v[162:165], v149 offset:3072
	s_add_u32 s4, s2, 0xfffc0080
	s_addc_u32 s5, s3, -1
	s_cmp_eq_u32 s61, 12
	s_cselect_b32 s25, s19, s5
	s_cselect_b32 s24, s57, s4
	s_cselect_b32 s5, s17, s60
	s_cselect_b32 s4, s58, s59
	s_add_i32 m0, s33, 0xc000
	ds_read_b128 v[166:169], v150
	ds_read_b128 v[170:173], v150 offset:1024
	ds_read_b128 v[174:177], v150 offset:2048
	ds_read_b128 v[178:181], v150 offset:3072
	ds_read_b128 v[182:185], v150 offset:4096
	ds_read_b128 v[186:189], v150 offset:5120
	ds_read_b128 v[190:193], v150 offset:6144
	ds_read_b128 v[194:197], v150 offset:7168
	global_load_lds_dwordx4 v136, s[2:3]
	s_add_i32 m0, s33, 0xe000
	s_nop 0
	global_load_lds_dwordx4 v138, s[2:3]
	s_waitcnt lgkmcnt(8)
	s_barrier
	s_waitcnt lgkmcnt(0)
	s_setprio 1
	s_waitcnt lgkmcnt(0)
	v_mfma_f32_16x16x32_bf16 v[124:127], v[140:143], v[166:169], v[124:127]
	v_mfma_f32_16x16x32_bf16 v[120:123], v[158:161], v[166:169], v[120:123]
	v_mfma_f32_16x16x32_bf16 v[108:111], v[140:143], v[174:177], v[108:111]
	v_mfma_f32_16x16x32_bf16 v[104:107], v[158:161], v[174:177], v[104:107]
	v_mfma_f32_16x16x32_bf16 v[92:95], v[140:143], v[182:185], v[92:95]
	v_mfma_f32_16x16x32_bf16 v[88:91], v[158:161], v[182:185], v[88:91]
	v_mfma_f32_16x16x32_bf16 v[76:79], v[140:143], v[190:193], v[76:79]
	v_mfma_f32_16x16x32_bf16 v[72:75], v[158:161], v[190:193], v[72:75]
	v_mfma_f32_16x16x32_bf16 v[124:127], v[154:157], v[170:173], v[124:127]
	v_mfma_f32_16x16x32_bf16 v[120:123], v[162:165], v[170:173], v[120:123]
	v_mfma_f32_16x16x32_bf16 v[108:111], v[154:157], v[178:181], v[108:111]
	v_mfma_f32_16x16x32_bf16 v[104:107], v[162:165], v[178:181], v[104:107]
	v_mfma_f32_16x16x32_bf16 v[92:95], v[154:157], v[186:189], v[92:95]
	v_mfma_f32_16x16x32_bf16 v[88:91], v[162:165], v[186:189], v[88:91]
	v_mfma_f32_16x16x32_bf16 v[76:79], v[154:157], v[194:197], v[76:79]
	v_mfma_f32_16x16x32_bf16 v[72:75], v[162:165], v[194:197], v[72:75]
	s_setprio 0
	s_barrier
	s_add_i32 s62, s47, s31
	s_mov_b32 m0, s62
	ds_read_b128 v[202:205], v151
	ds_read_b128 v[206:209], v151 offset:1024
	ds_read_b128 v[210:213], v151 offset:2048
	ds_read_b128 v[214:217], v151 offset:3072
	global_load_lds_dwordx4 v130, s[4:5]
	s_add_i32 m0, s62, 0x2000
	s_nop 0
	global_load_lds_dwordx4 v134, s[4:5]
	s_barrier
; #define PG8_STAGE(bufoff, gbase, voff) do { _Pragma("unroll") for (int _i = 0; _i < 2; ++_i) \
;         __builtin_amdgcn_global_load_lds((const unsigned*)((const char*)(gbase) + (voff)[_i]), (LAS unsigned*)(lds + (bufoff) + ldsw + _i * 8192), 16, 0, 0); } while (0)
; #define PG8_LDA(dst, b, h) do { _Pragma("unroll") for (int m = 0; m < 4; ++m) _Pragma("unroll") for (int k = 0; k < 2; ++k) dst[m][k] = *(const LAS bf16x8*)(lds + PG8_SA(b, h) + aoff + m * 2048 + k * 1024); } while (0)
; #define PG8_LDB(dst, b, h) do { _Pragma("unroll") for (int n = 0; n < 2; ++n) _Pragma("unroll") for (int k = 0; k < 2; ++k) dst[n][k] = *(const LAS bf16x8*)(lds + PG8_SB(b, h) + boff + n * 2048 + k * 1024); } while (0)
; #define PG8_MMA(ai, bj, At, Bt) do { __builtin_amdgcn_s_setprio(1); _Pragma("unroll") for (int m = 0; m < 4; ++m) _Pragma("unroll") for (int n = 0; n < 2; ++n) _Pragma("unroll") for (int k = 0; k < 2; ++k) \
;         acc[ai][bj][m][n] = __builtin_amdgcn_mfma_f32_16x16x32_bf16(Bt[n][k], At[m][k], acc[ai][bj][m][n], 0, 0, 0); __builtin_amdgcn_s_setprio(0); } while (0)
; #define PG8_WAIT_V(n) asm volatile("s_waitcnt vmcnt(" #n ")" ::: "memory")
; #define PG8_WAIT_L(n) asm volatile("s_waitcnt lgkmcnt(" #n ")" ::: "memory")
; #define PG8_BAR __builtin_amdgcn_s_barrier()
; #define PG8_SCHED __builtin_amdgcn_sched_barrier(0)
; template <class Epi, class Sched>
; __device__ __forceinline__ void gemm_phase(LAS unsigned char* lds, const Gemm g, const Sched& S, const Epi& E) {
;     ...
;             PG8_BAR; PG8_WAIT_L(0); PG8_MMA(0, 1, At, B1); PG8_BAR;
;             PG8_LDA(At, 0, 1); PG8_STAGE(PG8_SA(0, 0), a2, voffA);
;             PG8_BAR; PG8_WAIT_L(0); PG8_MMA(1, 0, At, B0); PG8_BAR; PG8_SCHED;
;             PG8_STAGE(PG8_SB(0, 1), b2 + hstep, voffB);
;             PG8_WAIT_V(6); PG8_BAR; PG8_MMA(1, 1, At, B1); PG8_BAR;
;             PG8_LDB(B0, 1, 0); PG8_SCHED; PG8_LDA(At, 1, 0); PG8_STAGE(PG8_SA(0, 1), a2 + hstep, voffA);
	s_waitcnt lgkmcnt(0)
	s_setprio 1
	s_waitcnt lgkmcnt(0)
	v_mfma_f32_16x16x32_bf16 v[116:119], v[202:205], v[166:169], v[116:119]
	v_mfma_f32_16x16x32_bf16 v[112:115], v[210:213], v[166:169], v[112:115]
	v_mfma_f32_16x16x32_bf16 v[100:103], v[202:205], v[174:177], v[100:103]
	v_mfma_f32_16x16x32_bf16 v[96:99], v[210:213], v[174:177], v[96:99]
	v_mfma_f32_16x16x32_bf16 v[84:87], v[202:205], v[182:185], v[84:87]
	v_mfma_f32_16x16x32_bf16 v[80:83], v[210:213], v[182:185], v[80:83]
	v_mfma_f32_16x16x32_bf16 v[68:71], v[202:205], v[190:193], v[68:71]
	v_mfma_f32_16x16x32_bf16 v[64:67], v[210:213], v[190:193], v[64:67]
	v_mfma_f32_16x16x32_bf16 v[116:119], v[206:209], v[170:173], v[116:119]
	v_mfma_f32_16x16x32_bf16 v[112:115], v[214:217], v[170:173], v[112:115]
	v_mfma_f32_16x16x32_bf16 v[100:103], v[206:209], v[178:181], v[100:103]
	v_mfma_f32_16x16x32_bf16 v[96:99], v[214:217], v[178:181], v[96:99]
	v_mfma_f32_16x16x32_bf16 v[84:87], v[206:209], v[186:189], v[84:87]
	v_mfma_f32_16x16x32_bf16 v[80:83], v[214:217], v[186:189], v[80:83]
	v_mfma_f32_16x16x32_bf16 v[68:71], v[206:209], v[194:197], v[68:71]
	v_mfma_f32_16x16x32_bf16 v[64:67], v[214:217], v[194:197], v[64:67]
	s_setprio 0
	s_mov_b32 m0, s33
	v_lshl_add_u64 v[218:219], s[24:25], 0, v[128:129]
	s_barrier
	ds_read_b128 v[166:169], v150 offset:16384
	ds_read_b128 v[170:173], v150 offset:17408
	ds_read_b128 v[174:177], v150 offset:18432
	ds_read_b128 v[178:181], v150 offset:19456
	ds_read_b128 v[182:185], v150 offset:20480
	ds_read_b128 v[186:189], v150 offset:21504
	ds_read_b128 v[190:193], v150 offset:22528
	ds_read_b128 v[194:197], v150 offset:23552
	global_load_lds_dwordx4 v128, s[24:25]
	v_lshl_add_u64 v[220:221], s[24:25], 0, v[132:133]
	s_mov_b32 m0, s34
	s_nop 0
	global_load_lds_dwordx4 v132, s[24:25]
	s_barrier
	s_waitcnt lgkmcnt(0)
	s_setprio 1
	s_waitcnt lgkmcnt(0)
	v_mfma_f32_16x16x32_bf16 v[60:63], v[140:143], v[166:169], v[60:63]
	v_mfma_f32_16x16x32_bf16 v[56:59], v[158:161], v[166:169], v[56:59]
	v_mfma_f32_16x16x32_bf16 v[44:47], v[140:143], v[174:177], v[44:47]
	v_mfma_f32_16x16x32_bf16 v[40:43], v[158:161], v[174:177], v[40:43]
	v_mfma_f32_16x16x32_bf16 v[28:31], v[140:143], v[182:185], v[28:31]
	v_mfma_f32_16x16x32_bf16 v[24:27], v[158:161], v[182:185], v[24:27]
	v_mfma_f32_16x16x32_bf16 v[12:15], v[140:143], v[190:193], v[12:15]
	v_mfma_f32_16x16x32_bf16 v[8:11], v[158:161], v[190:193], v[8:11]
	v_mfma_f32_16x16x32_bf16 v[60:63], v[154:157], v[170:173], v[60:63]
	v_mfma_f32_16x16x32_bf16 v[56:59], v[162:165], v[170:173], v[56:59]
	v_mfma_f32_16x16x32_bf16 v[44:47], v[154:157], v[178:181], v[44:47]
	v_mfma_f32_16x16x32_bf16 v[40:43], v[162:165], v[178:181], v[40:43]
	v_mfma_f32_16x16x32_bf16 v[28:31], v[154:157], v[186:189], v[28:31]
	v_mfma_f32_16x16x32_bf16 v[24:27], v[162:165], v[186:189], v[24:27]
	v_mfma_f32_16x16x32_bf16 v[12:15], v[154:157], v[194:197], v[12:15]
	v_mfma_f32_16x16x32_bf16 v[8:11], v[162:165], v[194:197], v[8:11]
	s_setprio 0
	s_barrier
	s_add_u32 s62, s4, 0x40000
	s_addc_u32 s63, s5, 0
	s_add_i32 s64, s48, s31
	s_mov_b32 m0, s64
	s_nop 0
	global_load_lds_dwordx4 v130, s[62:63]
	s_add_i32 m0, s64, 0x2000
	s_nop 0
	global_load_lds_dwordx4 v134, s[62:63]
	s_waitcnt vmcnt(6)
	s_barrier
	s_setprio 1
	v_mfma_f32_16x16x32_bf16 v[52:55], v[202:205], v[166:169], v[52:55]
	v_mfma_f32_16x16x32_bf16 v[48:51], v[210:213], v[166:169], v[48:51]
	v_mfma_f32_16x16x32_bf16 v[36:39], v[202:205], v[174:177], v[36:39]
	v_mfma_f32_16x16x32_bf16 v[32:35], v[210:213], v[174:177], v[32:35]
	v_mfma_f32_16x16x32_bf16 v[20:23], v[202:205], v[182:185], v[20:23]
	v_mfma_f32_16x16x32_bf16 v[16:19], v[210:213], v[182:185], v[16:19]
	v_mfma_f32_16x16x32_bf16 v[4:7], v[202:205], v[190:193], v[4:7]
	v_mfma_f32_16x16x32_bf16 v[0:3], v[210:213], v[190:193], v[0:3]
	v_mfma_f32_16x16x32_bf16 v[52:55], v[206:209], v[170:173], v[52:55]
	v_mfma_f32_16x16x32_bf16 v[48:51], v[214:217], v[170:173], v[48:51]
	v_mfma_f32_16x16x32_bf16 v[36:39], v[206:209], v[178:181], v[36:39]
	v_mfma_f32_16x16x32_bf16 v[32:35], v[214:217], v[178:181], v[32:35]
	v_mfma_f32_16x16x32_bf16 v[20:23], v[206:209], v[186:189], v[20:23]
	v_mfma_f32_16x16x32_bf16 v[16:19], v[214:217], v[186:189], v[16:19]
	v_mfma_f32_16x16x32_bf16 v[4:7], v[206:209], v[194:197], v[4:7]
	v_mfma_f32_16x16x32_bf16 v[0:3], v[214:217], v[194:197], v[0:3]
	s_setprio 0
	s_add_i32 s62, 0, 0x18000
	v_add_u32_e32 v162, s62, v148
	s_barrier
	ds_read_b128 v[140:143], v162
	ds_read_b128 v[154:157], v162 offset:1024
	ds_read_b128 v[158:161], v162 offset:2048
	ds_read_b128 v[162:165], v162 offset:3072
	s_add_u32 s24, s24, 0x40000
	s_addc_u32 s25, s25, 0
	s_mov_b32 m0, s35
	ds_read_b128 v[166:169], v150 offset:32768
	ds_read_b128 v[170:173], v150 offset:33792
	ds_read_b128 v[174:177], v150 offset:34816
	ds_read_b128 v[178:181], v150 offset:35840
	ds_read_b128 v[182:185], v150 offset:36864
	ds_read_b128 v[186:189], v150 offset:37888
	ds_read_b128 v[190:193], v150 offset:38912
	ds_read_b128 v[194:197], v150 offset:39936
	global_load_lds_dwordx4 v128, s[24:25]
	s_mov_b32 m0, s36
	s_nop 0
	global_load_lds_dwordx4 v132, s[24:25]
	s_waitcnt lgkmcnt(8)
	s_barrier
; #define PG8_STAGE(bufoff, gbase, voff) do { _Pragma("unroll") for (int _i = 0; _i < 2; ++_i) \
;         __builtin_amdgcn_global_load_lds((const unsigned*)((const char*)(gbase) + (voff)[_i]), (LAS unsigned*)(lds + (bufoff) + ldsw + _i * 8192), 16, 0, 0); } while (0)
; #define PG8_LDA(dst, b, h) do { _Pragma("unroll") for (int m = 0; m < 4; ++m) _Pragma("unroll") for (int k = 0; k < 2; ++k) dst[m][k] = *(const LAS bf16x8*)(lds + PG8_SA(b, h) + aoff + m * 2048 + k * 1024); } while (0)
; #define PG8_LDB(dst, b, h) do { _Pragma("unroll") for (int n = 0; n < 2; ++n) _Pragma("unroll") for (int k = 0; k < 2; ++k) dst[n][k] = *(const LAS bf16x8*)(lds + PG8_SB(b, h) + boff + n * 2048 + k * 1024); } while (0)
; #define PG8_MMA(ai, bj, At, Bt) do { __builtin_amdgcn_s_setprio(1); _Pragma("unroll") for (int m = 0; m < 4; ++m) _Pragma("unroll") for (int n = 0; n < 2; ++n) _Pragma("unroll") for (int k = 0; k < 2; ++k) \
;         acc[ai][bj][m][n] = __builtin_amdgcn_mfma_f32_16x16x32_bf16(Bt[n][k], At[m][k], acc[ai][bj][m][n], 0, 0, 0); __builtin_amdgcn_s_setprio(0); } while (0)
; #define PG8_WAIT_V(n) asm volatile("s_waitcnt vmcnt(" #n ")" ::: "memory")
; #define PG8_WAIT_L(n) asm volatile("s_waitcnt lgkmcnt(" #n ")" ::: "memory")
; #define PG8_BAR __builtin_amdgcn_s_barrier()
; #define PG8_SCHED __builtin_amdgcn_sched_barrier(0)
; template <class Epi, class Sched>
; __device__ __forceinline__ void gemm_phase(LAS unsigned char* lds, const Gemm g, const Sched& S, const Epi& E) {
;     ...
;             PG8_WAIT_L(8); PG8_BAR; PG8_WAIT_L(0); PG8_MMA(0, 0, At, B0); PG8_BAR; PG8_SCHED;
;             PG8_LDB(B1, 1, 1); PG8_STAGE(PG8_SB(1, 0), b3, voffB);
;             PG8_BAR; PG8_WAIT_L(0); PG8_MMA(0, 1, At, B1); PG8_BAR;
;             PG8_LDA(At, 1, 1); PG8_STAGE(PG8_SA(1, 0), a3, voffA);
;             PG8_BAR; PG8_WAIT_L(0); PG8_MMA(1, 0, At, B0); PG8_BAR; PG8_SCHED;
;             PG8_STAGE(PG8_SB(1, 1), b3 + hstep, voffB);
;             PG8_WAIT_V(6); PG8_BAR; PG8_MMA(1, 1, At, B1); PG8_BAR;
;         }
	s_waitcnt lgkmcnt(0)
	s_setprio 1
	s_waitcnt lgkmcnt(0)
	v_mfma_f32_16x16x32_bf16 v[124:127], v[140:143], v[166:169], v[124:127]
	v_mfma_f32_16x16x32_bf16 v[120:123], v[158:161], v[166:169], v[120:123]
	v_mfma_f32_16x16x32_bf16 v[108:111], v[140:143], v[174:177], v[108:111]
	v_mfma_f32_16x16x32_bf16 v[104:107], v[158:161], v[174:177], v[104:107]
	v_mfma_f32_16x16x32_bf16 v[92:95], v[140:143], v[182:185], v[92:95]
	v_mfma_f32_16x16x32_bf16 v[88:91], v[158:161], v[182:185], v[88:91]
	v_mfma_f32_16x16x32_bf16 v[76:79], v[140:143], v[190:193], v[76:79]
	v_mfma_f32_16x16x32_bf16 v[72:75], v[158:161], v[190:193], v[72:75]
	v_mfma_f32_16x16x32_bf16 v[124:127], v[154:157], v[170:173], v[124:127]
	v_mfma_f32_16x16x32_bf16 v[120:123], v[162:165], v[170:173], v[120:123]
	v_mfma_f32_16x16x32_bf16 v[108:111], v[154:157], v[178:181], v[108:111]
	v_mfma_f32_16x16x32_bf16 v[104:107], v[162:165], v[178:181], v[104:107]
	v_mfma_f32_16x16x32_bf16 v[92:95], v[154:157], v[186:189], v[92:95]
	v_mfma_f32_16x16x32_bf16 v[88:91], v[162:165], v[186:189], v[88:91]
	v_mfma_f32_16x16x32_bf16 v[76:79], v[154:157], v[194:197], v[76:79]
	v_mfma_f32_16x16x32_bf16 v[72:75], v[162:165], v[194:197], v[72:75]
	s_setprio 0
	s_barrier
	s_add_i32 s24, 0, 0x1c000
	s_add_i32 s25, s62, s31
	v_add_u32_e32 v214, s24, v148
	s_add_u32 s0, s4, 0x80
	s_addc_u32 s1, s5, 0
	s_mov_b32 m0, s25
	ds_read_b128 v[202:205], v214
	ds_read_b128 v[206:209], v214 offset:1024
	ds_read_b128 v[210:213], v214 offset:2048
	ds_read_b128 v[214:217], v214 offset:3072
	global_load_lds_dwordx4 v130, s[0:1]
	s_add_i32 m0, s25, 0x2000
	s_nop 0
	global_load_lds_dwordx4 v134, s[0:1]
	s_barrier
	s_waitcnt lgkmcnt(0)
	s_setprio 1
	s_waitcnt lgkmcnt(0)
	v_mfma_f32_16x16x32_bf16 v[116:119], v[202:205], v[166:169], v[116:119]
	v_mfma_f32_16x16x32_bf16 v[112:115], v[210:213], v[166:169], v[112:115]
	v_mfma_f32_16x16x32_bf16 v[100:103], v[202:205], v[174:177], v[100:103]
	v_mfma_f32_16x16x32_bf16 v[96:99], v[210:213], v[174:177], v[96:99]
	v_mfma_f32_16x16x32_bf16 v[84:87], v[202:205], v[182:185], v[84:87]
	v_mfma_f32_16x16x32_bf16 v[80:83], v[210:213], v[182:185], v[80:83]
	v_mfma_f32_16x16x32_bf16 v[68:71], v[202:205], v[190:193], v[68:71]
	v_mfma_f32_16x16x32_bf16 v[64:67], v[210:213], v[190:193], v[64:67]
	v_mfma_f32_16x16x32_bf16 v[116:119], v[206:209], v[170:173], v[116:119]
	v_mfma_f32_16x16x32_bf16 v[112:115], v[214:217], v[170:173], v[112:115]
	v_mfma_f32_16x16x32_bf16 v[100:103], v[206:209], v[178:181], v[100:103]
	v_mfma_f32_16x16x32_bf16 v[96:99], v[214:217], v[178:181], v[96:99]
	v_mfma_f32_16x16x32_bf16 v[84:87], v[206:209], v[186:189], v[84:87]
	v_mfma_f32_16x16x32_bf16 v[80:83], v[214:217], v[186:189], v[80:83]
	v_mfma_f32_16x16x32_bf16 v[68:71], v[206:209], v[194:197], v[68:71]
	v_mfma_f32_16x16x32_bf16 v[64:67], v[214:217], v[194:197], v[64:67]
	s_setprio 0
	s_mov_b32 m0, s44
	s_mov_b64 s[0:1], 0x80
	v_lshl_add_u64 v[144:145], v[218:219], 0, s[0:1]
	s_barrier
	ds_read_b128 v[166:169], v150 offset:49152
	ds_read_b128 v[170:173], v150 offset:50176
	ds_read_b128 v[174:177], v150 offset:51200
	ds_read_b128 v[178:181], v150 offset:52224
	ds_read_b128 v[182:185], v150 offset:53248
	ds_read_b128 v[186:189], v150 offset:54272
	ds_read_b128 v[190:193], v150 offset:55296
	ds_read_b128 v[194:197], v150 offset:56320
	global_load_lds_dwordx4 v[144:145], off
	v_lshl_add_u64 v[144:145], v[220:221], 0, s[0:1]
	s_mov_b32 m0, s45
	s_nop 0
	global_load_lds_dwordx4 v[144:145], off
	s_barrier
	s_waitcnt lgkmcnt(0)
	s_setprio 1
	s_waitcnt lgkmcnt(0)
	v_mfma_f32_16x16x32_bf16 v[60:63], v[140:143], v[166:169], v[60:63]
	v_mfma_f32_16x16x32_bf16 v[56:59], v[158:161], v[166:169], v[56:59]
	v_mfma_f32_16x16x32_bf16 v[44:47], v[140:143], v[174:177], v[44:47]
	v_mfma_f32_16x16x32_bf16 v[40:43], v[158:161], v[174:177], v[40:43]
	v_mfma_f32_16x16x32_bf16 v[28:31], v[140:143], v[182:185], v[28:31]
	v_mfma_f32_16x16x32_bf16 v[24:27], v[158:161], v[182:185], v[24:27]
	v_mfma_f32_16x16x32_bf16 v[12:15], v[140:143], v[190:193], v[12:15]
	v_mfma_f32_16x16x32_bf16 v[8:11], v[158:161], v[190:193], v[8:11]
	v_mfma_f32_16x16x32_bf16 v[60:63], v[154:157], v[170:173], v[60:63]
	v_mfma_f32_16x16x32_bf16 v[56:59], v[162:165], v[170:173], v[56:59]
	v_mfma_f32_16x16x32_bf16 v[44:47], v[154:157], v[178:181], v[44:47]
	v_mfma_f32_16x16x32_bf16 v[40:43], v[162:165], v[178:181], v[40:43]
	v_mfma_f32_16x16x32_bf16 v[28:31], v[154:157], v[186:189], v[28:31]
	v_mfma_f32_16x16x32_bf16 v[24:27], v[162:165], v[186:189], v[24:27]
	v_mfma_f32_16x16x32_bf16 v[12:15], v[154:157], v[194:197], v[12:15]
	v_mfma_f32_16x16x32_bf16 v[8:11], v[162:165], v[194:197], v[8:11]
	s_setprio 0
	s_barrier
	s_add_u32 s4, s4, 0x40080
	s_addc_u32 s5, s5, 0
	s_add_i32 s24, s24, s31
	s_mov_b32 m0, s24
	s_nop 0
	global_load_lds_dwordx4 v130, s[4:5]
	s_add_i32 m0, s24, 0x2000
	s_nop 0
	global_load_lds_dwordx4 v134, s[4:5]
	s_waitcnt vmcnt(6)
	s_barrier
	s_setprio 1
	v_mfma_f32_16x16x32_bf16 v[52:55], v[202:205], v[166:169], v[52:55]
	v_mfma_f32_16x16x32_bf16 v[48:51], v[210:213], v[166:169], v[48:51]
	v_mfma_f32_16x16x32_bf16 v[36:39], v[202:205], v[174:177], v[36:39]
	v_mfma_f32_16x16x32_bf16 v[32:35], v[210:213], v[174:177], v[32:35]
	v_mfma_f32_16x16x32_bf16 v[20:23], v[202:205], v[182:185], v[20:23]
	v_mfma_f32_16x16x32_bf16 v[16:19], v[210:213], v[182:185], v[16:19]
	v_mfma_f32_16x16x32_bf16 v[4:7], v[202:205], v[190:193], v[4:7]
	v_mfma_f32_16x16x32_bf16 v[0:3], v[210:213], v[190:193], v[0:3]
	v_mfma_f32_16x16x32_bf16 v[52:55], v[206:209], v[170:173], v[52:55]
	v_mfma_f32_16x16x32_bf16 v[48:51], v[214:217], v[170:173], v[48:51]
	v_mfma_f32_16x16x32_bf16 v[36:39], v[206:209], v[178:181], v[36:39]
	v_mfma_f32_16x16x32_bf16 v[32:35], v[214:217], v[178:181], v[32:35]
	v_mfma_f32_16x16x32_bf16 v[20:23], v[206:209], v[186:189], v[20:23]
	v_mfma_f32_16x16x32_bf16 v[16:19], v[214:217], v[186:189], v[16:19]
	v_mfma_f32_16x16x32_bf16 v[4:7], v[206:209], v[194:197], v[4:7]
	v_mfma_f32_16x16x32_bf16 v[0:3], v[214:217], v[194:197], v[0:3]
	s_setprio 0
	s_add_i32 s61, s61, 2
	s_add_u32 s2, s2, 0x100
	s_addc_u32 s3, s3, 0
	s_add_u32 s59, s59, 0x100
	s_addc_u32 s60, s60, 0
	s_cmp_gt_u32 s61, 13
	s_barrier
;     __device__ __forceinline__ void operator()(const AccT& acc, const Unit& u, int wr, int wc, int fr, int fq) const {
;     ...
;         const int rbase = wr * 64 + fr;
;         const int tb = u.pn * 256 + wc * 32 + 8 * fq;
;         const int o0 = wc * 32 + 8 * fq;
;         const int j = fr & 3; const float sgn = ((fr >> 2) & 1) ? 1.0f : -1.0f;
; #pragma unroll
;         for (int ai = 0; ai < 2; ++ai) {
;             const int hh = 2 * ai + wr;
;             const float l2f = lgd[hh] * 1.4426950408889634f, l2b = lgd[4 + hh] * 1.4426950408889634f;
;             const float zf0 = exp2f((float)(127 - o0) * l2f), zfs = exp2f(-l2f), zb0 = exp2f((float)o0 * l2b), zbs = exp2f(l2b);
; #pragma unroll
;             for (int m = 0; m < 4; ++m) {
;                 const int r = rbase + ai * 128 + m * 16;
;                 const int d = 4 * (2 * m + (fr >> 3)) + j;
; #pragma unroll
;                 for (int bj = 0; bj < 2; ++bj) {
;                     const int t0 = tb + bj * 128;
;                     float v[8];
; #pragma unroll
;                     for (int jj = 0; jj < 4; ++jj) { v[jj] = acc[ai][bj][m][0][jj]; v[4 + jj] = acc[ai][bj][m][1][jj]; }
;                     if constexpr (ROPE) {
;                         const int t = t0 & 2047;
; #pragma unroll
;                         for (int hf = 0; hf < 2; ++hf) {
;                             f32x4 cs, sn;
;                             if (m < 2) { const float c1 = ropeA[(t >> 6) * 16 + d], s1 = ropeA[1024 + (t >> 6) * 16 + d]; cs = (f32x4){c1, c1, c1, c1}; sn = (f32x4){s1, s1, s1, s1}; }
;                             else { const float* cb = ropeA + 2048 + (d - 16) * 64 + (t & 63) + 4 * hf; cs = *(const f32x4*)(cb); sn = *(const f32x4*)(cb + 1024); }
; #pragma unroll
;                             for (int jj = 0; jj < 4; ++jj) { const float pr = __shfl_xor(v[4 * hf + jj], 4); v[4 * hf + jj] = v[4 * hf + jj] * cs[jj] + sgn * pr * sn[jj]; }
;                             __builtin_amdgcn_sched_barrier(0);
;                         }
;                     }
;                     float zf[8], zb[8]; zf[0] = zf0; zb[0] = zb0;
; #pragma unroll
;                     for (int jj = 1; jj < 8; ++jj) { zf[jj] = zf[jj - 1] * zfs; zb[jj] = zb[jj - 1] * zbs; }
;                     u32x4 wf, wb;
	s_cbranch_scc0 .LBB0_693
	v_mov_b32_e32 v141, v147
	v_mov_b32_e32 v140, v146
	global_load_dword v156, v131, s[6:7]
	global_load_dword v157, v131, s[6:7] offset:16
	s_lshl_b32 s2, s56, 8
	s_or_b32 s2, s2, s43
	v_add_u32_e32 v140, s42, v140
	v_lshlrev_b32_e32 v141, 3, v141
	v_add_u32_e32 v142, s2, v141
	v_add_u32_e32 v143, s43, v141
	v_ashrrev_i32_e32 v141, 31, v140
	v_sub_u32_e32 v144, 0x7f, v143
	v_lshlrev_b64 v[140:141], 14, v[140:141]
	v_cvt_f32_i32_e32 v154, v143
	v_ashrrev_i32_e32 v143, 31, v142
	v_cvt_f32_i32_e32 v155, v144
	v_lshl_add_u64 v[140:141], s[70:71], 0, v[140:141]
	s_mov_b32 s3, 0x400000
	v_lshl_add_u64 v[140:141], v[142:143], 1, v[140:141]
	v_add_co_u32_e32 v144, vcc, s3, v140
	s_mov_b64 s[4:5], 0x400000
	s_nop 0
	v_addc_co_u32_e32 v145, vcc, 0, v141, vcc
	v_lshl_add_u64 v[142:143], v[140:141], 0, s[4:5]
	s_waitcnt vmcnt(0)
	v_mul_f32_e32 v158, 0x3fb8aa3b, v156
	v_mul_f32_e32 v159, 0x3fb8aa3b, v157
	v_mul_f32_e32 v160, v158, v155
	v_cmp_lt_f32_e32 vcc, s51, v158
	v_mul_f32_e32 v162, v159, v154
	v_cmp_gt_f32_e64 s[2:3], s49, v159
	v_cndmask_b32_e32 v161, 0, v153, vcc
	v_cmp_gt_f32_e64 s[4:5], s49, v160
	v_cndmask_b32_e64 v163, 0, v153, s[2:3]
	s_and_b64 s[24:25], vcc, exec
	v_cmp_gt_f32_e32 vcc, s49, v162
	v_fmac_f32_e32 v163, 0x3fb8aa3b, v157
	v_cndmask_b32_e64 v157, 0, v153, s[4:5]
	v_cndmask_b32_e32 v162, 0, v153, vcc
	v_fmac_f32_e32 v161, 0xbfb8aa3b, v156
	v_fmac_f32_e32 v157, v158, v155
	v_fmac_f32_e32 v162, v159, v154
	v_exp_f32_e32 v161, v161
	v_exp_f32_e32 v163, v163
	v_exp_f32_e32 v157, v157
	v_exp_f32_e32 v158, v162
	v_cndmask_b32_e64 v160, 0, v152, s[4:5]
	s_cselect_b32 s4, 0xffffffc0, 0
	s_and_b64 s[2:3], s[2:3], exec
	v_cndmask_b32_e32 v156, 0, v152, vcc
	s_cselect_b32 s2, 0xffffffc0, 0
	v_ldexp_f32 v161, v161, s4
	v_ldexp_f32 v162, v163, s2
	v_ldexp_f32 v163, v157, v160
	v_ldexp_f32 v156, v158, v156
	v_mul_f32_e32 v164, v161, v163
	v_mul_f32_e32 v157, v162, v156
	v_mul_f32_e32 v158, v124, v163
	v_mul_f32_e32 v165, v124, v156
	v_mul_f32_e32 v166, v161, v164
	v_mul_f32_e32 v124, v162, v157
	v_mul_f32_e32 v159, v125, v164
	v_mul_f32_e32 v167, v125, v157
	v_mul_f32_e32 v168, v161, v166
	v_mul_f32_e32 v125, v162, v124
	v_cvt_pk_bf16_f32 v158, v158, v159
	v_mul_f32_e32 v159, v126, v166
	v_mul_f32_e32 v169, v126, v124
	v_mul_f32_e32 v170, v161, v168
	v_mul_f32_e32 v126, v162, v125
	v_mul_f32_e32 v171, v161, v170
	v_mul_f32_e32 v172, v162, v126
	v_mul_f32_e32 v160, v127, v168
	v_mul_f32_e32 v174, v161, v171
	v_mul_f32_e32 v175, v162, v172
	v_cvt_pk_bf16_f32 v159, v159, v160
	v_mul_f32_e32 v160, v120, v170
	v_mul_f32_e32 v173, v120, v126
	v_mul_f32_e32 v120, v121, v171
	v_mul_f32_e32 v177, v161, v174
	v_mul_f32_e32 v162, v162, v175
	v_mul_f32_e32 v176, v121, v172
	v_cvt_pk_bf16_f32 v160, v160, v120
	v_mul_f32_e32 v120, v122, v174
	v_mul_f32_e32 v121, v123, v177
	v_mul_f32_e32 v123, v123, v162
	v_cvt_pk_bf16_f32 v161, v120, v121
	v_mul_f32_e32 v127, v127, v125
	v_mul_f32_e32 v178, v122, v175
	v_cvt_pk_bf16_f32 v120, v165, v167
	v_cvt_pk_bf16_f32 v121, v169, v127
	v_cvt_pk_bf16_f32 v122, v173, v176
	v_cvt_pk_bf16_f32 v123, v178, v123
	global_store_dwordx4 v[140:141], v[158:161], off
	global_store_dwordx4 v[144:145], v[120:123], off
	s_nop 1
	v_mul_f32_e32 v120, v116, v163
	v_mul_f32_e32 v121, v117, v164
	v_cvt_pk_bf16_f32 v120, v120, v121
	v_mul_f32_e32 v121, v118, v166
	v_mul_f32_e32 v122, v119, v168
	v_cvt_pk_bf16_f32 v121, v121, v122
	v_mul_f32_e32 v122, v112, v170
	v_mul_f32_e32 v123, v113, v171
	v_cvt_pk_bf16_f32 v122, v122, v123
	v_mul_f32_e32 v123, v114, v174
	v_mul_f32_e32 v116, v116, v156
	v_mul_f32_e32 v117, v117, v157
	v_mul_f32_e32 v127, v115, v177
	v_cvt_pk_bf16_f32 v123, v123, v127
	v_cvt_pk_bf16_f32 v116, v116, v117
	v_mul_f32_e32 v117, v118, v124
	v_mul_f32_e32 v118, v119, v125
	v_mul_f32_e32 v112, v112, v126
	v_mul_f32_e32 v113, v113, v172
	v_cvt_pk_bf16_f32 v117, v117, v118
	v_cvt_pk_bf16_f32 v118, v112, v113
	v_mul_f32_e32 v112, v114, v175
	v_mul_f32_e32 v113, v115, v162
	v_cvt_pk_bf16_f32 v119, v112, v113
	global_store_dwordx4 v[140:141], v[120:123], off offset:256
	global_store_dwordx4 v[142:143], v[116:119], off offset:256
	v_mul_f32_e32 v112, v108, v163
	v_mul_f32_e32 v113, v109, v164
	v_cvt_pk_bf16_f32 v112, v112, v113
	v_mul_f32_e32 v113, v110, v166
	v_mul_f32_e32 v114, v111, v168
	v_cvt_pk_bf16_f32 v113, v113, v114
	v_mul_f32_e32 v114, v104, v170
	v_mul_f32_e32 v115, v105, v171
	v_cvt_pk_bf16_f32 v114, v114, v115
	v_mul_f32_e32 v115, v106, v174
	v_mul_f32_e32 v108, v108, v156
	v_mul_f32_e32 v109, v109, v157
	v_mul_f32_e32 v116, v107, v177
	v_cvt_pk_bf16_f32 v115, v115, v116
	v_cvt_pk_bf16_f32 v108, v108, v109
	v_mul_f32_e32 v109, v110, v124
	v_mul_f32_e32 v110, v111, v125
	v_mul_f32_e32 v104, v104, v126
	s_mov_b64 s[2:3], 0x40000
	v_cvt_pk_bf16_f32 v109, v109, v110
	v_mul_f32_e32 v105, v105, v172
	v_cvt_pk_bf16_f32 v110, v104, v105
	v_mul_f32_e32 v104, v106, v175
	v_lshl_add_u64 v[116:117], v[140:141], 0, s[2:3]
	s_mov_b32 s2, 0x40000
	v_mul_f32_e32 v105, v107, v162
	v_cvt_pk_bf16_f32 v111, v104, v105
	v_add_co_u32_e32 v104, vcc, s2, v140
	s_mov_b64 s[2:3], 0x440000
	s_nop 0
	v_addc_co_u32_e32 v105, vcc, 0, v141, vcc
	global_store_dwordx4 v[104:105], v[112:115], off
	s_nop 1
	v_lshl_add_u64 v[112:113], v[140:141], 0, s[2:3]
	s_mov_b32 s2, 0x440000
	v_add_co_u32_e32 v104, vcc, s2, v140
	s_nop 1
	v_addc_co_u32_e32 v105, vcc, 0, v141, vcc
	global_store_dwordx4 v[104:105], v[108:111], off
	v_mul_f32_e32 v104, v100, v163
	v_mul_f32_e32 v105, v101, v164
	v_cvt_pk_bf16_f32 v104, v104, v105
	v_mul_f32_e32 v105, v102, v166
	v_mul_f32_e32 v106, v103, v168
	v_cvt_pk_bf16_f32 v105, v105, v106
;     __device__ __forceinline__ void operator()(const AccT& acc, const Unit& u, int wr, int wc, int fr, int fq) const {
;     ...
;             for (int m = 0; m < 4; ++m) {
;                 const int r = rbase + ai * 128 + m * 16;
;                 const int d = 4 * (2 * m + (fr >> 3)) + j;
; #pragma unroll
;                 for (int bj = 0; bj < 2; ++bj) {
;                     const int t0 = tb + bj * 128;
;                     float v[8];
; #pragma unroll
;                     for (int jj = 0; jj < 4; ++jj) { v[jj] = acc[ai][bj][m][0][jj]; v[4 + jj] = acc[ai][bj][m][1][jj]; }
;                     if constexpr (ROPE) {
;                         const int t = t0 & 2047;
; #pragma unroll
;                         for (int hf = 0; hf < 2; ++hf) {
;                             f32x4 cs, sn;
;                             if (m < 2) { const float c1 = ropeA[(t >> 6) * 16 + d], s1 = ropeA[1024 + (t >> 6) * 16 + d]; cs = (f32x4){c1, c1, c1, c1}; sn = (f32x4){s1, s1, s1, s1}; }
;                             else { const float* cb = ropeA + 2048 + (d - 16) * 64 + (t & 63) + 4 * hf; cs = *(const f32x4*)(cb); sn = *(const f32x4*)(cb + 1024); }
; #pragma unroll
;                             for (int jj = 0; jj < 4; ++jj) { const float pr = __shfl_xor(v[4 * hf + jj], 4); v[4 * hf + jj] = v[4 * hf + jj] * cs[jj] + sgn * pr * sn[jj]; }
;                             __builtin_amdgcn_sched_barrier(0);
;                         }
;                     }
;                     float zf[8], zb[8]; zf[0] = zf0; zb[0] = zb0;
; #pragma unroll
;                     for (int jj = 1; jj < 8; ++jj) { zf[jj] = zf[jj - 1] * zfs; zb[jj] = zb[jj - 1] * zbs; }
;                     u32x4 wf, wb;
;                     wf.x = cvt_pk_bf16(v[0] * zf[0], v[1] * zf[1]); wf.y = cvt_pk_bf16(v[2] * zf[2], v[3] * zf[3]); wf.z = cvt_pk_bf16(v[4] * zf[4], v[5] * zf[5]); wf.w = cvt_pk_bf16(v[6] * zf[6], v[7] * zf[7]);
;                     wb.x = cvt_pk_bf16(v[0] * zb[0], v[1] * zb[1]); wb.y = cvt_pk_bf16(v[2] * zb[2], v[3] * zb[3]); wb.z = cvt_pk_bf16(v[4] * zb[4], v[5] * zb[5]); wb.w = cvt_pk_bf16(v[6] * zb[6], v[7] * zb[7]);
;                     *(u32x4*)(KTZ + (size_t)r * NT + t0) = wf;
;                     *(u32x4*)(KTZ + (size_t)(256 + r) * NT + t0) = wb;
	v_mul_f32_e32 v106, v96, v170
	v_mul_f32_e32 v107, v97, v171
	v_cvt_pk_bf16_f32 v106, v106, v107
	v_mul_f32_e32 v107, v98, v174
	v_mul_f32_e32 v100, v100, v156
	v_mul_f32_e32 v101, v101, v157
	v_mul_f32_e32 v108, v99, v177
	v_cvt_pk_bf16_f32 v107, v107, v108
	v_cvt_pk_bf16_f32 v100, v100, v101
	v_mul_f32_e32 v101, v102, v124
	v_mul_f32_e32 v102, v103, v125
	v_mul_f32_e32 v96, v96, v126
	v_mul_f32_e32 v97, v97, v172
	v_cvt_pk_bf16_f32 v101, v101, v102
	v_cvt_pk_bf16_f32 v102, v96, v97
	v_mul_f32_e32 v96, v98, v175
	v_mul_f32_e32 v97, v99, v162
	v_cvt_pk_bf16_f32 v103, v96, v97
	global_store_dwordx4 v[116:117], v[104:107], off offset:256
	global_store_dwordx4 v[112:113], v[100:103], off offset:256
	v_mul_f32_e32 v96, v92, v163
	v_mul_f32_e32 v97, v93, v164
	v_cvt_pk_bf16_f32 v96, v96, v97
	v_mul_f32_e32 v97, v94, v166
	v_mul_f32_e32 v98, v95, v168
	v_cvt_pk_bf16_f32 v97, v97, v98
	v_mul_f32_e32 v98, v88, v170
	v_mul_f32_e32 v99, v89, v171
	v_cvt_pk_bf16_f32 v98, v98, v99
	v_mul_f32_e32 v99, v90, v174
	v_mul_f32_e32 v92, v92, v156
	v_mul_f32_e32 v93, v93, v157
	v_mul_f32_e32 v100, v91, v177
	v_cvt_pk_bf16_f32 v99, v99, v100
	v_cvt_pk_bf16_f32 v92, v92, v93
	v_mul_f32_e32 v93, v94, v124
	v_mul_f32_e32 v94, v95, v125
	v_mul_f32_e32 v88, v88, v126
	s_mov_b64 s[2:3], 0x80000
	v_cvt_pk_bf16_f32 v93, v93, v94
	v_mul_f32_e32 v89, v89, v172
	v_cvt_pk_bf16_f32 v94, v88, v89
	v_mul_f32_e32 v88, v90, v175
	v_lshl_add_u64 v[100:101], v[140:141], 0, s[2:3]
	s_mov_b32 s2, 0x80000
	v_mul_f32_e32 v89, v91, v162
	v_cvt_pk_bf16_f32 v95, v88, v89
	v_add_co_u32_e32 v88, vcc, s2, v140
	s_mov_b64 s[2:3], 0x480000
	s_nop 0
	v_addc_co_u32_e32 v89, vcc, 0, v141, vcc
	global_store_dwordx4 v[88:89], v[96:99], off
	s_nop 1
	v_lshl_add_u64 v[96:97], v[140:141], 0, s[2:3]
	s_mov_b32 s2, 0x480000
	v_add_co_u32_e32 v88, vcc, s2, v140
	s_nop 1
	v_addc_co_u32_e32 v89, vcc, 0, v141, vcc
	global_store_dwordx4 v[88:89], v[92:95], off
	v_mul_f32_e32 v88, v84, v163
	v_mul_f32_e32 v89, v85, v164
	v_cvt_pk_bf16_f32 v88, v88, v89
	v_mul_f32_e32 v89, v86, v166
	v_mul_f32_e32 v90, v87, v168
	v_cvt_pk_bf16_f32 v89, v89, v90
	v_mul_f32_e32 v90, v80, v170
	v_mul_f32_e32 v91, v81, v171
	v_cvt_pk_bf16_f32 v90, v90, v91
	v_mul_f32_e32 v91, v82, v174
	v_mul_f32_e32 v84, v84, v156
	v_mul_f32_e32 v85, v85, v157
	v_mul_f32_e32 v92, v83, v177
	v_cvt_pk_bf16_f32 v91, v91, v92
	v_cvt_pk_bf16_f32 v84, v84, v85
	v_mul_f32_e32 v85, v86, v124
	v_mul_f32_e32 v86, v87, v125
	v_mul_f32_e32 v80, v80, v126
	v_mul_f32_e32 v81, v81, v172
	v_cvt_pk_bf16_f32 v85, v85, v86
	v_cvt_pk_bf16_f32 v86, v80, v81
	v_mul_f32_e32 v80, v82, v175
	v_mul_f32_e32 v81, v83, v162
	v_cvt_pk_bf16_f32 v87, v80, v81
	global_store_dwordx4 v[100:101], v[88:91], off offset:256
	global_store_dwordx4 v[96:97], v[84:87], off offset:256
	v_mul_f32_e32 v80, v76, v163
	v_mul_f32_e32 v81, v77, v164
	v_cvt_pk_bf16_f32 v80, v80, v81
	v_mul_f32_e32 v81, v78, v166
	v_mul_f32_e32 v82, v79, v168
	v_cvt_pk_bf16_f32 v81, v81, v82
	v_mul_f32_e32 v82, v72, v170
	v_mul_f32_e32 v83, v73, v171
	v_cvt_pk_bf16_f32 v82, v82, v83
	v_mul_f32_e32 v83, v74, v174
	v_mul_f32_e32 v76, v76, v156
	v_mul_f32_e32 v77, v77, v157
	v_mul_f32_e32 v84, v75, v177
	v_cvt_pk_bf16_f32 v83, v83, v84
	v_cvt_pk_bf16_f32 v76, v76, v77
	v_mul_f32_e32 v77, v78, v124
	v_mul_f32_e32 v78, v79, v125
	v_mul_f32_e32 v72, v72, v126
	s_mov_b64 s[2:3], 0xc0000
	v_cvt_pk_bf16_f32 v77, v77, v78
	v_mul_f32_e32 v73, v73, v172
	v_cvt_pk_bf16_f32 v78, v72, v73
	v_mul_f32_e32 v72, v74, v175
	v_lshl_add_u64 v[84:85], v[140:141], 0, s[2:3]
	s_mov_b32 s2, 0xc0000
	v_mul_f32_e32 v73, v75, v162
	v_cvt_pk_bf16_f32 v79, v72, v73
	v_add_co_u32_e32 v72, vcc, s2, v140
	s_mov_b64 s[2:3], 0x4c0000
	s_nop 0
	v_addc_co_u32_e32 v73, vcc, 0, v141, vcc
	global_store_dwordx4 v[72:73], v[80:83], off
	s_nop 1
	v_lshl_add_u64 v[80:81], v[140:141], 0, s[2:3]
	s_mov_b32 s2, 0x4c0000
	v_add_co_u32_e32 v72, vcc, s2, v140
	s_nop 1
	v_addc_co_u32_e32 v73, vcc, 0, v141, vcc
	global_store_dwordx4 v[72:73], v[76:79], off
	v_mul_f32_e32 v72, v68, v163
	v_mul_f32_e32 v73, v69, v164
	v_cvt_pk_bf16_f32 v72, v72, v73
	v_mul_f32_e32 v73, v70, v166
	v_mul_f32_e32 v74, v71, v168
	v_cvt_pk_bf16_f32 v73, v73, v74
	v_mul_f32_e32 v74, v64, v170
	v_mul_f32_e32 v75, v65, v171
	v_cvt_pk_bf16_f32 v74, v74, v75
	v_mul_f32_e32 v75, v66, v174
	v_mul_f32_e32 v68, v68, v156
	v_mul_f32_e32 v69, v69, v157
	v_mul_f32_e32 v76, v67, v177
	v_cvt_pk_bf16_f32 v75, v75, v76
	v_cvt_pk_bf16_f32 v68, v68, v69
	v_mul_f32_e32 v69, v70, v124
	v_mul_f32_e32 v70, v71, v125
	v_mul_f32_e32 v64, v64, v126
	v_mul_f32_e32 v65, v65, v172
	v_cvt_pk_bf16_f32 v69, v69, v70
	v_cvt_pk_bf16_f32 v70, v64, v65
	v_mul_f32_e32 v64, v66, v175
	v_mul_f32_e32 v65, v67, v162
	v_cvt_pk_bf16_f32 v71, v64, v65
	global_store_dwordx4 v[84:85], v[72:75], off offset:256
	global_store_dwordx4 v[80:81], v[68:71], off offset:256
	global_load_dword v70, v131, s[6:7] offset:8
	s_nop 0
	global_load_dword v71, v131, s[6:7] offset:24
	s_mov_b32 s17, 0x200000
	v_add_co_u32_e32 v76, vcc, s17, v140
	s_mov_b32 s19, 0x600000
	s_nop 0
	v_addc_co_u32_e32 v77, vcc, 0, v141, vcc
	v_add_co_u32_e32 v68, vcc, s19, v140
	s_mov_b64 s[2:3], 0x200000
	s_nop 0
	v_addc_co_u32_e32 v69, vcc, 0, v141, vcc
	s_mov_b64 s[4:5], 0x600000
	v_lshl_add_u64 v[64:65], v[140:141], 0, s[2:3]
	v_lshl_add_u64 v[66:67], v[140:141], 0, s[4:5]
	s_waitcnt vmcnt(0)
;     __device__ __forceinline__ void operator()(const AccT& acc, const Unit& u, int wr, int wc, int fr, int fq) const {
;     ...
;         for (int ai = 0; ai < 2; ++ai) {
;             const int hh = 2 * ai + wr;
;             const float l2f = lgd[hh] * 1.4426950408889634f, l2b = lgd[4 + hh] * 1.4426950408889634f;
;             const float zf0 = exp2f((float)(127 - o0) * l2f), zfs = exp2f(-l2f), zb0 = exp2f((float)o0 * l2b), zbs = exp2f(l2b);
; #pragma unroll
;             for (int m = 0; m < 4; ++m) {
;                 const int r = rbase + ai * 128 + m * 16;
;                 const int d = 4 * (2 * m + (fr >> 3)) + j;
; #pragma unroll
;                 for (int bj = 0; bj < 2; ++bj) {
;                     const int t0 = tb + bj * 128;
;                     float v[8];
; #pragma unroll
;                     for (int jj = 0; jj < 4; ++jj) { v[jj] = acc[ai][bj][m][0][jj]; v[4 + jj] = acc[ai][bj][m][1][jj]; }
;                     if constexpr (ROPE) {
;                         const int t = t0 & 2047;
; #pragma unroll
;                         for (int hf = 0; hf < 2; ++hf) {
;                             f32x4 cs, sn;
;                             if (m < 2) { const float c1 = ropeA[(t >> 6) * 16 + d], s1 = ropeA[1024 + (t >> 6) * 16 + d]; cs = (f32x4){c1, c1, c1, c1}; sn = (f32x4){s1, s1, s1, s1}; }
;                             else { const float* cb = ropeA + 2048 + (d - 16) * 64 + (t & 63) + 4 * hf; cs = *(const f32x4*)(cb); sn = *(const f32x4*)(cb + 1024); }
; #pragma unroll
;                             for (int jj = 0; jj < 4; ++jj) { const float pr = __shfl_xor(v[4 * hf + jj], 4); v[4 * hf + jj] = v[4 * hf + jj] * cs[jj] + sgn * pr * sn[jj]; }
;                             __builtin_amdgcn_sched_barrier(0);
;                         }
;                     }
;                     float zf[8], zb[8]; zf[0] = zf0; zb[0] = zb0;
; #pragma unroll
;                     for (int jj = 1; jj < 8; ++jj) { zf[jj] = zf[jj - 1] * zfs; zb[jj] = zb[jj - 1] * zbs; }
;                     u32x4 wf, wb;
;                     wf.x = cvt_pk_bf16(v[0] * zf[0], v[1] * zf[1]); wf.y = cvt_pk_bf16(v[2] * zf[2], v[3] * zf[3]); wf.z = cvt_pk_bf16(v[4] * zf[4], v[5] * zf[5]); wf.w = cvt_pk_bf16(v[6] * zf[6], v[7] * zf[7]);
	v_mul_f32_e32 v72, 0x3fb8aa3b, v70
	v_mul_f32_e32 v73, 0x3fb8aa3b, v71
	v_mul_f32_e32 v74, v72, v155
	v_cmp_lt_f32_e32 vcc, s51, v72
	v_mul_f32_e32 v78, v73, v154
	v_cmp_gt_f32_e64 s[2:3], s49, v73
	v_cndmask_b32_e32 v75, 0, v153, vcc
	v_cmp_gt_f32_e64 s[4:5], s49, v74
	v_cndmask_b32_e64 v79, 0, v153, s[2:3]
	s_and_b64 s[24:25], vcc, exec
	v_cmp_gt_f32_e32 vcc, s49, v78
	v_fmac_f32_e32 v79, 0x3fb8aa3b, v71
	v_cndmask_b32_e64 v71, 0, v153, s[4:5]
	v_cndmask_b32_e32 v78, 0, v153, vcc
	v_fmac_f32_e32 v75, 0xbfb8aa3b, v70
	v_fmac_f32_e32 v71, v72, v155
	v_fmac_f32_e32 v78, v73, v154
	v_exp_f32_e32 v75, v75
	v_exp_f32_e32 v79, v79
	v_exp_f32_e32 v71, v71
	v_exp_f32_e32 v72, v78
	v_cndmask_b32_e64 v74, 0, v152, s[4:5]
	s_cselect_b32 s4, 0xffffffc0, 0
	s_and_b64 s[2:3], s[2:3], exec
	v_cndmask_b32_e32 v70, 0, v152, vcc
	s_cselect_b32 s2, 0xffffffc0, 0
	v_ldexp_f32 v75, v75, s4
	v_ldexp_f32 v78, v79, s2
	v_ldexp_f32 v79, v71, v74
	v_ldexp_f32 v70, v72, v70
	v_mul_f32_e32 v80, v75, v79
	v_mul_f32_e32 v71, v78, v70
	v_mul_f32_e32 v72, v60, v79
	v_mul_f32_e32 v81, v60, v70
	v_mul_f32_e32 v82, v75, v80
	v_mul_f32_e32 v60, v78, v71
	v_mul_f32_e32 v83, v75, v82
	v_mul_f32_e32 v84, v78, v60
	v_mul_f32_e32 v85, v75, v83
	v_mul_f32_e32 v86, v78, v84
	v_mul_f32_e32 v73, v61, v80
	v_mul_f32_e32 v87, v75, v85
	v_mul_f32_e32 v88, v78, v86
	v_cvt_pk_bf16_f32 v72, v72, v73
	v_mul_f32_e32 v73, v62, v82
	v_mul_f32_e32 v74, v63, v83
	v_mul_f32_e32 v90, v75, v87
	v_mul_f32_e32 v91, v78, v88
	v_cvt_pk_bf16_f32 v73, v73, v74
	v_mul_f32_e32 v74, v56, v85
	v_mul_f32_e32 v89, v56, v86
	v_mul_f32_e32 v56, v57, v87
	v_mul_f32_e32 v93, v75, v90
	v_mul_f32_e32 v78, v78, v91
	v_mul_f32_e32 v92, v57, v88
	v_cvt_pk_bf16_f32 v74, v74, v56
	v_mul_f32_e32 v56, v58, v90
	v_mul_f32_e32 v57, v59, v93
	v_mul_f32_e32 v59, v59, v78
	v_cvt_pk_bf16_f32 v75, v56, v57
	v_mul_f32_e32 v61, v61, v71
	v_mul_f32_e32 v62, v62, v60
	v_mul_f32_e32 v63, v63, v84
	v_mul_f32_e32 v94, v58, v91
	v_cvt_pk_bf16_f32 v56, v81, v61
	v_cvt_pk_bf16_f32 v57, v62, v63
	v_cvt_pk_bf16_f32 v58, v89, v92
	v_cvt_pk_bf16_f32 v59, v94, v59
	global_store_dwordx4 v[76:77], v[72:75], off
	global_store_dwordx4 v[68:69], v[56:59], off
	s_nop 1
	v_mul_f32_e32 v56, v52, v79
	v_mul_f32_e32 v57, v53, v80
	v_cvt_pk_bf16_f32 v56, v56, v57
	v_mul_f32_e32 v57, v54, v82
	v_mul_f32_e32 v58, v55, v83
	v_cvt_pk_bf16_f32 v57, v57, v58
	v_mul_f32_e32 v58, v48, v85
	v_mul_f32_e32 v59, v49, v87
	v_cvt_pk_bf16_f32 v58, v58, v59
	v_mul_f32_e32 v59, v50, v90
	v_mul_f32_e32 v52, v52, v70
	v_mul_f32_e32 v53, v53, v71
	v_mul_f32_e32 v61, v51, v93
	v_cvt_pk_bf16_f32 v59, v59, v61
	v_cvt_pk_bf16_f32 v52, v52, v53
	v_mul_f32_e32 v53, v54, v60
	v_mul_f32_e32 v54, v55, v84
	v_mul_f32_e32 v48, v48, v86
	v_mul_f32_e32 v49, v49, v88
	v_cvt_pk_bf16_f32 v53, v53, v54
	v_cvt_pk_bf16_f32 v54, v48, v49
	v_mul_f32_e32 v48, v50, v91
	v_mul_f32_e32 v49, v51, v78
	v_cvt_pk_bf16_f32 v55, v48, v49
	global_store_dwordx4 v[64:65], v[56:59], off offset:256
	global_store_dwordx4 v[66:67], v[52:55], off offset:256
	v_mul_f32_e32 v48, v44, v79
	v_mul_f32_e32 v49, v45, v80
	v_cvt_pk_bf16_f32 v48, v48, v49
	v_mul_f32_e32 v49, v46, v82
	v_mul_f32_e32 v50, v47, v83
	v_cvt_pk_bf16_f32 v49, v49, v50
	v_mul_f32_e32 v50, v40, v85
	v_mul_f32_e32 v51, v41, v87
	v_cvt_pk_bf16_f32 v50, v50, v51
	v_mul_f32_e32 v51, v42, v90
	v_mul_f32_e32 v44, v44, v70
	v_mul_f32_e32 v45, v45, v71
	v_mul_f32_e32 v52, v43, v93
	v_cvt_pk_bf16_f32 v51, v51, v52
	v_cvt_pk_bf16_f32 v44, v44, v45
	v_mul_f32_e32 v45, v46, v60
	v_mul_f32_e32 v46, v47, v84
	v_mul_f32_e32 v40, v40, v86
	s_mov_b64 s[2:3], 0x240000
	v_cvt_pk_bf16_f32 v45, v45, v46
	v_mul_f32_e32 v41, v41, v88
	v_cvt_pk_bf16_f32 v46, v40, v41
	v_mul_f32_e32 v40, v42, v91
	v_lshl_add_u64 v[52:53], v[140:141], 0, s[2:3]
	s_mov_b32 s2, 0x240000
	v_mul_f32_e32 v41, v43, v78
	v_cvt_pk_bf16_f32 v47, v40, v41
	v_add_co_u32_e32 v40, vcc, s2, v140
	s_mov_b64 s[2:3], 0x640000
	s_nop 0
	v_addc_co_u32_e32 v41, vcc, 0, v141, vcc
	global_store_dwordx4 v[40:41], v[48:51], off
	s_nop 1
	v_lshl_add_u64 v[48:49], v[140:141], 0, s[2:3]
	s_mov_b32 s2, 0x640000
	v_add_co_u32_e32 v40, vcc, s2, v140
	s_nop 1
	v_addc_co_u32_e32 v41, vcc, 0, v141, vcc
	global_store_dwordx4 v[40:41], v[44:47], off
	v_mul_f32_e32 v40, v36, v79
	v_mul_f32_e32 v41, v37, v80
	v_cvt_pk_bf16_f32 v40, v40, v41
	v_mul_f32_e32 v41, v38, v82
	v_mul_f32_e32 v42, v39, v83
	v_cvt_pk_bf16_f32 v41, v41, v42
	v_mul_f32_e32 v42, v32, v85
	v_mul_f32_e32 v43, v33, v87
	v_cvt_pk_bf16_f32 v42, v42, v43
	v_mul_f32_e32 v43, v34, v90
	v_mul_f32_e32 v36, v36, v70
; __device__ __forceinline__ unsigned cvt_pk_bf16(float lo, float hi) { unsigned r; asm volatile("v_cvt_pk_bf16_f32 %0, %1, %2" : "=v"(r) : "v"(lo), "v"(hi)); return r; }
; #define PG8_WAIT_V(n) asm volatile("s_waitcnt vmcnt(" #n ")" ::: "memory")
; #define PG8_BAR __builtin_amdgcn_s_barrier()
; template <class Epi, class Sched>
; __device__ __forceinline__ void gemm_phase(LAS unsigned char* lds, const Gemm g, const Sched& S, const Epi& E) {
;     ...
;         E(acc, cur, wr, wc, fr, fq);
;         if (!has_next) break;
; #pragma unroll
;         for (int a = 0; a < 2; ++a)
; #pragma unroll
;             for (int b = 0; b < 2; ++b)
; #pragma unroll
;                 for (int m = 0; m < 4; ++m)
; #pragma unroll
;                     for (int n = 0; n < 2; ++n) acc[a][b][m][n] = (f32x4){0.f, 0.f, 0.f, 0.f};
;         cur = nxt; cA = nA; cB = nB; ++ui;
;     }
;     PG8_WAIT_V(0);
;     if (wr == 0) PG8_BAR;
;     PG8_BAR;
;     __device__ __forceinline__ void operator()(const AccT& acc, const Unit& u, int wr, int wc, int fr, int fq) const {
;     ...
;                     float zf[8], zb[8]; zf[0] = zf0; zb[0] = zb0;
; #pragma unroll
;                     for (int jj = 1; jj < 8; ++jj) { zf[jj] = zf[jj - 1] * zfs; zb[jj] = zb[jj - 1] * zbs; }
;                     u32x4 wf, wb;
;                     wf.x = cvt_pk_bf16(v[0] * zf[0], v[1] * zf[1]); wf.y = cvt_pk_bf16(v[2] * zf[2], v[3] * zf[3]); wf.z = cvt_pk_bf16(v[4] * zf[4], v[5] * zf[5]); wf.w = cvt_pk_bf16(v[6] * zf[6], v[7] * zf[7]);
;                     wb.x = cvt_pk_bf16(v[0] * zb[0], v[1] * zb[1]); wb.y = cvt_pk_bf16(v[2] * zb[2], v[3] * zb[3]); wb.z = cvt_pk_bf16(v[4] * zb[4], v[5] * zb[5]); wb.w = cvt_pk_bf16(v[6] * zb[6], v[7] * zb[7]);
;                     *(u32x4*)(KTZ + (size_t)r * NT + t0) = wf;
;                     *(u32x4*)(KTZ + (size_t)(256 + r) * NT + t0) = wb;
	v_mul_f32_e32 v37, v37, v71
	v_mul_f32_e32 v44, v35, v93
	v_cvt_pk_bf16_f32 v43, v43, v44
	v_cvt_pk_bf16_f32 v36, v36, v37
	v_mul_f32_e32 v37, v38, v60
	v_mul_f32_e32 v38, v39, v84
	v_mul_f32_e32 v32, v32, v86
	v_mul_f32_e32 v33, v33, v88
	v_cvt_pk_bf16_f32 v37, v37, v38
	v_cvt_pk_bf16_f32 v38, v32, v33
	v_mul_f32_e32 v32, v34, v91
	v_mul_f32_e32 v33, v35, v78
	v_cvt_pk_bf16_f32 v39, v32, v33
	global_store_dwordx4 v[52:53], v[40:43], off offset:256
	global_store_dwordx4 v[48:49], v[36:39], off offset:256
	v_mul_f32_e32 v32, v28, v79
	v_mul_f32_e32 v33, v29, v80
	v_cvt_pk_bf16_f32 v32, v32, v33
	v_mul_f32_e32 v33, v30, v82
	v_mul_f32_e32 v34, v31, v83
	v_cvt_pk_bf16_f32 v33, v33, v34
	v_mul_f32_e32 v34, v24, v85
	v_mul_f32_e32 v35, v25, v87
	v_cvt_pk_bf16_f32 v34, v34, v35
	v_mul_f32_e32 v35, v26, v90
	v_mul_f32_e32 v28, v28, v70
	v_mul_f32_e32 v29, v29, v71
	v_mul_f32_e32 v36, v27, v93
	v_cvt_pk_bf16_f32 v35, v35, v36
	v_cvt_pk_bf16_f32 v28, v28, v29
	v_mul_f32_e32 v29, v30, v60
	v_mul_f32_e32 v30, v31, v84
	v_mul_f32_e32 v24, v24, v86
	v_cvt_pk_bf16_f32 v29, v29, v30
	v_mul_f32_e32 v25, v25, v88
	v_cvt_pk_bf16_f32 v30, v24, v25
	v_mul_f32_e32 v24, v26, v91
	v_mul_f32_e32 v25, v27, v78
	v_cvt_pk_bf16_f32 v31, v24, v25
	v_add_co_u32_e32 v24, vcc, s52, v140
	s_mov_b64 s[2:3], 0x280000
	s_nop 0
	v_addc_co_u32_e32 v25, vcc, 0, v141, vcc
	global_store_dwordx4 v[24:25], v[32:35], off
	v_add_co_u32_e32 v24, vcc, s53, v140
	v_lshl_add_u64 v[36:37], v[140:141], 0, s[2:3]
	s_nop 0
	v_addc_co_u32_e32 v25, vcc, 0, v141, vcc
	v_lshl_add_u64 v[32:33], v[140:141], 0, s[8:9]
	global_store_dwordx4 v[24:25], v[28:31], off
	v_mul_f32_e32 v24, v20, v79
	v_mul_f32_e32 v25, v21, v80
	v_cvt_pk_bf16_f32 v24, v24, v25
	v_mul_f32_e32 v25, v22, v82
	v_mul_f32_e32 v26, v23, v83
	v_cvt_pk_bf16_f32 v25, v25, v26
	v_mul_f32_e32 v26, v16, v85
	v_mul_f32_e32 v27, v17, v87
	v_cvt_pk_bf16_f32 v26, v26, v27
	v_mul_f32_e32 v27, v18, v90
	v_mul_f32_e32 v20, v20, v70
	v_mul_f32_e32 v21, v21, v71
	v_mul_f32_e32 v28, v19, v93
	v_cvt_pk_bf16_f32 v27, v27, v28
	v_cvt_pk_bf16_f32 v20, v20, v21
	v_mul_f32_e32 v21, v22, v60
	v_mul_f32_e32 v22, v23, v84
	v_mul_f32_e32 v16, v16, v86
	v_mul_f32_e32 v17, v17, v88
	v_cvt_pk_bf16_f32 v21, v21, v22
	v_cvt_pk_bf16_f32 v22, v16, v17
	v_mul_f32_e32 v16, v18, v91
	v_mul_f32_e32 v17, v19, v78
	v_cvt_pk_bf16_f32 v23, v16, v17
	global_store_dwordx4 v[36:37], v[24:27], off offset:256
	global_store_dwordx4 v[32:33], v[20:23], off offset:256
	v_mul_f32_e32 v16, v12, v79
	v_mul_f32_e32 v17, v13, v80
	v_cvt_pk_bf16_f32 v16, v16, v17
	v_mul_f32_e32 v17, v14, v82
	v_mul_f32_e32 v18, v15, v83
	v_cvt_pk_bf16_f32 v17, v17, v18
	v_mul_f32_e32 v18, v8, v85
	v_mul_f32_e32 v19, v9, v87
	v_cvt_pk_bf16_f32 v18, v18, v19
	v_mul_f32_e32 v19, v10, v90
	v_mul_f32_e32 v12, v12, v70
	v_mul_f32_e32 v13, v13, v71
	v_mul_f32_e32 v20, v11, v93
	v_cvt_pk_bf16_f32 v19, v19, v20
	v_cvt_pk_bf16_f32 v12, v12, v13
	v_mul_f32_e32 v13, v14, v60
	v_mul_f32_e32 v14, v15, v84
	v_mul_f32_e32 v8, v8, v86
	v_cvt_pk_bf16_f32 v13, v13, v14
	v_mul_f32_e32 v9, v9, v88
	v_cvt_pk_bf16_f32 v14, v8, v9
	v_mul_f32_e32 v8, v10, v91
	v_mul_f32_e32 v9, v11, v78
	v_cvt_pk_bf16_f32 v15, v8, v9
	v_add_co_u32_e32 v8, vcc, s54, v140
	v_lshl_add_u64 v[20:21], v[140:141], 0, s[10:11]
	s_nop 0
	v_addc_co_u32_e32 v9, vcc, 0, v141, vcc
	global_store_dwordx4 v[8:9], v[16:19], off
	v_add_co_u32_e32 v8, vcc, s55, v140
	s_nop 0
	v_lshl_add_u64 v[16:17], v[140:141], 0, s[12:13]
	v_addc_co_u32_e32 v9, vcc, 0, v141, vcc
	global_store_dwordx4 v[8:9], v[12:15], off
	v_mul_f32_e32 v8, v4, v79
	v_mul_f32_e32 v9, v5, v80
	v_cvt_pk_bf16_f32 v8, v8, v9
	v_mul_f32_e32 v9, v6, v82
	v_mul_f32_e32 v10, v7, v83
	v_cvt_pk_bf16_f32 v9, v9, v10
	v_mul_f32_e32 v10, v0, v85
	v_mul_f32_e32 v11, v1, v87
	v_cvt_pk_bf16_f32 v10, v10, v11
	v_mul_f32_e32 v11, v2, v90
	v_mul_f32_e32 v4, v4, v70
	v_mul_f32_e32 v5, v5, v71
	v_mul_f32_e32 v12, v3, v93
	v_cvt_pk_bf16_f32 v11, v11, v12
	v_cvt_pk_bf16_f32 v4, v4, v5
	v_mul_f32_e32 v5, v6, v60
	v_mul_f32_e32 v6, v7, v84
	v_mul_f32_e32 v0, v0, v86
	v_mul_f32_e32 v1, v1, v88
	v_cvt_pk_bf16_f32 v5, v5, v6
	v_cvt_pk_bf16_f32 v6, v0, v1
	v_mul_f32_e32 v0, v2, v91
	v_mul_f32_e32 v1, v3, v78
	v_cvt_pk_bf16_f32 v7, v0, v1
	global_store_dwordx4 v[20:21], v[8:11], off offset:256
	global_store_dwordx4 v[16:17], v[4:7], off offset:256
	s_and_b64 vcc, exec, s[14:15]
	s_mov_b32 s56, s16
	s_mov_b64 s[4:5], s[22:23]
	s_mov_b64 s[2:3], s[20:21]
	s_cbranch_vccz .LBB0_686
	s_waitcnt vmcnt(0)
	s_cmpk_gt_u32 s27, 0xff
	s_cbranch_scc1 .LBB0_697
	s_barrier

; #define PG8_STAGE(bufoff, gbase, voff) do { _Pragma("unroll") for (int _i = 0; _i < 2; ++_i) \
;         __builtin_amdgcn_global_load_lds((const unsigned*)((const char*)(gbase) + (voff)[_i]), (LAS unsigned*)(lds + (bufoff) + ldsw + _i * 8192), 16, 0, 0); } while (0)
; #define PG8_LDA(dst, b, h) do { _Pragma("unroll") for (int m = 0; m < 4; ++m) _Pragma("unroll") for (int k = 0; k < 2; ++k) dst[m][k] = *(const LAS bf16x8*)(lds + PG8_SA(b, h) + aoff + m * 2048 + k * 1024); } while (0)
; #define PG8_LDB(dst, b, h) do { _Pragma("unroll") for (int n = 0; n < 2; ++n) _Pragma("unroll") for (int k = 0; k < 2; ++k) dst[n][k] = *(const LAS bf16x8*)(lds + PG8_SB(b, h) + boff + n * 2048 + k * 1024); } while (0)
; #define PG8_WAIT_V(n) asm volatile("s_waitcnt vmcnt(" #n ")" ::: "memory")
; #define PG8_WAIT_L(n) asm volatile("s_waitcnt lgkmcnt(" #n ")" ::: "memory")
; #define PG8_BAR __builtin_amdgcn_s_barrier()
; #define PG8_SCHED __builtin_amdgcn_sched_barrier(0)
; template <class Epi, class Sched>
; __device__ __forceinline__ void gemm_phase(LAS unsigned char* lds, const Gemm g, const Sched& S, const Epi& E) {
;     ...
;     for (;;) {
;         const bool has_next = S.next(ui + 1, nxt);
;         const char* nA = has_next ? (const char*)g.A + (size_t)nxt.pm * tstep : cA; const char* nB = has_next ? (const char*)g.Bt + (size_t)nxt.pn * tstep : cB;
;         for (int t = 0; t < nt; t += 2) {
;             const bool last = (t == nt - 2);
;             const char* a1 = cA + (size_t)(t + 1) * kstep;
;             const char* a2 = last ? nA : cA + (size_t)(t + 2) * kstep; const char* b2 = last ? nB : cB + (size_t)(t + 2) * kstep;
;             const char* a3 = a2 + kstep; const char* b3 = b2 + kstep;
;             PG8_LDB(B0, 0, 0); PG8_SCHED; PG8_LDA(At, 0, 0); PG8_STAGE(PG8_SA(1, 1), a1 + hstep, voffA);
;             PG8_WAIT_L(8); PG8_BAR; PG8_WAIT_L(0); PG8_MMA(0, 0, At, B0); PG8_BAR; PG8_SCHED;
;             PG8_LDB(B1, 0, 1); PG8_STAGE(PG8_SB(0, 0), b2, voffB);
;             PG8_BAR; PG8_WAIT_L(0); PG8_MMA(0, 1, At, B1); PG8_BAR;
;             PG8_LDA(At, 0, 1); PG8_STAGE(PG8_SA(0, 0), a2, voffA);
;             PG8_BAR; PG8_WAIT_L(0); PG8_MMA(1, 0, At, B0); PG8_BAR; PG8_SCHED;
;             PG8_STAGE(PG8_SB(0, 1), b2 + hstep, voffB);
;             PG8_WAIT_V(6); PG8_BAR; PG8_MMA(1, 1, At, B1); PG8_BAR;
.LBB0_712:
	s_ashr_i32 s15, s14, 31
	v_cmp_lt_i64_e64 s[26:27], s[16:17], 64
	s_lshl_b64 s[16:17], s[14:15], 19
	s_add_u32 s16, s38, s16
	s_addc_u32 s17, s39, s17
	s_and_b64 s[18:19], s[26:27], exec
	s_cselect_b32 s15, s17, s23
	s_cselect_b32 s54, s16, s22
	s_ashr_i32 s13, s12, 31
	s_lshl_b64 s[18:19], s[12:13], 19
	s_add_u32 s18, s28, s18
	s_addc_u32 s19, s29, s19
	s_and_b64 s[26:27], s[26:27], exec
	s_cselect_b32 s13, s19, s25
	s_cselect_b32 s55, s18, s24
	s_add_u32 s22, s22, 0x40080
	s_addc_u32 s23, s23, 0
	s_add_u32 s56, s24, 0x100
	s_addc_u32 s57, s25, 0
	s_mov_b32 s58, -2
	s_waitcnt lgkmcnt(0)
	ds_read_b128 v[146:149], v143
	ds_read_b128 v[150:153], v143 offset:1024
	ds_read_b128 v[154:157], v143 offset:2048
	ds_read_b128 v[158:161], v143 offset:3072
	s_add_u32 s24, s22, 0xfffc0080
	s_addc_u32 s25, s23, -1
	s_cmp_eq_u32 s58, 12
	s_cselect_b32 s27, s15, s25
	s_cselect_b32 s26, s54, s24
	s_cselect_b32 s25, s13, s57
	s_cselect_b32 s24, s55, s56
	s_add_i32 m0, s21, 0xc000
	ds_read_b128 v[162:165], v144
	ds_read_b128 v[166:169], v144 offset:1024
	ds_read_b128 v[170:173], v144 offset:2048
	ds_read_b128 v[174:177], v144 offset:3072
	ds_read_b128 v[178:181], v144 offset:4096
	ds_read_b128 v[182:185], v144 offset:5120
	ds_read_b128 v[186:189], v144 offset:6144
	ds_read_b128 v[190:193], v144 offset:7168
	global_load_lds_dwordx4 v136, s[22:23]
	s_add_i32 m0, s21, 0xe000
	s_nop 0
	global_load_lds_dwordx4 v138, s[22:23]
	s_waitcnt lgkmcnt(8)
	s_barrier
	s_waitcnt lgkmcnt(0)
	s_setprio 1
	s_waitcnt lgkmcnt(0)
	v_mfma_f32_16x16x32_bf16 v[124:127], v[146:149], v[162:165], 0
	v_mfma_f32_16x16x32_bf16 v[120:123], v[154:157], v[162:165], 0
	v_mfma_f32_16x16x32_bf16 v[116:119], v[146:149], v[170:173], 0
	v_mfma_f32_16x16x32_bf16 v[108:111], v[154:157], v[170:173], 0
	v_mfma_f32_16x16x32_bf16 v[100:103], v[146:149], v[178:181], 0
	v_mfma_f32_16x16x32_bf16 v[92:95], v[154:157], v[178:181], 0
	v_mfma_f32_16x16x32_bf16 v[84:87], v[146:149], v[186:189], 0
	v_mfma_f32_16x16x32_bf16 v[76:79], v[154:157], v[186:189], 0
	v_mfma_f32_16x16x32_bf16 v[124:127], v[150:153], v[166:169], v[124:127]
	v_mfma_f32_16x16x32_bf16 v[120:123], v[158:161], v[166:169], v[120:123]
	v_mfma_f32_16x16x32_bf16 v[116:119], v[150:153], v[174:177], v[116:119]
	v_mfma_f32_16x16x32_bf16 v[108:111], v[158:161], v[174:177], v[108:111]
	v_mfma_f32_16x16x32_bf16 v[100:103], v[150:153], v[182:185], v[100:103]
	v_mfma_f32_16x16x32_bf16 v[92:95], v[158:161], v[182:185], v[92:95]
	v_mfma_f32_16x16x32_bf16 v[84:87], v[150:153], v[190:193], v[84:87]
	v_mfma_f32_16x16x32_bf16 v[76:79], v[158:161], v[190:193], v[76:79]
	s_setprio 0
	s_barrier
	s_add_i32 s59, s46, s34
	s_mov_b32 m0, s59
	ds_read_b128 v[194:197], v145
	ds_read_b128 v[202:205], v145 offset:1024
	ds_read_b128 v[206:209], v145 offset:2048
	ds_read_b128 v[210:213], v145 offset:3072
	global_load_lds_dwordx4 v130, s[24:25]
	s_add_i32 m0, s59, 0x2000
	s_nop 0
	global_load_lds_dwordx4 v134, s[24:25]
	s_barrier
	s_waitcnt lgkmcnt(0)
	s_setprio 1
	s_waitcnt lgkmcnt(0)
	v_mfma_f32_16x16x32_bf16 v[112:115], v[194:197], v[162:165], 0
	v_mfma_f32_16x16x32_bf16 v[104:107], v[206:209], v[162:165], 0
	v_mfma_f32_16x16x32_bf16 v[96:99], v[194:197], v[170:173], 0
	v_mfma_f32_16x16x32_bf16 v[88:91], v[206:209], v[170:173], 0
	v_mfma_f32_16x16x32_bf16 v[80:83], v[194:197], v[178:181], 0
	v_mfma_f32_16x16x32_bf16 v[72:75], v[206:209], v[178:181], 0
	v_mfma_f32_16x16x32_bf16 v[68:71], v[194:197], v[186:189], 0
	v_mfma_f32_16x16x32_bf16 v[64:67], v[206:209], v[186:189], 0
	v_mfma_f32_16x16x32_bf16 v[112:115], v[202:205], v[166:169], v[112:115]
	v_mfma_f32_16x16x32_bf16 v[104:107], v[210:213], v[166:169], v[104:107]
	v_mfma_f32_16x16x32_bf16 v[96:99], v[202:205], v[174:177], v[96:99]
	v_mfma_f32_16x16x32_bf16 v[88:91], v[210:213], v[174:177], v[88:91]
	v_mfma_f32_16x16x32_bf16 v[80:83], v[202:205], v[182:185], v[80:83]
	v_mfma_f32_16x16x32_bf16 v[72:75], v[210:213], v[182:185], v[72:75]
	v_mfma_f32_16x16x32_bf16 v[68:71], v[202:205], v[190:193], v[68:71]
	v_mfma_f32_16x16x32_bf16 v[64:67], v[210:213], v[190:193], v[64:67]
	s_setprio 0
	s_mov_b32 m0, s21
	v_lshl_add_u64 v[216:217], s[26:27], 0, v[128:129]
	s_barrier
	ds_read_b128 v[162:165], v144 offset:16384
	ds_read_b128 v[166:169], v144 offset:17408
	ds_read_b128 v[170:173], v144 offset:18432
	ds_read_b128 v[174:177], v144 offset:19456
	ds_read_b128 v[178:181], v144 offset:20480
	ds_read_b128 v[182:185], v144 offset:21504
	ds_read_b128 v[186:189], v144 offset:22528
	ds_read_b128 v[190:193], v144 offset:23552
	global_load_lds_dwordx4 v128, s[26:27]
	v_lshl_add_u64 v[218:219], s[26:27], 0, v[132:133]
	s_mov_b32 m0, s35
	s_nop 0
	global_load_lds_dwordx4 v132, s[26:27]
	s_barrier
	s_waitcnt lgkmcnt(0)
	s_setprio 1
	s_waitcnt lgkmcnt(0)
	v_mfma_f32_16x16x32_bf16 v[60:63], v[146:149], v[162:165], 0
	v_mfma_f32_16x16x32_bf16 v[56:59], v[154:157], v[162:165], 0
	v_mfma_f32_16x16x32_bf16 v[52:55], v[146:149], v[170:173], 0
	v_mfma_f32_16x16x32_bf16 v[44:47], v[154:157], v[170:173], 0
	v_mfma_f32_16x16x32_bf16 v[36:39], v[146:149], v[178:181], 0
	v_mfma_f32_16x16x32_bf16 v[28:31], v[154:157], v[178:181], 0
	v_mfma_f32_16x16x32_bf16 v[20:23], v[146:149], v[186:189], 0
	v_mfma_f32_16x16x32_bf16 v[12:15], v[154:157], v[186:189], 0
	v_mfma_f32_16x16x32_bf16 v[60:63], v[150:153], v[166:169], v[60:63]
	v_mfma_f32_16x16x32_bf16 v[56:59], v[158:161], v[166:169], v[56:59]
	v_mfma_f32_16x16x32_bf16 v[52:55], v[150:153], v[174:177], v[52:55]
	v_mfma_f32_16x16x32_bf16 v[44:47], v[158:161], v[174:177], v[44:47]
	v_mfma_f32_16x16x32_bf16 v[36:39], v[150:153], v[182:185], v[36:39]
	v_mfma_f32_16x16x32_bf16 v[28:31], v[158:161], v[182:185], v[28:31]
	v_mfma_f32_16x16x32_bf16 v[20:23], v[150:153], v[190:193], v[20:23]
	v_mfma_f32_16x16x32_bf16 v[12:15], v[158:161], v[190:193], v[12:15]
	s_setprio 0
	s_barrier
; #define PG8_STAGE(bufoff, gbase, voff) do { _Pragma("unroll") for (int _i = 0; _i < 2; ++_i) \
;         __builtin_amdgcn_global_load_lds((const unsigned*)((const char*)(gbase) + (voff)[_i]), (LAS unsigned*)(lds + (bufoff) + ldsw + _i * 8192), 16, 0, 0); } while (0)
; #define PG8_LDA(dst, b, h) do { _Pragma("unroll") for (int m = 0; m < 4; ++m) _Pragma("unroll") for (int k = 0; k < 2; ++k) dst[m][k] = *(const LAS bf16x8*)(lds + PG8_SA(b, h) + aoff + m * 2048 + k * 1024); } while (0)
; #define PG8_LDB(dst, b, h) do { _Pragma("unroll") for (int n = 0; n < 2; ++n) _Pragma("unroll") for (int k = 0; k < 2; ++k) dst[n][k] = *(const LAS bf16x8*)(lds + PG8_SB(b, h) + boff + n * 2048 + k * 1024); } while (0)
; #define PG8_MMA(ai, bj, At, Bt) do { __builtin_amdgcn_s_setprio(1); _Pragma("unroll") for (int m = 0; m < 4; ++m) _Pragma("unroll") for (int n = 0; n < 2; ++n) _Pragma("unroll") for (int k = 0; k < 2; ++k) \
;         acc[ai][bj][m][n] = __builtin_amdgcn_mfma_f32_16x16x32_bf16(Bt[n][k], At[m][k], acc[ai][bj][m][n], 0, 0, 0); __builtin_amdgcn_s_setprio(0); } while (0)
; #define PG8_WAIT_V(n) asm volatile("s_waitcnt vmcnt(" #n ")" ::: "memory")
; #define PG8_WAIT_L(n) asm volatile("s_waitcnt lgkmcnt(" #n ")" ::: "memory")
; #define PG8_BAR __builtin_amdgcn_s_barrier()
; #define PG8_SCHED __builtin_amdgcn_sched_barrier(0)
; template <class Epi, class Sched>
; __device__ __forceinline__ void gemm_phase(LAS unsigned char* lds, const Gemm g, const Sched& S, const Epi& E) {
;     ...
;             PG8_STAGE(PG8_SB(0, 1), b2 + hstep, voffB);
;             PG8_WAIT_V(6); PG8_BAR; PG8_MMA(1, 1, At, B1); PG8_BAR;
;             PG8_LDB(B0, 1, 0); PG8_SCHED; PG8_LDA(At, 1, 0); PG8_STAGE(PG8_SA(0, 1), a2 + hstep, voffA);
;             PG8_WAIT_L(8); PG8_BAR; PG8_WAIT_L(0); PG8_MMA(0, 0, At, B0); PG8_BAR; PG8_SCHED;
;             PG8_LDB(B1, 1, 1); PG8_STAGE(PG8_SB(1, 0), b3, voffB);
;             PG8_BAR; PG8_WAIT_L(0); PG8_MMA(0, 1, At, B1); PG8_BAR;
;             PG8_LDA(At, 1, 1); PG8_STAGE(PG8_SA(1, 0), a3, voffA);
;             PG8_BAR; PG8_WAIT_L(0); PG8_MMA(1, 0, At, B0); PG8_BAR; PG8_SCHED;
	s_add_u32 s60, s24, 0x40000
	s_addc_u32 s61, s25, 0
	s_add_i32 s59, s47, s34
	s_mov_b32 m0, s59
	s_nop 0
	global_load_lds_dwordx4 v130, s[60:61]
	s_add_i32 m0, s59, 0x2000
	s_nop 0
	global_load_lds_dwordx4 v134, s[60:61]
	s_waitcnt vmcnt(6)
	s_barrier
	s_setprio 1
	v_mfma_f32_16x16x32_bf16 v[48:51], v[194:197], v[162:165], 0
	v_mfma_f32_16x16x32_bf16 v[40:43], v[206:209], v[162:165], 0
	v_mfma_f32_16x16x32_bf16 v[32:35], v[194:197], v[170:173], 0
	v_mfma_f32_16x16x32_bf16 v[24:27], v[206:209], v[170:173], 0
	v_mfma_f32_16x16x32_bf16 v[16:19], v[194:197], v[178:181], 0
	v_mfma_f32_16x16x32_bf16 v[8:11], v[206:209], v[178:181], 0
	v_mfma_f32_16x16x32_bf16 v[4:7], v[194:197], v[186:189], 0
	v_mfma_f32_16x16x32_bf16 v[0:3], v[206:209], v[186:189], 0
	v_mfma_f32_16x16x32_bf16 v[48:51], v[202:205], v[166:169], v[48:51]
	v_mfma_f32_16x16x32_bf16 v[40:43], v[210:213], v[166:169], v[40:43]
	v_mfma_f32_16x16x32_bf16 v[32:35], v[202:205], v[174:177], v[32:35]
	v_mfma_f32_16x16x32_bf16 v[24:27], v[210:213], v[174:177], v[24:27]
	v_mfma_f32_16x16x32_bf16 v[16:19], v[202:205], v[182:185], v[16:19]
	v_mfma_f32_16x16x32_bf16 v[8:11], v[210:213], v[182:185], v[8:11]
	v_mfma_f32_16x16x32_bf16 v[4:7], v[202:205], v[190:193], v[4:7]
	v_mfma_f32_16x16x32_bf16 v[0:3], v[210:213], v[190:193], v[0:3]
	s_setprio 0
	s_add_i32 s59, 0, 0x18000
	v_add_u32_e32 v158, s59, v142
	s_barrier
	ds_read_b128 v[146:149], v158
	ds_read_b128 v[150:153], v158 offset:1024
	ds_read_b128 v[154:157], v158 offset:2048
	ds_read_b128 v[158:161], v158 offset:3072
	s_add_u32 s26, s26, 0x40000
	s_addc_u32 s27, s27, 0
	s_mov_b32 m0, s36
	ds_read_b128 v[162:165], v144 offset:32768
	ds_read_b128 v[166:169], v144 offset:33792
	ds_read_b128 v[170:173], v144 offset:34816
	ds_read_b128 v[174:177], v144 offset:35840
	ds_read_b128 v[178:181], v144 offset:36864
	ds_read_b128 v[182:185], v144 offset:37888
	ds_read_b128 v[186:189], v144 offset:38912
	ds_read_b128 v[190:193], v144 offset:39936
	global_load_lds_dwordx4 v128, s[26:27]
	s_mov_b32 m0, s37
	s_nop 0
	global_load_lds_dwordx4 v132, s[26:27]
	s_waitcnt lgkmcnt(8)
	s_barrier
	s_waitcnt lgkmcnt(0)
	s_setprio 1
	s_waitcnt lgkmcnt(0)
	v_mfma_f32_16x16x32_bf16 v[124:127], v[146:149], v[162:165], v[124:127]
	v_mfma_f32_16x16x32_bf16 v[120:123], v[154:157], v[162:165], v[120:123]
	v_mfma_f32_16x16x32_bf16 v[116:119], v[146:149], v[170:173], v[116:119]
	v_mfma_f32_16x16x32_bf16 v[108:111], v[154:157], v[170:173], v[108:111]
	v_mfma_f32_16x16x32_bf16 v[100:103], v[146:149], v[178:181], v[100:103]
	v_mfma_f32_16x16x32_bf16 v[92:95], v[154:157], v[178:181], v[92:95]
	v_mfma_f32_16x16x32_bf16 v[84:87], v[146:149], v[186:189], v[84:87]
	v_mfma_f32_16x16x32_bf16 v[76:79], v[154:157], v[186:189], v[76:79]
	v_mfma_f32_16x16x32_bf16 v[124:127], v[150:153], v[166:169], v[124:127]
	v_mfma_f32_16x16x32_bf16 v[120:123], v[158:161], v[166:169], v[120:123]
	v_mfma_f32_16x16x32_bf16 v[116:119], v[150:153], v[174:177], v[116:119]
	v_mfma_f32_16x16x32_bf16 v[108:111], v[158:161], v[174:177], v[108:111]
	v_mfma_f32_16x16x32_bf16 v[100:103], v[150:153], v[182:185], v[100:103]
	v_mfma_f32_16x16x32_bf16 v[92:95], v[158:161], v[182:185], v[92:95]
	v_mfma_f32_16x16x32_bf16 v[84:87], v[150:153], v[190:193], v[84:87]
	v_mfma_f32_16x16x32_bf16 v[76:79], v[158:161], v[190:193], v[76:79]
	s_setprio 0
	s_barrier
	s_add_i32 s26, 0, 0x1c000
	s_add_i32 s27, s59, s34
	v_add_u32_e32 v210, s26, v142
	s_add_u32 s0, s24, 0x80
	s_addc_u32 s1, s25, 0
	s_mov_b32 m0, s27
	ds_read_b128 v[194:197], v210
	ds_read_b128 v[202:205], v210 offset:1024
	ds_read_b128 v[206:209], v210 offset:2048
	ds_read_b128 v[210:213], v210 offset:3072
	global_load_lds_dwordx4 v130, s[0:1]
	s_add_i32 m0, s27, 0x2000
	s_nop 0
	global_load_lds_dwordx4 v134, s[0:1]
	s_barrier
	s_waitcnt lgkmcnt(0)
	s_setprio 1
	s_waitcnt lgkmcnt(0)
	v_mfma_f32_16x16x32_bf16 v[112:115], v[194:197], v[162:165], v[112:115]
	v_mfma_f32_16x16x32_bf16 v[104:107], v[206:209], v[162:165], v[104:107]
	v_mfma_f32_16x16x32_bf16 v[96:99], v[194:197], v[170:173], v[96:99]
	v_mfma_f32_16x16x32_bf16 v[88:91], v[206:209], v[170:173], v[88:91]
	v_mfma_f32_16x16x32_bf16 v[80:83], v[194:197], v[178:181], v[80:83]
	v_mfma_f32_16x16x32_bf16 v[72:75], v[206:209], v[178:181], v[72:75]
	v_mfma_f32_16x16x32_bf16 v[68:71], v[194:197], v[186:189], v[68:71]
	v_mfma_f32_16x16x32_bf16 v[64:67], v[206:209], v[186:189], v[64:67]
	v_mfma_f32_16x16x32_bf16 v[112:115], v[202:205], v[166:169], v[112:115]
	v_mfma_f32_16x16x32_bf16 v[104:107], v[210:213], v[166:169], v[104:107]
	v_mfma_f32_16x16x32_bf16 v[96:99], v[202:205], v[174:177], v[96:99]
	v_mfma_f32_16x16x32_bf16 v[88:91], v[210:213], v[174:177], v[88:91]
	v_mfma_f32_16x16x32_bf16 v[80:83], v[202:205], v[182:185], v[80:83]
	v_mfma_f32_16x16x32_bf16 v[72:75], v[210:213], v[182:185], v[72:75]
	v_mfma_f32_16x16x32_bf16 v[68:71], v[202:205], v[190:193], v[68:71]
	v_mfma_f32_16x16x32_bf16 v[64:67], v[210:213], v[190:193], v[64:67]
	s_setprio 0
	s_mov_b32 m0, s43
	s_mov_b64 s[0:1], 0x80
	v_lshl_add_u64 v[198:199], v[216:217], 0, s[0:1]
	s_barrier
	ds_read_b128 v[162:165], v144 offset:49152
	ds_read_b128 v[166:169], v144 offset:50176
	ds_read_b128 v[170:173], v144 offset:51200
	ds_read_b128 v[174:177], v144 offset:52224
	ds_read_b128 v[178:181], v144 offset:53248
	ds_read_b128 v[182:185], v144 offset:54272
	ds_read_b128 v[186:189], v144 offset:55296
	ds_read_b128 v[190:193], v144 offset:56320
	global_load_lds_dwordx4 v[198:199], off
	v_lshl_add_u64 v[198:199], v[218:219], 0, s[0:1]
	s_mov_b32 m0, s44
	s_nop 0
	global_load_lds_dwordx4 v[198:199], off
	s_barrier
; #define PG8_STAGE(bufoff, gbase, voff) do { _Pragma("unroll") for (int _i = 0; _i < 2; ++_i) \
;         __builtin_amdgcn_global_load_lds((const unsigned*)((const char*)(gbase) + (voff)[_i]), (LAS unsigned*)(lds + (bufoff) + ldsw + _i * 8192), 16, 0, 0); } while (0)
; #define PG8_LDA(dst, b, h) do { _Pragma("unroll") for (int m = 0; m < 4; ++m) _Pragma("unroll") for (int k = 0; k < 2; ++k) dst[m][k] = *(const LAS bf16x8*)(lds + PG8_SA(b, h) + aoff + m * 2048 + k * 1024); } while (0)
; #define PG8_WAIT_V(n) asm volatile("s_waitcnt vmcnt(" #n ")" ::: "memory")
; #define PG8_WAIT_L(n) asm volatile("s_waitcnt lgkmcnt(" #n ")" ::: "memory")
; template <class Epi, class Sched>
; __device__ __forceinline__ void gemm_phase(LAS unsigned char* lds, const Gemm g, const Sched& S, const Epi& E) {
;     ...
;         for (int t = 0; t < nt; t += 2) {
;             const bool last = (t == nt - 2);
;             const char* a1 = cA + (size_t)(t + 1) * kstep;
;             const char* a2 = last ? nA : cA + (size_t)(t + 2) * kstep; const char* b2 = last ? nB : cB + (size_t)(t + 2) * kstep;
;             const char* a3 = a2 + kstep; const char* b3 = b2 + kstep;
;             PG8_LDB(B0, 0, 0); PG8_SCHED; PG8_LDA(At, 0, 0); PG8_STAGE(PG8_SA(1, 1), a1 + hstep, voffA);
;             PG8_WAIT_L(8); PG8_BAR; PG8_WAIT_L(0); PG8_MMA(0, 0, At, B0); PG8_BAR; PG8_SCHED;
;             PG8_LDB(B1, 0, 1); PG8_STAGE(PG8_SB(0, 0), b2, voffB);
;             PG8_BAR; PG8_WAIT_L(0); PG8_MMA(0, 1, At, B1); PG8_BAR;
;             PG8_LDA(At, 0, 1); PG8_STAGE(PG8_SA(0, 0), a2, voffA);
;             PG8_BAR; PG8_WAIT_L(0); PG8_MMA(1, 0, At, B0); PG8_BAR; PG8_SCHED;
;             PG8_STAGE(PG8_SB(0, 1), b2 + hstep, voffB);
;             PG8_WAIT_V(6); PG8_BAR; PG8_MMA(1, 1, At, B1); PG8_BAR;
;             PG8_LDB(B0, 1, 0); PG8_SCHED; PG8_LDA(At, 1, 0); PG8_STAGE(PG8_SA(0, 1), a2 + hstep, voffA);
;             PG8_WAIT_L(8); PG8_BAR; PG8_WAIT_L(0); PG8_MMA(0, 0, At, B0); PG8_BAR; PG8_SCHED;
;             PG8_LDB(B1, 1, 1); PG8_STAGE(PG8_SB(1, 0), b3, voffB);
;             PG8_BAR; PG8_WAIT_L(0); PG8_MMA(0, 1, At, B1); PG8_BAR;
;             PG8_LDA(At, 1, 1); PG8_STAGE(PG8_SA(1, 0), a3, voffA);
;             PG8_BAR; PG8_WAIT_L(0); PG8_MMA(1, 0, At, B0); PG8_BAR; PG8_SCHED;
;             PG8_STAGE(PG8_SB(1, 1), b3 + hstep, voffB);
;             PG8_WAIT_V(6); PG8_BAR; PG8_MMA(1, 1, At, B1); PG8_BAR;
	s_waitcnt lgkmcnt(0)
	s_setprio 1
	s_waitcnt lgkmcnt(0)
	v_mfma_f32_16x16x32_bf16 v[60:63], v[146:149], v[162:165], v[60:63]
	v_mfma_f32_16x16x32_bf16 v[56:59], v[154:157], v[162:165], v[56:59]
	v_mfma_f32_16x16x32_bf16 v[52:55], v[146:149], v[170:173], v[52:55]
	v_mfma_f32_16x16x32_bf16 v[44:47], v[154:157], v[170:173], v[44:47]
	v_mfma_f32_16x16x32_bf16 v[36:39], v[146:149], v[178:181], v[36:39]
	v_mfma_f32_16x16x32_bf16 v[28:31], v[154:157], v[178:181], v[28:31]
	v_mfma_f32_16x16x32_bf16 v[20:23], v[146:149], v[186:189], v[20:23]
	v_mfma_f32_16x16x32_bf16 v[12:15], v[154:157], v[186:189], v[12:15]
	v_mfma_f32_16x16x32_bf16 v[60:63], v[150:153], v[166:169], v[60:63]
	v_mfma_f32_16x16x32_bf16 v[56:59], v[158:161], v[166:169], v[56:59]
	v_mfma_f32_16x16x32_bf16 v[52:55], v[150:153], v[174:177], v[52:55]
	v_mfma_f32_16x16x32_bf16 v[44:47], v[158:161], v[174:177], v[44:47]
	v_mfma_f32_16x16x32_bf16 v[36:39], v[150:153], v[182:185], v[36:39]
	v_mfma_f32_16x16x32_bf16 v[28:31], v[158:161], v[182:185], v[28:31]
	v_mfma_f32_16x16x32_bf16 v[20:23], v[150:153], v[190:193], v[20:23]
	v_mfma_f32_16x16x32_bf16 v[12:15], v[158:161], v[190:193], v[12:15]
	s_setprio 0
	s_barrier
	s_add_u32 s24, s24, 0x40080
	s_addc_u32 s25, s25, 0
	s_add_i32 s26, s26, s34
	s_mov_b32 m0, s26
	s_nop 0
	global_load_lds_dwordx4 v130, s[24:25]
	s_add_i32 m0, s26, 0x2000
	s_nop 0
	global_load_lds_dwordx4 v134, s[24:25]
	s_waitcnt vmcnt(6)
	s_barrier
	s_setprio 1
	v_mfma_f32_16x16x32_bf16 v[48:51], v[194:197], v[162:165], v[48:51]
	v_mfma_f32_16x16x32_bf16 v[40:43], v[206:209], v[162:165], v[40:43]
	v_mfma_f32_16x16x32_bf16 v[32:35], v[194:197], v[170:173], v[32:35]
	v_mfma_f32_16x16x32_bf16 v[24:27], v[206:209], v[170:173], v[24:27]
	v_mfma_f32_16x16x32_bf16 v[16:19], v[194:197], v[178:181], v[16:19]
	v_mfma_f32_16x16x32_bf16 v[8:11], v[206:209], v[178:181], v[8:11]
	v_mfma_f32_16x16x32_bf16 v[4:7], v[194:197], v[186:189], v[4:7]
	v_mfma_f32_16x16x32_bf16 v[0:3], v[206:209], v[186:189], v[0:3]
	v_mfma_f32_16x16x32_bf16 v[48:51], v[202:205], v[166:169], v[48:51]
	v_mfma_f32_16x16x32_bf16 v[40:43], v[210:213], v[166:169], v[40:43]
	v_mfma_f32_16x16x32_bf16 v[32:35], v[202:205], v[174:177], v[32:35]
	v_mfma_f32_16x16x32_bf16 v[24:27], v[210:213], v[174:177], v[24:27]
	v_mfma_f32_16x16x32_bf16 v[16:19], v[202:205], v[182:185], v[16:19]
	v_mfma_f32_16x16x32_bf16 v[8:11], v[210:213], v[182:185], v[8:11]
	v_mfma_f32_16x16x32_bf16 v[4:7], v[202:205], v[190:193], v[4:7]
	v_mfma_f32_16x16x32_bf16 v[0:3], v[210:213], v[190:193], v[0:3]
	s_setprio 0
	s_add_i32 s58, s58, 2
	s_add_u32 s22, s22, 0x100
	s_addc_u32 s23, s23, 0
	s_add_u32 s56, s56, 0x100
	s_addc_u32 s57, s57, 0
	s_cmp_gt_u32 s58, 13
	s_barrier
.LBB0_713:
	ds_read_b128 v[146:149], v143
	ds_read_b128 v[150:153], v143 offset:1024
	ds_read_b128 v[154:157], v143 offset:2048
	ds_read_b128 v[158:161], v143 offset:3072
	s_add_u32 s24, s22, 0xfffc0080
	s_addc_u32 s25, s23, -1
	s_cmp_eq_u32 s58, 12
	s_cselect_b32 s27, s15, s25
	s_cselect_b32 s26, s54, s24
	s_cselect_b32 s25, s13, s57
	s_cselect_b32 s24, s55, s56
	s_add_i32 m0, s21, 0xc000
	ds_read_b128 v[162:165], v144
	ds_read_b128 v[166:169], v144 offset:1024
	ds_read_b128 v[170:173], v144 offset:2048
	ds_read_b128 v[174:177], v144 offset:3072
	ds_read_b128 v[178:181], v144 offset:4096
	ds_read_b128 v[182:185], v144 offset:5120
	ds_read_b128 v[186:189], v144 offset:6144
	ds_read_b128 v[190:193], v144 offset:7168
	global_load_lds_dwordx4 v136, s[22:23]
	s_add_i32 m0, s21, 0xe000
	s_nop 0
	global_load_lds_dwordx4 v138, s[22:23]
	s_waitcnt lgkmcnt(8)
	s_barrier
	s_waitcnt lgkmcnt(0)
	s_setprio 1
	s_waitcnt lgkmcnt(0)
	v_mfma_f32_16x16x32_bf16 v[124:127], v[146:149], v[162:165], v[124:127]
	v_mfma_f32_16x16x32_bf16 v[120:123], v[154:157], v[162:165], v[120:123]
	v_mfma_f32_16x16x32_bf16 v[116:119], v[146:149], v[170:173], v[116:119]
	v_mfma_f32_16x16x32_bf16 v[108:111], v[154:157], v[170:173], v[108:111]
	v_mfma_f32_16x16x32_bf16 v[100:103], v[146:149], v[178:181], v[100:103]
	v_mfma_f32_16x16x32_bf16 v[92:95], v[154:157], v[178:181], v[92:95]
	v_mfma_f32_16x16x32_bf16 v[84:87], v[146:149], v[186:189], v[84:87]
	v_mfma_f32_16x16x32_bf16 v[76:79], v[154:157], v[186:189], v[76:79]
	v_mfma_f32_16x16x32_bf16 v[124:127], v[150:153], v[166:169], v[124:127]
	v_mfma_f32_16x16x32_bf16 v[120:123], v[158:161], v[166:169], v[120:123]
	v_mfma_f32_16x16x32_bf16 v[116:119], v[150:153], v[174:177], v[116:119]
	v_mfma_f32_16x16x32_bf16 v[108:111], v[158:161], v[174:177], v[108:111]
	v_mfma_f32_16x16x32_bf16 v[100:103], v[150:153], v[182:185], v[100:103]
	v_mfma_f32_16x16x32_bf16 v[92:95], v[158:161], v[182:185], v[92:95]
	v_mfma_f32_16x16x32_bf16 v[84:87], v[150:153], v[190:193], v[84:87]
	v_mfma_f32_16x16x32_bf16 v[76:79], v[158:161], v[190:193], v[76:79]
	s_setprio 0
	s_barrier
	s_add_i32 s59, s46, s34
	s_mov_b32 m0, s59
	ds_read_b128 v[194:197], v145
	ds_read_b128 v[202:205], v145 offset:1024
	ds_read_b128 v[206:209], v145 offset:2048
	ds_read_b128 v[210:213], v145 offset:3072
	global_load_lds_dwordx4 v130, s[24:25]
	s_add_i32 m0, s59, 0x2000
	s_nop 0
	global_load_lds_dwordx4 v134, s[24:25]
	s_barrier
; #define PG8_STAGE(bufoff, gbase, voff) do { _Pragma("unroll") for (int _i = 0; _i < 2; ++_i) \
;         __builtin_amdgcn_global_load_lds((const unsigned*)((const char*)(gbase) + (voff)[_i]), (LAS unsigned*)(lds + (bufoff) + ldsw + _i * 8192), 16, 0, 0); } while (0)
; #define PG8_LDA(dst, b, h) do { _Pragma("unroll") for (int m = 0; m < 4; ++m) _Pragma("unroll") for (int k = 0; k < 2; ++k) dst[m][k] = *(const LAS bf16x8*)(lds + PG8_SA(b, h) + aoff + m * 2048 + k * 1024); } while (0)
; #define PG8_LDB(dst, b, h) do { _Pragma("unroll") for (int n = 0; n < 2; ++n) _Pragma("unroll") for (int k = 0; k < 2; ++k) dst[n][k] = *(const LAS bf16x8*)(lds + PG8_SB(b, h) + boff + n * 2048 + k * 1024); } while (0)
; #define PG8_MMA(ai, bj, At, Bt) do { __builtin_amdgcn_s_setprio(1); _Pragma("unroll") for (int m = 0; m < 4; ++m) _Pragma("unroll") for (int n = 0; n < 2; ++n) _Pragma("unroll") for (int k = 0; k < 2; ++k) \
;         acc[ai][bj][m][n] = __builtin_amdgcn_mfma_f32_16x16x32_bf16(Bt[n][k], At[m][k], acc[ai][bj][m][n], 0, 0, 0); __builtin_amdgcn_s_setprio(0); } while (0)
; #define PG8_WAIT_V(n) asm volatile("s_waitcnt vmcnt(" #n ")" ::: "memory")
; #define PG8_WAIT_L(n) asm volatile("s_waitcnt lgkmcnt(" #n ")" ::: "memory")
; #define PG8_BAR __builtin_amdgcn_s_barrier()
; #define PG8_SCHED __builtin_amdgcn_sched_barrier(0)
; template <class Epi, class Sched>
; __device__ __forceinline__ void gemm_phase(LAS unsigned char* lds, const Gemm g, const Sched& S, const Epi& E) {
;     ...
;             PG8_BAR; PG8_WAIT_L(0); PG8_MMA(0, 1, At, B1); PG8_BAR;
;             PG8_LDA(At, 0, 1); PG8_STAGE(PG8_SA(0, 0), a2, voffA);
;             PG8_BAR; PG8_WAIT_L(0); PG8_MMA(1, 0, At, B0); PG8_BAR; PG8_SCHED;
;             PG8_STAGE(PG8_SB(0, 1), b2 + hstep, voffB);
;             PG8_WAIT_V(6); PG8_BAR; PG8_MMA(1, 1, At, B1); PG8_BAR;
;             PG8_LDB(B0, 1, 0); PG8_SCHED; PG8_LDA(At, 1, 0); PG8_STAGE(PG8_SA(0, 1), a2 + hstep, voffA);
;             PG8_WAIT_L(8); PG8_BAR; PG8_WAIT_L(0); PG8_MMA(0, 0, At, B0); PG8_BAR; PG8_SCHED;
	s_waitcnt lgkmcnt(0)
	s_setprio 1
	s_waitcnt lgkmcnt(0)
	v_mfma_f32_16x16x32_bf16 v[112:115], v[194:197], v[162:165], v[112:115]
	v_mfma_f32_16x16x32_bf16 v[104:107], v[206:209], v[162:165], v[104:107]
	v_mfma_f32_16x16x32_bf16 v[96:99], v[194:197], v[170:173], v[96:99]
	v_mfma_f32_16x16x32_bf16 v[88:91], v[206:209], v[170:173], v[88:91]
	v_mfma_f32_16x16x32_bf16 v[80:83], v[194:197], v[178:181], v[80:83]
	v_mfma_f32_16x16x32_bf16 v[72:75], v[206:209], v[178:181], v[72:75]
	v_mfma_f32_16x16x32_bf16 v[68:71], v[194:197], v[186:189], v[68:71]
	v_mfma_f32_16x16x32_bf16 v[64:67], v[206:209], v[186:189], v[64:67]
	v_mfma_f32_16x16x32_bf16 v[112:115], v[202:205], v[166:169], v[112:115]
	v_mfma_f32_16x16x32_bf16 v[104:107], v[210:213], v[166:169], v[104:107]
	v_mfma_f32_16x16x32_bf16 v[96:99], v[202:205], v[174:177], v[96:99]
	v_mfma_f32_16x16x32_bf16 v[88:91], v[210:213], v[174:177], v[88:91]
	v_mfma_f32_16x16x32_bf16 v[80:83], v[202:205], v[182:185], v[80:83]
	v_mfma_f32_16x16x32_bf16 v[72:75], v[210:213], v[182:185], v[72:75]
	v_mfma_f32_16x16x32_bf16 v[68:71], v[202:205], v[190:193], v[68:71]
	v_mfma_f32_16x16x32_bf16 v[64:67], v[210:213], v[190:193], v[64:67]
	s_setprio 0
	s_mov_b32 m0, s21
	v_lshl_add_u64 v[216:217], s[26:27], 0, v[128:129]
	s_barrier
	ds_read_b128 v[162:165], v144 offset:16384
	ds_read_b128 v[166:169], v144 offset:17408
	ds_read_b128 v[170:173], v144 offset:18432
	ds_read_b128 v[174:177], v144 offset:19456
	ds_read_b128 v[178:181], v144 offset:20480
	ds_read_b128 v[182:185], v144 offset:21504
	ds_read_b128 v[186:189], v144 offset:22528
	ds_read_b128 v[190:193], v144 offset:23552
	global_load_lds_dwordx4 v128, s[26:27]
	v_lshl_add_u64 v[218:219], s[26:27], 0, v[132:133]
	s_mov_b32 m0, s35
	s_nop 0
	global_load_lds_dwordx4 v132, s[26:27]
	s_barrier
	s_waitcnt lgkmcnt(0)
	s_setprio 1
	s_waitcnt lgkmcnt(0)
	v_mfma_f32_16x16x32_bf16 v[60:63], v[146:149], v[162:165], v[60:63]
	v_mfma_f32_16x16x32_bf16 v[56:59], v[154:157], v[162:165], v[56:59]
	v_mfma_f32_16x16x32_bf16 v[52:55], v[146:149], v[170:173], v[52:55]
	v_mfma_f32_16x16x32_bf16 v[44:47], v[154:157], v[170:173], v[44:47]
	v_mfma_f32_16x16x32_bf16 v[36:39], v[146:149], v[178:181], v[36:39]
	v_mfma_f32_16x16x32_bf16 v[28:31], v[154:157], v[178:181], v[28:31]
	v_mfma_f32_16x16x32_bf16 v[20:23], v[146:149], v[186:189], v[20:23]
	v_mfma_f32_16x16x32_bf16 v[12:15], v[154:157], v[186:189], v[12:15]
	v_mfma_f32_16x16x32_bf16 v[60:63], v[150:153], v[166:169], v[60:63]
	v_mfma_f32_16x16x32_bf16 v[56:59], v[158:161], v[166:169], v[56:59]
	v_mfma_f32_16x16x32_bf16 v[52:55], v[150:153], v[174:177], v[52:55]
	v_mfma_f32_16x16x32_bf16 v[44:47], v[158:161], v[174:177], v[44:47]
	v_mfma_f32_16x16x32_bf16 v[36:39], v[150:153], v[182:185], v[36:39]
	v_mfma_f32_16x16x32_bf16 v[28:31], v[158:161], v[182:185], v[28:31]
	v_mfma_f32_16x16x32_bf16 v[20:23], v[150:153], v[190:193], v[20:23]
	v_mfma_f32_16x16x32_bf16 v[12:15], v[158:161], v[190:193], v[12:15]
	s_setprio 0
	s_barrier
	s_add_u32 s60, s24, 0x40000
	s_addc_u32 s61, s25, 0
	s_add_i32 s59, s47, s34
	s_mov_b32 m0, s59
	s_nop 0
	global_load_lds_dwordx4 v130, s[60:61]
	s_add_i32 m0, s59, 0x2000
	s_nop 0
	global_load_lds_dwordx4 v134, s[60:61]
	s_waitcnt vmcnt(6)
	s_barrier
	s_setprio 1
	v_mfma_f32_16x16x32_bf16 v[48:51], v[194:197], v[162:165], v[48:51]
	v_mfma_f32_16x16x32_bf16 v[40:43], v[206:209], v[162:165], v[40:43]
	v_mfma_f32_16x16x32_bf16 v[32:35], v[194:197], v[170:173], v[32:35]
	v_mfma_f32_16x16x32_bf16 v[24:27], v[206:209], v[170:173], v[24:27]
	v_mfma_f32_16x16x32_bf16 v[16:19], v[194:197], v[178:181], v[16:19]
	v_mfma_f32_16x16x32_bf16 v[8:11], v[206:209], v[178:181], v[8:11]
	v_mfma_f32_16x16x32_bf16 v[4:7], v[194:197], v[186:189], v[4:7]
	v_mfma_f32_16x16x32_bf16 v[0:3], v[206:209], v[186:189], v[0:3]
	v_mfma_f32_16x16x32_bf16 v[48:51], v[202:205], v[166:169], v[48:51]
	v_mfma_f32_16x16x32_bf16 v[40:43], v[210:213], v[166:169], v[40:43]
	v_mfma_f32_16x16x32_bf16 v[32:35], v[202:205], v[174:177], v[32:35]
	v_mfma_f32_16x16x32_bf16 v[24:27], v[210:213], v[174:177], v[24:27]
	v_mfma_f32_16x16x32_bf16 v[16:19], v[202:205], v[182:185], v[16:19]
	v_mfma_f32_16x16x32_bf16 v[8:11], v[210:213], v[182:185], v[8:11]
	v_mfma_f32_16x16x32_bf16 v[4:7], v[202:205], v[190:193], v[4:7]
	v_mfma_f32_16x16x32_bf16 v[0:3], v[210:213], v[190:193], v[0:3]
	s_setprio 0
	s_add_i32 s59, 0, 0x18000
	v_add_u32_e32 v158, s59, v142
	s_barrier
	ds_read_b128 v[146:149], v158
	ds_read_b128 v[150:153], v158 offset:1024
	ds_read_b128 v[154:157], v158 offset:2048
	ds_read_b128 v[158:161], v158 offset:3072
	s_add_u32 s26, s26, 0x40000
	s_addc_u32 s27, s27, 0
	s_mov_b32 m0, s36
	ds_read_b128 v[162:165], v144 offset:32768
	ds_read_b128 v[166:169], v144 offset:33792
	ds_read_b128 v[170:173], v144 offset:34816
	ds_read_b128 v[174:177], v144 offset:35840
	ds_read_b128 v[178:181], v144 offset:36864
	ds_read_b128 v[182:185], v144 offset:37888
	ds_read_b128 v[186:189], v144 offset:38912
	ds_read_b128 v[190:193], v144 offset:39936
	global_load_lds_dwordx4 v128, s[26:27]
	s_mov_b32 m0, s37
	s_nop 0
	global_load_lds_dwordx4 v132, s[26:27]
	s_waitcnt lgkmcnt(8)
	s_barrier
; #define PG8_STAGE(bufoff, gbase, voff) do { _Pragma("unroll") for (int _i = 0; _i < 2; ++_i) \
;         __builtin_amdgcn_global_load_lds((const unsigned*)((const char*)(gbase) + (voff)[_i]), (LAS unsigned*)(lds + (bufoff) + ldsw + _i * 8192), 16, 0, 0); } while (0)
; #define PG8_LDA(dst, b, h) do { _Pragma("unroll") for (int m = 0; m < 4; ++m) _Pragma("unroll") for (int k = 0; k < 2; ++k) dst[m][k] = *(const LAS bf16x8*)(lds + PG8_SA(b, h) + aoff + m * 2048 + k * 1024); } while (0)
; #define PG8_LDB(dst, b, h) do { _Pragma("unroll") for (int n = 0; n < 2; ++n) _Pragma("unroll") for (int k = 0; k < 2; ++k) dst[n][k] = *(const LAS bf16x8*)(lds + PG8_SB(b, h) + boff + n * 2048 + k * 1024); } while (0)
; #define PG8_MMA(ai, bj, At, Bt) do { __builtin_amdgcn_s_setprio(1); _Pragma("unroll") for (int m = 0; m < 4; ++m) _Pragma("unroll") for (int n = 0; n < 2; ++n) _Pragma("unroll") for (int k = 0; k < 2; ++k) \
;         acc[ai][bj][m][n] = __builtin_amdgcn_mfma_f32_16x16x32_bf16(Bt[n][k], At[m][k], acc[ai][bj][m][n], 0, 0, 0); __builtin_amdgcn_s_setprio(0); } while (0)
; #define PG8_WAIT_V(n) asm volatile("s_waitcnt vmcnt(" #n ")" ::: "memory")
; #define PG8_WAIT_L(n) asm volatile("s_waitcnt lgkmcnt(" #n ")" ::: "memory")
; #define PG8_BAR __builtin_amdgcn_s_barrier()
; #define PG8_SCHED __builtin_amdgcn_sched_barrier(0)
; template <class Epi, class Sched>
; __device__ __forceinline__ void gemm_phase(LAS unsigned char* lds, const Gemm g, const Sched& S, const Epi& E) {
;     ...
;             PG8_WAIT_L(8); PG8_BAR; PG8_WAIT_L(0); PG8_MMA(0, 0, At, B0); PG8_BAR; PG8_SCHED;
;             PG8_LDB(B1, 1, 1); PG8_STAGE(PG8_SB(1, 0), b3, voffB);
;             PG8_BAR; PG8_WAIT_L(0); PG8_MMA(0, 1, At, B1); PG8_BAR;
;             PG8_LDA(At, 1, 1); PG8_STAGE(PG8_SA(1, 0), a3, voffA);
;             PG8_BAR; PG8_WAIT_L(0); PG8_MMA(1, 0, At, B0); PG8_BAR; PG8_SCHED;
;             PG8_STAGE(PG8_SB(1, 1), b3 + hstep, voffB);
;             PG8_WAIT_V(6); PG8_BAR; PG8_MMA(1, 1, At, B1); PG8_BAR;
	s_waitcnt lgkmcnt(0)
	s_setprio 1
	s_waitcnt lgkmcnt(0)
	v_mfma_f32_16x16x32_bf16 v[124:127], v[146:149], v[162:165], v[124:127]
	v_mfma_f32_16x16x32_bf16 v[120:123], v[154:157], v[162:165], v[120:123]
	v_mfma_f32_16x16x32_bf16 v[116:119], v[146:149], v[170:173], v[116:119]
	v_mfma_f32_16x16x32_bf16 v[108:111], v[154:157], v[170:173], v[108:111]
	v_mfma_f32_16x16x32_bf16 v[100:103], v[146:149], v[178:181], v[100:103]
	v_mfma_f32_16x16x32_bf16 v[92:95], v[154:157], v[178:181], v[92:95]
	v_mfma_f32_16x16x32_bf16 v[84:87], v[146:149], v[186:189], v[84:87]
	v_mfma_f32_16x16x32_bf16 v[76:79], v[154:157], v[186:189], v[76:79]
	v_mfma_f32_16x16x32_bf16 v[124:127], v[150:153], v[166:169], v[124:127]
	v_mfma_f32_16x16x32_bf16 v[120:123], v[158:161], v[166:169], v[120:123]
	v_mfma_f32_16x16x32_bf16 v[116:119], v[150:153], v[174:177], v[116:119]
	v_mfma_f32_16x16x32_bf16 v[108:111], v[158:161], v[174:177], v[108:111]
	v_mfma_f32_16x16x32_bf16 v[100:103], v[150:153], v[182:185], v[100:103]
	v_mfma_f32_16x16x32_bf16 v[92:95], v[158:161], v[182:185], v[92:95]
	v_mfma_f32_16x16x32_bf16 v[84:87], v[150:153], v[190:193], v[84:87]
	v_mfma_f32_16x16x32_bf16 v[76:79], v[158:161], v[190:193], v[76:79]
	s_setprio 0
	s_barrier
	s_add_i32 s26, 0, 0x1c000
	s_add_i32 s27, s59, s34
	v_add_u32_e32 v210, s26, v142
	s_add_u32 s0, s24, 0x80
	s_addc_u32 s1, s25, 0
	s_mov_b32 m0, s27
	ds_read_b128 v[194:197], v210
	ds_read_b128 v[202:205], v210 offset:1024
	ds_read_b128 v[206:209], v210 offset:2048
	ds_read_b128 v[210:213], v210 offset:3072
	global_load_lds_dwordx4 v130, s[0:1]
	s_add_i32 m0, s27, 0x2000
	s_nop 0
	global_load_lds_dwordx4 v134, s[0:1]
	s_barrier
	s_waitcnt lgkmcnt(0)
	s_setprio 1
	s_waitcnt lgkmcnt(0)
	v_mfma_f32_16x16x32_bf16 v[112:115], v[194:197], v[162:165], v[112:115]
	v_mfma_f32_16x16x32_bf16 v[104:107], v[206:209], v[162:165], v[104:107]
	v_mfma_f32_16x16x32_bf16 v[96:99], v[194:197], v[170:173], v[96:99]
	v_mfma_f32_16x16x32_bf16 v[88:91], v[206:209], v[170:173], v[88:91]
	v_mfma_f32_16x16x32_bf16 v[80:83], v[194:197], v[178:181], v[80:83]
	v_mfma_f32_16x16x32_bf16 v[72:75], v[206:209], v[178:181], v[72:75]
	v_mfma_f32_16x16x32_bf16 v[68:71], v[194:197], v[186:189], v[68:71]
	v_mfma_f32_16x16x32_bf16 v[64:67], v[206:209], v[186:189], v[64:67]
	v_mfma_f32_16x16x32_bf16 v[112:115], v[202:205], v[166:169], v[112:115]
	v_mfma_f32_16x16x32_bf16 v[104:107], v[210:213], v[166:169], v[104:107]
	v_mfma_f32_16x16x32_bf16 v[96:99], v[202:205], v[174:177], v[96:99]
	v_mfma_f32_16x16x32_bf16 v[88:91], v[210:213], v[174:177], v[88:91]
	v_mfma_f32_16x16x32_bf16 v[80:83], v[202:205], v[182:185], v[80:83]
	v_mfma_f32_16x16x32_bf16 v[72:75], v[210:213], v[182:185], v[72:75]
	v_mfma_f32_16x16x32_bf16 v[68:71], v[202:205], v[190:193], v[68:71]
	v_mfma_f32_16x16x32_bf16 v[64:67], v[210:213], v[190:193], v[64:67]
	s_setprio 0
	s_mov_b32 m0, s43
	s_mov_b64 s[0:1], 0x80
	v_lshl_add_u64 v[198:199], v[216:217], 0, s[0:1]
	s_barrier
	ds_read_b128 v[162:165], v144 offset:49152
	ds_read_b128 v[166:169], v144 offset:50176
	ds_read_b128 v[170:173], v144 offset:51200
	ds_read_b128 v[174:177], v144 offset:52224
	ds_read_b128 v[178:181], v144 offset:53248
	ds_read_b128 v[182:185], v144 offset:54272
	ds_read_b128 v[186:189], v144 offset:55296
	ds_read_b128 v[190:193], v144 offset:56320
	global_load_lds_dwordx4 v[198:199], off
	v_lshl_add_u64 v[198:199], v[218:219], 0, s[0:1]
	s_mov_b32 m0, s44
	s_nop 0
	global_load_lds_dwordx4 v[198:199], off
	s_barrier
	s_waitcnt lgkmcnt(0)
	s_setprio 1
	s_waitcnt lgkmcnt(0)
	v_mfma_f32_16x16x32_bf16 v[60:63], v[146:149], v[162:165], v[60:63]
	v_mfma_f32_16x16x32_bf16 v[56:59], v[154:157], v[162:165], v[56:59]
	v_mfma_f32_16x16x32_bf16 v[52:55], v[146:149], v[170:173], v[52:55]
	v_mfma_f32_16x16x32_bf16 v[44:47], v[154:157], v[170:173], v[44:47]
	v_mfma_f32_16x16x32_bf16 v[36:39], v[146:149], v[178:181], v[36:39]
	v_mfma_f32_16x16x32_bf16 v[28:31], v[154:157], v[178:181], v[28:31]
	v_mfma_f32_16x16x32_bf16 v[20:23], v[146:149], v[186:189], v[20:23]
	v_mfma_f32_16x16x32_bf16 v[12:15], v[154:157], v[186:189], v[12:15]
	v_mfma_f32_16x16x32_bf16 v[60:63], v[150:153], v[166:169], v[60:63]
	v_mfma_f32_16x16x32_bf16 v[56:59], v[158:161], v[166:169], v[56:59]
	v_mfma_f32_16x16x32_bf16 v[52:55], v[150:153], v[174:177], v[52:55]
	v_mfma_f32_16x16x32_bf16 v[44:47], v[158:161], v[174:177], v[44:47]
	v_mfma_f32_16x16x32_bf16 v[36:39], v[150:153], v[182:185], v[36:39]
	v_mfma_f32_16x16x32_bf16 v[28:31], v[158:161], v[182:185], v[28:31]
	v_mfma_f32_16x16x32_bf16 v[20:23], v[150:153], v[190:193], v[20:23]
	v_mfma_f32_16x16x32_bf16 v[12:15], v[158:161], v[190:193], v[12:15]
	s_setprio 0
	s_barrier
	s_add_u32 s24, s24, 0x40080
	s_addc_u32 s25, s25, 0
	s_add_i32 s26, s26, s34
	s_mov_b32 m0, s26
	s_nop 0
	global_load_lds_dwordx4 v130, s[24:25]
	s_add_i32 m0, s26, 0x2000
	s_nop 0
	global_load_lds_dwordx4 v134, s[24:25]
	s_waitcnt vmcnt(6)
	s_barrier
; __device__ __forceinline__ unsigned cvt_pk_bf16(float lo, float hi) { unsigned r; asm volatile("v_cvt_pk_bf16_f32 %0, %1, %2" : "=v"(r) : "v"(lo), "v"(hi)); return r; }
; #define PG8_MMA(ai, bj, At, Bt) do { __builtin_amdgcn_s_setprio(1); _Pragma("unroll") for (int m = 0; m < 4; ++m) _Pragma("unroll") for (int n = 0; n < 2; ++n) _Pragma("unroll") for (int k = 0; k < 2; ++k) \
;         acc[ai][bj][m][n] = __builtin_amdgcn_mfma_f32_16x16x32_bf16(Bt[n][k], At[m][k], acc[ai][bj][m][n], 0, 0, 0); __builtin_amdgcn_s_setprio(0); } while (0)
; #define PG8_WAIT_V(n) asm volatile("s_waitcnt vmcnt(" #n ")" ::: "memory")
; #define PG8_BAR __builtin_amdgcn_s_barrier()
; template <class Epi, class Sched>
; __device__ __forceinline__ void gemm_phase(LAS unsigned char* lds, const Gemm g, const Sched& S, const Epi& E) {
;     ...
;             PG8_WAIT_V(6); PG8_BAR; PG8_MMA(1, 1, At, B1); PG8_BAR;
;         }
;         E(acc, cur, wr, wc, fr, fq);
;         if (!has_next) break;
;     __device__ __forceinline__ void operator()(const AccT& acc, const Unit& u, int wr, int wc, int fr, int fq) const {
;         asm volatile("" : "+v"(fr), "+v"(fq));
;         const int rbase = u.pm * 256 + wr * 64 + fr;
;         const int tb = u.pn * 256 + wc * 32 + 8 * fq;
; #pragma unroll
;         for (int ai = 0; ai < 2; ++ai)
; #pragma unroll
;             for (int m = 0; m < 4; ++m) {
;                 const int r = rbase + ai * 128 + m * 16;
; #pragma unroll
;                 for (int bj = 0; bj < 2; ++bj) {
;                     const int t0 = tb + bj * 128;
;                     const f32x4 v0 = acc[ai][bj][m][0], v1 = acc[ai][bj][m][1];
;                     u32x4 w; w.x = cvt_pk_bf16(v0[0], v0[1]); w.y = cvt_pk_bf16(v0[2], v0[3]); w.z = cvt_pk_bf16(v1[0], v1[1]); w.w = cvt_pk_bf16(v1[2], v1[3]);
;                     *(u32x4*)(VT + (size_t)r * NT + t0) = w;
;                 }
;             }
;     }
	s_setprio 1
	v_mfma_f32_16x16x32_bf16 v[48:51], v[194:197], v[162:165], v[48:51]
	v_mfma_f32_16x16x32_bf16 v[40:43], v[206:209], v[162:165], v[40:43]
	v_mfma_f32_16x16x32_bf16 v[32:35], v[194:197], v[170:173], v[32:35]
	v_mfma_f32_16x16x32_bf16 v[24:27], v[206:209], v[170:173], v[24:27]
	v_mfma_f32_16x16x32_bf16 v[16:19], v[194:197], v[178:181], v[16:19]
	v_mfma_f32_16x16x32_bf16 v[8:11], v[206:209], v[178:181], v[8:11]
	v_mfma_f32_16x16x32_bf16 v[4:7], v[194:197], v[186:189], v[4:7]
	v_mfma_f32_16x16x32_bf16 v[0:3], v[206:209], v[186:189], v[0:3]
	v_mfma_f32_16x16x32_bf16 v[48:51], v[202:205], v[166:169], v[48:51]
	v_mfma_f32_16x16x32_bf16 v[40:43], v[210:213], v[166:169], v[40:43]
	v_mfma_f32_16x16x32_bf16 v[32:35], v[202:205], v[174:177], v[32:35]
	v_mfma_f32_16x16x32_bf16 v[24:27], v[210:213], v[174:177], v[24:27]
	v_mfma_f32_16x16x32_bf16 v[16:19], v[202:205], v[182:185], v[16:19]
	v_mfma_f32_16x16x32_bf16 v[8:11], v[210:213], v[182:185], v[8:11]
	v_mfma_f32_16x16x32_bf16 v[4:7], v[202:205], v[190:193], v[4:7]
	v_mfma_f32_16x16x32_bf16 v[0:3], v[210:213], v[190:193], v[0:3]
	s_setprio 0
	s_add_i32 s58, s58, 2
	s_add_u32 s22, s22, 0x100
	s_addc_u32 s23, s23, 0
	s_add_u32 s56, s56, 0x100
	s_addc_u32 s57, s57, 0
	s_cmp_gt_u32 s58, 13
	s_barrier
	s_cbranch_scc0 .LBB0_713
	v_mov_b32_e32 v146, v140
	v_mov_b32_e32 v147, v141
	s_lshl_b32 s13, s20, 8
	s_add_i32 s13, s13, s41
	v_add_u32_e32 v146, s13, v146
	s_lshl_b32 s13, s53, 8
	s_or_b32 s13, s13, s42
	v_lshl_add_u32 v148, v147, 3, s13
	v_ashrrev_i32_e32 v147, 31, v146
	v_cvt_pk_bf16_f32 v124, v124, v125
	v_cvt_pk_bf16_f32 v125, v126, v127
	v_cvt_pk_bf16_f32 v126, v120, v121
	v_lshlrev_b64 v[120:121], 14, v[146:147]
	v_lshl_add_u64 v[120:121], s[62:63], 0, v[120:121]
	v_ashrrev_i32_e32 v149, 31, v148
	v_lshl_add_u64 v[120:121], v[148:149], 1, v[120:121]
	s_mov_b32 s13, 0x40000
	v_cvt_pk_bf16_f32 v127, v122, v123
	global_store_dwordx4 v[120:121], v[124:127], off
	v_cvt_pk_bf16_f32 v112, v112, v113
	v_cvt_pk_bf16_f32 v113, v114, v115
	v_cvt_pk_bf16_f32 v114, v104, v105
	v_cvt_pk_bf16_f32 v115, v106, v107
	global_store_dwordx4 v[120:121], v[112:115], off offset:256
	v_cvt_pk_bf16_f32 v104, v116, v117
	v_cvt_pk_bf16_f32 v105, v118, v119
	v_cvt_pk_bf16_f32 v106, v108, v109
	v_cvt_pk_bf16_f32 v107, v110, v111
	s_mov_b64 s[22:23], 0x40000
	v_add_co_u32_e32 v110, vcc, s13, v120
	v_lshl_add_u64 v[108:109], v[120:121], 0, s[22:23]
	s_nop 0
	v_addc_co_u32_e32 v111, vcc, 0, v121, vcc
	s_mov_b32 s13, 0x80000
	global_store_dwordx4 v[110:111], v[104:107], off
	v_cvt_pk_bf16_f32 v96, v96, v97
	v_cvt_pk_bf16_f32 v97, v98, v99
	v_cvt_pk_bf16_f32 v98, v88, v89
	v_cvt_pk_bf16_f32 v99, v90, v91
	global_store_dwordx4 v[108:109], v[96:99], off offset:256
	v_cvt_pk_bf16_f32 v88, v100, v101
	v_cvt_pk_bf16_f32 v89, v102, v103
	v_cvt_pk_bf16_f32 v90, v92, v93
	v_cvt_pk_bf16_f32 v91, v94, v95
	s_mov_b64 s[22:23], 0x80000
	v_add_co_u32_e32 v94, vcc, s13, v120
	v_lshl_add_u64 v[92:93], v[120:121], 0, s[22:23]
	s_nop 0
	v_addc_co_u32_e32 v95, vcc, 0, v121, vcc
	global_store_dwordx4 v[94:95], v[88:91], off
	v_cvt_pk_bf16_f32 v80, v80, v81
	v_cvt_pk_bf16_f32 v81, v82, v83
	v_cvt_pk_bf16_f32 v82, v72, v73
	v_cvt_pk_bf16_f32 v83, v74, v75
	global_store_dwordx4 v[92:93], v[80:83], off offset:256
	v_cvt_pk_bf16_f32 v72, v84, v85
	v_cvt_pk_bf16_f32 v73, v86, v87
	v_cvt_pk_bf16_f32 v74, v76, v77
	v_cvt_pk_bf16_f32 v75, v78, v79
	s_mov_b64 s[22:23], 0xc0000
	v_add_co_u32_e32 v78, vcc, s48, v120
	v_lshl_add_u64 v[76:77], v[120:121], 0, s[22:23]
	s_nop 0
	v_addc_co_u32_e32 v79, vcc, 0, v121, vcc
	global_store_dwordx4 v[78:79], v[72:75], off
	v_cvt_pk_bf16_f32 v68, v68, v69
	v_cvt_pk_bf16_f32 v69, v70, v71
	v_cvt_pk_bf16_f32 v70, v64, v65
	v_cvt_pk_bf16_f32 v71, v66, v67
	global_store_dwordx4 v[76:77], v[68:71], off offset:256
	v_cvt_pk_bf16_f32 v60, v60, v61
	v_cvt_pk_bf16_f32 v61, v62, v63
	v_cvt_pk_bf16_f32 v62, v56, v57
	v_cvt_pk_bf16_f32 v63, v58, v59
	v_add_co_u32_e32 v58, vcc, s49, v120
	v_lshl_add_u64 v[56:57], v[120:121], 0, s[2:3]
	s_nop 0
	v_addc_co_u32_e32 v59, vcc, 0, v121, vcc
	global_store_dwordx4 v[58:59], v[60:63], off
	v_cvt_pk_bf16_f32 v48, v48, v49
	v_cvt_pk_bf16_f32 v49, v50, v51
	v_cvt_pk_bf16_f32 v50, v40, v41
	v_cvt_pk_bf16_f32 v51, v42, v43
	global_store_dwordx4 v[56:57], v[48:51], off offset:256
	v_cvt_pk_bf16_f32 v40, v52, v53
	v_cvt_pk_bf16_f32 v41, v54, v55
	v_cvt_pk_bf16_f32 v42, v44, v45
	v_cvt_pk_bf16_f32 v43, v46, v47
	v_add_co_u32_e32 v46, vcc, s50, v120
	v_lshl_add_u64 v[44:45], v[120:121], 0, s[4:5]
	s_nop 0
	v_addc_co_u32_e32 v47, vcc, 0, v121, vcc
	global_store_dwordx4 v[46:47], v[40:43], off
	v_cvt_pk_bf16_f32 v32, v32, v33
	v_cvt_pk_bf16_f32 v33, v34, v35
	v_cvt_pk_bf16_f32 v34, v24, v25
	v_cvt_pk_bf16_f32 v35, v26, v27
	global_store_dwordx4 v[44:45], v[32:35], off offset:256
	v_cvt_pk_bf16_f32 v24, v36, v37
	v_cvt_pk_bf16_f32 v25, v38, v39
	v_cvt_pk_bf16_f32 v26, v28, v29
	v_cvt_pk_bf16_f32 v27, v30, v31
	v_add_co_u32_e32 v30, vcc, s51, v120
	v_lshl_add_u64 v[28:29], v[120:121], 0, s[6:7]
	s_nop 0
	v_addc_co_u32_e32 v31, vcc, 0, v121, vcc
	global_store_dwordx4 v[30:31], v[24:27], off
	v_cvt_pk_bf16_f32 v16, v16, v17
	v_cvt_pk_bf16_f32 v17, v18, v19
	v_cvt_pk_bf16_f32 v18, v8, v9
	v_cvt_pk_bf16_f32 v19, v10, v11
	global_store_dwordx4 v[28:29], v[16:19], off offset:256
	v_cvt_pk_bf16_f32 v8, v20, v21
	v_cvt_pk_bf16_f32 v9, v22, v23
	v_cvt_pk_bf16_f32 v10, v12, v13
	v_cvt_pk_bf16_f32 v11, v14, v15
	v_add_co_u32_e32 v14, vcc, s52, v120
	v_lshl_add_u64 v[12:13], v[120:121], 0, s[8:9]
	s_nop 0
	v_addc_co_u32_e32 v15, vcc, 0, v121, vcc
	s_and_b64 vcc, exec, s[10:11]
	s_mov_b32 s53, s12
	s_mov_b32 s20, s14
	s_mov_b64 s[24:25], s[18:19]
	s_mov_b64 s[22:23], s[16:17]
	global_store_dwordx4 v[14:15], v[8:11], off
	v_cvt_pk_bf16_f32 v4, v4, v5
	v_cvt_pk_bf16_f32 v5, v6, v7
	v_cvt_pk_bf16_f32 v6, v0, v1
	v_cvt_pk_bf16_f32 v7, v2, v3
	global_store_dwordx4 v[12:13], v[4:7], off offset:256
	s_cbranch_vccz .LBB0_706
	s_waitcnt vmcnt(0)
	s_cmpk_gt_u32 s31, 0xff
	s_cbranch_scc1 .LBB0_717
	s_barrier

; #define PG8_STAGE(bufoff, gbase, voff) do { _Pragma("unroll") for (int _i = 0; _i < 2; ++_i) \
;         __builtin_amdgcn_global_load_lds((const unsigned*)((const char*)(gbase) + (voff)[_i]), (LAS unsigned*)(lds + (bufoff) + ldsw + _i * 8192), 16, 0, 0); } while (0)
; #define PG8_LDA(dst, b, h) do { _Pragma("unroll") for (int m = 0; m < 4; ++m) _Pragma("unroll") for (int k = 0; k < 2; ++k) dst[m][k] = *(const LAS bf16x8*)(lds + PG8_SA(b, h) + aoff + m * 2048 + k * 1024); } while (0)
; #define PG8_LDB(dst, b, h) do { _Pragma("unroll") for (int n = 0; n < 2; ++n) _Pragma("unroll") for (int k = 0; k < 2; ++k) dst[n][k] = *(const LAS bf16x8*)(lds + PG8_SB(b, h) + boff + n * 2048 + k * 1024); } while (0)
; #define PG8_WAIT_V(n) asm volatile("s_waitcnt vmcnt(" #n ")" ::: "memory")
; #define PG8_WAIT_L(n) asm volatile("s_waitcnt lgkmcnt(" #n ")" ::: "memory")
; #define PG8_BAR __builtin_amdgcn_s_barrier()
; #define PG8_SCHED __builtin_amdgcn_sched_barrier(0)
; template <class Epi, class Sched>
; __device__ __forceinline__ void gemm_phase(LAS unsigned char* lds, const Gemm g, const Sched& S, const Epi& E) {
;     ...
;     for (;;) {
;         const bool has_next = S.next(ui + 1, nxt);
;         const char* nA = has_next ? (const char*)g.A + (size_t)nxt.pm * tstep : cA; const char* nB = has_next ? (const char*)g.Bt + (size_t)nxt.pn * tstep : cB;
;         for (int t = 0; t < nt; t += 2) {
;             const bool last = (t == nt - 2);
;             const char* a1 = cA + (size_t)(t + 1) * kstep;
;             const char* a2 = last ? nA : cA + (size_t)(t + 2) * kstep; const char* b2 = last ? nB : cB + (size_t)(t + 2) * kstep;
;             const char* a3 = a2 + kstep; const char* b3 = b2 + kstep;
;             PG8_LDB(B0, 0, 0); PG8_SCHED; PG8_LDA(At, 0, 0); PG8_STAGE(PG8_SA(1, 1), a1 + hstep, voffA);
;             PG8_WAIT_L(8); PG8_BAR; PG8_WAIT_L(0); PG8_MMA(0, 0, At, B0); PG8_BAR; PG8_SCHED;
;             PG8_LDB(B1, 0, 1); PG8_STAGE(PG8_SB(0, 0), b2, voffB);
;             PG8_BAR; PG8_WAIT_L(0); PG8_MMA(0, 1, At, B1); PG8_BAR;
;             PG8_LDA(At, 0, 1); PG8_STAGE(PG8_SA(0, 0), a2, voffA);
;             PG8_BAR; PG8_WAIT_L(0); PG8_MMA(1, 0, At, B0); PG8_BAR; PG8_SCHED;
;             PG8_STAGE(PG8_SB(0, 1), b2 + hstep, voffB);
;             PG8_WAIT_V(6); PG8_BAR; PG8_MMA(1, 1, At, B1); PG8_BAR;
.LBB0_825:
	s_ashr_i32 s7, s6, 31
	v_cmp_lt_i64_e32 vcc, s[8:9], v[156:157]
	s_lshl_b64 s[8:9], s[6:7], 20
	s_add_u32 s8, s22, s8
	s_addc_u32 s9, s23, s9
	s_and_b64 s[10:11], vcc, exec
	s_cselect_b32 s7, s9, s15
	s_cselect_b32 s39, s8, s14
	s_ashr_i32 s5, s4, 31
	s_lshl_b64 s[10:11], s[4:5], 20
	s_add_u32 s10, s50, s10
	s_addc_u32 s11, s51, s11
	s_and_b64 s[18:19], vcc, exec
	s_cselect_b32 s5, s11, s17
	s_cselect_b32 s40, s10, s16
	s_add_u32 s14, s14, 0x80080
	s_addc_u32 s15, s15, 0
	s_add_u32 s41, s16, 0x100
	s_addc_u32 s42, s17, 0
	s_mov_b32 s43, -2
	ds_read_b128 v[128:131], v168
	ds_read_b128 v[132:135], v168 offset:1024
	ds_read_b128 v[136:139], v168 offset:2048
	ds_read_b128 v[140:143], v168 offset:3072
	s_add_u32 s16, s14, 0xfff80080
	s_addc_u32 s17, s15, -1
	s_cmp_eq_u32 s43, 28
	s_cselect_b32 s19, s7, s17
	s_cselect_b32 s18, s39, s16
	s_cselect_b32 s17, s5, s42
	s_cselect_b32 s16, s40, s41
	s_add_i32 m0, s13, 0xc000
	ds_read_b128 v[162:165], v169
	ds_read_b128 v[172:175], v169 offset:1024
	ds_read_b128 v[176:179], v169 offset:2048
	ds_read_b128 v[180:183], v169 offset:3072
	ds_read_b128 v[184:187], v169 offset:4096
	ds_read_b128 v[188:191], v169 offset:5120
	ds_read_b128 v[192:195], v169 offset:6144
	ds_read_b128 v[196:199], v169 offset:7168
	global_load_lds_dwordx4 v152, s[14:15]
	s_add_i32 m0, s13, 0xe000
	s_nop 0
	global_load_lds_dwordx4 v154, s[14:15]
	s_waitcnt lgkmcnt(8)
	s_barrier
	s_waitcnt lgkmcnt(0)
	s_setprio 1
	s_waitcnt lgkmcnt(0)
	v_mfma_f32_16x16x32_bf16 v[124:127], v[128:131], v[162:165], 0
	v_mfma_f32_16x16x32_bf16 v[120:123], v[136:139], v[162:165], 0
	v_mfma_f32_16x16x32_bf16 v[116:119], v[128:131], v[176:179], 0
	v_mfma_f32_16x16x32_bf16 v[112:115], v[136:139], v[176:179], 0
	v_mfma_f32_16x16x32_bf16 v[108:111], v[128:131], v[184:187], 0
	v_mfma_f32_16x16x32_bf16 v[100:103], v[136:139], v[184:187], 0
	v_mfma_f32_16x16x32_bf16 v[76:79], v[128:131], v[192:195], 0
	v_mfma_f32_16x16x32_bf16 v[72:75], v[136:139], v[192:195], 0
	v_mfma_f32_16x16x32_bf16 v[124:127], v[132:135], v[172:175], v[124:127]
	v_mfma_f32_16x16x32_bf16 v[120:123], v[140:143], v[172:175], v[120:123]
	v_mfma_f32_16x16x32_bf16 v[116:119], v[132:135], v[180:183], v[116:119]
	v_mfma_f32_16x16x32_bf16 v[112:115], v[140:143], v[180:183], v[112:115]
	v_mfma_f32_16x16x32_bf16 v[108:111], v[132:135], v[188:191], v[108:111]
	v_mfma_f32_16x16x32_bf16 v[100:103], v[140:143], v[188:191], v[100:103]
	v_mfma_f32_16x16x32_bf16 v[76:79], v[132:135], v[196:199], v[76:79]
	v_mfma_f32_16x16x32_bf16 v[72:75], v[140:143], v[196:199], v[72:75]
	s_setprio 0
	s_barrier
	s_add_i32 s44, s35, s24
	s_mov_b32 m0, s44
	ds_read_b128 v[202:205], v170
	ds_read_b128 v[206:209], v170 offset:1024
	ds_read_b128 v[210:213], v170 offset:2048
	ds_read_b128 v[214:217], v170 offset:3072
	global_load_lds_dwordx4 v146, s[16:17]
	s_add_i32 m0, s44, 0x2000
	s_nop 0
	global_load_lds_dwordx4 v150, s[16:17]
	s_barrier
	s_waitcnt lgkmcnt(0)
	s_setprio 1
	s_waitcnt lgkmcnt(0)
	v_mfma_f32_16x16x32_bf16 v[104:107], v[202:205], v[162:165], 0
	v_mfma_f32_16x16x32_bf16 v[96:99], v[210:213], v[162:165], 0
	v_mfma_f32_16x16x32_bf16 v[92:95], v[202:205], v[176:179], 0
	v_mfma_f32_16x16x32_bf16 v[88:91], v[210:213], v[176:179], 0
	v_mfma_f32_16x16x32_bf16 v[84:87], v[202:205], v[184:187], 0
	v_mfma_f32_16x16x32_bf16 v[80:83], v[210:213], v[184:187], 0
	v_mfma_f32_16x16x32_bf16 v[68:71], v[202:205], v[192:195], 0
	v_mfma_f32_16x16x32_bf16 v[64:67], v[210:213], v[192:195], 0
	v_mfma_f32_16x16x32_bf16 v[104:107], v[206:209], v[172:175], v[104:107]
	v_mfma_f32_16x16x32_bf16 v[96:99], v[214:217], v[172:175], v[96:99]
	v_mfma_f32_16x16x32_bf16 v[92:95], v[206:209], v[180:183], v[92:95]
	v_mfma_f32_16x16x32_bf16 v[88:91], v[214:217], v[180:183], v[88:91]
	v_mfma_f32_16x16x32_bf16 v[84:87], v[206:209], v[188:191], v[84:87]
	v_mfma_f32_16x16x32_bf16 v[80:83], v[214:217], v[188:191], v[80:83]
	v_mfma_f32_16x16x32_bf16 v[68:71], v[206:209], v[196:199], v[68:71]
	v_mfma_f32_16x16x32_bf16 v[64:67], v[214:217], v[196:199], v[64:67]
	s_setprio 0
	s_mov_b32 m0, s13
	v_lshl_add_u64 v[222:223], s[18:19], 0, v[144:145]
	s_barrier
	ds_read_b128 v[162:165], v169 offset:16384
	ds_read_b128 v[172:175], v169 offset:17408
	ds_read_b128 v[176:179], v169 offset:18432
	ds_read_b128 v[180:183], v169 offset:19456
	ds_read_b128 v[184:187], v169 offset:20480
	ds_read_b128 v[188:191], v169 offset:21504
	ds_read_b128 v[192:195], v169 offset:22528
	ds_read_b128 v[196:199], v169 offset:23552
	global_load_lds_dwordx4 v144, s[18:19]
	v_lshl_add_u64 v[224:225], s[18:19], 0, v[148:149]
	s_mov_b32 m0, s25
	s_nop 0
	global_load_lds_dwordx4 v148, s[18:19]
	s_barrier
	s_waitcnt lgkmcnt(0)
	s_setprio 1
	s_waitcnt lgkmcnt(0)
	v_mfma_f32_16x16x32_bf16 v[60:63], v[128:131], v[162:165], 0
	v_mfma_f32_16x16x32_bf16 v[56:59], v[136:139], v[162:165], 0
	v_mfma_f32_16x16x32_bf16 v[48:51], v[128:131], v[176:179], 0
	v_mfma_f32_16x16x32_bf16 v[40:43], v[136:139], v[176:179], 0
	v_mfma_f32_16x16x32_bf16 v[32:35], v[128:131], v[184:187], 0
	v_mfma_f32_16x16x32_bf16 v[24:27], v[136:139], v[184:187], 0
	v_mfma_f32_16x16x32_bf16 v[16:19], v[128:131], v[192:195], 0
	v_mfma_f32_16x16x32_bf16 v[8:11], v[136:139], v[192:195], 0
	v_mfma_f32_16x16x32_bf16 v[60:63], v[132:135], v[172:175], v[60:63]
	v_mfma_f32_16x16x32_bf16 v[56:59], v[140:143], v[172:175], v[56:59]
	v_mfma_f32_16x16x32_bf16 v[48:51], v[132:135], v[180:183], v[48:51]
	v_mfma_f32_16x16x32_bf16 v[40:43], v[140:143], v[180:183], v[40:43]
	v_mfma_f32_16x16x32_bf16 v[32:35], v[132:135], v[188:191], v[32:35]
	v_mfma_f32_16x16x32_bf16 v[24:27], v[140:143], v[188:191], v[24:27]
	v_mfma_f32_16x16x32_bf16 v[16:19], v[132:135], v[196:199], v[16:19]
	v_mfma_f32_16x16x32_bf16 v[8:11], v[140:143], v[196:199], v[8:11]
	s_setprio 0
	s_barrier
; #define PG8_STAGE(bufoff, gbase, voff) do { _Pragma("unroll") for (int _i = 0; _i < 2; ++_i) \
;         __builtin_amdgcn_global_load_lds((const unsigned*)((const char*)(gbase) + (voff)[_i]), (LAS unsigned*)(lds + (bufoff) + ldsw + _i * 8192), 16, 0, 0); } while (0)
; #define PG8_LDA(dst, b, h) do { _Pragma("unroll") for (int m = 0; m < 4; ++m) _Pragma("unroll") for (int k = 0; k < 2; ++k) dst[m][k] = *(const LAS bf16x8*)(lds + PG8_SA(b, h) + aoff + m * 2048 + k * 1024); } while (0)
; #define PG8_LDB(dst, b, h) do { _Pragma("unroll") for (int n = 0; n < 2; ++n) _Pragma("unroll") for (int k = 0; k < 2; ++k) dst[n][k] = *(const LAS bf16x8*)(lds + PG8_SB(b, h) + boff + n * 2048 + k * 1024); } while (0)
; #define PG8_MMA(ai, bj, At, Bt) do { __builtin_amdgcn_s_setprio(1); _Pragma("unroll") for (int m = 0; m < 4; ++m) _Pragma("unroll") for (int n = 0; n < 2; ++n) _Pragma("unroll") for (int k = 0; k < 2; ++k) \
;         acc[ai][bj][m][n] = __builtin_amdgcn_mfma_f32_16x16x32_bf16(Bt[n][k], At[m][k], acc[ai][bj][m][n], 0, 0, 0); __builtin_amdgcn_s_setprio(0); } while (0)
; #define PG8_WAIT_V(n) asm volatile("s_waitcnt vmcnt(" #n ")" ::: "memory")
; #define PG8_WAIT_L(n) asm volatile("s_waitcnt lgkmcnt(" #n ")" ::: "memory")
; #define PG8_BAR __builtin_amdgcn_s_barrier()
; #define PG8_SCHED __builtin_amdgcn_sched_barrier(0)
; template <class Epi, class Sched>
; __device__ __forceinline__ void gemm_phase(LAS unsigned char* lds, const Gemm g, const Sched& S, const Epi& E) {
;     ...
;             PG8_STAGE(PG8_SB(0, 1), b2 + hstep, voffB);
;             PG8_WAIT_V(6); PG8_BAR; PG8_MMA(1, 1, At, B1); PG8_BAR;
;             PG8_LDB(B0, 1, 0); PG8_SCHED; PG8_LDA(At, 1, 0); PG8_STAGE(PG8_SA(0, 1), a2 + hstep, voffA);
;             PG8_WAIT_L(8); PG8_BAR; PG8_WAIT_L(0); PG8_MMA(0, 0, At, B0); PG8_BAR; PG8_SCHED;
;             PG8_LDB(B1, 1, 1); PG8_STAGE(PG8_SB(1, 0), b3, voffB);
;             PG8_BAR; PG8_WAIT_L(0); PG8_MMA(0, 1, At, B1); PG8_BAR;
;             PG8_LDA(At, 1, 1); PG8_STAGE(PG8_SA(1, 0), a3, voffA);
;             PG8_BAR; PG8_WAIT_L(0); PG8_MMA(1, 0, At, B0); PG8_BAR; PG8_SCHED;
	s_add_u32 s44, s16, 0x80000
	s_addc_u32 s45, s17, 0
	s_add_i32 s46, s36, s24
	s_mov_b32 m0, s46
	s_nop 0
	global_load_lds_dwordx4 v146, s[44:45]
	s_add_i32 m0, s46, 0x2000
	s_nop 0
	global_load_lds_dwordx4 v150, s[44:45]
	s_waitcnt vmcnt(6)
	s_barrier
	s_setprio 1
	v_mfma_f32_16x16x32_bf16 v[52:55], v[202:205], v[162:165], 0
	v_mfma_f32_16x16x32_bf16 v[44:47], v[210:213], v[162:165], 0
	v_mfma_f32_16x16x32_bf16 v[36:39], v[202:205], v[176:179], 0
	v_mfma_f32_16x16x32_bf16 v[28:31], v[210:213], v[176:179], 0
	v_mfma_f32_16x16x32_bf16 v[20:23], v[202:205], v[184:187], 0
	v_mfma_f32_16x16x32_bf16 v[12:15], v[210:213], v[184:187], 0
	v_mfma_f32_16x16x32_bf16 v[4:7], v[202:205], v[192:195], 0
	v_mfma_f32_16x16x32_bf16 v[0:3], v[210:213], v[192:195], 0
	v_mfma_f32_16x16x32_bf16 v[52:55], v[206:209], v[172:175], v[52:55]
	v_mfma_f32_16x16x32_bf16 v[44:47], v[214:217], v[172:175], v[44:47]
	v_mfma_f32_16x16x32_bf16 v[36:39], v[206:209], v[180:183], v[36:39]
	v_mfma_f32_16x16x32_bf16 v[28:31], v[214:217], v[180:183], v[28:31]
	v_mfma_f32_16x16x32_bf16 v[20:23], v[206:209], v[188:191], v[20:23]
	v_mfma_f32_16x16x32_bf16 v[12:15], v[214:217], v[188:191], v[12:15]
	v_mfma_f32_16x16x32_bf16 v[4:7], v[206:209], v[196:199], v[4:7]
	v_mfma_f32_16x16x32_bf16 v[0:3], v[214:217], v[196:199], v[0:3]
	s_setprio 0
	s_add_i32 s44, 0, 0x18000
	v_add_u32_e32 v140, s44, v167
	s_barrier
	ds_read_b128 v[128:131], v140
	ds_read_b128 v[132:135], v140 offset:1024
	ds_read_b128 v[136:139], v140 offset:2048
	ds_read_b128 v[140:143], v140 offset:3072
	s_add_u32 s18, s18, 0x80000
	s_addc_u32 s19, s19, 0
	s_mov_b32 m0, s26
	ds_read_b128 v[162:165], v169 offset:32768
	ds_read_b128 v[172:175], v169 offset:33792
	ds_read_b128 v[176:179], v169 offset:34816
	ds_read_b128 v[180:183], v169 offset:35840
	ds_read_b128 v[184:187], v169 offset:36864
	ds_read_b128 v[188:191], v169 offset:37888
	ds_read_b128 v[192:195], v169 offset:38912
	ds_read_b128 v[196:199], v169 offset:39936
	global_load_lds_dwordx4 v144, s[18:19]
	s_mov_b32 m0, s27
	s_nop 0
	global_load_lds_dwordx4 v148, s[18:19]
	s_waitcnt lgkmcnt(8)
	s_barrier
	s_waitcnt lgkmcnt(0)
	s_setprio 1
	s_waitcnt lgkmcnt(0)
	v_mfma_f32_16x16x32_bf16 v[124:127], v[128:131], v[162:165], v[124:127]
	v_mfma_f32_16x16x32_bf16 v[120:123], v[136:139], v[162:165], v[120:123]
	v_mfma_f32_16x16x32_bf16 v[116:119], v[128:131], v[176:179], v[116:119]
	v_mfma_f32_16x16x32_bf16 v[112:115], v[136:139], v[176:179], v[112:115]
	v_mfma_f32_16x16x32_bf16 v[108:111], v[128:131], v[184:187], v[108:111]
	v_mfma_f32_16x16x32_bf16 v[100:103], v[136:139], v[184:187], v[100:103]
	v_mfma_f32_16x16x32_bf16 v[76:79], v[128:131], v[192:195], v[76:79]
	v_mfma_f32_16x16x32_bf16 v[72:75], v[136:139], v[192:195], v[72:75]
	v_mfma_f32_16x16x32_bf16 v[124:127], v[132:135], v[172:175], v[124:127]
	v_mfma_f32_16x16x32_bf16 v[120:123], v[140:143], v[172:175], v[120:123]
	v_mfma_f32_16x16x32_bf16 v[116:119], v[132:135], v[180:183], v[116:119]
	v_mfma_f32_16x16x32_bf16 v[112:115], v[140:143], v[180:183], v[112:115]
	v_mfma_f32_16x16x32_bf16 v[108:111], v[132:135], v[188:191], v[108:111]
	v_mfma_f32_16x16x32_bf16 v[100:103], v[140:143], v[188:191], v[100:103]
	v_mfma_f32_16x16x32_bf16 v[76:79], v[132:135], v[196:199], v[76:79]
	v_mfma_f32_16x16x32_bf16 v[72:75], v[140:143], v[196:199], v[72:75]
	s_setprio 0
	s_barrier
	s_add_i32 s18, 0, 0x1c000
	s_add_i32 s19, s44, s24
	v_add_u32_e32 v160, s18, v167
	s_add_u32 s0, s16, 0x80
	s_addc_u32 s1, s17, 0
	s_mov_b32 m0, s19
	ds_read_b128 v[202:205], v160
	ds_read_b128 v[206:209], v160 offset:1024
	ds_read_b128 v[210:213], v160 offset:2048
	ds_read_b128 v[214:217], v160 offset:3072
	global_load_lds_dwordx4 v146, s[0:1]
	s_add_i32 m0, s19, 0x2000
	s_nop 0
	global_load_lds_dwordx4 v150, s[0:1]
	s_barrier
	s_waitcnt lgkmcnt(0)
	s_setprio 1
	s_waitcnt lgkmcnt(0)
	v_mfma_f32_16x16x32_bf16 v[104:107], v[202:205], v[162:165], v[104:107]
	v_mfma_f32_16x16x32_bf16 v[96:99], v[210:213], v[162:165], v[96:99]
	v_mfma_f32_16x16x32_bf16 v[92:95], v[202:205], v[176:179], v[92:95]
	v_mfma_f32_16x16x32_bf16 v[88:91], v[210:213], v[176:179], v[88:91]
	v_mfma_f32_16x16x32_bf16 v[84:87], v[202:205], v[184:187], v[84:87]
	v_mfma_f32_16x16x32_bf16 v[80:83], v[210:213], v[184:187], v[80:83]
	v_mfma_f32_16x16x32_bf16 v[68:71], v[202:205], v[192:195], v[68:71]
	v_mfma_f32_16x16x32_bf16 v[64:67], v[210:213], v[192:195], v[64:67]
	v_mfma_f32_16x16x32_bf16 v[104:107], v[206:209], v[172:175], v[104:107]
	v_mfma_f32_16x16x32_bf16 v[96:99], v[214:217], v[172:175], v[96:99]
	v_mfma_f32_16x16x32_bf16 v[92:95], v[206:209], v[180:183], v[92:95]
	v_mfma_f32_16x16x32_bf16 v[88:91], v[214:217], v[180:183], v[88:91]
	v_mfma_f32_16x16x32_bf16 v[84:87], v[206:209], v[188:191], v[84:87]
	v_mfma_f32_16x16x32_bf16 v[80:83], v[214:217], v[188:191], v[80:83]
	v_mfma_f32_16x16x32_bf16 v[68:71], v[206:209], v[196:199], v[68:71]
	v_mfma_f32_16x16x32_bf16 v[64:67], v[214:217], v[196:199], v[64:67]
	s_setprio 0
	s_mov_b32 m0, s31
	s_mov_b64 s[0:1], 0x80
	v_lshl_add_u64 v[218:219], v[222:223], 0, s[0:1]
	s_barrier
	ds_read_b128 v[162:165], v169 offset:49152
	ds_read_b128 v[172:175], v169 offset:50176
	ds_read_b128 v[176:179], v169 offset:51200
	ds_read_b128 v[180:183], v169 offset:52224
	ds_read_b128 v[184:187], v169 offset:53248
	ds_read_b128 v[188:191], v169 offset:54272
	ds_read_b128 v[192:195], v169 offset:55296
	ds_read_b128 v[196:199], v169 offset:56320
	global_load_lds_dwordx4 v[218:219], off
	v_lshl_add_u64 v[218:219], v[224:225], 0, s[0:1]
	s_mov_b32 m0, s33
	s_nop 0
	global_load_lds_dwordx4 v[218:219], off
	s_barrier
; #define PG8_STAGE(bufoff, gbase, voff) do { _Pragma("unroll") for (int _i = 0; _i < 2; ++_i) \
;         __builtin_amdgcn_global_load_lds((const unsigned*)((const char*)(gbase) + (voff)[_i]), (LAS unsigned*)(lds + (bufoff) + ldsw + _i * 8192), 16, 0, 0); } while (0)
; #define PG8_LDA(dst, b, h) do { _Pragma("unroll") for (int m = 0; m < 4; ++m) _Pragma("unroll") for (int k = 0; k < 2; ++k) dst[m][k] = *(const LAS bf16x8*)(lds + PG8_SA(b, h) + aoff + m * 2048 + k * 1024); } while (0)
; #define PG8_WAIT_V(n) asm volatile("s_waitcnt vmcnt(" #n ")" ::: "memory")
; #define PG8_WAIT_L(n) asm volatile("s_waitcnt lgkmcnt(" #n ")" ::: "memory")
; template <class Epi, class Sched>
; __device__ __forceinline__ void gemm_phase(LAS unsigned char* lds, const Gemm g, const Sched& S, const Epi& E) {
;     ...
;         for (int t = 0; t < nt; t += 2) {
;             const bool last = (t == nt - 2);
;             const char* a1 = cA + (size_t)(t + 1) * kstep;
;             const char* a2 = last ? nA : cA + (size_t)(t + 2) * kstep; const char* b2 = last ? nB : cB + (size_t)(t + 2) * kstep;
;             const char* a3 = a2 + kstep; const char* b3 = b2 + kstep;
;             PG8_LDB(B0, 0, 0); PG8_SCHED; PG8_LDA(At, 0, 0); PG8_STAGE(PG8_SA(1, 1), a1 + hstep, voffA);
;             PG8_WAIT_L(8); PG8_BAR; PG8_WAIT_L(0); PG8_MMA(0, 0, At, B0); PG8_BAR; PG8_SCHED;
;             PG8_LDB(B1, 0, 1); PG8_STAGE(PG8_SB(0, 0), b2, voffB);
;             PG8_BAR; PG8_WAIT_L(0); PG8_MMA(0, 1, At, B1); PG8_BAR;
;             PG8_LDA(At, 0, 1); PG8_STAGE(PG8_SA(0, 0), a2, voffA);
;             PG8_BAR; PG8_WAIT_L(0); PG8_MMA(1, 0, At, B0); PG8_BAR; PG8_SCHED;
;             PG8_STAGE(PG8_SB(0, 1), b2 + hstep, voffB);
;             PG8_WAIT_V(6); PG8_BAR; PG8_MMA(1, 1, At, B1); PG8_BAR;
;             PG8_LDB(B0, 1, 0); PG8_SCHED; PG8_LDA(At, 1, 0); PG8_STAGE(PG8_SA(0, 1), a2 + hstep, voffA);
;             PG8_WAIT_L(8); PG8_BAR; PG8_WAIT_L(0); PG8_MMA(0, 0, At, B0); PG8_BAR; PG8_SCHED;
;             PG8_LDB(B1, 1, 1); PG8_STAGE(PG8_SB(1, 0), b3, voffB);
;             PG8_BAR; PG8_WAIT_L(0); PG8_MMA(0, 1, At, B1); PG8_BAR;
;             PG8_LDA(At, 1, 1); PG8_STAGE(PG8_SA(1, 0), a3, voffA);
;             PG8_BAR; PG8_WAIT_L(0); PG8_MMA(1, 0, At, B0); PG8_BAR; PG8_SCHED;
;             PG8_STAGE(PG8_SB(1, 1), b3 + hstep, voffB);
;             PG8_WAIT_V(6); PG8_BAR; PG8_MMA(1, 1, At, B1); PG8_BAR;
	s_waitcnt lgkmcnt(0)
	s_setprio 1
	s_waitcnt lgkmcnt(0)
	v_mfma_f32_16x16x32_bf16 v[60:63], v[128:131], v[162:165], v[60:63]
	v_mfma_f32_16x16x32_bf16 v[56:59], v[136:139], v[162:165], v[56:59]
	v_mfma_f32_16x16x32_bf16 v[48:51], v[128:131], v[176:179], v[48:51]
	v_mfma_f32_16x16x32_bf16 v[40:43], v[136:139], v[176:179], v[40:43]
	v_mfma_f32_16x16x32_bf16 v[32:35], v[128:131], v[184:187], v[32:35]
	v_mfma_f32_16x16x32_bf16 v[24:27], v[136:139], v[184:187], v[24:27]
	v_mfma_f32_16x16x32_bf16 v[16:19], v[128:131], v[192:195], v[16:19]
	v_mfma_f32_16x16x32_bf16 v[8:11], v[136:139], v[192:195], v[8:11]
	v_mfma_f32_16x16x32_bf16 v[60:63], v[132:135], v[172:175], v[60:63]
	v_mfma_f32_16x16x32_bf16 v[56:59], v[140:143], v[172:175], v[56:59]
	v_mfma_f32_16x16x32_bf16 v[48:51], v[132:135], v[180:183], v[48:51]
	v_mfma_f32_16x16x32_bf16 v[40:43], v[140:143], v[180:183], v[40:43]
	v_mfma_f32_16x16x32_bf16 v[32:35], v[132:135], v[188:191], v[32:35]
	v_mfma_f32_16x16x32_bf16 v[24:27], v[140:143], v[188:191], v[24:27]
	v_mfma_f32_16x16x32_bf16 v[16:19], v[132:135], v[196:199], v[16:19]
	v_mfma_f32_16x16x32_bf16 v[8:11], v[140:143], v[196:199], v[8:11]
	s_setprio 0
	s_barrier
	s_add_u32 s16, s16, 0x80080
	s_addc_u32 s17, s17, 0
	s_add_i32 s18, s18, s24
	s_mov_b32 m0, s18
	s_nop 0
	global_load_lds_dwordx4 v146, s[16:17]
	s_add_i32 m0, s18, 0x2000
	s_nop 0
	global_load_lds_dwordx4 v150, s[16:17]
	s_waitcnt vmcnt(6)
	s_barrier
	s_setprio 1
	v_mfma_f32_16x16x32_bf16 v[52:55], v[202:205], v[162:165], v[52:55]
	v_mfma_f32_16x16x32_bf16 v[44:47], v[210:213], v[162:165], v[44:47]
	v_mfma_f32_16x16x32_bf16 v[36:39], v[202:205], v[176:179], v[36:39]
	v_mfma_f32_16x16x32_bf16 v[28:31], v[210:213], v[176:179], v[28:31]
	v_mfma_f32_16x16x32_bf16 v[20:23], v[202:205], v[184:187], v[20:23]
	v_mfma_f32_16x16x32_bf16 v[12:15], v[210:213], v[184:187], v[12:15]
	v_mfma_f32_16x16x32_bf16 v[4:7], v[202:205], v[192:195], v[4:7]
	v_mfma_f32_16x16x32_bf16 v[0:3], v[210:213], v[192:195], v[0:3]
	v_mfma_f32_16x16x32_bf16 v[52:55], v[206:209], v[172:175], v[52:55]
	v_mfma_f32_16x16x32_bf16 v[44:47], v[214:217], v[172:175], v[44:47]
	v_mfma_f32_16x16x32_bf16 v[36:39], v[206:209], v[180:183], v[36:39]
	v_mfma_f32_16x16x32_bf16 v[28:31], v[214:217], v[180:183], v[28:31]
	v_mfma_f32_16x16x32_bf16 v[20:23], v[206:209], v[188:191], v[20:23]
	v_mfma_f32_16x16x32_bf16 v[12:15], v[214:217], v[188:191], v[12:15]
	v_mfma_f32_16x16x32_bf16 v[4:7], v[206:209], v[196:199], v[4:7]
	v_mfma_f32_16x16x32_bf16 v[0:3], v[214:217], v[196:199], v[0:3]
	s_setprio 0
	s_add_i32 s43, s43, 2
	s_add_u32 s14, s14, 0x100
	s_addc_u32 s15, s15, 0
	s_add_u32 s41, s41, 0x100
	s_addc_u32 s42, s42, 0
	s_cmp_gt_u32 s43, 29
	s_barrier
.LBB0_826:
	ds_read_b128 v[128:131], v168
	ds_read_b128 v[132:135], v168 offset:1024
	ds_read_b128 v[136:139], v168 offset:2048
	ds_read_b128 v[140:143], v168 offset:3072
	s_add_u32 s16, s14, 0xfff80080
	s_addc_u32 s17, s15, -1
	s_cmp_eq_u32 s43, 28
	s_cselect_b32 s19, s7, s17
	s_cselect_b32 s18, s39, s16
	s_cselect_b32 s17, s5, s42
	s_cselect_b32 s16, s40, s41
	s_add_i32 m0, s13, 0xc000
	ds_read_b128 v[162:165], v169
	ds_read_b128 v[172:175], v169 offset:1024
	ds_read_b128 v[176:179], v169 offset:2048
	ds_read_b128 v[180:183], v169 offset:3072
	ds_read_b128 v[184:187], v169 offset:4096
	ds_read_b128 v[188:191], v169 offset:5120
	ds_read_b128 v[192:195], v169 offset:6144
	ds_read_b128 v[196:199], v169 offset:7168
	global_load_lds_dwordx4 v152, s[14:15]
	s_add_i32 m0, s13, 0xe000
	s_nop 0
	global_load_lds_dwordx4 v154, s[14:15]
	s_waitcnt lgkmcnt(8)
	s_barrier
	s_waitcnt lgkmcnt(0)
	s_setprio 1
	s_waitcnt lgkmcnt(0)
	v_mfma_f32_16x16x32_bf16 v[124:127], v[128:131], v[162:165], v[124:127]
	v_mfma_f32_16x16x32_bf16 v[120:123], v[136:139], v[162:165], v[120:123]
	v_mfma_f32_16x16x32_bf16 v[116:119], v[128:131], v[176:179], v[116:119]
	v_mfma_f32_16x16x32_bf16 v[112:115], v[136:139], v[176:179], v[112:115]
	v_mfma_f32_16x16x32_bf16 v[108:111], v[128:131], v[184:187], v[108:111]
	v_mfma_f32_16x16x32_bf16 v[100:103], v[136:139], v[184:187], v[100:103]
	v_mfma_f32_16x16x32_bf16 v[76:79], v[128:131], v[192:195], v[76:79]
	v_mfma_f32_16x16x32_bf16 v[72:75], v[136:139], v[192:195], v[72:75]
	v_mfma_f32_16x16x32_bf16 v[124:127], v[132:135], v[172:175], v[124:127]
	v_mfma_f32_16x16x32_bf16 v[120:123], v[140:143], v[172:175], v[120:123]
	v_mfma_f32_16x16x32_bf16 v[116:119], v[132:135], v[180:183], v[116:119]
	v_mfma_f32_16x16x32_bf16 v[112:115], v[140:143], v[180:183], v[112:115]
	v_mfma_f32_16x16x32_bf16 v[108:111], v[132:135], v[188:191], v[108:111]
	v_mfma_f32_16x16x32_bf16 v[100:103], v[140:143], v[188:191], v[100:103]
	v_mfma_f32_16x16x32_bf16 v[76:79], v[132:135], v[196:199], v[76:79]
	v_mfma_f32_16x16x32_bf16 v[72:75], v[140:143], v[196:199], v[72:75]
	s_setprio 0
	s_barrier
	s_add_i32 s44, s35, s24
	s_mov_b32 m0, s44
	ds_read_b128 v[202:205], v170
	ds_read_b128 v[206:209], v170 offset:1024
	ds_read_b128 v[210:213], v170 offset:2048
	ds_read_b128 v[214:217], v170 offset:3072
	global_load_lds_dwordx4 v146, s[16:17]
	s_add_i32 m0, s44, 0x2000
	s_nop 0
	global_load_lds_dwordx4 v150, s[16:17]
	s_barrier
; #define PG8_STAGE(bufoff, gbase, voff) do { _Pragma("unroll") for (int _i = 0; _i < 2; ++_i) \
;         __builtin_amdgcn_global_load_lds((const unsigned*)((const char*)(gbase) + (voff)[_i]), (LAS unsigned*)(lds + (bufoff) + ldsw + _i * 8192), 16, 0, 0); } while (0)
; #define PG8_LDA(dst, b, h) do { _Pragma("unroll") for (int m = 0; m < 4; ++m) _Pragma("unroll") for (int k = 0; k < 2; ++k) dst[m][k] = *(const LAS bf16x8*)(lds + PG8_SA(b, h) + aoff + m * 2048 + k * 1024); } while (0)
; #define PG8_LDB(dst, b, h) do { _Pragma("unroll") for (int n = 0; n < 2; ++n) _Pragma("unroll") for (int k = 0; k < 2; ++k) dst[n][k] = *(const LAS bf16x8*)(lds + PG8_SB(b, h) + boff + n * 2048 + k * 1024); } while (0)
; #define PG8_MMA(ai, bj, At, Bt) do { __builtin_amdgcn_s_setprio(1); _Pragma("unroll") for (int m = 0; m < 4; ++m) _Pragma("unroll") for (int n = 0; n < 2; ++n) _Pragma("unroll") for (int k = 0; k < 2; ++k) \
;         acc[ai][bj][m][n] = __builtin_amdgcn_mfma_f32_16x16x32_bf16(Bt[n][k], At[m][k], acc[ai][bj][m][n], 0, 0, 0); __builtin_amdgcn_s_setprio(0); } while (0)
; #define PG8_WAIT_V(n) asm volatile("s_waitcnt vmcnt(" #n ")" ::: "memory")
; #define PG8_WAIT_L(n) asm volatile("s_waitcnt lgkmcnt(" #n ")" ::: "memory")
; #define PG8_BAR __builtin_amdgcn_s_barrier()
; #define PG8_SCHED __builtin_amdgcn_sched_barrier(0)
; template <class Epi, class Sched>
; __device__ __forceinline__ void gemm_phase(LAS unsigned char* lds, const Gemm g, const Sched& S, const Epi& E) {
;     ...
;             PG8_BAR; PG8_WAIT_L(0); PG8_MMA(0, 1, At, B1); PG8_BAR;
;             PG8_LDA(At, 0, 1); PG8_STAGE(PG8_SA(0, 0), a2, voffA);
;             PG8_BAR; PG8_WAIT_L(0); PG8_MMA(1, 0, At, B0); PG8_BAR; PG8_SCHED;
;             PG8_STAGE(PG8_SB(0, 1), b2 + hstep, voffB);
;             PG8_WAIT_V(6); PG8_BAR; PG8_MMA(1, 1, At, B1); PG8_BAR;
;             PG8_LDB(B0, 1, 0); PG8_SCHED; PG8_LDA(At, 1, 0); PG8_STAGE(PG8_SA(0, 1), a2 + hstep, voffA);
;             PG8_WAIT_L(8); PG8_BAR; PG8_WAIT_L(0); PG8_MMA(0, 0, At, B0); PG8_BAR; PG8_SCHED;
	s_waitcnt lgkmcnt(0)
	s_setprio 1
	s_waitcnt lgkmcnt(0)
	v_mfma_f32_16x16x32_bf16 v[104:107], v[202:205], v[162:165], v[104:107]
	v_mfma_f32_16x16x32_bf16 v[96:99], v[210:213], v[162:165], v[96:99]
	v_mfma_f32_16x16x32_bf16 v[92:95], v[202:205], v[176:179], v[92:95]
	v_mfma_f32_16x16x32_bf16 v[88:91], v[210:213], v[176:179], v[88:91]
	v_mfma_f32_16x16x32_bf16 v[84:87], v[202:205], v[184:187], v[84:87]
	v_mfma_f32_16x16x32_bf16 v[80:83], v[210:213], v[184:187], v[80:83]
	v_mfma_f32_16x16x32_bf16 v[68:71], v[202:205], v[192:195], v[68:71]
	v_mfma_f32_16x16x32_bf16 v[64:67], v[210:213], v[192:195], v[64:67]
	v_mfma_f32_16x16x32_bf16 v[104:107], v[206:209], v[172:175], v[104:107]
	v_mfma_f32_16x16x32_bf16 v[96:99], v[214:217], v[172:175], v[96:99]
	v_mfma_f32_16x16x32_bf16 v[92:95], v[206:209], v[180:183], v[92:95]
	v_mfma_f32_16x16x32_bf16 v[88:91], v[214:217], v[180:183], v[88:91]
	v_mfma_f32_16x16x32_bf16 v[84:87], v[206:209], v[188:191], v[84:87]
	v_mfma_f32_16x16x32_bf16 v[80:83], v[214:217], v[188:191], v[80:83]
	v_mfma_f32_16x16x32_bf16 v[68:71], v[206:209], v[196:199], v[68:71]
	v_mfma_f32_16x16x32_bf16 v[64:67], v[214:217], v[196:199], v[64:67]
	s_setprio 0
	s_mov_b32 m0, s13
	v_lshl_add_u64 v[222:223], s[18:19], 0, v[144:145]
	s_barrier
	ds_read_b128 v[162:165], v169 offset:16384
	ds_read_b128 v[172:175], v169 offset:17408
	ds_read_b128 v[176:179], v169 offset:18432
	ds_read_b128 v[180:183], v169 offset:19456
	ds_read_b128 v[184:187], v169 offset:20480
	ds_read_b128 v[188:191], v169 offset:21504
	ds_read_b128 v[192:195], v169 offset:22528
	ds_read_b128 v[196:199], v169 offset:23552
	global_load_lds_dwordx4 v144, s[18:19]
	v_lshl_add_u64 v[224:225], s[18:19], 0, v[148:149]
	s_mov_b32 m0, s25
	s_nop 0
	global_load_lds_dwordx4 v148, s[18:19]
	s_barrier
	s_waitcnt lgkmcnt(0)
	s_setprio 1
	s_waitcnt lgkmcnt(0)
	v_mfma_f32_16x16x32_bf16 v[60:63], v[128:131], v[162:165], v[60:63]
	v_mfma_f32_16x16x32_bf16 v[56:59], v[136:139], v[162:165], v[56:59]
	v_mfma_f32_16x16x32_bf16 v[48:51], v[128:131], v[176:179], v[48:51]
	v_mfma_f32_16x16x32_bf16 v[40:43], v[136:139], v[176:179], v[40:43]
	v_mfma_f32_16x16x32_bf16 v[32:35], v[128:131], v[184:187], v[32:35]
	v_mfma_f32_16x16x32_bf16 v[24:27], v[136:139], v[184:187], v[24:27]
	v_mfma_f32_16x16x32_bf16 v[16:19], v[128:131], v[192:195], v[16:19]
	v_mfma_f32_16x16x32_bf16 v[8:11], v[136:139], v[192:195], v[8:11]
	v_mfma_f32_16x16x32_bf16 v[60:63], v[132:135], v[172:175], v[60:63]
	v_mfma_f32_16x16x32_bf16 v[56:59], v[140:143], v[172:175], v[56:59]
	v_mfma_f32_16x16x32_bf16 v[48:51], v[132:135], v[180:183], v[48:51]
	v_mfma_f32_16x16x32_bf16 v[40:43], v[140:143], v[180:183], v[40:43]
	v_mfma_f32_16x16x32_bf16 v[32:35], v[132:135], v[188:191], v[32:35]
	v_mfma_f32_16x16x32_bf16 v[24:27], v[140:143], v[188:191], v[24:27]
	v_mfma_f32_16x16x32_bf16 v[16:19], v[132:135], v[196:199], v[16:19]
	v_mfma_f32_16x16x32_bf16 v[8:11], v[140:143], v[196:199], v[8:11]
	s_setprio 0
	s_barrier
	s_add_u32 s44, s16, 0x80000
	s_addc_u32 s45, s17, 0
	s_add_i32 s46, s36, s24
	s_mov_b32 m0, s46
	s_nop 0
	global_load_lds_dwordx4 v146, s[44:45]
	s_add_i32 m0, s46, 0x2000
	s_nop 0
	global_load_lds_dwordx4 v150, s[44:45]
	s_waitcnt vmcnt(6)
	s_barrier
	s_setprio 1
	v_mfma_f32_16x16x32_bf16 v[52:55], v[202:205], v[162:165], v[52:55]
	v_mfma_f32_16x16x32_bf16 v[44:47], v[210:213], v[162:165], v[44:47]
	v_mfma_f32_16x16x32_bf16 v[36:39], v[202:205], v[176:179], v[36:39]
	v_mfma_f32_16x16x32_bf16 v[28:31], v[210:213], v[176:179], v[28:31]
	v_mfma_f32_16x16x32_bf16 v[20:23], v[202:205], v[184:187], v[20:23]
	v_mfma_f32_16x16x32_bf16 v[12:15], v[210:213], v[184:187], v[12:15]
	v_mfma_f32_16x16x32_bf16 v[4:7], v[202:205], v[192:195], v[4:7]
	v_mfma_f32_16x16x32_bf16 v[0:3], v[210:213], v[192:195], v[0:3]
	v_mfma_f32_16x16x32_bf16 v[52:55], v[206:209], v[172:175], v[52:55]
	v_mfma_f32_16x16x32_bf16 v[44:47], v[214:217], v[172:175], v[44:47]
	v_mfma_f32_16x16x32_bf16 v[36:39], v[206:209], v[180:183], v[36:39]
	v_mfma_f32_16x16x32_bf16 v[28:31], v[214:217], v[180:183], v[28:31]
	v_mfma_f32_16x16x32_bf16 v[20:23], v[206:209], v[188:191], v[20:23]
	v_mfma_f32_16x16x32_bf16 v[12:15], v[214:217], v[188:191], v[12:15]
	v_mfma_f32_16x16x32_bf16 v[4:7], v[206:209], v[196:199], v[4:7]
	v_mfma_f32_16x16x32_bf16 v[0:3], v[214:217], v[196:199], v[0:3]
	s_setprio 0
	s_add_i32 s44, 0, 0x18000
	v_add_u32_e32 v140, s44, v167
	s_barrier
	ds_read_b128 v[128:131], v140
	ds_read_b128 v[132:135], v140 offset:1024
	ds_read_b128 v[136:139], v140 offset:2048
	ds_read_b128 v[140:143], v140 offset:3072
	s_add_u32 s18, s18, 0x80000
	s_addc_u32 s19, s19, 0
	s_mov_b32 m0, s26
	ds_read_b128 v[162:165], v169 offset:32768
	ds_read_b128 v[172:175], v169 offset:33792
	ds_read_b128 v[176:179], v169 offset:34816
	ds_read_b128 v[180:183], v169 offset:35840
	ds_read_b128 v[184:187], v169 offset:36864
	ds_read_b128 v[188:191], v169 offset:37888
	ds_read_b128 v[192:195], v169 offset:38912
	ds_read_b128 v[196:199], v169 offset:39936
	global_load_lds_dwordx4 v144, s[18:19]
	s_mov_b32 m0, s27
	s_nop 0
	global_load_lds_dwordx4 v148, s[18:19]
	s_waitcnt lgkmcnt(8)
	s_barrier
; #define PG8_STAGE(bufoff, gbase, voff) do { _Pragma("unroll") for (int _i = 0; _i < 2; ++_i) \
;         __builtin_amdgcn_global_load_lds((const unsigned*)((const char*)(gbase) + (voff)[_i]), (LAS unsigned*)(lds + (bufoff) + ldsw + _i * 8192), 16, 0, 0); } while (0)
; #define PG8_LDA(dst, b, h) do { _Pragma("unroll") for (int m = 0; m < 4; ++m) _Pragma("unroll") for (int k = 0; k < 2; ++k) dst[m][k] = *(const LAS bf16x8*)(lds + PG8_SA(b, h) + aoff + m * 2048 + k * 1024); } while (0)
; #define PG8_LDB(dst, b, h) do { _Pragma("unroll") for (int n = 0; n < 2; ++n) _Pragma("unroll") for (int k = 0; k < 2; ++k) dst[n][k] = *(const LAS bf16x8*)(lds + PG8_SB(b, h) + boff + n * 2048 + k * 1024); } while (0)
; #define PG8_MMA(ai, bj, At, Bt) do { __builtin_amdgcn_s_setprio(1); _Pragma("unroll") for (int m = 0; m < 4; ++m) _Pragma("unroll") for (int n = 0; n < 2; ++n) _Pragma("unroll") for (int k = 0; k < 2; ++k) \
;         acc[ai][bj][m][n] = __builtin_amdgcn_mfma_f32_16x16x32_bf16(Bt[n][k], At[m][k], acc[ai][bj][m][n], 0, 0, 0); __builtin_amdgcn_s_setprio(0); } while (0)
; #define PG8_WAIT_V(n) asm volatile("s_waitcnt vmcnt(" #n ")" ::: "memory")
; #define PG8_WAIT_L(n) asm volatile("s_waitcnt lgkmcnt(" #n ")" ::: "memory")
; #define PG8_BAR __builtin_amdgcn_s_barrier()
; #define PG8_SCHED __builtin_amdgcn_sched_barrier(0)
; template <class Epi, class Sched>
; __device__ __forceinline__ void gemm_phase(LAS unsigned char* lds, const Gemm g, const Sched& S, const Epi& E) {
;     ...
;             PG8_WAIT_L(8); PG8_BAR; PG8_WAIT_L(0); PG8_MMA(0, 0, At, B0); PG8_BAR; PG8_SCHED;
;             PG8_LDB(B1, 1, 1); PG8_STAGE(PG8_SB(1, 0), b3, voffB);
;             PG8_BAR; PG8_WAIT_L(0); PG8_MMA(0, 1, At, B1); PG8_BAR;
;             PG8_LDA(At, 1, 1); PG8_STAGE(PG8_SA(1, 0), a3, voffA);
;             PG8_BAR; PG8_WAIT_L(0); PG8_MMA(1, 0, At, B0); PG8_BAR; PG8_SCHED;
;             PG8_STAGE(PG8_SB(1, 1), b3 + hstep, voffB);
;             PG8_WAIT_V(6); PG8_BAR; PG8_MMA(1, 1, At, B1); PG8_BAR;
	s_waitcnt lgkmcnt(0)
	s_setprio 1
	s_waitcnt lgkmcnt(0)
	v_mfma_f32_16x16x32_bf16 v[124:127], v[128:131], v[162:165], v[124:127]
	v_mfma_f32_16x16x32_bf16 v[120:123], v[136:139], v[162:165], v[120:123]
	v_mfma_f32_16x16x32_bf16 v[116:119], v[128:131], v[176:179], v[116:119]
	v_mfma_f32_16x16x32_bf16 v[112:115], v[136:139], v[176:179], v[112:115]
	v_mfma_f32_16x16x32_bf16 v[108:111], v[128:131], v[184:187], v[108:111]
	v_mfma_f32_16x16x32_bf16 v[100:103], v[136:139], v[184:187], v[100:103]
	v_mfma_f32_16x16x32_bf16 v[76:79], v[128:131], v[192:195], v[76:79]
	v_mfma_f32_16x16x32_bf16 v[72:75], v[136:139], v[192:195], v[72:75]
	v_mfma_f32_16x16x32_bf16 v[124:127], v[132:135], v[172:175], v[124:127]
	v_mfma_f32_16x16x32_bf16 v[120:123], v[140:143], v[172:175], v[120:123]
	v_mfma_f32_16x16x32_bf16 v[116:119], v[132:135], v[180:183], v[116:119]
	v_mfma_f32_16x16x32_bf16 v[112:115], v[140:143], v[180:183], v[112:115]
	v_mfma_f32_16x16x32_bf16 v[108:111], v[132:135], v[188:191], v[108:111]
	v_mfma_f32_16x16x32_bf16 v[100:103], v[140:143], v[188:191], v[100:103]
	v_mfma_f32_16x16x32_bf16 v[76:79], v[132:135], v[196:199], v[76:79]
	v_mfma_f32_16x16x32_bf16 v[72:75], v[140:143], v[196:199], v[72:75]
	s_setprio 0
	s_barrier
	s_add_i32 s18, 0, 0x1c000
	s_add_i32 s19, s44, s24
	v_add_u32_e32 v160, s18, v167
	s_add_u32 s0, s16, 0x80
	s_addc_u32 s1, s17, 0
	s_mov_b32 m0, s19
	ds_read_b128 v[202:205], v160
	ds_read_b128 v[206:209], v160 offset:1024
	ds_read_b128 v[210:213], v160 offset:2048
	ds_read_b128 v[214:217], v160 offset:3072
	global_load_lds_dwordx4 v146, s[0:1]
	s_add_i32 m0, s19, 0x2000
	s_nop 0
	global_load_lds_dwordx4 v150, s[0:1]
	s_barrier
	s_waitcnt lgkmcnt(0)
	s_setprio 1
	s_waitcnt lgkmcnt(0)
	v_mfma_f32_16x16x32_bf16 v[104:107], v[202:205], v[162:165], v[104:107]
	v_mfma_f32_16x16x32_bf16 v[96:99], v[210:213], v[162:165], v[96:99]
	v_mfma_f32_16x16x32_bf16 v[92:95], v[202:205], v[176:179], v[92:95]
	v_mfma_f32_16x16x32_bf16 v[88:91], v[210:213], v[176:179], v[88:91]
	v_mfma_f32_16x16x32_bf16 v[84:87], v[202:205], v[184:187], v[84:87]
	v_mfma_f32_16x16x32_bf16 v[80:83], v[210:213], v[184:187], v[80:83]
	v_mfma_f32_16x16x32_bf16 v[68:71], v[202:205], v[192:195], v[68:71]
	v_mfma_f32_16x16x32_bf16 v[64:67], v[210:213], v[192:195], v[64:67]
	v_mfma_f32_16x16x32_bf16 v[104:107], v[206:209], v[172:175], v[104:107]
	v_mfma_f32_16x16x32_bf16 v[96:99], v[214:217], v[172:175], v[96:99]
	v_mfma_f32_16x16x32_bf16 v[92:95], v[206:209], v[180:183], v[92:95]
	v_mfma_f32_16x16x32_bf16 v[88:91], v[214:217], v[180:183], v[88:91]
	v_mfma_f32_16x16x32_bf16 v[84:87], v[206:209], v[188:191], v[84:87]
	v_mfma_f32_16x16x32_bf16 v[80:83], v[214:217], v[188:191], v[80:83]
	v_mfma_f32_16x16x32_bf16 v[68:71], v[206:209], v[196:199], v[68:71]
	v_mfma_f32_16x16x32_bf16 v[64:67], v[214:217], v[196:199], v[64:67]
	s_setprio 0
	s_mov_b32 m0, s31
	s_mov_b64 s[0:1], 0x80
	v_lshl_add_u64 v[218:219], v[222:223], 0, s[0:1]
	s_barrier
	ds_read_b128 v[162:165], v169 offset:49152
	ds_read_b128 v[172:175], v169 offset:50176
	ds_read_b128 v[176:179], v169 offset:51200
	ds_read_b128 v[180:183], v169 offset:52224
	ds_read_b128 v[184:187], v169 offset:53248
	ds_read_b128 v[188:191], v169 offset:54272
	ds_read_b128 v[192:195], v169 offset:55296
	ds_read_b128 v[196:199], v169 offset:56320
	global_load_lds_dwordx4 v[218:219], off
	v_lshl_add_u64 v[218:219], v[224:225], 0, s[0:1]
	s_mov_b32 m0, s33
	s_nop 0
	global_load_lds_dwordx4 v[218:219], off
	s_barrier
	s_waitcnt lgkmcnt(0)
	s_setprio 1
	s_waitcnt lgkmcnt(0)
	v_mfma_f32_16x16x32_bf16 v[60:63], v[128:131], v[162:165], v[60:63]
	v_mfma_f32_16x16x32_bf16 v[56:59], v[136:139], v[162:165], v[56:59]
	v_mfma_f32_16x16x32_bf16 v[48:51], v[128:131], v[176:179], v[48:51]
	v_mfma_f32_16x16x32_bf16 v[40:43], v[136:139], v[176:179], v[40:43]
	v_mfma_f32_16x16x32_bf16 v[32:35], v[128:131], v[184:187], v[32:35]
	v_mfma_f32_16x16x32_bf16 v[24:27], v[136:139], v[184:187], v[24:27]
	v_mfma_f32_16x16x32_bf16 v[16:19], v[128:131], v[192:195], v[16:19]
	v_mfma_f32_16x16x32_bf16 v[8:11], v[136:139], v[192:195], v[8:11]
	v_mfma_f32_16x16x32_bf16 v[60:63], v[132:135], v[172:175], v[60:63]
	v_mfma_f32_16x16x32_bf16 v[56:59], v[140:143], v[172:175], v[56:59]
	v_mfma_f32_16x16x32_bf16 v[48:51], v[132:135], v[180:183], v[48:51]
	v_mfma_f32_16x16x32_bf16 v[40:43], v[140:143], v[180:183], v[40:43]
	v_mfma_f32_16x16x32_bf16 v[32:35], v[132:135], v[188:191], v[32:35]
	v_mfma_f32_16x16x32_bf16 v[24:27], v[140:143], v[188:191], v[24:27]
	v_mfma_f32_16x16x32_bf16 v[16:19], v[132:135], v[196:199], v[16:19]
	v_mfma_f32_16x16x32_bf16 v[8:11], v[140:143], v[196:199], v[8:11]
	s_setprio 0
	s_barrier
	s_add_u32 s16, s16, 0x80080
	s_addc_u32 s17, s17, 0
	s_add_i32 s18, s18, s24
	s_mov_b32 m0, s18
	s_nop 0
	global_load_lds_dwordx4 v146, s[16:17]
	s_add_i32 m0, s18, 0x2000
	s_nop 0
	global_load_lds_dwordx4 v150, s[16:17]
	s_waitcnt vmcnt(6)
	s_barrier
	s_setprio 1
	v_mfma_f32_16x16x32_bf16 v[52:55], v[202:205], v[162:165], v[52:55]
	v_mfma_f32_16x16x32_bf16 v[44:47], v[210:213], v[162:165], v[44:47]
	v_mfma_f32_16x16x32_bf16 v[36:39], v[202:205], v[176:179], v[36:39]
	v_mfma_f32_16x16x32_bf16 v[28:31], v[210:213], v[176:179], v[28:31]
	v_mfma_f32_16x16x32_bf16 v[20:23], v[202:205], v[184:187], v[20:23]
	v_mfma_f32_16x16x32_bf16 v[12:15], v[210:213], v[184:187], v[12:15]
	v_mfma_f32_16x16x32_bf16 v[4:7], v[202:205], v[192:195], v[4:7]
	v_mfma_f32_16x16x32_bf16 v[0:3], v[210:213], v[192:195], v[0:3]
	v_mfma_f32_16x16x32_bf16 v[52:55], v[206:209], v[172:175], v[52:55]
	v_mfma_f32_16x16x32_bf16 v[44:47], v[214:217], v[172:175], v[44:47]
	v_mfma_f32_16x16x32_bf16 v[36:39], v[206:209], v[180:183], v[36:39]
	v_mfma_f32_16x16x32_bf16 v[28:31], v[214:217], v[180:183], v[28:31]
	v_mfma_f32_16x16x32_bf16 v[20:23], v[206:209], v[188:191], v[20:23]
	v_mfma_f32_16x16x32_bf16 v[12:15], v[214:217], v[188:191], v[12:15]
	v_mfma_f32_16x16x32_bf16 v[4:7], v[206:209], v[196:199], v[4:7]
	v_mfma_f32_16x16x32_bf16 v[0:3], v[214:217], v[196:199], v[0:3]
	s_setprio 0
	s_add_i32 s43, s43, 2
	s_add_u32 s14, s14, 0x100
	s_addc_u32 s15, s15, 0
	s_add_u32 s41, s41, 0x100
	s_addc_u32 s42, s42, 0
	s_cmp_gt_u32 s43, 29
	s_barrier
; __device__ __forceinline__ unsigned cvt_pk_bf16(float lo, float hi) { unsigned r; asm volatile("v_cvt_pk_bf16_f32 %0, %1, %2" : "=v"(r) : "v"(lo), "v"(hi)); return r; }
;     __device__ __forceinline__ void operator()(const AccT& acc, const Unit& u, int wr, int wc, int fr, int fq) const {
;         asm volatile("" : "+v"(fr), "+v"(fq));
;         const int row0 = u.pm * 256 + wr * 64 + fr; const int b = u.pn >> 1, ch0 = (u.pn & 1) * 256 + wc * 32 + 8 * fq;
;         const float sg = (fr & 1) ? -1.0f : 1.0f;
;         f32x4 yh[2][2];
; #pragma unroll
;         for (int bj = 0; bj < 2; ++bj)
; #pragma unroll
;             for (int n = 0; n < 2; ++n) yh[bj][n] = *(const f32x4*)(YCH + b * 512 + ch0 + bj * 128 + 4 * n) * sg;
; #pragma unroll
;         for (int ai = 0; ai < 2; ++ai)
; #pragma unroll
;             for (int m = 0; m < 4; ++m) {
;                 const int k = row0 + ai * 128 + m * 16;
; #pragma unroll
;                 for (int bj = 0; bj < 2; ++bj) {
;                     const f32x4 v0 = acc[ai][bj][m][0] + yh[bj][0], v1 = acc[ai][bj][m][1] + yh[bj][1];
;                     u32x4 w; w.x = cvt_pk_bf16(v0[0], v0[1]); w.y = cvt_pk_bf16(v0[2], v0[3]); w.z = cvt_pk_bf16(v1[0], v1[1]); w.w = cvt_pk_bf16(v1[2], v1[3]);
;                     *(u32x4*)(CAT + (size_t)(b * 2048 + k) * CATW + 1024 + ch0 + bj * 128) = w;
;                 }
;             }
;     }
	s_cbranch_scc0 .LBB0_826
	s_ashr_i32 s5, s38, 1
	s_lshl_b32 s7, s38, 8
	s_lshl_b32 s14, s5, 9
	s_and_b32 s7, s7, 0x100
	s_ashr_i32 s15, s14, 31
	v_mov_b32_e32 v171, v161
	v_mov_b32_e32 v128, v166
	s_or_b32 s7, s7, s30
	s_lshl_b64 s[14:15], s[14:15], 2
	s_add_u32 s14, s48, s14
	v_lshl_add_u32 v164, v128, 3, s7
	s_addc_u32 s15, s49, s15
	v_ashrrev_i32_e32 v165, 31, v164
	v_lshl_add_u64 v[128:129], v[164:165], 2, s[14:15]
	global_load_dwordx4 v[140:143], v[128:129], off
	global_load_dwordx4 v[136:139], v[128:129], off offset:16
	global_load_dwordx4 v[132:135], v[128:129], off offset:512
	s_nop 0
	global_load_dwordx4 v[128:131], v[128:129], off offset:528
	s_lshl_b32 s7, s12, 8
	s_lshl_b32 s5, s5, 11
	s_add_i32 s7, s7, s29
	v_and_b32_e32 v160, 1, v171
	s_add_i32 s7, s7, s5
	v_mov_b64_e32 v[162:163], s[96:97]
	v_cmp_eq_u32_e32 vcc, 0, v160
	v_add_u32_e32 v171, s7, v171
	v_lshlrev_b64 v[164:165], 1, v[164:165]
	v_cndmask_b32_e64 v160, -1.0, 1.0, vcc
	v_mad_i64_i32 v[172:173], s[14:15], v171, s37, v[162:163]
	v_add_u32_e32 v174, 16, v171
	v_lshl_add_u64 v[172:173], v[172:173], 0, v[164:165]
	v_mad_i64_i32 v[174:175], s[14:15], v174, s37, v[162:163]
	v_add_u32_e32 v176, 32, v171
	v_lshl_add_u64 v[174:175], v[174:175], 0, v[164:165]
	v_mad_i64_i32 v[176:177], s[14:15], v176, s37, v[162:163]
	v_lshl_add_u64 v[176:177], v[176:177], 0, v[164:165]
	v_add_u32_e32 v182, 48, v171
	s_and_b64 vcc, exec, s[2:3]
	s_mov_b32 s38, s4
	s_mov_b32 s12, s6
	s_mov_b64 s[16:17], s[10:11]
	s_waitcnt vmcnt(0)
	v_pk_fma_f32 v[126:127], v[142:143], v[160:161], v[126:127] op_sel_hi:[1,0,1]
	v_pk_fma_f32 v[124:125], v[140:141], v[160:161], v[124:125] op_sel_hi:[1,0,1]
	v_pk_fma_f32 v[122:123], v[138:139], v[160:161], v[122:123] op_sel_hi:[1,0,1]
	v_pk_fma_f32 v[180:181], v[128:129], v[160:161], v[80:81] op_sel_hi:[1,0,1]
	v_cvt_pk_bf16_f32 v80, v124, v125
	v_cvt_pk_bf16_f32 v81, v126, v127
	v_pk_fma_f32 v[120:121], v[136:137], v[160:161], v[120:121] op_sel_hi:[1,0,1]
	v_pk_fma_f32 v[106:107], v[134:135], v[160:161], v[106:107] op_sel_hi:[1,0,1]
	v_pk_fma_f32 v[104:105], v[132:133], v[160:161], v[104:105] op_sel_hi:[1,0,1]
	v_pk_fma_f32 v[178:179], v[130:131], v[160:161], v[82:83] op_sel_hi:[1,0,1]
	v_cvt_pk_bf16_f32 v82, v120, v121
	v_cvt_pk_bf16_f32 v83, v122, v123
	global_store_dwordx4 v[172:173], v[80:83], off offset:2048
	v_pk_fma_f32 v[98:99], v[130:131], v[160:161], v[98:99] op_sel_hi:[1,0,1]
	v_pk_fma_f32 v[96:97], v[128:129], v[160:161], v[96:97] op_sel_hi:[1,0,1]
	v_cvt_pk_bf16_f32 v80, v104, v105
	v_cvt_pk_bf16_f32 v81, v106, v107
	v_pk_fma_f32 v[118:119], v[142:143], v[160:161], v[118:119] op_sel_hi:[1,0,1]
	v_pk_fma_f32 v[116:117], v[140:141], v[160:161], v[116:117] op_sel_hi:[1,0,1]
	v_cvt_pk_bf16_f32 v82, v96, v97
	v_cvt_pk_bf16_f32 v83, v98, v99
	global_store_dwordx4 v[172:173], v[80:83], off offset:2304
	v_pk_fma_f32 v[114:115], v[138:139], v[160:161], v[114:115] op_sel_hi:[1,0,1]
	v_pk_fma_f32 v[112:113], v[136:137], v[160:161], v[112:113] op_sel_hi:[1,0,1]
	v_cvt_pk_bf16_f32 v80, v116, v117
	v_cvt_pk_bf16_f32 v81, v118, v119
	v_pk_fma_f32 v[94:95], v[134:135], v[160:161], v[94:95] op_sel_hi:[1,0,1]
	v_pk_fma_f32 v[92:93], v[132:133], v[160:161], v[92:93] op_sel_hi:[1,0,1]
	v_cvt_pk_bf16_f32 v82, v112, v113
	v_cvt_pk_bf16_f32 v83, v114, v115
	global_store_dwordx4 v[174:175], v[80:83], off offset:2048
	v_pk_fma_f32 v[90:91], v[130:131], v[160:161], v[90:91] op_sel_hi:[1,0,1]
	v_pk_fma_f32 v[88:89], v[128:129], v[160:161], v[88:89] op_sel_hi:[1,0,1]
	v_cvt_pk_bf16_f32 v80, v92, v93
	v_cvt_pk_bf16_f32 v81, v94, v95
	v_pk_fma_f32 v[110:111], v[142:143], v[160:161], v[110:111] op_sel_hi:[1,0,1]
	v_pk_fma_f32 v[108:109], v[140:141], v[160:161], v[108:109] op_sel_hi:[1,0,1]
	v_cvt_pk_bf16_f32 v82, v88, v89
	v_cvt_pk_bf16_f32 v83, v90, v91
	global_store_dwordx4 v[174:175], v[80:83], off offset:2304
	v_pk_fma_f32 v[102:103], v[138:139], v[160:161], v[102:103] op_sel_hi:[1,0,1]
	v_pk_fma_f32 v[100:101], v[136:137], v[160:161], v[100:101] op_sel_hi:[1,0,1]
	v_cvt_pk_bf16_f32 v80, v108, v109
	v_cvt_pk_bf16_f32 v81, v110, v111
	v_pk_fma_f32 v[86:87], v[134:135], v[160:161], v[86:87] op_sel_hi:[1,0,1]
	v_pk_fma_f32 v[84:85], v[132:133], v[160:161], v[84:85] op_sel_hi:[1,0,1]
	v_cvt_pk_bf16_f32 v82, v100, v101
	v_cvt_pk_bf16_f32 v83, v102, v103
	global_store_dwordx4 v[176:177], v[80:83], off offset:2048
	v_pk_fma_f32 v[76:77], v[140:141], v[160:161], v[76:77] op_sel_hi:[1,0,1]
	v_pk_fma_f32 v[78:79], v[142:143], v[160:161], v[78:79] op_sel_hi:[1,0,1]
	v_cvt_pk_bf16_f32 v80, v84, v85
	v_cvt_pk_bf16_f32 v81, v86, v87
	v_cvt_pk_bf16_f32 v82, v180, v181
	v_cvt_pk_bf16_f32 v83, v178, v179
	global_store_dwordx4 v[176:177], v[80:83], off offset:2304
	v_pk_fma_f32 v[70:71], v[134:135], v[160:161], v[70:71] op_sel_hi:[1,0,1]
	v_pk_fma_f32 v[68:69], v[132:133], v[160:161], v[68:69] op_sel_hi:[1,0,1]
	v_pk_fma_f32 v[80:81], v[138:139], v[160:161], v[74:75] op_sel_hi:[1,0,1]
	v_pk_fma_f32 v[74:75], v[136:137], v[160:161], v[72:73] op_sel_hi:[1,0,1]
	v_cvt_pk_bf16_f32 v72, v76, v77
	v_mad_i64_i32 v[76:77], s[14:15], v182, s37, v[162:163]
	v_cvt_pk_bf16_f32 v73, v78, v79
; __device__ __forceinline__ unsigned cvt_pk_bf16(float lo, float hi) { unsigned r; asm volatile("v_cvt_pk_bf16_f32 %0, %1, %2" : "=v"(r) : "v"(lo), "v"(hi)); return r; }
; #define PG8_WAIT_V(n) asm volatile("s_waitcnt vmcnt(" #n ")" ::: "memory")
; #define PG8_BAR __builtin_amdgcn_s_barrier()
; template <class Epi, class Sched>
; __device__ __forceinline__ void gemm_phase(LAS unsigned char* lds, const Gemm g, const Sched& S, const Epi& E) {
;     ...
;         E(acc, cur, wr, wc, fr, fq);
;         if (!has_next) break;
; #pragma unroll
;         for (int a = 0; a < 2; ++a)
; #pragma unroll
;             for (int b = 0; b < 2; ++b)
; #pragma unroll
;                 for (int m = 0; m < 4; ++m)
; #pragma unroll
;                     for (int n = 0; n < 2; ++n) acc[a][b][m][n] = (f32x4){0.f, 0.f, 0.f, 0.f};
;         cur = nxt; cA = nA; cB = nB; ++ui;
;     }
;     PG8_WAIT_V(0);
;     if (wr == 0) PG8_BAR;
;     PG8_BAR;
;     __device__ __forceinline__ void operator()(const AccT& acc, const Unit& u, int wr, int wc, int fr, int fq) const {
;     ...
;         for (int ai = 0; ai < 2; ++ai)
; #pragma unroll
;             for (int m = 0; m < 4; ++m) {
;                 const int k = row0 + ai * 128 + m * 16;
; #pragma unroll
;                 for (int bj = 0; bj < 2; ++bj) {
;                     const f32x4 v0 = acc[ai][bj][m][0] + yh[bj][0], v1 = acc[ai][bj][m][1] + yh[bj][1];
;                     u32x4 w; w.x = cvt_pk_bf16(v0[0], v0[1]); w.y = cvt_pk_bf16(v0[2], v0[3]); w.z = cvt_pk_bf16(v1[0], v1[1]); w.w = cvt_pk_bf16(v1[2], v1[3]);
;                     *(u32x4*)(CAT + (size_t)(b * 2048 + k) * CATW + 1024 + ch0 + bj * 128) = w;
;                 }
;             }
	v_lshl_add_u64 v[76:77], v[76:77], 0, v[164:165]
	v_cvt_pk_bf16_f32 v74, v74, v75
	v_cvt_pk_bf16_f32 v75, v80, v81
	global_store_dwordx4 v[76:77], v[72:75], off offset:2048
	v_pk_fma_f32 v[60:61], v[140:141], v[160:161], v[60:61] op_sel_hi:[1,0,1]
	v_pk_fma_f32 v[62:63], v[142:143], v[160:161], v[62:63] op_sel_hi:[1,0,1]
	v_pk_fma_f32 v[72:73], v[130:131], v[160:161], v[66:67] op_sel_hi:[1,0,1]
	v_pk_fma_f32 v[66:67], v[128:129], v[160:161], v[64:65] op_sel_hi:[1,0,1]
	v_cvt_pk_bf16_f32 v64, v68, v69
	v_cvt_pk_bf16_f32 v65, v70, v71
	v_pk_fma_f32 v[54:55], v[134:135], v[160:161], v[54:55] op_sel_hi:[1,0,1]
	v_cvt_pk_bf16_f32 v66, v66, v67
	v_cvt_pk_bf16_f32 v67, v72, v73
	global_store_dwordx4 v[76:77], v[64:67], off offset:2304
	v_pk_fma_f32 v[52:53], v[132:133], v[160:161], v[52:53] op_sel_hi:[1,0,1]
	v_pk_fma_f32 v[38:39], v[134:135], v[160:161], v[38:39] op_sel_hi:[1,0,1]
	v_add_u32_e32 v66, 0x80, v171
	v_pk_fma_f32 v[64:65], v[138:139], v[160:161], v[58:59] op_sel_hi:[1,0,1]
	v_pk_fma_f32 v[58:59], v[136:137], v[160:161], v[56:57] op_sel_hi:[1,0,1]
	v_cvt_pk_bf16_f32 v56, v60, v61
	v_mad_i64_i32 v[60:61], s[14:15], v66, s37, v[162:163]
	v_cvt_pk_bf16_f32 v57, v62, v63
	v_lshl_add_u64 v[60:61], v[60:61], 0, v[164:165]
	v_cvt_pk_bf16_f32 v58, v58, v59
	v_cvt_pk_bf16_f32 v59, v64, v65
	global_store_dwordx4 v[60:61], v[56:59], off offset:2048
	v_pk_fma_f32 v[36:37], v[132:133], v[160:161], v[36:37] op_sel_hi:[1,0,1]
	v_pk_fma_f32 v[22:23], v[134:135], v[160:161], v[22:23] op_sel_hi:[1,0,1]
	v_pk_fma_f32 v[56:57], v[130:131], v[160:161], v[46:47] op_sel_hi:[1,0,1]
	v_pk_fma_f32 v[46:47], v[128:129], v[160:161], v[44:45] op_sel_hi:[1,0,1]
	v_cvt_pk_bf16_f32 v44, v52, v53
	v_cvt_pk_bf16_f32 v45, v54, v55
	v_add_u32_e32 v52, 0x90, v171
	v_cvt_pk_bf16_f32 v46, v46, v47
	v_cvt_pk_bf16_f32 v47, v56, v57
	global_store_dwordx4 v[60:61], v[44:47], off offset:2304
	v_pk_fma_f32 v[20:21], v[132:133], v[160:161], v[20:21] op_sel_hi:[1,0,1]
	v_pk_fma_f32 v[6:7], v[134:135], v[160:161], v[6:7] op_sel_hi:[1,0,1]
	v_pk_fma_f32 v[44:45], v[142:143], v[160:161], v[50:51] op_sel_hi:[1,0,1]
	v_pk_fma_f32 v[46:47], v[140:141], v[160:161], v[48:49] op_sel_hi:[1,0,1]
	v_pk_fma_f32 v[48:49], v[138:139], v[160:161], v[42:43] op_sel_hi:[1,0,1]
	v_pk_fma_f32 v[42:43], v[136:137], v[160:161], v[40:41] op_sel_hi:[1,0,1]
	v_cvt_pk_bf16_f32 v40, v46, v47
	v_cvt_pk_bf16_f32 v41, v44, v45
	v_mad_i64_i32 v[44:45], s[14:15], v52, s37, v[162:163]
	v_lshl_add_u64 v[44:45], v[44:45], 0, v[164:165]
	v_cvt_pk_bf16_f32 v42, v42, v43
	v_cvt_pk_bf16_f32 v43, v48, v49
	global_store_dwordx4 v[44:45], v[40:43], off offset:2048
	v_pk_fma_f32 v[4:5], v[132:133], v[160:161], v[4:5] op_sel_hi:[1,0,1]
	s_nop 0
	v_pk_fma_f32 v[40:41], v[130:131], v[160:161], v[30:31] op_sel_hi:[1,0,1]
	v_pk_fma_f32 v[30:31], v[128:129], v[160:161], v[28:29] op_sel_hi:[1,0,1]
	v_cvt_pk_bf16_f32 v28, v36, v37
	v_cvt_pk_bf16_f32 v29, v38, v39
	v_add_u32_e32 v36, 0xa0, v171
	v_cvt_pk_bf16_f32 v30, v30, v31
	v_cvt_pk_bf16_f32 v31, v40, v41
	global_store_dwordx4 v[44:45], v[28:31], off offset:2304
	s_nop 1
	v_pk_fma_f32 v[28:29], v[142:143], v[160:161], v[34:35] op_sel_hi:[1,0,1]
	v_pk_fma_f32 v[30:31], v[140:141], v[160:161], v[32:33] op_sel_hi:[1,0,1]
	v_pk_fma_f32 v[32:33], v[138:139], v[160:161], v[26:27] op_sel_hi:[1,0,1]
	v_pk_fma_f32 v[26:27], v[136:137], v[160:161], v[24:25] op_sel_hi:[1,0,1]
	v_cvt_pk_bf16_f32 v24, v30, v31
	v_cvt_pk_bf16_f32 v25, v28, v29
	v_mad_i64_i32 v[28:29], s[14:15], v36, s37, v[162:163]
	v_lshl_add_u64 v[28:29], v[28:29], 0, v[164:165]
	v_cvt_pk_bf16_f32 v26, v26, v27
	v_cvt_pk_bf16_f32 v27, v32, v33
	global_store_dwordx4 v[28:29], v[24:27], off offset:2048
	s_nop 1
	v_pk_fma_f32 v[24:25], v[130:131], v[160:161], v[14:15] op_sel_hi:[1,0,1]
	v_pk_fma_f32 v[14:15], v[128:129], v[160:161], v[12:13] op_sel_hi:[1,0,1]
	v_cvt_pk_bf16_f32 v12, v20, v21
	v_cvt_pk_bf16_f32 v13, v22, v23
	v_add_u32_e32 v20, 0xb0, v171
	v_cvt_pk_bf16_f32 v14, v14, v15
	v_cvt_pk_bf16_f32 v15, v24, v25
	global_store_dwordx4 v[28:29], v[12:15], off offset:2304
	s_nop 1
	v_pk_fma_f32 v[12:13], v[142:143], v[160:161], v[18:19] op_sel_hi:[1,0,1]
	v_pk_fma_f32 v[14:15], v[140:141], v[160:161], v[16:17] op_sel_hi:[1,0,1]
	v_pk_fma_f32 v[16:17], v[138:139], v[160:161], v[10:11] op_sel_hi:[1,0,1]
	v_pk_fma_f32 v[10:11], v[136:137], v[160:161], v[8:9] op_sel_hi:[1,0,1]
	v_cvt_pk_bf16_f32 v8, v14, v15
	v_cvt_pk_bf16_f32 v9, v12, v13
	v_mad_i64_i32 v[12:13], s[14:15], v20, s37, v[162:163]
	v_lshl_add_u64 v[12:13], v[12:13], 0, v[164:165]
	v_cvt_pk_bf16_f32 v10, v10, v11
	v_cvt_pk_bf16_f32 v11, v16, v17
	global_store_dwordx4 v[12:13], v[8:11], off offset:2048
	s_mov_b64 s[14:15], s[8:9]
	s_nop 0
	v_pk_fma_f32 v[8:9], v[130:131], v[160:161], v[2:3] op_sel_hi:[1,0,1]
	v_pk_fma_f32 v[2:3], v[128:129], v[160:161], v[0:1] op_sel_hi:[1,0,1]
	v_cvt_pk_bf16_f32 v0, v4, v5
	v_cvt_pk_bf16_f32 v1, v6, v7
	s_nop 0
	v_cvt_pk_bf16_f32 v2, v2, v3
	v_cvt_pk_bf16_f32 v3, v8, v9
	global_store_dwordx4 v[12:13], v[0:3], off offset:2304
	s_cbranch_vccz .LBB0_819
	s_waitcnt vmcnt(0)
	s_cmpk_gt_u32 s20, 0xff
	s_cbranch_scc1 .LBB0_830
	s_barrier

; #define PG8_STAGE(bufoff, gbase, voff) do { _Pragma("unroll") for (int _i = 0; _i < 2; ++_i) \
;         __builtin_amdgcn_global_load_lds((const unsigned*)((const char*)(gbase) + (voff)[_i]), (LAS unsigned*)(lds + (bufoff) + ldsw + _i * 8192), 16, 0, 0); } while (0)
; #define PG8_LDA(dst, b, h) do { _Pragma("unroll") for (int m = 0; m < 4; ++m) _Pragma("unroll") for (int k = 0; k < 2; ++k) dst[m][k] = *(const LAS bf16x8*)(lds + PG8_SA(b, h) + aoff + m * 2048 + k * 1024); } while (0)
; #define PG8_LDB(dst, b, h) do { _Pragma("unroll") for (int n = 0; n < 2; ++n) _Pragma("unroll") for (int k = 0; k < 2; ++k) dst[n][k] = *(const LAS bf16x8*)(lds + PG8_SB(b, h) + boff + n * 2048 + k * 1024); } while (0)
; #define PG8_WAIT_V(n) asm volatile("s_waitcnt vmcnt(" #n ")" ::: "memory")
; #define PG8_WAIT_L(n) asm volatile("s_waitcnt lgkmcnt(" #n ")" ::: "memory")
; #define PG8_BAR __builtin_amdgcn_s_barrier()
; #define PG8_SCHED __builtin_amdgcn_sched_barrier(0)
; template <class Epi, class Sched>
; __device__ __forceinline__ void gemm_phase(LAS unsigned char* lds, const Gemm g, const Sched& S, const Epi& E) {
;     ...
;     for (;;) {
;         const bool has_next = S.next(ui + 1, nxt);
;         const char* nA = has_next ? (const char*)g.A + (size_t)nxt.pm * tstep : cA; const char* nB = has_next ? (const char*)g.Bt + (size_t)nxt.pn * tstep : cB;
;         for (int t = 0; t < nt; t += 2) {
;             const bool last = (t == nt - 2);
;             const char* a1 = cA + (size_t)(t + 1) * kstep;
;             const char* a2 = last ? nA : cA + (size_t)(t + 2) * kstep; const char* b2 = last ? nB : cB + (size_t)(t + 2) * kstep;
;             const char* a3 = a2 + kstep; const char* b3 = b2 + kstep;
;             PG8_LDB(B0, 0, 0); PG8_SCHED; PG8_LDA(At, 0, 0); PG8_STAGE(PG8_SA(1, 1), a1 + hstep, voffA);
;             PG8_WAIT_L(8); PG8_BAR; PG8_WAIT_L(0); PG8_MMA(0, 0, At, B0); PG8_BAR; PG8_SCHED;
;             PG8_LDB(B1, 0, 1); PG8_STAGE(PG8_SB(0, 0), b2, voffB);
;             PG8_BAR; PG8_WAIT_L(0); PG8_MMA(0, 1, At, B1); PG8_BAR;
;             PG8_LDA(At, 0, 1); PG8_STAGE(PG8_SA(0, 0), a2, voffA);
;             PG8_BAR; PG8_WAIT_L(0); PG8_MMA(1, 0, At, B0); PG8_BAR; PG8_SCHED;
;             PG8_STAGE(PG8_SB(0, 1), b2 + hstep, voffB);
;             PG8_WAIT_V(6); PG8_BAR; PG8_MMA(1, 1, At, B1); PG8_BAR;
.LBB0_901:
	s_add_u32 s56, s26, 0x100
	s_addc_u32 s57, s27, 0
	s_mov_b32 s58, -2
	s_waitcnt vmcnt(0)
	ds_read_b128 v[128:131], v237
	ds_read_b128 v[132:135], v237 offset:1024
	ds_read_b128 v[136:139], v237 offset:2048
	ds_read_b128 v[140:143], v237 offset:3072
	s_add_u32 s26, s24, 0x100
	s_addc_u32 s27, s25, 0
	s_cmp_eq_u32 s58, 20
	s_cselect_b32 s31, s5, s27
	s_cselect_b32 s30, s4, s26
	s_cselect_b32 s29, s7, s57
	s_cselect_b32 s28, s6, s56
	v_lshl_add_u64 v[176:177], s[24:25], 0, v[210:211]
	s_add_i32 m0, s38, 0xc000
	ds_read_b128 v[144:147], v238
	ds_read_b128 v[148:151], v238 offset:1024
	ds_read_b128 v[152:155], v238 offset:2048
	ds_read_b128 v[156:159], v238 offset:3072
	ds_read_b128 v[160:163], v238 offset:4096
	ds_read_b128 v[164:167], v238 offset:5120
	ds_read_b128 v[168:171], v238 offset:6144
	ds_read_b128 v[172:175], v238 offset:7168
	global_load_lds_dwordx4 v[176:177], off
	v_lshl_add_u64 v[176:177], s[24:25], 0, v[212:213]
	s_add_i32 m0, s38, 0xe000
	s_nop 0
	global_load_lds_dwordx4 v[176:177], off
	s_waitcnt lgkmcnt(8)
	s_barrier
	s_waitcnt lgkmcnt(0)
	s_setprio 1
	s_waitcnt lgkmcnt(0)
	v_mfma_f32_16x16x32_bf16 v[124:127], v[128:131], v[144:147], 0
	v_mfma_f32_16x16x32_bf16 v[120:123], v[136:139], v[144:147], 0
	v_mfma_f32_16x16x32_bf16 v[108:111], v[128:131], v[152:155], 0
	v_mfma_f32_16x16x32_bf16 v[104:107], v[136:139], v[152:155], 0
	v_mfma_f32_16x16x32_bf16 v[92:95], v[128:131], v[160:163], 0
	v_mfma_f32_16x16x32_bf16 v[88:91], v[136:139], v[160:163], 0
	v_mfma_f32_16x16x32_bf16 v[76:79], v[128:131], v[168:171], 0
	v_mfma_f32_16x16x32_bf16 v[72:75], v[136:139], v[168:171], 0
	v_mfma_f32_16x16x32_bf16 v[124:127], v[132:135], v[148:151], v[124:127]
	v_mfma_f32_16x16x32_bf16 v[120:123], v[140:143], v[148:151], v[120:123]
	v_mfma_f32_16x16x32_bf16 v[108:111], v[132:135], v[156:159], v[108:111]
	v_mfma_f32_16x16x32_bf16 v[104:107], v[140:143], v[156:159], v[104:107]
	v_mfma_f32_16x16x32_bf16 v[92:95], v[132:135], v[164:167], v[92:95]
	v_mfma_f32_16x16x32_bf16 v[88:91], v[140:143], v[164:167], v[88:91]
	v_mfma_f32_16x16x32_bf16 v[76:79], v[132:135], v[172:175], v[76:79]
	v_mfma_f32_16x16x32_bf16 v[72:75], v[140:143], v[172:175], v[72:75]
	s_setprio 0
	s_barrier
	s_add_i32 s24, s50, s37
	s_mov_b32 m0, s24
	ds_read_b128 v[176:179], v239
	ds_read_b128 v[180:183], v239 offset:1024
	ds_read_b128 v[184:187], v239 offset:2048
	ds_read_b128 v[188:191], v239 offset:3072
	global_load_lds_dwordx4 v204, s[28:29]
	s_add_i32 m0, s24, 0x2000
	s_nop 0
	global_load_lds_dwordx4 v208, s[28:29]
	s_barrier
	s_waitcnt lgkmcnt(0)
	s_setprio 1
	s_waitcnt lgkmcnt(0)
	v_mfma_f32_16x16x32_bf16 v[116:119], v[176:179], v[144:147], 0
	v_mfma_f32_16x16x32_bf16 v[112:115], v[184:187], v[144:147], 0
	v_mfma_f32_16x16x32_bf16 v[100:103], v[176:179], v[152:155], 0
	v_mfma_f32_16x16x32_bf16 v[96:99], v[184:187], v[152:155], 0
	v_mfma_f32_16x16x32_bf16 v[84:87], v[176:179], v[160:163], 0
	v_mfma_f32_16x16x32_bf16 v[80:83], v[184:187], v[160:163], 0
	v_mfma_f32_16x16x32_bf16 v[68:71], v[176:179], v[168:171], 0
	v_mfma_f32_16x16x32_bf16 v[64:67], v[184:187], v[168:171], 0
	v_mfma_f32_16x16x32_bf16 v[116:119], v[180:183], v[148:151], v[116:119]
	v_mfma_f32_16x16x32_bf16 v[112:115], v[188:191], v[148:151], v[112:115]
	v_mfma_f32_16x16x32_bf16 v[100:103], v[180:183], v[156:159], v[100:103]
	v_mfma_f32_16x16x32_bf16 v[96:99], v[188:191], v[156:159], v[96:99]
	v_mfma_f32_16x16x32_bf16 v[84:87], v[180:183], v[164:167], v[84:87]
	v_mfma_f32_16x16x32_bf16 v[80:83], v[188:191], v[164:167], v[80:83]
	v_mfma_f32_16x16x32_bf16 v[68:71], v[180:183], v[172:175], v[68:71]
	v_mfma_f32_16x16x32_bf16 v[64:67], v[188:191], v[172:175], v[64:67]
	s_setprio 0
	s_mov_b32 m0, s38
	v_lshl_add_u64 v[196:197], s[30:31], 0, v[202:203]
	s_barrier
	ds_read_b128 v[144:147], v238 offset:16384
	ds_read_b128 v[148:151], v238 offset:17408
	ds_read_b128 v[152:155], v238 offset:18432
	ds_read_b128 v[156:159], v238 offset:19456
	ds_read_b128 v[160:163], v238 offset:20480
	ds_read_b128 v[164:167], v238 offset:21504
	ds_read_b128 v[168:171], v238 offset:22528
	ds_read_b128 v[172:175], v238 offset:23552
	global_load_lds_dwordx4 v202, s[30:31]
	v_lshl_add_u64 v[198:199], s[30:31], 0, v[206:207]
	s_mov_b32 m0, s39
	s_nop 0
	global_load_lds_dwordx4 v206, s[30:31]
	s_barrier
	s_waitcnt lgkmcnt(0)
	s_setprio 1
	s_waitcnt lgkmcnt(0)
	v_mfma_f32_16x16x32_bf16 v[60:63], v[128:131], v[144:147], 0
	v_mfma_f32_16x16x32_bf16 v[56:59], v[136:139], v[144:147], 0
	v_mfma_f32_16x16x32_bf16 v[44:47], v[128:131], v[152:155], 0
	v_mfma_f32_16x16x32_bf16 v[40:43], v[136:139], v[152:155], 0
	v_mfma_f32_16x16x32_bf16 v[28:31], v[128:131], v[160:163], 0
	v_mfma_f32_16x16x32_bf16 v[24:27], v[136:139], v[160:163], 0
	v_mfma_f32_16x16x32_bf16 v[12:15], v[128:131], v[168:171], 0
	v_mfma_f32_16x16x32_bf16 v[8:11], v[136:139], v[168:171], 0
	v_mfma_f32_16x16x32_bf16 v[60:63], v[132:135], v[148:151], v[60:63]
	v_mfma_f32_16x16x32_bf16 v[56:59], v[140:143], v[148:151], v[56:59]
	v_mfma_f32_16x16x32_bf16 v[44:47], v[132:135], v[156:159], v[44:47]
	v_mfma_f32_16x16x32_bf16 v[40:43], v[140:143], v[156:159], v[40:43]
	v_mfma_f32_16x16x32_bf16 v[28:31], v[132:135], v[164:167], v[28:31]
	v_mfma_f32_16x16x32_bf16 v[24:27], v[140:143], v[164:167], v[24:27]
	v_mfma_f32_16x16x32_bf16 v[12:15], v[132:135], v[172:175], v[12:15]
	v_mfma_f32_16x16x32_bf16 v[8:11], v[140:143], v[172:175], v[8:11]
	s_setprio 0
	s_barrier
	s_add_u32 s24, s28, 0x60000
	s_addc_u32 s25, s29, 0
	s_add_i32 s59, s51, s37
	s_mov_b32 m0, s59
	s_nop 0
	global_load_lds_dwordx4 v204, s[24:25]
	s_add_i32 m0, s59, 0x2000
	s_nop 0
	global_load_lds_dwordx4 v208, s[24:25]
	s_waitcnt vmcnt(6)
	s_barrier
; #define PG8_STAGE(bufoff, gbase, voff) do { _Pragma("unroll") for (int _i = 0; _i < 2; ++_i) \
;         __builtin_amdgcn_global_load_lds((const unsigned*)((const char*)(gbase) + (voff)[_i]), (LAS unsigned*)(lds + (bufoff) + ldsw + _i * 8192), 16, 0, 0); } while (0)
; #define PG8_LDA(dst, b, h) do { _Pragma("unroll") for (int m = 0; m < 4; ++m) _Pragma("unroll") for (int k = 0; k < 2; ++k) dst[m][k] = *(const LAS bf16x8*)(lds + PG8_SA(b, h) + aoff + m * 2048 + k * 1024); } while (0)
; #define PG8_LDB(dst, b, h) do { _Pragma("unroll") for (int n = 0; n < 2; ++n) _Pragma("unroll") for (int k = 0; k < 2; ++k) dst[n][k] = *(const LAS bf16x8*)(lds + PG8_SB(b, h) + boff + n * 2048 + k * 1024); } while (0)
; #define PG8_MMA(ai, bj, At, Bt) do { __builtin_amdgcn_s_setprio(1); _Pragma("unroll") for (int m = 0; m < 4; ++m) _Pragma("unroll") for (int n = 0; n < 2; ++n) _Pragma("unroll") for (int k = 0; k < 2; ++k) \
;         acc[ai][bj][m][n] = __builtin_amdgcn_mfma_f32_16x16x32_bf16(Bt[n][k], At[m][k], acc[ai][bj][m][n], 0, 0, 0); __builtin_amdgcn_s_setprio(0); } while (0)
; #define PG8_WAIT_V(n) asm volatile("s_waitcnt vmcnt(" #n ")" ::: "memory")
; #define PG8_WAIT_L(n) asm volatile("s_waitcnt lgkmcnt(" #n ")" ::: "memory")
; #define PG8_BAR __builtin_amdgcn_s_barrier()
; #define PG8_SCHED __builtin_amdgcn_sched_barrier(0)
; template <class Epi, class Sched>
; __device__ __forceinline__ void gemm_phase(LAS unsigned char* lds, const Gemm g, const Sched& S, const Epi& E) {
;     ...
;             PG8_STAGE(PG8_SB(0, 1), b2 + hstep, voffB);
;             PG8_WAIT_V(6); PG8_BAR; PG8_MMA(1, 1, At, B1); PG8_BAR;
;             PG8_LDB(B0, 1, 0); PG8_SCHED; PG8_LDA(At, 1, 0); PG8_STAGE(PG8_SA(0, 1), a2 + hstep, voffA);
;             PG8_WAIT_L(8); PG8_BAR; PG8_WAIT_L(0); PG8_MMA(0, 0, At, B0); PG8_BAR; PG8_SCHED;
;             PG8_LDB(B1, 1, 1); PG8_STAGE(PG8_SB(1, 0), b3, voffB);
;             PG8_BAR; PG8_WAIT_L(0); PG8_MMA(0, 1, At, B1); PG8_BAR;
;             PG8_LDA(At, 1, 1); PG8_STAGE(PG8_SA(1, 0), a3, voffA);
;             PG8_BAR; PG8_WAIT_L(0); PG8_MMA(1, 0, At, B0); PG8_BAR; PG8_SCHED;
	s_setprio 1
	v_mfma_f32_16x16x32_bf16 v[52:55], v[176:179], v[144:147], 0
	v_mfma_f32_16x16x32_bf16 v[48:51], v[184:187], v[144:147], 0
	v_mfma_f32_16x16x32_bf16 v[36:39], v[176:179], v[152:155], 0
	v_mfma_f32_16x16x32_bf16 v[32:35], v[184:187], v[152:155], 0
	v_mfma_f32_16x16x32_bf16 v[20:23], v[176:179], v[160:163], 0
	v_mfma_f32_16x16x32_bf16 v[16:19], v[184:187], v[160:163], 0
	v_mfma_f32_16x16x32_bf16 v[4:7], v[176:179], v[168:171], 0
	v_mfma_f32_16x16x32_bf16 v[0:3], v[184:187], v[168:171], 0
	v_mfma_f32_16x16x32_bf16 v[52:55], v[180:183], v[148:151], v[52:55]
	v_mfma_f32_16x16x32_bf16 v[48:51], v[188:191], v[148:151], v[48:51]
	v_mfma_f32_16x16x32_bf16 v[36:39], v[180:183], v[156:159], v[36:39]
	v_mfma_f32_16x16x32_bf16 v[32:35], v[188:191], v[156:159], v[32:35]
	v_mfma_f32_16x16x32_bf16 v[20:23], v[180:183], v[164:167], v[20:23]
	v_mfma_f32_16x16x32_bf16 v[16:19], v[188:191], v[164:167], v[16:19]
	v_mfma_f32_16x16x32_bf16 v[4:7], v[180:183], v[172:175], v[4:7]
	v_mfma_f32_16x16x32_bf16 v[0:3], v[188:191], v[172:175], v[0:3]
	s_setprio 0
	s_add_i32 s59, 0, 0x18000
	v_add_u32_e32 v140, s59, v236
	s_barrier
	ds_read_b128 v[128:131], v140
	ds_read_b128 v[132:135], v140 offset:1024
	ds_read_b128 v[136:139], v140 offset:2048
	ds_read_b128 v[140:143], v140 offset:3072
	s_add_u32 s24, s30, 0x60000
	s_addc_u32 s25, s31, 0
	s_mov_b32 m0, s40
	ds_read_b128 v[144:147], v238 offset:32768
	ds_read_b128 v[148:151], v238 offset:33792
	ds_read_b128 v[152:155], v238 offset:34816
	ds_read_b128 v[156:159], v238 offset:35840
	ds_read_b128 v[160:163], v238 offset:36864
	ds_read_b128 v[164:167], v238 offset:37888
	ds_read_b128 v[168:171], v238 offset:38912
	ds_read_b128 v[172:175], v238 offset:39936
	global_load_lds_dwordx4 v202, s[24:25]
	s_mov_b32 m0, s41
	s_nop 0
	global_load_lds_dwordx4 v206, s[24:25]
	s_waitcnt lgkmcnt(8)
	s_barrier
	s_waitcnt lgkmcnt(0)
	s_setprio 1
	s_waitcnt lgkmcnt(0)
	v_mfma_f32_16x16x32_bf16 v[124:127], v[128:131], v[144:147], v[124:127]
	v_mfma_f32_16x16x32_bf16 v[120:123], v[136:139], v[144:147], v[120:123]
	v_mfma_f32_16x16x32_bf16 v[108:111], v[128:131], v[152:155], v[108:111]
	v_mfma_f32_16x16x32_bf16 v[104:107], v[136:139], v[152:155], v[104:107]
	v_mfma_f32_16x16x32_bf16 v[92:95], v[128:131], v[160:163], v[92:95]
	v_mfma_f32_16x16x32_bf16 v[88:91], v[136:139], v[160:163], v[88:91]
	v_mfma_f32_16x16x32_bf16 v[76:79], v[128:131], v[168:171], v[76:79]
	v_mfma_f32_16x16x32_bf16 v[72:75], v[136:139], v[168:171], v[72:75]
	v_mfma_f32_16x16x32_bf16 v[124:127], v[132:135], v[148:151], v[124:127]
	v_mfma_f32_16x16x32_bf16 v[120:123], v[140:143], v[148:151], v[120:123]
	v_mfma_f32_16x16x32_bf16 v[108:111], v[132:135], v[156:159], v[108:111]
	v_mfma_f32_16x16x32_bf16 v[104:107], v[140:143], v[156:159], v[104:107]
	v_mfma_f32_16x16x32_bf16 v[92:95], v[132:135], v[164:167], v[92:95]
	v_mfma_f32_16x16x32_bf16 v[88:91], v[140:143], v[164:167], v[88:91]
	v_mfma_f32_16x16x32_bf16 v[76:79], v[132:135], v[172:175], v[76:79]
	v_mfma_f32_16x16x32_bf16 v[72:75], v[140:143], v[172:175], v[72:75]
	s_setprio 0
	s_barrier
	s_add_i32 s30, 0, 0x1c000
	s_add_i32 s24, s59, s37
	v_add_u32_e32 v188, s30, v236
	s_add_u32 s0, s28, 0x80
	s_addc_u32 s1, s29, 0
	s_mov_b32 m0, s24
	ds_read_b128 v[176:179], v188
	ds_read_b128 v[180:183], v188 offset:1024
	ds_read_b128 v[184:187], v188 offset:2048
	ds_read_b128 v[188:191], v188 offset:3072
	global_load_lds_dwordx4 v204, s[0:1]
	s_add_i32 m0, s24, 0x2000
	s_nop 0
	global_load_lds_dwordx4 v208, s[0:1]
	s_barrier
	s_waitcnt lgkmcnt(0)
	s_setprio 1
	s_waitcnt lgkmcnt(0)
	v_mfma_f32_16x16x32_bf16 v[116:119], v[176:179], v[144:147], v[116:119]
	v_mfma_f32_16x16x32_bf16 v[112:115], v[184:187], v[144:147], v[112:115]
	v_mfma_f32_16x16x32_bf16 v[100:103], v[176:179], v[152:155], v[100:103]
	v_mfma_f32_16x16x32_bf16 v[96:99], v[184:187], v[152:155], v[96:99]
	v_mfma_f32_16x16x32_bf16 v[84:87], v[176:179], v[160:163], v[84:87]
	v_mfma_f32_16x16x32_bf16 v[80:83], v[184:187], v[160:163], v[80:83]
	v_mfma_f32_16x16x32_bf16 v[68:71], v[176:179], v[168:171], v[68:71]
	v_mfma_f32_16x16x32_bf16 v[64:67], v[184:187], v[168:171], v[64:67]
	v_mfma_f32_16x16x32_bf16 v[116:119], v[180:183], v[148:151], v[116:119]
	v_mfma_f32_16x16x32_bf16 v[112:115], v[188:191], v[148:151], v[112:115]
	v_mfma_f32_16x16x32_bf16 v[100:103], v[180:183], v[156:159], v[100:103]
	v_mfma_f32_16x16x32_bf16 v[96:99], v[188:191], v[156:159], v[96:99]
	v_mfma_f32_16x16x32_bf16 v[84:87], v[180:183], v[164:167], v[84:87]
	v_mfma_f32_16x16x32_bf16 v[80:83], v[188:191], v[164:167], v[80:83]
	v_mfma_f32_16x16x32_bf16 v[68:71], v[180:183], v[172:175], v[68:71]
	v_mfma_f32_16x16x32_bf16 v[64:67], v[188:191], v[172:175], v[64:67]
	s_setprio 0
	s_mov_b32 m0, s47
	s_mov_b64 s[0:1], 0x80
	v_lshl_add_u64 v[192:193], v[196:197], 0, s[0:1]
	s_barrier
	ds_read_b128 v[144:147], v238 offset:49152
	ds_read_b128 v[148:151], v238 offset:50176
	ds_read_b128 v[152:155], v238 offset:51200
	ds_read_b128 v[156:159], v238 offset:52224
	ds_read_b128 v[160:163], v238 offset:53248
	ds_read_b128 v[164:167], v238 offset:54272
	ds_read_b128 v[168:171], v238 offset:55296
	ds_read_b128 v[172:175], v238 offset:56320
	global_load_lds_dwordx4 v[192:193], off
	v_lshl_add_u64 v[192:193], v[198:199], 0, s[0:1]
	s_mov_b32 m0, s48
	s_nop 0
	global_load_lds_dwordx4 v[192:193], off
	s_barrier
; #define PG8_STAGE(bufoff, gbase, voff) do { _Pragma("unroll") for (int _i = 0; _i < 2; ++_i) \
;         __builtin_amdgcn_global_load_lds((const unsigned*)((const char*)(gbase) + (voff)[_i]), (LAS unsigned*)(lds + (bufoff) + ldsw + _i * 8192), 16, 0, 0); } while (0)
; #define PG8_LDA(dst, b, h) do { _Pragma("unroll") for (int m = 0; m < 4; ++m) _Pragma("unroll") for (int k = 0; k < 2; ++k) dst[m][k] = *(const LAS bf16x8*)(lds + PG8_SA(b, h) + aoff + m * 2048 + k * 1024); } while (0)
; #define PG8_WAIT_V(n) asm volatile("s_waitcnt vmcnt(" #n ")" ::: "memory")
; #define PG8_WAIT_L(n) asm volatile("s_waitcnt lgkmcnt(" #n ")" ::: "memory")
; template <class Epi, class Sched>
; __device__ __forceinline__ void gemm_phase(LAS unsigned char* lds, const Gemm g, const Sched& S, const Epi& E) {
;     ...
;         for (int t = 0; t < nt; t += 2) {
;             const bool last = (t == nt - 2);
;             const char* a1 = cA + (size_t)(t + 1) * kstep;
;             const char* a2 = last ? nA : cA + (size_t)(t + 2) * kstep; const char* b2 = last ? nB : cB + (size_t)(t + 2) * kstep;
;             const char* a3 = a2 + kstep; const char* b3 = b2 + kstep;
;             PG8_LDB(B0, 0, 0); PG8_SCHED; PG8_LDA(At, 0, 0); PG8_STAGE(PG8_SA(1, 1), a1 + hstep, voffA);
;             PG8_WAIT_L(8); PG8_BAR; PG8_WAIT_L(0); PG8_MMA(0, 0, At, B0); PG8_BAR; PG8_SCHED;
;             PG8_LDB(B1, 0, 1); PG8_STAGE(PG8_SB(0, 0), b2, voffB);
;             PG8_BAR; PG8_WAIT_L(0); PG8_MMA(0, 1, At, B1); PG8_BAR;
;             PG8_LDA(At, 0, 1); PG8_STAGE(PG8_SA(0, 0), a2, voffA);
;             PG8_BAR; PG8_WAIT_L(0); PG8_MMA(1, 0, At, B0); PG8_BAR; PG8_SCHED;
;             PG8_STAGE(PG8_SB(0, 1), b2 + hstep, voffB);
;             PG8_WAIT_V(6); PG8_BAR; PG8_MMA(1, 1, At, B1); PG8_BAR;
;             PG8_LDB(B0, 1, 0); PG8_SCHED; PG8_LDA(At, 1, 0); PG8_STAGE(PG8_SA(0, 1), a2 + hstep, voffA);
;             PG8_WAIT_L(8); PG8_BAR; PG8_WAIT_L(0); PG8_MMA(0, 0, At, B0); PG8_BAR; PG8_SCHED;
;             PG8_LDB(B1, 1, 1); PG8_STAGE(PG8_SB(1, 0), b3, voffB);
;             PG8_BAR; PG8_WAIT_L(0); PG8_MMA(0, 1, At, B1); PG8_BAR;
;             PG8_LDA(At, 1, 1); PG8_STAGE(PG8_SA(1, 0), a3, voffA);
;             PG8_BAR; PG8_WAIT_L(0); PG8_MMA(1, 0, At, B0); PG8_BAR; PG8_SCHED;
;             PG8_STAGE(PG8_SB(1, 1), b3 + hstep, voffB);
;             PG8_WAIT_V(6); PG8_BAR; PG8_MMA(1, 1, At, B1); PG8_BAR;
	s_waitcnt lgkmcnt(0)
	s_setprio 1
	s_waitcnt lgkmcnt(0)
	v_mfma_f32_16x16x32_bf16 v[60:63], v[128:131], v[144:147], v[60:63]
	v_mfma_f32_16x16x32_bf16 v[56:59], v[136:139], v[144:147], v[56:59]
	v_mfma_f32_16x16x32_bf16 v[44:47], v[128:131], v[152:155], v[44:47]
	v_mfma_f32_16x16x32_bf16 v[40:43], v[136:139], v[152:155], v[40:43]
	v_mfma_f32_16x16x32_bf16 v[28:31], v[128:131], v[160:163], v[28:31]
	v_mfma_f32_16x16x32_bf16 v[24:27], v[136:139], v[160:163], v[24:27]
	v_mfma_f32_16x16x32_bf16 v[12:15], v[128:131], v[168:171], v[12:15]
	v_mfma_f32_16x16x32_bf16 v[8:11], v[136:139], v[168:171], v[8:11]
	v_mfma_f32_16x16x32_bf16 v[60:63], v[132:135], v[148:151], v[60:63]
	v_mfma_f32_16x16x32_bf16 v[56:59], v[140:143], v[148:151], v[56:59]
	v_mfma_f32_16x16x32_bf16 v[44:47], v[132:135], v[156:159], v[44:47]
	v_mfma_f32_16x16x32_bf16 v[40:43], v[140:143], v[156:159], v[40:43]
	v_mfma_f32_16x16x32_bf16 v[28:31], v[132:135], v[164:167], v[28:31]
	v_mfma_f32_16x16x32_bf16 v[24:27], v[140:143], v[164:167], v[24:27]
	v_mfma_f32_16x16x32_bf16 v[12:15], v[132:135], v[172:175], v[12:15]
	v_mfma_f32_16x16x32_bf16 v[8:11], v[140:143], v[172:175], v[8:11]
	s_setprio 0
	s_barrier
	s_add_u32 s24, s28, 0x60080
	s_addc_u32 s25, s29, 0
	s_add_i32 s28, s30, s37
	s_mov_b32 m0, s28
	s_nop 0
	global_load_lds_dwordx4 v204, s[24:25]
	s_add_i32 m0, s28, 0x2000
	s_nop 0
	global_load_lds_dwordx4 v208, s[24:25]
	s_waitcnt vmcnt(6)
	s_barrier
	s_setprio 1
	v_mfma_f32_16x16x32_bf16 v[52:55], v[176:179], v[144:147], v[52:55]
	v_mfma_f32_16x16x32_bf16 v[48:51], v[184:187], v[144:147], v[48:51]
	v_mfma_f32_16x16x32_bf16 v[36:39], v[176:179], v[152:155], v[36:39]
	v_mfma_f32_16x16x32_bf16 v[32:35], v[184:187], v[152:155], v[32:35]
	v_mfma_f32_16x16x32_bf16 v[20:23], v[176:179], v[160:163], v[20:23]
	v_mfma_f32_16x16x32_bf16 v[16:19], v[184:187], v[160:163], v[16:19]
	v_mfma_f32_16x16x32_bf16 v[4:7], v[176:179], v[168:171], v[4:7]
	v_mfma_f32_16x16x32_bf16 v[0:3], v[184:187], v[168:171], v[0:3]
	v_mfma_f32_16x16x32_bf16 v[52:55], v[180:183], v[148:151], v[52:55]
	v_mfma_f32_16x16x32_bf16 v[48:51], v[188:191], v[148:151], v[48:51]
	v_mfma_f32_16x16x32_bf16 v[36:39], v[180:183], v[156:159], v[36:39]
	v_mfma_f32_16x16x32_bf16 v[32:35], v[188:191], v[156:159], v[32:35]
	v_mfma_f32_16x16x32_bf16 v[20:23], v[180:183], v[164:167], v[20:23]
	v_mfma_f32_16x16x32_bf16 v[16:19], v[188:191], v[164:167], v[16:19]
	v_mfma_f32_16x16x32_bf16 v[4:7], v[180:183], v[172:175], v[4:7]
	v_mfma_f32_16x16x32_bf16 v[0:3], v[188:191], v[172:175], v[0:3]
	s_setprio 0
	s_add_i32 s58, s58, 2
	s_add_u32 s56, s56, 0x100
	s_addc_u32 s57, s57, 0
	s_cmp_gt_u32 s58, 21
	s_mov_b64 s[24:25], s[26:27]
	s_barrier
.LBB0_902:
	ds_read_b128 v[128:131], v237
	ds_read_b128 v[132:135], v237 offset:1024
	ds_read_b128 v[136:139], v237 offset:2048
	ds_read_b128 v[140:143], v237 offset:3072
	s_add_u32 s26, s24, 0x100
	s_addc_u32 s27, s25, 0
	s_cmp_eq_u32 s58, 20
	s_cselect_b32 s31, s5, s27
	s_cselect_b32 s30, s4, s26
	s_cselect_b32 s29, s7, s57
	s_cselect_b32 s28, s6, s56
	v_lshl_add_u64 v[176:177], s[24:25], 0, v[210:211]
	s_add_i32 m0, s38, 0xc000
	ds_read_b128 v[144:147], v238
	ds_read_b128 v[148:151], v238 offset:1024
	ds_read_b128 v[152:155], v238 offset:2048
	ds_read_b128 v[156:159], v238 offset:3072
	ds_read_b128 v[160:163], v238 offset:4096
	ds_read_b128 v[164:167], v238 offset:5120
	ds_read_b128 v[168:171], v238 offset:6144
	ds_read_b128 v[172:175], v238 offset:7168
	global_load_lds_dwordx4 v[176:177], off
	v_lshl_add_u64 v[176:177], s[24:25], 0, v[212:213]
	s_add_i32 m0, s38, 0xe000
	s_nop 0
	global_load_lds_dwordx4 v[176:177], off
	s_waitcnt lgkmcnt(8)
	s_barrier
	s_waitcnt lgkmcnt(0)
	s_setprio 1
	s_waitcnt lgkmcnt(0)
	v_mfma_f32_16x16x32_bf16 v[124:127], v[128:131], v[144:147], v[124:127]
	v_mfma_f32_16x16x32_bf16 v[120:123], v[136:139], v[144:147], v[120:123]
	v_mfma_f32_16x16x32_bf16 v[108:111], v[128:131], v[152:155], v[108:111]
	v_mfma_f32_16x16x32_bf16 v[104:107], v[136:139], v[152:155], v[104:107]
	v_mfma_f32_16x16x32_bf16 v[92:95], v[128:131], v[160:163], v[92:95]
	v_mfma_f32_16x16x32_bf16 v[88:91], v[136:139], v[160:163], v[88:91]
	v_mfma_f32_16x16x32_bf16 v[76:79], v[128:131], v[168:171], v[76:79]
	v_mfma_f32_16x16x32_bf16 v[72:75], v[136:139], v[168:171], v[72:75]
	v_mfma_f32_16x16x32_bf16 v[124:127], v[132:135], v[148:151], v[124:127]
	v_mfma_f32_16x16x32_bf16 v[120:123], v[140:143], v[148:151], v[120:123]
	v_mfma_f32_16x16x32_bf16 v[108:111], v[132:135], v[156:159], v[108:111]
	v_mfma_f32_16x16x32_bf16 v[104:107], v[140:143], v[156:159], v[104:107]
	v_mfma_f32_16x16x32_bf16 v[92:95], v[132:135], v[164:167], v[92:95]
	v_mfma_f32_16x16x32_bf16 v[88:91], v[140:143], v[164:167], v[88:91]
	v_mfma_f32_16x16x32_bf16 v[76:79], v[132:135], v[172:175], v[76:79]
	v_mfma_f32_16x16x32_bf16 v[72:75], v[140:143], v[172:175], v[72:75]
	s_setprio 0
	s_barrier
	s_add_i32 s24, s50, s37
	s_mov_b32 m0, s24
	ds_read_b128 v[176:179], v239
	ds_read_b128 v[180:183], v239 offset:1024
	ds_read_b128 v[184:187], v239 offset:2048
	ds_read_b128 v[188:191], v239 offset:3072
	global_load_lds_dwordx4 v204, s[28:29]
	s_add_i32 m0, s24, 0x2000
	s_nop 0
	global_load_lds_dwordx4 v208, s[28:29]
	s_barrier
; #define PG8_STAGE(bufoff, gbase, voff) do { _Pragma("unroll") for (int _i = 0; _i < 2; ++_i) \
;         __builtin_amdgcn_global_load_lds((const unsigned*)((const char*)(gbase) + (voff)[_i]), (LAS unsigned*)(lds + (bufoff) + ldsw + _i * 8192), 16, 0, 0); } while (0)
; #define PG8_LDA(dst, b, h) do { _Pragma("unroll") for (int m = 0; m < 4; ++m) _Pragma("unroll") for (int k = 0; k < 2; ++k) dst[m][k] = *(const LAS bf16x8*)(lds + PG8_SA(b, h) + aoff + m * 2048 + k * 1024); } while (0)
; #define PG8_LDB(dst, b, h) do { _Pragma("unroll") for (int n = 0; n < 2; ++n) _Pragma("unroll") for (int k = 0; k < 2; ++k) dst[n][k] = *(const LAS bf16x8*)(lds + PG8_SB(b, h) + boff + n * 2048 + k * 1024); } while (0)
; #define PG8_MMA(ai, bj, At, Bt) do { __builtin_amdgcn_s_setprio(1); _Pragma("unroll") for (int m = 0; m < 4; ++m) _Pragma("unroll") for (int n = 0; n < 2; ++n) _Pragma("unroll") for (int k = 0; k < 2; ++k) \
;         acc[ai][bj][m][n] = __builtin_amdgcn_mfma_f32_16x16x32_bf16(Bt[n][k], At[m][k], acc[ai][bj][m][n], 0, 0, 0); __builtin_amdgcn_s_setprio(0); } while (0)
; #define PG8_WAIT_V(n) asm volatile("s_waitcnt vmcnt(" #n ")" ::: "memory")
; #define PG8_WAIT_L(n) asm volatile("s_waitcnt lgkmcnt(" #n ")" ::: "memory")
; #define PG8_BAR __builtin_amdgcn_s_barrier()
; #define PG8_SCHED __builtin_amdgcn_sched_barrier(0)
; template <class Epi, class Sched>
; __device__ __forceinline__ void gemm_phase(LAS unsigned char* lds, const Gemm g, const Sched& S, const Epi& E) {
;     ...
;             PG8_BAR; PG8_WAIT_L(0); PG8_MMA(0, 1, At, B1); PG8_BAR;
;             PG8_LDA(At, 0, 1); PG8_STAGE(PG8_SA(0, 0), a2, voffA);
;             PG8_BAR; PG8_WAIT_L(0); PG8_MMA(1, 0, At, B0); PG8_BAR; PG8_SCHED;
;             PG8_STAGE(PG8_SB(0, 1), b2 + hstep, voffB);
;             PG8_WAIT_V(6); PG8_BAR; PG8_MMA(1, 1, At, B1); PG8_BAR;
;             PG8_LDB(B0, 1, 0); PG8_SCHED; PG8_LDA(At, 1, 0); PG8_STAGE(PG8_SA(0, 1), a2 + hstep, voffA);
;             PG8_WAIT_L(8); PG8_BAR; PG8_WAIT_L(0); PG8_MMA(0, 0, At, B0); PG8_BAR; PG8_SCHED;
	s_waitcnt lgkmcnt(0)
	s_setprio 1
	s_waitcnt lgkmcnt(0)
	v_mfma_f32_16x16x32_bf16 v[116:119], v[176:179], v[144:147], v[116:119]
	v_mfma_f32_16x16x32_bf16 v[112:115], v[184:187], v[144:147], v[112:115]
	v_mfma_f32_16x16x32_bf16 v[100:103], v[176:179], v[152:155], v[100:103]
	v_mfma_f32_16x16x32_bf16 v[96:99], v[184:187], v[152:155], v[96:99]
	v_mfma_f32_16x16x32_bf16 v[84:87], v[176:179], v[160:163], v[84:87]
	v_mfma_f32_16x16x32_bf16 v[80:83], v[184:187], v[160:163], v[80:83]
	v_mfma_f32_16x16x32_bf16 v[68:71], v[176:179], v[168:171], v[68:71]
	v_mfma_f32_16x16x32_bf16 v[64:67], v[184:187], v[168:171], v[64:67]
	v_mfma_f32_16x16x32_bf16 v[116:119], v[180:183], v[148:151], v[116:119]
	v_mfma_f32_16x16x32_bf16 v[112:115], v[188:191], v[148:151], v[112:115]
	v_mfma_f32_16x16x32_bf16 v[100:103], v[180:183], v[156:159], v[100:103]
	v_mfma_f32_16x16x32_bf16 v[96:99], v[188:191], v[156:159], v[96:99]
	v_mfma_f32_16x16x32_bf16 v[84:87], v[180:183], v[164:167], v[84:87]
	v_mfma_f32_16x16x32_bf16 v[80:83], v[188:191], v[164:167], v[80:83]
	v_mfma_f32_16x16x32_bf16 v[68:71], v[180:183], v[172:175], v[68:71]
	v_mfma_f32_16x16x32_bf16 v[64:67], v[188:191], v[172:175], v[64:67]
	s_setprio 0
	s_mov_b32 m0, s38
	v_lshl_add_u64 v[196:197], s[30:31], 0, v[202:203]
	s_barrier
	ds_read_b128 v[144:147], v238 offset:16384
	ds_read_b128 v[148:151], v238 offset:17408
	ds_read_b128 v[152:155], v238 offset:18432
	ds_read_b128 v[156:159], v238 offset:19456
	ds_read_b128 v[160:163], v238 offset:20480
	ds_read_b128 v[164:167], v238 offset:21504
	ds_read_b128 v[168:171], v238 offset:22528
	ds_read_b128 v[172:175], v238 offset:23552
	global_load_lds_dwordx4 v202, s[30:31]
	v_lshl_add_u64 v[198:199], s[30:31], 0, v[206:207]
	s_mov_b32 m0, s39
	s_nop 0
	global_load_lds_dwordx4 v206, s[30:31]
	s_barrier
	s_waitcnt lgkmcnt(0)
	s_setprio 1
	s_waitcnt lgkmcnt(0)
	v_mfma_f32_16x16x32_bf16 v[60:63], v[128:131], v[144:147], v[60:63]
	v_mfma_f32_16x16x32_bf16 v[56:59], v[136:139], v[144:147], v[56:59]
	v_mfma_f32_16x16x32_bf16 v[44:47], v[128:131], v[152:155], v[44:47]
	v_mfma_f32_16x16x32_bf16 v[40:43], v[136:139], v[152:155], v[40:43]
	v_mfma_f32_16x16x32_bf16 v[28:31], v[128:131], v[160:163], v[28:31]
	v_mfma_f32_16x16x32_bf16 v[24:27], v[136:139], v[160:163], v[24:27]
	v_mfma_f32_16x16x32_bf16 v[12:15], v[128:131], v[168:171], v[12:15]
	v_mfma_f32_16x16x32_bf16 v[8:11], v[136:139], v[168:171], v[8:11]
	v_mfma_f32_16x16x32_bf16 v[60:63], v[132:135], v[148:151], v[60:63]
	v_mfma_f32_16x16x32_bf16 v[56:59], v[140:143], v[148:151], v[56:59]
	v_mfma_f32_16x16x32_bf16 v[44:47], v[132:135], v[156:159], v[44:47]
	v_mfma_f32_16x16x32_bf16 v[40:43], v[140:143], v[156:159], v[40:43]
	v_mfma_f32_16x16x32_bf16 v[28:31], v[132:135], v[164:167], v[28:31]
	v_mfma_f32_16x16x32_bf16 v[24:27], v[140:143], v[164:167], v[24:27]
	v_mfma_f32_16x16x32_bf16 v[12:15], v[132:135], v[172:175], v[12:15]
	v_mfma_f32_16x16x32_bf16 v[8:11], v[140:143], v[172:175], v[8:11]
	s_setprio 0
	s_barrier
	s_add_u32 s24, s28, 0x60000
	s_addc_u32 s25, s29, 0
	s_add_i32 s59, s51, s37
	s_mov_b32 m0, s59
	s_nop 0
	global_load_lds_dwordx4 v204, s[24:25]
	s_add_i32 m0, s59, 0x2000
	s_nop 0
	global_load_lds_dwordx4 v208, s[24:25]
	s_waitcnt vmcnt(6)
	s_barrier
	s_setprio 1
	v_mfma_f32_16x16x32_bf16 v[52:55], v[176:179], v[144:147], v[52:55]
	v_mfma_f32_16x16x32_bf16 v[48:51], v[184:187], v[144:147], v[48:51]
	v_mfma_f32_16x16x32_bf16 v[36:39], v[176:179], v[152:155], v[36:39]
	v_mfma_f32_16x16x32_bf16 v[32:35], v[184:187], v[152:155], v[32:35]
	v_mfma_f32_16x16x32_bf16 v[20:23], v[176:179], v[160:163], v[20:23]
	v_mfma_f32_16x16x32_bf16 v[16:19], v[184:187], v[160:163], v[16:19]
	v_mfma_f32_16x16x32_bf16 v[4:7], v[176:179], v[168:171], v[4:7]
	v_mfma_f32_16x16x32_bf16 v[0:3], v[184:187], v[168:171], v[0:3]
	v_mfma_f32_16x16x32_bf16 v[52:55], v[180:183], v[148:151], v[52:55]
	v_mfma_f32_16x16x32_bf16 v[48:51], v[188:191], v[148:151], v[48:51]
	v_mfma_f32_16x16x32_bf16 v[36:39], v[180:183], v[156:159], v[36:39]
	v_mfma_f32_16x16x32_bf16 v[32:35], v[188:191], v[156:159], v[32:35]
	v_mfma_f32_16x16x32_bf16 v[20:23], v[180:183], v[164:167], v[20:23]
	v_mfma_f32_16x16x32_bf16 v[16:19], v[188:191], v[164:167], v[16:19]
	v_mfma_f32_16x16x32_bf16 v[4:7], v[180:183], v[172:175], v[4:7]
	v_mfma_f32_16x16x32_bf16 v[0:3], v[188:191], v[172:175], v[0:3]
	s_setprio 0
	s_add_i32 s59, 0, 0x18000
	v_add_u32_e32 v140, s59, v236
	s_barrier
	ds_read_b128 v[128:131], v140
	ds_read_b128 v[132:135], v140 offset:1024
	ds_read_b128 v[136:139], v140 offset:2048
	ds_read_b128 v[140:143], v140 offset:3072
	s_add_u32 s24, s30, 0x60000
	s_addc_u32 s25, s31, 0
	s_mov_b32 m0, s40
	ds_read_b128 v[144:147], v238 offset:32768
	ds_read_b128 v[148:151], v238 offset:33792
	ds_read_b128 v[152:155], v238 offset:34816
	ds_read_b128 v[156:159], v238 offset:35840
	ds_read_b128 v[160:163], v238 offset:36864
	ds_read_b128 v[164:167], v238 offset:37888
	ds_read_b128 v[168:171], v238 offset:38912
	ds_read_b128 v[172:175], v238 offset:39936
	global_load_lds_dwordx4 v202, s[24:25]
	s_mov_b32 m0, s41
	s_nop 0
	global_load_lds_dwordx4 v206, s[24:25]
	s_waitcnt lgkmcnt(8)
	s_barrier
; #define PG8_STAGE(bufoff, gbase, voff) do { _Pragma("unroll") for (int _i = 0; _i < 2; ++_i) \
;         __builtin_amdgcn_global_load_lds((const unsigned*)((const char*)(gbase) + (voff)[_i]), (LAS unsigned*)(lds + (bufoff) + ldsw + _i * 8192), 16, 0, 0); } while (0)
; #define PG8_LDA(dst, b, h) do { _Pragma("unroll") for (int m = 0; m < 4; ++m) _Pragma("unroll") for (int k = 0; k < 2; ++k) dst[m][k] = *(const LAS bf16x8*)(lds + PG8_SA(b, h) + aoff + m * 2048 + k * 1024); } while (0)
; #define PG8_LDB(dst, b, h) do { _Pragma("unroll") for (int n = 0; n < 2; ++n) _Pragma("unroll") for (int k = 0; k < 2; ++k) dst[n][k] = *(const LAS bf16x8*)(lds + PG8_SB(b, h) + boff + n * 2048 + k * 1024); } while (0)
; #define PG8_MMA(ai, bj, At, Bt) do { __builtin_amdgcn_s_setprio(1); _Pragma("unroll") for (int m = 0; m < 4; ++m) _Pragma("unroll") for (int n = 0; n < 2; ++n) _Pragma("unroll") for (int k = 0; k < 2; ++k) \
;         acc[ai][bj][m][n] = __builtin_amdgcn_mfma_f32_16x16x32_bf16(Bt[n][k], At[m][k], acc[ai][bj][m][n], 0, 0, 0); __builtin_amdgcn_s_setprio(0); } while (0)
; #define PG8_WAIT_V(n) asm volatile("s_waitcnt vmcnt(" #n ")" ::: "memory")
; #define PG8_WAIT_L(n) asm volatile("s_waitcnt lgkmcnt(" #n ")" ::: "memory")
; #define PG8_BAR __builtin_amdgcn_s_barrier()
; #define PG8_SCHED __builtin_amdgcn_sched_barrier(0)
; template <class Epi, class Sched>
; __device__ __forceinline__ void gemm_phase(LAS unsigned char* lds, const Gemm g, const Sched& S, const Epi& E) {
;     ...
;             PG8_WAIT_L(8); PG8_BAR; PG8_WAIT_L(0); PG8_MMA(0, 0, At, B0); PG8_BAR; PG8_SCHED;
;             PG8_LDB(B1, 1, 1); PG8_STAGE(PG8_SB(1, 0), b3, voffB);
;             PG8_BAR; PG8_WAIT_L(0); PG8_MMA(0, 1, At, B1); PG8_BAR;
;             PG8_LDA(At, 1, 1); PG8_STAGE(PG8_SA(1, 0), a3, voffA);
;             PG8_BAR; PG8_WAIT_L(0); PG8_MMA(1, 0, At, B0); PG8_BAR; PG8_SCHED;
;             PG8_STAGE(PG8_SB(1, 1), b3 + hstep, voffB);
;             PG8_WAIT_V(6); PG8_BAR; PG8_MMA(1, 1, At, B1); PG8_BAR;
	s_waitcnt lgkmcnt(0)
	s_setprio 1
	s_waitcnt lgkmcnt(0)
	v_mfma_f32_16x16x32_bf16 v[124:127], v[128:131], v[144:147], v[124:127]
	v_mfma_f32_16x16x32_bf16 v[120:123], v[136:139], v[144:147], v[120:123]
	v_mfma_f32_16x16x32_bf16 v[108:111], v[128:131], v[152:155], v[108:111]
	v_mfma_f32_16x16x32_bf16 v[104:107], v[136:139], v[152:155], v[104:107]
	v_mfma_f32_16x16x32_bf16 v[92:95], v[128:131], v[160:163], v[92:95]
	v_mfma_f32_16x16x32_bf16 v[88:91], v[136:139], v[160:163], v[88:91]
	v_mfma_f32_16x16x32_bf16 v[76:79], v[128:131], v[168:171], v[76:79]
	v_mfma_f32_16x16x32_bf16 v[72:75], v[136:139], v[168:171], v[72:75]
	v_mfma_f32_16x16x32_bf16 v[124:127], v[132:135], v[148:151], v[124:127]
	v_mfma_f32_16x16x32_bf16 v[120:123], v[140:143], v[148:151], v[120:123]
	v_mfma_f32_16x16x32_bf16 v[108:111], v[132:135], v[156:159], v[108:111]
	v_mfma_f32_16x16x32_bf16 v[104:107], v[140:143], v[156:159], v[104:107]
	v_mfma_f32_16x16x32_bf16 v[92:95], v[132:135], v[164:167], v[92:95]
	v_mfma_f32_16x16x32_bf16 v[88:91], v[140:143], v[164:167], v[88:91]
	v_mfma_f32_16x16x32_bf16 v[76:79], v[132:135], v[172:175], v[76:79]
	v_mfma_f32_16x16x32_bf16 v[72:75], v[140:143], v[172:175], v[72:75]
	s_setprio 0
	s_barrier
	s_add_i32 s30, 0, 0x1c000
	s_add_i32 s24, s59, s37
	v_add_u32_e32 v188, s30, v236
	s_add_u32 s0, s28, 0x80
	s_addc_u32 s1, s29, 0
	s_mov_b32 m0, s24
	ds_read_b128 v[176:179], v188
	ds_read_b128 v[180:183], v188 offset:1024
	ds_read_b128 v[184:187], v188 offset:2048
	ds_read_b128 v[188:191], v188 offset:3072
	global_load_lds_dwordx4 v204, s[0:1]
	s_add_i32 m0, s24, 0x2000
	s_nop 0
	global_load_lds_dwordx4 v208, s[0:1]
	s_barrier
	s_waitcnt lgkmcnt(0)
	s_setprio 1
	s_waitcnt lgkmcnt(0)
	v_mfma_f32_16x16x32_bf16 v[116:119], v[176:179], v[144:147], v[116:119]
	v_mfma_f32_16x16x32_bf16 v[112:115], v[184:187], v[144:147], v[112:115]
	v_mfma_f32_16x16x32_bf16 v[100:103], v[176:179], v[152:155], v[100:103]
	v_mfma_f32_16x16x32_bf16 v[96:99], v[184:187], v[152:155], v[96:99]
	v_mfma_f32_16x16x32_bf16 v[84:87], v[176:179], v[160:163], v[84:87]
	v_mfma_f32_16x16x32_bf16 v[80:83], v[184:187], v[160:163], v[80:83]
	v_mfma_f32_16x16x32_bf16 v[68:71], v[176:179], v[168:171], v[68:71]
	v_mfma_f32_16x16x32_bf16 v[64:67], v[184:187], v[168:171], v[64:67]
	v_mfma_f32_16x16x32_bf16 v[116:119], v[180:183], v[148:151], v[116:119]
	v_mfma_f32_16x16x32_bf16 v[112:115], v[188:191], v[148:151], v[112:115]
	v_mfma_f32_16x16x32_bf16 v[100:103], v[180:183], v[156:159], v[100:103]
	v_mfma_f32_16x16x32_bf16 v[96:99], v[188:191], v[156:159], v[96:99]
	v_mfma_f32_16x16x32_bf16 v[84:87], v[180:183], v[164:167], v[84:87]
	v_mfma_f32_16x16x32_bf16 v[80:83], v[188:191], v[164:167], v[80:83]
	v_mfma_f32_16x16x32_bf16 v[68:71], v[180:183], v[172:175], v[68:71]
	v_mfma_f32_16x16x32_bf16 v[64:67], v[188:191], v[172:175], v[64:67]
	s_setprio 0
	s_mov_b32 m0, s47
	s_mov_b64 s[0:1], 0x80
	v_lshl_add_u64 v[192:193], v[196:197], 0, s[0:1]
	s_barrier
	ds_read_b128 v[144:147], v238 offset:49152
	ds_read_b128 v[148:151], v238 offset:50176
	ds_read_b128 v[152:155], v238 offset:51200
	ds_read_b128 v[156:159], v238 offset:52224
	ds_read_b128 v[160:163], v238 offset:53248
	ds_read_b128 v[164:167], v238 offset:54272
	ds_read_b128 v[168:171], v238 offset:55296
	ds_read_b128 v[172:175], v238 offset:56320
	global_load_lds_dwordx4 v[192:193], off
	v_lshl_add_u64 v[192:193], v[198:199], 0, s[0:1]
	s_mov_b32 m0, s48
	s_nop 0
	global_load_lds_dwordx4 v[192:193], off
	s_barrier
	s_waitcnt lgkmcnt(0)
	s_setprio 1
	s_waitcnt lgkmcnt(0)
	v_mfma_f32_16x16x32_bf16 v[60:63], v[128:131], v[144:147], v[60:63]
	v_mfma_f32_16x16x32_bf16 v[56:59], v[136:139], v[144:147], v[56:59]
	v_mfma_f32_16x16x32_bf16 v[44:47], v[128:131], v[152:155], v[44:47]
	v_mfma_f32_16x16x32_bf16 v[40:43], v[136:139], v[152:155], v[40:43]
	v_mfma_f32_16x16x32_bf16 v[28:31], v[128:131], v[160:163], v[28:31]
	v_mfma_f32_16x16x32_bf16 v[24:27], v[136:139], v[160:163], v[24:27]
	v_mfma_f32_16x16x32_bf16 v[12:15], v[128:131], v[168:171], v[12:15]
	v_mfma_f32_16x16x32_bf16 v[8:11], v[136:139], v[168:171], v[8:11]
	v_mfma_f32_16x16x32_bf16 v[60:63], v[132:135], v[148:151], v[60:63]
	v_mfma_f32_16x16x32_bf16 v[56:59], v[140:143], v[148:151], v[56:59]
	v_mfma_f32_16x16x32_bf16 v[44:47], v[132:135], v[156:159], v[44:47]
	v_mfma_f32_16x16x32_bf16 v[40:43], v[140:143], v[156:159], v[40:43]
	v_mfma_f32_16x16x32_bf16 v[28:31], v[132:135], v[164:167], v[28:31]
	v_mfma_f32_16x16x32_bf16 v[24:27], v[140:143], v[164:167], v[24:27]
	v_mfma_f32_16x16x32_bf16 v[12:15], v[132:135], v[172:175], v[12:15]
	v_mfma_f32_16x16x32_bf16 v[8:11], v[140:143], v[172:175], v[8:11]
	s_setprio 0
	s_barrier
	s_add_u32 s24, s28, 0x60080
	s_addc_u32 s25, s29, 0
	s_add_i32 s28, s30, s37
	s_mov_b32 m0, s28
	s_nop 0
	global_load_lds_dwordx4 v204, s[24:25]
	s_add_i32 m0, s28, 0x2000
	s_nop 0
	global_load_lds_dwordx4 v208, s[24:25]
	s_waitcnt vmcnt(6)
	s_barrier
	s_setprio 1
	v_mfma_f32_16x16x32_bf16 v[52:55], v[176:179], v[144:147], v[52:55]
	v_mfma_f32_16x16x32_bf16 v[48:51], v[184:187], v[144:147], v[48:51]
	v_mfma_f32_16x16x32_bf16 v[36:39], v[176:179], v[152:155], v[36:39]
	v_mfma_f32_16x16x32_bf16 v[32:35], v[184:187], v[152:155], v[32:35]
	v_mfma_f32_16x16x32_bf16 v[20:23], v[176:179], v[160:163], v[20:23]
	v_mfma_f32_16x16x32_bf16 v[16:19], v[184:187], v[160:163], v[16:19]
	v_mfma_f32_16x16x32_bf16 v[4:7], v[176:179], v[168:171], v[4:7]
	v_mfma_f32_16x16x32_bf16 v[0:3], v[184:187], v[168:171], v[0:3]
	v_mfma_f32_16x16x32_bf16 v[52:55], v[180:183], v[148:151], v[52:55]
	v_mfma_f32_16x16x32_bf16 v[48:51], v[188:191], v[148:151], v[48:51]
	v_mfma_f32_16x16x32_bf16 v[36:39], v[180:183], v[156:159], v[36:39]
	v_mfma_f32_16x16x32_bf16 v[32:35], v[188:191], v[156:159], v[32:35]
	v_mfma_f32_16x16x32_bf16 v[20:23], v[180:183], v[164:167], v[20:23]
	v_mfma_f32_16x16x32_bf16 v[16:19], v[188:191], v[164:167], v[16:19]
	v_mfma_f32_16x16x32_bf16 v[4:7], v[180:183], v[172:175], v[4:7]
	v_mfma_f32_16x16x32_bf16 v[0:3], v[188:191], v[172:175], v[0:3]
	s_setprio 0
	s_add_i32 s58, s58, 2
	s_add_u32 s56, s56, 0x100
	s_addc_u32 s57, s57, 0
	s_cmp_gt_u32 s58, 21
	s_mov_b64 s[24:25], s[26:27]
	s_barrier
; __device__ __forceinline__ unsigned cvt_pk_bf16(float lo, float hi) { unsigned r; asm volatile("v_cvt_pk_bf16_f32 %0, %1, %2" : "=v"(r) : "v"(lo), "v"(hi)); return r; }
; __device__ __forceinline__ float bf_lo(unsigned u) { return __uint_as_float(u << 16); }
; __device__ __forceinline__ float bf_hi(unsigned u) { return __uint_as_float(u & 0xffff0000u); }
;     __device__ __forceinline__ void operator()(const AccT& acc, const Unit& u, int wr, int wc, int fr, int fq) const {
;         asm volatile("" : "+v"(fr), "+v"(fq));
;         const int rowt = u.pm * 256; const int b = rowt >> 11;
;         const bf16_t* res = res_b + (size_t)rowt * DM; bf16_t* out = hb + (size_t)rowt * DM;
;         const int col0 = u.pn * 256 + wc * 32 + 8 * fq;
;         f32x4 gv[2][2];
; #pragma unroll
;         for (int bj = 0; bj < 2; ++bj)
; #pragma unroll
;             for (int n = 0; n < 2; ++n) gv[bj][n] = *(const f32x4*)(gate + (size_t)b * NMOD + col0 + bj * 128 + n * 4) * gs;
;         u32x4 r[2][4][2];
; #pragma unroll
;         for (int ai = 0; ai < 2; ++ai)
; #pragma unroll
;             for (int m = 0; m < 4; ++m)
; #pragma unroll
;                 for (int bj = 0; bj < 2; ++bj) r[ai][m][bj] = *(const u32x4*)(res + (size_t)(wr * 64 + fr + ai * 128 + m * 16) * DM + col0 + bj * 128);
; #pragma unroll
;         for (int ai = 0; ai < 2; ++ai)
; #pragma unroll
;             for (int m = 0; m < 4; ++m)
; #pragma unroll
;                 for (int bj = 0; bj < 2; ++bj) {
;                     const u32x4 q = r[ai][m][bj];
;                     const f32x4 r0 = {bf_lo(q.x), bf_hi(q.x), bf_lo(q.y), bf_hi(q.y)}, r1 = {bf_lo(q.z), bf_hi(q.z), bf_lo(q.w), bf_hi(q.w)};
;                     const f32x4 h0 = r0 + gv[bj][0] * acc[ai][bj][m][0], h1 = r1 + gv[bj][1] * acc[ai][bj][m][1];
;                     u32x4 w; w.x = cvt_pk_bf16(h0[0], h0[1]); w.y = cvt_pk_bf16(h0[2], h0[3]); w.z = cvt_pk_bf16(h1[0], h1[1]); w.w = cvt_pk_bf16(h1[2], h1[3]);
;                     *(u32x4*)(out + (size_t)(wr * 64 + fr + ai * 128 + m * 16) * DM + col0 + bj * 128) = w;
;                 }
;     }
	s_cbranch_scc0 .LBB0_902
	s_lshl_b32 s27, s55, 8
	v_mov_b32_e32 v146, v235
	v_mov_b32_e32 v128, v234
	s_lshl_b32 s24, s54, 8
	s_ashr_i32 s26, s54, 3
	s_or_b32 s27, s27, s46
	s_ashr_i32 s25, s24, 31
	v_lshl_add_u32 v144, v128, 3, s27
	s_mul_hi_i32 s27, s26, 0x9000
	s_mul_i32 s26, s26, 0x9000
	s_add_u32 s26, s43, s26
	s_addc_u32 s27, s44, s27
	v_ashrrev_i32_e32 v145, 31, v144
	s_lshl_b64 s[24:25], s[24:25], 11
	v_lshl_add_u64 v[132:133], v[144:145], 2, s[26:27]
	s_add_u32 s26, s62, s24
	v_add_u32_e32 v146, s45, v146
	s_addc_u32 s27, s63, s25
	v_lshlrev_b64 v[222:223], 1, v[144:145]
	v_ashrrev_i32_e32 v147, 31, v146
	v_lshl_add_u64 v[144:145], s[26:27], 0, v[222:223]
	v_lshlrev_b64 v[248:249], 11, v[146:147]
	v_lshl_add_u64 v[146:147], v[144:145], 0, v[248:249]
	global_load_dwordx4 v[136:139], v[132:133], off offset:16
	global_load_dwordx4 v[140:143], v[132:133], off
	global_load_dwordx4 v[128:131], v[132:133], off offset:528
	s_nop 0
	global_load_dwordx4 v[132:135], v[132:133], off offset:512
	s_nop 0
	global_load_dwordx4 v[240:243], v[146:147], off
	global_load_dwordx4 v[244:247], v[146:147], off offset:256
	v_lshl_add_u64 v[232:233], v[248:249], 0, s[10:11]
	v_lshl_add_u64 v[146:147], v[144:145], 0, v[232:233]
	global_load_dwordx4 v[196:199], v[146:147], off
	global_load_dwordx4 v[192:195], v[146:147], off offset:256
	v_lshl_add_u64 v[230:231], v[248:249], 0, s[12:13]
	v_lshl_add_u64 v[146:147], v[144:145], 0, v[230:231]
	global_load_dwordx4 v[188:191], v[146:147], off
	global_load_dwordx4 v[184:187], v[146:147], off offset:256
	v_lshl_add_u64 v[228:229], v[248:249], 0, s[14:15]
	v_lshl_add_u64 v[146:147], v[144:145], 0, v[228:229]
	global_load_dwordx4 v[180:183], v[146:147], off
	global_load_dwordx4 v[176:179], v[146:147], off offset:256
	v_lshl_add_u64 v[226:227], v[248:249], 0, s[16:17]
	v_lshl_add_u64 v[146:147], v[144:145], 0, v[226:227]
	global_load_dwordx4 v[172:175], v[146:147], off
	global_load_dwordx4 v[168:171], v[146:147], off offset:256
	v_lshl_add_u64 v[224:225], v[248:249], 0, s[18:19]
	v_lshl_add_u64 v[146:147], v[144:145], 0, v[224:225]
	global_load_dwordx4 v[164:167], v[146:147], off
	global_load_dwordx4 v[160:163], v[146:147], off offset:256
	v_lshl_add_u64 v[220:221], v[248:249], 0, s[20:21]
	v_lshl_add_u64 v[146:147], v[144:145], 0, v[220:221]
	global_load_dwordx4 v[156:159], v[146:147], off
	global_load_dwordx4 v[152:155], v[146:147], off offset:256
	v_lshl_add_u64 v[218:219], v[248:249], 0, s[22:23]
	v_lshl_add_u64 v[144:145], v[144:145], 0, v[218:219]
	global_load_dwordx4 v[148:151], v[144:145], off
	s_nop 0
	global_load_dwordx4 v[144:147], v[144:145], off offset:256
	s_add_u32 s24, s80, s24
	s_addc_u32 s25, s81, s25
	v_lshl_add_u64 v[222:223], s[24:25], 0, v[222:223]
	v_lshl_add_u64 v[248:249], v[222:223], 0, v[248:249]
	s_and_b64 vcc, exec, s[2:3]
	s_mov_b32 s55, s52
	s_mov_b32 s54, s53
	s_mov_b64 s[26:27], s[6:7]
	s_mov_b64 s[24:25], s[4:5]
	s_waitcnt vmcnt(0)
	v_lshlrev_b32_e32 v250, 16, v240
	v_and_b32_e32 v251, 0xffff0000, v240
	v_lshlrev_b32_e32 v240, 16, v241
	v_and_b32_e32 v241, 0xffff0000, v241
	v_lshlrev_b32_e32 v252, 16, v242
	v_and_b32_e32 v253, 0xffff0000, v242
	v_lshlrev_b32_e32 v242, 16, v243
	v_and_b32_e32 v243, 0xffff0000, v243
	v_pk_fma_f32 v[126:127], v[126:127], v[142:143], v[240:241]
	v_pk_fma_f32 v[124:125], v[124:125], v[140:141], v[250:251]
	v_pk_fma_f32 v[240:241], v[122:123], v[138:139], v[242:243]
	v_pk_fma_f32 v[122:123], v[120:121], v[136:137], v[252:253]
	v_cvt_pk_bf16_f32 v120, v124, v125
	v_cvt_pk_bf16_f32 v121, v126, v127
	v_lshlrev_b32_e32 v124, 16, v246
	v_cvt_pk_bf16_f32 v122, v122, v123
	v_cvt_pk_bf16_f32 v123, v240, v241
	global_store_dwordx4 v[248:249], v[120:123], off
	v_and_b32_e32 v125, 0xffff0000, v246
	v_lshlrev_b32_e32 v126, 16, v247
	v_lshlrev_b32_e32 v120, 16, v244
	v_and_b32_e32 v121, 0xffff0000, v244
	v_and_b32_e32 v127, 0xffff0000, v247
	v_lshlrev_b32_e32 v122, 16, v245
	v_and_b32_e32 v123, 0xffff0000, v245
	v_pk_fma_f32 v[116:117], v[116:117], v[132:133], v[120:121]
	v_pk_fma_f32 v[120:121], v[114:115], v[130:131], v[126:127]
	v_pk_fma_f32 v[114:115], v[112:113], v[128:129], v[124:125]
	v_pk_fma_f32 v[118:119], v[118:119], v[134:135], v[122:123]
	v_cvt_pk_bf16_f32 v112, v116, v117
	v_lshlrev_b32_e32 v116, 16, v197
	v_cvt_pk_bf16_f32 v113, v118, v119
	v_cvt_pk_bf16_f32 v114, v114, v115
	v_cvt_pk_bf16_f32 v115, v120, v121
	global_store_dwordx4 v[248:249], v[112:115], off offset:256
	v_and_b32_e32 v117, 0xffff0000, v197
	v_lshlrev_b32_e32 v118, 16, v198
	v_lshlrev_b32_e32 v114, 16, v196
	v_and_b32_e32 v115, 0xffff0000, v196
	v_and_b32_e32 v119, 0xffff0000, v198
	v_lshlrev_b32_e32 v120, 16, v199
	v_and_b32_e32 v121, 0xffff0000, v199
	v_lshl_add_u64 v[112:113], v[222:223], 0, v[232:233]
	v_pk_fma_f32 v[110:111], v[110:111], v[142:143], v[116:117]
	v_pk_fma_f32 v[108:109], v[108:109], v[140:141], v[114:115]
	v_pk_fma_f32 v[114:115], v[106:107], v[138:139], v[120:121]
	v_pk_fma_f32 v[106:107], v[104:105], v[136:137], v[118:119]
	v_cvt_pk_bf16_f32 v104, v108, v109
	v_cvt_pk_bf16_f32 v105, v110, v111
	v_lshlrev_b32_e32 v108, 16, v194
	v_cvt_pk_bf16_f32 v106, v106, v107
	v_cvt_pk_bf16_f32 v107, v114, v115
	global_store_dwordx4 v[112:113], v[104:107], off
	v_and_b32_e32 v109, 0xffff0000, v194
	v_lshlrev_b32_e32 v110, 16, v195
	v_lshlrev_b32_e32 v104, 16, v192
	v_and_b32_e32 v105, 0xffff0000, v192
	v_and_b32_e32 v111, 0xffff0000, v195
	v_lshlrev_b32_e32 v106, 16, v193
	v_and_b32_e32 v107, 0xffff0000, v193
	v_pk_fma_f32 v[100:101], v[100:101], v[132:133], v[104:105]
	v_pk_fma_f32 v[104:105], v[98:99], v[130:131], v[110:111]
	v_pk_fma_f32 v[98:99], v[96:97], v[128:129], v[108:109]
	v_pk_fma_f32 v[102:103], v[102:103], v[134:135], v[106:107]
	v_cvt_pk_bf16_f32 v96, v100, v101
	v_lshlrev_b32_e32 v100, 16, v189
	v_cvt_pk_bf16_f32 v97, v102, v103
	v_cvt_pk_bf16_f32 v98, v98, v99
	v_cvt_pk_bf16_f32 v99, v104, v105
	global_store_dwordx4 v[112:113], v[96:99], off offset:256
	v_and_b32_e32 v101, 0xffff0000, v189
	v_lshlrev_b32_e32 v102, 16, v190
	v_lshlrev_b32_e32 v98, 16, v188
	v_and_b32_e32 v99, 0xffff0000, v188
	v_and_b32_e32 v103, 0xffff0000, v190
	v_lshlrev_b32_e32 v104, 16, v191
	v_and_b32_e32 v105, 0xffff0000, v191
	v_lshl_add_u64 v[96:97], v[222:223], 0, v[230:231]
	v_pk_fma_f32 v[94:95], v[94:95], v[142:143], v[100:101]
	v_pk_fma_f32 v[92:93], v[92:93], v[140:141], v[98:99]
	v_pk_fma_f32 v[98:99], v[90:91], v[138:139], v[104:105]
	v_pk_fma_f32 v[90:91], v[88:89], v[136:137], v[102:103]
	v_cvt_pk_bf16_f32 v88, v92, v93
	v_cvt_pk_bf16_f32 v89, v94, v95
	v_lshlrev_b32_e32 v92, 16, v186
	v_cvt_pk_bf16_f32 v90, v90, v91
	v_cvt_pk_bf16_f32 v91, v98, v99
	global_store_dwordx4 v[96:97], v[88:91], off
	v_and_b32_e32 v93, 0xffff0000, v186
	v_lshlrev_b32_e32 v94, 16, v187
	v_lshlrev_b32_e32 v88, 16, v184
	v_and_b32_e32 v89, 0xffff0000, v184
	v_and_b32_e32 v95, 0xffff0000, v187
	v_lshlrev_b32_e32 v90, 16, v185
	v_and_b32_e32 v91, 0xffff0000, v185
	v_pk_fma_f32 v[84:85], v[84:85], v[132:133], v[88:89]
	v_pk_fma_f32 v[88:89], v[82:83], v[130:131], v[94:95]
	v_pk_fma_f32 v[82:83], v[80:81], v[128:129], v[92:93]
	v_pk_fma_f32 v[86:87], v[86:87], v[134:135], v[90:91]
	v_cvt_pk_bf16_f32 v80, v84, v85
	v_lshlrev_b32_e32 v84, 16, v181
	v_cvt_pk_bf16_f32 v81, v86, v87
	v_cvt_pk_bf16_f32 v82, v82, v83
	v_cvt_pk_bf16_f32 v83, v88, v89
	global_store_dwordx4 v[96:97], v[80:83], off offset:256
	v_and_b32_e32 v85, 0xffff0000, v181
	v_lshlrev_b32_e32 v86, 16, v182
	v_lshlrev_b32_e32 v82, 16, v180
	v_and_b32_e32 v83, 0xffff0000, v180
	v_and_b32_e32 v87, 0xffff0000, v182
	v_lshlrev_b32_e32 v88, 16, v183
	v_and_b32_e32 v89, 0xffff0000, v183
	v_lshl_add_u64 v[80:81], v[222:223], 0, v[228:229]
	v_pk_fma_f32 v[78:79], v[78:79], v[142:143], v[84:85]
	v_pk_fma_f32 v[76:77], v[76:77], v[140:141], v[82:83]
	v_pk_fma_f32 v[82:83], v[74:75], v[138:139], v[88:89]
	v_pk_fma_f32 v[74:75], v[72:73], v[136:137], v[86:87]
	v_cvt_pk_bf16_f32 v72, v76, v77
	v_cvt_pk_bf16_f32 v73, v78, v79
	v_lshlrev_b32_e32 v76, 16, v178
	v_cvt_pk_bf16_f32 v74, v74, v75
	v_cvt_pk_bf16_f32 v75, v82, v83
	global_store_dwordx4 v[80:81], v[72:75], off
	v_and_b32_e32 v77, 0xffff0000, v178
	v_lshlrev_b32_e32 v78, 16, v179
	v_lshlrev_b32_e32 v72, 16, v176
	v_and_b32_e32 v73, 0xffff0000, v176
	v_and_b32_e32 v79, 0xffff0000, v179
	v_lshlrev_b32_e32 v74, 16, v177
	v_and_b32_e32 v75, 0xffff0000, v177
	v_pk_fma_f32 v[68:69], v[68:69], v[132:133], v[72:73]
	v_pk_fma_f32 v[72:73], v[66:67], v[130:131], v[78:79]
	v_pk_fma_f32 v[66:67], v[64:65], v[128:129], v[76:77]
	v_pk_fma_f32 v[70:71], v[70:71], v[134:135], v[74:75]
	v_cvt_pk_bf16_f32 v64, v68, v69
	v_lshlrev_b32_e32 v68, 16, v173
	v_cvt_pk_bf16_f32 v65, v70, v71
	v_cvt_pk_bf16_f32 v66, v66, v67
	v_cvt_pk_bf16_f32 v67, v72, v73
	global_store_dwordx4 v[80:81], v[64:67], off offset:256
	v_and_b32_e32 v69, 0xffff0000, v173
	v_lshlrev_b32_e32 v70, 16, v174
	v_lshlrev_b32_e32 v66, 16, v172
	v_and_b32_e32 v67, 0xffff0000, v172
	v_and_b32_e32 v71, 0xffff0000, v174
	v_lshlrev_b32_e32 v72, 16, v175
	v_and_b32_e32 v73, 0xffff0000, v175
	v_lshl_add_u64 v[64:65], v[222:223], 0, v[226:227]
	v_pk_fma_f32 v[62:63], v[62:63], v[142:143], v[68:69]
	v_pk_fma_f32 v[60:61], v[60:61], v[140:141], v[66:67]
	v_pk_fma_f32 v[66:67], v[58:59], v[138:139], v[72:73]
	v_pk_fma_f32 v[58:59], v[56:57], v[136:137], v[70:71]
	v_cvt_pk_bf16_f32 v56, v60, v61
	v_cvt_pk_bf16_f32 v57, v62, v63
	v_lshlrev_b32_e32 v60, 16, v170
	v_cvt_pk_bf16_f32 v58, v58, v59
	v_cvt_pk_bf16_f32 v59, v66, v67
	global_store_dwordx4 v[64:65], v[56:59], off
	v_and_b32_e32 v61, 0xffff0000, v170
	v_lshlrev_b32_e32 v62, 16, v171
	v_lshlrev_b32_e32 v56, 16, v168
	v_and_b32_e32 v57, 0xffff0000, v168
	v_and_b32_e32 v63, 0xffff0000, v171
	v_lshlrev_b32_e32 v58, 16, v169
	v_and_b32_e32 v59, 0xffff0000, v169
	v_pk_fma_f32 v[52:53], v[52:53], v[132:133], v[56:57]
	v_pk_fma_f32 v[56:57], v[50:51], v[130:131], v[62:63]
	v_pk_fma_f32 v[50:51], v[48:49], v[128:129], v[60:61]
	v_pk_fma_f32 v[54:55], v[54:55], v[134:135], v[58:59]
	v_cvt_pk_bf16_f32 v48, v52, v53
	v_lshlrev_b32_e32 v52, 16, v165
	v_cvt_pk_bf16_f32 v49, v54, v55
	v_cvt_pk_bf16_f32 v50, v50, v51
	v_cvt_pk_bf16_f32 v51, v56, v57
	global_store_dwordx4 v[64:65], v[48:51], off offset:256
	v_and_b32_e32 v53, 0xffff0000, v165
	v_lshlrev_b32_e32 v54, 16, v166
	v_lshlrev_b32_e32 v50, 16, v164
	v_and_b32_e32 v51, 0xffff0000, v164
	v_and_b32_e32 v55, 0xffff0000, v166
	v_lshlrev_b32_e32 v56, 16, v167
	v_and_b32_e32 v57, 0xffff0000, v167
	v_lshl_add_u64 v[48:49], v[222:223], 0, v[224:225]
	v_pk_fma_f32 v[46:47], v[46:47], v[142:143], v[52:53]
	v_pk_fma_f32 v[44:45], v[44:45], v[140:141], v[50:51]
	v_pk_fma_f32 v[50:51], v[42:43], v[138:139], v[56:57]
	v_pk_fma_f32 v[42:43], v[40:41], v[136:137], v[54:55]
	v_cvt_pk_bf16_f32 v40, v44, v45
	v_cvt_pk_bf16_f32 v41, v46, v47
	v_lshlrev_b32_e32 v44, 16, v162
	v_cvt_pk_bf16_f32 v42, v42, v43
	v_cvt_pk_bf16_f32 v43, v50, v51
	global_store_dwordx4 v[48:49], v[40:43], off
	v_and_b32_e32 v45, 0xffff0000, v162
	v_lshlrev_b32_e32 v46, 16, v163
	v_lshlrev_b32_e32 v40, 16, v160
	v_and_b32_e32 v41, 0xffff0000, v160
	v_and_b32_e32 v47, 0xffff0000, v163
	v_lshlrev_b32_e32 v42, 16, v161
	v_and_b32_e32 v43, 0xffff0000, v161
	v_pk_fma_f32 v[36:37], v[36:37], v[132:133], v[40:41]
	v_pk_fma_f32 v[40:41], v[34:35], v[130:131], v[46:47]
	v_pk_fma_f32 v[34:35], v[32:33], v[128:129], v[44:45]
	v_pk_fma_f32 v[38:39], v[38:39], v[134:135], v[42:43]
	v_cvt_pk_bf16_f32 v32, v36, v37
	v_lshlrev_b32_e32 v36, 16, v157
	v_cvt_pk_bf16_f32 v33, v38, v39
	v_cvt_pk_bf16_f32 v34, v34, v35
	v_cvt_pk_bf16_f32 v35, v40, v41
	global_store_dwordx4 v[48:49], v[32:35], off offset:256
	v_and_b32_e32 v37, 0xffff0000, v157
	v_lshlrev_b32_e32 v38, 16, v158
	v_lshlrev_b32_e32 v34, 16, v156
	v_and_b32_e32 v35, 0xffff0000, v156
	v_and_b32_e32 v39, 0xffff0000, v158
	v_lshlrev_b32_e32 v40, 16, v159
	v_and_b32_e32 v41, 0xffff0000, v159
	v_lshl_add_u64 v[32:33], v[222:223], 0, v[220:221]
	v_pk_fma_f32 v[30:31], v[30:31], v[142:143], v[36:37]
	v_pk_fma_f32 v[28:29], v[28:29], v[140:141], v[34:35]
	v_pk_fma_f32 v[34:35], v[26:27], v[138:139], v[40:41]
	v_pk_fma_f32 v[26:27], v[24:25], v[136:137], v[38:39]
	v_cvt_pk_bf16_f32 v24, v28, v29
	v_cvt_pk_bf16_f32 v25, v30, v31
	v_lshlrev_b32_e32 v28, 16, v154
	v_cvt_pk_bf16_f32 v26, v26, v27
	v_cvt_pk_bf16_f32 v27, v34, v35
	global_store_dwordx4 v[32:33], v[24:27], off
	v_and_b32_e32 v29, 0xffff0000, v154
	v_lshlrev_b32_e32 v30, 16, v155
	v_lshlrev_b32_e32 v24, 16, v152
	v_and_b32_e32 v25, 0xffff0000, v152
	v_and_b32_e32 v31, 0xffff0000, v155
	v_lshlrev_b32_e32 v26, 16, v153
	v_and_b32_e32 v27, 0xffff0000, v153
	v_pk_fma_f32 v[20:21], v[20:21], v[132:133], v[24:25]
	v_pk_fma_f32 v[24:25], v[18:19], v[130:131], v[30:31]
	v_pk_fma_f32 v[18:19], v[16:17], v[128:129], v[28:29]
	v_pk_fma_f32 v[22:23], v[22:23], v[134:135], v[26:27]
	v_cvt_pk_bf16_f32 v16, v20, v21
	v_lshlrev_b32_e32 v20, 16, v149
	v_cvt_pk_bf16_f32 v17, v22, v23
	v_cvt_pk_bf16_f32 v18, v18, v19
	v_cvt_pk_bf16_f32 v19, v24, v25
	global_store_dwordx4 v[32:33], v[16:19], off offset:256
	v_and_b32_e32 v21, 0xffff0000, v149
	v_lshlrev_b32_e32 v22, 16, v150
	v_lshlrev_b32_e32 v18, 16, v148
	v_and_b32_e32 v19, 0xffff0000, v148
	v_and_b32_e32 v23, 0xffff0000, v150
	v_lshlrev_b32_e32 v24, 16, v151
	v_and_b32_e32 v25, 0xffff0000, v151
	v_lshl_add_u64 v[16:17], v[222:223], 0, v[218:219]
	v_pk_fma_f32 v[14:15], v[14:15], v[142:143], v[20:21]
	v_pk_fma_f32 v[12:13], v[12:13], v[140:141], v[18:19]
	v_pk_fma_f32 v[18:19], v[10:11], v[138:139], v[24:25]
	v_pk_fma_f32 v[10:11], v[8:9], v[136:137], v[22:23]
	v_cvt_pk_bf16_f32 v8, v12, v13
	v_cvt_pk_bf16_f32 v9, v14, v15
	v_lshlrev_b32_e32 v12, 16, v146
	v_cvt_pk_bf16_f32 v10, v10, v11
	v_cvt_pk_bf16_f32 v11, v18, v19
	global_store_dwordx4 v[16:17], v[8:11], off
	v_and_b32_e32 v13, 0xffff0000, v146
	v_lshlrev_b32_e32 v14, 16, v147
	v_lshlrev_b32_e32 v8, 16, v144
	v_and_b32_e32 v9, 0xffff0000, v144
	v_and_b32_e32 v15, 0xffff0000, v147
	v_lshlrev_b32_e32 v10, 16, v145
	v_and_b32_e32 v11, 0xffff0000, v145
	v_pk_fma_f32 v[4:5], v[4:5], v[132:133], v[8:9]
	v_pk_fma_f32 v[8:9], v[2:3], v[130:131], v[14:15]
	v_pk_fma_f32 v[2:3], v[0:1], v[128:129], v[12:13]
	v_pk_fma_f32 v[6:7], v[6:7], v[134:135], v[10:11]
	v_cvt_pk_bf16_f32 v0, v4, v5
	s_nop 0
	v_cvt_pk_bf16_f32 v1, v6, v7
	v_cvt_pk_bf16_f32 v2, v2, v3
	v_cvt_pk_bf16_f32 v3, v8, v9
	global_store_dwordx4 v[16:17], v[0:3], off offset:256
	s_cbranch_vccz .LBB0_891
	s_waitcnt vmcnt(0)
	s_cmpk_gt_u32 s33, 0xff
	s_cbranch_scc1 .LBB0_906
	s_barrier

.LBB0_1020:
	s_ashr_i32 s7, s6, 31
	v_cmp_lt_i64_e32 vcc, s[10:11], v[140:141]
	s_lshl_b64 s[10:11], s[6:7], 19
	s_add_u32 s10, s96, s10
	s_addc_u32 s11, s97, s11
	s_and_b64 s[12:13], vcc, exec
	s_cselect_b32 s7, s11, s17
	s_cselect_b32 s42, s10, s16
	s_ashr_i32 s5, s4, 31
	s_lshl_b64 s[12:13], s[4:5], 19
	s_add_u32 s12, s23, s12
	s_addc_u32 s13, s24, s13
	s_and_b64 s[20:21], vcc, exec
	s_cselect_b32 s5, s13, s19
	s_cselect_b32 s43, s12, s18
	s_add_u32 s16, s16, 0x40080
	s_addc_u32 s17, s17, 0
	s_add_u32 s44, s18, 0x100
	s_addc_u32 s45, s19, 0
	s_mov_b32 s46, -2
	ds_read_b128 v[150:153], v147
	ds_read_b128 v[154:157], v147 offset:1024
	ds_read_b128 v[158:161], v147 offset:2048
	ds_read_b128 v[162:165], v147 offset:3072
	s_add_u32 s18, s16, 0xfffc0080
	s_addc_u32 s19, s17, -1
	s_cmp_eq_u32 s46, 12
	s_cselect_b32 s21, s7, s19
	s_cselect_b32 s20, s42, s18
	s_cselect_b32 s19, s5, s45
	s_cselect_b32 s18, s43, s44
	s_add_i32 m0, s15, 0xc000
	ds_read_b128 v[166:169], v148
	ds_read_b128 v[170:173], v148 offset:1024
	ds_read_b128 v[174:177], v148 offset:2048
	ds_read_b128 v[178:181], v148 offset:3072
	ds_read_b128 v[182:185], v148 offset:4096
	ds_read_b128 v[186:189], v148 offset:5120
	ds_read_b128 v[190:193], v148 offset:6144
	ds_read_b128 v[194:197], v148 offset:7168
	global_load_lds_dwordx4 v136, s[16:17]
	s_add_i32 m0, s15, 0xe000
	s_nop 0
	global_load_lds_dwordx4 v138, s[16:17]
	s_waitcnt lgkmcnt(8)
	s_barrier
	s_waitcnt lgkmcnt(0)
	s_setprio 1
	s_waitcnt lgkmcnt(0)
	v_mfma_f32_16x16x32_bf16 v[124:127], v[150:153], v[166:169], 0
	v_mfma_f32_16x16x32_bf16 v[116:119], v[158:161], v[166:169], 0
	v_mfma_f32_16x16x32_bf16 v[108:111], v[150:153], v[174:177], 0
	v_mfma_f32_16x16x32_bf16 v[100:103], v[158:161], v[174:177], 0
	v_mfma_f32_16x16x32_bf16 v[92:95], v[150:153], v[182:185], 0
	v_mfma_f32_16x16x32_bf16 v[84:87], v[158:161], v[182:185], 0
	v_mfma_f32_16x16x32_bf16 v[76:79], v[150:153], v[190:193], 0
	v_mfma_f32_16x16x32_bf16 v[68:71], v[158:161], v[190:193], 0
	v_mfma_f32_16x16x32_bf16 v[124:127], v[154:157], v[170:173], v[124:127]
	v_mfma_f32_16x16x32_bf16 v[116:119], v[162:165], v[170:173], v[116:119]
	v_mfma_f32_16x16x32_bf16 v[108:111], v[154:157], v[178:181], v[108:111]
	v_mfma_f32_16x16x32_bf16 v[100:103], v[162:165], v[178:181], v[100:103]
	v_mfma_f32_16x16x32_bf16 v[92:95], v[154:157], v[186:189], v[92:95]
	v_mfma_f32_16x16x32_bf16 v[84:87], v[162:165], v[186:189], v[84:87]
	v_mfma_f32_16x16x32_bf16 v[76:79], v[154:157], v[194:197], v[76:79]
	v_mfma_f32_16x16x32_bf16 v[68:71], v[162:165], v[194:197], v[68:71]
	s_setprio 0
	s_barrier
	s_add_i32 s47, s38, s25
	s_mov_b32 m0, s47
	ds_read_b128 v[202:205], v149
	ds_read_b128 v[206:209], v149 offset:1024
	ds_read_b128 v[210:213], v149 offset:2048
	ds_read_b128 v[214:217], v149 offset:3072
	global_load_lds_dwordx4 v132, s[18:19]
	s_add_i32 m0, s47, 0x2000
	s_nop 0
	global_load_lds_dwordx4 v128, s[18:19]
	s_barrier
	s_waitcnt lgkmcnt(0)
	s_setprio 1
	s_waitcnt lgkmcnt(0)
	v_mfma_f32_16x16x32_bf16 v[120:123], v[202:205], v[166:169], 0
	v_mfma_f32_16x16x32_bf16 v[112:115], v[210:213], v[166:169], 0
	v_mfma_f32_16x16x32_bf16 v[104:107], v[202:205], v[174:177], 0
	v_mfma_f32_16x16x32_bf16 v[96:99], v[210:213], v[174:177], 0
	v_mfma_f32_16x16x32_bf16 v[88:91], v[202:205], v[182:185], 0
	v_mfma_f32_16x16x32_bf16 v[80:83], v[210:213], v[182:185], 0
	v_mfma_f32_16x16x32_bf16 v[72:75], v[202:205], v[190:193], 0
	v_mfma_f32_16x16x32_bf16 v[64:67], v[210:213], v[190:193], 0
	v_mfma_f32_16x16x32_bf16 v[120:123], v[206:209], v[170:173], v[120:123]
	v_mfma_f32_16x16x32_bf16 v[112:115], v[214:217], v[170:173], v[112:115]
	v_mfma_f32_16x16x32_bf16 v[104:107], v[206:209], v[178:181], v[104:107]
	v_mfma_f32_16x16x32_bf16 v[96:99], v[214:217], v[178:181], v[96:99]
	v_mfma_f32_16x16x32_bf16 v[88:91], v[206:209], v[186:189], v[88:91]
	v_mfma_f32_16x16x32_bf16 v[80:83], v[214:217], v[186:189], v[80:83]
	v_mfma_f32_16x16x32_bf16 v[72:75], v[206:209], v[194:197], v[72:75]
	v_mfma_f32_16x16x32_bf16 v[64:67], v[214:217], v[194:197], v[64:67]
	s_setprio 0
	s_mov_b32 m0, s15
	v_lshl_add_u64 v[220:221], s[20:21], 0, v[134:135]
	s_barrier
	ds_read_b128 v[166:169], v148 offset:16384
	ds_read_b128 v[170:173], v148 offset:17408
	ds_read_b128 v[174:177], v148 offset:18432
	ds_read_b128 v[178:181], v148 offset:19456
	ds_read_b128 v[182:185], v148 offset:20480
	ds_read_b128 v[186:189], v148 offset:21504
	ds_read_b128 v[190:193], v148 offset:22528
	ds_read_b128 v[194:197], v148 offset:23552
	global_load_lds_dwordx4 v134, s[20:21]
	v_lshl_add_u64 v[222:223], s[20:21], 0, v[130:131]
	s_mov_b32 m0, s28
	s_nop 0
	global_load_lds_dwordx4 v130, s[20:21]
	s_barrier
	s_waitcnt lgkmcnt(0)
	s_setprio 1
	s_waitcnt lgkmcnt(0)
	v_mfma_f32_16x16x32_bf16 v[60:63], v[150:153], v[166:169], 0
	v_mfma_f32_16x16x32_bf16 v[56:59], v[158:161], v[166:169], 0
	v_mfma_f32_16x16x32_bf16 v[44:47], v[150:153], v[174:177], 0
	v_mfma_f32_16x16x32_bf16 v[40:43], v[158:161], v[174:177], 0
	v_mfma_f32_16x16x32_bf16 v[28:31], v[150:153], v[182:185], 0
	v_mfma_f32_16x16x32_bf16 v[24:27], v[158:161], v[182:185], 0
	v_mfma_f32_16x16x32_bf16 v[12:15], v[150:153], v[190:193], 0
	v_mfma_f32_16x16x32_bf16 v[8:11], v[158:161], v[190:193], 0
	v_mfma_f32_16x16x32_bf16 v[60:63], v[154:157], v[170:173], v[60:63]
	v_mfma_f32_16x16x32_bf16 v[56:59], v[162:165], v[170:173], v[56:59]
	v_mfma_f32_16x16x32_bf16 v[44:47], v[154:157], v[178:181], v[44:47]
	v_mfma_f32_16x16x32_bf16 v[40:43], v[162:165], v[178:181], v[40:43]
	v_mfma_f32_16x16x32_bf16 v[28:31], v[154:157], v[186:189], v[28:31]
	v_mfma_f32_16x16x32_bf16 v[24:27], v[162:165], v[186:189], v[24:27]
	v_mfma_f32_16x16x32_bf16 v[12:15], v[154:157], v[194:197], v[12:15]
	v_mfma_f32_16x16x32_bf16 v[8:11], v[162:165], v[194:197], v[8:11]
	s_setprio 0
	s_barrier
	s_add_u32 s48, s18, 0x40000
	s_addc_u32 s49, s19, 0
	s_add_i32 s47, s39, s25
	s_mov_b32 m0, s47
	s_nop 0
	global_load_lds_dwordx4 v132, s[48:49]
	s_add_i32 m0, s47, 0x2000
	s_nop 0
	global_load_lds_dwordx4 v128, s[48:49]
	s_waitcnt vmcnt(6)
	s_barrier
	s_setprio 1
	v_mfma_f32_16x16x32_bf16 v[52:55], v[202:205], v[166:169], 0
	v_mfma_f32_16x16x32_bf16 v[48:51], v[210:213], v[166:169], 0
	v_mfma_f32_16x16x32_bf16 v[36:39], v[202:205], v[174:177], 0
	v_mfma_f32_16x16x32_bf16 v[32:35], v[210:213], v[174:177], 0
	v_mfma_f32_16x16x32_bf16 v[20:23], v[202:205], v[182:185], 0
	v_mfma_f32_16x16x32_bf16 v[16:19], v[210:213], v[182:185], 0
	v_mfma_f32_16x16x32_bf16 v[4:7], v[202:205], v[190:193], 0
	v_mfma_f32_16x16x32_bf16 v[0:3], v[210:213], v[190:193], 0
	v_mfma_f32_16x16x32_bf16 v[52:55], v[206:209], v[170:173], v[52:55]
	v_mfma_f32_16x16x32_bf16 v[48:51], v[214:217], v[170:173], v[48:51]
	v_mfma_f32_16x16x32_bf16 v[36:39], v[206:209], v[178:181], v[36:39]
	v_mfma_f32_16x16x32_bf16 v[32:35], v[214:217], v[178:181], v[32:35]
	v_mfma_f32_16x16x32_bf16 v[20:23], v[206:209], v[186:189], v[20:23]
	v_mfma_f32_16x16x32_bf16 v[16:19], v[214:217], v[186:189], v[16:19]
	v_mfma_f32_16x16x32_bf16 v[4:7], v[206:209], v[194:197], v[4:7]
	v_mfma_f32_16x16x32_bf16 v[0:3], v[214:217], v[194:197], v[0:3]
	s_setprio 0
	s_add_i32 s47, 0, 0x18000
	v_add_u32_e32 v162, s47, v146
	s_barrier
	ds_read_b128 v[150:153], v162
	ds_read_b128 v[154:157], v162 offset:1024
	ds_read_b128 v[158:161], v162 offset:2048
	ds_read_b128 v[162:165], v162 offset:3072
	s_add_u32 s20, s20, 0x40000
	s_addc_u32 s21, s21, 0
	s_mov_b32 m0, s29
	ds_read_b128 v[166:169], v148 offset:32768
	ds_read_b128 v[170:173], v148 offset:33792
	ds_read_b128 v[174:177], v148 offset:34816
	ds_read_b128 v[178:181], v148 offset:35840
	ds_read_b128 v[182:185], v148 offset:36864
	ds_read_b128 v[186:189], v148 offset:37888
	ds_read_b128 v[190:193], v148 offset:38912
	ds_read_b128 v[194:197], v148 offset:39936
	global_load_lds_dwordx4 v134, s[20:21]
	s_mov_b32 m0, s30
	s_nop 0
	global_load_lds_dwordx4 v130, s[20:21]
	s_waitcnt lgkmcnt(8)
	s_barrier
	s_waitcnt lgkmcnt(0)
	s_setprio 1
	s_waitcnt lgkmcnt(0)
	v_mfma_f32_16x16x32_bf16 v[124:127], v[150:153], v[166:169], v[124:127]
	v_mfma_f32_16x16x32_bf16 v[116:119], v[158:161], v[166:169], v[116:119]
	v_mfma_f32_16x16x32_bf16 v[108:111], v[150:153], v[174:177], v[108:111]
	v_mfma_f32_16x16x32_bf16 v[100:103], v[158:161], v[174:177], v[100:103]
	v_mfma_f32_16x16x32_bf16 v[92:95], v[150:153], v[182:185], v[92:95]
	v_mfma_f32_16x16x32_bf16 v[84:87], v[158:161], v[182:185], v[84:87]
	v_mfma_f32_16x16x32_bf16 v[76:79], v[150:153], v[190:193], v[76:79]
	v_mfma_f32_16x16x32_bf16 v[68:71], v[158:161], v[190:193], v[68:71]
	v_mfma_f32_16x16x32_bf16 v[124:127], v[154:157], v[170:173], v[124:127]
	v_mfma_f32_16x16x32_bf16 v[116:119], v[162:165], v[170:173], v[116:119]
	v_mfma_f32_16x16x32_bf16 v[108:111], v[154:157], v[178:181], v[108:111]
	v_mfma_f32_16x16x32_bf16 v[100:103], v[162:165], v[178:181], v[100:103]
	v_mfma_f32_16x16x32_bf16 v[92:95], v[154:157], v[186:189], v[92:95]
	v_mfma_f32_16x16x32_bf16 v[84:87], v[162:165], v[186:189], v[84:87]
	v_mfma_f32_16x16x32_bf16 v[76:79], v[154:157], v[194:197], v[76:79]
	v_mfma_f32_16x16x32_bf16 v[68:71], v[162:165], v[194:197], v[68:71]
	s_setprio 0
	s_barrier
	s_add_i32 s20, 0, 0x1c000
	s_add_i32 s21, s47, s25
	v_add_u32_e32 v214, s20, v146
	s_add_u32 s0, s18, 0x80
	s_addc_u32 s1, s19, 0
	s_mov_b32 m0, s21
	ds_read_b128 v[202:205], v214
	ds_read_b128 v[206:209], v214 offset:1024
	ds_read_b128 v[210:213], v214 offset:2048
	ds_read_b128 v[214:217], v214 offset:3072
	global_load_lds_dwordx4 v132, s[0:1]
	s_add_i32 m0, s21, 0x2000
	s_nop 0
	global_load_lds_dwordx4 v128, s[0:1]
	s_barrier
	s_waitcnt lgkmcnt(0)
	s_setprio 1
	s_waitcnt lgkmcnt(0)
	v_mfma_f32_16x16x32_bf16 v[120:123], v[202:205], v[166:169], v[120:123]
	v_mfma_f32_16x16x32_bf16 v[112:115], v[210:213], v[166:169], v[112:115]
	v_mfma_f32_16x16x32_bf16 v[104:107], v[202:205], v[174:177], v[104:107]
	v_mfma_f32_16x16x32_bf16 v[96:99], v[210:213], v[174:177], v[96:99]
	v_mfma_f32_16x16x32_bf16 v[88:91], v[202:205], v[182:185], v[88:91]
	v_mfma_f32_16x16x32_bf16 v[80:83], v[210:213], v[182:185], v[80:83]
	v_mfma_f32_16x16x32_bf16 v[72:75], v[202:205], v[190:193], v[72:75]
	v_mfma_f32_16x16x32_bf16 v[64:67], v[210:213], v[190:193], v[64:67]
	v_mfma_f32_16x16x32_bf16 v[120:123], v[206:209], v[170:173], v[120:123]
	v_mfma_f32_16x16x32_bf16 v[112:115], v[214:217], v[170:173], v[112:115]
	v_mfma_f32_16x16x32_bf16 v[104:107], v[206:209], v[178:181], v[104:107]
	v_mfma_f32_16x16x32_bf16 v[96:99], v[214:217], v[178:181], v[96:99]
	v_mfma_f32_16x16x32_bf16 v[88:91], v[206:209], v[186:189], v[88:91]
	v_mfma_f32_16x16x32_bf16 v[80:83], v[214:217], v[186:189], v[80:83]
	v_mfma_f32_16x16x32_bf16 v[72:75], v[206:209], v[194:197], v[72:75]
	v_mfma_f32_16x16x32_bf16 v[64:67], v[214:217], v[194:197], v[64:67]
	s_setprio 0
	s_mov_b32 m0, s35
	s_mov_b64 s[0:1], 0x80
	v_lshl_add_u64 v[198:199], v[220:221], 0, s[0:1]
	s_barrier
	ds_read_b128 v[166:169], v148 offset:49152
	ds_read_b128 v[170:173], v148 offset:50176
	ds_read_b128 v[174:177], v148 offset:51200
	ds_read_b128 v[178:181], v148 offset:52224
	ds_read_b128 v[182:185], v148 offset:53248
	ds_read_b128 v[186:189], v148 offset:54272
	ds_read_b128 v[190:193], v148 offset:55296
	ds_read_b128 v[194:197], v148 offset:56320
	global_load_lds_dwordx4 v[198:199], off
	v_lshl_add_u64 v[198:199], v[222:223], 0, s[0:1]
	s_mov_b32 m0, s36
	s_nop 0
	global_load_lds_dwordx4 v[198:199], off
	s_barrier
	s_waitcnt lgkmcnt(0)
	s_setprio 1
	s_waitcnt lgkmcnt(0)
	v_mfma_f32_16x16x32_bf16 v[60:63], v[150:153], v[166:169], v[60:63]
	v_mfma_f32_16x16x32_bf16 v[56:59], v[158:161], v[166:169], v[56:59]
	v_mfma_f32_16x16x32_bf16 v[44:47], v[150:153], v[174:177], v[44:47]
	v_mfma_f32_16x16x32_bf16 v[40:43], v[158:161], v[174:177], v[40:43]
	v_mfma_f32_16x16x32_bf16 v[28:31], v[150:153], v[182:185], v[28:31]
	v_mfma_f32_16x16x32_bf16 v[24:27], v[158:161], v[182:185], v[24:27]
	v_mfma_f32_16x16x32_bf16 v[12:15], v[150:153], v[190:193], v[12:15]
	v_mfma_f32_16x16x32_bf16 v[8:11], v[158:161], v[190:193], v[8:11]
	v_mfma_f32_16x16x32_bf16 v[60:63], v[154:157], v[170:173], v[60:63]
	v_mfma_f32_16x16x32_bf16 v[56:59], v[162:165], v[170:173], v[56:59]
	v_mfma_f32_16x16x32_bf16 v[44:47], v[154:157], v[178:181], v[44:47]
	v_mfma_f32_16x16x32_bf16 v[40:43], v[162:165], v[178:181], v[40:43]
	v_mfma_f32_16x16x32_bf16 v[28:31], v[154:157], v[186:189], v[28:31]
	v_mfma_f32_16x16x32_bf16 v[24:27], v[162:165], v[186:189], v[24:27]
	v_mfma_f32_16x16x32_bf16 v[12:15], v[154:157], v[194:197], v[12:15]
	v_mfma_f32_16x16x32_bf16 v[8:11], v[162:165], v[194:197], v[8:11]
	s_setprio 0
	s_barrier
	s_add_u32 s18, s18, 0x40080
	s_addc_u32 s19, s19, 0
	s_add_i32 s20, s20, s25
	s_mov_b32 m0, s20
	s_nop 0
	global_load_lds_dwordx4 v132, s[18:19]
	s_add_i32 m0, s20, 0x2000
	s_nop 0
	global_load_lds_dwordx4 v128, s[18:19]
	s_waitcnt vmcnt(6)
	s_barrier
	s_setprio 1
	v_mfma_f32_16x16x32_bf16 v[52:55], v[202:205], v[166:169], v[52:55]
	v_mfma_f32_16x16x32_bf16 v[48:51], v[210:213], v[166:169], v[48:51]
	v_mfma_f32_16x16x32_bf16 v[36:39], v[202:205], v[174:177], v[36:39]
	v_mfma_f32_16x16x32_bf16 v[32:35], v[210:213], v[174:177], v[32:35]
	v_mfma_f32_16x16x32_bf16 v[20:23], v[202:205], v[182:185], v[20:23]
	v_mfma_f32_16x16x32_bf16 v[16:19], v[210:213], v[182:185], v[16:19]
	v_mfma_f32_16x16x32_bf16 v[4:7], v[202:205], v[190:193], v[4:7]
	v_mfma_f32_16x16x32_bf16 v[0:3], v[210:213], v[190:193], v[0:3]
	v_mfma_f32_16x16x32_bf16 v[52:55], v[206:209], v[170:173], v[52:55]
	v_mfma_f32_16x16x32_bf16 v[48:51], v[214:217], v[170:173], v[48:51]
	v_mfma_f32_16x16x32_bf16 v[36:39], v[206:209], v[178:181], v[36:39]
	v_mfma_f32_16x16x32_bf16 v[32:35], v[214:217], v[178:181], v[32:35]
	v_mfma_f32_16x16x32_bf16 v[20:23], v[206:209], v[186:189], v[20:23]
	v_mfma_f32_16x16x32_bf16 v[16:19], v[214:217], v[186:189], v[16:19]
	v_mfma_f32_16x16x32_bf16 v[4:7], v[206:209], v[194:197], v[4:7]
	v_mfma_f32_16x16x32_bf16 v[0:3], v[214:217], v[194:197], v[0:3]
	s_setprio 0
	s_add_i32 s46, s46, 2
	s_add_u32 s16, s16, 0x100
	s_addc_u32 s17, s17, 0
	s_add_u32 s44, s44, 0x100
	s_addc_u32 s45, s45, 0
	s_cmp_gt_u32 s46, 13
	s_barrier
.LBB0_1021:
	ds_read_b128 v[150:153], v147
	ds_read_b128 v[154:157], v147 offset:1024
	ds_read_b128 v[158:161], v147 offset:2048
	ds_read_b128 v[162:165], v147 offset:3072
	s_add_u32 s18, s16, 0xfffc0080
	s_addc_u32 s19, s17, -1
	s_cmp_eq_u32 s46, 12
	s_cselect_b32 s21, s7, s19
	s_cselect_b32 s20, s42, s18
	s_cselect_b32 s19, s5, s45
	s_cselect_b32 s18, s43, s44
	s_add_i32 m0, s15, 0xc000
	ds_read_b128 v[166:169], v148
	ds_read_b128 v[170:173], v148 offset:1024
	ds_read_b128 v[174:177], v148 offset:2048
	ds_read_b128 v[178:181], v148 offset:3072
	ds_read_b128 v[182:185], v148 offset:4096
	ds_read_b128 v[186:189], v148 offset:5120
	ds_read_b128 v[190:193], v148 offset:6144
	ds_read_b128 v[194:197], v148 offset:7168
	global_load_lds_dwordx4 v136, s[16:17]
	s_add_i32 m0, s15, 0xe000
	s_nop 0
	global_load_lds_dwordx4 v138, s[16:17]
	s_waitcnt lgkmcnt(8)
	s_barrier
	s_waitcnt lgkmcnt(0)
	s_setprio 1
	s_waitcnt lgkmcnt(0)
	v_mfma_f32_16x16x32_bf16 v[124:127], v[150:153], v[166:169], v[124:127]
	v_mfma_f32_16x16x32_bf16 v[116:119], v[158:161], v[166:169], v[116:119]
	v_mfma_f32_16x16x32_bf16 v[108:111], v[150:153], v[174:177], v[108:111]
	v_mfma_f32_16x16x32_bf16 v[100:103], v[158:161], v[174:177], v[100:103]
	v_mfma_f32_16x16x32_bf16 v[92:95], v[150:153], v[182:185], v[92:95]
	v_mfma_f32_16x16x32_bf16 v[84:87], v[158:161], v[182:185], v[84:87]
	v_mfma_f32_16x16x32_bf16 v[76:79], v[150:153], v[190:193], v[76:79]
	v_mfma_f32_16x16x32_bf16 v[68:71], v[158:161], v[190:193], v[68:71]
	v_mfma_f32_16x16x32_bf16 v[124:127], v[154:157], v[170:173], v[124:127]
	v_mfma_f32_16x16x32_bf16 v[116:119], v[162:165], v[170:173], v[116:119]
	v_mfma_f32_16x16x32_bf16 v[108:111], v[154:157], v[178:181], v[108:111]
	v_mfma_f32_16x16x32_bf16 v[100:103], v[162:165], v[178:181], v[100:103]
	v_mfma_f32_16x16x32_bf16 v[92:95], v[154:157], v[186:189], v[92:95]
	v_mfma_f32_16x16x32_bf16 v[84:87], v[162:165], v[186:189], v[84:87]
	v_mfma_f32_16x16x32_bf16 v[76:79], v[154:157], v[194:197], v[76:79]
	v_mfma_f32_16x16x32_bf16 v[68:71], v[162:165], v[194:197], v[68:71]
	s_setprio 0
	s_barrier
	s_add_i32 s47, s38, s25
	s_mov_b32 m0, s47
	ds_read_b128 v[202:205], v149
	ds_read_b128 v[206:209], v149 offset:1024
	ds_read_b128 v[210:213], v149 offset:2048
	ds_read_b128 v[214:217], v149 offset:3072
	global_load_lds_dwordx4 v132, s[18:19]
	s_add_i32 m0, s47, 0x2000
	s_nop 0
	global_load_lds_dwordx4 v128, s[18:19]
	s_barrier
	s_waitcnt lgkmcnt(0)
	s_setprio 1
	s_waitcnt lgkmcnt(0)
	v_mfma_f32_16x16x32_bf16 v[120:123], v[202:205], v[166:169], v[120:123]
	v_mfma_f32_16x16x32_bf16 v[112:115], v[210:213], v[166:169], v[112:115]
	v_mfma_f32_16x16x32_bf16 v[104:107], v[202:205], v[174:177], v[104:107]
	v_mfma_f32_16x16x32_bf16 v[96:99], v[210:213], v[174:177], v[96:99]
	v_mfma_f32_16x16x32_bf16 v[88:91], v[202:205], v[182:185], v[88:91]
	v_mfma_f32_16x16x32_bf16 v[80:83], v[210:213], v[182:185], v[80:83]
	v_mfma_f32_16x16x32_bf16 v[72:75], v[202:205], v[190:193], v[72:75]
	v_mfma_f32_16x16x32_bf16 v[64:67], v[210:213], v[190:193], v[64:67]
	v_mfma_f32_16x16x32_bf16 v[120:123], v[206:209], v[170:173], v[120:123]
	v_mfma_f32_16x16x32_bf16 v[112:115], v[214:217], v[170:173], v[112:115]
	v_mfma_f32_16x16x32_bf16 v[104:107], v[206:209], v[178:181], v[104:107]
	v_mfma_f32_16x16x32_bf16 v[96:99], v[214:217], v[178:181], v[96:99]
	v_mfma_f32_16x16x32_bf16 v[88:91], v[206:209], v[186:189], v[88:91]
	v_mfma_f32_16x16x32_bf16 v[80:83], v[214:217], v[186:189], v[80:83]
	v_mfma_f32_16x16x32_bf16 v[72:75], v[206:209], v[194:197], v[72:75]
	v_mfma_f32_16x16x32_bf16 v[64:67], v[214:217], v[194:197], v[64:67]
	s_setprio 0
	s_mov_b32 m0, s15
	v_lshl_add_u64 v[220:221], s[20:21], 0, v[134:135]
	s_barrier
	ds_read_b128 v[166:169], v148 offset:16384
	ds_read_b128 v[170:173], v148 offset:17408
	ds_read_b128 v[174:177], v148 offset:18432
	ds_read_b128 v[178:181], v148 offset:19456
	ds_read_b128 v[182:185], v148 offset:20480
	ds_read_b128 v[186:189], v148 offset:21504
	ds_read_b128 v[190:193], v148 offset:22528
	ds_read_b128 v[194:197], v148 offset:23552
	global_load_lds_dwordx4 v134, s[20:21]
	v_lshl_add_u64 v[222:223], s[20:21], 0, v[130:131]
	s_mov_b32 m0, s28
	s_nop 0
	global_load_lds_dwordx4 v130, s[20:21]
	s_barrier
	s_waitcnt lgkmcnt(0)
	s_setprio 1
	s_waitcnt lgkmcnt(0)
	v_mfma_f32_16x16x32_bf16 v[60:63], v[150:153], v[166:169], v[60:63]
	v_mfma_f32_16x16x32_bf16 v[56:59], v[158:161], v[166:169], v[56:59]
	v_mfma_f32_16x16x32_bf16 v[44:47], v[150:153], v[174:177], v[44:47]
	v_mfma_f32_16x16x32_bf16 v[40:43], v[158:161], v[174:177], v[40:43]
	v_mfma_f32_16x16x32_bf16 v[28:31], v[150:153], v[182:185], v[28:31]
	v_mfma_f32_16x16x32_bf16 v[24:27], v[158:161], v[182:185], v[24:27]
	v_mfma_f32_16x16x32_bf16 v[12:15], v[150:153], v[190:193], v[12:15]
	v_mfma_f32_16x16x32_bf16 v[8:11], v[158:161], v[190:193], v[8:11]
	v_mfma_f32_16x16x32_bf16 v[60:63], v[154:157], v[170:173], v[60:63]
	v_mfma_f32_16x16x32_bf16 v[56:59], v[162:165], v[170:173], v[56:59]
	v_mfma_f32_16x16x32_bf16 v[44:47], v[154:157], v[178:181], v[44:47]
	v_mfma_f32_16x16x32_bf16 v[40:43], v[162:165], v[178:181], v[40:43]
	v_mfma_f32_16x16x32_bf16 v[28:31], v[154:157], v[186:189], v[28:31]
	v_mfma_f32_16x16x32_bf16 v[24:27], v[162:165], v[186:189], v[24:27]
	v_mfma_f32_16x16x32_bf16 v[12:15], v[154:157], v[194:197], v[12:15]
	v_mfma_f32_16x16x32_bf16 v[8:11], v[162:165], v[194:197], v[8:11]
	s_setprio 0
	s_barrier
	s_add_u32 s48, s18, 0x40000
	s_addc_u32 s49, s19, 0
	s_add_i32 s47, s39, s25
	s_mov_b32 m0, s47
	s_nop 0
	global_load_lds_dwordx4 v132, s[48:49]
	s_add_i32 m0, s47, 0x2000
	s_nop 0
	global_load_lds_dwordx4 v128, s[48:49]
	s_waitcnt vmcnt(6)
	s_barrier
	s_setprio 1
	v_mfma_f32_16x16x32_bf16 v[52:55], v[202:205], v[166:169], v[52:55]
	v_mfma_f32_16x16x32_bf16 v[48:51], v[210:213], v[166:169], v[48:51]
	v_mfma_f32_16x16x32_bf16 v[36:39], v[202:205], v[174:177], v[36:39]
	v_mfma_f32_16x16x32_bf16 v[32:35], v[210:213], v[174:177], v[32:35]
	v_mfma_f32_16x16x32_bf16 v[20:23], v[202:205], v[182:185], v[20:23]
	v_mfma_f32_16x16x32_bf16 v[16:19], v[210:213], v[182:185], v[16:19]
	v_mfma_f32_16x16x32_bf16 v[4:7], v[202:205], v[190:193], v[4:7]
	v_mfma_f32_16x16x32_bf16 v[0:3], v[210:213], v[190:193], v[0:3]
	v_mfma_f32_16x16x32_bf16 v[52:55], v[206:209], v[170:173], v[52:55]
	v_mfma_f32_16x16x32_bf16 v[48:51], v[214:217], v[170:173], v[48:51]
	v_mfma_f32_16x16x32_bf16 v[36:39], v[206:209], v[178:181], v[36:39]
	v_mfma_f32_16x16x32_bf16 v[32:35], v[214:217], v[178:181], v[32:35]
	v_mfma_f32_16x16x32_bf16 v[20:23], v[206:209], v[186:189], v[20:23]
	v_mfma_f32_16x16x32_bf16 v[16:19], v[214:217], v[186:189], v[16:19]
	v_mfma_f32_16x16x32_bf16 v[4:7], v[206:209], v[194:197], v[4:7]
	v_mfma_f32_16x16x32_bf16 v[0:3], v[214:217], v[194:197], v[0:3]
	s_setprio 0
	s_add_i32 s47, 0, 0x18000
	v_add_u32_e32 v162, s47, v146
	s_barrier
	ds_read_b128 v[150:153], v162
	ds_read_b128 v[154:157], v162 offset:1024
	ds_read_b128 v[158:161], v162 offset:2048
	ds_read_b128 v[162:165], v162 offset:3072
	s_add_u32 s20, s20, 0x40000
	s_addc_u32 s21, s21, 0
	s_mov_b32 m0, s29
	ds_read_b128 v[166:169], v148 offset:32768
	ds_read_b128 v[170:173], v148 offset:33792
	ds_read_b128 v[174:177], v148 offset:34816
	ds_read_b128 v[178:181], v148 offset:35840
	ds_read_b128 v[182:185], v148 offset:36864
	ds_read_b128 v[186:189], v148 offset:37888
	ds_read_b128 v[190:193], v148 offset:38912
	ds_read_b128 v[194:197], v148 offset:39936
	global_load_lds_dwordx4 v134, s[20:21]
	s_mov_b32 m0, s30
	s_nop 0
	global_load_lds_dwordx4 v130, s[20:21]
	s_waitcnt lgkmcnt(8)
	s_barrier
	s_waitcnt lgkmcnt(0)
	s_setprio 1
	s_waitcnt lgkmcnt(0)
	v_mfma_f32_16x16x32_bf16 v[124:127], v[150:153], v[166:169], v[124:127]
	v_mfma_f32_16x16x32_bf16 v[116:119], v[158:161], v[166:169], v[116:119]
	v_mfma_f32_16x16x32_bf16 v[108:111], v[150:153], v[174:177], v[108:111]
	v_mfma_f32_16x16x32_bf16 v[100:103], v[158:161], v[174:177], v[100:103]
	v_mfma_f32_16x16x32_bf16 v[92:95], v[150:153], v[182:185], v[92:95]
	v_mfma_f32_16x16x32_bf16 v[84:87], v[158:161], v[182:185], v[84:87]
	v_mfma_f32_16x16x32_bf16 v[76:79], v[150:153], v[190:193], v[76:79]
	v_mfma_f32_16x16x32_bf16 v[68:71], v[158:161], v[190:193], v[68:71]
	v_mfma_f32_16x16x32_bf16 v[124:127], v[154:157], v[170:173], v[124:127]
	v_mfma_f32_16x16x32_bf16 v[116:119], v[162:165], v[170:173], v[116:119]
	v_mfma_f32_16x16x32_bf16 v[108:111], v[154:157], v[178:181], v[108:111]
	v_mfma_f32_16x16x32_bf16 v[100:103], v[162:165], v[178:181], v[100:103]
	v_mfma_f32_16x16x32_bf16 v[92:95], v[154:157], v[186:189], v[92:95]
	v_mfma_f32_16x16x32_bf16 v[84:87], v[162:165], v[186:189], v[84:87]
	v_mfma_f32_16x16x32_bf16 v[76:79], v[154:157], v[194:197], v[76:79]
	v_mfma_f32_16x16x32_bf16 v[68:71], v[162:165], v[194:197], v[68:71]
	s_setprio 0
	s_barrier
	s_add_i32 s20, 0, 0x1c000
	s_add_i32 s21, s47, s25
	v_add_u32_e32 v214, s20, v146
	s_add_u32 s0, s18, 0x80
	s_addc_u32 s1, s19, 0
	s_mov_b32 m0, s21
	ds_read_b128 v[202:205], v214
	ds_read_b128 v[206:209], v214 offset:1024
	ds_read_b128 v[210:213], v214 offset:2048
	ds_read_b128 v[214:217], v214 offset:3072
	global_load_lds_dwordx4 v132, s[0:1]
	s_add_i32 m0, s21, 0x2000
	s_nop 0
	global_load_lds_dwordx4 v128, s[0:1]
	s_barrier
	s_waitcnt lgkmcnt(0)
	s_setprio 1
	s_waitcnt lgkmcnt(0)
	v_mfma_f32_16x16x32_bf16 v[120:123], v[202:205], v[166:169], v[120:123]
	v_mfma_f32_16x16x32_bf16 v[112:115], v[210:213], v[166:169], v[112:115]
	v_mfma_f32_16x16x32_bf16 v[104:107], v[202:205], v[174:177], v[104:107]
	v_mfma_f32_16x16x32_bf16 v[96:99], v[210:213], v[174:177], v[96:99]
	v_mfma_f32_16x16x32_bf16 v[88:91], v[202:205], v[182:185], v[88:91]
	v_mfma_f32_16x16x32_bf16 v[80:83], v[210:213], v[182:185], v[80:83]
	v_mfma_f32_16x16x32_bf16 v[72:75], v[202:205], v[190:193], v[72:75]
	v_mfma_f32_16x16x32_bf16 v[64:67], v[210:213], v[190:193], v[64:67]
	v_mfma_f32_16x16x32_bf16 v[120:123], v[206:209], v[170:173], v[120:123]
	v_mfma_f32_16x16x32_bf16 v[112:115], v[214:217], v[170:173], v[112:115]
	v_mfma_f32_16x16x32_bf16 v[104:107], v[206:209], v[178:181], v[104:107]
	v_mfma_f32_16x16x32_bf16 v[96:99], v[214:217], v[178:181], v[96:99]
	v_mfma_f32_16x16x32_bf16 v[88:91], v[206:209], v[186:189], v[88:91]
	v_mfma_f32_16x16x32_bf16 v[80:83], v[214:217], v[186:189], v[80:83]
	v_mfma_f32_16x16x32_bf16 v[72:75], v[206:209], v[194:197], v[72:75]
	v_mfma_f32_16x16x32_bf16 v[64:67], v[214:217], v[194:197], v[64:67]
	s_setprio 0
	s_mov_b32 m0, s35
	s_mov_b64 s[0:1], 0x80
	v_lshl_add_u64 v[198:199], v[220:221], 0, s[0:1]
	s_barrier
	ds_read_b128 v[166:169], v148 offset:49152
	ds_read_b128 v[170:173], v148 offset:50176
	ds_read_b128 v[174:177], v148 offset:51200
	ds_read_b128 v[178:181], v148 offset:52224
	ds_read_b128 v[182:185], v148 offset:53248
	ds_read_b128 v[186:189], v148 offset:54272
	ds_read_b128 v[190:193], v148 offset:55296
	ds_read_b128 v[194:197], v148 offset:56320
	global_load_lds_dwordx4 v[198:199], off
	v_lshl_add_u64 v[198:199], v[222:223], 0, s[0:1]
	s_mov_b32 m0, s36
	s_nop 0
	global_load_lds_dwordx4 v[198:199], off
	s_barrier
	s_waitcnt lgkmcnt(0)
	s_setprio 1
	s_waitcnt lgkmcnt(0)
	v_mfma_f32_16x16x32_bf16 v[60:63], v[150:153], v[166:169], v[60:63]
	v_mfma_f32_16x16x32_bf16 v[56:59], v[158:161], v[166:169], v[56:59]
	v_mfma_f32_16x16x32_bf16 v[44:47], v[150:153], v[174:177], v[44:47]
	v_mfma_f32_16x16x32_bf16 v[40:43], v[158:161], v[174:177], v[40:43]
	v_mfma_f32_16x16x32_bf16 v[28:31], v[150:153], v[182:185], v[28:31]
	v_mfma_f32_16x16x32_bf16 v[24:27], v[158:161], v[182:185], v[24:27]
	v_mfma_f32_16x16x32_bf16 v[12:15], v[150:153], v[190:193], v[12:15]
	v_mfma_f32_16x16x32_bf16 v[8:11], v[158:161], v[190:193], v[8:11]
	v_mfma_f32_16x16x32_bf16 v[60:63], v[154:157], v[170:173], v[60:63]
	v_mfma_f32_16x16x32_bf16 v[56:59], v[162:165], v[170:173], v[56:59]
	v_mfma_f32_16x16x32_bf16 v[44:47], v[154:157], v[178:181], v[44:47]
	v_mfma_f32_16x16x32_bf16 v[40:43], v[162:165], v[178:181], v[40:43]
	v_mfma_f32_16x16x32_bf16 v[28:31], v[154:157], v[186:189], v[28:31]
	v_mfma_f32_16x16x32_bf16 v[24:27], v[162:165], v[186:189], v[24:27]
	v_mfma_f32_16x16x32_bf16 v[12:15], v[154:157], v[194:197], v[12:15]
	v_mfma_f32_16x16x32_bf16 v[8:11], v[162:165], v[194:197], v[8:11]
	s_setprio 0
	s_barrier
	s_add_u32 s18, s18, 0x40080
	s_addc_u32 s19, s19, 0
	s_add_i32 s20, s20, s25
	s_mov_b32 m0, s20
	s_nop 0
	global_load_lds_dwordx4 v132, s[18:19]
	s_add_i32 m0, s20, 0x2000
	s_nop 0
	global_load_lds_dwordx4 v128, s[18:19]
	s_waitcnt vmcnt(6)
	s_barrier
	s_setprio 1
	v_mfma_f32_16x16x32_bf16 v[52:55], v[202:205], v[166:169], v[52:55]
	v_mfma_f32_16x16x32_bf16 v[48:51], v[210:213], v[166:169], v[48:51]
	v_mfma_f32_16x16x32_bf16 v[36:39], v[202:205], v[174:177], v[36:39]
	v_mfma_f32_16x16x32_bf16 v[32:35], v[210:213], v[174:177], v[32:35]
	v_mfma_f32_16x16x32_bf16 v[20:23], v[202:205], v[182:185], v[20:23]
	v_mfma_f32_16x16x32_bf16 v[16:19], v[210:213], v[182:185], v[16:19]
	v_mfma_f32_16x16x32_bf16 v[4:7], v[202:205], v[190:193], v[4:7]
	v_mfma_f32_16x16x32_bf16 v[0:3], v[210:213], v[190:193], v[0:3]
	v_mfma_f32_16x16x32_bf16 v[52:55], v[206:209], v[170:173], v[52:55]
	v_mfma_f32_16x16x32_bf16 v[48:51], v[214:217], v[170:173], v[48:51]
	v_mfma_f32_16x16x32_bf16 v[36:39], v[206:209], v[178:181], v[36:39]
	v_mfma_f32_16x16x32_bf16 v[32:35], v[214:217], v[178:181], v[32:35]
	v_mfma_f32_16x16x32_bf16 v[20:23], v[206:209], v[186:189], v[20:23]
	v_mfma_f32_16x16x32_bf16 v[16:19], v[214:217], v[186:189], v[16:19]
	v_mfma_f32_16x16x32_bf16 v[4:7], v[206:209], v[194:197], v[4:7]
	v_mfma_f32_16x16x32_bf16 v[0:3], v[214:217], v[194:197], v[0:3]
	s_setprio 0
	s_add_i32 s46, s46, 2
	s_add_u32 s16, s16, 0x100
	s_addc_u32 s17, s17, 0
	s_add_u32 s44, s44, 0x100
	s_addc_u32 s45, s45, 0
	s_cmp_gt_u32 s46, 13
	s_barrier
	s_cbranch_scc0 .LBB0_1021
	v_mul_f32_e32 v152, 0xbfb8aa3b, v124
	v_mov_b32_e32 v150, v144
	v_mov_b32_e32 v151, v145
	s_lshl_b32 s5, s14, 8
	v_exp_f32_e32 v153, v152
	v_mul_f32_e32 v152, 0xbfb8aa3b, v125
	s_add_i32 s5, s5, s33
	v_exp_f32_e32 v154, v152
	v_add_u32_e32 v150, s5, v150
	s_lshl_b32 s5, s41, 7
	s_or_b32 s5, s5, s34
	v_lshl_add_u32 v152, v151, 3, s5
	v_add_f32_e32 v151, 1.0, v153
	v_rcp_f32_e32 v151, v151
	v_add_f32_e32 v153, 1.0, v154
	v_rcp_f32_e32 v154, v153
	v_ashrrev_i32_e32 v153, 31, v152
	v_mul_f32_e32 v124, v124, v151
	v_mul_f32_e32 v120, v124, v120
	v_mul_f32_e32 v124, v125, v154
	v_mul_f32_e32 v125, 0xbfb8aa3b, v126
	v_exp_f32_e32 v125, v125
	v_mul_f32_e32 v151, 0xbfb8aa3b, v127
	v_exp_f32_e32 v151, v151
	v_mul_f32_e32 v121, v124, v121
	v_add_f32_e32 v124, 1.0, v125
	v_rcp_f32_e32 v124, v124
	v_add_f32_e32 v125, 1.0, v151
	v_rcp_f32_e32 v125, v125
	v_cvt_pk_bf16_f32 v120, v120, v121
	v_mul_f32_e32 v121, v126, v124
	v_mul_f32_e32 v124, 0xbfb8aa3b, v116
	v_mul_f32_e32 v121, v121, v122
	v_mul_f32_e32 v122, v127, v125
	v_exp_f32_e32 v124, v124
	v_mul_f32_e32 v125, 0xbfb8aa3b, v117
	v_exp_f32_e32 v125, v125
	v_mul_f32_e32 v122, v122, v123
	v_add_f32_e32 v123, 1.0, v124
	v_rcp_f32_e32 v123, v123
	v_add_f32_e32 v124, 1.0, v125
	v_rcp_f32_e32 v124, v124
	v_cvt_pk_bf16_f32 v121, v121, v122
	v_mul_f32_e32 v116, v116, v123
	v_mul_f32_e32 v112, v116, v112
	v_mul_f32_e32 v116, v117, v124
	v_mul_f32_e32 v117, 0xbfb8aa3b, v118
	v_exp_f32_e32 v117, v117
	v_mul_f32_e32 v122, 0xbfb8aa3b, v119
	v_exp_f32_e32 v122, v122
	v_mul_f32_e32 v113, v116, v113
	v_add_f32_e32 v116, 1.0, v117
	v_rcp_f32_e32 v116, v116
	v_add_f32_e32 v117, 1.0, v122
	v_rcp_f32_e32 v117, v117
	v_cvt_pk_bf16_f32 v122, v112, v113
	v_mul_f32_e32 v112, v118, v116
	v_mul_f32_e32 v118, 0xbfb8aa3b, v108
	v_mul_f32_e32 v113, v119, v117
	v_exp_f32_e32 v118, v118
	v_mul_f32_e32 v119, 0xbfb8aa3b, v109
	v_exp_f32_e32 v119, v119
	v_mul_f32_e32 v112, v112, v114
	v_add_f32_e32 v118, 1.0, v118
	v_rcp_f32_e32 v118, v118
	v_add_f32_e32 v119, 1.0, v119
	v_rcp_f32_e32 v119, v119
	v_mul_f32_e32 v113, v113, v115
	v_cvt_pk_bf16_f32 v123, v112, v113
	v_mov_b64_e32 v[112:113], s[82:83]
	v_mad_i64_i32 v[116:117], s[16:17], v150, s40, v[112:113]
	v_lshlrev_b64 v[114:115], 1, v[152:153]
	v_mul_f32_e32 v108, v108, v118
	v_lshl_add_u64 v[116:117], v[116:117], 0, v[114:115]
	v_mul_f32_e32 v104, v108, v104
	v_mul_f32_e32 v108, v109, v119
	v_mul_f32_e32 v109, 0xbfb8aa3b, v110
	global_store_dwordx4 v[116:117], v[120:123], off
	v_exp_f32_e32 v109, v109
	v_mul_f32_e32 v116, 0xbfb8aa3b, v111
	v_exp_f32_e32 v116, v116
	v_mul_f32_e32 v105, v108, v105
	v_add_f32_e32 v108, 1.0, v109
	v_rcp_f32_e32 v108, v108
	v_add_f32_e32 v109, 1.0, v116
	v_rcp_f32_e32 v109, v109
	v_cvt_pk_bf16_f32 v104, v104, v105
	v_mul_f32_e32 v105, v110, v108
	v_mul_f32_e32 v108, 0xbfb8aa3b, v100
	v_mul_f32_e32 v105, v105, v106
	v_mul_f32_e32 v106, v111, v109
	v_exp_f32_e32 v108, v108
	v_mul_f32_e32 v109, 0xbfb8aa3b, v101
	v_exp_f32_e32 v109, v109
	v_mul_f32_e32 v106, v106, v107
	v_add_f32_e32 v107, 1.0, v108
	v_rcp_f32_e32 v107, v107
	v_add_f32_e32 v108, 1.0, v109
	v_rcp_f32_e32 v108, v108
	v_cvt_pk_bf16_f32 v105, v105, v106
	v_mul_f32_e32 v100, v100, v107
	v_mul_f32_e32 v96, v100, v96
	v_mul_f32_e32 v100, v101, v108
	v_mul_f32_e32 v101, 0xbfb8aa3b, v102
	v_exp_f32_e32 v101, v101
	v_mul_f32_e32 v106, 0xbfb8aa3b, v103
	v_exp_f32_e32 v106, v106
	v_mul_f32_e32 v97, v100, v97
	v_add_f32_e32 v100, 1.0, v101
	v_rcp_f32_e32 v100, v100
	v_add_f32_e32 v101, 1.0, v106
	v_rcp_f32_e32 v101, v101
	v_cvt_pk_bf16_f32 v106, v96, v97
	v_mul_f32_e32 v96, v102, v100
	v_mul_f32_e32 v96, v96, v98
	v_mul_f32_e32 v97, v103, v101
	v_mul_f32_e32 v98, 0xbfb8aa3b, v92
	v_mul_f32_e32 v97, v97, v99
	v_exp_f32_e32 v98, v98
	v_mul_f32_e32 v99, 0xbfb8aa3b, v93
	v_exp_f32_e32 v99, v99
	v_cvt_pk_bf16_f32 v107, v96, v97
	v_add_f32_e32 v98, 1.0, v98
	v_rcp_f32_e32 v98, v98
	v_add_f32_e32 v99, 1.0, v99
	v_rcp_f32_e32 v99, v99
	v_add_u32_e32 v96, 16, v150
	v_mad_i64_i32 v[96:97], s[16:17], v96, s40, v[112:113]
	v_mul_f32_e32 v92, v92, v98
	v_lshl_add_u64 v[96:97], v[96:97], 0, v[114:115]
	v_mul_f32_e32 v88, v92, v88
	v_mul_f32_e32 v92, v93, v99
	v_mul_f32_e32 v93, 0xbfb8aa3b, v94
	global_store_dwordx4 v[96:97], v[104:107], off
	v_exp_f32_e32 v93, v93
	v_mul_f32_e32 v96, 0xbfb8aa3b, v95
	v_exp_f32_e32 v96, v96
	v_mul_f32_e32 v89, v92, v89
	v_add_f32_e32 v92, 1.0, v93
	v_rcp_f32_e32 v92, v92
	v_add_f32_e32 v93, 1.0, v96
	v_rcp_f32_e32 v93, v93
	v_cvt_pk_bf16_f32 v88, v88, v89
	v_mul_f32_e32 v89, v94, v92
	v_mul_f32_e32 v92, 0xbfb8aa3b, v84
	v_mul_f32_e32 v89, v89, v90
	v_mul_f32_e32 v90, v95, v93
	v_exp_f32_e32 v92, v92
	v_mul_f32_e32 v93, 0xbfb8aa3b, v85
	v_exp_f32_e32 v93, v93
	v_mul_f32_e32 v90, v90, v91
	v_add_f32_e32 v91, 1.0, v92
	v_rcp_f32_e32 v91, v91
	v_add_f32_e32 v92, 1.0, v93
	v_rcp_f32_e32 v92, v92
	v_cvt_pk_bf16_f32 v89, v89, v90
	v_mul_f32_e32 v84, v84, v91
	v_mul_f32_e32 v80, v84, v80
	v_mul_f32_e32 v84, v85, v92
	v_mul_f32_e32 v85, 0xbfb8aa3b, v86
	v_exp_f32_e32 v85, v85
	v_mul_f32_e32 v90, 0xbfb8aa3b, v87
	v_exp_f32_e32 v90, v90
	v_mul_f32_e32 v81, v84, v81
	v_add_f32_e32 v84, 1.0, v85
	v_rcp_f32_e32 v84, v84
	v_add_f32_e32 v85, 1.0, v90
	v_rcp_f32_e32 v85, v85
	v_cvt_pk_bf16_f32 v90, v80, v81
	v_mul_f32_e32 v80, v86, v84
	v_mul_f32_e32 v80, v80, v82
	v_mul_f32_e32 v81, v87, v85
	v_mul_f32_e32 v82, 0xbfb8aa3b, v76
	v_mul_f32_e32 v81, v81, v83
	v_exp_f32_e32 v82, v82
	v_mul_f32_e32 v83, 0xbfb8aa3b, v77
	v_exp_f32_e32 v83, v83
	v_cvt_pk_bf16_f32 v91, v80, v81
	v_add_f32_e32 v82, 1.0, v82
	v_rcp_f32_e32 v82, v82
	v_add_f32_e32 v83, 1.0, v83
	v_rcp_f32_e32 v83, v83
	v_add_u32_e32 v80, 32, v150
	v_mad_i64_i32 v[80:81], s[16:17], v80, s40, v[112:113]
	v_mul_f32_e32 v76, v76, v82
	v_lshl_add_u64 v[80:81], v[80:81], 0, v[114:115]
	v_mul_f32_e32 v72, v76, v72
	v_mul_f32_e32 v76, v77, v83
	v_mul_f32_e32 v77, 0xbfb8aa3b, v78
	global_store_dwordx4 v[80:81], v[88:91], off
	v_exp_f32_e32 v77, v77
	v_mul_f32_e32 v80, 0xbfb8aa3b, v79
	v_exp_f32_e32 v80, v80
	v_mul_f32_e32 v73, v76, v73
	v_add_f32_e32 v76, 1.0, v77
	v_rcp_f32_e32 v76, v76
	v_add_f32_e32 v77, 1.0, v80
	v_rcp_f32_e32 v77, v77
	v_cvt_pk_bf16_f32 v72, v72, v73
	v_mul_f32_e32 v73, v78, v76
	v_mul_f32_e32 v76, 0xbfb8aa3b, v68
	v_mul_f32_e32 v73, v73, v74
	v_mul_f32_e32 v74, v79, v77
	v_exp_f32_e32 v76, v76
	v_mul_f32_e32 v77, 0xbfb8aa3b, v69
	v_exp_f32_e32 v77, v77
	v_mul_f32_e32 v74, v74, v75
	v_add_f32_e32 v75, 1.0, v76
	v_rcp_f32_e32 v75, v75
	v_add_f32_e32 v76, 1.0, v77
	v_rcp_f32_e32 v76, v76
	v_cvt_pk_bf16_f32 v73, v73, v74
	v_mul_f32_e32 v68, v68, v75
	v_mul_f32_e32 v64, v68, v64
	v_mul_f32_e32 v68, v69, v76
	v_mul_f32_e32 v69, 0xbfb8aa3b, v70
	v_exp_f32_e32 v69, v69
	v_mul_f32_e32 v74, 0xbfb8aa3b, v71
	v_exp_f32_e32 v74, v74
	v_mul_f32_e32 v65, v68, v65
	v_add_f32_e32 v68, 1.0, v69
	v_rcp_f32_e32 v68, v68
	v_add_f32_e32 v69, 1.0, v74
	v_rcp_f32_e32 v69, v69
	v_cvt_pk_bf16_f32 v74, v64, v65
	v_mul_f32_e32 v64, v70, v68
	v_mul_f32_e32 v64, v64, v66
	v_mul_f32_e32 v65, v71, v69
	v_mul_f32_e32 v66, 0xbfb8aa3b, v60
	v_mul_f32_e32 v65, v65, v67
	v_exp_f32_e32 v66, v66
	v_mul_f32_e32 v67, 0xbfb8aa3b, v61
	v_cvt_pk_bf16_f32 v75, v64, v65
	v_add_u32_e32 v64, 48, v150
	v_exp_f32_e32 v67, v67
	v_mad_i64_i32 v[64:65], s[16:17], v64, s40, v[112:113]
	v_lshl_add_u64 v[64:65], v[64:65], 0, v[114:115]
	global_store_dwordx4 v[64:65], v[72:75], off
	v_add_f32_e32 v64, 1.0, v66
	v_rcp_f32_e32 v64, v64
	v_add_f32_e32 v65, 1.0, v67
	v_rcp_f32_e32 v65, v65
	v_add_u32_e32 v66, 0x80, v150
	v_mul_f32_e32 v60, v60, v64
	v_mul_f32_e32 v52, v60, v52
	v_mul_f32_e32 v60, v61, v65
	v_mul_f32_e32 v61, 0xbfb8aa3b, v62
	v_exp_f32_e32 v61, v61
	v_mul_f32_e32 v64, 0xbfb8aa3b, v63
	v_exp_f32_e32 v64, v64
	v_mul_f32_e32 v53, v60, v53
	v_add_f32_e32 v60, 1.0, v61
	v_rcp_f32_e32 v60, v60
	v_add_f32_e32 v61, 1.0, v64
	v_rcp_f32_e32 v61, v61
	v_cvt_pk_bf16_f32 v52, v52, v53
	v_mul_f32_e32 v53, v62, v60
	v_mul_f32_e32 v60, 0xbfb8aa3b, v56
	v_exp_f32_e32 v60, v60
	v_mul_f32_e32 v53, v53, v54
	v_mul_f32_e32 v54, v63, v61
	v_mul_f32_e32 v61, 0xbfb8aa3b, v57
	v_exp_f32_e32 v61, v61
	v_mul_f32_e32 v54, v54, v55
	v_add_f32_e32 v55, 1.0, v60
	v_rcp_f32_e32 v55, v55
	v_add_f32_e32 v60, 1.0, v61
	v_rcp_f32_e32 v60, v60
	v_cvt_pk_bf16_f32 v53, v53, v54
	v_mul_f32_e32 v54, v56, v55
	v_mul_f32_e32 v55, 0xbfb8aa3b, v58
	v_exp_f32_e32 v55, v55
	v_mul_f32_e32 v56, 0xbfb8aa3b, v59
	v_exp_f32_e32 v56, v56
	v_mul_f32_e32 v48, v54, v48
	v_mul_f32_e32 v54, v57, v60
	v_mul_f32_e32 v49, v54, v49
	v_add_f32_e32 v54, 1.0, v55
	v_rcp_f32_e32 v55, v54
	v_add_f32_e32 v54, 1.0, v56
	v_rcp_f32_e32 v56, v54
	v_cvt_pk_bf16_f32 v54, v48, v49
	v_mul_f32_e32 v48, v58, v55
	v_mul_f32_e32 v48, v48, v50
	v_mul_f32_e32 v49, v59, v56
	v_mul_f32_e32 v50, 0xbfb8aa3b, v44
	v_mul_f32_e32 v49, v49, v51
	v_exp_f32_e32 v50, v50
	v_mul_f32_e32 v51, 0xbfb8aa3b, v45
	v_exp_f32_e32 v51, v51
	v_cvt_pk_bf16_f32 v55, v48, v49
	v_add_f32_e32 v50, 1.0, v50
	v_rcp_f32_e32 v50, v50
	v_add_f32_e32 v51, 1.0, v51
	v_rcp_f32_e32 v51, v51
	v_mad_i64_i32 v[48:49], s[16:17], v66, s40, v[112:113]
	v_mul_f32_e32 v44, v44, v50
	v_mul_f32_e32 v36, v44, v36
	v_mul_f32_e32 v44, v45, v51
	v_mul_f32_e32 v45, 0xbfb8aa3b, v46
	v_exp_f32_e32 v45, v45
	v_lshl_add_u64 v[48:49], v[48:49], 0, v[114:115]
	global_store_dwordx4 v[48:49], v[52:55], off
	v_mul_f32_e32 v48, 0xbfb8aa3b, v47
	v_exp_f32_e32 v48, v48
	v_mul_f32_e32 v37, v44, v37
	v_add_f32_e32 v44, 1.0, v45
	v_rcp_f32_e32 v44, v44
	v_add_f32_e32 v45, 1.0, v48
	v_rcp_f32_e32 v45, v45
	v_cvt_pk_bf16_f32 v36, v36, v37
	v_mul_f32_e32 v37, v46, v44
	v_mul_f32_e32 v44, 0xbfb8aa3b, v40
	v_exp_f32_e32 v44, v44
	v_mul_f32_e32 v37, v37, v38
	v_mul_f32_e32 v38, v47, v45
	v_mul_f32_e32 v45, 0xbfb8aa3b, v41
	v_exp_f32_e32 v45, v45
	v_mul_f32_e32 v38, v38, v39
	v_add_f32_e32 v39, 1.0, v44
	v_rcp_f32_e32 v39, v39
	v_add_f32_e32 v44, 1.0, v45
	v_rcp_f32_e32 v44, v44
	v_cvt_pk_bf16_f32 v37, v37, v38
	v_mul_f32_e32 v38, v40, v39
	v_mul_f32_e32 v39, 0xbfb8aa3b, v42
	v_exp_f32_e32 v39, v39
	v_mul_f32_e32 v40, 0xbfb8aa3b, v43
	v_exp_f32_e32 v40, v40
	v_mul_f32_e32 v32, v38, v32
	v_mul_f32_e32 v38, v41, v44
	v_mul_f32_e32 v33, v38, v33
	v_add_f32_e32 v38, 1.0, v39
	v_rcp_f32_e32 v39, v38
	v_add_f32_e32 v38, 1.0, v40
	v_rcp_f32_e32 v40, v38
	v_cvt_pk_bf16_f32 v38, v32, v33
	v_mul_f32_e32 v32, v42, v39
	v_mul_f32_e32 v32, v32, v34
	v_mul_f32_e32 v33, v43, v40
	v_mul_f32_e32 v34, 0xbfb8aa3b, v28
	v_mul_f32_e32 v33, v33, v35
	v_exp_f32_e32 v34, v34
	v_mul_f32_e32 v35, 0xbfb8aa3b, v29
	v_exp_f32_e32 v35, v35
	v_cvt_pk_bf16_f32 v39, v32, v33
	v_add_f32_e32 v34, 1.0, v34
	v_rcp_f32_e32 v34, v34
	v_add_f32_e32 v35, 1.0, v35
	v_rcp_f32_e32 v35, v35
	v_add_u32_e32 v32, 0x90, v150
	v_mul_f32_e32 v28, v28, v34
	v_mul_f32_e32 v20, v28, v20
	v_mul_f32_e32 v28, v29, v35
	v_mul_f32_e32 v29, 0xbfb8aa3b, v30
	v_exp_f32_e32 v29, v29
	v_mad_i64_i32 v[32:33], s[16:17], v32, s40, v[112:113]
	v_lshl_add_u64 v[32:33], v[32:33], 0, v[114:115]
	global_store_dwordx4 v[32:33], v[36:39], off
	v_mul_f32_e32 v32, 0xbfb8aa3b, v31
	v_exp_f32_e32 v32, v32
	v_mul_f32_e32 v21, v28, v21
	v_add_f32_e32 v28, 1.0, v29
	v_rcp_f32_e32 v28, v28
	v_add_f32_e32 v29, 1.0, v32
	v_rcp_f32_e32 v29, v29
	v_cvt_pk_bf16_f32 v20, v20, v21
	v_mul_f32_e32 v21, v30, v28
	v_mul_f32_e32 v28, 0xbfb8aa3b, v24
	v_exp_f32_e32 v28, v28
	v_mul_f32_e32 v21, v21, v22
	v_mul_f32_e32 v22, v31, v29
	v_mul_f32_e32 v29, 0xbfb8aa3b, v25
	v_exp_f32_e32 v29, v29
	v_mul_f32_e32 v22, v22, v23
	v_add_f32_e32 v23, 1.0, v28
	v_rcp_f32_e32 v23, v23
	v_add_f32_e32 v28, 1.0, v29
	v_rcp_f32_e32 v28, v28
	v_cvt_pk_bf16_f32 v21, v21, v22
	v_mul_f32_e32 v22, v24, v23
	v_mul_f32_e32 v23, 0xbfb8aa3b, v26
	v_exp_f32_e32 v23, v23
	v_mul_f32_e32 v24, 0xbfb8aa3b, v27
	v_exp_f32_e32 v24, v24
	v_mul_f32_e32 v16, v22, v16
	v_mul_f32_e32 v22, v25, v28
	v_mul_f32_e32 v17, v22, v17
	v_add_f32_e32 v22, 1.0, v23
	v_rcp_f32_e32 v23, v22
	v_add_f32_e32 v22, 1.0, v24
	v_rcp_f32_e32 v24, v22
	v_cvt_pk_bf16_f32 v22, v16, v17
	v_mul_f32_e32 v16, v26, v23
	v_mul_f32_e32 v16, v16, v18
	v_mul_f32_e32 v17, v27, v24
	v_mul_f32_e32 v18, 0xbfb8aa3b, v12
	v_mul_f32_e32 v17, v17, v19
	v_exp_f32_e32 v18, v18
	v_mul_f32_e32 v19, 0xbfb8aa3b, v13
	v_exp_f32_e32 v19, v19
	v_cvt_pk_bf16_f32 v23, v16, v17
	v_add_f32_e32 v18, 1.0, v18
	v_rcp_f32_e32 v18, v18
	v_add_f32_e32 v19, 1.0, v19
	v_rcp_f32_e32 v19, v19
	v_add_u32_e32 v16, 0xa0, v150
	v_mul_f32_e32 v12, v12, v18
	v_mul_f32_e32 v4, v12, v4
	v_mul_f32_e32 v12, v13, v19
	v_mul_f32_e32 v13, 0xbfb8aa3b, v14
	v_exp_f32_e32 v13, v13
	v_mad_i64_i32 v[16:17], s[16:17], v16, s40, v[112:113]
	v_lshl_add_u64 v[16:17], v[16:17], 0, v[114:115]
	global_store_dwordx4 v[16:17], v[20:23], off
	v_mul_f32_e32 v16, 0xbfb8aa3b, v15
	v_exp_f32_e32 v16, v16
	v_mul_f32_e32 v5, v12, v5
	v_add_f32_e32 v12, 1.0, v13
	v_rcp_f32_e32 v12, v12
	v_add_f32_e32 v13, 1.0, v16
	v_rcp_f32_e32 v13, v13
	v_cvt_pk_bf16_f32 v4, v4, v5
	v_mul_f32_e32 v5, v14, v12
	v_mul_f32_e32 v12, 0xbfb8aa3b, v8
	v_exp_f32_e32 v12, v12
	v_mul_f32_e32 v5, v5, v6
	v_mul_f32_e32 v6, v15, v13
	v_mul_f32_e32 v13, 0xbfb8aa3b, v9
	v_exp_f32_e32 v13, v13
	v_mul_f32_e32 v6, v6, v7
	v_add_f32_e32 v7, 1.0, v12
	v_rcp_f32_e32 v7, v7
	v_add_f32_e32 v12, 1.0, v13
	v_rcp_f32_e32 v12, v12
	v_cvt_pk_bf16_f32 v5, v5, v6
	v_mul_f32_e32 v6, v8, v7
	v_mul_f32_e32 v7, 0xbfb8aa3b, v10
	v_exp_f32_e32 v7, v7
	v_mul_f32_e32 v8, 0xbfb8aa3b, v11
	v_exp_f32_e32 v8, v8
	v_mul_f32_e32 v0, v6, v0
	v_mul_f32_e32 v6, v9, v12
	v_mul_f32_e32 v1, v6, v1
	v_add_f32_e32 v6, 1.0, v7
	v_rcp_f32_e32 v7, v6
	v_add_f32_e32 v6, 1.0, v8
	v_rcp_f32_e32 v8, v6
	v_cvt_pk_bf16_f32 v6, v0, v1
	v_mul_f32_e32 v0, v10, v7
	v_mul_f32_e32 v0, v0, v2
	v_mul_f32_e32 v1, v11, v8
	v_mul_f32_e32 v1, v1, v3
	v_cvt_pk_bf16_f32 v7, v0, v1
	v_add_u32_e32 v0, 0xb0, v150
	v_mad_i64_i32 v[0:1], s[16:17], v0, s40, v[112:113]
	v_lshl_add_u64 v[0:1], v[0:1], 0, v[114:115]
	s_and_b64 vcc, exec, s[2:3]
	s_mov_b32 s41, s4
	s_mov_b32 s14, s6
	s_mov_b64 s[18:19], s[12:13]
	s_mov_b64 s[16:17], s[10:11]
	global_store_dwordx4 v[0:1], v[4:7], off
	s_cbranch_vccz .LBB0_1018
	s_waitcnt vmcnt(0)
	s_cmpk_gt_u32 s22, 0xff
	s_cbranch_scc1 .LBB0_1025
	s_barrier

.LBB0_1096:
	s_add_u32 s54, s24, 0x100
	s_addc_u32 s55, s25, 0
	s_mov_b32 s56, -2
	ds_read_b128 v[128:131], v241
	ds_read_b128 v[132:135], v241 offset:1024
	ds_read_b128 v[136:139], v241 offset:2048
	ds_read_b128 v[140:143], v241 offset:3072
	s_add_u32 s24, s22, 0x100
	s_addc_u32 s25, s23, 0
	s_cmp_eq_u32 s56, 40
	s_cselect_b32 s29, s5, s25
	s_cselect_b32 s28, s4, s24
	s_cselect_b32 s27, s7, s55
	s_cselect_b32 s26, s6, s54
	v_lshl_add_u64 v[176:177], s[22:23], 0, v[196:197]
	s_add_i32 m0, s35, 0xc000
	ds_read_b128 v[144:147], v242
	ds_read_b128 v[148:151], v242 offset:1024
	ds_read_b128 v[152:155], v242 offset:2048
	ds_read_b128 v[156:159], v242 offset:3072
	ds_read_b128 v[160:163], v242 offset:4096
	ds_read_b128 v[164:167], v242 offset:5120
	ds_read_b128 v[168:171], v242 offset:6144
	ds_read_b128 v[172:175], v242 offset:7168
	global_load_lds_dwordx4 v[176:177], off
	v_lshl_add_u64 v[176:177], s[22:23], 0, v[198:199]
	s_add_i32 m0, s35, 0xe000
	s_nop 0
	global_load_lds_dwordx4 v[176:177], off
	s_waitcnt lgkmcnt(8)
	s_barrier
	s_waitcnt lgkmcnt(0)
	s_setprio 1
	s_waitcnt lgkmcnt(0)
	v_mfma_f32_16x16x32_bf16 v[124:127], v[128:131], v[144:147], 0
	v_mfma_f32_16x16x32_bf16 v[120:123], v[136:139], v[144:147], 0
	v_mfma_f32_16x16x32_bf16 v[108:111], v[128:131], v[152:155], 0
	v_mfma_f32_16x16x32_bf16 v[104:107], v[136:139], v[152:155], 0
	v_mfma_f32_16x16x32_bf16 v[92:95], v[128:131], v[160:163], 0
	v_mfma_f32_16x16x32_bf16 v[88:91], v[136:139], v[160:163], 0
	v_mfma_f32_16x16x32_bf16 v[76:79], v[128:131], v[168:171], 0
	v_mfma_f32_16x16x32_bf16 v[72:75], v[136:139], v[168:171], 0
	v_mfma_f32_16x16x32_bf16 v[124:127], v[132:135], v[148:151], v[124:127]
	v_mfma_f32_16x16x32_bf16 v[120:123], v[140:143], v[148:151], v[120:123]
	v_mfma_f32_16x16x32_bf16 v[108:111], v[132:135], v[156:159], v[108:111]
	v_mfma_f32_16x16x32_bf16 v[104:107], v[140:143], v[156:159], v[104:107]
	v_mfma_f32_16x16x32_bf16 v[92:95], v[132:135], v[164:167], v[92:95]
	v_mfma_f32_16x16x32_bf16 v[88:91], v[140:143], v[164:167], v[88:91]
	v_mfma_f32_16x16x32_bf16 v[76:79], v[132:135], v[172:175], v[76:79]
	v_mfma_f32_16x16x32_bf16 v[72:75], v[140:143], v[172:175], v[72:75]
	s_setprio 0
	s_barrier
	s_add_i32 s22, s48, s34
	s_mov_b32 m0, s22
	ds_read_b128 v[176:179], v243
	ds_read_b128 v[180:183], v243 offset:1024
	ds_read_b128 v[184:187], v243 offset:2048
	ds_read_b128 v[206:209], v243 offset:3072
	global_load_lds_dwordx4 v190, s[26:27]
	s_add_i32 m0, s22, 0x2000
	s_nop 0
	global_load_lds_dwordx4 v194, s[26:27]
	s_barrier
	s_waitcnt lgkmcnt(0)
	s_setprio 1
	s_waitcnt lgkmcnt(0)
	v_mfma_f32_16x16x32_bf16 v[116:119], v[176:179], v[144:147], 0
	v_mfma_f32_16x16x32_bf16 v[112:115], v[184:187], v[144:147], 0
	v_mfma_f32_16x16x32_bf16 v[100:103], v[176:179], v[152:155], 0
	v_mfma_f32_16x16x32_bf16 v[96:99], v[184:187], v[152:155], 0
	v_mfma_f32_16x16x32_bf16 v[84:87], v[176:179], v[160:163], 0
	v_mfma_f32_16x16x32_bf16 v[80:83], v[184:187], v[160:163], 0
	v_mfma_f32_16x16x32_bf16 v[68:71], v[176:179], v[168:171], 0
	v_mfma_f32_16x16x32_bf16 v[64:67], v[184:187], v[168:171], 0
	v_mfma_f32_16x16x32_bf16 v[116:119], v[180:183], v[148:151], v[116:119]
	v_mfma_f32_16x16x32_bf16 v[112:115], v[206:209], v[148:151], v[112:115]
	v_mfma_f32_16x16x32_bf16 v[100:103], v[180:183], v[156:159], v[100:103]
	v_mfma_f32_16x16x32_bf16 v[96:99], v[206:209], v[156:159], v[96:99]
	v_mfma_f32_16x16x32_bf16 v[84:87], v[180:183], v[164:167], v[84:87]
	v_mfma_f32_16x16x32_bf16 v[80:83], v[206:209], v[164:167], v[80:83]
	v_mfma_f32_16x16x32_bf16 v[68:71], v[180:183], v[172:175], v[68:71]
	v_mfma_f32_16x16x32_bf16 v[64:67], v[206:209], v[172:175], v[64:67]
	s_setprio 0
	s_mov_b32 m0, s35
	v_lshl_add_u64 v[214:215], s[28:29], 0, v[188:189]
	s_barrier
	ds_read_b128 v[144:147], v242 offset:16384
	ds_read_b128 v[148:151], v242 offset:17408
	ds_read_b128 v[152:155], v242 offset:18432
	ds_read_b128 v[156:159], v242 offset:19456
	ds_read_b128 v[160:163], v242 offset:20480
	ds_read_b128 v[164:167], v242 offset:21504
	ds_read_b128 v[168:171], v242 offset:22528
	ds_read_b128 v[172:175], v242 offset:23552
	global_load_lds_dwordx4 v188, s[28:29]
	v_lshl_add_u64 v[216:217], s[28:29], 0, v[192:193]
	s_mov_b32 m0, s36
	s_nop 0
	global_load_lds_dwordx4 v192, s[28:29]
	s_barrier
	s_waitcnt lgkmcnt(0)
	s_setprio 1
	s_waitcnt lgkmcnt(0)
	v_mfma_f32_16x16x32_bf16 v[60:63], v[128:131], v[144:147], 0
	v_mfma_f32_16x16x32_bf16 v[56:59], v[136:139], v[144:147], 0
	v_mfma_f32_16x16x32_bf16 v[44:47], v[128:131], v[152:155], 0
	v_mfma_f32_16x16x32_bf16 v[40:43], v[136:139], v[152:155], 0
	v_mfma_f32_16x16x32_bf16 v[28:31], v[128:131], v[160:163], 0
	v_mfma_f32_16x16x32_bf16 v[24:27], v[136:139], v[160:163], 0
	v_mfma_f32_16x16x32_bf16 v[12:15], v[128:131], v[168:171], 0
	v_mfma_f32_16x16x32_bf16 v[8:11], v[136:139], v[168:171], 0
	v_mfma_f32_16x16x32_bf16 v[60:63], v[132:135], v[148:151], v[60:63]
	v_mfma_f32_16x16x32_bf16 v[56:59], v[140:143], v[148:151], v[56:59]
	v_mfma_f32_16x16x32_bf16 v[44:47], v[132:135], v[156:159], v[44:47]
	v_mfma_f32_16x16x32_bf16 v[40:43], v[140:143], v[156:159], v[40:43]
	v_mfma_f32_16x16x32_bf16 v[28:31], v[132:135], v[164:167], v[28:31]
	v_mfma_f32_16x16x32_bf16 v[24:27], v[140:143], v[164:167], v[24:27]
	v_mfma_f32_16x16x32_bf16 v[12:15], v[132:135], v[172:175], v[12:15]
	v_mfma_f32_16x16x32_bf16 v[8:11], v[140:143], v[172:175], v[8:11]
	s_setprio 0
	s_barrier
	s_add_u32 s22, s26, 0xb0000
	s_addc_u32 s23, s27, 0
	s_add_i32 s57, s49, s34
	s_mov_b32 m0, s57
	s_nop 0
	global_load_lds_dwordx4 v190, s[22:23]
	s_add_i32 m0, s57, 0x2000
	s_nop 0
	global_load_lds_dwordx4 v194, s[22:23]
	s_waitcnt vmcnt(6)
	s_barrier
	s_setprio 1
	v_mfma_f32_16x16x32_bf16 v[52:55], v[176:179], v[144:147], 0
	v_mfma_f32_16x16x32_bf16 v[48:51], v[184:187], v[144:147], 0
	v_mfma_f32_16x16x32_bf16 v[36:39], v[176:179], v[152:155], 0
	v_mfma_f32_16x16x32_bf16 v[32:35], v[184:187], v[152:155], 0
	v_mfma_f32_16x16x32_bf16 v[20:23], v[176:179], v[160:163], 0
	v_mfma_f32_16x16x32_bf16 v[16:19], v[184:187], v[160:163], 0
	v_mfma_f32_16x16x32_bf16 v[4:7], v[176:179], v[168:171], 0
	v_mfma_f32_16x16x32_bf16 v[0:3], v[184:187], v[168:171], 0
	v_mfma_f32_16x16x32_bf16 v[52:55], v[180:183], v[148:151], v[52:55]
	v_mfma_f32_16x16x32_bf16 v[48:51], v[206:209], v[148:151], v[48:51]
	v_mfma_f32_16x16x32_bf16 v[36:39], v[180:183], v[156:159], v[36:39]
	v_mfma_f32_16x16x32_bf16 v[32:35], v[206:209], v[156:159], v[32:35]
	v_mfma_f32_16x16x32_bf16 v[20:23], v[180:183], v[164:167], v[20:23]
	v_mfma_f32_16x16x32_bf16 v[16:19], v[206:209], v[164:167], v[16:19]
	v_mfma_f32_16x16x32_bf16 v[4:7], v[180:183], v[172:175], v[4:7]
	v_mfma_f32_16x16x32_bf16 v[0:3], v[206:209], v[172:175], v[0:3]
	s_setprio 0
	s_add_i32 s57, 0, 0x18000
	v_add_u32_e32 v140, s57, v240
	s_barrier
	ds_read_b128 v[128:131], v140
	ds_read_b128 v[132:135], v140 offset:1024
	ds_read_b128 v[136:139], v140 offset:2048
	ds_read_b128 v[140:143], v140 offset:3072
	s_add_u32 s22, s28, 0xb0000
	s_addc_u32 s23, s29, 0
	s_mov_b32 m0, s37
	ds_read_b128 v[144:147], v242 offset:32768
	ds_read_b128 v[148:151], v242 offset:33792
	ds_read_b128 v[152:155], v242 offset:34816
	ds_read_b128 v[156:159], v242 offset:35840
	ds_read_b128 v[160:163], v242 offset:36864
	ds_read_b128 v[164:167], v242 offset:37888
	ds_read_b128 v[168:171], v242 offset:38912
	ds_read_b128 v[172:175], v242 offset:39936
	global_load_lds_dwordx4 v188, s[22:23]
	s_mov_b32 m0, s38
	s_nop 0
	global_load_lds_dwordx4 v192, s[22:23]
	s_waitcnt lgkmcnt(8)
	s_barrier
	s_waitcnt lgkmcnt(0)
	s_setprio 1
	s_waitcnt lgkmcnt(0)
	v_mfma_f32_16x16x32_bf16 v[124:127], v[128:131], v[144:147], v[124:127]
	v_mfma_f32_16x16x32_bf16 v[120:123], v[136:139], v[144:147], v[120:123]
	v_mfma_f32_16x16x32_bf16 v[108:111], v[128:131], v[152:155], v[108:111]
	v_mfma_f32_16x16x32_bf16 v[104:107], v[136:139], v[152:155], v[104:107]
	v_mfma_f32_16x16x32_bf16 v[92:95], v[128:131], v[160:163], v[92:95]
	v_mfma_f32_16x16x32_bf16 v[88:91], v[136:139], v[160:163], v[88:91]
	v_mfma_f32_16x16x32_bf16 v[76:79], v[128:131], v[168:171], v[76:79]
	v_mfma_f32_16x16x32_bf16 v[72:75], v[136:139], v[168:171], v[72:75]
	v_mfma_f32_16x16x32_bf16 v[124:127], v[132:135], v[148:151], v[124:127]
	v_mfma_f32_16x16x32_bf16 v[120:123], v[140:143], v[148:151], v[120:123]
	v_mfma_f32_16x16x32_bf16 v[108:111], v[132:135], v[156:159], v[108:111]
	v_mfma_f32_16x16x32_bf16 v[104:107], v[140:143], v[156:159], v[104:107]
	v_mfma_f32_16x16x32_bf16 v[92:95], v[132:135], v[164:167], v[92:95]
	v_mfma_f32_16x16x32_bf16 v[88:91], v[140:143], v[164:167], v[88:91]
	v_mfma_f32_16x16x32_bf16 v[76:79], v[132:135], v[172:175], v[76:79]
	v_mfma_f32_16x16x32_bf16 v[72:75], v[140:143], v[172:175], v[72:75]
	s_setprio 0
	s_barrier
	s_add_i32 s28, 0, 0x1c000
	s_add_i32 s22, s57, s34
	v_add_u32_e32 v206, s28, v240
	s_add_u32 s0, s26, 0x80
	s_addc_u32 s1, s27, 0
	s_mov_b32 m0, s22
	ds_read_b128 v[176:179], v206
	ds_read_b128 v[180:183], v206 offset:1024
	ds_read_b128 v[184:187], v206 offset:2048
	ds_read_b128 v[206:209], v206 offset:3072
	global_load_lds_dwordx4 v190, s[0:1]
	s_add_i32 m0, s22, 0x2000
	s_nop 0
	global_load_lds_dwordx4 v194, s[0:1]
	s_barrier
	s_waitcnt lgkmcnt(0)
	s_setprio 1
	s_waitcnt lgkmcnt(0)
	v_mfma_f32_16x16x32_bf16 v[116:119], v[176:179], v[144:147], v[116:119]
	v_mfma_f32_16x16x32_bf16 v[112:115], v[184:187], v[144:147], v[112:115]
	v_mfma_f32_16x16x32_bf16 v[100:103], v[176:179], v[152:155], v[100:103]
	v_mfma_f32_16x16x32_bf16 v[96:99], v[184:187], v[152:155], v[96:99]
	v_mfma_f32_16x16x32_bf16 v[84:87], v[176:179], v[160:163], v[84:87]
	v_mfma_f32_16x16x32_bf16 v[80:83], v[184:187], v[160:163], v[80:83]
	v_mfma_f32_16x16x32_bf16 v[68:71], v[176:179], v[168:171], v[68:71]
	v_mfma_f32_16x16x32_bf16 v[64:67], v[184:187], v[168:171], v[64:67]
	v_mfma_f32_16x16x32_bf16 v[116:119], v[180:183], v[148:151], v[116:119]
	v_mfma_f32_16x16x32_bf16 v[112:115], v[206:209], v[148:151], v[112:115]
	v_mfma_f32_16x16x32_bf16 v[100:103], v[180:183], v[156:159], v[100:103]
	v_mfma_f32_16x16x32_bf16 v[96:99], v[206:209], v[156:159], v[96:99]
	v_mfma_f32_16x16x32_bf16 v[84:87], v[180:183], v[164:167], v[84:87]
	v_mfma_f32_16x16x32_bf16 v[80:83], v[206:209], v[164:167], v[80:83]
	v_mfma_f32_16x16x32_bf16 v[68:71], v[180:183], v[172:175], v[68:71]
	v_mfma_f32_16x16x32_bf16 v[64:67], v[206:209], v[172:175], v[64:67]
	s_setprio 0
	s_mov_b32 m0, s44
	s_mov_b64 s[0:1], 0x80
	v_lshl_add_u64 v[210:211], v[214:215], 0, s[0:1]
	s_barrier
	ds_read_b128 v[144:147], v242 offset:49152
	ds_read_b128 v[148:151], v242 offset:50176
	ds_read_b128 v[152:155], v242 offset:51200
	ds_read_b128 v[156:159], v242 offset:52224
	ds_read_b128 v[160:163], v242 offset:53248
	ds_read_b128 v[164:167], v242 offset:54272
	ds_read_b128 v[168:171], v242 offset:55296
	ds_read_b128 v[172:175], v242 offset:56320
	global_load_lds_dwordx4 v[210:211], off
	v_lshl_add_u64 v[210:211], v[216:217], 0, s[0:1]
	s_mov_b32 m0, s45
	s_nop 0
	global_load_lds_dwordx4 v[210:211], off
	s_barrier
	s_waitcnt lgkmcnt(0)
	s_setprio 1
	s_waitcnt lgkmcnt(0)
	v_mfma_f32_16x16x32_bf16 v[60:63], v[128:131], v[144:147], v[60:63]
	v_mfma_f32_16x16x32_bf16 v[56:59], v[136:139], v[144:147], v[56:59]
	v_mfma_f32_16x16x32_bf16 v[44:47], v[128:131], v[152:155], v[44:47]
	v_mfma_f32_16x16x32_bf16 v[40:43], v[136:139], v[152:155], v[40:43]
	v_mfma_f32_16x16x32_bf16 v[28:31], v[128:131], v[160:163], v[28:31]
	v_mfma_f32_16x16x32_bf16 v[24:27], v[136:139], v[160:163], v[24:27]
	v_mfma_f32_16x16x32_bf16 v[12:15], v[128:131], v[168:171], v[12:15]
	v_mfma_f32_16x16x32_bf16 v[8:11], v[136:139], v[168:171], v[8:11]
	v_mfma_f32_16x16x32_bf16 v[60:63], v[132:135], v[148:151], v[60:63]
	v_mfma_f32_16x16x32_bf16 v[56:59], v[140:143], v[148:151], v[56:59]
	v_mfma_f32_16x16x32_bf16 v[44:47], v[132:135], v[156:159], v[44:47]
	v_mfma_f32_16x16x32_bf16 v[40:43], v[140:143], v[156:159], v[40:43]
	v_mfma_f32_16x16x32_bf16 v[28:31], v[132:135], v[164:167], v[28:31]
	v_mfma_f32_16x16x32_bf16 v[24:27], v[140:143], v[164:167], v[24:27]
	v_mfma_f32_16x16x32_bf16 v[12:15], v[132:135], v[172:175], v[12:15]
	v_mfma_f32_16x16x32_bf16 v[8:11], v[140:143], v[172:175], v[8:11]
	s_setprio 0
	s_barrier
	s_add_u32 s22, s26, 0xb0080
	s_addc_u32 s23, s27, 0
	s_add_i32 s26, s28, s34
	s_mov_b32 m0, s26
	s_nop 0
	global_load_lds_dwordx4 v190, s[22:23]
	s_add_i32 m0, s26, 0x2000
	s_nop 0
	global_load_lds_dwordx4 v194, s[22:23]
	s_waitcnt vmcnt(6)
	s_barrier
	s_setprio 1
	v_mfma_f32_16x16x32_bf16 v[52:55], v[176:179], v[144:147], v[52:55]
	v_mfma_f32_16x16x32_bf16 v[48:51], v[184:187], v[144:147], v[48:51]
	v_mfma_f32_16x16x32_bf16 v[36:39], v[176:179], v[152:155], v[36:39]
	v_mfma_f32_16x16x32_bf16 v[32:35], v[184:187], v[152:155], v[32:35]
	v_mfma_f32_16x16x32_bf16 v[20:23], v[176:179], v[160:163], v[20:23]
	v_mfma_f32_16x16x32_bf16 v[16:19], v[184:187], v[160:163], v[16:19]
	v_mfma_f32_16x16x32_bf16 v[4:7], v[176:179], v[168:171], v[4:7]
	v_mfma_f32_16x16x32_bf16 v[0:3], v[184:187], v[168:171], v[0:3]
	v_mfma_f32_16x16x32_bf16 v[52:55], v[180:183], v[148:151], v[52:55]
	v_mfma_f32_16x16x32_bf16 v[48:51], v[206:209], v[148:151], v[48:51]
	v_mfma_f32_16x16x32_bf16 v[36:39], v[180:183], v[156:159], v[36:39]
	v_mfma_f32_16x16x32_bf16 v[32:35], v[206:209], v[156:159], v[32:35]
	v_mfma_f32_16x16x32_bf16 v[20:23], v[180:183], v[164:167], v[20:23]
	v_mfma_f32_16x16x32_bf16 v[16:19], v[206:209], v[164:167], v[16:19]
	v_mfma_f32_16x16x32_bf16 v[4:7], v[180:183], v[172:175], v[4:7]
	v_mfma_f32_16x16x32_bf16 v[0:3], v[206:209], v[172:175], v[0:3]
	s_setprio 0
	s_add_i32 s56, s56, 2
	s_add_u32 s54, s54, 0x100
	s_addc_u32 s55, s55, 0
	s_cmp_gt_u32 s56, 41
	s_mov_b64 s[22:23], s[24:25]
	s_barrier
.LBB0_1097:
	ds_read_b128 v[128:131], v241
	ds_read_b128 v[132:135], v241 offset:1024
	ds_read_b128 v[136:139], v241 offset:2048
	ds_read_b128 v[140:143], v241 offset:3072
	s_add_u32 s24, s22, 0x100
	s_addc_u32 s25, s23, 0
	s_cmp_eq_u32 s56, 40
	s_cselect_b32 s29, s5, s25
	s_cselect_b32 s28, s4, s24
	s_cselect_b32 s27, s7, s55
	s_cselect_b32 s26, s6, s54
	v_lshl_add_u64 v[176:177], s[22:23], 0, v[196:197]
	s_add_i32 m0, s35, 0xc000
	ds_read_b128 v[144:147], v242
	ds_read_b128 v[148:151], v242 offset:1024
	ds_read_b128 v[152:155], v242 offset:2048
	ds_read_b128 v[156:159], v242 offset:3072
	ds_read_b128 v[160:163], v242 offset:4096
	ds_read_b128 v[164:167], v242 offset:5120
	ds_read_b128 v[168:171], v242 offset:6144
	ds_read_b128 v[172:175], v242 offset:7168
	global_load_lds_dwordx4 v[176:177], off
	v_lshl_add_u64 v[176:177], s[22:23], 0, v[198:199]
	s_add_i32 m0, s35, 0xe000
	s_nop 0
	global_load_lds_dwordx4 v[176:177], off
	s_waitcnt lgkmcnt(8)
	s_barrier
	s_waitcnt lgkmcnt(0)
	s_setprio 1
	s_waitcnt lgkmcnt(0)
	v_mfma_f32_16x16x32_bf16 v[124:127], v[128:131], v[144:147], v[124:127]
	v_mfma_f32_16x16x32_bf16 v[120:123], v[136:139], v[144:147], v[120:123]
	v_mfma_f32_16x16x32_bf16 v[108:111], v[128:131], v[152:155], v[108:111]
	v_mfma_f32_16x16x32_bf16 v[104:107], v[136:139], v[152:155], v[104:107]
	v_mfma_f32_16x16x32_bf16 v[92:95], v[128:131], v[160:163], v[92:95]
	v_mfma_f32_16x16x32_bf16 v[88:91], v[136:139], v[160:163], v[88:91]
	v_mfma_f32_16x16x32_bf16 v[76:79], v[128:131], v[168:171], v[76:79]
	v_mfma_f32_16x16x32_bf16 v[72:75], v[136:139], v[168:171], v[72:75]
	v_mfma_f32_16x16x32_bf16 v[124:127], v[132:135], v[148:151], v[124:127]
	v_mfma_f32_16x16x32_bf16 v[120:123], v[140:143], v[148:151], v[120:123]
	v_mfma_f32_16x16x32_bf16 v[108:111], v[132:135], v[156:159], v[108:111]
	v_mfma_f32_16x16x32_bf16 v[104:107], v[140:143], v[156:159], v[104:107]
	v_mfma_f32_16x16x32_bf16 v[92:95], v[132:135], v[164:167], v[92:95]
	v_mfma_f32_16x16x32_bf16 v[88:91], v[140:143], v[164:167], v[88:91]
	v_mfma_f32_16x16x32_bf16 v[76:79], v[132:135], v[172:175], v[76:79]
	v_mfma_f32_16x16x32_bf16 v[72:75], v[140:143], v[172:175], v[72:75]
	s_setprio 0
	s_barrier
	s_add_i32 s22, s48, s34
	s_mov_b32 m0, s22
	ds_read_b128 v[176:179], v243
	ds_read_b128 v[180:183], v243 offset:1024
	ds_read_b128 v[184:187], v243 offset:2048
	ds_read_b128 v[206:209], v243 offset:3072
	global_load_lds_dwordx4 v190, s[26:27]
	s_add_i32 m0, s22, 0x2000
	s_nop 0
	global_load_lds_dwordx4 v194, s[26:27]
	s_barrier
	s_waitcnt lgkmcnt(0)
	s_setprio 1
	s_waitcnt lgkmcnt(0)
	v_mfma_f32_16x16x32_bf16 v[116:119], v[176:179], v[144:147], v[116:119]
	v_mfma_f32_16x16x32_bf16 v[112:115], v[184:187], v[144:147], v[112:115]
	v_mfma_f32_16x16x32_bf16 v[100:103], v[176:179], v[152:155], v[100:103]
	v_mfma_f32_16x16x32_bf16 v[96:99], v[184:187], v[152:155], v[96:99]
	v_mfma_f32_16x16x32_bf16 v[84:87], v[176:179], v[160:163], v[84:87]
	v_mfma_f32_16x16x32_bf16 v[80:83], v[184:187], v[160:163], v[80:83]
	v_mfma_f32_16x16x32_bf16 v[68:71], v[176:179], v[168:171], v[68:71]
	v_mfma_f32_16x16x32_bf16 v[64:67], v[184:187], v[168:171], v[64:67]
	v_mfma_f32_16x16x32_bf16 v[116:119], v[180:183], v[148:151], v[116:119]
	v_mfma_f32_16x16x32_bf16 v[112:115], v[206:209], v[148:151], v[112:115]
	v_mfma_f32_16x16x32_bf16 v[100:103], v[180:183], v[156:159], v[100:103]
	v_mfma_f32_16x16x32_bf16 v[96:99], v[206:209], v[156:159], v[96:99]
	v_mfma_f32_16x16x32_bf16 v[84:87], v[180:183], v[164:167], v[84:87]
	v_mfma_f32_16x16x32_bf16 v[80:83], v[206:209], v[164:167], v[80:83]
	v_mfma_f32_16x16x32_bf16 v[68:71], v[180:183], v[172:175], v[68:71]
	v_mfma_f32_16x16x32_bf16 v[64:67], v[206:209], v[172:175], v[64:67]
	s_setprio 0
	s_mov_b32 m0, s35
	v_lshl_add_u64 v[214:215], s[28:29], 0, v[188:189]
	s_barrier
	ds_read_b128 v[144:147], v242 offset:16384
	ds_read_b128 v[148:151], v242 offset:17408
	ds_read_b128 v[152:155], v242 offset:18432
	ds_read_b128 v[156:159], v242 offset:19456
	ds_read_b128 v[160:163], v242 offset:20480
	ds_read_b128 v[164:167], v242 offset:21504
	ds_read_b128 v[168:171], v242 offset:22528
	ds_read_b128 v[172:175], v242 offset:23552
	global_load_lds_dwordx4 v188, s[28:29]
	v_lshl_add_u64 v[216:217], s[28:29], 0, v[192:193]
	s_mov_b32 m0, s36
	s_nop 0
	global_load_lds_dwordx4 v192, s[28:29]
	s_barrier
	s_waitcnt lgkmcnt(0)
	s_setprio 1
	s_waitcnt lgkmcnt(0)
	v_mfma_f32_16x16x32_bf16 v[60:63], v[128:131], v[144:147], v[60:63]
	v_mfma_f32_16x16x32_bf16 v[56:59], v[136:139], v[144:147], v[56:59]
	v_mfma_f32_16x16x32_bf16 v[44:47], v[128:131], v[152:155], v[44:47]
	v_mfma_f32_16x16x32_bf16 v[40:43], v[136:139], v[152:155], v[40:43]
	v_mfma_f32_16x16x32_bf16 v[28:31], v[128:131], v[160:163], v[28:31]
	v_mfma_f32_16x16x32_bf16 v[24:27], v[136:139], v[160:163], v[24:27]
	v_mfma_f32_16x16x32_bf16 v[12:15], v[128:131], v[168:171], v[12:15]
	v_mfma_f32_16x16x32_bf16 v[8:11], v[136:139], v[168:171], v[8:11]
	v_mfma_f32_16x16x32_bf16 v[60:63], v[132:135], v[148:151], v[60:63]
	v_mfma_f32_16x16x32_bf16 v[56:59], v[140:143], v[148:151], v[56:59]
	v_mfma_f32_16x16x32_bf16 v[44:47], v[132:135], v[156:159], v[44:47]
	v_mfma_f32_16x16x32_bf16 v[40:43], v[140:143], v[156:159], v[40:43]
	v_mfma_f32_16x16x32_bf16 v[28:31], v[132:135], v[164:167], v[28:31]
	v_mfma_f32_16x16x32_bf16 v[24:27], v[140:143], v[164:167], v[24:27]
	v_mfma_f32_16x16x32_bf16 v[12:15], v[132:135], v[172:175], v[12:15]
	v_mfma_f32_16x16x32_bf16 v[8:11], v[140:143], v[172:175], v[8:11]
	s_setprio 0
	s_barrier
	s_add_u32 s22, s26, 0xb0000
	s_addc_u32 s23, s27, 0
	s_add_i32 s57, s49, s34
	s_mov_b32 m0, s57
	s_nop 0
	global_load_lds_dwordx4 v190, s[22:23]
	s_add_i32 m0, s57, 0x2000
	s_nop 0
	global_load_lds_dwordx4 v194, s[22:23]
	s_waitcnt vmcnt(6)
	s_barrier
	s_setprio 1
	v_mfma_f32_16x16x32_bf16 v[52:55], v[176:179], v[144:147], v[52:55]
	v_mfma_f32_16x16x32_bf16 v[48:51], v[184:187], v[144:147], v[48:51]
	v_mfma_f32_16x16x32_bf16 v[36:39], v[176:179], v[152:155], v[36:39]
	v_mfma_f32_16x16x32_bf16 v[32:35], v[184:187], v[152:155], v[32:35]
	v_mfma_f32_16x16x32_bf16 v[20:23], v[176:179], v[160:163], v[20:23]
	v_mfma_f32_16x16x32_bf16 v[16:19], v[184:187], v[160:163], v[16:19]
	v_mfma_f32_16x16x32_bf16 v[4:7], v[176:179], v[168:171], v[4:7]
	v_mfma_f32_16x16x32_bf16 v[0:3], v[184:187], v[168:171], v[0:3]
	v_mfma_f32_16x16x32_bf16 v[52:55], v[180:183], v[148:151], v[52:55]
	v_mfma_f32_16x16x32_bf16 v[48:51], v[206:209], v[148:151], v[48:51]
	v_mfma_f32_16x16x32_bf16 v[36:39], v[180:183], v[156:159], v[36:39]
	v_mfma_f32_16x16x32_bf16 v[32:35], v[206:209], v[156:159], v[32:35]
	v_mfma_f32_16x16x32_bf16 v[20:23], v[180:183], v[164:167], v[20:23]
	v_mfma_f32_16x16x32_bf16 v[16:19], v[206:209], v[164:167], v[16:19]
	v_mfma_f32_16x16x32_bf16 v[4:7], v[180:183], v[172:175], v[4:7]
	v_mfma_f32_16x16x32_bf16 v[0:3], v[206:209], v[172:175], v[0:3]
	s_setprio 0
	s_add_i32 s57, 0, 0x18000
	v_add_u32_e32 v140, s57, v240
	s_barrier
	ds_read_b128 v[128:131], v140
	ds_read_b128 v[132:135], v140 offset:1024
	ds_read_b128 v[136:139], v140 offset:2048
	ds_read_b128 v[140:143], v140 offset:3072
	s_add_u32 s22, s28, 0xb0000
	s_addc_u32 s23, s29, 0
	s_mov_b32 m0, s37
	ds_read_b128 v[144:147], v242 offset:32768
	ds_read_b128 v[148:151], v242 offset:33792
	ds_read_b128 v[152:155], v242 offset:34816
	ds_read_b128 v[156:159], v242 offset:35840
	ds_read_b128 v[160:163], v242 offset:36864
	ds_read_b128 v[164:167], v242 offset:37888
	ds_read_b128 v[168:171], v242 offset:38912
	ds_read_b128 v[172:175], v242 offset:39936
	global_load_lds_dwordx4 v188, s[22:23]
	s_mov_b32 m0, s38
	s_nop 0
	global_load_lds_dwordx4 v192, s[22:23]
	s_waitcnt lgkmcnt(8)
	s_barrier
	s_waitcnt lgkmcnt(0)
	s_setprio 1
	s_waitcnt lgkmcnt(0)
	v_mfma_f32_16x16x32_bf16 v[124:127], v[128:131], v[144:147], v[124:127]
	v_mfma_f32_16x16x32_bf16 v[120:123], v[136:139], v[144:147], v[120:123]
	v_mfma_f32_16x16x32_bf16 v[108:111], v[128:131], v[152:155], v[108:111]
	v_mfma_f32_16x16x32_bf16 v[104:107], v[136:139], v[152:155], v[104:107]
	v_mfma_f32_16x16x32_bf16 v[92:95], v[128:131], v[160:163], v[92:95]
	v_mfma_f32_16x16x32_bf16 v[88:91], v[136:139], v[160:163], v[88:91]
	v_mfma_f32_16x16x32_bf16 v[76:79], v[128:131], v[168:171], v[76:79]
	v_mfma_f32_16x16x32_bf16 v[72:75], v[136:139], v[168:171], v[72:75]
	v_mfma_f32_16x16x32_bf16 v[124:127], v[132:135], v[148:151], v[124:127]
	v_mfma_f32_16x16x32_bf16 v[120:123], v[140:143], v[148:151], v[120:123]
	v_mfma_f32_16x16x32_bf16 v[108:111], v[132:135], v[156:159], v[108:111]
	v_mfma_f32_16x16x32_bf16 v[104:107], v[140:143], v[156:159], v[104:107]
	v_mfma_f32_16x16x32_bf16 v[92:95], v[132:135], v[164:167], v[92:95]
	v_mfma_f32_16x16x32_bf16 v[88:91], v[140:143], v[164:167], v[88:91]
	v_mfma_f32_16x16x32_bf16 v[76:79], v[132:135], v[172:175], v[76:79]
	v_mfma_f32_16x16x32_bf16 v[72:75], v[140:143], v[172:175], v[72:75]
	s_setprio 0
	s_barrier
	s_add_i32 s28, 0, 0x1c000
	s_add_i32 s22, s57, s34
	v_add_u32_e32 v206, s28, v240
	s_add_u32 s0, s26, 0x80
	s_addc_u32 s1, s27, 0
	s_mov_b32 m0, s22
	ds_read_b128 v[176:179], v206
	ds_read_b128 v[180:183], v206 offset:1024
	ds_read_b128 v[184:187], v206 offset:2048
	ds_read_b128 v[206:209], v206 offset:3072
	global_load_lds_dwordx4 v190, s[0:1]
	s_add_i32 m0, s22, 0x2000
	s_nop 0
	global_load_lds_dwordx4 v194, s[0:1]
	s_barrier
	s_waitcnt lgkmcnt(0)
	s_setprio 1
	s_waitcnt lgkmcnt(0)
	v_mfma_f32_16x16x32_bf16 v[116:119], v[176:179], v[144:147], v[116:119]
	v_mfma_f32_16x16x32_bf16 v[112:115], v[184:187], v[144:147], v[112:115]
	v_mfma_f32_16x16x32_bf16 v[100:103], v[176:179], v[152:155], v[100:103]
	v_mfma_f32_16x16x32_bf16 v[96:99], v[184:187], v[152:155], v[96:99]
	v_mfma_f32_16x16x32_bf16 v[84:87], v[176:179], v[160:163], v[84:87]
	v_mfma_f32_16x16x32_bf16 v[80:83], v[184:187], v[160:163], v[80:83]
	v_mfma_f32_16x16x32_bf16 v[68:71], v[176:179], v[168:171], v[68:71]
	v_mfma_f32_16x16x32_bf16 v[64:67], v[184:187], v[168:171], v[64:67]
	v_mfma_f32_16x16x32_bf16 v[116:119], v[180:183], v[148:151], v[116:119]
	v_mfma_f32_16x16x32_bf16 v[112:115], v[206:209], v[148:151], v[112:115]
	v_mfma_f32_16x16x32_bf16 v[100:103], v[180:183], v[156:159], v[100:103]
	v_mfma_f32_16x16x32_bf16 v[96:99], v[206:209], v[156:159], v[96:99]
	v_mfma_f32_16x16x32_bf16 v[84:87], v[180:183], v[164:167], v[84:87]
	v_mfma_f32_16x16x32_bf16 v[80:83], v[206:209], v[164:167], v[80:83]
	v_mfma_f32_16x16x32_bf16 v[68:71], v[180:183], v[172:175], v[68:71]
	v_mfma_f32_16x16x32_bf16 v[64:67], v[206:209], v[172:175], v[64:67]
	s_setprio 0
	s_mov_b32 m0, s44
	s_mov_b64 s[0:1], 0x80
	v_lshl_add_u64 v[210:211], v[214:215], 0, s[0:1]
	s_barrier
	ds_read_b128 v[144:147], v242 offset:49152
	ds_read_b128 v[148:151], v242 offset:50176
	ds_read_b128 v[152:155], v242 offset:51200
	ds_read_b128 v[156:159], v242 offset:52224
	ds_read_b128 v[160:163], v242 offset:53248
	ds_read_b128 v[164:167], v242 offset:54272
	ds_read_b128 v[168:171], v242 offset:55296
	ds_read_b128 v[172:175], v242 offset:56320
	global_load_lds_dwordx4 v[210:211], off
	v_lshl_add_u64 v[210:211], v[216:217], 0, s[0:1]
	s_mov_b32 m0, s45
	s_nop 0
	global_load_lds_dwordx4 v[210:211], off
	s_barrier
	s_waitcnt lgkmcnt(0)
	s_setprio 1
	s_waitcnt lgkmcnt(0)
	v_mfma_f32_16x16x32_bf16 v[60:63], v[128:131], v[144:147], v[60:63]
	v_mfma_f32_16x16x32_bf16 v[56:59], v[136:139], v[144:147], v[56:59]
	v_mfma_f32_16x16x32_bf16 v[44:47], v[128:131], v[152:155], v[44:47]
	v_mfma_f32_16x16x32_bf16 v[40:43], v[136:139], v[152:155], v[40:43]
	v_mfma_f32_16x16x32_bf16 v[28:31], v[128:131], v[160:163], v[28:31]
	v_mfma_f32_16x16x32_bf16 v[24:27], v[136:139], v[160:163], v[24:27]
	v_mfma_f32_16x16x32_bf16 v[12:15], v[128:131], v[168:171], v[12:15]
	v_mfma_f32_16x16x32_bf16 v[8:11], v[136:139], v[168:171], v[8:11]
	v_mfma_f32_16x16x32_bf16 v[60:63], v[132:135], v[148:151], v[60:63]
	v_mfma_f32_16x16x32_bf16 v[56:59], v[140:143], v[148:151], v[56:59]
	v_mfma_f32_16x16x32_bf16 v[44:47], v[132:135], v[156:159], v[44:47]
	v_mfma_f32_16x16x32_bf16 v[40:43], v[140:143], v[156:159], v[40:43]
	v_mfma_f32_16x16x32_bf16 v[28:31], v[132:135], v[164:167], v[28:31]
	v_mfma_f32_16x16x32_bf16 v[24:27], v[140:143], v[164:167], v[24:27]
	v_mfma_f32_16x16x32_bf16 v[12:15], v[132:135], v[172:175], v[12:15]
	v_mfma_f32_16x16x32_bf16 v[8:11], v[140:143], v[172:175], v[8:11]
	s_setprio 0
	s_barrier
	s_add_u32 s22, s26, 0xb0080
	s_addc_u32 s23, s27, 0
	s_add_i32 s26, s28, s34
	s_mov_b32 m0, s26
	s_nop 0
	global_load_lds_dwordx4 v190, s[22:23]
	s_add_i32 m0, s26, 0x2000
	s_nop 0
	global_load_lds_dwordx4 v194, s[22:23]
	s_waitcnt vmcnt(6)
	s_barrier
	s_setprio 1
	v_mfma_f32_16x16x32_bf16 v[52:55], v[176:179], v[144:147], v[52:55]
	v_mfma_f32_16x16x32_bf16 v[48:51], v[184:187], v[144:147], v[48:51]
	v_mfma_f32_16x16x32_bf16 v[36:39], v[176:179], v[152:155], v[36:39]
	v_mfma_f32_16x16x32_bf16 v[32:35], v[184:187], v[152:155], v[32:35]
	v_mfma_f32_16x16x32_bf16 v[20:23], v[176:179], v[160:163], v[20:23]
	v_mfma_f32_16x16x32_bf16 v[16:19], v[184:187], v[160:163], v[16:19]
	v_mfma_f32_16x16x32_bf16 v[4:7], v[176:179], v[168:171], v[4:7]
	v_mfma_f32_16x16x32_bf16 v[0:3], v[184:187], v[168:171], v[0:3]
	v_mfma_f32_16x16x32_bf16 v[52:55], v[180:183], v[148:151], v[52:55]
	v_mfma_f32_16x16x32_bf16 v[48:51], v[206:209], v[148:151], v[48:51]
	v_mfma_f32_16x16x32_bf16 v[36:39], v[180:183], v[156:159], v[36:39]
	v_mfma_f32_16x16x32_bf16 v[32:35], v[206:209], v[156:159], v[32:35]
	v_mfma_f32_16x16x32_bf16 v[20:23], v[180:183], v[164:167], v[20:23]
	v_mfma_f32_16x16x32_bf16 v[16:19], v[206:209], v[164:167], v[16:19]
	v_mfma_f32_16x16x32_bf16 v[4:7], v[180:183], v[172:175], v[4:7]
	v_mfma_f32_16x16x32_bf16 v[0:3], v[206:209], v[172:175], v[0:3]
	s_setprio 0
	s_add_i32 s56, s56, 2
	s_add_u32 s54, s54, 0x100
	s_addc_u32 s55, s55, 0
	s_cmp_gt_u32 s56, 41
	s_mov_b64 s[22:23], s[24:25]
	s_barrier
	s_cbranch_scc0 .LBB0_1097
	s_lshl_b32 s25, s52, 8
	v_mov_b32_e32 v140, v239
	v_mov_b32_e32 v128, v238
	s_lshl_b32 s22, s53, 8
	s_ashr_i32 s24, s53, 3
	s_or_b32 s25, s25, s43
	s_ashr_i32 s23, s22, 31
	v_lshl_add_u32 v136, v128, 3, s25
	s_mul_hi_i32 s25, s24, 0x9000
	s_mul_i32 s24, s24, 0x9000
	s_add_u32 s24, s40, s24
	s_addc_u32 s25, s41, s25
	v_ashrrev_i32_e32 v137, 31, v136
	v_lshl_add_u64 v[138:139], v[136:137], 2, s[24:25]
	global_load_dwordx4 v[128:131], v[138:139], off offset:16
	global_load_dwordx4 v[132:135], v[138:139], off
	s_lshl_b64 s[22:23], s[22:23], 11
	s_add_u32 s24, s80, s22
	s_addc_u32 s25, s81, s23
	v_lshlrev_b64 v[226:227], 1, v[136:137]
	s_add_u32 s22, s96, s22
	s_addc_u32 s23, s97, s23
	s_and_b64 vcc, exec, s[2:3]
	s_mov_b32 s52, s50
	s_mov_b32 s53, s51
	s_waitcnt vmcnt(0)
	v_pk_mul_f32 v[216:217], v[130:131], 0.5 op_sel_hi:[1,0]
	v_pk_mul_f32 v[220:221], v[134:135], 0.5 op_sel_hi:[1,0]
	v_pk_mul_f32 v[218:219], v[132:133], 0.5 op_sel_hi:[1,0]
	v_pk_mul_f32 v[214:215], v[128:129], 0.5 op_sel_hi:[1,0]
	global_load_dwordx4 v[128:131], v[138:139], off offset:528
	global_load_dwordx4 v[132:135], v[138:139], off offset:512
	s_waitcnt vmcnt(0)
	v_pk_mul_f32 v[206:207], v[128:129], 0.5 op_sel_hi:[1,0]
	v_add_u32_e32 v128, s42, v140
	v_ashrrev_i32_e32 v129, 31, v128
	v_pk_mul_f32 v[208:209], v[130:131], 0.5 op_sel_hi:[1,0]
	v_lshl_add_u64 v[130:131], s[24:25], 0, v[226:227]
	v_lshlrev_b64 v[248:249], 11, v[128:129]
	v_lshl_add_u64 v[128:129], v[130:131], 0, v[248:249]
	global_load_dwordx4 v[244:247], v[128:129], off
	global_load_dwordx4 v[184:187], v[128:129], off offset:256
	v_lshl_add_u64 v[236:237], v[248:249], 0, s[8:9]
	v_lshl_add_u64 v[128:129], v[130:131], 0, v[236:237]
	global_load_dwordx4 v[180:183], v[128:129], off
	global_load_dwordx4 v[176:179], v[128:129], off offset:256
	v_lshl_add_u64 v[234:235], v[248:249], 0, s[10:11]
	v_lshl_add_u64 v[128:129], v[130:131], 0, v[234:235]
	global_load_dwordx4 v[172:175], v[128:129], off
	global_load_dwordx4 v[168:171], v[128:129], off offset:256
	v_lshl_add_u64 v[232:233], v[248:249], 0, s[12:13]
	v_lshl_add_u64 v[128:129], v[130:131], 0, v[232:233]
	global_load_dwordx4 v[164:167], v[128:129], off
	global_load_dwordx4 v[160:163], v[128:129], off offset:256
	v_lshl_add_u64 v[230:231], v[248:249], 0, s[14:15]
	v_lshl_add_u64 v[128:129], v[130:131], 0, v[230:231]
	global_load_dwordx4 v[156:159], v[128:129], off
	global_load_dwordx4 v[152:155], v[128:129], off offset:256
	v_lshl_add_u64 v[228:229], v[248:249], 0, s[16:17]
	v_lshl_add_u64 v[128:129], v[130:131], 0, v[228:229]
	global_load_dwordx4 v[148:151], v[128:129], off
	global_load_dwordx4 v[144:147], v[128:129], off offset:256
	v_lshl_add_u64 v[224:225], v[248:249], 0, s[18:19]
	v_lshl_add_u64 v[128:129], v[130:131], 0, v[224:225]
	global_load_dwordx4 v[140:143], v[128:129], off
	global_load_dwordx4 v[136:139], v[128:129], off offset:256
	v_lshl_add_u64 v[222:223], v[248:249], 0, s[20:21]
	v_lshl_add_u64 v[128:129], v[130:131], 0, v[222:223]
	v_pk_mul_f32 v[212:213], v[134:135], 0.5 op_sel_hi:[1,0]
	v_pk_mul_f32 v[210:211], v[132:133], 0.5 op_sel_hi:[1,0]
	global_load_dwordx4 v[132:135], v[128:129], off
	s_nop 0
	global_load_dwordx4 v[128:131], v[128:129], off offset:256
	v_lshl_add_u64 v[226:227], s[22:23], 0, v[226:227]
	v_lshl_add_u64 v[248:249], v[226:227], 0, v[248:249]
	s_mov_b64 s[24:25], s[6:7]
	s_mov_b64 s[22:23], s[4:5]
	s_waitcnt vmcnt(0)
	v_lshlrev_b32_e32 v250, 16, v244
	v_and_b32_e32 v251, 0xffff0000, v244
	v_lshlrev_b32_e32 v244, 16, v245
	v_and_b32_e32 v245, 0xffff0000, v245
	v_lshlrev_b32_e32 v252, 16, v246
	v_and_b32_e32 v253, 0xffff0000, v246
	v_lshlrev_b32_e32 v246, 16, v247
	v_and_b32_e32 v247, 0xffff0000, v247
	v_pk_fma_f32 v[126:127], v[126:127], v[220:221], v[244:245]
	v_pk_fma_f32 v[124:125], v[124:125], v[218:219], v[250:251]
	v_pk_fma_f32 v[244:245], v[122:123], v[216:217], v[246:247]
	v_pk_fma_f32 v[122:123], v[120:121], v[214:215], v[252:253]
	v_cvt_pk_bf16_f32 v120, v124, v125
	v_cvt_pk_bf16_f32 v121, v126, v127
	v_lshlrev_b32_e32 v124, 16, v186
	v_cvt_pk_bf16_f32 v122, v122, v123
	v_cvt_pk_bf16_f32 v123, v244, v245
	global_store_dwordx4 v[248:249], v[120:123], off
	v_and_b32_e32 v125, 0xffff0000, v186
	v_lshlrev_b32_e32 v126, 16, v187
	v_lshlrev_b32_e32 v120, 16, v184
	v_and_b32_e32 v121, 0xffff0000, v184
	v_and_b32_e32 v127, 0xffff0000, v187
	v_lshlrev_b32_e32 v122, 16, v185
	v_and_b32_e32 v123, 0xffff0000, v185
	v_pk_fma_f32 v[116:117], v[116:117], v[210:211], v[120:121]
	v_pk_fma_f32 v[120:121], v[114:115], v[208:209], v[126:127]
	v_pk_fma_f32 v[114:115], v[112:113], v[206:207], v[124:125]
	v_pk_fma_f32 v[118:119], v[118:119], v[212:213], v[122:123]
	v_cvt_pk_bf16_f32 v112, v116, v117
	v_lshlrev_b32_e32 v116, 16, v181
	v_cvt_pk_bf16_f32 v113, v118, v119
	v_cvt_pk_bf16_f32 v114, v114, v115
	v_cvt_pk_bf16_f32 v115, v120, v121
	global_store_dwordx4 v[248:249], v[112:115], off offset:256
	v_and_b32_e32 v117, 0xffff0000, v181
	v_lshlrev_b32_e32 v118, 16, v182
	v_lshlrev_b32_e32 v114, 16, v180
	v_and_b32_e32 v115, 0xffff0000, v180
	v_and_b32_e32 v119, 0xffff0000, v182
	v_lshlrev_b32_e32 v120, 16, v183
	v_and_b32_e32 v121, 0xffff0000, v183
	v_lshl_add_u64 v[112:113], v[226:227], 0, v[236:237]
	v_pk_fma_f32 v[110:111], v[110:111], v[220:221], v[116:117]
	v_pk_fma_f32 v[108:109], v[108:109], v[218:219], v[114:115]
	v_pk_fma_f32 v[114:115], v[106:107], v[216:217], v[120:121]
	v_pk_fma_f32 v[106:107], v[104:105], v[214:215], v[118:119]
	v_cvt_pk_bf16_f32 v104, v108, v109
	v_cvt_pk_bf16_f32 v105, v110, v111
	v_lshlrev_b32_e32 v108, 16, v178
	v_cvt_pk_bf16_f32 v106, v106, v107
	v_cvt_pk_bf16_f32 v107, v114, v115
	global_store_dwordx4 v[112:113], v[104:107], off
	v_and_b32_e32 v109, 0xffff0000, v178
	v_lshlrev_b32_e32 v110, 16, v179
	v_lshlrev_b32_e32 v104, 16, v176
	v_and_b32_e32 v105, 0xffff0000, v176
	v_and_b32_e32 v111, 0xffff0000, v179
	v_lshlrev_b32_e32 v106, 16, v177
	v_and_b32_e32 v107, 0xffff0000, v177
	v_pk_fma_f32 v[100:101], v[100:101], v[210:211], v[104:105]
	v_pk_fma_f32 v[104:105], v[98:99], v[208:209], v[110:111]
	v_pk_fma_f32 v[98:99], v[96:97], v[206:207], v[108:109]
	v_pk_fma_f32 v[102:103], v[102:103], v[212:213], v[106:107]
	v_cvt_pk_bf16_f32 v96, v100, v101
	v_lshlrev_b32_e32 v100, 16, v173
	v_cvt_pk_bf16_f32 v97, v102, v103
	v_cvt_pk_bf16_f32 v98, v98, v99
	v_cvt_pk_bf16_f32 v99, v104, v105
	global_store_dwordx4 v[112:113], v[96:99], off offset:256
	v_and_b32_e32 v101, 0xffff0000, v173
	v_lshlrev_b32_e32 v102, 16, v174
	v_lshlrev_b32_e32 v98, 16, v172
	v_and_b32_e32 v99, 0xffff0000, v172
	v_and_b32_e32 v103, 0xffff0000, v174
	v_lshlrev_b32_e32 v104, 16, v175
	v_and_b32_e32 v105, 0xffff0000, v175
	v_lshl_add_u64 v[96:97], v[226:227], 0, v[234:235]
	v_pk_fma_f32 v[94:95], v[94:95], v[220:221], v[100:101]
	v_pk_fma_f32 v[92:93], v[92:93], v[218:219], v[98:99]
	v_pk_fma_f32 v[98:99], v[90:91], v[216:217], v[104:105]
	v_pk_fma_f32 v[90:91], v[88:89], v[214:215], v[102:103]
	v_cvt_pk_bf16_f32 v88, v92, v93
	v_cvt_pk_bf16_f32 v89, v94, v95
	v_lshlrev_b32_e32 v92, 16, v170
	v_cvt_pk_bf16_f32 v90, v90, v91
	v_cvt_pk_bf16_f32 v91, v98, v99
	global_store_dwordx4 v[96:97], v[88:91], off
	v_and_b32_e32 v93, 0xffff0000, v170
	v_lshlrev_b32_e32 v94, 16, v171
	v_lshlrev_b32_e32 v88, 16, v168
	v_and_b32_e32 v89, 0xffff0000, v168
	v_and_b32_e32 v95, 0xffff0000, v171
	v_lshlrev_b32_e32 v90, 16, v169
	v_and_b32_e32 v91, 0xffff0000, v169
	v_pk_fma_f32 v[84:85], v[84:85], v[210:211], v[88:89]
	v_pk_fma_f32 v[88:89], v[82:83], v[208:209], v[94:95]
	v_pk_fma_f32 v[82:83], v[80:81], v[206:207], v[92:93]
	v_pk_fma_f32 v[86:87], v[86:87], v[212:213], v[90:91]
	v_cvt_pk_bf16_f32 v80, v84, v85
	v_lshlrev_b32_e32 v84, 16, v165
	v_cvt_pk_bf16_f32 v81, v86, v87
	v_cvt_pk_bf16_f32 v82, v82, v83
	v_cvt_pk_bf16_f32 v83, v88, v89
	global_store_dwordx4 v[96:97], v[80:83], off offset:256
	v_and_b32_e32 v85, 0xffff0000, v165
	v_lshlrev_b32_e32 v86, 16, v166
	v_lshlrev_b32_e32 v82, 16, v164
	v_and_b32_e32 v83, 0xffff0000, v164
	v_and_b32_e32 v87, 0xffff0000, v166
	v_lshlrev_b32_e32 v88, 16, v167
	v_and_b32_e32 v89, 0xffff0000, v167
	v_lshl_add_u64 v[80:81], v[226:227], 0, v[232:233]
	v_pk_fma_f32 v[78:79], v[78:79], v[220:221], v[84:85]
	v_pk_fma_f32 v[76:77], v[76:77], v[218:219], v[82:83]
	v_pk_fma_f32 v[82:83], v[74:75], v[216:217], v[88:89]
	v_pk_fma_f32 v[74:75], v[72:73], v[214:215], v[86:87]
	v_cvt_pk_bf16_f32 v72, v76, v77
	v_cvt_pk_bf16_f32 v73, v78, v79
	v_lshlrev_b32_e32 v76, 16, v162
	v_cvt_pk_bf16_f32 v74, v74, v75
	v_cvt_pk_bf16_f32 v75, v82, v83
	global_store_dwordx4 v[80:81], v[72:75], off
	v_and_b32_e32 v77, 0xffff0000, v162
	v_lshlrev_b32_e32 v78, 16, v163
	v_lshlrev_b32_e32 v72, 16, v160
	v_and_b32_e32 v73, 0xffff0000, v160
	v_and_b32_e32 v79, 0xffff0000, v163
	v_lshlrev_b32_e32 v74, 16, v161
	v_and_b32_e32 v75, 0xffff0000, v161
	v_pk_fma_f32 v[68:69], v[68:69], v[210:211], v[72:73]
	v_pk_fma_f32 v[72:73], v[66:67], v[208:209], v[78:79]
	v_pk_fma_f32 v[66:67], v[64:65], v[206:207], v[76:77]
	v_pk_fma_f32 v[70:71], v[70:71], v[212:213], v[74:75]
	v_cvt_pk_bf16_f32 v64, v68, v69
	v_lshlrev_b32_e32 v68, 16, v157
	v_cvt_pk_bf16_f32 v65, v70, v71
	v_cvt_pk_bf16_f32 v66, v66, v67
	v_cvt_pk_bf16_f32 v67, v72, v73
	global_store_dwordx4 v[80:81], v[64:67], off offset:256
	v_and_b32_e32 v69, 0xffff0000, v157
	v_lshlrev_b32_e32 v70, 16, v158
	v_lshlrev_b32_e32 v66, 16, v156
	v_and_b32_e32 v67, 0xffff0000, v156
	v_and_b32_e32 v71, 0xffff0000, v158
	v_lshlrev_b32_e32 v72, 16, v159
	v_and_b32_e32 v73, 0xffff0000, v159
	v_lshl_add_u64 v[64:65], v[226:227], 0, v[230:231]
	v_pk_fma_f32 v[62:63], v[62:63], v[220:221], v[68:69]
	v_pk_fma_f32 v[60:61], v[60:61], v[218:219], v[66:67]
	v_pk_fma_f32 v[66:67], v[58:59], v[216:217], v[72:73]
	v_pk_fma_f32 v[58:59], v[56:57], v[214:215], v[70:71]
	v_cvt_pk_bf16_f32 v56, v60, v61
	v_cvt_pk_bf16_f32 v57, v62, v63
	v_lshlrev_b32_e32 v60, 16, v154
	v_cvt_pk_bf16_f32 v58, v58, v59
	v_cvt_pk_bf16_f32 v59, v66, v67
	global_store_dwordx4 v[64:65], v[56:59], off
	v_and_b32_e32 v61, 0xffff0000, v154
	v_lshlrev_b32_e32 v62, 16, v155
	v_lshlrev_b32_e32 v56, 16, v152
	v_and_b32_e32 v57, 0xffff0000, v152
	v_and_b32_e32 v63, 0xffff0000, v155
	v_lshlrev_b32_e32 v58, 16, v153
	v_and_b32_e32 v59, 0xffff0000, v153
	v_pk_fma_f32 v[52:53], v[52:53], v[210:211], v[56:57]
	v_pk_fma_f32 v[56:57], v[50:51], v[208:209], v[62:63]
	v_pk_fma_f32 v[50:51], v[48:49], v[206:207], v[60:61]
	v_pk_fma_f32 v[54:55], v[54:55], v[212:213], v[58:59]
	v_cvt_pk_bf16_f32 v48, v52, v53
	v_lshlrev_b32_e32 v52, 16, v149
	v_cvt_pk_bf16_f32 v49, v54, v55
	v_cvt_pk_bf16_f32 v50, v50, v51
	v_cvt_pk_bf16_f32 v51, v56, v57
	global_store_dwordx4 v[64:65], v[48:51], off offset:256
	v_and_b32_e32 v53, 0xffff0000, v149
	v_lshlrev_b32_e32 v54, 16, v150
	v_lshlrev_b32_e32 v50, 16, v148
	v_and_b32_e32 v51, 0xffff0000, v148
	v_and_b32_e32 v55, 0xffff0000, v150
	v_lshlrev_b32_e32 v56, 16, v151
	v_and_b32_e32 v57, 0xffff0000, v151
	v_lshl_add_u64 v[48:49], v[226:227], 0, v[228:229]
	v_pk_fma_f32 v[46:47], v[46:47], v[220:221], v[52:53]
	v_pk_fma_f32 v[44:45], v[44:45], v[218:219], v[50:51]
	v_pk_fma_f32 v[50:51], v[42:43], v[216:217], v[56:57]
	v_pk_fma_f32 v[42:43], v[40:41], v[214:215], v[54:55]
	v_cvt_pk_bf16_f32 v40, v44, v45
	v_cvt_pk_bf16_f32 v41, v46, v47
	v_lshlrev_b32_e32 v44, 16, v146
	v_cvt_pk_bf16_f32 v42, v42, v43
	v_cvt_pk_bf16_f32 v43, v50, v51
	global_store_dwordx4 v[48:49], v[40:43], off
	v_and_b32_e32 v45, 0xffff0000, v146
	v_lshlrev_b32_e32 v46, 16, v147
	v_lshlrev_b32_e32 v40, 16, v144
	v_and_b32_e32 v41, 0xffff0000, v144
	v_and_b32_e32 v47, 0xffff0000, v147
	v_lshlrev_b32_e32 v42, 16, v145
	v_and_b32_e32 v43, 0xffff0000, v145
	v_pk_fma_f32 v[36:37], v[36:37], v[210:211], v[40:41]
	v_pk_fma_f32 v[40:41], v[34:35], v[208:209], v[46:47]
	v_pk_fma_f32 v[34:35], v[32:33], v[206:207], v[44:45]
	v_pk_fma_f32 v[38:39], v[38:39], v[212:213], v[42:43]
	v_cvt_pk_bf16_f32 v32, v36, v37
	v_lshlrev_b32_e32 v36, 16, v141
	v_cvt_pk_bf16_f32 v33, v38, v39
	v_cvt_pk_bf16_f32 v34, v34, v35
	v_cvt_pk_bf16_f32 v35, v40, v41
	global_store_dwordx4 v[48:49], v[32:35], off offset:256
	v_and_b32_e32 v37, 0xffff0000, v141
	v_lshlrev_b32_e32 v38, 16, v142
	v_lshlrev_b32_e32 v34, 16, v140
	v_and_b32_e32 v35, 0xffff0000, v140
	v_and_b32_e32 v39, 0xffff0000, v142
	v_lshlrev_b32_e32 v40, 16, v143
	v_and_b32_e32 v41, 0xffff0000, v143
	v_lshl_add_u64 v[32:33], v[226:227], 0, v[224:225]
	v_pk_fma_f32 v[30:31], v[30:31], v[220:221], v[36:37]
	v_pk_fma_f32 v[28:29], v[28:29], v[218:219], v[34:35]
	v_pk_fma_f32 v[34:35], v[26:27], v[216:217], v[40:41]
	v_pk_fma_f32 v[26:27], v[24:25], v[214:215], v[38:39]
	v_cvt_pk_bf16_f32 v24, v28, v29
	v_cvt_pk_bf16_f32 v25, v30, v31
	v_lshlrev_b32_e32 v28, 16, v138
	v_cvt_pk_bf16_f32 v26, v26, v27
	v_cvt_pk_bf16_f32 v27, v34, v35
	global_store_dwordx4 v[32:33], v[24:27], off
	v_and_b32_e32 v29, 0xffff0000, v138
	v_lshlrev_b32_e32 v30, 16, v139
	v_lshlrev_b32_e32 v24, 16, v136
	v_and_b32_e32 v25, 0xffff0000, v136
	v_and_b32_e32 v31, 0xffff0000, v139
	v_lshlrev_b32_e32 v26, 16, v137
	v_and_b32_e32 v27, 0xffff0000, v137
	v_pk_fma_f32 v[20:21], v[20:21], v[210:211], v[24:25]
	v_pk_fma_f32 v[24:25], v[18:19], v[208:209], v[30:31]
	v_pk_fma_f32 v[18:19], v[16:17], v[206:207], v[28:29]
	v_pk_fma_f32 v[22:23], v[22:23], v[212:213], v[26:27]
	v_cvt_pk_bf16_f32 v16, v20, v21
	v_lshlrev_b32_e32 v20, 16, v133
	v_cvt_pk_bf16_f32 v17, v22, v23
	v_cvt_pk_bf16_f32 v18, v18, v19
	v_cvt_pk_bf16_f32 v19, v24, v25
	global_store_dwordx4 v[32:33], v[16:19], off offset:256
	v_and_b32_e32 v21, 0xffff0000, v133
	v_lshlrev_b32_e32 v22, 16, v134
	v_lshlrev_b32_e32 v18, 16, v132
	v_and_b32_e32 v19, 0xffff0000, v132
	v_and_b32_e32 v23, 0xffff0000, v134
	v_lshlrev_b32_e32 v24, 16, v135
	v_and_b32_e32 v25, 0xffff0000, v135
	v_lshl_add_u64 v[16:17], v[226:227], 0, v[222:223]
	v_pk_fma_f32 v[14:15], v[14:15], v[220:221], v[20:21]
	v_pk_fma_f32 v[12:13], v[12:13], v[218:219], v[18:19]
	v_pk_fma_f32 v[18:19], v[10:11], v[216:217], v[24:25]
	v_pk_fma_f32 v[10:11], v[8:9], v[214:215], v[22:23]
	v_cvt_pk_bf16_f32 v8, v12, v13
	v_cvt_pk_bf16_f32 v9, v14, v15
	v_lshlrev_b32_e32 v12, 16, v130
	v_cvt_pk_bf16_f32 v10, v10, v11
	v_cvt_pk_bf16_f32 v11, v18, v19
	global_store_dwordx4 v[16:17], v[8:11], off
	v_and_b32_e32 v13, 0xffff0000, v130
	v_lshlrev_b32_e32 v14, 16, v131
	v_lshlrev_b32_e32 v8, 16, v128
	v_and_b32_e32 v9, 0xffff0000, v128
	v_and_b32_e32 v15, 0xffff0000, v131
	v_lshlrev_b32_e32 v10, 16, v129
	v_and_b32_e32 v11, 0xffff0000, v129
	v_pk_fma_f32 v[4:5], v[4:5], v[210:211], v[8:9]
	v_pk_fma_f32 v[8:9], v[2:3], v[208:209], v[14:15]
	v_pk_fma_f32 v[2:3], v[0:1], v[206:207], v[12:13]
	v_pk_fma_f32 v[6:7], v[6:7], v[212:213], v[10:11]
	v_cvt_pk_bf16_f32 v0, v4, v5
	s_nop 0
	v_cvt_pk_bf16_f32 v1, v6, v7
	v_cvt_pk_bf16_f32 v2, v2, v3
	v_cvt_pk_bf16_f32 v3, v8, v9
	global_store_dwordx4 v[16:17], v[0:3], off offset:256
	s_cbranch_vccz .LBB0_1086
	s_waitcnt vmcnt(0)
	s_cmpk_gt_u32 s30, 0xff
	s_cbranch_scc1 .LBB0_1101
	s_barrier
